# speedup vs baseline: 1.0126x; 1.0126x over previous
; #define LAS __attribute__((address_space(3)))
; #define GAS __attribute__((address_space(1)))
; __device__ __forceinline__ unsigned pk2(float lo, float hi) { unsigned r; asm("s_nop 1\n\tv_cvt_pk_bf16_f32 %0, %1, %2" : "=v"(r) : "v"(lo), "v"(hi)); return r; }
; __device__ __forceinline__ void tr_wave_job(const GAS float* src0, const GAS float* src1, int ld, int mode, GAS bf16* dst, int K, int ldd, int n0, int k0, int lane, int wid, const GAS float* gk) {
;     ...
;   for (int q = 0; q < 8; ++q) {
;     u32x4 o = {pk2(v[8 * q + 0], v[8 * q + 1]), pk2(v[8 * q + 2], v[8 * q + 3]), pk2(v[8 * q + 4], v[8 * q + 5]), pk2(v[8 * q + 6], v[8 * q + 7])};
;     *(LAS u32x4*)(scr + (lane * 8 + (q ^ (lane & 7))) * 16) = o;
;   }
;   asm volatile("s_waitcnt lgkmcnt(0)" ::: "memory");
;   const int rq = lane & 7;
; #pragma unroll
;   for (int i = 0; i < 8; ++i) {
;     const int r = i * 8 + (lane >> 3);
;     const u32x4 o = *(const LAS u32x4*)(scr + (r * 8 + (rq ^ (r & 7))) * 16);
;     *(GAS u32x4*)(dst + (size_t)(n0 + r) * ldd + k0 + rq * 8) = o;
;   }
;   asm volatile("s_waitcnt lgkmcnt(0)" ::: "memory");
.LBB0_24:
	s_waitcnt vmcnt(8)
	v_cvt_pk_bf16_f32 v74, v74, v75
	v_cvt_pk_bf16_f32 v75, v68, v69
	v_add_u32_e32 v68, v79, v2
	v_cvt_pk_bf16_f32 v10, v10, v11
	v_cvt_pk_bf16_f32 v11, v12, v13
	v_cvt_pk_bf16_f32 v12, v14, v15
	v_cvt_pk_bf16_f32 v13, v16, v17
	v_cvt_pk_bf16_f32 v76, v70, v71
	v_cvt_pk_bf16_f32 v77, v72, v73
	ds_write_b128 v68, v[74:77]
	ds_write_b128 v89, v[10:13]
	v_cvt_pk_bf16_f32 v10, v18, v19
	v_cvt_pk_bf16_f32 v11, v20, v21
	v_cvt_pk_bf16_f32 v12, v22, v23
	v_cvt_pk_bf16_f32 v13, v24, v25
	ds_write_b128 v90, v[10:13]
	v_cvt_pk_bf16_f32 v10, v26, v27
	v_cvt_pk_bf16_f32 v11, v28, v29
	v_cvt_pk_bf16_f32 v12, v30, v31
	v_cvt_pk_bf16_f32 v13, v32, v33
	ds_write_b128 v91, v[10:13]
	v_cvt_pk_bf16_f32 v10, v34, v35
	v_cvt_pk_bf16_f32 v11, v36, v37
	v_cvt_pk_bf16_f32 v12, v38, v39
	v_cvt_pk_bf16_f32 v13, v40, v41
	ds_write_b128 v92, v[10:13]
	v_cvt_pk_bf16_f32 v10, v42, v43
	v_cvt_pk_bf16_f32 v11, v44, v45
	v_cvt_pk_bf16_f32 v12, v46, v47
	v_cvt_pk_bf16_f32 v13, v48, v49
	ds_write_b128 v93, v[10:13]
	v_cvt_pk_bf16_f32 v10, v52, v53
	v_cvt_pk_bf16_f32 v11, v54, v55
	v_cvt_pk_bf16_f32 v12, v56, v57
	v_cvt_pk_bf16_f32 v13, v58, v59
	ds_write_b128 v94, v[10:13]
	s_waitcnt vmcnt(6)
	v_cvt_pk_bf16_f32 v10, v60, v61
	s_waitcnt vmcnt(4)
	v_cvt_pk_bf16_f32 v11, v62, v63
	s_waitcnt vmcnt(2)
	v_cvt_pk_bf16_f32 v12, v64, v65
	s_waitcnt vmcnt(0)
	v_cvt_pk_bf16_f32 v13, v66, v67
	ds_write_b128 v95, v[10:13]
	s_waitcnt lgkmcnt(0)
	v_lshl_add_u64 v[16:17], v[8:9], 1, v[6:7]
	ds_read_b128 v[8:11], v96
	v_or_b32_e32 v12, v105, v80
	v_ashrrev_i32_e32 v13, 31, v12
	v_lshlrev_b64 v[12:13], 11, v[12:13]
	v_lshl_add_u64 v[18:19], v[16:17], 0, v[12:13]
	ds_read_b128 v[12:15], v97
	s_waitcnt lgkmcnt(1)
	global_store_dwordx4 v[18:19], v[8:11], off
	v_add_u32_e32 v104, v104, v78
	v_cmp_lt_i32_e32 vcc, s77, v104
	v_or_b32_e32 v8, v105, v81
	v_ashrrev_i32_e32 v9, 31, v8
	v_lshlrev_b64 v[8:9], 11, v[8:9]
	v_lshl_add_u64 v[8:9], v[16:17], 0, v[8:9]
	s_waitcnt lgkmcnt(0)
	global_store_dwordx4 v[8:9], v[12:15], off
	ds_read_b128 v[8:11], v98
	s_or_b64 s[6:7], vcc, s[6:7]
	v_or_b32_e32 v12, v105, v82
	v_ashrrev_i32_e32 v13, 31, v12
	v_lshlrev_b64 v[12:13], 11, v[12:13]
	v_lshl_add_u64 v[18:19], v[16:17], 0, v[12:13]
	ds_read_b128 v[12:15], v99
	s_waitcnt lgkmcnt(1)
	global_store_dwordx4 v[18:19], v[8:11], off
	v_add_u32_e32 v3, v3, v88
	s_nop 0
	v_or_b32_e32 v8, v105, v83
	v_ashrrev_i32_e32 v9, 31, v8
	v_lshlrev_b64 v[8:9], 11, v[8:9]
	v_lshl_add_u64 v[8:9], v[16:17], 0, v[8:9]
	s_waitcnt lgkmcnt(0)
	global_store_dwordx4 v[8:9], v[12:15], off
	ds_read_b128 v[8:11], v100
	s_nop 0
	v_or_b32_e32 v12, v105, v84
	v_ashrrev_i32_e32 v13, 31, v12
	v_lshlrev_b64 v[12:13], 11, v[12:13]
	v_lshl_add_u64 v[18:19], v[16:17], 0, v[12:13]
	ds_read_b128 v[12:15], v101
	s_waitcnt lgkmcnt(1)
	global_store_dwordx4 v[18:19], v[8:11], off
	s_nop 1
	v_or_b32_e32 v8, v105, v85
	v_ashrrev_i32_e32 v9, 31, v8
	v_lshlrev_b64 v[8:9], 11, v[8:9]
	v_lshl_add_u64 v[8:9], v[16:17], 0, v[8:9]
	s_waitcnt lgkmcnt(0)
	global_store_dwordx4 v[8:9], v[12:15], off
	ds_read_b128 v[8:11], v102
	s_nop 0
	v_or_b32_e32 v12, v105, v86
	v_ashrrev_i32_e32 v13, 31, v12
	v_lshlrev_b64 v[12:13], 11, v[12:13]
	v_lshl_add_u64 v[18:19], v[16:17], 0, v[12:13]
	ds_read_b128 v[12:15], v103
	s_waitcnt lgkmcnt(1)
	global_store_dwordx4 v[18:19], v[8:11], off
	s_nop 1
	v_or_b32_e32 v8, v105, v87
	v_ashrrev_i32_e32 v9, 31, v8
	v_lshlrev_b64 v[8:9], 11, v[8:9]
	v_lshl_add_u64 v[8:9], v[16:17], 0, v[8:9]
	s_waitcnt lgkmcnt(0)
	global_store_dwordx4 v[8:9], v[12:15], off
	s_waitcnt lgkmcnt(0)
	s_andn2_b64 exec, exec, s[6:7]
	s_cbranch_execz .LBB0_27

; #define GAS __attribute__((address_space(1)))
; __device__ __forceinline__ unsigned pk2(float lo, float hi) { unsigned r; asm("s_nop 1\n\tv_cvt_pk_bf16_f32 %0, %1, %2" : "=v"(r) : "v"(lo), "v"(hi)); return r; }
; __device__ __forceinline__ void phase0() {
;     ...
;   for (int row0 = blockIdx.x * 8 + wid; row0 < T; row0 += 4 * nwv) {
;     f32x4 v[4][4];
; #pragma unroll
;     for (int q = 0; q < 4; ++q) {
;       const int row = row0 + q * nwv;
;       const GAS f32x4* xr = (const GAS f32x4*)(P.x + (size_t)(row < T ? row : row0) * DM) + lane;
; #pragma unroll
;       for (int j = 0; j < 4; ++j) v[q][j] = xr[64 * j];
;     }
; #pragma unroll
;     for (int q = 0; q < 4; ++q) {
;       const int row = row0 + q * nwv;
;       if (row < T) {
;         GAS u32x2* o8 = (GAS u32x2*)(ws + OFF_XG + (size_t)row * DM * 2) + lane;
;         float s = 0.f;
; #pragma unroll
;         for (int j = 0; j < 4; ++j) {
;           const f32x4 w = v[q][j];
;           s += (w.x * w.x + w.y * w.y) + (w.z * w.z + w.w * w.w);
;           u32x2 o = {pk2(w.x, w.y), pk2(w.z, w.w)};
;           o8[64 * j] = o;
;         }
;         s = wave_sum(s);
;         if (lane < 16) ssq[(size_t)row * 16 + lane] = (lane == 0) ? s : 0.f;
;       }
;     }
.LBB0_30:
	v_ashrrev_i32_e32 v51, 31, v50
	v_lshlrev_b64 v[2:3], 12, v[50:51]
	v_lshl_add_u64 v[2:3], v[52:53], 0, v[2:3]
	global_load_dwordx4 v[80:83], v[2:3], off
	global_load_dwordx4 v[84:87], v[2:3], off offset:1024
	global_load_dwordx4 v[88:91], v[2:3], off offset:2048
	global_load_dwordx4 v[92:95], v[2:3], off offset:3072
	v_add_u32_e32 v58, v50, v78
	v_add_u32_e32 v62, v64, v50
	v_add_u32_e32 v60, v65, v50
	v_cmp_gt_i32_e64 s[10:11], s3, v58
	v_cmp_gt_i32_e64 s[8:9], s3, v62
	v_cmp_gt_i32_e64 s[6:7], s3, v60
	v_cndmask_b32_e64 v2, v50, v58, s[10:11]
	v_cndmask_b32_e64 v4, v50, v62, s[8:9]
	v_cndmask_b32_e64 v6, v50, v60, s[6:7]
	v_ashrrev_i32_e32 v3, 31, v2
	v_ashrrev_i32_e32 v5, 31, v4
	s_waitcnt lgkmcnt(0)
	v_ashrrev_i32_e32 v7, 31, v6
	v_lshlrev_b64 v[2:3], 12, v[2:3]
	v_lshlrev_b64 v[4:5], 12, v[4:5]
	v_lshlrev_b64 v[6:7], 12, v[6:7]
	v_lshl_add_u64 v[74:75], v[52:53], 0, v[2:3]
	v_lshl_add_u64 v[76:77], v[52:53], 0, v[4:5]
	v_lshl_add_u64 v[96:97], v[52:53], 0, v[6:7]
	global_load_dwordx4 v[46:49], v[74:75], off
	global_load_dwordx4 v[42:45], v[74:75], off offset:1024
	global_load_dwordx4 v[38:41], v[74:75], off offset:2048
	global_load_dwordx4 v[34:37], v[74:75], off offset:3072
	global_load_dwordx4 v[30:33], v[76:77], off
	global_load_dwordx4 v[26:29], v[76:77], off offset:1024
	global_load_dwordx4 v[22:25], v[76:77], off offset:2048
	global_load_dwordx4 v[18:21], v[76:77], off offset:3072
	global_load_dwordx4 v[14:17], v[96:97], off
	global_load_dwordx4 v[10:13], v[96:97], off offset:1024
	global_load_dwordx4 v[6:9], v[96:97], off offset:2048
	global_load_dwordx4 v[2:5], v[96:97], off offset:3072
	v_cmp_lt_i32_e64 s[12:13], v68, v67
	s_waitcnt vmcnt(15)
	v_mul_f32_e32 v74, v83, v83
	v_cndmask_b32_e64 v59, v66, v68, s[12:13]
	v_lshlrev_b32_e32 v61, 2, v59
	v_mul_f32_e32 v59, v81, v81
	s_waitcnt vmcnt(14)
	v_mul_f32_e32 v75, v85, v85
	v_mul_f32_e32 v76, v87, v87
	s_waitcnt vmcnt(13)
	v_mul_f32_e32 v77, v89, v89
	v_mul_f32_e32 v79, v91, v91
	v_fmac_f32_e32 v59, v80, v80
	v_fmac_f32_e32 v74, v82, v82
	v_fmac_f32_e32 v75, v84, v84
	v_fmac_f32_e32 v76, v86, v86
	s_waitcnt vmcnt(12)
	v_mul_f32_e32 v96, v93, v93
	v_mul_f32_e32 v97, v95, v95
	v_fmac_f32_e32 v77, v88, v88
	v_fmac_f32_e32 v79, v90, v90
	v_add_f32_e32 v59, v59, v74
	v_add_f32_e32 v74, v75, v76
	v_fmac_f32_e32 v96, v92, v92
	v_fmac_f32_e32 v97, v94, v94
	v_add_f32_e32 v75, v77, v79
	v_add_f32_e32 v59, v74, v59
	v_add_f32_e32 v76, v96, v97
	v_add_f32_e32 v59, v75, v59
	v_add_f32_e32 v59, v76, v59
	ds_bpermute_b32 v75, v61, v59
	v_cmp_lt_i32_e64 s[12:13], v69, v67
	v_lshlrev_b64 v[96:97], 11, v[50:51]
	v_lshl_add_u64 v[96:97], v[54:55], 0, v[96:97]
	v_cndmask_b32_e64 v63, v66, v69, s[12:13]
	v_lshlrev_b32_e32 v74, 2, v63
	s_waitcnt lgkmcnt(0)
	v_add_f32_e32 v59, v59, v75
	ds_bpermute_b32 v63, v74, v59
	v_cmp_lt_i32_e64 s[12:13], v70, v67
	v_cvt_pk_bf16_f32 v80, v80, v81
	v_cvt_pk_bf16_f32 v81, v82, v83
	v_cvt_pk_bf16_f32 v82, v84, v85
	s_waitcnt lgkmcnt(0)
	v_add_f32_e32 v59, v59, v63
	v_cvt_pk_bf16_f32 v83, v86, v87
	v_cndmask_b32_e64 v76, v66, v70, s[12:13]
	v_lshlrev_b32_e32 v77, 2, v76
	ds_bpermute_b32 v63, v77, v59
	v_cmp_lt_i32_e64 s[12:13], v71, v67
	v_cvt_pk_bf16_f32 v84, v88, v89
	v_cvt_pk_bf16_f32 v85, v90, v91
	global_store_dwordx2 v[96:97], v[80:81], off
	global_store_dwordx2 v[96:97], v[82:83], off offset:512
	v_cndmask_b32_e64 v79, v66, v71, s[12:13]
	v_lshlrev_b32_e32 v76, 2, v79
	s_waitcnt lgkmcnt(0)
	v_add_f32_e32 v59, v59, v63
	ds_bpermute_b32 v63, v76, v59
	v_cmp_lt_i32_e64 s[12:13], v72, v67
	global_store_dwordx2 v[96:97], v[84:85], off offset:1024
	v_cvt_pk_bf16_f32 v80, v92, v93
	v_cvt_pk_bf16_f32 v81, v94, v95
	s_waitcnt lgkmcnt(0)
	v_add_f32_e32 v59, v59, v63
	v_cndmask_b32_e64 v75, v66, v72, s[12:13]
	v_lshlrev_b32_e32 v75, 2, v75
	ds_bpermute_b32 v63, v75, v59
	v_cmp_lt_i32_e64 s[12:13], v73, v67
	global_store_dwordx2 v[96:97], v[80:81], off offset:1536
	s_waitcnt lgkmcnt(0)
	v_add_f32_e32 v59, v59, v63
	v_cndmask_b32_e64 v98, v66, v73, s[12:13]
	v_lshlrev_b32_e32 v79, 2, v98
	ds_bpermute_b32 v63, v79, v59
	s_and_saveexec_b64 s[12:13], vcc
	s_cbranch_execz .LBB0_32
	s_waitcnt lgkmcnt(0)
	v_add_f32_e32 v59, v59, v63
	v_lshlrev_b64 v[50:51], 6, v[50:51]
	v_cndmask_b32_e64 v59, 0, v59, s[4:5]
	v_lshl_add_u64 v[50:51], v[56:57], 0, v[50:51]
	global_store_dword v[50:51], v59, off
; #define GAS __attribute__((address_space(1)))
; __device__ __forceinline__ unsigned pk2(float lo, float hi) { unsigned r; asm("s_nop 1\n\tv_cvt_pk_bf16_f32 %0, %1, %2" : "=v"(r) : "v"(lo), "v"(hi)); return r; }
; __device__ __forceinline__ void phase0() {
;     ...
;     for (int q = 0; q < 4; ++q) {
;       const int row = row0 + q * nwv;
;       if (row < T) {
;         GAS u32x2* o8 = (GAS u32x2*)(ws + OFF_XG + (size_t)row * DM * 2) + lane;
;         float s = 0.f;
; #pragma unroll
;         for (int j = 0; j < 4; ++j) {
;           const f32x4 w = v[q][j];
;           s += (w.x * w.x + w.y * w.y) + (w.z * w.z + w.w * w.w);
;           u32x2 o = {pk2(w.x, w.y), pk2(w.z, w.w)};
;           o8[64 * j] = o;
;         }
;         s = wave_sum(s);
;         if (lane < 16) ssq[(size_t)row * 16 + lane] = (lane == 0) ? s : 0.f;
;       }
;     }
.LBB0_32:
	s_or_b64 exec, exec, s[12:13]
	s_and_saveexec_b64 s[12:13], s[10:11]
	s_cbranch_execz .LBB0_35
	s_waitcnt vmcnt(15)
	v_mul_f32_e32 v50, v47, v47
	v_mul_f32_e32 v51, v49, v49
	v_fmac_f32_e32 v50, v46, v46
	v_fmac_f32_e32 v51, v48, v48
	v_add_f32_e32 v50, v50, v51
	s_waitcnt vmcnt(14)
	v_mul_f32_e32 v51, v43, v43
	v_mul_f32_e32 v59, v45, v45
	v_fmac_f32_e32 v51, v42, v42
	v_fmac_f32_e32 v59, v44, v44
	v_add_f32_e32 v51, v51, v59
	v_add_f32_e32 v50, v50, v51
	s_waitcnt vmcnt(13)
	v_mul_f32_e32 v51, v39, v39
	v_mul_f32_e32 v59, v41, v41
	v_fmac_f32_e32 v51, v38, v38
	v_fmac_f32_e32 v59, v40, v40
	v_add_f32_e32 v51, v51, v59
	v_add_f32_e32 v50, v50, v51
	s_waitcnt vmcnt(12)
	v_mul_f32_e32 v51, v35, v35
	v_mul_f32_e32 v59, v37, v37
	v_fmac_f32_e32 v51, v34, v34
	v_fmac_f32_e32 v59, v36, v36
	v_add_f32_e32 v51, v51, v59
	v_add_f32_e32 v50, v50, v51
	ds_bpermute_b32 v51, v61, v50
	v_ashrrev_i32_e32 v59, 31, v58
	v_cvt_pk_bf16_f32 v46, v46, v47
	v_cvt_pk_bf16_f32 v47, v48, v49
	v_cvt_pk_bf16_f32 v42, v42, v43
	s_waitcnt lgkmcnt(0)
	v_add_f32_e32 v50, v50, v51
	ds_bpermute_b32 v51, v74, v50
	v_cvt_pk_bf16_f32 v43, v44, v45
	v_cvt_pk_bf16_f32 v34, v34, v35
	v_cvt_pk_bf16_f32 v35, v36, v37
	s_waitcnt lgkmcnt(0)
	v_add_f32_e32 v63, v50, v51
	ds_bpermute_b32 v80, v77, v63
	v_lshlrev_b64 v[50:51], 11, v[58:59]
	v_lshl_add_u64 v[50:51], v[54:55], 0, v[50:51]
	global_store_dwordx2 v[50:51], v[46:47], off
	global_store_dwordx2 v[50:51], v[42:43], off offset:512
	s_waitcnt lgkmcnt(0)
	v_add_f32_e32 v63, v63, v80
	ds_bpermute_b32 v80, v76, v63
	v_cvt_pk_bf16_f32 v42, v38, v39
	v_cvt_pk_bf16_f32 v43, v40, v41
	global_store_dwordx2 v[50:51], v[42:43], off offset:1024
	global_store_dwordx2 v[50:51], v[34:35], off offset:1536
	s_waitcnt lgkmcnt(0)
	v_add_f32_e32 v46, v63, v80
	ds_bpermute_b32 v47, v75, v46
	s_waitcnt lgkmcnt(0)
	v_add_f32_e32 v38, v46, v47
	ds_bpermute_b32 v39, v79, v38
	s_and_b64 exec, exec, vcc
	s_cbranch_execz .LBB0_35
	s_waitcnt lgkmcnt(0)
	v_add_f32_e32 v34, v38, v39
	v_cndmask_b32_e64 v36, 0, v34, s[4:5]
	v_lshlrev_b64 v[34:35], 6, v[58:59]
	v_lshl_add_u64 v[34:35], v[56:57], 0, v[34:35]
	global_store_dword v[34:35], v36, off
.LBB0_35:
	s_or_b64 exec, exec, s[12:13]
	s_and_saveexec_b64 s[10:11], s[8:9]
	s_cbranch_execz .LBB0_38
	s_waitcnt vmcnt(11)
	v_mul_f32_e32 v34, v31, v31
	v_mul_f32_e32 v35, v33, v33
	v_fmac_f32_e32 v34, v30, v30
	v_fmac_f32_e32 v35, v32, v32
	v_add_f32_e32 v34, v34, v35
	s_waitcnt vmcnt(10)
	v_mul_f32_e32 v35, v27, v27
	v_mul_f32_e32 v36, v29, v29
	v_fmac_f32_e32 v35, v26, v26
	v_fmac_f32_e32 v36, v28, v28
	v_add_f32_e32 v35, v35, v36
	v_add_f32_e32 v34, v34, v35
	s_waitcnt vmcnt(9)
	v_mul_f32_e32 v35, v23, v23
	v_mul_f32_e32 v36, v25, v25
	v_fmac_f32_e32 v35, v22, v22
	v_fmac_f32_e32 v36, v24, v24
	v_add_f32_e32 v35, v35, v36
	v_add_f32_e32 v34, v34, v35
	s_waitcnt vmcnt(8)
	v_mul_f32_e32 v35, v19, v19
	v_mul_f32_e32 v36, v21, v21
	v_fmac_f32_e32 v35, v18, v18
	v_fmac_f32_e32 v36, v20, v20
	v_add_f32_e32 v35, v35, v36
	v_add_f32_e32 v34, v34, v35
	ds_bpermute_b32 v35, v61, v34
	s_waitcnt lgkmcnt(1)
	v_ashrrev_i32_e32 v63, 31, v62
	v_cvt_pk_bf16_f32 v30, v30, v31
	v_cvt_pk_bf16_f32 v31, v32, v33
	v_cvt_pk_bf16_f32 v26, v26, v27
	s_waitcnt lgkmcnt(0)
	v_add_f32_e32 v34, v34, v35
	ds_bpermute_b32 v35, v74, v34
	v_cvt_pk_bf16_f32 v27, v28, v29
	v_cvt_pk_bf16_f32 v18, v18, v19
	v_cvt_pk_bf16_f32 v19, v20, v21
	s_waitcnt lgkmcnt(0)
	v_add_f32_e32 v36, v34, v35
	ds_bpermute_b32 v37, v77, v36
	v_lshlrev_b64 v[34:35], 11, v[62:63]
	v_lshl_add_u64 v[34:35], v[54:55], 0, v[34:35]
	global_store_dwordx2 v[34:35], v[30:31], off
	global_store_dwordx2 v[34:35], v[26:27], off offset:512
	s_waitcnt lgkmcnt(0)
	v_add_f32_e32 v36, v36, v37
	ds_bpermute_b32 v37, v76, v36
	v_cvt_pk_bf16_f32 v26, v22, v23
	v_cvt_pk_bf16_f32 v27, v24, v25
	global_store_dwordx2 v[34:35], v[26:27], off offset:1024
	global_store_dwordx2 v[34:35], v[18:19], off offset:1536
	s_waitcnt lgkmcnt(0)
	v_add_f32_e32 v30, v36, v37
	ds_bpermute_b32 v31, v75, v30
	s_waitcnt lgkmcnt(0)
	v_add_f32_e32 v22, v30, v31
	ds_bpermute_b32 v23, v79, v22
	s_and_b64 exec, exec, vcc
	s_cbranch_execz .LBB0_38
	s_waitcnt lgkmcnt(0)
	v_add_f32_e32 v18, v22, v23
	v_cndmask_b32_e64 v20, 0, v18, s[4:5]
	v_lshlrev_b64 v[18:19], 6, v[62:63]
	v_lshl_add_u64 v[18:19], v[56:57], 0, v[18:19]
	global_store_dword v[18:19], v20, off
.LBB0_38:
	s_or_b64 exec, exec, s[10:11]
	s_and_saveexec_b64 s[8:9], s[6:7]
	s_cbranch_execz .LBB0_29
	s_waitcnt vmcnt(7)
	v_mul_f32_e32 v18, v15, v15
	v_mul_f32_e32 v19, v17, v17
	v_fmac_f32_e32 v18, v14, v14
	v_fmac_f32_e32 v19, v16, v16
	v_add_f32_e32 v18, v18, v19
	s_waitcnt vmcnt(6)
	v_mul_f32_e32 v19, v11, v11
	v_mul_f32_e32 v20, v13, v13
	v_fmac_f32_e32 v19, v10, v10
	v_fmac_f32_e32 v20, v12, v12
	v_add_f32_e32 v19, v19, v20
	v_add_f32_e32 v18, v18, v19
	s_waitcnt vmcnt(5)
	v_mul_f32_e32 v19, v7, v7
	v_mul_f32_e32 v20, v9, v9
	v_fmac_f32_e32 v19, v6, v6
	v_fmac_f32_e32 v20, v8, v8
	v_add_f32_e32 v19, v19, v20
	v_add_f32_e32 v18, v18, v19
	s_waitcnt vmcnt(4)
	v_mul_f32_e32 v19, v3, v3
	v_mul_f32_e32 v20, v5, v5
	v_fmac_f32_e32 v19, v2, v2
	v_fmac_f32_e32 v20, v4, v4
	v_add_f32_e32 v19, v19, v20
	v_add_f32_e32 v18, v18, v19
	ds_bpermute_b32 v19, v61, v18
	v_ashrrev_i32_e32 v61, 31, v60
	v_cvt_pk_bf16_f32 v14, v14, v15
	v_cvt_pk_bf16_f32 v15, v16, v17
	v_cvt_pk_bf16_f32 v10, v10, v11
	s_waitcnt lgkmcnt(0)
	v_add_f32_e32 v18, v18, v19
	ds_bpermute_b32 v19, v74, v18
	v_cvt_pk_bf16_f32 v11, v12, v13
	v_cvt_pk_bf16_f32 v2, v2, v3
	v_cvt_pk_bf16_f32 v3, v4, v5
	s_waitcnt lgkmcnt(0)
	v_add_f32_e32 v20, v18, v19
	ds_bpermute_b32 v21, v77, v20
	v_lshlrev_b64 v[18:19], 11, v[60:61]
	v_lshl_add_u64 v[18:19], v[54:55], 0, v[18:19]
	global_store_dwordx2 v[18:19], v[14:15], off
	global_store_dwordx2 v[18:19], v[10:11], off offset:512
	s_waitcnt lgkmcnt(0)
	v_add_f32_e32 v20, v20, v21
	ds_bpermute_b32 v21, v76, v20
	v_cvt_pk_bf16_f32 v10, v6, v7
	v_cvt_pk_bf16_f32 v11, v8, v9
	global_store_dwordx2 v[18:19], v[10:11], off offset:1024
	global_store_dwordx2 v[18:19], v[2:3], off offset:1536
	s_waitcnt lgkmcnt(0)
	v_add_f32_e32 v14, v20, v21
	ds_bpermute_b32 v15, v75, v14
	s_waitcnt lgkmcnt(0)
	v_add_f32_e32 v6, v14, v15
	ds_bpermute_b32 v7, v79, v6
	s_and_b64 exec, exec, vcc
	s_cbranch_execz .LBB0_29
	s_waitcnt lgkmcnt(0)
	v_add_f32_e32 v2, v6, v7
	v_cndmask_b32_e64 v4, 0, v2, s[4:5]
	v_lshlrev_b64 v[2:3], 6, v[60:61]
	v_lshl_add_u64 v[2:3], v[56:57], 0, v[2:3]
	global_store_dword v[2:3], v4, off
	s_branch .LBB0_29

; #define GAS __attribute__((address_space(1)))
; __device__ __forceinline__ unsigned f2bf(float f) { return pk2(f, f) & 0xffffu; }
; __device__ __forceinline__ float sigmoidf_(float v) { return __builtin_amdgcn_rcpf(1.f + __builtin_amdgcn_exp2f(-LOG2E * v)); }
; __device__ __forceinline__ void phase_up(int pass) {
;     ...
;     EPI_IDS
;     const float* rr = (const float*)(smem_raw + LDS_RR) + par * 256;
;     GAS char* tb = (GAS char*)act + ((size_t)brow * FFP + (bcol >> 1)) * 2;
;     const unsigned off0 = (unsigned)((wr * 64 + fq * 4) * FFP + wc * 16 + fr) * 2u;
; #pragma unroll
;     for (int ai = 0; ai < 2; ++ai)
; #pragma unroll
;       for (int m = 0; m < 4; ++m)
; #pragma unroll
;         for (int j = 0; j < 4; ++j) {
;           const int rowl = ai * 128 + wr * 64 + m * 16 + fq * 4 + j;
;           const float r = rr[rowl];
; #pragma unroll
;           for (int bj = 0; bj < 2; ++bj) {
;             const float g = acc[ai][bj][m][0][j] * r, u = acc[ai][bj][m][1][j] * r;
;             const float v = g * sigmoidf_(g) * u;
;             *(GAS unsigned short*)(tb + (off0 + (unsigned)(((ai * 128 + m * 16 + j) * FFP + bj * 64) * 2))) = (unsigned short)f2bf(v);
;           }
;         }
.LBB0_85:
	v_mov_b32_e32 v130, v170
	s_lshl_b32 s17, s37, 10
	v_ashrrev_i32_e32 v132, 2, v130
	v_lshrrev_b32_e32 v143, 2, v130
	v_and_b32_e32 v142, 15, v130
	s_addk_i32 s17, 0x100
	v_and_b32_e32 v132, 0xffffffc0, v132
	v_and_b32_e32 v130, 12, v143
	s_add_i32 s18, s17, 0x20000
	v_or_b32_e32 v136, v132, v130
	v_lshlrev_b32_e32 v132, 2, v132
	v_lshlrev_b32_e32 v130, 2, v130
	v_add3_u32 v130, s18, v132, v130
	ds_read2_b32 v[132:133], v130 offset1:1
	v_mul_lo_u32 v144, v136, s40
	s_lshl_b32 s19, s41, 7
	s_mul_hi_i32 s17, s16, 0xb40
	s_mulk_i32 s16, 0xb40
	s_waitcnt lgkmcnt(0)
	v_mul_f32_e32 v145, v118, v132
	v_mul_f32_e32 v118, 0xbfb8aa3b, v145
	v_exp_f32_e32 v146, v118
	v_and_b32_e32 v118, 48, v143
	v_or3_b32 v118, v144, v118, v142
	v_mul_f32_e32 v126, v126, v132
	v_add_f32_e32 v142, 1.0, v146
	v_rcp_f32_e32 v142, v142
	v_mul_f32_e32 v143, 0xbfb8aa3b, v126
	v_exp_f32_e32 v143, v143
	s_ashr_i32 s20, s19, 31
	v_mul_f32_e32 v114, v114, v132
	v_mul_f32_e32 v142, v145, v142
	s_add_u32 s16, s16, s19
	v_mul_f32_e32 v114, v114, v142
	v_add_f32_e32 v142, 1.0, v143
	s_addc_u32 s17, s17, s20
	v_rcp_f32_e32 v142, v142
	s_lshl_b64 s[16:17], s[16:17], 1
	s_add_u32 s16, s35, s16
	s_addc_u32 s17, s36, s17
	v_lshlrev_b32_e32 v118, 1, v118
	v_cvt_pk_bf16_f32 v114, v114, v114
	ds_read2_b32 v[136:137], v130 offset0:2 offset1:3
	ds_read2_b32 v[138:139], v130 offset0:16 offset1:17
	ds_read2_b32 v[140:141], v130 offset0:18 offset1:19
	global_store_short v118, v114, s[16:17]
	v_mul_f32_e32 v114, v122, v132
	v_mul_f32_e32 v122, v126, v142
	v_mul_f32_e32 v119, v119, v133
	v_mul_f32_e32 v114, v114, v122
	v_mul_f32_e32 v122, 0xbfb8aa3b, v119
	v_exp_f32_e32 v122, v122
	v_mul_f32_e32 v126, v127, v133
	v_mul_f32_e32 v127, 0xbfb8aa3b, v126
	v_exp_f32_e32 v127, v127
	v_add_f32_e32 v122, 1.0, v122
	v_rcp_f32_e32 v122, v122
	v_mul_f32_e32 v115, v115, v133
	v_cvt_pk_bf16_f32 v114, v114, v114
	global_store_short v118, v114, s[16:17] offset:128
	v_mul_f32_e32 v119, v119, v122
	v_mul_f32_e32 v115, v115, v119
	v_add_f32_e32 v119, 1.0, v127
	v_rcp_f32_e32 v119, v119
	v_add_u32_e32 v114, 0x1680, v118
	v_cvt_pk_bf16_f32 v115, v115, v115
	global_store_short v114, v115, s[16:17]
	v_mul_f32_e32 v114, v123, v133
	v_mul_f32_e32 v115, v126, v119
	v_mul_f32_e32 v114, v114, v115
	s_waitcnt lgkmcnt(0)
	v_mul_f32_e32 v115, v120, v136
	v_mul_f32_e32 v119, 0xbfb8aa3b, v115
	v_exp_f32_e32 v119, v119
	v_add_u32_e32 v120, 0x1700, v118
	v_cvt_pk_bf16_f32 v114, v114, v114
	global_store_short v120, v114, s[16:17]
	v_add_f32_e32 v119, 1.0, v119
	v_mul_f32_e32 v120, v128, v136
	v_rcp_f32_e32 v119, v119
	v_mul_f32_e32 v122, 0xbfb8aa3b, v120
	v_exp_f32_e32 v122, v122
	v_mul_f32_e32 v116, v116, v136
	v_mul_f32_e32 v115, v115, v119
	v_mul_f32_e32 v115, v116, v115
	v_add_f32_e32 v116, 1.0, v122
	v_rcp_f32_e32 v116, v116
	v_add_u32_e32 v114, 0x2d00, v118
	v_cvt_pk_bf16_f32 v115, v115, v115
	global_store_short v114, v115, s[16:17]
	v_mul_f32_e32 v114, v124, v136
	v_mul_f32_e32 v115, v120, v116
	v_mul_f32_e32 v114, v114, v115
	v_mul_f32_e32 v115, v121, v137
	v_mul_f32_e32 v116, 0xbfb8aa3b, v115
	v_exp_f32_e32 v116, v116
	v_add_u32_e32 v119, 0x2d80, v118
	v_cvt_pk_bf16_f32 v114, v114, v114
	global_store_short v119, v114, s[16:17]
	v_mul_f32_e32 v119, v129, v137
	v_add_f32_e32 v116, 1.0, v116
	v_mul_f32_e32 v120, 0xbfb8aa3b, v119
	v_rcp_f32_e32 v116, v116
	v_exp_f32_e32 v120, v120
	v_mul_f32_e32 v117, v117, v137
	v_add_u32_e32 v114, 0x4380, v118
	v_mul_f32_e32 v115, v115, v116
	v_add_f32_e32 v116, 1.0, v120
	v_rcp_f32_e32 v116, v116
	v_mul_f32_e32 v115, v117, v115
	v_cvt_pk_bf16_f32 v115, v115, v115
	global_store_short v114, v115, s[16:17]
	v_mul_f32_e32 v114, v125, v137
	v_mul_f32_e32 v115, v119, v116
	v_mul_f32_e32 v102, v102, v138
	v_mul_f32_e32 v114, v114, v115
	v_mul_f32_e32 v115, 0xbfb8aa3b, v102
	v_exp_f32_e32 v115, v115
	v_add_u32_e32 v116, 0x4400, v118
	v_mul_f32_e32 v110, v110, v138
	v_cvt_pk_bf16_f32 v114, v114, v114
	v_add_f32_e32 v115, 1.0, v115
	global_store_short v116, v114, s[16:17]
	v_rcp_f32_e32 v115, v115
	v_mul_f32_e32 v116, 0xbfb8aa3b, v110
	v_exp_f32_e32 v116, v116
	v_mul_f32_e32 v98, v98, v138
	v_mul_f32_e32 v102, v102, v115
	v_mul_f32_e32 v98, v98, v102
	v_add_f32_e32 v102, 1.0, v116
	v_rcp_f32_e32 v102, v102
	v_add_u32_e32 v114, 0x16800, v118
	v_cvt_pk_bf16_f32 v98, v98, v98
	global_store_short v114, v98, s[16:17]
	v_mul_f32_e32 v98, v106, v138
	v_mul_f32_e32 v102, v110, v102
	v_mul_f32_e32 v98, v98, v102
	v_mul_f32_e32 v102, v103, v139
	v_mul_f32_e32 v103, 0xbfb8aa3b, v102
	v_exp_f32_e32 v103, v103
	v_add_u32_e32 v106, 0x16880, v118
	v_cvt_pk_bf16_f32 v98, v98, v98
	global_store_short v106, v98, s[16:17]
	v_add_f32_e32 v103, 1.0, v103
	v_mul_f32_e32 v106, v111, v139
	v_rcp_f32_e32 v103, v103
	v_mul_f32_e32 v110, 0xbfb8aa3b, v106
	v_exp_f32_e32 v110, v110
	v_mul_f32_e32 v99, v99, v139
	v_mul_f32_e32 v102, v102, v103
	v_mul_f32_e32 v99, v99, v102
	v_add_f32_e32 v102, 1.0, v110
	v_rcp_f32_e32 v102, v102
	v_add_u32_e32 v98, 0x17e80, v118
	v_cvt_pk_bf16_f32 v99, v99, v99
	global_store_short v98, v99, s[16:17]
	v_mul_f32_e32 v98, v107, v139
	v_mul_f32_e32 v99, v106, v102
	v_mul_f32_e32 v98, v98, v99
	v_mul_f32_e32 v99, v104, v140
	v_mul_f32_e32 v102, 0xbfb8aa3b, v99
	v_exp_f32_e32 v102, v102
	v_add_u32_e32 v103, 0x17f00, v118
	v_cvt_pk_bf16_f32 v98, v98, v98
	global_store_short v103, v98, s[16:17]
	v_add_f32_e32 v102, 1.0, v102
	v_mul_f32_e32 v103, v112, v140
	v_rcp_f32_e32 v102, v102
	v_mul_f32_e32 v104, 0xbfb8aa3b, v103
	v_exp_f32_e32 v104, v104
	v_mul_f32_e32 v100, v100, v140
	v_mul_f32_e32 v99, v99, v102
	v_mul_f32_e32 v99, v100, v99
	v_add_f32_e32 v100, 1.0, v104
	v_rcp_f32_e32 v100, v100
	v_add_u32_e32 v98, 0x19500, v118
	v_cvt_pk_bf16_f32 v99, v99, v99
	global_store_short v98, v99, s[16:17]
	v_mul_f32_e32 v98, v108, v140
	v_mul_f32_e32 v99, v103, v100
	v_mul_f32_e32 v98, v98, v99
	v_mul_f32_e32 v99, v105, v141
	v_mul_f32_e32 v100, 0xbfb8aa3b, v99
	v_exp_f32_e32 v100, v100
	v_add_u32_e32 v102, 0x19580, v118
	v_cvt_pk_bf16_f32 v98, v98, v98
	global_store_short v102, v98, s[16:17]
	v_mul_f32_e32 v102, v113, v141
	v_add_f32_e32 v100, 1.0, v100
	v_mul_f32_e32 v103, 0xbfb8aa3b, v102
	v_rcp_f32_e32 v100, v100
	v_exp_f32_e32 v103, v103
	v_mul_f32_e32 v101, v101, v141
	v_add_u32_e32 v98, 0x1ab80, v118
	v_mul_f32_e32 v99, v99, v100
	v_add_f32_e32 v100, 1.0, v103
	v_rcp_f32_e32 v100, v100
	v_mul_f32_e32 v99, v101, v99
	v_cvt_pk_bf16_f32 v99, v99, v99
	global_store_short v98, v99, s[16:17]
	v_mul_f32_e32 v98, v109, v141
	v_mul_f32_e32 v99, v102, v100
	v_mul_f32_e32 v100, v98, v99
	ds_read2_b32 v[98:99], v130 offset0:32 offset1:33
	v_add_u32_e32 v108, 0x1ac00, v118
	v_cvt_pk_bf16_f32 v106, v100, v100
	ds_read2_b32 v[100:101], v130 offset0:34 offset1:35
	ds_read2_b32 v[102:103], v130 offset0:48 offset1:49
	ds_read2_b32 v[104:105], v130 offset0:50 offset1:51
	global_store_short v108, v106, s[16:17]
	s_waitcnt lgkmcnt(0)
; #define GAS __attribute__((address_space(1)))
; __device__ __forceinline__ unsigned f2bf(float f) { return pk2(f, f) & 0xffffu; }
; __device__ __forceinline__ float sigmoidf_(float v) { return __builtin_amdgcn_rcpf(1.f + __builtin_amdgcn_exp2f(-LOG2E * v)); }
; __device__ __forceinline__ void phase_up(int pass) {
;     ...
; #pragma unroll
;     for (int ai = 0; ai < 2; ++ai)
; #pragma unroll
;       for (int m = 0; m < 4; ++m)
; #pragma unroll
;         for (int j = 0; j < 4; ++j) {
;           const int rowl = ai * 128 + wr * 64 + m * 16 + fq * 4 + j;
;           const float r = rr[rowl];
; #pragma unroll
;           for (int bj = 0; bj < 2; ++bj) {
;             const float g = acc[ai][bj][m][0][j] * r, u = acc[ai][bj][m][1][j] * r;
;             const float v = g * sigmoidf_(g) * u;
;             *(GAS unsigned short*)(tb + (off0 + (unsigned)(((ai * 128 + m * 16 + j) * FFP + bj * 64) * 2))) = (unsigned short)f2bf(v);
;           }
;         }
	v_mul_f32_e32 v86, v86, v98
	v_mul_f32_e32 v107, 0xbfb8aa3b, v86
	v_exp_f32_e32 v107, v107
	v_mul_f32_e32 v94, v94, v98
	v_mul_f32_e32 v108, 0xbfb8aa3b, v94
	v_exp_f32_e32 v108, v108
	v_add_f32_e32 v107, 1.0, v107
	v_rcp_f32_e32 v107, v107
	v_mul_f32_e32 v82, v82, v98
	v_add_u32_e32 v106, 0x2d000, v118
	v_mul_f32_e32 v83, v83, v99
	v_mul_f32_e32 v86, v86, v107
	v_mul_f32_e32 v82, v82, v86
	v_add_f32_e32 v86, 1.0, v108
	v_rcp_f32_e32 v86, v86
	v_cvt_pk_bf16_f32 v82, v82, v82
	global_store_short v106, v82, s[16:17]
	v_mul_f32_e32 v82, v90, v98
	v_mul_f32_e32 v86, v94, v86
	v_mul_f32_e32 v82, v82, v86
	v_mul_f32_e32 v86, v87, v99
	v_mul_f32_e32 v87, 0xbfb8aa3b, v86
	v_exp_f32_e32 v87, v87
	v_add_u32_e32 v90, 0x2d080, v118
	v_cvt_pk_bf16_f32 v82, v82, v82
	global_store_short v90, v82, s[16:17]
	v_add_f32_e32 v87, 1.0, v87
	v_mul_f32_e32 v90, v95, v99
	v_rcp_f32_e32 v87, v87
	v_mul_f32_e32 v94, 0xbfb8aa3b, v90
	v_exp_f32_e32 v94, v94
	v_add_u32_e32 v82, 0x2e680, v118
	v_mul_f32_e32 v86, v86, v87
	v_mul_f32_e32 v83, v83, v86
	v_add_f32_e32 v86, 1.0, v94
	v_rcp_f32_e32 v86, v86
	v_cvt_pk_bf16_f32 v83, v83, v83
	global_store_short v82, v83, s[16:17]
	v_mul_f32_e32 v82, v91, v99
	v_mul_f32_e32 v83, v90, v86
	v_mul_f32_e32 v82, v82, v83
	v_mul_f32_e32 v83, v88, v100
	v_mul_f32_e32 v86, 0xbfb8aa3b, v83
	v_exp_f32_e32 v86, v86
	v_add_u32_e32 v87, 0x2e700, v118
	v_cvt_pk_bf16_f32 v82, v82, v82
	global_store_short v87, v82, s[16:17]
	v_add_f32_e32 v86, 1.0, v86
	v_mul_f32_e32 v87, v96, v100
	v_rcp_f32_e32 v86, v86
	v_mul_f32_e32 v88, 0xbfb8aa3b, v87
	v_exp_f32_e32 v88, v88
	v_mul_f32_e32 v84, v84, v100
	v_mul_f32_e32 v83, v83, v86
	v_mul_f32_e32 v83, v84, v83
	v_add_f32_e32 v84, 1.0, v88
	v_rcp_f32_e32 v84, v84
	v_add_u32_e32 v82, 0x2fd00, v118
	v_cvt_pk_bf16_f32 v83, v83, v83
	global_store_short v82, v83, s[16:17]
	v_mul_f32_e32 v82, v92, v100
	v_mul_f32_e32 v83, v87, v84
	v_mul_f32_e32 v82, v82, v83
	v_mul_f32_e32 v83, v89, v101
	v_mul_f32_e32 v84, 0xbfb8aa3b, v83
	v_exp_f32_e32 v84, v84
	v_add_u32_e32 v86, 0x2fd80, v118
	v_cvt_pk_bf16_f32 v82, v82, v82
	global_store_short v86, v82, s[16:17]
	v_mul_f32_e32 v86, v97, v101
	v_add_f32_e32 v84, 1.0, v84
	v_mul_f32_e32 v87, 0xbfb8aa3b, v86
	v_rcp_f32_e32 v84, v84
	v_exp_f32_e32 v87, v87
	v_mul_f32_e32 v85, v85, v101
	v_add_u32_e32 v82, 0x31380, v118
	v_mul_f32_e32 v83, v83, v84
	v_add_f32_e32 v84, 1.0, v87
	v_rcp_f32_e32 v84, v84
	v_mul_f32_e32 v83, v85, v83
	v_cvt_pk_bf16_f32 v83, v83, v83
	global_store_short v82, v83, s[16:17]
	v_mul_f32_e32 v82, v93, v101
	v_mul_f32_e32 v83, v86, v84
	v_mul_f32_e32 v70, v70, v102
	v_mul_f32_e32 v82, v82, v83
	v_mul_f32_e32 v83, 0xbfb8aa3b, v70
	v_exp_f32_e32 v83, v83
	v_add_u32_e32 v84, 0x31400, v118
	v_mul_f32_e32 v78, v78, v102
	v_cvt_pk_bf16_f32 v82, v82, v82
	v_add_f32_e32 v83, 1.0, v83
	global_store_short v84, v82, s[16:17]
	v_rcp_f32_e32 v83, v83
	v_mul_f32_e32 v84, 0xbfb8aa3b, v78
	v_exp_f32_e32 v84, v84
	v_mul_f32_e32 v66, v66, v102
	v_mul_f32_e32 v70, v70, v83
	v_mul_f32_e32 v66, v66, v70
	v_add_f32_e32 v70, 1.0, v84
	v_rcp_f32_e32 v70, v70
	v_add_u32_e32 v82, 0x43800, v118
	v_cvt_pk_bf16_f32 v66, v66, v66
	global_store_short v82, v66, s[16:17]
	v_mul_f32_e32 v66, v74, v102
	v_mul_f32_e32 v70, v78, v70
	v_mul_f32_e32 v66, v66, v70
	v_mul_f32_e32 v70, v71, v103
	v_mul_f32_e32 v71, 0xbfb8aa3b, v70
	v_exp_f32_e32 v71, v71
	v_add_u32_e32 v74, 0x43880, v118
	v_cvt_pk_bf16_f32 v66, v66, v66
	global_store_short v74, v66, s[16:17]
	v_add_f32_e32 v71, 1.0, v71
	v_mul_f32_e32 v74, v79, v103
	v_rcp_f32_e32 v71, v71
	v_mul_f32_e32 v78, 0xbfb8aa3b, v74
	v_exp_f32_e32 v78, v78
	v_mul_f32_e32 v67, v67, v103
	v_mul_f32_e32 v70, v70, v71
	v_mul_f32_e32 v67, v67, v70
	v_add_f32_e32 v70, 1.0, v78
	v_rcp_f32_e32 v70, v70
	v_add_u32_e32 v66, 0x44e80, v118
	v_cvt_pk_bf16_f32 v67, v67, v67
	global_store_short v66, v67, s[16:17]
	v_mul_f32_e32 v66, v75, v103
	v_mul_f32_e32 v67, v74, v70
	v_mul_f32_e32 v66, v66, v67
	v_mul_f32_e32 v67, v72, v104
	v_mul_f32_e32 v70, 0xbfb8aa3b, v67
	v_exp_f32_e32 v70, v70
	v_add_u32_e32 v71, 0x44f00, v118
	v_cvt_pk_bf16_f32 v66, v66, v66
	global_store_short v71, v66, s[16:17]
	v_add_f32_e32 v70, 1.0, v70
	v_mul_f32_e32 v71, v80, v104
	v_rcp_f32_e32 v70, v70
	v_mul_f32_e32 v72, 0xbfb8aa3b, v71
	v_exp_f32_e32 v72, v72
	v_mul_f32_e32 v68, v68, v104
	v_mul_f32_e32 v67, v67, v70
	v_mul_f32_e32 v67, v68, v67
	v_add_f32_e32 v68, 1.0, v72
	v_rcp_f32_e32 v68, v68
	v_add_u32_e32 v66, 0x46500, v118
	v_cvt_pk_bf16_f32 v67, v67, v67
	global_store_short v66, v67, s[16:17]
	v_mul_f32_e32 v66, v76, v104
	v_mul_f32_e32 v67, v71, v68
	v_mul_f32_e32 v66, v66, v67
	v_mul_f32_e32 v67, v73, v105
	v_mul_f32_e32 v68, 0xbfb8aa3b, v67
	v_exp_f32_e32 v68, v68
	v_add_u32_e32 v70, 0x46580, v118
	v_cvt_pk_bf16_f32 v66, v66, v66
	global_store_short v70, v66, s[16:17]
	v_mul_f32_e32 v70, v81, v105
	v_add_f32_e32 v68, 1.0, v68
	v_mul_f32_e32 v71, 0xbfb8aa3b, v70
	v_rcp_f32_e32 v68, v68
	v_exp_f32_e32 v71, v71
	v_mul_f32_e32 v69, v69, v105
	v_add_u32_e32 v66, 0x47b80, v118
	v_mul_f32_e32 v67, v67, v68
	v_add_f32_e32 v68, 1.0, v71
	v_rcp_f32_e32 v68, v68
	v_mul_f32_e32 v67, v69, v67
	v_cvt_pk_bf16_f32 v67, v67, v67
	global_store_short v66, v67, s[16:17]
	v_mul_f32_e32 v66, v77, v105
	v_mul_f32_e32 v67, v70, v68
	v_mul_f32_e32 v68, v66, v67
	ds_read2_b32 v[66:67], v130 offset0:128 offset1:129
	v_add_u32_e32 v76, 0x47c00, v118
	v_cvt_pk_bf16_f32 v74, v68, v68
	ds_read2_b32 v[68:69], v130 offset0:130 offset1:131
	ds_read2_b32 v[70:71], v130 offset0:144 offset1:145
	ds_read2_b32 v[72:73], v130 offset0:146 offset1:147
	global_store_short v76, v74, s[16:17]
	s_waitcnt lgkmcnt(0)
; #define GAS __attribute__((address_space(1)))
; __device__ __forceinline__ unsigned f2bf(float f) { return pk2(f, f) & 0xffffu; }
; __device__ __forceinline__ float sigmoidf_(float v) { return __builtin_amdgcn_rcpf(1.f + __builtin_amdgcn_exp2f(-LOG2E * v)); }
; __device__ __forceinline__ void phase_up(int pass) {
;     ...
; #pragma unroll
;     for (int ai = 0; ai < 2; ++ai)
; #pragma unroll
;       for (int m = 0; m < 4; ++m)
; #pragma unroll
;         for (int j = 0; j < 4; ++j) {
;           const int rowl = ai * 128 + wr * 64 + m * 16 + fq * 4 + j;
;           const float r = rr[rowl];
; #pragma unroll
;           for (int bj = 0; bj < 2; ++bj) {
;             const float g = acc[ai][bj][m][0][j] * r, u = acc[ai][bj][m][1][j] * r;
;             const float v = g * sigmoidf_(g) * u;
;             *(GAS unsigned short*)(tb + (off0 + (unsigned)(((ai * 128 + m * 16 + j) * FFP + bj * 64) * 2))) = (unsigned short)f2bf(v);
;           }
;         }
	v_mul_f32_e32 v54, v54, v66
	v_mul_f32_e32 v75, 0xbfb8aa3b, v54
	v_exp_f32_e32 v75, v75
	v_mul_f32_e32 v62, v62, v66
	v_mul_f32_e32 v76, 0xbfb8aa3b, v62
	v_exp_f32_e32 v76, v76
	v_add_f32_e32 v75, 1.0, v75
	v_rcp_f32_e32 v75, v75
	v_mul_f32_e32 v50, v50, v66
	v_add_u32_e32 v74, 0xb4000, v118
	v_mul_f32_e32 v51, v51, v67
	v_mul_f32_e32 v54, v54, v75
	v_mul_f32_e32 v50, v50, v54
	v_add_f32_e32 v54, 1.0, v76
	v_rcp_f32_e32 v54, v54
	v_cvt_pk_bf16_f32 v50, v50, v50
	global_store_short v74, v50, s[16:17]
	v_mul_f32_e32 v50, v58, v66
	v_mul_f32_e32 v54, v62, v54
	v_mul_f32_e32 v50, v50, v54
	v_mul_f32_e32 v54, v55, v67
	v_mul_f32_e32 v55, 0xbfb8aa3b, v54
	v_exp_f32_e32 v55, v55
	v_add_u32_e32 v58, 0xb4080, v118
	v_cvt_pk_bf16_f32 v50, v50, v50
	global_store_short v58, v50, s[16:17]
	v_add_f32_e32 v55, 1.0, v55
	v_mul_f32_e32 v58, v63, v67
	v_rcp_f32_e32 v55, v55
	v_mul_f32_e32 v62, 0xbfb8aa3b, v58
	v_exp_f32_e32 v62, v62
	v_add_u32_e32 v50, 0xb5680, v118
	v_mul_f32_e32 v54, v54, v55
	v_mul_f32_e32 v51, v51, v54
	v_add_f32_e32 v54, 1.0, v62
	v_rcp_f32_e32 v54, v54
	v_cvt_pk_bf16_f32 v51, v51, v51
	global_store_short v50, v51, s[16:17]
	v_mul_f32_e32 v50, v59, v67
	v_mul_f32_e32 v51, v58, v54
	v_mul_f32_e32 v50, v50, v51
	v_mul_f32_e32 v51, v56, v68
	v_mul_f32_e32 v54, 0xbfb8aa3b, v51
	v_exp_f32_e32 v54, v54
	v_add_u32_e32 v55, 0xb5700, v118
	v_cvt_pk_bf16_f32 v50, v50, v50
	global_store_short v55, v50, s[16:17]
	v_add_f32_e32 v54, 1.0, v54
	v_mul_f32_e32 v55, v64, v68
	v_rcp_f32_e32 v54, v54
	v_mul_f32_e32 v56, 0xbfb8aa3b, v55
	v_exp_f32_e32 v56, v56
	v_mul_f32_e32 v52, v52, v68
	v_mul_f32_e32 v51, v51, v54
	v_mul_f32_e32 v51, v52, v51
	v_add_f32_e32 v52, 1.0, v56
	v_rcp_f32_e32 v52, v52
	v_add_u32_e32 v50, 0xb6d00, v118
	v_cvt_pk_bf16_f32 v51, v51, v51
	global_store_short v50, v51, s[16:17]
	v_mul_f32_e32 v50, v60, v68
	v_mul_f32_e32 v51, v55, v52
	v_mul_f32_e32 v50, v50, v51
	v_mul_f32_e32 v51, v57, v69
	v_mul_f32_e32 v52, 0xbfb8aa3b, v51
	v_exp_f32_e32 v52, v52
	v_add_u32_e32 v54, 0xb6d80, v118
	v_cvt_pk_bf16_f32 v50, v50, v50
	global_store_short v54, v50, s[16:17]
	v_mul_f32_e32 v54, v65, v69
	v_add_f32_e32 v52, 1.0, v52
	v_mul_f32_e32 v55, 0xbfb8aa3b, v54
	v_rcp_f32_e32 v52, v52
	v_exp_f32_e32 v55, v55
	v_mul_f32_e32 v53, v53, v69
	v_add_u32_e32 v50, 0xb8380, v118
	v_mul_f32_e32 v51, v51, v52
	v_add_f32_e32 v52, 1.0, v55
	v_rcp_f32_e32 v52, v52
	v_mul_f32_e32 v51, v53, v51
	v_cvt_pk_bf16_f32 v51, v51, v51
	global_store_short v50, v51, s[16:17]
	v_mul_f32_e32 v50, v61, v69
	v_mul_f32_e32 v51, v54, v52
	v_mul_f32_e32 v42, v42, v70
	v_mul_f32_e32 v50, v50, v51
	v_mul_f32_e32 v51, 0xbfb8aa3b, v42
	v_exp_f32_e32 v51, v51
	v_add_u32_e32 v52, 0xb8400, v118
	v_mul_f32_e32 v46, v46, v70
	v_cvt_pk_bf16_f32 v50, v50, v50
	v_add_f32_e32 v51, 1.0, v51
	global_store_short v52, v50, s[16:17]
	v_rcp_f32_e32 v51, v51
	v_mul_f32_e32 v52, 0xbfb8aa3b, v46
	v_exp_f32_e32 v52, v52
	v_mul_f32_e32 v34, v34, v70
	v_mul_f32_e32 v42, v42, v51
	v_mul_f32_e32 v34, v34, v42
	v_add_f32_e32 v42, 1.0, v52
	v_rcp_f32_e32 v42, v42
	v_add_u32_e32 v50, 0xca800, v118
	v_cvt_pk_bf16_f32 v34, v34, v34
	global_store_short v50, v34, s[16:17]
	v_mul_f32_e32 v34, v38, v70
	v_mul_f32_e32 v38, v46, v42
	v_mul_f32_e32 v34, v34, v38
	v_mul_f32_e32 v38, v43, v71
	v_mul_f32_e32 v42, 0xbfb8aa3b, v38
	v_exp_f32_e32 v42, v42
	v_add_u32_e32 v43, 0xca880, v118
	v_cvt_pk_bf16_f32 v34, v34, v34
	global_store_short v43, v34, s[16:17]
	v_add_f32_e32 v42, 1.0, v42
	v_mul_f32_e32 v43, v47, v71
	v_rcp_f32_e32 v42, v42
	v_mul_f32_e32 v46, 0xbfb8aa3b, v43
	v_exp_f32_e32 v46, v46
	v_mul_f32_e32 v35, v35, v71
	v_mul_f32_e32 v38, v38, v42
	v_mul_f32_e32 v35, v35, v38
	v_add_f32_e32 v38, 1.0, v46
	v_rcp_f32_e32 v38, v38
	v_add_u32_e32 v34, 0xcbe80, v118
	v_cvt_pk_bf16_f32 v35, v35, v35
	global_store_short v34, v35, s[16:17]
	v_mul_f32_e32 v34, v39, v71
	v_mul_f32_e32 v35, v43, v38
	v_mul_f32_e32 v34, v34, v35
	v_mul_f32_e32 v35, v44, v72
	v_mul_f32_e32 v38, 0xbfb8aa3b, v35
	v_exp_f32_e32 v38, v38
	v_add_u32_e32 v39, 0xcbf00, v118
	v_cvt_pk_bf16_f32 v34, v34, v34
	global_store_short v39, v34, s[16:17]
	v_add_f32_e32 v38, 1.0, v38
	v_mul_f32_e32 v39, v48, v72
	v_rcp_f32_e32 v38, v38
	v_mul_f32_e32 v42, 0xbfb8aa3b, v39
	v_exp_f32_e32 v42, v42
	v_mul_f32_e32 v36, v36, v72
	v_mul_f32_e32 v35, v35, v38
	v_mul_f32_e32 v35, v36, v35
	v_add_f32_e32 v36, 1.0, v42
	v_rcp_f32_e32 v36, v36
	v_add_u32_e32 v34, 0xcd500, v118
	v_cvt_pk_bf16_f32 v35, v35, v35
	global_store_short v34, v35, s[16:17]
	v_mul_f32_e32 v34, v40, v72
	v_mul_f32_e32 v35, v39, v36
	v_mul_f32_e32 v34, v34, v35
	v_mul_f32_e32 v35, v45, v73
	v_mul_f32_e32 v36, 0xbfb8aa3b, v35
	v_exp_f32_e32 v36, v36
	v_add_u32_e32 v38, 0xcd580, v118
	v_cvt_pk_bf16_f32 v34, v34, v34
	global_store_short v38, v34, s[16:17]
	v_mul_f32_e32 v38, v49, v73
	v_add_f32_e32 v36, 1.0, v36
	v_mul_f32_e32 v39, 0xbfb8aa3b, v38
	v_rcp_f32_e32 v36, v36
	v_exp_f32_e32 v39, v39
	v_mul_f32_e32 v37, v37, v73
	v_add_u32_e32 v34, 0xceb80, v118
	v_mul_f32_e32 v35, v35, v36
	v_add_f32_e32 v36, 1.0, v39
	v_rcp_f32_e32 v36, v36
	v_mul_f32_e32 v35, v37, v35
	v_cvt_pk_bf16_f32 v35, v35, v35
	global_store_short v34, v35, s[16:17]
	v_mul_f32_e32 v34, v41, v73
	v_mul_f32_e32 v35, v38, v36
	v_mul_f32_e32 v36, v34, v35
	ds_read2_b32 v[34:35], v130 offset0:160 offset1:161
	v_add_u32_e32 v44, 0xcec00, v118
	v_cvt_pk_bf16_f32 v42, v36, v36
	ds_read2_b32 v[36:37], v130 offset0:162 offset1:163
	ds_read2_b32 v[38:39], v130 offset0:176 offset1:177
	ds_read2_b32 v[40:41], v130 offset0:178 offset1:179
	global_store_short v44, v42, s[16:17]
	s_waitcnt lgkmcnt(0)
; #define GAS __attribute__((address_space(1)))
; __device__ __forceinline__ unsigned f2bf(float f) { return pk2(f, f) & 0xffffu; }
; __device__ __forceinline__ float sigmoidf_(float v) { return __builtin_amdgcn_rcpf(1.f + __builtin_amdgcn_exp2f(-LOG2E * v)); }
; __device__ __forceinline__ void phase_up(int pass) {
;     ...
; #pragma unroll
;     for (int ai = 0; ai < 2; ++ai)
; #pragma unroll
;       for (int m = 0; m < 4; ++m)
; #pragma unroll
;         for (int j = 0; j < 4; ++j) {
;           const int rowl = ai * 128 + wr * 64 + m * 16 + fq * 4 + j;
;           const float r = rr[rowl];
; #pragma unroll
;           for (int bj = 0; bj < 2; ++bj) {
;             const float g = acc[ai][bj][m][0][j] * r, u = acc[ai][bj][m][1][j] * r;
;             const float v = g * sigmoidf_(g) * u;
;             *(GAS unsigned short*)(tb + (off0 + (unsigned)(((ai * 128 + m * 16 + j) * FFP + bj * 64) * 2))) = (unsigned short)f2bf(v);
;           }
;         }
;     par ^= 1;
	v_mul_f32_e32 v22, v22, v34
	v_mul_f32_e32 v43, 0xbfb8aa3b, v22
	v_exp_f32_e32 v43, v43
	v_mul_f32_e32 v30, v30, v34
	v_mul_f32_e32 v44, 0xbfb8aa3b, v30
	v_exp_f32_e32 v44, v44
	v_add_f32_e32 v43, 1.0, v43
	v_rcp_f32_e32 v43, v43
	v_mul_f32_e32 v18, v18, v34
	v_add_u32_e32 v42, 0xe1000, v118
	v_mul_f32_e32 v19, v19, v35
	v_mul_f32_e32 v22, v22, v43
	v_mul_f32_e32 v18, v18, v22
	v_add_f32_e32 v22, 1.0, v44
	v_rcp_f32_e32 v22, v22
	v_cvt_pk_bf16_f32 v18, v18, v18
	global_store_short v42, v18, s[16:17]
	v_mul_f32_e32 v18, v26, v34
	v_mul_f32_e32 v22, v30, v22
	v_mul_f32_e32 v18, v18, v22
	v_mul_f32_e32 v22, v23, v35
	v_mul_f32_e32 v23, 0xbfb8aa3b, v22
	v_exp_f32_e32 v23, v23
	v_add_u32_e32 v26, 0xe1080, v118
	v_cvt_pk_bf16_f32 v18, v18, v18
	global_store_short v26, v18, s[16:17]
	v_add_f32_e32 v23, 1.0, v23
	v_mul_f32_e32 v26, v31, v35
	v_rcp_f32_e32 v23, v23
	v_mul_f32_e32 v30, 0xbfb8aa3b, v26
	v_exp_f32_e32 v30, v30
	v_add_u32_e32 v18, 0xe2680, v118
	v_mul_f32_e32 v22, v22, v23
	v_mul_f32_e32 v19, v19, v22
	v_add_f32_e32 v22, 1.0, v30
	v_rcp_f32_e32 v22, v22
	v_cvt_pk_bf16_f32 v19, v19, v19
	global_store_short v18, v19, s[16:17]
	v_mul_f32_e32 v18, v27, v35
	v_mul_f32_e32 v19, v26, v22
	v_mul_f32_e32 v18, v18, v19
	v_mul_f32_e32 v19, v24, v36
	v_mul_f32_e32 v22, 0xbfb8aa3b, v19
	v_exp_f32_e32 v22, v22
	v_add_u32_e32 v23, 0xe2700, v118
	v_cvt_pk_bf16_f32 v18, v18, v18
	global_store_short v23, v18, s[16:17]
	v_add_f32_e32 v22, 1.0, v22
	v_mul_f32_e32 v23, v32, v36
	v_rcp_f32_e32 v22, v22
	v_mul_f32_e32 v24, 0xbfb8aa3b, v23
	v_exp_f32_e32 v24, v24
	v_mul_f32_e32 v20, v20, v36
	v_mul_f32_e32 v19, v19, v22
	v_mul_f32_e32 v19, v20, v19
	v_add_f32_e32 v20, 1.0, v24
	v_rcp_f32_e32 v20, v20
	v_add_u32_e32 v18, 0xe3d00, v118
	v_cvt_pk_bf16_f32 v19, v19, v19
	global_store_short v18, v19, s[16:17]
	v_mul_f32_e32 v18, v28, v36
	v_mul_f32_e32 v19, v23, v20
	v_mul_f32_e32 v18, v18, v19
	v_mul_f32_e32 v19, v25, v37
	v_mul_f32_e32 v20, 0xbfb8aa3b, v19
	v_exp_f32_e32 v20, v20
	v_add_u32_e32 v22, 0xe3d80, v118
	v_cvt_pk_bf16_f32 v18, v18, v18
	global_store_short v22, v18, s[16:17]
	v_mul_f32_e32 v22, v33, v37
	v_add_f32_e32 v20, 1.0, v20
	v_mul_f32_e32 v23, 0xbfb8aa3b, v22
	v_rcp_f32_e32 v20, v20
	v_exp_f32_e32 v23, v23
	v_mul_f32_e32 v21, v21, v37
	v_add_u32_e32 v18, 0xe5380, v118
	v_mul_f32_e32 v19, v19, v20
	v_add_f32_e32 v20, 1.0, v23
	v_rcp_f32_e32 v20, v20
	v_mul_f32_e32 v19, v21, v19
	v_cvt_pk_bf16_f32 v19, v19, v19
	global_store_short v18, v19, s[16:17]
	v_mul_f32_e32 v18, v29, v37
	v_mul_f32_e32 v19, v22, v20
	v_mul_f32_e32 v10, v10, v38
	v_mul_f32_e32 v18, v18, v19
	v_mul_f32_e32 v19, 0xbfb8aa3b, v10
	v_exp_f32_e32 v19, v19
	v_add_u32_e32 v20, 0xe5400, v118
	v_mul_f32_e32 v14, v14, v38
	v_cvt_pk_bf16_f32 v18, v18, v18
	v_add_f32_e32 v19, 1.0, v19
	global_store_short v20, v18, s[16:17]
	v_rcp_f32_e32 v19, v19
	v_mul_f32_e32 v20, 0xbfb8aa3b, v14
	v_exp_f32_e32 v20, v20
	v_mul_f32_e32 v2, v2, v38
	v_mul_f32_e32 v10, v10, v19
	v_mul_f32_e32 v2, v2, v10
	v_add_f32_e32 v10, 1.0, v20
	v_rcp_f32_e32 v10, v10
	v_add_u32_e32 v18, 0xf7800, v118
	v_cvt_pk_bf16_f32 v2, v2, v2
	global_store_short v18, v2, s[16:17]
	v_mul_f32_e32 v2, v6, v38
	v_mul_f32_e32 v6, v14, v10
	v_mul_f32_e32 v2, v2, v6
	v_mul_f32_e32 v6, v11, v39
	v_mul_f32_e32 v10, 0xbfb8aa3b, v6
	v_exp_f32_e32 v10, v10
	v_add_u32_e32 v11, 0xf7880, v118
	v_cvt_pk_bf16_f32 v2, v2, v2
	global_store_short v11, v2, s[16:17]
	v_add_f32_e32 v10, 1.0, v10
	v_mul_f32_e32 v11, v15, v39
	v_rcp_f32_e32 v10, v10
	v_mul_f32_e32 v14, 0xbfb8aa3b, v11
	v_exp_f32_e32 v14, v14
	v_mul_f32_e32 v3, v3, v39
	v_mul_f32_e32 v6, v6, v10
	v_mul_f32_e32 v3, v3, v6
	v_add_f32_e32 v6, 1.0, v14
	v_rcp_f32_e32 v6, v6
	v_add_u32_e32 v2, 0xf8e80, v118
	v_cvt_pk_bf16_f32 v3, v3, v3
	global_store_short v2, v3, s[16:17]
	v_mul_f32_e32 v2, v7, v39
	v_mul_f32_e32 v3, v11, v6
	v_mul_f32_e32 v2, v2, v3
	v_mul_f32_e32 v3, v12, v40
	v_mul_f32_e32 v6, 0xbfb8aa3b, v3
	v_exp_f32_e32 v6, v6
	v_add_u32_e32 v7, 0xf8f00, v118
	v_cvt_pk_bf16_f32 v2, v2, v2
	global_store_short v7, v2, s[16:17]
	v_add_f32_e32 v6, 1.0, v6
	v_mul_f32_e32 v7, v16, v40
	v_rcp_f32_e32 v6, v6
	v_mul_f32_e32 v10, 0xbfb8aa3b, v7
	v_exp_f32_e32 v10, v10
	v_mul_f32_e32 v4, v4, v40
	v_mul_f32_e32 v3, v3, v6
	v_mul_f32_e32 v3, v4, v3
	v_add_f32_e32 v4, 1.0, v10
	v_rcp_f32_e32 v4, v4
	v_add_u32_e32 v2, 0xfa500, v118
	v_cvt_pk_bf16_f32 v3, v3, v3
	global_store_short v2, v3, s[16:17]
	v_mul_f32_e32 v2, v8, v40
	v_mul_f32_e32 v3, v7, v4
	v_mul_f32_e32 v2, v2, v3
	v_mul_f32_e32 v3, v13, v41
	v_mul_f32_e32 v4, 0xbfb8aa3b, v3
	v_exp_f32_e32 v4, v4
	v_add_u32_e32 v6, 0xfa580, v118
	v_cvt_pk_bf16_f32 v2, v2, v2
	global_store_short v6, v2, s[16:17]
	v_mul_f32_e32 v6, v17, v41
	v_add_f32_e32 v4, 1.0, v4
	v_mul_f32_e32 v7, 0xbfb8aa3b, v6
	v_rcp_f32_e32 v4, v4
	v_exp_f32_e32 v7, v7
	v_mul_f32_e32 v5, v5, v41
	v_add_u32_e32 v2, 0xfbb80, v118
	v_mul_f32_e32 v3, v3, v4
	v_add_f32_e32 v4, 1.0, v7
	v_rcp_f32_e32 v4, v4
	v_mul_f32_e32 v3, v5, v3
	v_cvt_pk_bf16_f32 v3, v3, v3
	global_store_short v2, v3, s[16:17]
	v_mul_f32_e32 v2, v9, v41
	v_mul_f32_e32 v3, v6, v4
	v_mul_f32_e32 v2, v2, v3
	v_add_u32_e32 v3, 0xfbc00, v118
	s_xor_b32 s37, s37, 1
	s_andn2_b64 vcc, exec, s[14:15]
	s_mov_b32 s41, s22
	v_cvt_pk_bf16_f32 v2, v2, v2
	global_store_short v3, v2, s[16:17]
	s_cbranch_vccz .LBB0_95

; #define LAS __attribute__((address_space(3)))
; #define GAS __attribute__((address_space(1)))
; __device__ __forceinline__ unsigned pk2(float lo, float hi) { unsigned r; asm("s_nop 1\n\tv_cvt_pk_bf16_f32 %0, %1, %2" : "=v"(r) : "v"(lo), "v"(hi)); return r; }
; __device__ __forceinline__ void tr_wave_job(const GAS float* src0, const GAS float* src1, int ld, int mode, GAS bf16* dst, int K, int ldd, int n0, int k0, int lane, int wid, const GAS float* gk) {
;     ...
;   for (int q = 0; q < 8; ++q) {
;     u32x4 o = {pk2(v[8 * q + 0], v[8 * q + 1]), pk2(v[8 * q + 2], v[8 * q + 3]), pk2(v[8 * q + 4], v[8 * q + 5]), pk2(v[8 * q + 6], v[8 * q + 7])};
;     *(LAS u32x4*)(scr + (lane * 8 + (q ^ (lane & 7))) * 16) = o;
;   }
;   asm volatile("s_waitcnt lgkmcnt(0)" ::: "memory");
;   const int rq = lane & 7;
; #pragma unroll
;   for (int i = 0; i < 8; ++i) {
;     const int r = i * 8 + (lane >> 3);
;     const u32x4 o = *(const LAS u32x4*)(scr + (r * 8 + (rq ^ (r & 7))) * 16);
;     *(GAS u32x4*)(dst + (size_t)(n0 + r) * ldd + k0 + rq * 8) = o;
;   }
;   asm volatile("s_waitcnt lgkmcnt(0)" ::: "memory");
.LBB0_101:
	s_or_b64 exec, exec, s[48:49]
	s_waitcnt vmcnt(62)
	v_cvt_pk_bf16_f32 v12, v14, v15
	s_waitcnt vmcnt(60)
	v_cvt_pk_bf16_f32 v13, v16, v17
	s_waitcnt vmcnt(58)
	v_cvt_pk_bf16_f32 v14, v18, v19
	s_waitcnt vmcnt(56)
	v_cvt_pk_bf16_f32 v15, v20, v21
	v_add_u32_e32 v2, v82, v83
	ds_write_b128 v2, v[12:15]
	s_waitcnt vmcnt(54)
	v_cvt_pk_bf16_f32 v12, v22, v23
	s_waitcnt vmcnt(52)
	v_cvt_pk_bf16_f32 v13, v24, v25
	s_waitcnt vmcnt(50)
	v_cvt_pk_bf16_f32 v14, v26, v27
	s_waitcnt vmcnt(48)
	v_cvt_pk_bf16_f32 v15, v28, v29
	ds_write_b128 v93, v[12:15]
	s_waitcnt vmcnt(46)
	v_cvt_pk_bf16_f32 v12, v30, v31
	s_waitcnt vmcnt(44)
	v_cvt_pk_bf16_f32 v13, v32, v33
	s_waitcnt vmcnt(42)
	v_cvt_pk_bf16_f32 v14, v34, v35
	s_waitcnt vmcnt(40)
	v_cvt_pk_bf16_f32 v15, v36, v37
	ds_write_b128 v94, v[12:15]
	s_waitcnt vmcnt(38)
	v_cvt_pk_bf16_f32 v12, v38, v39
	s_waitcnt vmcnt(36)
	v_cvt_pk_bf16_f32 v13, v40, v41
	s_waitcnt vmcnt(34)
	v_cvt_pk_bf16_f32 v14, v42, v43
	s_waitcnt vmcnt(32)
	v_cvt_pk_bf16_f32 v15, v44, v45
	ds_write_b128 v95, v[12:15]
	s_waitcnt vmcnt(30)
	v_cvt_pk_bf16_f32 v12, v46, v47
	s_waitcnt vmcnt(28)
	v_cvt_pk_bf16_f32 v13, v48, v49
	s_waitcnt vmcnt(26)
	v_cvt_pk_bf16_f32 v14, v50, v51
	s_waitcnt vmcnt(24)
	v_cvt_pk_bf16_f32 v15, v52, v53
	ds_write_b128 v96, v[12:15]
	s_waitcnt vmcnt(22)
	v_cvt_pk_bf16_f32 v12, v54, v55
	s_waitcnt vmcnt(20)
	v_cvt_pk_bf16_f32 v13, v56, v57
	s_waitcnt vmcnt(18)
	v_cvt_pk_bf16_f32 v14, v58, v59
	s_waitcnt vmcnt(16)
	v_cvt_pk_bf16_f32 v15, v60, v61
	ds_write_b128 v97, v[12:15]
	s_waitcnt vmcnt(14)
	v_cvt_pk_bf16_f32 v12, v62, v63
	s_waitcnt vmcnt(12)
	v_cvt_pk_bf16_f32 v13, v64, v65
	s_waitcnt vmcnt(10)
	v_cvt_pk_bf16_f32 v14, v66, v67
	s_waitcnt vmcnt(8)
	v_cvt_pk_bf16_f32 v15, v68, v69
	ds_write_b128 v98, v[12:15]
	s_waitcnt vmcnt(6)
	v_cvt_pk_bf16_f32 v12, v70, v71
	s_waitcnt vmcnt(4)
	v_cvt_pk_bf16_f32 v13, v72, v73
	s_waitcnt vmcnt(2)
	v_cvt_pk_bf16_f32 v14, v74, v75
	s_waitcnt vmcnt(0)
	v_cvt_pk_bf16_f32 v15, v76, v77
	ds_write_b128 v99, v[12:15]
	s_waitcnt lgkmcnt(0)
	v_lshl_add_u64 v[8:9], v[10:11], 1, v[8:9]
	v_mov_b32_e32 v5, v3
	v_lshl_add_u64 v[16:17], v[8:9], 0, v[4:5]
	ds_read_b128 v[8:11], v100
	v_or_b32_e32 v2, v108, v84
	v_ashrrev_i32_e32 v5, 31, v108
	v_mul_lo_u32 v14, v7, v2
	v_mul_lo_u32 v5, v6, v5
	v_mad_u64_u32 v[12:13], s[4:5], v6, v2, 0
	v_add3_u32 v13, v13, v5, v14
	v_lshl_add_u64 v[18:19], v[12:13], 1, v[16:17]
	ds_read_b128 v[12:15], v101
	v_or_b32_e32 v2, v108, v85
	s_waitcnt lgkmcnt(1)
	global_store_dwordx4 v[18:19], v[8:11], off
	v_add_u32_e32 v92, s60, v92
	v_add_u32_e32 v80, s60, v80
	v_mul_lo_u32 v10, v7, v2
	v_mad_u64_u32 v[8:9], s[4:5], v6, v2, 0
	v_add3_u32 v9, v9, v5, v10
	v_lshl_add_u64 v[8:9], v[8:9], 1, v[16:17]
	s_waitcnt lgkmcnt(0)
	global_store_dwordx4 v[8:9], v[12:15], off
	ds_read_b128 v[8:11], v102
	v_or_b32_e32 v2, v108, v86
	v_mul_lo_u32 v14, v7, v2
	v_mad_u64_u32 v[12:13], s[4:5], v6, v2, 0
	v_add3_u32 v13, v13, v5, v14
	v_lshl_add_u64 v[18:19], v[12:13], 1, v[16:17]
	ds_read_b128 v[12:15], v103
	v_or_b32_e32 v2, v108, v87
	s_waitcnt lgkmcnt(1)
	global_store_dwordx4 v[18:19], v[8:11], off
	s_nop 1
	v_mul_lo_u32 v10, v7, v2
	v_mad_u64_u32 v[8:9], s[4:5], v6, v2, 0
	v_add3_u32 v9, v9, v5, v10
	v_lshl_add_u64 v[8:9], v[8:9], 1, v[16:17]
	s_waitcnt lgkmcnt(0)
	global_store_dwordx4 v[8:9], v[12:15], off
	ds_read_b128 v[8:11], v104
	v_or_b32_e32 v2, v108, v88
	v_mul_lo_u32 v14, v7, v2
	v_mad_u64_u32 v[12:13], s[4:5], v6, v2, 0
	v_add3_u32 v13, v13, v5, v14
	v_lshl_add_u64 v[18:19], v[12:13], 1, v[16:17]
	ds_read_b128 v[12:15], v105
	v_or_b32_e32 v2, v108, v89
	s_waitcnt lgkmcnt(1)
	global_store_dwordx4 v[18:19], v[8:11], off
	s_nop 1
	v_mul_lo_u32 v10, v7, v2
	v_mad_u64_u32 v[8:9], s[4:5], v6, v2, 0
	v_add3_u32 v9, v9, v5, v10
	v_lshl_add_u64 v[8:9], v[8:9], 1, v[16:17]
	s_waitcnt lgkmcnt(0)
	global_store_dwordx4 v[8:9], v[12:15], off
	ds_read_b128 v[8:11], v106
	v_or_b32_e32 v2, v108, v90
	v_mul_lo_u32 v14, v7, v2
	v_mad_u64_u32 v[12:13], s[4:5], v6, v2, 0
	v_add3_u32 v13, v13, v5, v14
	v_lshl_add_u64 v[18:19], v[12:13], 1, v[16:17]
	ds_read_b128 v[12:15], v107
	v_or_b32_e32 v2, v108, v91
	s_waitcnt lgkmcnt(1)
	global_store_dwordx4 v[18:19], v[8:11], off
	s_nop 1
	v_mul_lo_u32 v8, v7, v2
	v_mad_u64_u32 v[6:7], s[4:5], v6, v2, 0
	v_add3_u32 v7, v7, v5, v8
	v_lshl_add_u64 v[6:7], v[6:7], 1, v[16:17]
	s_waitcnt lgkmcnt(0)
	global_store_dwordx4 v[6:7], v[12:15], off
	s_waitcnt lgkmcnt(0)
	v_add_u32_e32 v2, 0x13c0, v92
	v_cmp_lt_i32_e64 s[4:5], s69, v2
	s_or_b64 s[46:47], s[4:5], s[46:47]
	s_andn2_b64 exec, exec, s[46:47]
	s_cbranch_execz .LBB0_136

; #define GAS __attribute__((address_space(1)))
; __device__ __forceinline__ unsigned f2bf(float f) { return pk2(f, f) & 0xffffu; }
; __device__ __forceinline__ void convert_late(int part, int brank, int nblocks) {
;     ...
;     for (int i = gtid; i < 8 * DM; i += gn) { const int j = i >> 10, k = i & 1023; ((GAS unsigned short*)(ws + OFF_WF))[i] = (unsigned short)f2bf(((const GAS float*)P.w_in)[(size_t)k * INW + 1536 + j] * ((const GAS float*)P.mix_norm)[k]); }
.LBB0_138:
	v_ashrrev_i32_e32 v8, 10, v2
	v_and_b32_e32 v3, 0x3ff, v2
	v_ashrrev_i32_e32 v9, 31, v8
	v_mad_u64_u32 v[10:11], s[16:17], v3, s15, v[6:7]
	v_lshl_add_u64 v[8:9], v[8:9], 2, v[10:11]
	v_add_co_u32_e32 v8, vcc, 0x1000, v8
	v_lshlrev_b32_e32 v3, 2, v3
	s_nop 0
	v_addc_co_u32_e32 v9, vcc, 0, v9, vcc
	global_load_dword v3, v3, s[4:5]
	v_add_u32_e32 v2, s14, v2
	global_load_dword v8, v[8:9], off offset:2048
	v_cmp_lt_i32_e32 vcc, s6, v2
	s_or_b64 s[10:11], vcc, s[10:11]
	s_waitcnt vmcnt(0)
	v_mul_f32_e32 v3, v8, v3
	v_cvt_pk_bf16_f32 v3, v3, v3
	global_store_short v[4:5], v3, off
	v_lshl_add_u64 v[4:5], v[4:5], 0, s[8:9]
	s_andn2_b64 exec, exec, s[10:11]
	s_cbranch_execnz .LBB0_138

; #define LAS __attribute__((address_space(3)))
; #define GAS __attribute__((address_space(1)))
; __device__ __forceinline__ unsigned pk2(float lo, float hi) { unsigned r; asm("s_nop 1\n\tv_cvt_pk_bf16_f32 %0, %1, %2" : "=v"(r) : "v"(lo), "v"(hi)); return r; }
; __device__ __forceinline__ void tr_wave_job(const GAS float* src0, const GAS float* src1, int ld, int mode, GAS bf16* dst, int K, int ldd, int n0, int k0, int lane, int wid, const GAS float* gk) {
;     ...
;   for (int q = 0; q < 8; ++q) {
;     u32x4 o = {pk2(v[8 * q + 0], v[8 * q + 1]), pk2(v[8 * q + 2], v[8 * q + 3]), pk2(v[8 * q + 4], v[8 * q + 5]), pk2(v[8 * q + 6], v[8 * q + 7])};
;     *(LAS u32x4*)(scr + (lane * 8 + (q ^ (lane & 7))) * 16) = o;
;   }
;   asm volatile("s_waitcnt lgkmcnt(0)" ::: "memory");
;   const int rq = lane & 7;
; #pragma unroll
;   for (int i = 0; i < 8; ++i) {
;     const int r = i * 8 + (lane >> 3);
;     const u32x4 o = *(const LAS u32x4*)(scr + (r * 8 + (rq ^ (r & 7))) * 16);
;     *(GAS u32x4*)(dst + (size_t)(n0 + r) * ldd + k0 + rq * 8) = o;
;   }
;   asm volatile("s_waitcnt lgkmcnt(0)" ::: "memory");
.LBB0_144:
	s_or_b64 exec, exec, s[48:49]
	s_waitcnt vmcnt(62)
	v_cvt_pk_bf16_f32 v12, v14, v15
	s_waitcnt vmcnt(60)
	v_cvt_pk_bf16_f32 v13, v16, v17
	s_waitcnt vmcnt(58)
	v_cvt_pk_bf16_f32 v14, v18, v19
	s_waitcnt vmcnt(56)
	v_cvt_pk_bf16_f32 v15, v20, v21
	v_add_u32_e32 v2, v82, v83
	ds_write_b128 v2, v[12:15]
	s_waitcnt vmcnt(54)
	v_cvt_pk_bf16_f32 v12, v22, v23
	s_waitcnt vmcnt(52)
	v_cvt_pk_bf16_f32 v13, v24, v25
	s_waitcnt vmcnt(50)
	v_cvt_pk_bf16_f32 v14, v26, v27
	s_waitcnt vmcnt(48)
	v_cvt_pk_bf16_f32 v15, v28, v29
	ds_write_b128 v93, v[12:15]
	s_waitcnt vmcnt(46)
	v_cvt_pk_bf16_f32 v12, v30, v31
	s_waitcnt vmcnt(44)
	v_cvt_pk_bf16_f32 v13, v32, v33
	s_waitcnt vmcnt(42)
	v_cvt_pk_bf16_f32 v14, v34, v35
	s_waitcnt vmcnt(40)
	v_cvt_pk_bf16_f32 v15, v36, v37
	ds_write_b128 v94, v[12:15]
	s_waitcnt vmcnt(38)
	v_cvt_pk_bf16_f32 v12, v38, v39
	s_waitcnt vmcnt(36)
	v_cvt_pk_bf16_f32 v13, v40, v41
	s_waitcnt vmcnt(34)
	v_cvt_pk_bf16_f32 v14, v42, v43
	s_waitcnt vmcnt(32)
	v_cvt_pk_bf16_f32 v15, v44, v45
	ds_write_b128 v95, v[12:15]
	s_waitcnt vmcnt(30)
	v_cvt_pk_bf16_f32 v12, v46, v47
	s_waitcnt vmcnt(28)
	v_cvt_pk_bf16_f32 v13, v48, v49
	s_waitcnt vmcnt(26)
	v_cvt_pk_bf16_f32 v14, v50, v51
	s_waitcnt vmcnt(24)
	v_cvt_pk_bf16_f32 v15, v52, v53
	ds_write_b128 v96, v[12:15]
	s_waitcnt vmcnt(22)
	v_cvt_pk_bf16_f32 v12, v54, v55
	s_waitcnt vmcnt(20)
	v_cvt_pk_bf16_f32 v13, v56, v57
	s_waitcnt vmcnt(18)
	v_cvt_pk_bf16_f32 v14, v58, v59
	s_waitcnt vmcnt(16)
	v_cvt_pk_bf16_f32 v15, v60, v61
	ds_write_b128 v97, v[12:15]
	s_waitcnt vmcnt(14)
	v_cvt_pk_bf16_f32 v12, v62, v63
	s_waitcnt vmcnt(12)
	v_cvt_pk_bf16_f32 v13, v64, v65
	s_waitcnt vmcnt(10)
	v_cvt_pk_bf16_f32 v14, v66, v67
	s_waitcnt vmcnt(8)
	v_cvt_pk_bf16_f32 v15, v68, v69
	ds_write_b128 v98, v[12:15]
	s_waitcnt vmcnt(6)
	v_cvt_pk_bf16_f32 v12, v70, v71
	s_waitcnt vmcnt(4)
	v_cvt_pk_bf16_f32 v13, v72, v73
	s_waitcnt vmcnt(2)
	v_cvt_pk_bf16_f32 v14, v74, v75
	s_waitcnt vmcnt(0)
	v_cvt_pk_bf16_f32 v15, v76, v77
	ds_write_b128 v99, v[12:15]
	s_waitcnt lgkmcnt(0)
	v_lshl_add_u64 v[8:9], v[10:11], 1, v[8:9]
	v_mov_b32_e32 v5, v3
	v_lshl_add_u64 v[16:17], v[8:9], 0, v[4:5]
	ds_read_b128 v[8:11], v100
	v_or_b32_e32 v2, v108, v84
	v_ashrrev_i32_e32 v5, 31, v108
	v_mul_lo_u32 v14, v7, v2
	v_mul_lo_u32 v5, v6, v5
	v_mad_u64_u32 v[12:13], s[4:5], v6, v2, 0
	v_add3_u32 v13, v13, v5, v14
	v_lshl_add_u64 v[18:19], v[12:13], 1, v[16:17]
	ds_read_b128 v[12:15], v101
	v_or_b32_e32 v2, v108, v85
	s_waitcnt lgkmcnt(1)
	global_store_dwordx4 v[18:19], v[8:11], off
	v_add_u32_e32 v92, s44, v92
	v_add_u32_e32 v80, s44, v80
	v_mul_lo_u32 v10, v7, v2
	v_mad_u64_u32 v[8:9], s[4:5], v6, v2, 0
	v_add3_u32 v9, v9, v5, v10
	v_lshl_add_u64 v[8:9], v[8:9], 1, v[16:17]
	s_waitcnt lgkmcnt(0)
	global_store_dwordx4 v[8:9], v[12:15], off
	ds_read_b128 v[8:11], v102
	v_or_b32_e32 v2, v108, v86
	v_mul_lo_u32 v14, v7, v2
	v_mad_u64_u32 v[12:13], s[4:5], v6, v2, 0
	v_add3_u32 v13, v13, v5, v14
	v_lshl_add_u64 v[18:19], v[12:13], 1, v[16:17]
	ds_read_b128 v[12:15], v103
	v_or_b32_e32 v2, v108, v87
	s_waitcnt lgkmcnt(1)
	global_store_dwordx4 v[18:19], v[8:11], off
	s_nop 1
	v_mul_lo_u32 v10, v7, v2
	v_mad_u64_u32 v[8:9], s[4:5], v6, v2, 0
	v_add3_u32 v9, v9, v5, v10
	v_lshl_add_u64 v[8:9], v[8:9], 1, v[16:17]
	s_waitcnt lgkmcnt(0)
	global_store_dwordx4 v[8:9], v[12:15], off
	ds_read_b128 v[8:11], v104
	v_or_b32_e32 v2, v108, v88
	v_mul_lo_u32 v14, v7, v2
	v_mad_u64_u32 v[12:13], s[4:5], v6, v2, 0
	v_add3_u32 v13, v13, v5, v14
	v_lshl_add_u64 v[18:19], v[12:13], 1, v[16:17]
	ds_read_b128 v[12:15], v105
	v_or_b32_e32 v2, v108, v89
	s_waitcnt lgkmcnt(1)
	global_store_dwordx4 v[18:19], v[8:11], off
	s_nop 1
	v_mul_lo_u32 v10, v7, v2
	v_mad_u64_u32 v[8:9], s[4:5], v6, v2, 0
	v_add3_u32 v9, v9, v5, v10
	v_lshl_add_u64 v[8:9], v[8:9], 1, v[16:17]
	s_waitcnt lgkmcnt(0)
	global_store_dwordx4 v[8:9], v[12:15], off
	ds_read_b128 v[8:11], v106
	v_or_b32_e32 v2, v108, v90
	v_mul_lo_u32 v14, v7, v2
	v_mad_u64_u32 v[12:13], s[4:5], v6, v2, 0
	v_add3_u32 v13, v13, v5, v14
	v_lshl_add_u64 v[18:19], v[12:13], 1, v[16:17]
	ds_read_b128 v[12:15], v107
	v_or_b32_e32 v2, v108, v91
	s_waitcnt lgkmcnt(1)
	global_store_dwordx4 v[18:19], v[8:11], off
	s_nop 1
	v_mul_lo_u32 v8, v7, v2
	v_mad_u64_u32 v[6:7], s[4:5], v6, v2, 0
	v_add3_u32 v7, v7, v5, v8
	v_lshl_add_u64 v[6:7], v[6:7], 1, v[16:17]
	s_waitcnt lgkmcnt(0)
	global_store_dwordx4 v[6:7], v[12:15], off
	s_waitcnt lgkmcnt(0)
	v_add_u32_e32 v2, 0x13c0, v92
	v_cmp_lt_i32_e64 s[4:5], s67, v2
	s_or_b64 s[46:47], s[4:5], s[46:47]
	s_andn2_b64 exec, exec, s[46:47]
	s_cbranch_execz .LBB0_179

; #define GAS __attribute__((address_space(1)))
; __device__ __forceinline__ unsigned f2bf(float f) { return pk2(f, f) & 0xffffu; }
; __device__ __forceinline__ void convert_late(int part, int brank, int nblocks) {
;     ...
;     for (int i = gtid; i < 8 * DM; i += gn) { const int j = i >> 10, k = i & 1023; ((GAS unsigned short*)(ws + OFF_WF))[i] = (unsigned short)f2bf(((const GAS float*)P.w_in)[(size_t)k * INW + 1536 + j] * ((const GAS float*)P.mix_norm)[k]); }
.LBB0_181:
	v_ashrrev_i32_e32 v8, 10, v2
	v_and_b32_e32 v3, 0x3ff, v2
	v_ashrrev_i32_e32 v9, 31, v8
	v_mad_u64_u32 v[10:11], s[16:17], v3, s3, v[6:7]
	v_lshl_add_u64 v[8:9], v[8:9], 2, v[10:11]
	v_add_co_u32_e32 v8, vcc, 0x1000, v8
	v_lshlrev_b32_e32 v3, 2, v3
	s_nop 0
	v_addc_co_u32_e32 v9, vcc, 0, v9, vcc
	global_load_dword v3, v3, s[4:5]
	v_add_u32_e32 v2, s14, v2
	global_load_dword v8, v[8:9], off offset:2048
	v_cmp_lt_i32_e32 vcc, s6, v2
	s_or_b64 s[10:11], vcc, s[10:11]
	s_waitcnt vmcnt(0)
	v_mul_f32_e32 v3, v8, v3
	v_cvt_pk_bf16_f32 v3, v3, v3
	global_store_short v[4:5], v3, off
	v_lshl_add_u64 v[4:5], v[4:5], 0, s[8:9]
	s_andn2_b64 exec, exec, s[10:11]
	s_cbranch_execnz .LBB0_181

; __device__ __forceinline__ unsigned f2bf(float f) { return pk2(f, f) & 0xffffu; }
; template <int K, int LD>
; __device__ __forceinline__ void phase_resid(int mode) {
;     ...
;     EPI_IDS
; #pragma unroll
;     for (int ai = 0; ai < 2; ++ai)
; #pragma unroll
;     for (int mh = 0; mh < 2; ++mh) {
;       float xo[2][4][2][2];
; #pragma unroll
;       for (int m2 = 0; m2 < 2; ++m2)
; #pragma unroll
;         for (int j = 0; j < 4; ++j)
; #pragma unroll
;           for (int bj = 0; bj < 2; ++bj)
; #pragma unroll
;             for (int n = 0; n < 2; ++n) {
;               const size_t idx = (size_t)(brow + ai * 128 + wr * 64 + (mh * 2 + m2) * 16 + fq * 4 + j) * DM + bcol + bj * 128 + wc * 32 + n * 16 + fr;
;               xo[m2][j][bj][n] = (mode == 0) ? xin[idx] : bf2f(xg[idx]);
;             }
; #pragma unroll
;       for (int m2 = 0; m2 < 2; ++m2)
; #pragma unroll
;         for (int j = 0; j < 4; ++j) {
;           const int m = mh * 2 + m2; const int row = brow + ai * 128 + wr * 64 + m * 16 + fq * 4 + j;
;           float ss = 0.f;
; #pragma unroll
;           for (int bj = 0; bj < 2; ++bj)
; #pragma unroll
;             for (int n = 0; n < 2; ++n) {
;               const size_t idx = (size_t)row * DM + bcol + bj * 128 + wc * 32 + n * 16 + fr;
;               const float xn = xo[m2][j][bj][n] + scale * acc[ai][bj][m][n][j];
;               ss += xn * xn;
;               xg[idx] = (unsigned short)f2bf(xn);
;             }
;           ss = sum16(ss);
;           if (fr == 0) ssq[(size_t)row * 16 + pn0 * 4 + wc] = ss;
;         }
.LBB0_235:
	v_mov_b32_e32 v130, v170
	v_mov_b32_e32 v133, s15
	v_ashrrev_i32_e32 v132, 2, v130
	v_and_b32_e32 v132, 0xffffffc0, v132
	v_bfe_u32 v187, v130, 6, 2
	v_and_b32_e32 v188, 15, v130
	v_lshrrev_b32_e32 v130, 2, v130
	v_add_u32_e32 v132, s42, v132
	v_and_or_b32 v136, v130, 12, v132
	v_lshlrev_b32_e32 v130, 5, v187
	v_ashrrev_i32_e32 v137, 31, v136
	v_or3_b32 v132, v130, v188, s14
	v_lshlrev_b64 v[134:135], 12, v[136:137]
	v_or_b32_e32 v152, 1, v136
	v_lshl_add_u64 v[134:135], s[4:5], 0, v[134:135]
	v_lshlrev_b64 v[138:139], 2, v[132:133]
	v_ashrrev_i32_e32 v153, 31, v152
	v_lshl_add_u64 v[132:133], v[134:135], 0, v[138:139]
	v_lshlrev_b64 v[134:135], 12, v[152:153]
	v_or_b32_e32 v150, 2, v136
	v_lshl_add_u64 v[134:135], s[4:5], 0, v[134:135]
	v_ashrrev_i32_e32 v151, 31, v150
	v_or_b32_e32 v148, 3, v136
	v_lshl_add_u64 v[134:135], v[134:135], 0, v[138:139]
	global_load_dword v190, v[132:133], off
	global_load_dword v191, v[132:133], off offset:64
	global_load_dword v192, v[132:133], off offset:512
	global_load_dword v193, v[132:133], off offset:576
	global_load_dword v186, v[134:135], off
	global_load_dword v185, v[134:135], off offset:64
	global_load_dword v184, v[134:135], off offset:512
	global_load_dword v183, v[134:135], off offset:576
	v_lshlrev_b64 v[132:133], 12, v[150:151]
	v_ashrrev_i32_e32 v149, 31, v148
	v_lshl_add_u64 v[132:133], s[4:5], 0, v[132:133]
	v_lshlrev_b64 v[134:135], 12, v[148:149]
	v_or_b32_e32 v146, 16, v136
	v_lshl_add_u64 v[132:133], v[132:133], 0, v[138:139]
	v_lshl_add_u64 v[134:135], s[4:5], 0, v[134:135]
	v_ashrrev_i32_e32 v147, 31, v146
	v_or_b32_e32 v144, 17, v136
	v_lshl_add_u64 v[134:135], v[134:135], 0, v[138:139]
	global_load_dword v182, v[132:133], off
	global_load_dword v181, v[132:133], off offset:64
	global_load_dword v180, v[132:133], off offset:512
	global_load_dword v179, v[132:133], off offset:576
	global_load_dword v178, v[134:135], off
	global_load_dword v177, v[134:135], off offset:64
	global_load_dword v176, v[134:135], off offset:512
	global_load_dword v175, v[134:135], off offset:576
	v_lshlrev_b64 v[132:133], 12, v[146:147]
	v_ashrrev_i32_e32 v145, 31, v144
	v_lshl_add_u64 v[132:133], s[4:5], 0, v[132:133]
	v_lshlrev_b64 v[134:135], 12, v[144:145]
	v_or_b32_e32 v142, 18, v136
	v_lshl_add_u64 v[132:133], v[132:133], 0, v[138:139]
	v_lshl_add_u64 v[134:135], s[4:5], 0, v[134:135]
	v_ashrrev_i32_e32 v143, 31, v142
	v_or_b32_e32 v140, 19, v136
	v_lshl_add_u64 v[134:135], v[134:135], 0, v[138:139]
	global_load_dword v174, v[132:133], off
	global_load_dword v169, v[132:133], off offset:64
	global_load_dword v168, v[132:133], off offset:512
	global_load_dword v167, v[132:133], off offset:576
	global_load_dword v166, v[134:135], off
	global_load_dword v165, v[134:135], off offset:64
	global_load_dword v164, v[134:135], off offset:512
	global_load_dword v163, v[134:135], off offset:576
	v_lshlrev_b64 v[132:133], 12, v[142:143]
	v_ashrrev_i32_e32 v141, 31, v140
	v_lshl_add_u64 v[132:133], s[4:5], 0, v[132:133]
	v_lshlrev_b64 v[134:135], 12, v[140:141]
	v_lshl_add_u64 v[132:133], v[132:133], 0, v[138:139]
	v_lshl_add_u64 v[134:135], s[4:5], 0, v[134:135]
	v_lshl_add_u64 v[134:135], v[134:135], 0, v[138:139]
	global_load_dword v162, v[132:133], off
	global_load_dword v161, v[132:133], off offset:64
	global_load_dword v160, v[132:133], off offset:512
	global_load_dword v159, v[132:133], off offset:576
	global_load_dword v158, v[134:135], off
	global_load_dword v157, v[134:135], off offset:64
	global_load_dword v156, v[134:135], off offset:512
	global_load_dword v155, v[134:135], off offset:576
	s_lshl_b64 s[14:15], s[14:15], 1
	s_add_u32 s14, s29, s14
	s_addc_u32 s15, s30, s15
	v_lshlrev_b32_e32 v130, 6, v187
	v_lshl_add_u64 v[132:133], s[14:15], 0, v[130:131]
	v_lshlrev_b32_e32 v130, 1, v188
	v_lshl_add_u64 v[134:135], v[132:133], 0, v[130:131]
	v_cmp_eq_u32_e32 vcc, 0, v188
	v_lshlrev_b64 v[188:189], 11, v[136:137]
	s_lshl_b32 s14, s41, 2
	v_lshl_add_u64 v[188:189], v[134:135], 0, v[188:189]
	s_ashr_i32 s15, s14, 31
	s_lshl_b64 s[14:15], s[14:15], 2
	s_add_u32 s14, s31, s14
	s_addc_u32 s15, s33, s15
	v_lshlrev_b32_e32 v130, 2, v187
	v_lshl_add_u64 v[132:133], s[14:15], 0, v[130:131]
	s_waitcnt vmcnt(0)
	v_fmac_f32_e32 v190, 0.5, v118
	v_fmac_f32_e32 v191, 0.5, v114
	v_mul_f32_e32 v114, v191, v191
	v_fmac_f32_e32 v114, v190, v190
	v_fmac_f32_e32 v192, 0.5, v126
	v_cvt_pk_bf16_f32 v118, v190, v190
	v_fmac_f32_e32 v114, v192, v192
	v_fmac_f32_e32 v193, 0.5, v122
	global_store_short v[188:189], v118, off
	v_cvt_pk_bf16_f32 v118, v191, v191
	v_fmac_f32_e32 v114, v193, v193
	global_store_short v[188:189], v118, off offset:32
	v_cvt_pk_bf16_f32 v118, v192, v192
	global_store_short v[188:189], v118, off offset:256
	v_add_f32_dpp v114, v114, v114 quad_perm:[1,0,3,2] row_mask:0xf bank_mask:0xf bound_ctrl:1
	v_cvt_pk_bf16_f32 v118, v193, v193
	global_store_short v[188:189], v118, off offset:288
	v_mov_b32_e32 v118, 0
	v_add_f32_dpp v114, v114, v114 quad_perm:[2,3,0,1] row_mask:0xf bank_mask:0xf bound_ctrl:1
	s_nop 1
	v_add_f32_dpp v114, v114, v114 row_half_mirror row_mask:0xf bank_mask:0xf bound_ctrl:1
	s_nop 1
	v_mov_b32_dpp v118, v114 row_mirror row_mask:0xf bank_mask:0xf
	s_and_saveexec_b64 s[14:15], vcc
	s_cbranch_execz .LBB0_237
	v_lshlrev_b64 v[188:189], 6, v[136:137]
	v_add_f32_e32 v114, v114, v118
	v_lshl_add_u64 v[188:189], v[132:133], 0, v[188:189]
	global_store_dword v[188:189], v114, off
; __device__ __forceinline__ unsigned f2bf(float f) { return pk2(f, f) & 0xffffu; }
; template <int K, int LD>
; __device__ __forceinline__ void phase_resid(int mode) {
;     ...
; #pragma unroll
;       for (int m2 = 0; m2 < 2; ++m2)
; #pragma unroll
;         for (int j = 0; j < 4; ++j) {
;           const int m = mh * 2 + m2; const int row = brow + ai * 128 + wr * 64 + m * 16 + fq * 4 + j;
;           float ss = 0.f;
; #pragma unroll
;           for (int bj = 0; bj < 2; ++bj)
; #pragma unroll
;             for (int n = 0; n < 2; ++n) {
;               const size_t idx = (size_t)row * DM + bcol + bj * 128 + wc * 32 + n * 16 + fr;
;               const float xn = xo[m2][j][bj][n] + scale * acc[ai][bj][m][n][j];
;               ss += xn * xn;
;               xg[idx] = (unsigned short)f2bf(xn);
;             }
;           ss = sum16(ss);
;           if (fr == 0) ssq[(size_t)row * 16 + pn0 * 4 + wc] = ss;
;         }
.LBB0_237:
	s_or_b64 exec, exec, s[14:15]
	v_lshlrev_b64 v[188:189], 11, v[152:153]
	v_lshl_add_u64 v[188:189], v[134:135], 0, v[188:189]
	v_fmac_f32_e32 v186, 0.5, v119
	v_cvt_pk_bf16_f32 v114, v186, v186
	v_fmac_f32_e32 v185, 0.5, v115
	global_store_short v[188:189], v114, off
	v_mul_f32_e32 v114, v185, v185
	v_fmac_f32_e32 v114, v186, v186
	v_fmac_f32_e32 v184, 0.5, v127
	v_fmac_f32_e32 v114, v184, v184
	v_fmac_f32_e32 v183, 0.5, v123
	v_cvt_pk_bf16_f32 v115, v185, v185
	v_fmac_f32_e32 v114, v183, v183
	global_store_short v[188:189], v115, off offset:32
	v_cvt_pk_bf16_f32 v115, v184, v184
	global_store_short v[188:189], v115, off offset:256
	v_add_f32_dpp v114, v114, v114 quad_perm:[1,0,3,2] row_mask:0xf bank_mask:0xf bound_ctrl:1
	v_cvt_pk_bf16_f32 v115, v183, v183
	global_store_short v[188:189], v115, off offset:288
	v_mov_b32_e32 v115, 0
	v_add_f32_dpp v114, v114, v114 quad_perm:[2,3,0,1] row_mask:0xf bank_mask:0xf bound_ctrl:1
	s_nop 1
	v_add_f32_dpp v114, v114, v114 row_half_mirror row_mask:0xf bank_mask:0xf bound_ctrl:1
	s_nop 1
	v_mov_b32_dpp v115, v114 row_mirror row_mask:0xf bank_mask:0xf
	s_and_saveexec_b64 s[14:15], vcc
	s_cbranch_execz .LBB0_239
	v_add_f32_e32 v118, v114, v115
	v_lshlrev_b64 v[114:115], 6, v[152:153]
	v_lshl_add_u64 v[114:115], v[132:133], 0, v[114:115]
	global_store_dword v[114:115], v118, off
.LBB0_239:
	s_or_b64 exec, exec, s[14:15]
	v_fmac_f32_e32 v181, 0.5, v116
	v_lshlrev_b64 v[114:115], 11, v[150:151]
	v_fmac_f32_e32 v182, 0.5, v120
	v_mul_f32_e32 v116, v181, v181
	v_lshl_add_u64 v[114:115], v[134:135], 0, v[114:115]
	v_cvt_pk_bf16_f32 v118, v182, v182
	v_fmac_f32_e32 v116, v182, v182
	v_fmac_f32_e32 v180, 0.5, v128
	global_store_short v[114:115], v118, off
	v_cvt_pk_bf16_f32 v118, v181, v181
	v_fmac_f32_e32 v116, v180, v180
	v_fmac_f32_e32 v179, 0.5, v124
	global_store_short v[114:115], v118, off offset:32
	v_cvt_pk_bf16_f32 v118, v180, v180
	v_fmac_f32_e32 v116, v179, v179
	global_store_short v[114:115], v118, off offset:256
	v_cvt_pk_bf16_f32 v118, v179, v179
	global_store_short v[114:115], v118, off offset:288
	v_add_f32_dpp v114, v116, v116 quad_perm:[1,0,3,2] row_mask:0xf bank_mask:0xf bound_ctrl:1
	v_mov_b32_e32 v115, 0
	s_nop 0
	v_add_f32_dpp v114, v114, v114 quad_perm:[2,3,0,1] row_mask:0xf bank_mask:0xf bound_ctrl:1
	s_nop 1
	v_add_f32_dpp v114, v114, v114 row_half_mirror row_mask:0xf bank_mask:0xf bound_ctrl:1
	s_nop 1
	v_mov_b32_dpp v115, v114 row_mirror row_mask:0xf bank_mask:0xf
	s_and_saveexec_b64 s[14:15], vcc
	s_cbranch_execz .LBB0_241
	v_add_f32_e32 v116, v114, v115
	v_lshlrev_b64 v[114:115], 6, v[150:151]
	v_lshl_add_u64 v[114:115], v[132:133], 0, v[114:115]
	global_store_dword v[114:115], v116, off
.LBB0_241:
	s_or_b64 exec, exec, s[14:15]
	v_lshlrev_b64 v[114:115], 11, v[148:149]
	v_lshl_add_u64 v[114:115], v[134:135], 0, v[114:115]
	v_fmac_f32_e32 v178, 0.5, v121
	v_cvt_pk_bf16_f32 v116, v178, v178
	v_fmac_f32_e32 v177, 0.5, v117
	global_store_short v[114:115], v116, off
	v_mul_f32_e32 v116, v177, v177
	v_fmac_f32_e32 v116, v178, v178
	v_fmac_f32_e32 v176, 0.5, v129
	v_cvt_pk_bf16_f32 v117, v177, v177
	v_fmac_f32_e32 v116, v176, v176
	v_fmac_f32_e32 v175, 0.5, v125
	global_store_short v[114:115], v117, off offset:32
	v_cvt_pk_bf16_f32 v117, v176, v176
	v_fmac_f32_e32 v116, v175, v175
	global_store_short v[114:115], v117, off offset:256
	v_cvt_pk_bf16_f32 v117, v175, v175
	global_store_short v[114:115], v117, off offset:288
	v_add_f32_dpp v114, v116, v116 quad_perm:[1,0,3,2] row_mask:0xf bank_mask:0xf bound_ctrl:1
	v_mov_b32_e32 v115, 0
	s_nop 0
	v_add_f32_dpp v114, v114, v114 quad_perm:[2,3,0,1] row_mask:0xf bank_mask:0xf bound_ctrl:1
	s_nop 1
	v_add_f32_dpp v114, v114, v114 row_half_mirror row_mask:0xf bank_mask:0xf bound_ctrl:1
	s_nop 1
	v_mov_b32_dpp v115, v114 row_mirror row_mask:0xf bank_mask:0xf
	s_and_saveexec_b64 s[14:15], vcc
	s_cbranch_execz .LBB0_243
	v_add_f32_e32 v116, v114, v115
	v_lshlrev_b64 v[114:115], 6, v[148:149]
	v_lshl_add_u64 v[114:115], v[132:133], 0, v[114:115]
	global_store_dword v[114:115], v116, off
.LBB0_243:
	s_or_b64 exec, exec, s[14:15]
	v_fmac_f32_e32 v169, 0.5, v98
	v_fmac_f32_e32 v174, 0.5, v102
	v_mul_f32_e32 v98, v169, v169
	v_lshlrev_b64 v[114:115], 11, v[146:147]
	v_fmac_f32_e32 v98, v174, v174
	v_fmac_f32_e32 v168, 0.5, v110
	v_lshl_add_u64 v[114:115], v[134:135], 0, v[114:115]
	v_cvt_pk_bf16_f32 v102, v174, v174
	v_fmac_f32_e32 v98, v168, v168
	v_fmac_f32_e32 v167, 0.5, v106
	global_store_short v[114:115], v102, off
	v_cvt_pk_bf16_f32 v102, v169, v169
	v_fmac_f32_e32 v98, v167, v167
	global_store_short v[114:115], v102, off offset:32
	v_cvt_pk_bf16_f32 v102, v168, v168
	global_store_short v[114:115], v102, off offset:256
	v_add_f32_dpp v98, v98, v98 quad_perm:[1,0,3,2] row_mask:0xf bank_mask:0xf bound_ctrl:1
	v_cvt_pk_bf16_f32 v102, v167, v167
	global_store_short v[114:115], v102, off offset:288
	v_mov_b32_e32 v102, 0
	v_add_f32_dpp v98, v98, v98 quad_perm:[2,3,0,1] row_mask:0xf bank_mask:0xf bound_ctrl:1
	s_nop 1
	v_add_f32_dpp v98, v98, v98 row_half_mirror row_mask:0xf bank_mask:0xf bound_ctrl:1
	s_nop 1
	v_mov_b32_dpp v102, v98 row_mirror row_mask:0xf bank_mask:0xf
	s_and_saveexec_b64 s[14:15], vcc
	s_cbranch_execz .LBB0_245
	v_lshlrev_b64 v[114:115], 6, v[146:147]
	v_add_f32_e32 v98, v98, v102
	v_lshl_add_u64 v[114:115], v[132:133], 0, v[114:115]
	global_store_dword v[114:115], v98, off
; __device__ __forceinline__ unsigned f2bf(float f) { return pk2(f, f) & 0xffffu; }
; template <int K, int LD>
; __device__ __forceinline__ void phase_resid(int mode) {
;     ...
;     for (int ai = 0; ai < 2; ++ai)
; #pragma unroll
;     for (int mh = 0; mh < 2; ++mh) {
;       float xo[2][4][2][2];
; #pragma unroll
;       for (int m2 = 0; m2 < 2; ++m2)
; #pragma unroll
;         for (int j = 0; j < 4; ++j)
; #pragma unroll
;           for (int bj = 0; bj < 2; ++bj)
; #pragma unroll
;             for (int n = 0; n < 2; ++n) {
;               const size_t idx = (size_t)(brow + ai * 128 + wr * 64 + (mh * 2 + m2) * 16 + fq * 4 + j) * DM + bcol + bj * 128 + wc * 32 + n * 16 + fr;
;               xo[m2][j][bj][n] = (mode == 0) ? xin[idx] : bf2f(xg[idx]);
;             }
; #pragma unroll
;       for (int m2 = 0; m2 < 2; ++m2)
; #pragma unroll
;         for (int j = 0; j < 4; ++j) {
;           const int m = mh * 2 + m2; const int row = brow + ai * 128 + wr * 64 + m * 16 + fq * 4 + j;
;           float ss = 0.f;
; #pragma unroll
;           for (int bj = 0; bj < 2; ++bj)
; #pragma unroll
;             for (int n = 0; n < 2; ++n) {
;               const size_t idx = (size_t)row * DM + bcol + bj * 128 + wc * 32 + n * 16 + fr;
;               const float xn = xo[m2][j][bj][n] + scale * acc[ai][bj][m][n][j];
;               ss += xn * xn;
;               xg[idx] = (unsigned short)f2bf(xn);
;             }
;           ss = sum16(ss);
;           if (fr == 0) ssq[(size_t)row * 16 + pn0 * 4 + wc] = ss;
;         }
.LBB0_245:
	s_or_b64 exec, exec, s[14:15]
	v_lshlrev_b64 v[114:115], 11, v[144:145]
	v_lshl_add_u64 v[114:115], v[134:135], 0, v[114:115]
	v_fmac_f32_e32 v166, 0.5, v103
	v_cvt_pk_bf16_f32 v98, v166, v166
	v_fmac_f32_e32 v165, 0.5, v99
	global_store_short v[114:115], v98, off
	v_mul_f32_e32 v98, v165, v165
	v_fmac_f32_e32 v98, v166, v166
	v_fmac_f32_e32 v164, 0.5, v111
	v_fmac_f32_e32 v98, v164, v164
	v_fmac_f32_e32 v163, 0.5, v107
	v_cvt_pk_bf16_f32 v99, v165, v165
	v_fmac_f32_e32 v98, v163, v163
	global_store_short v[114:115], v99, off offset:32
	v_cvt_pk_bf16_f32 v99, v164, v164
	global_store_short v[114:115], v99, off offset:256
	v_add_f32_dpp v98, v98, v98 quad_perm:[1,0,3,2] row_mask:0xf bank_mask:0xf bound_ctrl:1
	v_cvt_pk_bf16_f32 v99, v163, v163
	global_store_short v[114:115], v99, off offset:288
	v_mov_b32_e32 v99, 0
	v_add_f32_dpp v98, v98, v98 quad_perm:[2,3,0,1] row_mask:0xf bank_mask:0xf bound_ctrl:1
	s_nop 1
	v_add_f32_dpp v98, v98, v98 row_half_mirror row_mask:0xf bank_mask:0xf bound_ctrl:1
	s_nop 1
	v_mov_b32_dpp v99, v98 row_mirror row_mask:0xf bank_mask:0xf
	s_and_saveexec_b64 s[14:15], vcc
	s_cbranch_execz .LBB0_247
	v_add_f32_e32 v102, v98, v99
	v_lshlrev_b64 v[98:99], 6, v[144:145]
	v_lshl_add_u64 v[98:99], v[132:133], 0, v[98:99]
	global_store_dword v[98:99], v102, off
.LBB0_247:
	s_or_b64 exec, exec, s[14:15]
	v_fmac_f32_e32 v161, 0.5, v100
	v_lshlrev_b64 v[98:99], 11, v[142:143]
	v_fmac_f32_e32 v162, 0.5, v104
	v_mul_f32_e32 v100, v161, v161
	v_lshl_add_u64 v[98:99], v[134:135], 0, v[98:99]
	v_cvt_pk_bf16_f32 v102, v162, v162
	v_fmac_f32_e32 v100, v162, v162
	v_fmac_f32_e32 v160, 0.5, v112
	global_store_short v[98:99], v102, off
	v_cvt_pk_bf16_f32 v102, v161, v161
	v_fmac_f32_e32 v100, v160, v160
	v_fmac_f32_e32 v159, 0.5, v108
	global_store_short v[98:99], v102, off offset:32
	v_cvt_pk_bf16_f32 v102, v160, v160
	v_fmac_f32_e32 v100, v159, v159
	global_store_short v[98:99], v102, off offset:256
	v_cvt_pk_bf16_f32 v102, v159, v159
	global_store_short v[98:99], v102, off offset:288
	v_add_f32_dpp v98, v100, v100 quad_perm:[1,0,3,2] row_mask:0xf bank_mask:0xf bound_ctrl:1
	v_mov_b32_e32 v99, 0
	s_nop 0
	v_add_f32_dpp v98, v98, v98 quad_perm:[2,3,0,1] row_mask:0xf bank_mask:0xf bound_ctrl:1
	s_nop 1
	v_add_f32_dpp v98, v98, v98 row_half_mirror row_mask:0xf bank_mask:0xf bound_ctrl:1
	s_nop 1
	v_mov_b32_dpp v99, v98 row_mirror row_mask:0xf bank_mask:0xf
	s_and_saveexec_b64 s[14:15], vcc
	s_cbranch_execz .LBB0_249
	v_add_f32_e32 v100, v98, v99
	v_lshlrev_b64 v[98:99], 6, v[142:143]
	v_lshl_add_u64 v[98:99], v[132:133], 0, v[98:99]
	global_store_dword v[98:99], v100, off
.LBB0_249:
	s_or_b64 exec, exec, s[14:15]
	v_lshlrev_b64 v[98:99], 11, v[140:141]
	v_lshl_add_u64 v[98:99], v[134:135], 0, v[98:99]
	v_fmac_f32_e32 v158, 0.5, v105
	v_cvt_pk_bf16_f32 v100, v158, v158
	v_fmac_f32_e32 v157, 0.5, v101
	global_store_short v[98:99], v100, off
	v_mul_f32_e32 v100, v157, v157
	v_fmac_f32_e32 v100, v158, v158
	v_fmac_f32_e32 v156, 0.5, v113
	v_cvt_pk_bf16_f32 v101, v157, v157
	v_fmac_f32_e32 v100, v156, v156
	v_fmac_f32_e32 v155, 0.5, v109
	global_store_short v[98:99], v101, off offset:32
	v_cvt_pk_bf16_f32 v101, v156, v156
	v_fmac_f32_e32 v100, v155, v155
	global_store_short v[98:99], v101, off offset:256
	v_cvt_pk_bf16_f32 v101, v155, v155
	global_store_short v[98:99], v101, off offset:288
	v_add_f32_dpp v98, v100, v100 quad_perm:[1,0,3,2] row_mask:0xf bank_mask:0xf bound_ctrl:1
	v_mov_b32_e32 v99, 0
	s_nop 0
	v_add_f32_dpp v98, v98, v98 quad_perm:[2,3,0,1] row_mask:0xf bank_mask:0xf bound_ctrl:1
	s_nop 1
	v_add_f32_dpp v98, v98, v98 row_half_mirror row_mask:0xf bank_mask:0xf bound_ctrl:1
	s_nop 1
	v_mov_b32_dpp v99, v98 row_mirror row_mask:0xf bank_mask:0xf
	s_and_saveexec_b64 s[14:15], vcc
	s_cbranch_execz .LBB0_251
	v_add_f32_e32 v100, v98, v99
	v_lshlrev_b64 v[98:99], 6, v[140:141]
	v_lshl_add_u64 v[98:99], v[132:133], 0, v[98:99]
	global_store_dword v[98:99], v100, off
.LBB0_251:
	s_or_b64 exec, exec, s[14:15]
	v_or_b32_e32 v112, 32, v136
	v_or_b32_e32 v110, 33, v136
	v_ashrrev_i32_e32 v113, 31, v112
	v_ashrrev_i32_e32 v111, 31, v110
	v_lshlrev_b64 v[98:99], 12, v[112:113]
	v_lshlrev_b64 v[100:101], 12, v[110:111]
	v_lshl_add_u64 v[98:99], s[4:5], 0, v[98:99]
	v_lshl_add_u64 v[100:101], s[4:5], 0, v[100:101]
	v_or_b32_e32 v108, 34, v136
	v_or_b32_e32 v106, 35, v136
	v_lshl_add_u64 v[98:99], v[98:99], 0, v[138:139]
	v_lshl_add_u64 v[100:101], v[100:101], 0, v[138:139]
	v_ashrrev_i32_e32 v109, 31, v108
	v_ashrrev_i32_e32 v107, 31, v106
	global_load_dword v152, v[98:99], off
	global_load_dword v153, v[98:99], off offset:64
	global_load_dword v155, v[98:99], off offset:512
	global_load_dword v156, v[98:99], off offset:576
	global_load_dword v149, v[100:101], off
	global_load_dword v148, v[100:101], off offset:64
	global_load_dword v147, v[100:101], off offset:512
	global_load_dword v146, v[100:101], off offset:576
	v_lshlrev_b64 v[98:99], 12, v[108:109]
	v_lshlrev_b64 v[100:101], 12, v[106:107]
	v_lshl_add_u64 v[98:99], s[4:5], 0, v[98:99]
	v_lshl_add_u64 v[100:101], s[4:5], 0, v[100:101]
	v_or_b32_e32 v104, 48, v136
	v_or_b32_e32 v102, 49, v136
	v_lshl_add_u64 v[98:99], v[98:99], 0, v[138:139]
	v_lshl_add_u64 v[100:101], v[100:101], 0, v[138:139]
	v_ashrrev_i32_e32 v105, 31, v104
	v_ashrrev_i32_e32 v103, 31, v102
	global_load_dword v145, v[98:99], off
	global_load_dword v144, v[98:99], off offset:64
	global_load_dword v143, v[98:99], off offset:512
	global_load_dword v142, v[98:99], off offset:576
	global_load_dword v141, v[100:101], off
	global_load_dword v140, v[100:101], off offset:64
	global_load_dword v137, v[100:101], off offset:512
; __device__ __forceinline__ unsigned f2bf(float f) { return pk2(f, f) & 0xffffu; }
; template <int K, int LD>
; __device__ __forceinline__ void phase_resid(int mode) {
;     ...
;     for (int ai = 0; ai < 2; ++ai)
; #pragma unroll
;     for (int mh = 0; mh < 2; ++mh) {
;       float xo[2][4][2][2];
; #pragma unroll
;       for (int m2 = 0; m2 < 2; ++m2)
; #pragma unroll
;         for (int j = 0; j < 4; ++j)
; #pragma unroll
;           for (int bj = 0; bj < 2; ++bj)
; #pragma unroll
;             for (int n = 0; n < 2; ++n) {
;               const size_t idx = (size_t)(brow + ai * 128 + wr * 64 + (mh * 2 + m2) * 16 + fq * 4 + j) * DM + bcol + bj * 128 + wc * 32 + n * 16 + fr;
;               xo[m2][j][bj][n] = (mode == 0) ? xin[idx] : bf2f(xg[idx]);
;             }
; #pragma unroll
;       for (int m2 = 0; m2 < 2; ++m2)
; #pragma unroll
;         for (int j = 0; j < 4; ++j) {
;           const int m = mh * 2 + m2; const int row = brow + ai * 128 + wr * 64 + m * 16 + fq * 4 + j;
;           float ss = 0.f;
; #pragma unroll
;           for (int bj = 0; bj < 2; ++bj)
; #pragma unroll
;             for (int n = 0; n < 2; ++n) {
;               const size_t idx = (size_t)row * DM + bcol + bj * 128 + wc * 32 + n * 16 + fr;
;               const float xn = xo[m2][j][bj][n] + scale * acc[ai][bj][m][n][j];
;               ss += xn * xn;
;               xg[idx] = (unsigned short)f2bf(xn);
;             }
;           ss = sum16(ss);
;           if (fr == 0) ssq[(size_t)row * 16 + pn0 * 4 + wc] = ss;
;         }
	global_load_dword v130, v[100:101], off offset:576
	v_lshlrev_b64 v[98:99], 12, v[104:105]
	v_lshlrev_b64 v[100:101], 12, v[102:103]
	v_lshl_add_u64 v[98:99], s[4:5], 0, v[98:99]
	v_lshl_add_u64 v[100:101], s[4:5], 0, v[100:101]
	v_lshl_add_u64 v[98:99], v[98:99], 0, v[138:139]
	v_lshl_add_u64 v[100:101], v[100:101], 0, v[138:139]
	global_load_dword v129, v[98:99], off
	global_load_dword v128, v[98:99], off offset:64
	global_load_dword v127, v[98:99], off offset:512
	global_load_dword v126, v[98:99], off offset:576
	global_load_dword v125, v[100:101], off
	global_load_dword v124, v[100:101], off offset:64
	global_load_dword v123, v[100:101], off offset:512
	global_load_dword v122, v[100:101], off offset:576
	v_or_b32_e32 v100, 50, v136
	v_ashrrev_i32_e32 v101, 31, v100
	v_lshlrev_b64 v[98:99], 12, v[100:101]
	v_lshl_add_u64 v[98:99], s[4:5], 0, v[98:99]
	v_lshl_add_u64 v[114:115], v[98:99], 0, v[138:139]
	v_or_b32_e32 v98, 51, v136
	v_ashrrev_i32_e32 v99, 31, v98
	v_lshlrev_b64 v[116:117], 12, v[98:99]
	v_lshl_add_u64 v[116:117], s[4:5], 0, v[116:117]
	v_lshl_add_u64 v[150:151], v[116:117], 0, v[138:139]
	global_load_dword v121, v[114:115], off
	global_load_dword v120, v[114:115], off offset:64
	global_load_dword v119, v[114:115], off offset:512
	global_load_dword v118, v[114:115], off offset:576
	global_load_dword v117, v[150:151], off
	global_load_dword v116, v[150:151], off offset:64
	s_nop 0
	global_load_dword v115, v[150:151], off offset:512
	global_load_dword v114, v[150:151], off offset:576
	v_lshlrev_b64 v[150:151], 11, v[112:113]
	v_lshl_add_u64 v[150:151], v[134:135], 0, v[150:151]
	s_waitcnt vmcnt(0)
	v_fmac_f32_e32 v152, 0.5, v86
	v_fmac_f32_e32 v153, 0.5, v82
	v_mul_f32_e32 v86, v153, v153
	v_fmac_f32_e32 v155, 0.5, v94
	v_fmac_f32_e32 v86, v152, v152
	v_fmac_f32_e32 v156, 0.5, v90
	v_fmac_f32_e32 v86, v155, v155
	v_cvt_pk_bf16_f32 v82, v152, v152
	v_fmac_f32_e32 v86, v156, v156
	global_store_short v[150:151], v82, off
	v_cvt_pk_bf16_f32 v90, v153, v153
	v_cvt_pk_bf16_f32 v94, v155, v155
	v_cvt_pk_bf16_f32 v153, v156, v156
	global_store_short v[150:151], v90, off offset:32
	global_store_short v[150:151], v94, off offset:256
	global_store_short v[150:151], v153, off offset:288
	v_add_f32_dpp v82, v86, v86 quad_perm:[1,0,3,2] row_mask:0xf bank_mask:0xf bound_ctrl:1
	v_mov_b32_e32 v86, 0
	s_nop 0
	v_add_f32_dpp v82, v82, v82 quad_perm:[2,3,0,1] row_mask:0xf bank_mask:0xf bound_ctrl:1
	s_nop 1
	v_add_f32_dpp v82, v82, v82 row_half_mirror row_mask:0xf bank_mask:0xf bound_ctrl:1
	s_nop 1
	v_mov_b32_dpp v86, v82 row_mirror row_mask:0xf bank_mask:0xf
	s_and_saveexec_b64 s[14:15], vcc
	s_cbranch_execz .LBB0_253
	v_lshlrev_b64 v[112:113], 6, v[112:113]
	v_add_f32_e32 v82, v82, v86
	v_lshl_add_u64 v[112:113], v[132:133], 0, v[112:113]
	global_store_dword v[112:113], v82, off
.LBB0_253:
	s_or_b64 exec, exec, s[14:15]
	v_lshlrev_b64 v[112:113], 11, v[110:111]
	v_lshl_add_u64 v[112:113], v[134:135], 0, v[112:113]
	v_fmac_f32_e32 v149, 0.5, v87
	v_cvt_pk_bf16_f32 v82, v149, v149
	v_fmac_f32_e32 v148, 0.5, v83
	global_store_short v[112:113], v82, off
	v_mul_f32_e32 v82, v148, v148
	v_fmac_f32_e32 v82, v149, v149
	v_fmac_f32_e32 v147, 0.5, v95
	v_fmac_f32_e32 v82, v147, v147
	v_fmac_f32_e32 v146, 0.5, v91
	v_cvt_pk_bf16_f32 v83, v148, v148
	v_fmac_f32_e32 v82, v146, v146
	global_store_short v[112:113], v83, off offset:32
	v_cvt_pk_bf16_f32 v83, v147, v147
	global_store_short v[112:113], v83, off offset:256
	v_add_f32_dpp v82, v82, v82 quad_perm:[1,0,3,2] row_mask:0xf bank_mask:0xf bound_ctrl:1
	v_cvt_pk_bf16_f32 v83, v146, v146
	global_store_short v[112:113], v83, off offset:288
	v_mov_b32_e32 v83, 0
	v_add_f32_dpp v82, v82, v82 quad_perm:[2,3,0,1] row_mask:0xf bank_mask:0xf bound_ctrl:1
	s_nop 1
	v_add_f32_dpp v82, v82, v82 row_half_mirror row_mask:0xf bank_mask:0xf bound_ctrl:1
	s_nop 1
	v_mov_b32_dpp v83, v82 row_mirror row_mask:0xf bank_mask:0xf
	s_and_saveexec_b64 s[14:15], vcc
	s_cbranch_execz .LBB0_255
	v_add_f32_e32 v86, v82, v83
	v_lshlrev_b64 v[82:83], 6, v[110:111]
	v_lshl_add_u64 v[82:83], v[132:133], 0, v[82:83]
	global_store_dword v[82:83], v86, off
.LBB0_255:
	s_or_b64 exec, exec, s[14:15]
	v_fmac_f32_e32 v144, 0.5, v84
	v_lshlrev_b64 v[82:83], 11, v[108:109]
	v_fmac_f32_e32 v145, 0.5, v88
	v_mul_f32_e32 v84, v144, v144
	v_lshl_add_u64 v[82:83], v[134:135], 0, v[82:83]
	v_cvt_pk_bf16_f32 v86, v145, v145
	v_fmac_f32_e32 v84, v145, v145
	v_fmac_f32_e32 v143, 0.5, v96
	global_store_short v[82:83], v86, off
	v_cvt_pk_bf16_f32 v86, v144, v144
	v_fmac_f32_e32 v84, v143, v143
	v_fmac_f32_e32 v142, 0.5, v92
	global_store_short v[82:83], v86, off offset:32
	v_cvt_pk_bf16_f32 v86, v143, v143
	v_fmac_f32_e32 v84, v142, v142
	global_store_short v[82:83], v86, off offset:256
	v_cvt_pk_bf16_f32 v86, v142, v142
	global_store_short v[82:83], v86, off offset:288
	v_add_f32_dpp v82, v84, v84 quad_perm:[1,0,3,2] row_mask:0xf bank_mask:0xf bound_ctrl:1
	v_mov_b32_e32 v83, 0
	s_nop 0
	v_add_f32_dpp v82, v82, v82 quad_perm:[2,3,0,1] row_mask:0xf bank_mask:0xf bound_ctrl:1
	s_nop 1
	v_add_f32_dpp v82, v82, v82 row_half_mirror row_mask:0xf bank_mask:0xf bound_ctrl:1
	s_nop 1
	v_mov_b32_dpp v83, v82 row_mirror row_mask:0xf bank_mask:0xf
	s_and_saveexec_b64 s[14:15], vcc
	s_cbranch_execz .LBB0_257
	v_add_f32_e32 v84, v82, v83
	v_lshlrev_b64 v[82:83], 6, v[108:109]
	v_lshl_add_u64 v[82:83], v[132:133], 0, v[82:83]
	global_store_dword v[82:83], v84, off
; __device__ __forceinline__ unsigned f2bf(float f) { return pk2(f, f) & 0xffffu; }
; template <int K, int LD>
; __device__ __forceinline__ void phase_resid(int mode) {
;     ...
; #pragma unroll
;       for (int m2 = 0; m2 < 2; ++m2)
; #pragma unroll
;         for (int j = 0; j < 4; ++j) {
;           const int m = mh * 2 + m2; const int row = brow + ai * 128 + wr * 64 + m * 16 + fq * 4 + j;
;           float ss = 0.f;
; #pragma unroll
;           for (int bj = 0; bj < 2; ++bj)
; #pragma unroll
;             for (int n = 0; n < 2; ++n) {
;               const size_t idx = (size_t)row * DM + bcol + bj * 128 + wc * 32 + n * 16 + fr;
;               const float xn = xo[m2][j][bj][n] + scale * acc[ai][bj][m][n][j];
;               ss += xn * xn;
;               xg[idx] = (unsigned short)f2bf(xn);
;             }
;           ss = sum16(ss);
;           if (fr == 0) ssq[(size_t)row * 16 + pn0 * 4 + wc] = ss;
;         }
.LBB0_257:
	s_or_b64 exec, exec, s[14:15]
	v_lshlrev_b64 v[82:83], 11, v[106:107]
	v_lshl_add_u64 v[82:83], v[134:135], 0, v[82:83]
	v_fmac_f32_e32 v141, 0.5, v89
	v_cvt_pk_bf16_f32 v84, v141, v141
	v_fmac_f32_e32 v140, 0.5, v85
	global_store_short v[82:83], v84, off
	v_mul_f32_e32 v84, v140, v140
	v_fmac_f32_e32 v84, v141, v141
	v_fmac_f32_e32 v137, 0.5, v97
	v_cvt_pk_bf16_f32 v85, v140, v140
	v_fmac_f32_e32 v84, v137, v137
	v_fmac_f32_e32 v130, 0.5, v93
	global_store_short v[82:83], v85, off offset:32
	v_cvt_pk_bf16_f32 v85, v137, v137
	v_fmac_f32_e32 v84, v130, v130
	global_store_short v[82:83], v85, off offset:256
	v_cvt_pk_bf16_f32 v85, v130, v130
	global_store_short v[82:83], v85, off offset:288
	v_add_f32_dpp v82, v84, v84 quad_perm:[1,0,3,2] row_mask:0xf bank_mask:0xf bound_ctrl:1
	v_mov_b32_e32 v83, 0
	s_nop 0
	v_add_f32_dpp v82, v82, v82 quad_perm:[2,3,0,1] row_mask:0xf bank_mask:0xf bound_ctrl:1
	s_nop 1
	v_add_f32_dpp v82, v82, v82 row_half_mirror row_mask:0xf bank_mask:0xf bound_ctrl:1
	s_nop 1
	v_mov_b32_dpp v83, v82 row_mirror row_mask:0xf bank_mask:0xf
	s_and_saveexec_b64 s[14:15], vcc
	s_cbranch_execz .LBB0_259
	v_add_f32_e32 v84, v82, v83
	v_lshlrev_b64 v[82:83], 6, v[106:107]
	v_lshl_add_u64 v[82:83], v[132:133], 0, v[82:83]
	global_store_dword v[82:83], v84, off
.LBB0_259:
	s_or_b64 exec, exec, s[14:15]
	v_fmac_f32_e32 v128, 0.5, v66
	v_fmac_f32_e32 v129, 0.5, v70
	v_mul_f32_e32 v66, v128, v128
	v_lshlrev_b64 v[82:83], 11, v[104:105]
	v_fmac_f32_e32 v66, v129, v129
	v_fmac_f32_e32 v127, 0.5, v78
	v_lshl_add_u64 v[82:83], v[134:135], 0, v[82:83]
	v_cvt_pk_bf16_f32 v70, v129, v129
	v_fmac_f32_e32 v66, v127, v127
	v_fmac_f32_e32 v126, 0.5, v74
	global_store_short v[82:83], v70, off
	v_cvt_pk_bf16_f32 v70, v128, v128
	v_fmac_f32_e32 v66, v126, v126
	global_store_short v[82:83], v70, off offset:32
	v_cvt_pk_bf16_f32 v70, v127, v127
	global_store_short v[82:83], v70, off offset:256
	v_add_f32_dpp v66, v66, v66 quad_perm:[1,0,3,2] row_mask:0xf bank_mask:0xf bound_ctrl:1
	v_cvt_pk_bf16_f32 v70, v126, v126
	global_store_short v[82:83], v70, off offset:288
	v_mov_b32_e32 v70, 0
	v_add_f32_dpp v66, v66, v66 quad_perm:[2,3,0,1] row_mask:0xf bank_mask:0xf bound_ctrl:1
	s_nop 1
	v_add_f32_dpp v66, v66, v66 row_half_mirror row_mask:0xf bank_mask:0xf bound_ctrl:1
	s_nop 1
	v_mov_b32_dpp v70, v66 row_mirror row_mask:0xf bank_mask:0xf
	s_and_saveexec_b64 s[14:15], vcc
	s_cbranch_execz .LBB0_261
	v_lshlrev_b64 v[82:83], 6, v[104:105]
	v_add_f32_e32 v66, v66, v70
	v_lshl_add_u64 v[82:83], v[132:133], 0, v[82:83]
	global_store_dword v[82:83], v66, off
.LBB0_261:
	s_or_b64 exec, exec, s[14:15]
	v_lshlrev_b64 v[82:83], 11, v[102:103]
	v_lshl_add_u64 v[82:83], v[134:135], 0, v[82:83]
	v_fmac_f32_e32 v125, 0.5, v71
	v_cvt_pk_bf16_f32 v66, v125, v125
	v_fmac_f32_e32 v124, 0.5, v67
	global_store_short v[82:83], v66, off
	v_mul_f32_e32 v66, v124, v124
	v_fmac_f32_e32 v66, v125, v125
	v_fmac_f32_e32 v123, 0.5, v79
	v_fmac_f32_e32 v66, v123, v123
	v_fmac_f32_e32 v122, 0.5, v75
	v_cvt_pk_bf16_f32 v67, v124, v124
	v_fmac_f32_e32 v66, v122, v122
	global_store_short v[82:83], v67, off offset:32
	v_cvt_pk_bf16_f32 v67, v123, v123
	global_store_short v[82:83], v67, off offset:256
	v_add_f32_dpp v66, v66, v66 quad_perm:[1,0,3,2] row_mask:0xf bank_mask:0xf bound_ctrl:1
	v_cvt_pk_bf16_f32 v67, v122, v122
	global_store_short v[82:83], v67, off offset:288
	v_mov_b32_e32 v67, 0
	v_add_f32_dpp v66, v66, v66 quad_perm:[2,3,0,1] row_mask:0xf bank_mask:0xf bound_ctrl:1
	s_nop 1
	v_add_f32_dpp v66, v66, v66 row_half_mirror row_mask:0xf bank_mask:0xf bound_ctrl:1
	s_nop 1
	v_mov_b32_dpp v67, v66 row_mirror row_mask:0xf bank_mask:0xf
	s_and_saveexec_b64 s[14:15], vcc
	s_cbranch_execz .LBB0_263
	v_add_f32_e32 v70, v66, v67
	v_lshlrev_b64 v[66:67], 6, v[102:103]
	v_lshl_add_u64 v[66:67], v[132:133], 0, v[66:67]
	global_store_dword v[66:67], v70, off
.LBB0_263:
	s_or_b64 exec, exec, s[14:15]
	v_fmac_f32_e32 v120, 0.5, v68
	v_lshlrev_b64 v[66:67], 11, v[100:101]
	v_fmac_f32_e32 v121, 0.5, v72
	v_mul_f32_e32 v68, v120, v120
	v_lshl_add_u64 v[66:67], v[134:135], 0, v[66:67]
	v_cvt_pk_bf16_f32 v70, v121, v121
	v_fmac_f32_e32 v68, v121, v121
	v_fmac_f32_e32 v119, 0.5, v80
	global_store_short v[66:67], v70, off
	v_cvt_pk_bf16_f32 v70, v120, v120
	v_fmac_f32_e32 v68, v119, v119
	v_fmac_f32_e32 v118, 0.5, v76
	global_store_short v[66:67], v70, off offset:32
	v_cvt_pk_bf16_f32 v70, v119, v119
	v_fmac_f32_e32 v68, v118, v118
	global_store_short v[66:67], v70, off offset:256
	v_cvt_pk_bf16_f32 v70, v118, v118
	global_store_short v[66:67], v70, off offset:288
	v_add_f32_dpp v66, v68, v68 quad_perm:[1,0,3,2] row_mask:0xf bank_mask:0xf bound_ctrl:1
	v_mov_b32_e32 v67, 0
	s_nop 0
	v_add_f32_dpp v66, v66, v66 quad_perm:[2,3,0,1] row_mask:0xf bank_mask:0xf bound_ctrl:1
	s_nop 1
	v_add_f32_dpp v66, v66, v66 row_half_mirror row_mask:0xf bank_mask:0xf bound_ctrl:1
	s_nop 1
	v_mov_b32_dpp v67, v66 row_mirror row_mask:0xf bank_mask:0xf
	s_and_saveexec_b64 s[14:15], vcc
	s_cbranch_execz .LBB0_265
	v_add_f32_e32 v68, v66, v67
	v_lshlrev_b64 v[66:67], 6, v[100:101]
	v_lshl_add_u64 v[66:67], v[132:133], 0, v[66:67]
	global_store_dword v[66:67], v68, off
; __device__ __forceinline__ unsigned f2bf(float f) { return pk2(f, f) & 0xffffu; }
; template <int K, int LD>
; __device__ __forceinline__ void phase_resid(int mode) {
;     ...
;     for (int ai = 0; ai < 2; ++ai)
; #pragma unroll
;     for (int mh = 0; mh < 2; ++mh) {
;       float xo[2][4][2][2];
; #pragma unroll
;       for (int m2 = 0; m2 < 2; ++m2)
; #pragma unroll
;         for (int j = 0; j < 4; ++j)
; #pragma unroll
;           for (int bj = 0; bj < 2; ++bj)
; #pragma unroll
;             for (int n = 0; n < 2; ++n) {
;               const size_t idx = (size_t)(brow + ai * 128 + wr * 64 + (mh * 2 + m2) * 16 + fq * 4 + j) * DM + bcol + bj * 128 + wc * 32 + n * 16 + fr;
;               xo[m2][j][bj][n] = (mode == 0) ? xin[idx] : bf2f(xg[idx]);
;             }
; #pragma unroll
;       for (int m2 = 0; m2 < 2; ++m2)
; #pragma unroll
;         for (int j = 0; j < 4; ++j) {
;           const int m = mh * 2 + m2; const int row = brow + ai * 128 + wr * 64 + m * 16 + fq * 4 + j;
;           float ss = 0.f;
; #pragma unroll
;           for (int bj = 0; bj < 2; ++bj)
; #pragma unroll
;             for (int n = 0; n < 2; ++n) {
;               const size_t idx = (size_t)row * DM + bcol + bj * 128 + wc * 32 + n * 16 + fr;
;               const float xn = xo[m2][j][bj][n] + scale * acc[ai][bj][m][n][j];
;               ss += xn * xn;
;               xg[idx] = (unsigned short)f2bf(xn);
;             }
;           ss = sum16(ss);
;           if (fr == 0) ssq[(size_t)row * 16 + pn0 * 4 + wc] = ss;
;         }
.LBB0_265:
	s_or_b64 exec, exec, s[14:15]
	v_lshlrev_b64 v[66:67], 11, v[98:99]
	v_lshl_add_u64 v[66:67], v[134:135], 0, v[66:67]
	v_fmac_f32_e32 v117, 0.5, v73
	v_cvt_pk_bf16_f32 v68, v117, v117
	v_fmac_f32_e32 v116, 0.5, v69
	global_store_short v[66:67], v68, off
	v_mul_f32_e32 v68, v116, v116
	v_fmac_f32_e32 v68, v117, v117
	v_fmac_f32_e32 v115, 0.5, v81
	v_cvt_pk_bf16_f32 v69, v116, v116
	v_fmac_f32_e32 v68, v115, v115
	v_fmac_f32_e32 v114, 0.5, v77
	global_store_short v[66:67], v69, off offset:32
	v_cvt_pk_bf16_f32 v69, v115, v115
	v_fmac_f32_e32 v68, v114, v114
	global_store_short v[66:67], v69, off offset:256
	v_cvt_pk_bf16_f32 v69, v114, v114
	global_store_short v[66:67], v69, off offset:288
	v_add_f32_dpp v66, v68, v68 quad_perm:[1,0,3,2] row_mask:0xf bank_mask:0xf bound_ctrl:1
	v_mov_b32_e32 v67, 0
	s_nop 0
	v_add_f32_dpp v66, v66, v66 quad_perm:[2,3,0,1] row_mask:0xf bank_mask:0xf bound_ctrl:1
	s_nop 1
	v_add_f32_dpp v66, v66, v66 row_half_mirror row_mask:0xf bank_mask:0xf bound_ctrl:1
	s_nop 1
	v_mov_b32_dpp v67, v66 row_mirror row_mask:0xf bank_mask:0xf
	s_and_saveexec_b64 s[14:15], vcc
	s_cbranch_execz .LBB0_267
	v_add_f32_e32 v68, v66, v67
	v_lshlrev_b64 v[66:67], 6, v[98:99]
	v_lshl_add_u64 v[66:67], v[132:133], 0, v[66:67]
	global_store_dword v[66:67], v68, off
.LBB0_267:
	s_or_b64 exec, exec, s[14:15]
	v_add_u32_e32 v80, 0x80, v136
	v_add_u32_e32 v78, 0x81, v136
	v_ashrrev_i32_e32 v81, 31, v80
	v_ashrrev_i32_e32 v79, 31, v78
	v_lshlrev_b64 v[66:67], 12, v[80:81]
	v_lshlrev_b64 v[68:69], 12, v[78:79]
	v_lshl_add_u64 v[66:67], s[4:5], 0, v[66:67]
	v_lshl_add_u64 v[68:69], s[4:5], 0, v[68:69]
	v_add_u32_e32 v76, 0x82, v136
	v_add_u32_e32 v74, 0x83, v136
	v_lshl_add_u64 v[66:67], v[66:67], 0, v[138:139]
	v_lshl_add_u64 v[68:69], v[68:69], 0, v[138:139]
	v_ashrrev_i32_e32 v77, 31, v76
	v_ashrrev_i32_e32 v75, 31, v74
	global_load_dword v112, v[66:67], off
	global_load_dword v113, v[66:67], off offset:64
	global_load_dword v114, v[66:67], off offset:512
	global_load_dword v115, v[66:67], off offset:576
	global_load_dword v109, v[68:69], off
	global_load_dword v108, v[68:69], off offset:64
	global_load_dword v107, v[68:69], off offset:512
	global_load_dword v106, v[68:69], off offset:576
	v_lshlrev_b64 v[66:67], 12, v[76:77]
	v_lshlrev_b64 v[68:69], 12, v[74:75]
	v_lshl_add_u64 v[66:67], s[4:5], 0, v[66:67]
	v_lshl_add_u64 v[68:69], s[4:5], 0, v[68:69]
	v_add_u32_e32 v72, 0x90, v136
	v_add_u32_e32 v70, 0x91, v136
	v_lshl_add_u64 v[66:67], v[66:67], 0, v[138:139]
	v_lshl_add_u64 v[68:69], v[68:69], 0, v[138:139]
	v_ashrrev_i32_e32 v73, 31, v72
	v_ashrrev_i32_e32 v71, 31, v70
	global_load_dword v105, v[66:67], off
	global_load_dword v104, v[66:67], off offset:64
	global_load_dword v103, v[66:67], off offset:512
	global_load_dword v102, v[66:67], off offset:576
	global_load_dword v101, v[68:69], off
	global_load_dword v100, v[68:69], off offset:64
	global_load_dword v99, v[68:69], off offset:512
	global_load_dword v98, v[68:69], off offset:576
	v_lshlrev_b64 v[66:67], 12, v[72:73]
	v_lshlrev_b64 v[68:69], 12, v[70:71]
	v_lshl_add_u64 v[66:67], s[4:5], 0, v[66:67]
	v_lshl_add_u64 v[68:69], s[4:5], 0, v[68:69]
	v_lshl_add_u64 v[66:67], v[66:67], 0, v[138:139]
	v_lshl_add_u64 v[68:69], v[68:69], 0, v[138:139]
	global_load_dword v97, v[66:67], off
	global_load_dword v96, v[66:67], off offset:64
	global_load_dword v95, v[66:67], off offset:512
	global_load_dword v94, v[66:67], off offset:576
	global_load_dword v93, v[68:69], off
	global_load_dword v92, v[68:69], off offset:64
	global_load_dword v91, v[68:69], off offset:512
	global_load_dword v90, v[68:69], off offset:576
	v_add_u32_e32 v68, 0x92, v136
	v_ashrrev_i32_e32 v69, 31, v68
	v_lshlrev_b64 v[66:67], 12, v[68:69]
	v_lshl_add_u64 v[66:67], s[4:5], 0, v[66:67]
	v_lshl_add_u64 v[82:83], v[66:67], 0, v[138:139]
	v_add_u32_e32 v66, 0x93, v136
	v_ashrrev_i32_e32 v67, 31, v66
	v_lshlrev_b64 v[84:85], 12, v[66:67]
	v_lshl_add_u64 v[84:85], s[4:5], 0, v[84:85]
	v_lshl_add_u64 v[110:111], v[84:85], 0, v[138:139]
	global_load_dword v89, v[82:83], off
	global_load_dword v88, v[82:83], off offset:64
	global_load_dword v87, v[82:83], off offset:512
	global_load_dword v86, v[82:83], off offset:576
	global_load_dword v84, v[110:111], off
	global_load_dword v85, v[110:111], off offset:64
	s_nop 0
	global_load_dword v83, v[110:111], off offset:512
	global_load_dword v82, v[110:111], off offset:576
	v_lshlrev_b64 v[110:111], 11, v[80:81]
	v_lshl_add_u64 v[110:111], v[134:135], 0, v[110:111]
	s_waitcnt vmcnt(0)
	v_fmac_f32_e32 v112, 0.5, v54
	v_fmac_f32_e32 v113, 0.5, v50
	v_mul_f32_e32 v54, v113, v113
	v_fmac_f32_e32 v114, 0.5, v62
	v_fmac_f32_e32 v54, v112, v112
	v_fmac_f32_e32 v115, 0.5, v58
	v_fmac_f32_e32 v54, v114, v114
	v_cvt_pk_bf16_f32 v50, v112, v112
	v_fmac_f32_e32 v54, v115, v115
	global_store_short v[110:111], v50, off
	v_cvt_pk_bf16_f32 v58, v113, v113
	v_cvt_pk_bf16_f32 v62, v114, v114
	v_cvt_pk_bf16_f32 v113, v115, v115
	global_store_short v[110:111], v58, off offset:32
	global_store_short v[110:111], v62, off offset:256
	global_store_short v[110:111], v113, off offset:288
	v_add_f32_dpp v50, v54, v54 quad_perm:[1,0,3,2] row_mask:0xf bank_mask:0xf bound_ctrl:1
	v_mov_b32_e32 v54, 0
	s_nop 0
	v_add_f32_dpp v50, v50, v50 quad_perm:[2,3,0,1] row_mask:0xf bank_mask:0xf bound_ctrl:1
	s_nop 1
	v_add_f32_dpp v50, v50, v50 row_half_mirror row_mask:0xf bank_mask:0xf bound_ctrl:1
	s_nop 1
	v_mov_b32_dpp v54, v50 row_mirror row_mask:0xf bank_mask:0xf
	s_and_saveexec_b64 s[14:15], vcc
	s_cbranch_execz .LBB0_269
	v_lshlrev_b64 v[80:81], 6, v[80:81]
	v_add_f32_e32 v50, v50, v54
	v_lshl_add_u64 v[80:81], v[132:133], 0, v[80:81]
	global_store_dword v[80:81], v50, off
; __device__ __forceinline__ unsigned f2bf(float f) { return pk2(f, f) & 0xffffu; }
; template <int K, int LD>
; __device__ __forceinline__ void phase_resid(int mode) {
;     ...
; #pragma unroll
;       for (int m2 = 0; m2 < 2; ++m2)
; #pragma unroll
;         for (int j = 0; j < 4; ++j) {
;           const int m = mh * 2 + m2; const int row = brow + ai * 128 + wr * 64 + m * 16 + fq * 4 + j;
;           float ss = 0.f;
; #pragma unroll
;           for (int bj = 0; bj < 2; ++bj)
; #pragma unroll
;             for (int n = 0; n < 2; ++n) {
;               const size_t idx = (size_t)row * DM + bcol + bj * 128 + wc * 32 + n * 16 + fr;
;               const float xn = xo[m2][j][bj][n] + scale * acc[ai][bj][m][n][j];
;               ss += xn * xn;
;               xg[idx] = (unsigned short)f2bf(xn);
;             }
;           ss = sum16(ss);
;           if (fr == 0) ssq[(size_t)row * 16 + pn0 * 4 + wc] = ss;
;         }
.LBB0_269:
	s_or_b64 exec, exec, s[14:15]
	v_lshlrev_b64 v[80:81], 11, v[78:79]
	v_lshl_add_u64 v[80:81], v[134:135], 0, v[80:81]
	v_fmac_f32_e32 v109, 0.5, v55
	v_cvt_pk_bf16_f32 v50, v109, v109
	v_fmac_f32_e32 v108, 0.5, v51
	global_store_short v[80:81], v50, off
	v_mul_f32_e32 v50, v108, v108
	v_fmac_f32_e32 v50, v109, v109
	v_fmac_f32_e32 v107, 0.5, v63
	v_fmac_f32_e32 v50, v107, v107
	v_fmac_f32_e32 v106, 0.5, v59
	v_cvt_pk_bf16_f32 v51, v108, v108
	v_fmac_f32_e32 v50, v106, v106
	global_store_short v[80:81], v51, off offset:32
	v_cvt_pk_bf16_f32 v51, v107, v107
	global_store_short v[80:81], v51, off offset:256
	v_add_f32_dpp v50, v50, v50 quad_perm:[1,0,3,2] row_mask:0xf bank_mask:0xf bound_ctrl:1
	v_cvt_pk_bf16_f32 v51, v106, v106
	global_store_short v[80:81], v51, off offset:288
	v_mov_b32_e32 v51, 0
	v_add_f32_dpp v50, v50, v50 quad_perm:[2,3,0,1] row_mask:0xf bank_mask:0xf bound_ctrl:1
	s_nop 1
	v_add_f32_dpp v50, v50, v50 row_half_mirror row_mask:0xf bank_mask:0xf bound_ctrl:1
	s_nop 1
	v_mov_b32_dpp v51, v50 row_mirror row_mask:0xf bank_mask:0xf
	s_and_saveexec_b64 s[14:15], vcc
	s_cbranch_execz .LBB0_271
	v_add_f32_e32 v54, v50, v51
	v_lshlrev_b64 v[50:51], 6, v[78:79]
	v_lshl_add_u64 v[50:51], v[132:133], 0, v[50:51]
	global_store_dword v[50:51], v54, off
.LBB0_271:
	s_or_b64 exec, exec, s[14:15]
	v_fmac_f32_e32 v104, 0.5, v52
	v_lshlrev_b64 v[50:51], 11, v[76:77]
	v_fmac_f32_e32 v105, 0.5, v56
	v_mul_f32_e32 v52, v104, v104
	v_lshl_add_u64 v[50:51], v[134:135], 0, v[50:51]
	v_cvt_pk_bf16_f32 v54, v105, v105
	v_fmac_f32_e32 v52, v105, v105
	v_fmac_f32_e32 v103, 0.5, v64
	global_store_short v[50:51], v54, off
	v_cvt_pk_bf16_f32 v54, v104, v104
	v_fmac_f32_e32 v52, v103, v103
	v_fmac_f32_e32 v102, 0.5, v60
	global_store_short v[50:51], v54, off offset:32
	v_cvt_pk_bf16_f32 v54, v103, v103
	v_fmac_f32_e32 v52, v102, v102
	global_store_short v[50:51], v54, off offset:256
	v_cvt_pk_bf16_f32 v54, v102, v102
	global_store_short v[50:51], v54, off offset:288
	v_add_f32_dpp v50, v52, v52 quad_perm:[1,0,3,2] row_mask:0xf bank_mask:0xf bound_ctrl:1
	v_mov_b32_e32 v51, 0
	s_nop 0
	v_add_f32_dpp v50, v50, v50 quad_perm:[2,3,0,1] row_mask:0xf bank_mask:0xf bound_ctrl:1
	s_nop 1
	v_add_f32_dpp v50, v50, v50 row_half_mirror row_mask:0xf bank_mask:0xf bound_ctrl:1
	s_nop 1
	v_mov_b32_dpp v51, v50 row_mirror row_mask:0xf bank_mask:0xf
	s_and_saveexec_b64 s[14:15], vcc
	s_cbranch_execz .LBB0_273
	v_add_f32_e32 v52, v50, v51
	v_lshlrev_b64 v[50:51], 6, v[76:77]
	v_lshl_add_u64 v[50:51], v[132:133], 0, v[50:51]
	global_store_dword v[50:51], v52, off
.LBB0_273:
	s_or_b64 exec, exec, s[14:15]
	v_lshlrev_b64 v[50:51], 11, v[74:75]
	v_lshl_add_u64 v[50:51], v[134:135], 0, v[50:51]
	v_fmac_f32_e32 v101, 0.5, v57
	v_cvt_pk_bf16_f32 v52, v101, v101
	v_fmac_f32_e32 v100, 0.5, v53
	global_store_short v[50:51], v52, off
	v_mul_f32_e32 v52, v100, v100
	v_fmac_f32_e32 v52, v101, v101
	v_fmac_f32_e32 v99, 0.5, v65
	v_cvt_pk_bf16_f32 v53, v100, v100
	v_fmac_f32_e32 v52, v99, v99
	v_fmac_f32_e32 v98, 0.5, v61
	global_store_short v[50:51], v53, off offset:32
	v_cvt_pk_bf16_f32 v53, v99, v99
	v_fmac_f32_e32 v52, v98, v98
	global_store_short v[50:51], v53, off offset:256
	v_cvt_pk_bf16_f32 v53, v98, v98
	global_store_short v[50:51], v53, off offset:288
	v_add_f32_dpp v50, v52, v52 quad_perm:[1,0,3,2] row_mask:0xf bank_mask:0xf bound_ctrl:1
	v_mov_b32_e32 v51, 0
	s_nop 0
	v_add_f32_dpp v50, v50, v50 quad_perm:[2,3,0,1] row_mask:0xf bank_mask:0xf bound_ctrl:1
	s_nop 1
	v_add_f32_dpp v50, v50, v50 row_half_mirror row_mask:0xf bank_mask:0xf bound_ctrl:1
	s_nop 1
	v_mov_b32_dpp v51, v50 row_mirror row_mask:0xf bank_mask:0xf
	s_and_saveexec_b64 s[14:15], vcc
	s_cbranch_execz .LBB0_275
	v_add_f32_e32 v52, v50, v51
	v_lshlrev_b64 v[50:51], 6, v[74:75]
	v_lshl_add_u64 v[50:51], v[132:133], 0, v[50:51]
	global_store_dword v[50:51], v52, off
.LBB0_275:
	s_or_b64 exec, exec, s[14:15]
	v_fmac_f32_e32 v96, 0.5, v34
	v_fmac_f32_e32 v97, 0.5, v38
	v_mul_f32_e32 v34, v96, v96
	v_lshlrev_b64 v[50:51], 11, v[72:73]
	v_fmac_f32_e32 v34, v97, v97
	v_fmac_f32_e32 v95, 0.5, v46
	v_lshl_add_u64 v[50:51], v[134:135], 0, v[50:51]
	v_cvt_pk_bf16_f32 v38, v97, v97
	v_fmac_f32_e32 v34, v95, v95
	v_fmac_f32_e32 v94, 0.5, v42
	global_store_short v[50:51], v38, off
	v_cvt_pk_bf16_f32 v38, v96, v96
	v_fmac_f32_e32 v34, v94, v94
	global_store_short v[50:51], v38, off offset:32
	v_cvt_pk_bf16_f32 v38, v95, v95
	global_store_short v[50:51], v38, off offset:256
	v_add_f32_dpp v34, v34, v34 quad_perm:[1,0,3,2] row_mask:0xf bank_mask:0xf bound_ctrl:1
	v_cvt_pk_bf16_f32 v38, v94, v94
	global_store_short v[50:51], v38, off offset:288
	v_mov_b32_e32 v38, 0
	v_add_f32_dpp v34, v34, v34 quad_perm:[2,3,0,1] row_mask:0xf bank_mask:0xf bound_ctrl:1
	s_nop 1
	v_add_f32_dpp v34, v34, v34 row_half_mirror row_mask:0xf bank_mask:0xf bound_ctrl:1
	s_nop 1
	v_mov_b32_dpp v38, v34 row_mirror row_mask:0xf bank_mask:0xf
	s_and_saveexec_b64 s[14:15], vcc
	s_cbranch_execz .LBB0_277
	v_lshlrev_b64 v[50:51], 6, v[72:73]
	v_add_f32_e32 v34, v34, v38
	v_lshl_add_u64 v[50:51], v[132:133], 0, v[50:51]
	global_store_dword v[50:51], v34, off
; __device__ __forceinline__ unsigned f2bf(float f) { return pk2(f, f) & 0xffffu; }
; template <int K, int LD>
; __device__ __forceinline__ void phase_resid(int mode) {
;     ...
;     for (int ai = 0; ai < 2; ++ai)
; #pragma unroll
;     for (int mh = 0; mh < 2; ++mh) {
;       float xo[2][4][2][2];
; #pragma unroll
;       for (int m2 = 0; m2 < 2; ++m2)
; #pragma unroll
;         for (int j = 0; j < 4; ++j)
; #pragma unroll
;           for (int bj = 0; bj < 2; ++bj)
; #pragma unroll
;             for (int n = 0; n < 2; ++n) {
;               const size_t idx = (size_t)(brow + ai * 128 + wr * 64 + (mh * 2 + m2) * 16 + fq * 4 + j) * DM + bcol + bj * 128 + wc * 32 + n * 16 + fr;
;               xo[m2][j][bj][n] = (mode == 0) ? xin[idx] : bf2f(xg[idx]);
;             }
; #pragma unroll
;       for (int m2 = 0; m2 < 2; ++m2)
; #pragma unroll
;         for (int j = 0; j < 4; ++j) {
;           const int m = mh * 2 + m2; const int row = brow + ai * 128 + wr * 64 + m * 16 + fq * 4 + j;
;           float ss = 0.f;
; #pragma unroll
;           for (int bj = 0; bj < 2; ++bj)
; #pragma unroll
;             for (int n = 0; n < 2; ++n) {
;               const size_t idx = (size_t)row * DM + bcol + bj * 128 + wc * 32 + n * 16 + fr;
;               const float xn = xo[m2][j][bj][n] + scale * acc[ai][bj][m][n][j];
;               ss += xn * xn;
;               xg[idx] = (unsigned short)f2bf(xn);
;             }
;           ss = sum16(ss);
;           if (fr == 0) ssq[(size_t)row * 16 + pn0 * 4 + wc] = ss;
;         }
.LBB0_277:
	s_or_b64 exec, exec, s[14:15]
	v_lshlrev_b64 v[50:51], 11, v[70:71]
	v_lshl_add_u64 v[50:51], v[134:135], 0, v[50:51]
	v_fmac_f32_e32 v93, 0.5, v39
	v_cvt_pk_bf16_f32 v34, v93, v93
	v_fmac_f32_e32 v92, 0.5, v35
	global_store_short v[50:51], v34, off
	v_mul_f32_e32 v34, v92, v92
	v_fmac_f32_e32 v34, v93, v93
	v_fmac_f32_e32 v91, 0.5, v47
	v_fmac_f32_e32 v34, v91, v91
	v_fmac_f32_e32 v90, 0.5, v43
	v_cvt_pk_bf16_f32 v35, v92, v92
	v_fmac_f32_e32 v34, v90, v90
	global_store_short v[50:51], v35, off offset:32
	v_cvt_pk_bf16_f32 v35, v91, v91
	global_store_short v[50:51], v35, off offset:256
	v_add_f32_dpp v34, v34, v34 quad_perm:[1,0,3,2] row_mask:0xf bank_mask:0xf bound_ctrl:1
	v_cvt_pk_bf16_f32 v35, v90, v90
	global_store_short v[50:51], v35, off offset:288
	v_mov_b32_e32 v35, 0
	v_add_f32_dpp v34, v34, v34 quad_perm:[2,3,0,1] row_mask:0xf bank_mask:0xf bound_ctrl:1
	s_nop 1
	v_add_f32_dpp v34, v34, v34 row_half_mirror row_mask:0xf bank_mask:0xf bound_ctrl:1
	s_nop 1
	v_mov_b32_dpp v35, v34 row_mirror row_mask:0xf bank_mask:0xf
	s_and_saveexec_b64 s[14:15], vcc
	s_cbranch_execz .LBB0_279
	v_add_f32_e32 v38, v34, v35
	v_lshlrev_b64 v[34:35], 6, v[70:71]
	v_lshl_add_u64 v[34:35], v[132:133], 0, v[34:35]
	global_store_dword v[34:35], v38, off
.LBB0_279:
	s_or_b64 exec, exec, s[14:15]
	v_fmac_f32_e32 v88, 0.5, v36
	v_lshlrev_b64 v[34:35], 11, v[68:69]
	v_fmac_f32_e32 v89, 0.5, v40
	v_mul_f32_e32 v36, v88, v88
	v_lshl_add_u64 v[34:35], v[134:135], 0, v[34:35]
	v_cvt_pk_bf16_f32 v38, v89, v89
	v_fmac_f32_e32 v36, v89, v89
	v_fmac_f32_e32 v87, 0.5, v48
	global_store_short v[34:35], v38, off
	v_cvt_pk_bf16_f32 v38, v88, v88
	v_fmac_f32_e32 v36, v87, v87
	v_fmac_f32_e32 v86, 0.5, v44
	global_store_short v[34:35], v38, off offset:32
	v_cvt_pk_bf16_f32 v38, v87, v87
	v_fmac_f32_e32 v36, v86, v86
	global_store_short v[34:35], v38, off offset:256
	v_cvt_pk_bf16_f32 v38, v86, v86
	global_store_short v[34:35], v38, off offset:288
	v_add_f32_dpp v34, v36, v36 quad_perm:[1,0,3,2] row_mask:0xf bank_mask:0xf bound_ctrl:1
	v_mov_b32_e32 v35, 0
	s_nop 0
	v_add_f32_dpp v34, v34, v34 quad_perm:[2,3,0,1] row_mask:0xf bank_mask:0xf bound_ctrl:1
	s_nop 1
	v_add_f32_dpp v34, v34, v34 row_half_mirror row_mask:0xf bank_mask:0xf bound_ctrl:1
	s_nop 1
	v_mov_b32_dpp v35, v34 row_mirror row_mask:0xf bank_mask:0xf
	s_and_saveexec_b64 s[14:15], vcc
	s_cbranch_execz .LBB0_281
	v_add_f32_e32 v36, v34, v35
	v_lshlrev_b64 v[34:35], 6, v[68:69]
	v_lshl_add_u64 v[34:35], v[132:133], 0, v[34:35]
	global_store_dword v[34:35], v36, off
.LBB0_281:
	s_or_b64 exec, exec, s[14:15]
	v_lshlrev_b64 v[34:35], 11, v[66:67]
	v_lshl_add_u64 v[34:35], v[134:135], 0, v[34:35]
	v_fmac_f32_e32 v84, 0.5, v41
	v_cvt_pk_bf16_f32 v36, v84, v84
	v_fmac_f32_e32 v85, 0.5, v37
	global_store_short v[34:35], v36, off
	v_mul_f32_e32 v36, v85, v85
	v_fmac_f32_e32 v36, v84, v84
	v_fmac_f32_e32 v83, 0.5, v49
	v_cvt_pk_bf16_f32 v37, v85, v85
	v_fmac_f32_e32 v36, v83, v83
	v_fmac_f32_e32 v82, 0.5, v45
	global_store_short v[34:35], v37, off offset:32
	v_cvt_pk_bf16_f32 v37, v83, v83
	v_fmac_f32_e32 v36, v82, v82
	global_store_short v[34:35], v37, off offset:256
	v_cvt_pk_bf16_f32 v37, v82, v82
	global_store_short v[34:35], v37, off offset:288
	v_add_f32_dpp v34, v36, v36 quad_perm:[1,0,3,2] row_mask:0xf bank_mask:0xf bound_ctrl:1
	v_mov_b32_e32 v35, 0
	s_nop 0
	v_add_f32_dpp v34, v34, v34 quad_perm:[2,3,0,1] row_mask:0xf bank_mask:0xf bound_ctrl:1
	s_nop 1
	v_add_f32_dpp v34, v34, v34 row_half_mirror row_mask:0xf bank_mask:0xf bound_ctrl:1
	s_nop 1
	v_mov_b32_dpp v35, v34 row_mirror row_mask:0xf bank_mask:0xf
	s_and_saveexec_b64 s[14:15], vcc
	s_cbranch_execz .LBB0_283
	v_add_f32_e32 v36, v34, v35
	v_lshlrev_b64 v[34:35], 6, v[66:67]
	v_lshl_add_u64 v[34:35], v[132:133], 0, v[34:35]
	global_store_dword v[34:35], v36, off
.LBB0_283:
	s_or_b64 exec, exec, s[14:15]
	v_add_u32_e32 v48, 0xa0, v136
	v_add_u32_e32 v46, 0xa1, v136
	v_ashrrev_i32_e32 v49, 31, v48
	v_ashrrev_i32_e32 v47, 31, v46
	v_lshlrev_b64 v[34:35], 12, v[48:49]
	v_lshlrev_b64 v[36:37], 12, v[46:47]
	v_lshl_add_u64 v[34:35], s[4:5], 0, v[34:35]
	v_lshl_add_u64 v[36:37], s[4:5], 0, v[36:37]
	v_add_u32_e32 v44, 0xa2, v136
	v_add_u32_e32 v42, 0xa3, v136
	v_lshl_add_u64 v[34:35], v[34:35], 0, v[138:139]
	v_lshl_add_u64 v[36:37], v[36:37], 0, v[138:139]
	v_ashrrev_i32_e32 v45, 31, v44
	v_ashrrev_i32_e32 v43, 31, v42
	global_load_dword v82, v[34:35], off
	global_load_dword v83, v[34:35], off offset:64
	global_load_dword v84, v[34:35], off offset:512
	global_load_dword v85, v[34:35], off offset:576
	global_load_dword v77, v[36:37], off
	global_load_dword v76, v[36:37], off offset:64
	global_load_dword v75, v[36:37], off offset:512
	global_load_dword v74, v[36:37], off offset:576
	v_lshlrev_b64 v[34:35], 12, v[44:45]
	v_lshlrev_b64 v[36:37], 12, v[42:43]
	v_lshl_add_u64 v[34:35], s[4:5], 0, v[34:35]
	v_lshl_add_u64 v[36:37], s[4:5], 0, v[36:37]
	v_add_u32_e32 v40, 0xb0, v136
	v_add_u32_e32 v38, 0xb1, v136
	v_lshl_add_u64 v[34:35], v[34:35], 0, v[138:139]
	v_lshl_add_u64 v[36:37], v[36:37], 0, v[138:139]
	v_ashrrev_i32_e32 v41, 31, v40
	v_ashrrev_i32_e32 v39, 31, v38
	global_load_dword v73, v[34:35], off
	global_load_dword v72, v[34:35], off offset:64
	global_load_dword v71, v[34:35], off offset:512
	global_load_dword v70, v[34:35], off offset:576
	global_load_dword v69, v[36:37], off
	global_load_dword v68, v[36:37], off offset:64
	global_load_dword v67, v[36:37], off offset:512
	global_load_dword v66, v[36:37], off offset:576
	v_lshlrev_b64 v[34:35], 12, v[40:41]
	v_lshlrev_b64 v[36:37], 12, v[38:39]
	v_lshl_add_u64 v[34:35], s[4:5], 0, v[34:35]
	v_lshl_add_u64 v[36:37], s[4:5], 0, v[36:37]
	v_lshl_add_u64 v[34:35], v[34:35], 0, v[138:139]
	v_lshl_add_u64 v[36:37], v[36:37], 0, v[138:139]
	global_load_dword v65, v[34:35], off
	global_load_dword v64, v[34:35], off offset:64
	global_load_dword v63, v[34:35], off offset:512
	global_load_dword v62, v[34:35], off offset:576
	global_load_dword v61, v[36:37], off
	global_load_dword v60, v[36:37], off offset:64
	global_load_dword v59, v[36:37], off offset:512
	global_load_dword v58, v[36:37], off offset:576
	v_add_u32_e32 v36, 0xb2, v136
	v_ashrrev_i32_e32 v37, 31, v36
	v_lshlrev_b64 v[34:35], 12, v[36:37]
	v_lshl_add_u64 v[34:35], s[4:5], 0, v[34:35]
	v_lshl_add_u64 v[78:79], v[34:35], 0, v[138:139]
	v_add_u32_e32 v34, 0xb3, v136
	v_ashrrev_i32_e32 v35, 31, v34
	v_lshlrev_b64 v[50:51], 12, v[34:35]
	v_lshl_add_u64 v[50:51], s[4:5], 0, v[50:51]
	v_lshl_add_u64 v[80:81], v[50:51], 0, v[138:139]
	global_load_dword v57, v[78:79], off
	global_load_dword v56, v[78:79], off offset:64
	global_load_dword v55, v[78:79], off offset:512
	global_load_dword v54, v[78:79], off offset:576
	global_load_dword v53, v[80:81], off
	global_load_dword v52, v[80:81], off offset:64
	global_load_dword v51, v[80:81], off offset:512
	global_load_dword v50, v[80:81], off offset:576
	v_lshlrev_b64 v[78:79], 11, v[48:49]
	v_lshl_add_u64 v[78:79], v[134:135], 0, v[78:79]
	s_waitcnt vmcnt(0)
; __device__ __forceinline__ unsigned f2bf(float f) { return pk2(f, f) & 0xffffu; }
; template <int K, int LD>
; __device__ __forceinline__ void phase_resid(int mode) {
;     ...
;       for (int m2 = 0; m2 < 2; ++m2)
; #pragma unroll
;         for (int j = 0; j < 4; ++j) {
;           const int m = mh * 2 + m2; const int row = brow + ai * 128 + wr * 64 + m * 16 + fq * 4 + j;
;           float ss = 0.f;
; #pragma unroll
;           for (int bj = 0; bj < 2; ++bj)
; #pragma unroll
;             for (int n = 0; n < 2; ++n) {
;               const size_t idx = (size_t)row * DM + bcol + bj * 128 + wc * 32 + n * 16 + fr;
;               const float xn = xo[m2][j][bj][n] + scale * acc[ai][bj][m][n][j];
;               ss += xn * xn;
;               xg[idx] = (unsigned short)f2bf(xn);
;             }
;           ss = sum16(ss);
;           if (fr == 0) ssq[(size_t)row * 16 + pn0 * 4 + wc] = ss;
;         }
	v_fmac_f32_e32 v82, 0.5, v22
	v_fmac_f32_e32 v83, 0.5, v18
	v_mul_f32_e32 v22, v83, v83
	v_fmac_f32_e32 v84, 0.5, v30
	v_fmac_f32_e32 v22, v82, v82
	v_fmac_f32_e32 v85, 0.5, v26
	v_fmac_f32_e32 v22, v84, v84
	v_cvt_pk_bf16_f32 v18, v82, v82
	v_fmac_f32_e32 v22, v85, v85
	global_store_short v[78:79], v18, off
	v_cvt_pk_bf16_f32 v26, v83, v83
	v_cvt_pk_bf16_f32 v30, v84, v84
	v_cvt_pk_bf16_f32 v80, v85, v85
	global_store_short v[78:79], v26, off offset:32
	global_store_short v[78:79], v30, off offset:256
	global_store_short v[78:79], v80, off offset:288
	v_add_f32_dpp v18, v22, v22 quad_perm:[1,0,3,2] row_mask:0xf bank_mask:0xf bound_ctrl:1
	v_mov_b32_e32 v22, 0
	s_nop 0
	v_add_f32_dpp v18, v18, v18 quad_perm:[2,3,0,1] row_mask:0xf bank_mask:0xf bound_ctrl:1
	s_nop 1
	v_add_f32_dpp v18, v18, v18 row_half_mirror row_mask:0xf bank_mask:0xf bound_ctrl:1
	s_nop 1
	v_mov_b32_dpp v22, v18 row_mirror row_mask:0xf bank_mask:0xf
	s_and_saveexec_b64 s[14:15], vcc
	s_cbranch_execz .LBB0_285
	v_lshlrev_b64 v[48:49], 6, v[48:49]
	v_add_f32_e32 v18, v18, v22
	v_lshl_add_u64 v[48:49], v[132:133], 0, v[48:49]
	global_store_dword v[48:49], v18, off
.LBB0_285:
	s_or_b64 exec, exec, s[14:15]
	v_lshlrev_b64 v[48:49], 11, v[46:47]
	v_lshl_add_u64 v[48:49], v[134:135], 0, v[48:49]
	v_fmac_f32_e32 v77, 0.5, v23
	v_cvt_pk_bf16_f32 v18, v77, v77
	v_fmac_f32_e32 v76, 0.5, v19
	global_store_short v[48:49], v18, off
	v_mul_f32_e32 v18, v76, v76
	v_fmac_f32_e32 v18, v77, v77
	v_fmac_f32_e32 v75, 0.5, v31
	v_fmac_f32_e32 v18, v75, v75
	v_fmac_f32_e32 v74, 0.5, v27
	v_cvt_pk_bf16_f32 v19, v76, v76
	v_fmac_f32_e32 v18, v74, v74
	global_store_short v[48:49], v19, off offset:32
	v_cvt_pk_bf16_f32 v19, v75, v75
	global_store_short v[48:49], v19, off offset:256
	v_add_f32_dpp v18, v18, v18 quad_perm:[1,0,3,2] row_mask:0xf bank_mask:0xf bound_ctrl:1
	v_cvt_pk_bf16_f32 v19, v74, v74
	global_store_short v[48:49], v19, off offset:288
	v_mov_b32_e32 v19, 0
	v_add_f32_dpp v18, v18, v18 quad_perm:[2,3,0,1] row_mask:0xf bank_mask:0xf bound_ctrl:1
	s_nop 1
	v_add_f32_dpp v18, v18, v18 row_half_mirror row_mask:0xf bank_mask:0xf bound_ctrl:1
	s_nop 1
	v_mov_b32_dpp v19, v18 row_mirror row_mask:0xf bank_mask:0xf
	s_and_saveexec_b64 s[14:15], vcc
	s_cbranch_execz .LBB0_287
	v_add_f32_e32 v22, v18, v19
	v_lshlrev_b64 v[18:19], 6, v[46:47]
	v_lshl_add_u64 v[18:19], v[132:133], 0, v[18:19]
	global_store_dword v[18:19], v22, off
.LBB0_287:
	s_or_b64 exec, exec, s[14:15]
	v_fmac_f32_e32 v72, 0.5, v20
	v_lshlrev_b64 v[18:19], 11, v[44:45]
	v_fmac_f32_e32 v73, 0.5, v24
	v_mul_f32_e32 v20, v72, v72
	v_lshl_add_u64 v[18:19], v[134:135], 0, v[18:19]
	v_cvt_pk_bf16_f32 v22, v73, v73
	v_fmac_f32_e32 v20, v73, v73
	v_fmac_f32_e32 v71, 0.5, v32
	global_store_short v[18:19], v22, off
	v_cvt_pk_bf16_f32 v22, v72, v72
	v_fmac_f32_e32 v20, v71, v71
	v_fmac_f32_e32 v70, 0.5, v28
	global_store_short v[18:19], v22, off offset:32
	v_cvt_pk_bf16_f32 v22, v71, v71
	v_fmac_f32_e32 v20, v70, v70
	global_store_short v[18:19], v22, off offset:256
	v_cvt_pk_bf16_f32 v22, v70, v70
	global_store_short v[18:19], v22, off offset:288
	v_add_f32_dpp v18, v20, v20 quad_perm:[1,0,3,2] row_mask:0xf bank_mask:0xf bound_ctrl:1
	v_mov_b32_e32 v19, 0
	s_nop 0
	v_add_f32_dpp v18, v18, v18 quad_perm:[2,3,0,1] row_mask:0xf bank_mask:0xf bound_ctrl:1
	s_nop 1
	v_add_f32_dpp v18, v18, v18 row_half_mirror row_mask:0xf bank_mask:0xf bound_ctrl:1
	s_nop 1
	v_mov_b32_dpp v19, v18 row_mirror row_mask:0xf bank_mask:0xf
	s_and_saveexec_b64 s[14:15], vcc
	s_cbranch_execz .LBB0_289
	v_add_f32_e32 v20, v18, v19
	v_lshlrev_b64 v[18:19], 6, v[44:45]
	v_lshl_add_u64 v[18:19], v[132:133], 0, v[18:19]
	global_store_dword v[18:19], v20, off
.LBB0_289:
	s_or_b64 exec, exec, s[14:15]
	v_lshlrev_b64 v[18:19], 11, v[42:43]
	v_lshl_add_u64 v[18:19], v[134:135], 0, v[18:19]
	v_fmac_f32_e32 v69, 0.5, v25
	v_cvt_pk_bf16_f32 v20, v69, v69
	v_fmac_f32_e32 v68, 0.5, v21
	global_store_short v[18:19], v20, off
	v_mul_f32_e32 v20, v68, v68
	v_fmac_f32_e32 v20, v69, v69
	v_fmac_f32_e32 v67, 0.5, v33
	v_cvt_pk_bf16_f32 v21, v68, v68
	v_fmac_f32_e32 v20, v67, v67
	v_fmac_f32_e32 v66, 0.5, v29
	global_store_short v[18:19], v21, off offset:32
	v_cvt_pk_bf16_f32 v21, v67, v67
	v_fmac_f32_e32 v20, v66, v66
	global_store_short v[18:19], v21, off offset:256
	v_cvt_pk_bf16_f32 v21, v66, v66
	global_store_short v[18:19], v21, off offset:288
	v_add_f32_dpp v18, v20, v20 quad_perm:[1,0,3,2] row_mask:0xf bank_mask:0xf bound_ctrl:1
	v_mov_b32_e32 v19, 0
	s_nop 0
	v_add_f32_dpp v18, v18, v18 quad_perm:[2,3,0,1] row_mask:0xf bank_mask:0xf bound_ctrl:1
	s_nop 1
	v_add_f32_dpp v18, v18, v18 row_half_mirror row_mask:0xf bank_mask:0xf bound_ctrl:1
	s_nop 1
	v_mov_b32_dpp v19, v18 row_mirror row_mask:0xf bank_mask:0xf
	s_and_saveexec_b64 s[14:15], vcc
	s_cbranch_execz .LBB0_291
	v_add_f32_e32 v20, v18, v19
	v_lshlrev_b64 v[18:19], 6, v[42:43]
	v_lshl_add_u64 v[18:19], v[132:133], 0, v[18:19]
	global_store_dword v[18:19], v20, off
; __device__ __forceinline__ unsigned f2bf(float f) { return pk2(f, f) & 0xffffu; }
; template <int K, int LD>
; __device__ __forceinline__ void phase_resid(int mode) {
;     ...
;       for (int m2 = 0; m2 < 2; ++m2)
; #pragma unroll
;         for (int j = 0; j < 4; ++j) {
;           const int m = mh * 2 + m2; const int row = brow + ai * 128 + wr * 64 + m * 16 + fq * 4 + j;
;           float ss = 0.f;
; #pragma unroll
;           for (int bj = 0; bj < 2; ++bj)
; #pragma unroll
;             for (int n = 0; n < 2; ++n) {
;               const size_t idx = (size_t)row * DM + bcol + bj * 128 + wc * 32 + n * 16 + fr;
;               const float xn = xo[m2][j][bj][n] + scale * acc[ai][bj][m][n][j];
;               ss += xn * xn;
;               xg[idx] = (unsigned short)f2bf(xn);
;             }
;           ss = sum16(ss);
;           if (fr == 0) ssq[(size_t)row * 16 + pn0 * 4 + wc] = ss;
;         }
.LBB0_291:
	s_or_b64 exec, exec, s[14:15]
	v_fmac_f32_e32 v64, 0.5, v2
	v_fmac_f32_e32 v65, 0.5, v6
	v_mul_f32_e32 v2, v64, v64
	v_lshlrev_b64 v[18:19], 11, v[40:41]
	v_fmac_f32_e32 v2, v65, v65
	v_fmac_f32_e32 v63, 0.5, v14
	v_lshl_add_u64 v[18:19], v[134:135], 0, v[18:19]
	v_cvt_pk_bf16_f32 v6, v65, v65
	v_fmac_f32_e32 v2, v63, v63
	v_fmac_f32_e32 v62, 0.5, v10
	global_store_short v[18:19], v6, off
	v_cvt_pk_bf16_f32 v6, v64, v64
	v_fmac_f32_e32 v2, v62, v62
	global_store_short v[18:19], v6, off offset:32
	v_cvt_pk_bf16_f32 v6, v63, v63
	global_store_short v[18:19], v6, off offset:256
	v_add_f32_dpp v2, v2, v2 quad_perm:[1,0,3,2] row_mask:0xf bank_mask:0xf bound_ctrl:1
	v_cvt_pk_bf16_f32 v6, v62, v62
	global_store_short v[18:19], v6, off offset:288
	v_mov_b32_e32 v6, 0
	v_add_f32_dpp v2, v2, v2 quad_perm:[2,3,0,1] row_mask:0xf bank_mask:0xf bound_ctrl:1
	s_nop 1
	v_add_f32_dpp v2, v2, v2 row_half_mirror row_mask:0xf bank_mask:0xf bound_ctrl:1
	s_nop 1
	v_mov_b32_dpp v6, v2 row_mirror row_mask:0xf bank_mask:0xf
	s_and_saveexec_b64 s[14:15], vcc
	s_cbranch_execz .LBB0_293
	v_lshlrev_b64 v[18:19], 6, v[40:41]
	v_add_f32_e32 v2, v2, v6
	v_lshl_add_u64 v[18:19], v[132:133], 0, v[18:19]
	global_store_dword v[18:19], v2, off
.LBB0_293:
	s_or_b64 exec, exec, s[14:15]
	v_lshlrev_b64 v[18:19], 11, v[38:39]
	v_lshl_add_u64 v[18:19], v[134:135], 0, v[18:19]
	v_fmac_f32_e32 v61, 0.5, v7
	v_cvt_pk_bf16_f32 v2, v61, v61
	v_fmac_f32_e32 v60, 0.5, v3
	global_store_short v[18:19], v2, off
	v_mul_f32_e32 v2, v60, v60
	v_fmac_f32_e32 v2, v61, v61
	v_fmac_f32_e32 v59, 0.5, v15
	v_fmac_f32_e32 v2, v59, v59
	v_fmac_f32_e32 v58, 0.5, v11
	v_cvt_pk_bf16_f32 v3, v60, v60
	v_fmac_f32_e32 v2, v58, v58
	global_store_short v[18:19], v3, off offset:32
	v_cvt_pk_bf16_f32 v3, v59, v59
	global_store_short v[18:19], v3, off offset:256
	v_add_f32_dpp v2, v2, v2 quad_perm:[1,0,3,2] row_mask:0xf bank_mask:0xf bound_ctrl:1
	v_cvt_pk_bf16_f32 v3, v58, v58
	global_store_short v[18:19], v3, off offset:288
	v_mov_b32_e32 v3, 0
	v_add_f32_dpp v2, v2, v2 quad_perm:[2,3,0,1] row_mask:0xf bank_mask:0xf bound_ctrl:1
	s_nop 1
	v_add_f32_dpp v2, v2, v2 row_half_mirror row_mask:0xf bank_mask:0xf bound_ctrl:1
	s_nop 1
	v_mov_b32_dpp v3, v2 row_mirror row_mask:0xf bank_mask:0xf
	s_and_saveexec_b64 s[14:15], vcc
	s_cbranch_execz .LBB0_295
	v_add_f32_e32 v6, v2, v3
	v_lshlrev_b64 v[2:3], 6, v[38:39]
	v_lshl_add_u64 v[2:3], v[132:133], 0, v[2:3]
	global_store_dword v[2:3], v6, off
.LBB0_295:
	s_or_b64 exec, exec, s[14:15]
	v_fmac_f32_e32 v56, 0.5, v4
	v_lshlrev_b64 v[2:3], 11, v[36:37]
	v_fmac_f32_e32 v57, 0.5, v8
	v_mul_f32_e32 v4, v56, v56
	v_lshl_add_u64 v[2:3], v[134:135], 0, v[2:3]
	v_cvt_pk_bf16_f32 v6, v57, v57
	v_fmac_f32_e32 v4, v57, v57
	v_fmac_f32_e32 v55, 0.5, v16
	global_store_short v[2:3], v6, off
	v_cvt_pk_bf16_f32 v6, v56, v56
	v_fmac_f32_e32 v4, v55, v55
	v_fmac_f32_e32 v54, 0.5, v12
	global_store_short v[2:3], v6, off offset:32
	v_cvt_pk_bf16_f32 v6, v55, v55
	v_fmac_f32_e32 v4, v54, v54
	global_store_short v[2:3], v6, off offset:256
	v_cvt_pk_bf16_f32 v6, v54, v54
	global_store_short v[2:3], v6, off offset:288
	v_add_f32_dpp v2, v4, v4 quad_perm:[1,0,3,2] row_mask:0xf bank_mask:0xf bound_ctrl:1
	v_mov_b32_e32 v3, 0
	s_nop 0
	v_add_f32_dpp v2, v2, v2 quad_perm:[2,3,0,1] row_mask:0xf bank_mask:0xf bound_ctrl:1
	s_nop 1
	v_add_f32_dpp v2, v2, v2 row_half_mirror row_mask:0xf bank_mask:0xf bound_ctrl:1
	s_nop 1
	v_mov_b32_dpp v3, v2 row_mirror row_mask:0xf bank_mask:0xf
	s_and_saveexec_b64 s[14:15], vcc
	s_cbranch_execz .LBB0_297
	v_add_f32_e32 v4, v2, v3
	v_lshlrev_b64 v[2:3], 6, v[36:37]
	v_lshl_add_u64 v[2:3], v[132:133], 0, v[2:3]
	global_store_dword v[2:3], v4, off
.LBB0_297:
	s_or_b64 exec, exec, s[14:15]
	v_lshlrev_b64 v[2:3], 11, v[34:35]
	v_lshl_add_u64 v[2:3], v[134:135], 0, v[2:3]
	v_fmac_f32_e32 v53, 0.5, v9
	v_cvt_pk_bf16_f32 v4, v53, v53
	v_fmac_f32_e32 v52, 0.5, v5
	global_store_short v[2:3], v4, off
	v_mul_f32_e32 v4, v52, v52
	v_fmac_f32_e32 v4, v53, v53
	v_fmac_f32_e32 v51, 0.5, v17
	v_cvt_pk_bf16_f32 v5, v52, v52
	v_fmac_f32_e32 v4, v51, v51
	v_fmac_f32_e32 v50, 0.5, v13
	global_store_short v[2:3], v5, off offset:32
	v_cvt_pk_bf16_f32 v5, v51, v51
	v_fmac_f32_e32 v4, v50, v50
	global_store_short v[2:3], v5, off offset:256
	v_cvt_pk_bf16_f32 v5, v50, v50
	global_store_short v[2:3], v5, off offset:288
	v_add_f32_dpp v2, v4, v4 quad_perm:[1,0,3,2] row_mask:0xf bank_mask:0xf bound_ctrl:1
	v_mov_b32_e32 v3, 0
	s_nop 0
	v_add_f32_dpp v2, v2, v2 quad_perm:[2,3,0,1] row_mask:0xf bank_mask:0xf bound_ctrl:1
	s_nop 1
	v_add_f32_dpp v2, v2, v2 row_half_mirror row_mask:0xf bank_mask:0xf bound_ctrl:1
	s_nop 1
	v_mov_b32_dpp v3, v2 row_mirror row_mask:0xf bank_mask:0xf
	s_and_saveexec_b64 s[14:15], vcc
	s_cbranch_execz .LBB0_226
	v_add_f32_e32 v4, v2, v3
	v_lshlrev_b64 v[2:3], 6, v[34:35]
	v_lshl_add_u64 v[2:3], v[132:133], 0, v[2:3]
	global_store_dword v[2:3], v4, off
	s_branch .LBB0_226

; #define GAS __attribute__((address_space(1)))
; __device__ __forceinline__ float sigmoidf_(float v) { return __builtin_amdgcn_rcpf(1.f + __builtin_amdgcn_exp2f(-LOG2E * v)); }
; __device__ __forceinline__ void phase_inproj() {
;     ...
;       if (pn < 12) { const int reg = pn >> 1; ld = AW; coff = (pn & 1) * 256;
;         dst = (GAS unsigned short*)(ws + OFF_RA + (reg == 2 ? RA_VF : reg == 3 ? RA_QS : reg == 4 ? RA_KS : RA_VS)); }
;       else if (pn < 16) { ld = DM; coff = (pn - 12) * 256; dst = (GAS unsigned short*)(ws + OFF_SGF); sg = true; }
;       else { ld = DM; coff = (pn - 16) * 256; dst = (GAS unsigned short*)(ws + OFF_SGS); sg = true; }
;     ...
;       if (sg) { INPROJ_STORE(sigmoidf_(v)) } else { INPROJ_STORE(v) }
.LBB0_368:
	v_lshlrev_b32_e32 v130, 6, v149
	v_lshl_or_b32 v134, v148, 2, v130
	s_lshl_b64 s[30:31], s[20:21], 1
	v_lshl_add_u32 v150, v134, 2, s5
	s_add_u32 s30, s36, s30
	ds_read_b32 v136, v150
	s_addc_u32 s31, s37, s31
	v_lshlrev_b32_e32 v130, 6, v147
	v_lshl_add_u64 v[132:133], s[30:31], 0, v[130:131]
	v_lshlrev_b32_e32 v130, 1, v146
	v_lshl_add_u64 v[132:133], v[132:133], 0, v[130:131]
	v_add_u32_e32 v130, s4, v134
	v_mad_i64_i32 v[134:135], s[30:31], s28, v130, 0
	v_lshl_add_u64 v[134:135], v[134:135], 1, v[132:133]
	s_waitcnt lgkmcnt(0)
	v_mul_f32_e32 v178, v114, v136
	s_mov_b64 s[30:31], -1
	s_andn2_b64 vcc, exec, s[34:35]
	v_add_u32_e32 v142, 0x80, v130
	v_add_u32_e32 v157, 0x81, v130
	v_add_u32_e32 v156, 0x82, v130
	v_mul_f32_e32 v179, v118, v136
	v_mul_f32_e32 v177, v122, v136
	v_mul_f32_e32 v176, v126, v136
	v_add_u32_e32 v175, 1, v130
	v_add_u32_e32 v174, 2, v130
	v_add_u32_e32 v169, 3, v130
	v_add_u32_e32 v168, 16, v130
	v_add_u32_e32 v167, 17, v130
	v_add_u32_e32 v166, 18, v130
	v_add_u32_e32 v165, 19, v130
	v_add_u32_e32 v164, 32, v130
	v_add_u32_e32 v163, 33, v130
	v_add_u32_e32 v162, 34, v130
	v_add_u32_e32 v161, 35, v130
	v_add_u32_e32 v160, 48, v130
	v_add_u32_e32 v159, 49, v130
	v_add_u32_e32 v158, 50, v130
	v_add_u32_e32 v143, 51, v130
	v_add_u32_e32 v155, 0x83, v130
	v_add_u32_e32 v154, 0x90, v130
	v_add_u32_e32 v153, 0x91, v130
	v_add_u32_e32 v152, 0x92, v130
	v_add_u32_e32 v151, 0x93, v130
	s_cbranch_vccnz .LBB0_370
	v_cvt_pk_bf16_f32 v136, v178, v178
	global_store_short v[134:135], v136, off
	v_cvt_pk_bf16_f32 v136, v179, v179
	global_store_short v[134:135], v136, off offset:32
	v_cvt_pk_bf16_f32 v136, v177, v177
	global_store_short v[134:135], v136, off offset:256
	v_cvt_pk_bf16_f32 v136, v176, v176
	global_store_short v[134:135], v136, off offset:288
	v_mad_i64_i32 v[136:137], s[30:31], s28, v175, 0
	v_lshl_add_u64 v[140:141], v[136:137], 1, v[132:133]
	ds_read2_b32 v[138:139], v150 offset0:1 offset1:2
	ds_read2_b32 v[136:137], v150 offset0:3 offset1:16
	ds_read2_b32 v[180:181], v150 offset0:17 offset1:18
	ds_read2_b32 v[182:183], v150 offset0:33 offset1:34
	ds_read2_b32 v[184:185], v150 offset0:49 offset1:50
	s_waitcnt lgkmcnt(0)
	v_mul_f32_e32 v186, v115, v138
	v_cvt_pk_bf16_f32 v186, v186, v186
	global_store_short v[140:141], v186, off
	v_mul_f32_e32 v186, v119, v138
	v_cvt_pk_bf16_f32 v186, v186, v186
	global_store_short v[140:141], v186, off offset:32
	v_mul_f32_e32 v186, v123, v138
	v_mul_f32_e32 v138, v127, v138
	v_cvt_pk_bf16_f32 v138, v138, v138
	v_cvt_pk_bf16_f32 v186, v186, v186
	global_store_short v[140:141], v186, off offset:256
	global_store_short v[140:141], v138, off offset:288
	v_mad_i64_i32 v[140:141], s[30:31], s28, v174, 0
	v_mul_f32_e32 v138, v116, v139
	v_lshl_add_u64 v[140:141], v[140:141], 1, v[132:133]
	v_cvt_pk_bf16_f32 v138, v138, v138
	global_store_short v[140:141], v138, off
	v_mul_f32_e32 v138, v120, v139
	v_cvt_pk_bf16_f32 v138, v138, v138
	global_store_short v[140:141], v138, off offset:32
	v_mul_f32_e32 v138, v124, v139
	v_cvt_pk_bf16_f32 v138, v138, v138
	global_store_short v[140:141], v138, off offset:256
	v_mul_f32_e32 v138, v128, v139
	v_cvt_pk_bf16_f32 v138, v138, v138
	global_store_short v[140:141], v138, off offset:288
	v_mad_i64_i32 v[138:139], s[30:31], s28, v169, 0
	v_mul_f32_e32 v140, v117, v136
	v_lshl_add_u64 v[138:139], v[138:139], 1, v[132:133]
	v_cvt_pk_bf16_f32 v140, v140, v140
	global_store_short v[138:139], v140, off
	v_mul_f32_e32 v140, v121, v136
	v_cvt_pk_bf16_f32 v140, v140, v140
	global_store_short v[138:139], v140, off offset:32
	v_mul_f32_e32 v140, v125, v136
	v_mul_f32_e32 v136, v129, v136
	v_cvt_pk_bf16_f32 v136, v136, v136
	v_cvt_pk_bf16_f32 v140, v140, v140
	global_store_short v[138:139], v140, off offset:256
	global_store_short v[138:139], v136, off offset:288
	v_mad_i64_i32 v[138:139], s[30:31], s28, v168, 0
	v_mul_f32_e32 v136, v102, v137
	v_lshl_add_u64 v[138:139], v[138:139], 1, v[132:133]
	v_cvt_pk_bf16_f32 v136, v136, v136
	global_store_short v[138:139], v136, off
	v_mul_f32_e32 v136, v98, v137
	v_cvt_pk_bf16_f32 v136, v136, v136
	global_store_short v[138:139], v136, off offset:32
	v_mul_f32_e32 v136, v106, v137
	v_cvt_pk_bf16_f32 v136, v136, v136
	global_store_short v[138:139], v136, off offset:256
	v_mul_f32_e32 v136, v110, v137
	v_cvt_pk_bf16_f32 v136, v136, v136
	global_store_short v[138:139], v136, off offset:288
	v_mad_i64_i32 v[136:137], s[30:31], s28, v167, 0
	v_mul_f32_e32 v138, v103, v180
	v_lshl_add_u64 v[136:137], v[136:137], 1, v[132:133]
	v_cvt_pk_bf16_f32 v138, v138, v138
	global_store_short v[136:137], v138, off
	v_mul_f32_e32 v138, v99, v180
	v_cvt_pk_bf16_f32 v138, v138, v138
	global_store_short v[136:137], v138, off offset:32
	v_mul_f32_e32 v138, v107, v180
	v_cvt_pk_bf16_f32 v138, v138, v138
	global_store_short v[136:137], v138, off offset:256
	v_mul_f32_e32 v138, v111, v180
	v_cvt_pk_bf16_f32 v138, v138, v138
	global_store_short v[136:137], v138, off offset:288
	v_mad_i64_i32 v[136:137], s[30:31], s28, v166, 0
	v_mul_f32_e32 v138, v104, v181
	v_lshl_add_u64 v[136:137], v[136:137], 1, v[132:133]
	v_cvt_pk_bf16_f32 v138, v138, v138
	global_store_short v[136:137], v138, off
	v_mul_f32_e32 v138, v100, v181
	v_cvt_pk_bf16_f32 v138, v138, v138
	global_store_short v[136:137], v138, off offset:32
	v_mul_f32_e32 v138, v108, v181
	v_cvt_pk_bf16_f32 v138, v138, v138
	global_store_short v[136:137], v138, off offset:256
	v_mul_f32_e32 v138, v112, v181
	v_cvt_pk_bf16_f32 v140, v138, v138
	ds_read2_b32 v[138:139], v150 offset0:19 offset1:32
	global_store_short v[136:137], v140, off offset:288
	v_mad_i64_i32 v[136:137], s[30:31], s28, v165, 0
	v_lshl_add_u64 v[136:137], v[136:137], 1, v[132:133]
	s_waitcnt lgkmcnt(0)
; __device__ __forceinline__ float sigmoidf_(float v) { return __builtin_amdgcn_rcpf(1.f + __builtin_amdgcn_exp2f(-LOG2E * v)); }
; __device__ __forceinline__ void phase_inproj() {
;     ...
;       if (sg) { INPROJ_STORE(sigmoidf_(v)) } else { INPROJ_STORE(v) }
	v_mul_f32_e32 v140, v105, v138
	v_cvt_pk_bf16_f32 v140, v140, v140
	global_store_short v[136:137], v140, off
	v_mul_f32_e32 v140, v101, v138
	v_cvt_pk_bf16_f32 v140, v140, v140
	global_store_short v[136:137], v140, off offset:32
	v_mul_f32_e32 v140, v109, v138
	v_mul_f32_e32 v138, v113, v138
	v_cvt_pk_bf16_f32 v138, v138, v138
	v_cvt_pk_bf16_f32 v140, v140, v140
	global_store_short v[136:137], v140, off offset:256
	global_store_short v[136:137], v138, off offset:288
	v_mad_i64_i32 v[136:137], s[30:31], s28, v164, 0
	v_mul_f32_e32 v138, v82, v139
	v_lshl_add_u64 v[136:137], v[136:137], 1, v[132:133]
	v_cvt_pk_bf16_f32 v138, v138, v138
	global_store_short v[136:137], v138, off
	v_mul_f32_e32 v138, v86, v139
	v_cvt_pk_bf16_f32 v138, v138, v138
	global_store_short v[136:137], v138, off offset:32
	v_mul_f32_e32 v138, v90, v139
	v_cvt_pk_bf16_f32 v138, v138, v138
	global_store_short v[136:137], v138, off offset:256
	v_mul_f32_e32 v138, v94, v139
	v_cvt_pk_bf16_f32 v138, v138, v138
	global_store_short v[136:137], v138, off offset:288
	v_mad_i64_i32 v[136:137], s[30:31], s28, v163, 0
	v_mul_f32_e32 v138, v83, v182
	v_lshl_add_u64 v[136:137], v[136:137], 1, v[132:133]
	v_cvt_pk_bf16_f32 v138, v138, v138
	global_store_short v[136:137], v138, off
	v_mul_f32_e32 v138, v87, v182
	v_cvt_pk_bf16_f32 v138, v138, v138
	global_store_short v[136:137], v138, off offset:32
	v_mul_f32_e32 v138, v91, v182
	v_cvt_pk_bf16_f32 v138, v138, v138
	global_store_short v[136:137], v138, off offset:256
	v_mul_f32_e32 v138, v95, v182
	v_cvt_pk_bf16_f32 v138, v138, v138
	global_store_short v[136:137], v138, off offset:288
	v_mad_i64_i32 v[136:137], s[30:31], s28, v162, 0
	v_mul_f32_e32 v138, v84, v183
	v_lshl_add_u64 v[136:137], v[136:137], 1, v[132:133]
	v_cvt_pk_bf16_f32 v138, v138, v138
	global_store_short v[136:137], v138, off
	v_mul_f32_e32 v138, v88, v183
	v_cvt_pk_bf16_f32 v138, v138, v138
	global_store_short v[136:137], v138, off offset:32
	v_mul_f32_e32 v138, v92, v183
	v_cvt_pk_bf16_f32 v138, v138, v138
	global_store_short v[136:137], v138, off offset:256
	v_mul_f32_e32 v138, v96, v183
	v_cvt_pk_bf16_f32 v140, v138, v138
	ds_read2_b32 v[138:139], v150 offset0:35 offset1:48
	global_store_short v[136:137], v140, off offset:288
	v_mad_i64_i32 v[136:137], s[30:31], s28, v161, 0
	v_lshl_add_u64 v[136:137], v[136:137], 1, v[132:133]
	s_waitcnt lgkmcnt(0)
	v_mul_f32_e32 v140, v85, v138
	v_cvt_pk_bf16_f32 v140, v140, v140
	global_store_short v[136:137], v140, off
	v_mul_f32_e32 v140, v89, v138
	v_cvt_pk_bf16_f32 v140, v140, v140
	global_store_short v[136:137], v140, off offset:32
	v_mul_f32_e32 v140, v93, v138
	v_mul_f32_e32 v138, v97, v138
	v_cvt_pk_bf16_f32 v138, v138, v138
	v_cvt_pk_bf16_f32 v140, v140, v140
	global_store_short v[136:137], v140, off offset:256
	global_store_short v[136:137], v138, off offset:288
	v_mad_i64_i32 v[136:137], s[30:31], s28, v160, 0
	v_mul_f32_e32 v138, v70, v139
	v_lshl_add_u64 v[136:137], v[136:137], 1, v[132:133]
	v_cvt_pk_bf16_f32 v138, v138, v138
	global_store_short v[136:137], v138, off
	v_mul_f32_e32 v138, v66, v139
	v_cvt_pk_bf16_f32 v138, v138, v138
	global_store_short v[136:137], v138, off offset:32
	v_mul_f32_e32 v138, v74, v139
	v_cvt_pk_bf16_f32 v138, v138, v138
	global_store_short v[136:137], v138, off offset:256
	v_mul_f32_e32 v138, v78, v139
	v_cvt_pk_bf16_f32 v138, v138, v138
	global_store_short v[136:137], v138, off offset:288
	v_mad_i64_i32 v[136:137], s[30:31], s28, v159, 0
	v_mul_f32_e32 v138, v71, v184
	v_lshl_add_u64 v[136:137], v[136:137], 1, v[132:133]
	v_cvt_pk_bf16_f32 v138, v138, v138
	global_store_short v[136:137], v138, off
	v_mul_f32_e32 v138, v67, v184
	v_cvt_pk_bf16_f32 v138, v138, v138
	global_store_short v[136:137], v138, off offset:32
	v_mul_f32_e32 v138, v75, v184
	v_cvt_pk_bf16_f32 v138, v138, v138
	global_store_short v[136:137], v138, off offset:256
	v_mul_f32_e32 v138, v79, v184
	v_cvt_pk_bf16_f32 v138, v138, v138
	global_store_short v[136:137], v138, off offset:288
	v_mad_i64_i32 v[136:137], s[30:31], s28, v158, 0
	v_mul_f32_e32 v138, v72, v185
	v_lshl_add_u64 v[136:137], v[136:137], 1, v[132:133]
	v_cvt_pk_bf16_f32 v138, v138, v138
	global_store_short v[136:137], v138, off
	v_mul_f32_e32 v138, v68, v185
	v_cvt_pk_bf16_f32 v138, v138, v138
	global_store_short v[136:137], v138, off offset:32
	v_mul_f32_e32 v138, v76, v185
	v_cvt_pk_bf16_f32 v138, v138, v138
	global_store_short v[136:137], v138, off offset:256
	v_mul_f32_e32 v138, v80, v185
	v_cvt_pk_bf16_f32 v140, v138, v138
	ds_read2_b32 v[138:139], v150 offset0:51 offset1:128
	global_store_short v[136:137], v140, off offset:288
	v_mad_i64_i32 v[136:137], s[30:31], s28, v143, 0
	v_lshl_add_u64 v[136:137], v[136:137], 1, v[132:133]
	s_waitcnt lgkmcnt(0)
	v_mul_f32_e32 v140, v73, v138
	v_cvt_pk_bf16_f32 v140, v140, v140
	global_store_short v[136:137], v140, off
	v_mul_f32_e32 v140, v69, v138
	v_cvt_pk_bf16_f32 v140, v140, v140
	global_store_short v[136:137], v140, off offset:32
	v_mul_f32_e32 v140, v77, v138
	v_mul_f32_e32 v138, v81, v138
	v_cvt_pk_bf16_f32 v138, v138, v138
	v_cvt_pk_bf16_f32 v140, v140, v140
	global_store_short v[136:137], v140, off offset:256
	global_store_short v[136:137], v138, off offset:288
	v_mad_i64_i32 v[136:137], s[30:31], s28, v142, 0
	v_mul_f32_e32 v138, v50, v139
	v_lshl_add_u64 v[136:137], v[136:137], 1, v[132:133]
	v_cvt_pk_bf16_f32 v138, v138, v138
	global_store_short v[136:137], v138, off
	v_mul_f32_e32 v138, v54, v139
	v_cvt_pk_bf16_f32 v138, v138, v138
	global_store_short v[136:137], v138, off offset:32
	v_mul_f32_e32 v138, v58, v139
	v_cvt_pk_bf16_f32 v138, v138, v138
	global_store_short v[136:137], v138, off offset:256
	v_mul_f32_e32 v138, v62, v139
	v_cvt_pk_bf16_f32 v138, v138, v138
	global_store_short v[136:137], v138, off offset:288
	ds_read2_b32 v[136:137], v150 offset0:129 offset1:130
	v_mad_i64_i32 v[138:139], s[30:31], s28, v157, 0
	v_lshl_add_u64 v[138:139], v[138:139], 1, v[132:133]
	ds_read2_b32 v[140:141], v150 offset0:145 offset1:146
	ds_read2_b32 v[180:181], v150 offset0:161 offset1:162
	ds_read2_b32 v[182:183], v150 offset0:177 offset1:178
	s_waitcnt lgkmcnt(0)
; __device__ __forceinline__ float sigmoidf_(float v) { return __builtin_amdgcn_rcpf(1.f + __builtin_amdgcn_exp2f(-LOG2E * v)); }
; __device__ __forceinline__ void phase_inproj() {
;     ...
;       if (sg) { INPROJ_STORE(sigmoidf_(v)) } else { INPROJ_STORE(v) }
	v_mul_f32_e32 v184, v51, v136
	v_cvt_pk_bf16_f32 v184, v184, v184
	global_store_short v[138:139], v184, off
	v_mul_f32_e32 v184, v55, v136
	v_cvt_pk_bf16_f32 v184, v184, v184
	global_store_short v[138:139], v184, off offset:32
	v_mul_f32_e32 v184, v59, v136
	v_mul_f32_e32 v136, v63, v136
	v_cvt_pk_bf16_f32 v136, v136, v136
	v_cvt_pk_bf16_f32 v184, v184, v184
	global_store_short v[138:139], v184, off offset:256
	global_store_short v[138:139], v136, off offset:288
	v_mad_i64_i32 v[138:139], s[30:31], s28, v156, 0
	v_mul_f32_e32 v136, v52, v137
	v_lshl_add_u64 v[138:139], v[138:139], 1, v[132:133]
	v_cvt_pk_bf16_f32 v136, v136, v136
	global_store_short v[138:139], v136, off
	v_mul_f32_e32 v136, v56, v137
	v_cvt_pk_bf16_f32 v136, v136, v136
	global_store_short v[138:139], v136, off offset:32
	v_mul_f32_e32 v136, v60, v137
	v_cvt_pk_bf16_f32 v136, v136, v136
	global_store_short v[138:139], v136, off offset:256
	v_mul_f32_e32 v136, v64, v137
	v_cvt_pk_bf16_f32 v184, v136, v136
	ds_read2_b32 v[136:137], v150 offset0:131 offset1:144
	global_store_short v[138:139], v184, off offset:288
	v_mad_i64_i32 v[138:139], s[30:31], s28, v155, 0
	v_lshl_add_u64 v[138:139], v[138:139], 1, v[132:133]
	s_waitcnt lgkmcnt(0)
	v_mul_f32_e32 v184, v53, v136
	v_cvt_pk_bf16_f32 v184, v184, v184
	global_store_short v[138:139], v184, off
	v_mul_f32_e32 v184, v57, v136
	v_cvt_pk_bf16_f32 v184, v184, v184
	global_store_short v[138:139], v184, off offset:32
	v_mul_f32_e32 v184, v61, v136
	v_mul_f32_e32 v136, v65, v136
	v_cvt_pk_bf16_f32 v136, v136, v136
	v_cvt_pk_bf16_f32 v184, v184, v184
	global_store_short v[138:139], v184, off offset:256
	global_store_short v[138:139], v136, off offset:288
	v_mad_i64_i32 v[138:139], s[30:31], s28, v154, 0
	v_mul_f32_e32 v136, v38, v137
	v_lshl_add_u64 v[138:139], v[138:139], 1, v[132:133]
	v_cvt_pk_bf16_f32 v136, v136, v136
	global_store_short v[138:139], v136, off
	v_mul_f32_e32 v136, v34, v137
	v_cvt_pk_bf16_f32 v136, v136, v136
	global_store_short v[138:139], v136, off offset:32
	v_mul_f32_e32 v136, v42, v137
	v_cvt_pk_bf16_f32 v136, v136, v136
	global_store_short v[138:139], v136, off offset:256
	v_mul_f32_e32 v136, v46, v137
	v_cvt_pk_bf16_f32 v136, v136, v136
	global_store_short v[138:139], v136, off offset:288
	v_mad_i64_i32 v[136:137], s[30:31], s28, v153, 0
	v_mul_f32_e32 v138, v39, v140
	v_lshl_add_u64 v[136:137], v[136:137], 1, v[132:133]
	v_cvt_pk_bf16_f32 v138, v138, v138
	global_store_short v[136:137], v138, off
	v_mul_f32_e32 v138, v35, v140
	v_cvt_pk_bf16_f32 v138, v138, v138
	global_store_short v[136:137], v138, off offset:32
	v_mul_f32_e32 v138, v43, v140
	v_cvt_pk_bf16_f32 v138, v138, v138
	global_store_short v[136:137], v138, off offset:256
	v_mul_f32_e32 v138, v47, v140
	v_cvt_pk_bf16_f32 v138, v138, v138
	global_store_short v[136:137], v138, off offset:288
	v_mad_i64_i32 v[136:137], s[30:31], s28, v152, 0
	v_mul_f32_e32 v138, v40, v141
	v_lshl_add_u64 v[136:137], v[136:137], 1, v[132:133]
	v_cvt_pk_bf16_f32 v138, v138, v138
	global_store_short v[136:137], v138, off
	v_mul_f32_e32 v138, v36, v141
	v_cvt_pk_bf16_f32 v138, v138, v138
	global_store_short v[136:137], v138, off offset:32
	v_mul_f32_e32 v138, v44, v141
	v_cvt_pk_bf16_f32 v138, v138, v138
	global_store_short v[136:137], v138, off offset:256
	v_mul_f32_e32 v138, v48, v141
	v_cvt_pk_bf16_f32 v140, v138, v138
	ds_read2_b32 v[138:139], v150 offset0:147 offset1:160
	global_store_short v[136:137], v140, off offset:288
	v_mad_i64_i32 v[136:137], s[30:31], s28, v151, 0
	v_lshl_add_u64 v[136:137], v[136:137], 1, v[132:133]
	s_waitcnt lgkmcnt(0)
	v_mul_f32_e32 v140, v41, v138
	v_cvt_pk_bf16_f32 v140, v140, v140
	global_store_short v[136:137], v140, off
	v_mul_f32_e32 v140, v37, v138
	v_cvt_pk_bf16_f32 v140, v140, v140
	global_store_short v[136:137], v140, off offset:32
	v_mul_f32_e32 v140, v45, v138
	v_mul_f32_e32 v138, v49, v138
	v_cvt_pk_bf16_f32 v140, v140, v140
	global_store_short v[136:137], v140, off offset:256
	v_cvt_pk_bf16_f32 v138, v138, v138
	global_store_short v[136:137], v138, off offset:288
	v_add_u32_e32 v136, 0xa0, v130
	v_mad_i64_i32 v[136:137], s[30:31], s28, v136, 0
	v_mul_f32_e32 v138, v18, v139
	v_lshl_add_u64 v[136:137], v[136:137], 1, v[132:133]
	v_cvt_pk_bf16_f32 v138, v138, v138
	global_store_short v[136:137], v138, off
	v_mul_f32_e32 v138, v22, v139
	v_cvt_pk_bf16_f32 v138, v138, v138
	global_store_short v[136:137], v138, off offset:32
	v_mul_f32_e32 v138, v26, v139
	v_cvt_pk_bf16_f32 v138, v138, v138
	global_store_short v[136:137], v138, off offset:256
	v_mul_f32_e32 v138, v30, v139
	v_cvt_pk_bf16_f32 v138, v138, v138
	global_store_short v[136:137], v138, off offset:288
	v_add_u32_e32 v136, 0xa1, v130
	v_mad_i64_i32 v[136:137], s[30:31], s28, v136, 0
	v_mul_f32_e32 v138, v19, v180
	v_lshl_add_u64 v[136:137], v[136:137], 1, v[132:133]
	v_cvt_pk_bf16_f32 v138, v138, v138
	global_store_short v[136:137], v138, off
	v_mul_f32_e32 v138, v23, v180
	v_cvt_pk_bf16_f32 v138, v138, v138
	global_store_short v[136:137], v138, off offset:32
	v_mul_f32_e32 v138, v27, v180
	v_cvt_pk_bf16_f32 v138, v138, v138
	global_store_short v[136:137], v138, off offset:256
	v_mul_f32_e32 v138, v31, v180
	v_cvt_pk_bf16_f32 v138, v138, v138
	global_store_short v[136:137], v138, off offset:288
	v_add_u32_e32 v136, 0xa2, v130
	v_mad_i64_i32 v[136:137], s[30:31], s28, v136, 0
	v_mul_f32_e32 v138, v20, v181
	v_lshl_add_u64 v[136:137], v[136:137], 1, v[132:133]
	v_cvt_pk_bf16_f32 v138, v138, v138
	global_store_short v[136:137], v138, off
	v_mul_f32_e32 v138, v24, v181
	v_cvt_pk_bf16_f32 v138, v138, v138
	global_store_short v[136:137], v138, off offset:32
	v_mul_f32_e32 v138, v28, v181
	v_cvt_pk_bf16_f32 v138, v138, v138
	global_store_short v[136:137], v138, off offset:256
	v_mul_f32_e32 v138, v32, v181
	v_cvt_pk_bf16_f32 v138, v138, v138
	global_store_short v[136:137], v138, off offset:288
	ds_read2_b32 v[136:137], v150 offset0:163 offset1:176
	v_add_u32_e32 v138, 0xa3, v130
	v_mad_i64_i32 v[138:139], s[30:31], s28, v138, 0
	v_lshl_add_u64 v[138:139], v[138:139], 1, v[132:133]
	s_waitcnt lgkmcnt(0)
; __device__ __forceinline__ float sigmoidf_(float v) { return __builtin_amdgcn_rcpf(1.f + __builtin_amdgcn_exp2f(-LOG2E * v)); }
; __device__ __forceinline__ void phase_inproj() {
;     ...
;       if (sg) { INPROJ_STORE(sigmoidf_(v)) } else { INPROJ_STORE(v) }
	v_mul_f32_e32 v140, v21, v136
	v_cvt_pk_bf16_f32 v140, v140, v140
	global_store_short v[138:139], v140, off
	v_mul_f32_e32 v140, v25, v136
	v_cvt_pk_bf16_f32 v140, v140, v140
	global_store_short v[138:139], v140, off offset:32
	v_mul_f32_e32 v140, v29, v136
	v_mul_f32_e32 v136, v33, v136
	v_cvt_pk_bf16_f32 v136, v136, v136
	global_store_short v[138:139], v136, off offset:288
	v_add_u32_e32 v136, 0xb0, v130
	v_cvt_pk_bf16_f32 v140, v140, v140
	global_store_short v[138:139], v140, off offset:256
	v_mad_i64_i32 v[138:139], s[30:31], s28, v136, 0
	v_mul_f32_e32 v136, v6, v137
	v_lshl_add_u64 v[138:139], v[138:139], 1, v[132:133]
	v_cvt_pk_bf16_f32 v136, v136, v136
	global_store_short v[138:139], v136, off
	v_mul_f32_e32 v136, v2, v137
	v_cvt_pk_bf16_f32 v136, v136, v136
	global_store_short v[138:139], v136, off offset:32
	v_mul_f32_e32 v136, v10, v137
	v_cvt_pk_bf16_f32 v136, v136, v136
	global_store_short v[138:139], v136, off offset:256
	v_mul_f32_e32 v136, v14, v137
	v_cvt_pk_bf16_f32 v136, v136, v136
	global_store_short v[138:139], v136, off offset:288
	v_add_u32_e32 v136, 0xb1, v130
	v_mad_i64_i32 v[136:137], s[30:31], s28, v136, 0
	v_mul_f32_e32 v138, v7, v182
	v_lshl_add_u64 v[136:137], v[136:137], 1, v[132:133]
	v_cvt_pk_bf16_f32 v138, v138, v138
	global_store_short v[136:137], v138, off
	v_mul_f32_e32 v138, v3, v182
	v_cvt_pk_bf16_f32 v138, v138, v138
	global_store_short v[136:137], v138, off offset:32
	v_mul_f32_e32 v138, v11, v182
	v_cvt_pk_bf16_f32 v138, v138, v138
	global_store_short v[136:137], v138, off offset:256
	v_mul_f32_e32 v138, v15, v182
	v_cvt_pk_bf16_f32 v138, v138, v138
	global_store_short v[136:137], v138, off offset:288
	v_add_u32_e32 v136, 0xb2, v130
	v_mad_i64_i32 v[136:137], s[30:31], s28, v136, 0
	v_mul_f32_e32 v138, v8, v183
	v_lshl_add_u64 v[136:137], v[136:137], 1, v[132:133]
	v_cvt_pk_bf16_f32 v138, v138, v138
	global_store_short v[136:137], v138, off
	v_mul_f32_e32 v138, v4, v183
	v_cvt_pk_bf16_f32 v138, v138, v138
	global_store_short v[136:137], v138, off offset:32
	v_mul_f32_e32 v138, v12, v183
	v_cvt_pk_bf16_f32 v138, v138, v138
	global_store_short v[136:137], v138, off offset:256
	v_mul_f32_e32 v138, v16, v183
	v_cvt_pk_bf16_f32 v138, v138, v138
	global_store_short v[136:137], v138, off offset:288
	ds_read_b32 v138, v150 offset:716
	v_add_u32_e32 v136, 0xb3, v130
	v_mad_i64_i32 v[136:137], s[30:31], s28, v136, 0
	v_lshl_add_u64 v[136:137], v[136:137], 1, v[132:133]
	s_waitcnt lgkmcnt(0)
	v_mul_f32_e32 v139, v9, v138
	v_cvt_pk_bf16_f32 v139, v139, v139
	global_store_short v[136:137], v139, off
	v_mul_f32_e32 v139, v5, v138
	v_cvt_pk_bf16_f32 v139, v139, v139
	global_store_short v[136:137], v139, off offset:32
	v_mul_f32_e32 v139, v13, v138
	v_mul_f32_e32 v138, v17, v138
	s_mov_b64 s[30:31], 0
	v_cvt_pk_bf16_f32 v139, v139, v139
	global_store_short v[136:137], v139, off offset:256
	v_cvt_pk_bf16_f32 v138, v138, v138
	global_store_short v[136:137], v138, off offset:288
.LBB0_370:
	s_andn2_b64 vcc, exec, s[30:31]
	s_cbranch_vccnz .LBB0_372
	v_mul_f32_e32 v136, 0xbfb8aa3b, v178
	v_exp_f32_e32 v136, v136
	v_mul_f32_e32 v137, 0xbfb8aa3b, v179
	v_exp_f32_e32 v137, v137
	v_mul_f32_e32 v138, 0xbfb8aa3b, v177
	v_add_f32_e32 v136, 1.0, v136
	v_rcp_f32_e32 v136, v136
	s_nop 0
	v_cvt_pk_bf16_f32 v136, v136, v136
	global_store_short v[134:135], v136, off
	v_mul_f32_e32 v136, 0xbfb8aa3b, v176
	v_exp_f32_e32 v138, v138
	v_exp_f32_e32 v136, v136
	v_add_f32_e32 v137, 1.0, v137
	v_rcp_f32_e32 v137, v137
	s_nop 0
	v_cvt_pk_bf16_f32 v137, v137, v137
	v_add_f32_e32 v138, 1.0, v138
	v_add_f32_e32 v136, 1.0, v136
	v_rcp_f32_e32 v138, v138
	v_rcp_f32_e32 v136, v136
	global_store_short v[134:135], v137, off offset:32
	v_cvt_pk_bf16_f32 v137, v138, v138
	global_store_short v[134:135], v137, off offset:256
	v_cvt_pk_bf16_f32 v138, v136, v136
	ds_read2_b32 v[136:137], v150 offset0:1 offset1:2
	global_store_short v[134:135], v138, off offset:288
	ds_read2_b32 v[134:135], v150 offset0:17 offset1:18
	ds_read2_b32 v[140:141], v150 offset0:33 offset1:34
	ds_read2_b32 v[138:139], v150 offset0:49 offset1:50
	s_waitcnt lgkmcnt(0)
	v_mul_f32_e32 v176, v115, v136
	v_mul_f32_e32 v176, 0xbfb8aa3b, v176
	v_exp_f32_e32 v178, v176
	v_mad_i64_i32 v[176:177], s[30:31], s28, v175, 0
	v_lshl_add_u64 v[176:177], v[176:177], 1, v[132:133]
	v_add_f32_e32 v175, 1.0, v178
	v_mul_f32_e32 v178, v119, v136
	v_mul_f32_e32 v178, 0xbfb8aa3b, v178
	v_exp_f32_e32 v180, v178
	v_rcp_f32_e32 v175, v175
	s_nop 0
	v_cvt_pk_bf16_f32 v175, v175, v175
	global_store_short v[176:177], v175, off
	v_add_f32_e32 v175, 1.0, v180
	v_mul_f32_e32 v180, v123, v136
	v_mul_f32_e32 v180, 0xbfb8aa3b, v180
	v_exp_f32_e32 v180, v180
	v_mul_f32_e32 v136, v127, v136
	v_mul_f32_e32 v136, 0xbfb8aa3b, v136
	v_rcp_f32_e32 v175, v175
	v_exp_f32_e32 v136, v136
	v_cvt_pk_bf16_f32 v175, v175, v175
	v_add_f32_e32 v180, 1.0, v180
	v_rcp_f32_e32 v180, v180
	global_store_short v[176:177], v175, off offset:32
	v_cvt_pk_bf16_f32 v175, v180, v180
	global_store_short v[176:177], v175, off offset:256
	v_mul_f32_e32 v175, v116, v137
	v_add_f32_e32 v136, 1.0, v136
	v_mul_f32_e32 v175, 0xbfb8aa3b, v175
	v_rcp_f32_e32 v136, v136
	v_exp_f32_e32 v180, v175
	v_cvt_pk_bf16_f32 v136, v136, v136
	global_store_short v[176:177], v136, off offset:288
	v_mul_f32_e32 v176, v120, v137
	v_mul_f32_e32 v176, 0xbfb8aa3b, v176
	v_exp_f32_e32 v176, v176
	v_add_f32_e32 v136, 1.0, v180
	v_mad_i64_i32 v[174:175], s[30:31], s28, v174, 0
	v_rcp_f32_e32 v136, v136
	v_lshl_add_u64 v[174:175], v[174:175], 1, v[132:133]
	v_cvt_pk_bf16_f32 v136, v136, v136
	global_store_short v[174:175], v136, off
	v_add_f32_e32 v136, 1.0, v176
	v_mul_f32_e32 v176, v124, v137
	v_mul_f32_e32 v137, v128, v137
	v_mul_f32_e32 v176, 0xbfb8aa3b, v176
	v_mul_f32_e32 v137, 0xbfb8aa3b, v137
	v_exp_f32_e32 v176, v176
	v_exp_f32_e32 v137, v137
	ds_read2_b32 v[178:179], v150 offset0:3 offset1:16
	v_rcp_f32_e32 v136, v136
	s_nop 0
	v_cvt_pk_bf16_f32 v136, v136, v136
	v_add_f32_e32 v176, 1.0, v176
	v_add_f32_e32 v137, 1.0, v137
	v_rcp_f32_e32 v176, v176
	v_rcp_f32_e32 v137, v137
	global_store_short v[174:175], v136, off offset:32
	v_cvt_pk_bf16_f32 v136, v176, v176
	global_store_short v[174:175], v136, off offset:256
	v_cvt_pk_bf16_f32 v136, v137, v137
	s_waitcnt lgkmcnt(0)
; __device__ __forceinline__ float sigmoidf_(float v) { return __builtin_amdgcn_rcpf(1.f + __builtin_amdgcn_exp2f(-LOG2E * v)); }
; __device__ __forceinline__ void phase_inproj() {
;     ...
;       if (sg) { INPROJ_STORE(sigmoidf_(v)) } else { INPROJ_STORE(v) }
	v_mul_f32_e32 v137, v117, v178
	v_mul_f32_e32 v137, 0xbfb8aa3b, v137
	v_exp_f32_e32 v176, v137
	global_store_short v[174:175], v136, off offset:288
	v_mul_f32_e32 v174, v121, v178
	v_mul_f32_e32 v174, 0xbfb8aa3b, v174
	v_exp_f32_e32 v174, v174
	v_mad_i64_i32 v[136:137], s[30:31], s28, v169, 0
	v_add_f32_e32 v169, 1.0, v176
	v_rcp_f32_e32 v169, v169
	v_lshl_add_u64 v[136:137], v[136:137], 1, v[132:133]
	v_cvt_pk_bf16_f32 v169, v169, v169
	global_store_short v[136:137], v169, off
	v_add_f32_e32 v169, 1.0, v174
	v_mul_f32_e32 v174, v125, v178
	v_mul_f32_e32 v174, 0xbfb8aa3b, v174
	v_exp_f32_e32 v174, v174
	v_mul_f32_e32 v175, v129, v178
	v_mul_f32_e32 v175, 0xbfb8aa3b, v175
	v_exp_f32_e32 v175, v175
	v_rcp_f32_e32 v169, v169
	v_add_f32_e32 v174, 1.0, v174
	v_cvt_pk_bf16_f32 v169, v169, v169
	v_rcp_f32_e32 v174, v174
	global_store_short v[136:137], v169, off offset:32
	v_cvt_pk_bf16_f32 v169, v174, v174
	v_mul_f32_e32 v174, v102, v179
	v_add_f32_e32 v175, 1.0, v175
	v_mul_f32_e32 v174, 0xbfb8aa3b, v174
	v_rcp_f32_e32 v175, v175
	global_store_short v[136:137], v169, off offset:256
	v_cvt_pk_bf16_f32 v169, v175, v175
	v_exp_f32_e32 v174, v174
	global_store_short v[136:137], v169, off offset:288
	v_mul_f32_e32 v169, v98, v179
	v_mul_f32_e32 v169, 0xbfb8aa3b, v169
	v_exp_f32_e32 v169, v169
	v_mad_i64_i32 v[136:137], s[30:31], s28, v168, 0
	v_add_f32_e32 v168, 1.0, v174
	v_rcp_f32_e32 v168, v168
	v_lshl_add_u64 v[136:137], v[136:137], 1, v[132:133]
	v_cvt_pk_bf16_f32 v168, v168, v168
	global_store_short v[136:137], v168, off
	v_add_f32_e32 v168, 1.0, v169
	v_mul_f32_e32 v169, v106, v179
	v_mul_f32_e32 v169, 0xbfb8aa3b, v169
	v_exp_f32_e32 v169, v169
	v_mul_f32_e32 v174, v110, v179
	v_mul_f32_e32 v174, 0xbfb8aa3b, v174
	v_exp_f32_e32 v174, v174
	v_rcp_f32_e32 v168, v168
	v_add_f32_e32 v169, 1.0, v169
	v_cvt_pk_bf16_f32 v168, v168, v168
	v_rcp_f32_e32 v169, v169
	global_store_short v[136:137], v168, off offset:32
	v_cvt_pk_bf16_f32 v168, v169, v169
	v_mul_f32_e32 v169, v103, v134
	v_add_f32_e32 v174, 1.0, v174
	v_mul_f32_e32 v169, 0xbfb8aa3b, v169
	v_rcp_f32_e32 v174, v174
	global_store_short v[136:137], v168, off offset:256
	v_cvt_pk_bf16_f32 v168, v174, v174
	v_exp_f32_e32 v169, v169
	global_store_short v[136:137], v168, off offset:288
	v_mul_f32_e32 v168, v99, v134
	v_mul_f32_e32 v168, 0xbfb8aa3b, v168
	v_exp_f32_e32 v168, v168
	v_mad_i64_i32 v[136:137], s[30:31], s28, v167, 0
	v_add_f32_e32 v167, 1.0, v169
	v_rcp_f32_e32 v167, v167
	v_lshl_add_u64 v[136:137], v[136:137], 1, v[132:133]
	v_cvt_pk_bf16_f32 v167, v167, v167
	global_store_short v[136:137], v167, off
	v_add_f32_e32 v167, 1.0, v168
	v_mul_f32_e32 v168, v107, v134
	v_mul_f32_e32 v168, 0xbfb8aa3b, v168
	v_exp_f32_e32 v168, v168
	v_mul_f32_e32 v134, v111, v134
	v_mul_f32_e32 v134, 0xbfb8aa3b, v134
	v_rcp_f32_e32 v167, v167
	v_exp_f32_e32 v134, v134
	v_cvt_pk_bf16_f32 v167, v167, v167
	v_add_f32_e32 v168, 1.0, v168
	v_rcp_f32_e32 v168, v168
	global_store_short v[136:137], v167, off offset:32
	v_cvt_pk_bf16_f32 v167, v168, v168
	global_store_short v[136:137], v167, off offset:256
	v_mul_f32_e32 v167, v104, v135
	v_add_f32_e32 v134, 1.0, v134
	v_mul_f32_e32 v167, 0xbfb8aa3b, v167
	v_rcp_f32_e32 v134, v134
	v_exp_f32_e32 v167, v167
	v_cvt_pk_bf16_f32 v134, v134, v134
	global_store_short v[136:137], v134, off offset:288
	v_mad_i64_i32 v[136:137], s[30:31], s28, v166, 0
	v_mul_f32_e32 v166, v100, v135
	v_mul_f32_e32 v166, 0xbfb8aa3b, v166
	v_exp_f32_e32 v166, v166
	v_add_f32_e32 v134, 1.0, v167
	v_rcp_f32_e32 v134, v134
	v_lshl_add_u64 v[136:137], v[136:137], 1, v[132:133]
	v_cvt_pk_bf16_f32 v134, v134, v134
	global_store_short v[136:137], v134, off
	v_add_f32_e32 v134, 1.0, v166
	v_mul_f32_e32 v166, v108, v135
	v_mul_f32_e32 v166, 0xbfb8aa3b, v166
	v_mul_f32_e32 v135, v112, v135
	v_exp_f32_e32 v166, v166
	v_mul_f32_e32 v135, 0xbfb8aa3b, v135
	v_exp_f32_e32 v135, v135
	v_rcp_f32_e32 v134, v134
	s_nop 0
	v_cvt_pk_bf16_f32 v167, v134, v134
	v_add_f32_e32 v134, 1.0, v166
	v_rcp_f32_e32 v166, v134
	v_add_f32_e32 v134, 1.0, v135
	v_rcp_f32_e32 v168, v134
	ds_read2_b32 v[134:135], v150 offset0:19 offset1:32
	global_store_short v[136:137], v167, off offset:32
	v_cvt_pk_bf16_f32 v166, v166, v166
	global_store_short v[136:137], v166, off offset:256
	v_cvt_pk_bf16_f32 v166, v168, v168
	s_waitcnt lgkmcnt(0)
; __device__ __forceinline__ float sigmoidf_(float v) { return __builtin_amdgcn_rcpf(1.f + __builtin_amdgcn_exp2f(-LOG2E * v)); }
; __device__ __forceinline__ void phase_inproj() {
;     ...
;       if (sg) { INPROJ_STORE(sigmoidf_(v)) } else { INPROJ_STORE(v) }
	v_mul_f32_e32 v167, v105, v134
	v_mul_f32_e32 v167, 0xbfb8aa3b, v167
	v_exp_f32_e32 v167, v167
	global_store_short v[136:137], v166, off offset:288
	v_mul_f32_e32 v166, v101, v134
	v_mul_f32_e32 v166, 0xbfb8aa3b, v166
	v_exp_f32_e32 v166, v166
	v_mad_i64_i32 v[136:137], s[30:31], s28, v165, 0
	v_add_f32_e32 v165, 1.0, v167
	v_rcp_f32_e32 v165, v165
	v_lshl_add_u64 v[136:137], v[136:137], 1, v[132:133]
	v_cvt_pk_bf16_f32 v165, v165, v165
	global_store_short v[136:137], v165, off
	v_add_f32_e32 v165, 1.0, v166
	v_mul_f32_e32 v166, v109, v134
	v_mul_f32_e32 v166, 0xbfb8aa3b, v166
	v_exp_f32_e32 v166, v166
	v_mul_f32_e32 v134, v113, v134
	v_mul_f32_e32 v134, 0xbfb8aa3b, v134
	v_rcp_f32_e32 v165, v165
	v_exp_f32_e32 v134, v134
	v_cvt_pk_bf16_f32 v165, v165, v165
	v_add_f32_e32 v166, 1.0, v166
	v_rcp_f32_e32 v166, v166
	global_store_short v[136:137], v165, off offset:32
	v_cvt_pk_bf16_f32 v165, v166, v166
	global_store_short v[136:137], v165, off offset:256
	v_mul_f32_e32 v165, v82, v135
	v_add_f32_e32 v134, 1.0, v134
	v_mul_f32_e32 v165, 0xbfb8aa3b, v165
	v_rcp_f32_e32 v134, v134
	v_exp_f32_e32 v165, v165
	v_cvt_pk_bf16_f32 v134, v134, v134
	global_store_short v[136:137], v134, off offset:288
	v_mad_i64_i32 v[136:137], s[30:31], s28, v164, 0
	v_mul_f32_e32 v164, v86, v135
	v_mul_f32_e32 v164, 0xbfb8aa3b, v164
	v_exp_f32_e32 v164, v164
	v_add_f32_e32 v134, 1.0, v165
	v_rcp_f32_e32 v134, v134
	v_lshl_add_u64 v[136:137], v[136:137], 1, v[132:133]
	v_cvt_pk_bf16_f32 v134, v134, v134
	global_store_short v[136:137], v134, off
	v_add_f32_e32 v134, 1.0, v164
	v_mul_f32_e32 v164, v90, v135
	v_mul_f32_e32 v135, v94, v135
	v_mul_f32_e32 v164, 0xbfb8aa3b, v164
	v_mul_f32_e32 v135, 0xbfb8aa3b, v135
	v_exp_f32_e32 v164, v164
	v_exp_f32_e32 v135, v135
	v_rcp_f32_e32 v134, v134
	s_nop 0
	v_cvt_pk_bf16_f32 v134, v134, v134
	v_add_f32_e32 v164, 1.0, v164
	v_add_f32_e32 v135, 1.0, v135
	v_rcp_f32_e32 v164, v164
	v_rcp_f32_e32 v135, v135
	global_store_short v[136:137], v134, off offset:32
	v_cvt_pk_bf16_f32 v134, v164, v164
	global_store_short v[136:137], v134, off offset:256
	v_cvt_pk_bf16_f32 v134, v135, v135
	v_mul_f32_e32 v135, v83, v140
	v_mul_f32_e32 v135, 0xbfb8aa3b, v135
	v_exp_f32_e32 v164, v135
	global_store_short v[136:137], v134, off offset:288
	v_mul_f32_e32 v137, v87, v140
	v_mul_f32_e32 v137, 0xbfb8aa3b, v137
	v_exp_f32_e32 v137, v137
	v_add_f32_e32 v136, 1.0, v164
	v_mad_i64_i32 v[134:135], s[30:31], s28, v163, 0
	v_rcp_f32_e32 v136, v136
	v_lshl_add_u64 v[134:135], v[134:135], 1, v[132:133]
	v_cvt_pk_bf16_f32 v136, v136, v136
	global_store_short v[134:135], v136, off
	v_add_f32_e32 v136, 1.0, v137
	v_mul_f32_e32 v137, v91, v140
	v_mul_f32_e32 v137, 0xbfb8aa3b, v137
	v_exp_f32_e32 v137, v137
	v_rcp_f32_e32 v136, v136
	v_mul_f32_e32 v140, v95, v140
	v_mul_f32_e32 v140, 0xbfb8aa3b, v140
	v_add_f32_e32 v137, 1.0, v137
	v_cvt_pk_bf16_f32 v136, v136, v136
	v_rcp_f32_e32 v137, v137
	v_exp_f32_e32 v140, v140
	global_store_short v[134:135], v136, off offset:32
	v_cvt_pk_bf16_f32 v136, v137, v137
	v_mul_f32_e32 v137, v84, v141
	v_mul_f32_e32 v137, 0xbfb8aa3b, v137
	v_exp_f32_e32 v137, v137
	v_add_f32_e32 v140, 1.0, v140
	v_rcp_f32_e32 v140, v140
	global_store_short v[134:135], v136, off offset:256
	v_cvt_pk_bf16_f32 v136, v140, v140
	global_store_short v[134:135], v136, off offset:288
	v_add_f32_e32 v136, 1.0, v137
	v_mul_f32_e32 v137, v88, v141
	v_mul_f32_e32 v137, 0xbfb8aa3b, v137
	v_exp_f32_e32 v137, v137
	v_mad_i64_i32 v[134:135], s[30:31], s28, v162, 0
	v_rcp_f32_e32 v136, v136
	v_lshl_add_u64 v[134:135], v[134:135], 1, v[132:133]
	v_cvt_pk_bf16_f32 v136, v136, v136
	global_store_short v[134:135], v136, off
	v_add_f32_e32 v136, 1.0, v137
	v_mul_f32_e32 v137, v92, v141
	v_mul_f32_e32 v137, 0xbfb8aa3b, v137
	v_mul_f32_e32 v140, v96, v141
	v_exp_f32_e32 v137, v137
	v_mul_f32_e32 v140, 0xbfb8aa3b, v140
	v_exp_f32_e32 v140, v140
	v_rcp_f32_e32 v136, v136
	s_nop 0
	v_cvt_pk_bf16_f32 v141, v136, v136
	v_add_f32_e32 v136, 1.0, v137
	v_rcp_f32_e32 v162, v136
	v_add_f32_e32 v136, 1.0, v140
	v_rcp_f32_e32 v140, v136
	ds_read2_b32 v[136:137], v150 offset0:35 offset1:48
	global_store_short v[134:135], v141, off offset:32
	v_cvt_pk_bf16_f32 v141, v162, v162
	global_store_short v[134:135], v141, off offset:256
	v_cvt_pk_bf16_f32 v140, v140, v140
	s_waitcnt lgkmcnt(0)
; __device__ __forceinline__ float sigmoidf_(float v) { return __builtin_amdgcn_rcpf(1.f + __builtin_amdgcn_exp2f(-LOG2E * v)); }
; __device__ __forceinline__ void phase_inproj() {
;     ...
;       if (sg) { INPROJ_STORE(sigmoidf_(v)) } else { INPROJ_STORE(v) }
	v_mul_f32_e32 v141, v85, v136
	v_mul_f32_e32 v141, 0xbfb8aa3b, v141
	v_exp_f32_e32 v141, v141
	global_store_short v[134:135], v140, off offset:288
	v_mad_i64_i32 v[134:135], s[30:31], s28, v161, 0
	v_add_f32_e32 v140, 1.0, v141
	v_mul_f32_e32 v141, v89, v136
	v_mul_f32_e32 v141, 0xbfb8aa3b, v141
	v_exp_f32_e32 v141, v141
	v_rcp_f32_e32 v140, v140
	v_lshl_add_u64 v[134:135], v[134:135], 1, v[132:133]
	v_cvt_pk_bf16_f32 v140, v140, v140
	global_store_short v[134:135], v140, off
	v_add_f32_e32 v140, 1.0, v141
	v_mul_f32_e32 v141, v93, v136
	v_mul_f32_e32 v141, 0xbfb8aa3b, v141
	v_exp_f32_e32 v141, v141
	v_rcp_f32_e32 v140, v140
	v_mul_f32_e32 v136, v97, v136
	v_mul_f32_e32 v136, 0xbfb8aa3b, v136
	v_cvt_pk_bf16_f32 v140, v140, v140
	v_add_f32_e32 v141, 1.0, v141
	v_exp_f32_e32 v136, v136
	v_rcp_f32_e32 v141, v141
	global_store_short v[134:135], v140, off offset:32
	v_cvt_pk_bf16_f32 v140, v141, v141
	global_store_short v[134:135], v140, off offset:256
	v_mul_f32_e32 v140, v70, v137
	v_mul_f32_e32 v140, 0xbfb8aa3b, v140
	v_exp_f32_e32 v140, v140
	v_add_f32_e32 v136, 1.0, v136
	v_rcp_f32_e32 v136, v136
	s_nop 0
	v_cvt_pk_bf16_f32 v136, v136, v136
	global_store_short v[134:135], v136, off offset:288
	v_add_f32_e32 v136, 1.0, v140
	v_mul_f32_e32 v140, v66, v137
	v_mul_f32_e32 v140, 0xbfb8aa3b, v140
	v_exp_f32_e32 v140, v140
	v_mad_i64_i32 v[134:135], s[30:31], s28, v160, 0
	v_rcp_f32_e32 v136, v136
	v_lshl_add_u64 v[134:135], v[134:135], 1, v[132:133]
	v_cvt_pk_bf16_f32 v136, v136, v136
	global_store_short v[134:135], v136, off
	v_add_f32_e32 v136, 1.0, v140
	v_mul_f32_e32 v140, v74, v137
	v_mul_f32_e32 v137, v78, v137
	v_mul_f32_e32 v140, 0xbfb8aa3b, v140
	v_mul_f32_e32 v137, 0xbfb8aa3b, v137
	v_exp_f32_e32 v140, v140
	v_exp_f32_e32 v137, v137
	v_rcp_f32_e32 v136, v136
	s_nop 0
	v_cvt_pk_bf16_f32 v136, v136, v136
	v_add_f32_e32 v140, 1.0, v140
	v_add_f32_e32 v137, 1.0, v137
	v_rcp_f32_e32 v140, v140
	v_rcp_f32_e32 v137, v137
	global_store_short v[134:135], v136, off offset:32
	v_cvt_pk_bf16_f32 v136, v140, v140
	global_store_short v[134:135], v136, off offset:256
	v_cvt_pk_bf16_f32 v136, v137, v137
	v_mul_f32_e32 v137, v71, v138
	v_mul_f32_e32 v137, 0xbfb8aa3b, v137
	v_exp_f32_e32 v137, v137
	global_store_short v[134:135], v136, off offset:288
	v_mad_i64_i32 v[134:135], s[30:31], s28, v159, 0
	v_add_f32_e32 v136, 1.0, v137
	v_mul_f32_e32 v137, v67, v138
	v_mul_f32_e32 v137, 0xbfb8aa3b, v137
	v_exp_f32_e32 v137, v137
	v_rcp_f32_e32 v136, v136
	v_lshl_add_u64 v[134:135], v[134:135], 1, v[132:133]
	v_cvt_pk_bf16_f32 v136, v136, v136
	global_store_short v[134:135], v136, off
	v_add_f32_e32 v136, 1.0, v137
	v_mul_f32_e32 v137, v75, v138
	v_mul_f32_e32 v137, 0xbfb8aa3b, v137
	v_exp_f32_e32 v137, v137
	v_rcp_f32_e32 v136, v136
	v_mul_f32_e32 v138, v79, v138
	v_mul_f32_e32 v138, 0xbfb8aa3b, v138
	v_add_f32_e32 v137, 1.0, v137
	v_cvt_pk_bf16_f32 v136, v136, v136
	v_rcp_f32_e32 v137, v137
	v_exp_f32_e32 v138, v138
	global_store_short v[134:135], v136, off offset:32
	v_cvt_pk_bf16_f32 v136, v137, v137
	v_mul_f32_e32 v137, v72, v139
	v_mul_f32_e32 v137, 0xbfb8aa3b, v137
	v_exp_f32_e32 v137, v137
	v_add_f32_e32 v138, 1.0, v138
	v_rcp_f32_e32 v138, v138
	global_store_short v[134:135], v136, off offset:256
	v_cvt_pk_bf16_f32 v136, v138, v138
	global_store_short v[134:135], v136, off offset:288
	v_add_f32_e32 v136, 1.0, v137
	v_mul_f32_e32 v137, v68, v139
	v_mul_f32_e32 v137, 0xbfb8aa3b, v137
	v_exp_f32_e32 v137, v137
	v_mul_f32_e32 v138, v80, v139
	v_mul_f32_e32 v138, 0xbfb8aa3b, v138
	v_mad_i64_i32 v[134:135], s[30:31], s28, v158, 0
	v_rcp_f32_e32 v136, v136
	v_exp_f32_e32 v138, v138
	v_lshl_add_u64 v[134:135], v[134:135], 1, v[132:133]
	v_cvt_pk_bf16_f32 v136, v136, v136
	global_store_short v[134:135], v136, off
	v_add_f32_e32 v136, 1.0, v137
	v_mul_f32_e32 v137, v76, v139
	v_mul_f32_e32 v137, 0xbfb8aa3b, v137
	v_exp_f32_e32 v137, v137
	v_add_f32_e32 v138, 1.0, v138
	v_rcp_f32_e32 v140, v138
	ds_read2_b32 v[138:139], v150 offset0:51 offset1:128
	v_rcp_f32_e32 v136, v136
	v_add_f32_e32 v137, 1.0, v137
	v_cvt_pk_bf16_f32 v136, v136, v136
	v_rcp_f32_e32 v137, v137
	global_store_short v[134:135], v136, off offset:32
	v_cvt_pk_bf16_f32 v136, v137, v137
	s_waitcnt lgkmcnt(0)
	v_mul_f32_e32 v137, v73, v138
	v_mul_f32_e32 v137, 0xbfb8aa3b, v137
	v_exp_f32_e32 v137, v137
	global_store_short v[134:135], v136, off offset:256
	v_cvt_pk_bf16_f32 v136, v140, v140
	global_store_short v[134:135], v136, off offset:288
	v_add_f32_e32 v136, 1.0, v137
	v_mul_f32_e32 v137, v69, v138
	v_mul_f32_e32 v137, 0xbfb8aa3b, v137
	v_exp_f32_e32 v137, v137
	v_mad_i64_i32 v[134:135], s[30:31], s28, v143, 0
	v_rcp_f32_e32 v136, v136
	v_lshl_add_u64 v[134:135], v[134:135], 1, v[132:133]
	v_cvt_pk_bf16_f32 v136, v136, v136
	global_store_short v[134:135], v136, off
	v_add_f32_e32 v136, 1.0, v137
	v_mul_f32_e32 v137, v77, v138
	v_mul_f32_e32 v137, 0xbfb8aa3b, v137
	v_mul_f32_e32 v138, v81, v138
	v_exp_f32_e32 v137, v137
	v_mul_f32_e32 v138, 0xbfb8aa3b, v138
	v_exp_f32_e32 v138, v138
	v_rcp_f32_e32 v136, v136
	s_nop 0
	v_cvt_pk_bf16_f32 v136, v136, v136
	v_add_f32_e32 v137, 1.0, v137
	v_rcp_f32_e32 v137, v137
	v_add_f32_e32 v138, 1.0, v138
	global_store_short v[134:135], v136, off offset:32
	v_cvt_pk_bf16_f32 v136, v137, v137
	v_rcp_f32_e32 v138, v138
	global_store_short v[134:135], v136, off offset:256
	v_cvt_pk_bf16_f32 v136, v138, v138
	global_store_short v[134:135], v136, off offset:288
	v_mul_f32_e32 v134, v50, v139
	v_mul_f32_e32 v134, 0xbfb8aa3b, v134
	v_exp_f32_e32 v136, v134
	v_mul_f32_e32 v134, v54, v139
	v_mul_f32_e32 v134, 0xbfb8aa3b, v134
	v_exp_f32_e32 v137, v134
	v_add_f32_e32 v136, 1.0, v136
	v_mad_i64_i32 v[134:135], s[30:31], s28, v142, 0
	v_rcp_f32_e32 v138, v136
	v_add_f32_e32 v136, 1.0, v137
	v_rcp_f32_e32 v140, v136
	v_lshl_add_u64 v[136:137], v[134:135], 1, v[132:133]
	v_cvt_pk_bf16_f32 v134, v138, v138
	v_mul_f32_e32 v135, v58, v139
	v_mul_f32_e32 v138, v62, v139
	v_mul_f32_e32 v135, 0xbfb8aa3b, v135
	v_mul_f32_e32 v138, 0xbfb8aa3b, v138
	v_exp_f32_e32 v135, v135
	v_exp_f32_e32 v138, v138
	global_store_short v[136:137], v134, off
	v_cvt_pk_bf16_f32 v134, v140, v140
	v_add_f32_e32 v135, 1.0, v135
	global_store_short v[136:137], v134, off offset:32
	v_add_f32_e32 v134, 1.0, v138
	v_rcp_f32_e32 v135, v135
	v_rcp_f32_e32 v138, v134
	v_cvt_pk_bf16_f32 v134, v135, v135
	global_store_short v[136:137], v134, off offset:256
	ds_read2_b32 v[134:135], v150 offset0:129 offset1:130
	v_cvt_pk_bf16_f32 v158, v138, v138
	ds_read2_b32 v[138:139], v150 offset0:145 offset1:146
	ds_read2_b32 v[142:143], v150 offset0:161 offset1:162
	ds_read2_b32 v[140:141], v150 offset0:177 offset1:178
	global_store_short v[136:137], v158, off offset:288
	v_mad_i64_i32 v[136:137], s[30:31], s28, v157, 0
	s_waitcnt lgkmcnt(0)
; __device__ __forceinline__ float sigmoidf_(float v) { return __builtin_amdgcn_rcpf(1.f + __builtin_amdgcn_exp2f(-LOG2E * v)); }
; __device__ __forceinline__ void phase_inproj() {
;     ...
;       if (sg) { INPROJ_STORE(sigmoidf_(v)) } else { INPROJ_STORE(v) }
	v_mul_f32_e32 v159, v51, v134
	v_mul_f32_e32 v159, 0xbfb8aa3b, v159
	v_exp_f32_e32 v159, v159
	v_mul_f32_e32 v158, v55, v134
	v_mul_f32_e32 v158, 0xbfb8aa3b, v158
	v_exp_f32_e32 v158, v158
	v_add_f32_e32 v157, 1.0, v159
	v_rcp_f32_e32 v157, v157
	v_lshl_add_u64 v[136:137], v[136:137], 1, v[132:133]
	v_cvt_pk_bf16_f32 v157, v157, v157
	global_store_short v[136:137], v157, off
	v_add_f32_e32 v157, 1.0, v158
	v_mul_f32_e32 v158, v59, v134
	v_mul_f32_e32 v158, 0xbfb8aa3b, v158
	v_exp_f32_e32 v158, v158
	v_mul_f32_e32 v134, v63, v134
	v_mul_f32_e32 v134, 0xbfb8aa3b, v134
	v_rcp_f32_e32 v157, v157
	v_exp_f32_e32 v134, v134
	v_cvt_pk_bf16_f32 v157, v157, v157
	v_add_f32_e32 v158, 1.0, v158
	v_rcp_f32_e32 v158, v158
	global_store_short v[136:137], v157, off offset:32
	v_cvt_pk_bf16_f32 v157, v158, v158
	global_store_short v[136:137], v157, off offset:256
	v_mul_f32_e32 v157, v52, v135
	v_add_f32_e32 v134, 1.0, v134
	v_mul_f32_e32 v157, 0xbfb8aa3b, v157
	v_rcp_f32_e32 v134, v134
	v_exp_f32_e32 v157, v157
	v_cvt_pk_bf16_f32 v134, v134, v134
	global_store_short v[136:137], v134, off offset:288
	v_mad_i64_i32 v[136:137], s[30:31], s28, v156, 0
	v_mul_f32_e32 v156, v56, v135
	v_mul_f32_e32 v156, 0xbfb8aa3b, v156
	v_exp_f32_e32 v156, v156
	v_add_f32_e32 v134, 1.0, v157
	v_rcp_f32_e32 v134, v134
	v_lshl_add_u64 v[136:137], v[136:137], 1, v[132:133]
	v_cvt_pk_bf16_f32 v134, v134, v134
	global_store_short v[136:137], v134, off
	v_add_f32_e32 v134, 1.0, v156
	v_mul_f32_e32 v156, v60, v135
	v_mul_f32_e32 v156, 0xbfb8aa3b, v156
	v_mul_f32_e32 v135, v64, v135
	v_exp_f32_e32 v156, v156
	v_mul_f32_e32 v135, 0xbfb8aa3b, v135
	v_exp_f32_e32 v135, v135
	v_rcp_f32_e32 v134, v134
	s_nop 0
	v_cvt_pk_bf16_f32 v157, v134, v134
	v_add_f32_e32 v134, 1.0, v156
	v_rcp_f32_e32 v156, v134
	v_add_f32_e32 v134, 1.0, v135
	v_rcp_f32_e32 v158, v134
	ds_read2_b32 v[134:135], v150 offset0:131 offset1:144
	global_store_short v[136:137], v157, off offset:32
	v_cvt_pk_bf16_f32 v156, v156, v156
	global_store_short v[136:137], v156, off offset:256
	v_cvt_pk_bf16_f32 v156, v158, v158
	s_waitcnt lgkmcnt(0)
	v_mul_f32_e32 v157, v53, v134
	v_mul_f32_e32 v157, 0xbfb8aa3b, v157
	v_exp_f32_e32 v157, v157
	global_store_short v[136:137], v156, off offset:288
	v_mul_f32_e32 v156, v57, v134
	v_mul_f32_e32 v156, 0xbfb8aa3b, v156
	v_exp_f32_e32 v156, v156
	v_mad_i64_i32 v[136:137], s[30:31], s28, v155, 0
	v_add_f32_e32 v155, 1.0, v157
	v_rcp_f32_e32 v155, v155
	v_lshl_add_u64 v[136:137], v[136:137], 1, v[132:133]
	v_cvt_pk_bf16_f32 v155, v155, v155
	global_store_short v[136:137], v155, off
	v_add_f32_e32 v155, 1.0, v156
	v_mul_f32_e32 v156, v61, v134
	v_mul_f32_e32 v156, 0xbfb8aa3b, v156
	v_exp_f32_e32 v156, v156
	v_mul_f32_e32 v134, v65, v134
	v_mul_f32_e32 v134, 0xbfb8aa3b, v134
	v_rcp_f32_e32 v155, v155
	v_exp_f32_e32 v134, v134
	v_cvt_pk_bf16_f32 v155, v155, v155
	v_add_f32_e32 v156, 1.0, v156
	v_rcp_f32_e32 v156, v156
	global_store_short v[136:137], v155, off offset:32
	v_cvt_pk_bf16_f32 v155, v156, v156
	global_store_short v[136:137], v155, off offset:256
	v_mul_f32_e32 v155, v38, v135
	v_add_f32_e32 v134, 1.0, v134
	v_mul_f32_e32 v155, 0xbfb8aa3b, v155
	v_rcp_f32_e32 v134, v134
	v_exp_f32_e32 v155, v155
	v_cvt_pk_bf16_f32 v134, v134, v134
	global_store_short v[136:137], v134, off offset:288
	v_mad_i64_i32 v[136:137], s[30:31], s28, v154, 0
	v_mul_f32_e32 v154, v34, v135
	v_mul_f32_e32 v154, 0xbfb8aa3b, v154
	v_exp_f32_e32 v154, v154
	v_add_f32_e32 v134, 1.0, v155
	v_rcp_f32_e32 v134, v134
	v_lshl_add_u64 v[136:137], v[136:137], 1, v[132:133]
	v_cvt_pk_bf16_f32 v134, v134, v134
	global_store_short v[136:137], v134, off
	v_add_f32_e32 v134, 1.0, v154
	v_mul_f32_e32 v154, v42, v135
	v_mul_f32_e32 v135, v46, v135
	v_mul_f32_e32 v154, 0xbfb8aa3b, v154
	v_mul_f32_e32 v135, 0xbfb8aa3b, v135
	v_exp_f32_e32 v154, v154
	v_exp_f32_e32 v135, v135
	v_rcp_f32_e32 v134, v134
	s_nop 0
	v_cvt_pk_bf16_f32 v134, v134, v134
	v_add_f32_e32 v154, 1.0, v154
	v_add_f32_e32 v135, 1.0, v135
	v_rcp_f32_e32 v154, v154
	v_rcp_f32_e32 v135, v135
	global_store_short v[136:137], v134, off offset:32
	v_cvt_pk_bf16_f32 v134, v154, v154
	global_store_short v[136:137], v134, off offset:256
	v_cvt_pk_bf16_f32 v134, v135, v135
	v_mul_f32_e32 v135, v39, v138
	v_mul_f32_e32 v135, 0xbfb8aa3b, v135
	v_exp_f32_e32 v154, v135
	global_store_short v[136:137], v134, off offset:288
	v_mul_f32_e32 v137, v35, v138
	v_mul_f32_e32 v137, 0xbfb8aa3b, v137
	v_exp_f32_e32 v137, v137
	v_add_f32_e32 v136, 1.0, v154
	v_mad_i64_i32 v[134:135], s[30:31], s28, v153, 0
	v_rcp_f32_e32 v136, v136
	v_lshl_add_u64 v[134:135], v[134:135], 1, v[132:133]
	v_cvt_pk_bf16_f32 v136, v136, v136
	global_store_short v[134:135], v136, off
	v_add_f32_e32 v136, 1.0, v137
	v_mul_f32_e32 v137, v43, v138
	v_mul_f32_e32 v137, 0xbfb8aa3b, v137
	v_exp_f32_e32 v137, v137
	v_rcp_f32_e32 v136, v136
	v_mul_f32_e32 v138, v47, v138
	v_mul_f32_e32 v138, 0xbfb8aa3b, v138
	v_add_f32_e32 v137, 1.0, v137
	v_cvt_pk_bf16_f32 v136, v136, v136
	v_rcp_f32_e32 v137, v137
	v_exp_f32_e32 v138, v138
	global_store_short v[134:135], v136, off offset:32
	v_cvt_pk_bf16_f32 v136, v137, v137
	v_mul_f32_e32 v137, v40, v139
	v_mul_f32_e32 v137, 0xbfb8aa3b, v137
	v_exp_f32_e32 v137, v137
	v_add_f32_e32 v138, 1.0, v138
	v_rcp_f32_e32 v138, v138
	global_store_short v[134:135], v136, off offset:256
	v_cvt_pk_bf16_f32 v136, v138, v138
	global_store_short v[134:135], v136, off offset:288
	v_add_f32_e32 v136, 1.0, v137
	v_mul_f32_e32 v137, v36, v139
	v_mul_f32_e32 v137, 0xbfb8aa3b, v137
	v_exp_f32_e32 v137, v137
	v_mad_i64_i32 v[134:135], s[30:31], s28, v152, 0
	v_rcp_f32_e32 v136, v136
	v_lshl_add_u64 v[134:135], v[134:135], 1, v[132:133]
	v_cvt_pk_bf16_f32 v136, v136, v136
	global_store_short v[134:135], v136, off
	v_add_f32_e32 v136, 1.0, v137
	v_mul_f32_e32 v137, v44, v139
	v_mul_f32_e32 v137, 0xbfb8aa3b, v137
	v_mul_f32_e32 v138, v48, v139
	v_exp_f32_e32 v137, v137
	v_mul_f32_e32 v138, 0xbfb8aa3b, v138
	v_exp_f32_e32 v138, v138
	v_rcp_f32_e32 v136, v136
	s_nop 0
	v_cvt_pk_bf16_f32 v139, v136, v136
	v_add_f32_e32 v136, 1.0, v137
	v_rcp_f32_e32 v152, v136
	v_add_f32_e32 v136, 1.0, v138
	v_rcp_f32_e32 v138, v136
	ds_read2_b32 v[136:137], v150 offset0:147 offset1:160
	global_store_short v[134:135], v139, off offset:32
	v_cvt_pk_bf16_f32 v139, v152, v152
	global_store_short v[134:135], v139, off offset:256
	v_cvt_pk_bf16_f32 v138, v138, v138
	s_waitcnt lgkmcnt(0)
; __device__ __forceinline__ float sigmoidf_(float v) { return __builtin_amdgcn_rcpf(1.f + __builtin_amdgcn_exp2f(-LOG2E * v)); }
; __device__ __forceinline__ void phase_inproj() {
;     ...
;       if (sg) { INPROJ_STORE(sigmoidf_(v)) } else { INPROJ_STORE(v) }
	v_mul_f32_e32 v139, v41, v136
	v_mul_f32_e32 v139, 0xbfb8aa3b, v139
	v_exp_f32_e32 v139, v139
	global_store_short v[134:135], v138, off offset:288
	v_mad_i64_i32 v[134:135], s[30:31], s28, v151, 0
	v_add_f32_e32 v138, 1.0, v139
	v_mul_f32_e32 v139, v37, v136
	v_mul_f32_e32 v139, 0xbfb8aa3b, v139
	v_exp_f32_e32 v139, v139
	v_rcp_f32_e32 v138, v138
	v_lshl_add_u64 v[134:135], v[134:135], 1, v[132:133]
	v_cvt_pk_bf16_f32 v138, v138, v138
	global_store_short v[134:135], v138, off
	v_add_f32_e32 v138, 1.0, v139
	v_mul_f32_e32 v139, v45, v136
	v_mul_f32_e32 v136, v49, v136
	v_mul_f32_e32 v136, 0xbfb8aa3b, v136
	v_mul_f32_e32 v139, 0xbfb8aa3b, v139
	v_exp_f32_e32 v136, v136
	v_exp_f32_e32 v139, v139
	v_rcp_f32_e32 v138, v138
	s_nop 0
	v_cvt_pk_bf16_f32 v138, v138, v138
	v_add_f32_e32 v136, 1.0, v136
	v_add_f32_e32 v139, 1.0, v139
	v_rcp_f32_e32 v136, v136
	v_rcp_f32_e32 v139, v139
	global_store_short v[134:135], v138, off offset:32
	v_cvt_pk_bf16_f32 v138, v139, v139
	global_store_short v[134:135], v138, off offset:256
	v_cvt_pk_bf16_f32 v136, v136, v136
	global_store_short v[134:135], v136, off offset:288
	v_mul_f32_e32 v134, v18, v137
	v_mul_f32_e32 v134, 0xbfb8aa3b, v134
	v_exp_f32_e32 v136, v134
	v_mul_f32_e32 v138, v22, v137
	v_mul_f32_e32 v138, 0xbfb8aa3b, v138
	v_exp_f32_e32 v138, v138
	v_add_u32_e32 v134, 0xa0, v130
	v_add_f32_e32 v136, 1.0, v136
	v_mad_i64_i32 v[134:135], s[30:31], s28, v134, 0
	v_rcp_f32_e32 v136, v136
	v_lshl_add_u64 v[134:135], v[134:135], 1, v[132:133]
	v_cvt_pk_bf16_f32 v136, v136, v136
	global_store_short v[134:135], v136, off
	v_add_f32_e32 v136, 1.0, v138
	v_mul_f32_e32 v138, v26, v137
	v_mul_f32_e32 v138, 0xbfb8aa3b, v138
	v_mul_f32_e32 v137, v30, v137
	v_exp_f32_e32 v138, v138
	v_mul_f32_e32 v137, 0xbfb8aa3b, v137
	v_exp_f32_e32 v137, v137
	v_rcp_f32_e32 v136, v136
	s_nop 0
	v_cvt_pk_bf16_f32 v136, v136, v136
	v_add_f32_e32 v138, 1.0, v138
	v_rcp_f32_e32 v138, v138
	v_add_f32_e32 v137, 1.0, v137
	global_store_short v[134:135], v136, off offset:32
	v_cvt_pk_bf16_f32 v136, v138, v138
	v_rcp_f32_e32 v137, v137
	global_store_short v[134:135], v136, off offset:256
	v_cvt_pk_bf16_f32 v136, v137, v137
	global_store_short v[134:135], v136, off offset:288
	v_mul_f32_e32 v134, v19, v142
	v_mul_f32_e32 v134, 0xbfb8aa3b, v134
	v_exp_f32_e32 v136, v134
	v_mul_f32_e32 v137, v23, v142
	v_mul_f32_e32 v137, 0xbfb8aa3b, v137
	v_exp_f32_e32 v137, v137
	v_add_u32_e32 v134, 0xa1, v130
	v_add_f32_e32 v136, 1.0, v136
	v_mad_i64_i32 v[134:135], s[30:31], s28, v134, 0
	v_rcp_f32_e32 v136, v136
	v_lshl_add_u64 v[134:135], v[134:135], 1, v[132:133]
	v_cvt_pk_bf16_f32 v136, v136, v136
	global_store_short v[134:135], v136, off
	v_add_f32_e32 v136, 1.0, v137
	v_mul_f32_e32 v137, v27, v142
	v_mul_f32_e32 v137, 0xbfb8aa3b, v137
	v_mul_f32_e32 v138, v31, v142
	v_exp_f32_e32 v137, v137
	v_mul_f32_e32 v138, 0xbfb8aa3b, v138
	v_exp_f32_e32 v138, v138
	v_rcp_f32_e32 v136, v136
	s_nop 0
	v_cvt_pk_bf16_f32 v136, v136, v136
	v_add_f32_e32 v137, 1.0, v137
	v_rcp_f32_e32 v137, v137
	v_add_f32_e32 v138, 1.0, v138
	global_store_short v[134:135], v136, off offset:32
	v_cvt_pk_bf16_f32 v136, v137, v137
	v_rcp_f32_e32 v138, v138
	global_store_short v[134:135], v136, off offset:256
	v_cvt_pk_bf16_f32 v136, v138, v138
	global_store_short v[134:135], v136, off offset:288
	v_mul_f32_e32 v135, v20, v143
	v_mul_f32_e32 v135, 0xbfb8aa3b, v135
	v_exp_f32_e32 v136, v135
	v_mul_f32_e32 v135, v24, v143
	v_mul_f32_e32 v135, 0xbfb8aa3b, v135
	v_exp_f32_e32 v137, v135
	v_add_u32_e32 v134, 0xa2, v130
	v_add_f32_e32 v136, 1.0, v136
	v_mad_i64_i32 v[134:135], s[30:31], s28, v134, 0
	v_rcp_f32_e32 v136, v136
	v_add_f32_e32 v137, 1.0, v137
	v_rcp_f32_e32 v137, v137
	v_lshl_add_u64 v[134:135], v[134:135], 1, v[132:133]
	v_cvt_pk_bf16_f32 v136, v136, v136
	global_store_short v[134:135], v136, off
	v_cvt_pk_bf16_f32 v136, v137, v137
	v_mul_f32_e32 v137, v28, v143
	v_mul_f32_e32 v137, 0xbfb8aa3b, v137
	v_mul_f32_e32 v138, v32, v143
	v_exp_f32_e32 v137, v137
	v_mul_f32_e32 v138, 0xbfb8aa3b, v138
	v_exp_f32_e32 v138, v138
	global_store_short v[134:135], v136, off offset:32
	v_add_f32_e32 v136, 1.0, v137
	v_rcp_f32_e32 v139, v136
	v_add_f32_e32 v136, 1.0, v138
	v_rcp_f32_e32 v138, v136
	ds_read2_b32 v[136:137], v150 offset0:163 offset1:176
	v_cvt_pk_bf16_f32 v139, v139, v139
	global_store_short v[134:135], v139, off offset:256
	v_cvt_pk_bf16_f32 v138, v138, v138
	global_store_short v[134:135], v138, off offset:288
	s_waitcnt lgkmcnt(0)
; __device__ __forceinline__ float sigmoidf_(float v) { return __builtin_amdgcn_rcpf(1.f + __builtin_amdgcn_exp2f(-LOG2E * v)); }
; __device__ __forceinline__ void phase_inproj() {
;     ...
;       if (sg) { INPROJ_STORE(sigmoidf_(v)) } else { INPROJ_STORE(v) }
	v_mul_f32_e32 v134, v21, v136
	v_mul_f32_e32 v134, 0xbfb8aa3b, v134
	v_exp_f32_e32 v138, v134
	v_mul_f32_e32 v139, v25, v136
	v_mul_f32_e32 v139, 0xbfb8aa3b, v139
	v_exp_f32_e32 v139, v139
	v_add_u32_e32 v134, 0xa3, v130
	v_add_f32_e32 v138, 1.0, v138
	v_mad_i64_i32 v[134:135], s[30:31], s28, v134, 0
	v_rcp_f32_e32 v138, v138
	v_lshl_add_u64 v[134:135], v[134:135], 1, v[132:133]
	v_cvt_pk_bf16_f32 v138, v138, v138
	global_store_short v[134:135], v138, off
	v_add_f32_e32 v138, 1.0, v139
	v_mul_f32_e32 v139, v29, v136
	v_mul_f32_e32 v136, v33, v136
	v_mul_f32_e32 v136, 0xbfb8aa3b, v136
	v_mul_f32_e32 v139, 0xbfb8aa3b, v139
	v_exp_f32_e32 v136, v136
	v_exp_f32_e32 v139, v139
	v_rcp_f32_e32 v138, v138
	s_nop 0
	v_cvt_pk_bf16_f32 v138, v138, v138
	v_add_f32_e32 v136, 1.0, v136
	v_add_f32_e32 v139, 1.0, v139
	v_rcp_f32_e32 v136, v136
	v_rcp_f32_e32 v139, v139
	global_store_short v[134:135], v138, off offset:32
	v_cvt_pk_bf16_f32 v138, v139, v139
	global_store_short v[134:135], v138, off offset:256
	v_cvt_pk_bf16_f32 v136, v136, v136
	global_store_short v[134:135], v136, off offset:288
	v_mul_f32_e32 v134, v6, v137
	v_mul_f32_e32 v134, 0xbfb8aa3b, v134
	v_exp_f32_e32 v136, v134
	v_mul_f32_e32 v138, v2, v137
	v_mul_f32_e32 v138, 0xbfb8aa3b, v138
	v_exp_f32_e32 v138, v138
	v_add_u32_e32 v134, 0xb0, v130
	v_add_f32_e32 v136, 1.0, v136
	v_mad_i64_i32 v[134:135], s[30:31], s28, v134, 0
	v_rcp_f32_e32 v136, v136
	v_lshl_add_u64 v[134:135], v[134:135], 1, v[132:133]
	v_cvt_pk_bf16_f32 v136, v136, v136
	global_store_short v[134:135], v136, off
	v_add_f32_e32 v136, 1.0, v138
	v_mul_f32_e32 v138, v10, v137
	v_mul_f32_e32 v138, 0xbfb8aa3b, v138
	v_mul_f32_e32 v137, v14, v137
	v_exp_f32_e32 v138, v138
	v_mul_f32_e32 v137, 0xbfb8aa3b, v137
	v_exp_f32_e32 v137, v137
	v_rcp_f32_e32 v136, v136
	s_nop 0
	v_cvt_pk_bf16_f32 v136, v136, v136
	v_add_f32_e32 v138, 1.0, v138
	v_rcp_f32_e32 v138, v138
	v_add_f32_e32 v137, 1.0, v137
	global_store_short v[134:135], v136, off offset:32
	v_cvt_pk_bf16_f32 v136, v138, v138
	v_rcp_f32_e32 v137, v137
	global_store_short v[134:135], v136, off offset:256
	v_cvt_pk_bf16_f32 v136, v137, v137
	global_store_short v[134:135], v136, off offset:288
	v_mul_f32_e32 v134, v7, v140
	v_mul_f32_e32 v134, 0xbfb8aa3b, v134
	v_exp_f32_e32 v136, v134
	v_mul_f32_e32 v137, v3, v140
	v_mul_f32_e32 v137, 0xbfb8aa3b, v137
	v_exp_f32_e32 v137, v137
	v_add_u32_e32 v134, 0xb1, v130
	v_add_f32_e32 v136, 1.0, v136
	v_mad_i64_i32 v[134:135], s[30:31], s28, v134, 0
	v_rcp_f32_e32 v136, v136
	v_lshl_add_u64 v[134:135], v[134:135], 1, v[132:133]
	v_cvt_pk_bf16_f32 v136, v136, v136
	global_store_short v[134:135], v136, off
	v_add_f32_e32 v136, 1.0, v137
	v_mul_f32_e32 v137, v11, v140
	v_mul_f32_e32 v137, 0xbfb8aa3b, v137
	v_mul_f32_e32 v138, v15, v140
	v_exp_f32_e32 v137, v137
	v_mul_f32_e32 v138, 0xbfb8aa3b, v138
	v_exp_f32_e32 v138, v138
	v_rcp_f32_e32 v136, v136
	s_nop 0
	v_cvt_pk_bf16_f32 v136, v136, v136
	v_add_f32_e32 v137, 1.0, v137
	v_rcp_f32_e32 v137, v137
	v_add_f32_e32 v138, 1.0, v138
	global_store_short v[134:135], v136, off offset:32
	v_cvt_pk_bf16_f32 v136, v137, v137
	v_rcp_f32_e32 v138, v138
	global_store_short v[134:135], v136, off offset:256
	v_cvt_pk_bf16_f32 v136, v138, v138
	global_store_short v[134:135], v136, off offset:288
	v_mul_f32_e32 v135, v8, v141
	v_mul_f32_e32 v135, 0xbfb8aa3b, v135
	v_exp_f32_e32 v136, v135
	v_mul_f32_e32 v135, v4, v141
	v_mul_f32_e32 v135, 0xbfb8aa3b, v135
	v_exp_f32_e32 v137, v135
	v_add_u32_e32 v134, 0xb2, v130
	v_add_f32_e32 v136, 1.0, v136
	v_mad_i64_i32 v[134:135], s[30:31], s28, v134, 0
	v_rcp_f32_e32 v136, v136
	v_add_f32_e32 v137, 1.0, v137
	v_rcp_f32_e32 v137, v137
	v_lshl_add_u64 v[134:135], v[134:135], 1, v[132:133]
	v_cvt_pk_bf16_f32 v136, v136, v136
	global_store_short v[134:135], v136, off
	v_cvt_pk_bf16_f32 v136, v137, v137
	v_mul_f32_e32 v137, v12, v141
	v_mul_f32_e32 v138, v16, v141
	v_mul_f32_e32 v137, 0xbfb8aa3b, v137
	v_mul_f32_e32 v138, 0xbfb8aa3b, v138
	v_exp_f32_e32 v137, v137
	v_exp_f32_e32 v138, v138
	global_store_short v[134:135], v136, off offset:32
	v_add_u32_e32 v130, 0xb3, v130
	v_add_f32_e32 v136, 1.0, v137
	v_add_f32_e32 v137, 1.0, v138
	ds_read_b32 v138, v150 offset:716
	v_rcp_f32_e32 v136, v136
	s_nop 0
	v_cvt_pk_bf16_f32 v136, v136, v136
	v_rcp_f32_e32 v137, v137
	global_store_short v[134:135], v136, off offset:256
	v_cvt_pk_bf16_f32 v136, v137, v137
	global_store_short v[134:135], v136, off offset:288
	s_waitcnt lgkmcnt(0)
	v_mul_f32_e32 v134, v9, v138
	v_mul_f32_e32 v134, 0xbfb8aa3b, v134
	v_exp_f32_e32 v136, v134
	v_mad_i64_i32 v[134:135], s[28:29], s28, v130, 0
	v_lshl_add_u64 v[132:133], v[134:135], 1, v[132:133]
	v_add_f32_e32 v130, 1.0, v136
	v_mul_f32_e32 v136, v5, v138
	v_mul_f32_e32 v136, 0xbfb8aa3b, v136
	v_exp_f32_e32 v136, v136
	v_mul_f32_e32 v134, v13, v138
	v_mul_f32_e32 v134, 0xbfb8aa3b, v134
	v_mul_f32_e32 v135, v17, v138
	v_rcp_f32_e32 v130, v130
	v_exp_f32_e32 v134, v134
	v_mul_f32_e32 v135, 0xbfb8aa3b, v135
	v_cvt_pk_bf16_f32 v130, v130, v130
	v_exp_f32_e32 v135, v135
	global_store_short v[132:133], v130, off
	v_add_f32_e32 v130, 1.0, v136
	v_rcp_f32_e32 v130, v130
	s_nop 0
	v_cvt_pk_bf16_f32 v130, v130, v130
	v_add_f32_e32 v134, 1.0, v134
	v_rcp_f32_e32 v134, v134
	v_add_f32_e32 v135, 1.0, v135
	global_store_short v[132:133], v130, off offset:32
	v_cvt_pk_bf16_f32 v130, v134, v134
	v_rcp_f32_e32 v135, v135
	global_store_short v[132:133], v130, off offset:256
	v_cvt_pk_bf16_f32 v130, v135, v135
	global_store_short v[132:133], v130, off offset:288

; #define GAS __attribute__((address_space(1)))
; __device__ __forceinline__ unsigned f2bf(float f) { return pk2(f, f) & 0xffffu; }
; __device__ __forceinline__ void phase_inproj() {
;     ...
;     if (pn < 4) {
;       const GAS float* gsrc = (const GAS float*)((pn < 2) ? P.q_norm : P.k_norm);
;       GAS unsigned short* dst = (GAS unsigned short*)(ws + OFF_RA + ((pn < 2) ? RA_QF : RA_KF));
;       const int head = (pn & 1) * 4 + wc;
;       float gn[2][2];
; #pragma unroll
;       for (int bj = 0; bj < 2; ++bj)
; #pragma unroll
;         for (int n = 0; n < 2; ++n) gn[bj][n] = gsrc[bj * 32 + n * 16 + fr];
; #pragma unroll
;       for (int ai = 0; ai < 2; ++ai)
; #pragma unroll
;         for (int m = 0; m < 4; ++m)
; #pragma unroll
;           for (int j = 0; j < 4; ++j) {
;             const int rowl = ai * 128 + wr * 64 + m * 16 + fq * 4 + j;
;             const float r = rr[rowl];
;             float v[2][2]; float ss = 0.f;
; #pragma unroll
;             for (int bj = 0; bj < 2; ++bj)
; #pragma unroll
;               for (int n = 0; n < 2; ++n) { v[bj][n] = acc[ai][bj][m][n][j] * r; ss += v[bj][n] * v[bj][n]; }
;             ss = sum16(ss);
;             const float ri = rsqrtf(ss * (1.f / 64.f) + EPS);
; #pragma unroll
;             for (int bj = 0; bj < 2; ++bj)
; #pragma unroll
;               for (int n = 0; n < 2; ++n)
;                 dst[(size_t)(brow + rowl) * AW + head * 64 + bj * 32 + n * 16 + fr] = (unsigned short)f2bf(v[bj][n] * ri * gn[bj][n]);
;           }
.LBB0_373:
	s_cmp_lt_i32 s57, 2
	s_cselect_b32 s28, s54, 0x50
	s_cselect_b32 s20, 0, 0x2000000
	s_add_u32 s28, s6, s28
	s_addc_u32 s29, s7, 0
	s_load_dwordx2 s[28:29], s[28:29], 0x0
	v_lshlrev_b32_e32 v130, 2, v146
	v_mov_b32_e32 v134, v114
	v_mov_b32_e32 v135, v118
	s_waitcnt lgkmcnt(0)
	global_load_dword v151, v130, s[28:29]
	global_load_dword v150, v130, s[28:29] offset:64
	global_load_dword v143, v130, s[28:29] offset:128
	global_load_dword v142, v130, s[28:29] offset:192
	v_lshlrev_b32_e32 v130, 6, v149
	v_lshl_or_b32 v114, v148, 2, v130
	v_lshl_add_u32 v148, v114, 2, s5
	v_add_u32_e32 v114, s4, v114
	s_lshl_b32 s4, s57, 2
	ds_read2_b32 v[152:153], v148 offset1:1
	ds_read2_b32 v[132:133], v148 offset0:2 offset1:3
	ds_read2_b32 v[138:139], v148 offset0:16 offset1:17
	ds_read2_b32 v[140:141], v148 offset0:18 offset1:19
	v_mov_b32_e32 v136, v126
	v_add_u32_e32 v126, 1, v114
	s_add_u32 s28, s49, s20
	v_and_or_b32 v130, s4, 4, v147
	v_mov_b32_e32 v137, v122
	v_mov_b32_e32 v122, v127
	v_ashrrev_i32_e32 v127, 31, v126
	s_addc_u32 s29, s50, 0
	v_lshlrev_b32_e32 v130, 7, v130
	s_waitcnt lgkmcnt(0)
	v_pk_mul_f32 v[134:135], v[134:135], v[152:153] op_sel_hi:[1,0]
	v_mov_b32_e32 v118, v115
	v_ashrrev_i32_e32 v115, 31, v114
	v_lshlrev_b64 v[156:157], 10, v[126:127]
	v_lshl_add_u64 v[126:127], s[28:29], 0, v[130:131]
	v_lshlrev_b32_e32 v130, 1, v146
	v_pk_mul_f32 v[136:137], v[136:137], v[152:153] op_sel_hi:[1,0]
	v_pk_mul_f32 v[146:147], v[134:135], v[134:135]
	v_lshlrev_b64 v[154:155], 10, v[114:115]
	v_lshl_add_u64 v[126:127], v[126:127], 0, v[130:131]
	v_mov_b32_e32 v130, v153
	v_pk_mul_f32 v[152:153], v[136:137], v[136:137]
	v_add_f32_e32 v115, v146, v147
	v_pk_mul_f32 v[118:119], v[118:119], v[130:131] op_sel_hi:[1,0]
	v_add_f32_e32 v115, v153, v115
	v_pk_mul_f32 v[122:123], v[122:123], v[130:131] op_sel_hi:[1,0]
	v_pk_mul_f32 v[146:147], v[118:119], v[118:119]
	v_add_f32_e32 v115, v152, v115
	v_pk_mul_f32 v[158:159], v[122:123], v[122:123]
	v_add_f32_e32 v130, v146, v147
	v_add_f32_dpp v115, v115, v115 quad_perm:[1,0,3,2] row_mask:0xf bank_mask:0xf bound_ctrl:1
	v_add_f32_e32 v130, v159, v130
	v_add_f32_e32 v130, v158, v130
	v_add_f32_dpp v115, v115, v115 quad_perm:[2,3,0,1] row_mask:0xf bank_mask:0xf bound_ctrl:1
	s_nop 0
	v_add_f32_dpp v130, v130, v130 quad_perm:[1,0,3,2] row_mask:0xf bank_mask:0xf bound_ctrl:1
	v_add_f32_dpp v115, v115, v115 row_half_mirror row_mask:0xf bank_mask:0xf bound_ctrl:1
	s_nop 0
	v_add_f32_dpp v130, v130, v130 quad_perm:[2,3,0,1] row_mask:0xf bank_mask:0xf bound_ctrl:1
	v_add_f32_dpp v115, v115, v115 row_mirror row_mask:0xf bank_mask:0xf bound_ctrl:1
	v_fmamk_f32 v115, v115, 0x3c800000, v145
	v_add_f32_dpp v130, v130, v130 row_half_mirror row_mask:0xf bank_mask:0xf bound_ctrl:1
	v_mul_f32_e32 v146, 0x4b800000, v115
	v_cmp_gt_f32_e32 vcc, s52, v115
	v_add_f32_dpp v130, v130, v130 row_mirror row_mask:0xf bank_mask:0xf bound_ctrl:1
	v_fmamk_f32 v130, v130, 0x3c800000, v145
	v_cndmask_b32_e32 v115, v115, v146, vcc
	v_rsq_f32_e32 v115, v115
	v_mul_f32_e32 v146, 0x4b800000, v130
	v_cmp_gt_f32_e64 s[4:5], s52, v130
	v_mul_f32_e32 v149, 0x45800000, v115
	s_nop 0
	v_cndmask_b32_e64 v130, v130, v146, s[4:5]
	v_rsq_f32_e32 v130, v130
	v_cndmask_b32_e32 v115, v115, v149, vcc
	v_mul_f32_e32 v134, v134, v115
	v_mul_f32_e32 v135, v135, v115
	v_mul_f32_e32 v137, v137, v115
	v_mul_f32_e32 v115, v136, v115
	v_mul_f32_e32 v149, 0x45800000, v130
	v_lshl_add_u64 v[146:147], v[126:127], 0, v[154:155]
	v_cndmask_b32_e64 v130, v130, v149, s[4:5]
	s_waitcnt vmcnt(0)
	v_mul_f32_e32 v134, v151, v134
	v_mul_f32_e32 v135, v150, v135
	v_mul_f32_e32 v136, v143, v137
	v_mul_f32_e32 v115, v142, v115
	v_cvt_pk_bf16_f32 v134, v134, v134
	v_cvt_pk_bf16_f32 v115, v115, v115
	v_cvt_pk_bf16_f32 v135, v135, v135
	v_cvt_pk_bf16_f32 v136, v136, v136
	global_store_short v[146:147], v134, off
	global_store_short v[146:147], v135, off offset:32
	global_store_short v[146:147], v136, off offset:64
	global_store_short v[146:147], v115, off offset:96
	v_mul_f32_e32 v115, v118, v130
	v_mul_f32_e32 v115, v151, v115
	v_lshl_add_u64 v[134:135], v[126:127], 0, v[156:157]
	v_cvt_pk_bf16_f32 v115, v115, v115
	global_store_short v[134:135], v115, off
	v_mul_f32_e32 v115, v119, v130
	v_mul_f32_e32 v115, v150, v115
	v_cvt_pk_bf16_f32 v115, v115, v115
	global_store_short v[134:135], v115, off offset:32
	v_mul_f32_e32 v115, v123, v130
	v_mul_f32_e32 v115, v143, v115
	v_mov_b32_e32 v118, v116
	v_mov_b32_e32 v119, v120
	v_cvt_pk_bf16_f32 v115, v115, v115
	v_pk_mul_f32 v[118:119], v[118:119], v[132:133] op_sel_hi:[1,0]
	v_mov_b32_e32 v136, v128
	v_mov_b32_e32 v137, v124
	global_store_short v[134:135], v115, off offset:64
	v_mul_f32_e32 v115, v122, v130
	v_pk_mul_f32 v[122:123], v[118:119], v[118:119]
	v_pk_mul_f32 v[136:137], v[136:137], v[132:133] op_sel_hi:[1,0]
	v_add_f32_e32 v116, v122, v123
	v_pk_mul_f32 v[146:147], v[136:137], v[136:137]
	v_mul_f32_e32 v115, v142, v115
	v_add_f32_e32 v116, v147, v116
	v_add_f32_e32 v116, v146, v116
	v_cvt_pk_bf16_f32 v115, v115, v115
	global_store_short v[134:135], v115, off offset:96
	v_add_u32_e32 v122, 2, v114
	v_add_f32_dpp v116, v116, v116 quad_perm:[1,0,3,2] row_mask:0xf bank_mask:0xf bound_ctrl:1
	v_ashrrev_i32_e32 v123, 31, v122
	v_lshlrev_b64 v[122:123], 10, v[122:123]
	v_add_f32_dpp v116, v116, v116 quad_perm:[2,3,0,1] row_mask:0xf bank_mask:0xf bound_ctrl:1
	v_lshl_add_u64 v[122:123], v[126:127], 0, v[122:123]
	v_mov_b32_e32 v124, v129
	v_add_f32_dpp v116, v116, v116 row_half_mirror row_mask:0xf bank_mask:0xf bound_ctrl:1
	s_nop 1
	v_add_f32_dpp v116, v116, v116 row_mirror row_mask:0xf bank_mask:0xf bound_ctrl:1
; __device__ __forceinline__ unsigned f2bf(float f) { return pk2(f, f) & 0xffffu; }
; __device__ __forceinline__ void phase_inproj() {
;     ...
;       for (int ai = 0; ai < 2; ++ai)
; #pragma unroll
;         for (int m = 0; m < 4; ++m)
; #pragma unroll
;           for (int j = 0; j < 4; ++j) {
;             const int rowl = ai * 128 + wr * 64 + m * 16 + fq * 4 + j;
;             const float r = rr[rowl];
;             float v[2][2]; float ss = 0.f;
; #pragma unroll
;             for (int bj = 0; bj < 2; ++bj)
; #pragma unroll
;               for (int n = 0; n < 2; ++n) { v[bj][n] = acc[ai][bj][m][n][j] * r; ss += v[bj][n] * v[bj][n]; }
;             ss = sum16(ss);
;             const float ri = rsqrtf(ss * (1.f / 64.f) + EPS);
; #pragma unroll
;             for (int bj = 0; bj < 2; ++bj)
; #pragma unroll
;               for (int n = 0; n < 2; ++n)
;                 dst[(size_t)(brow + rowl) * AW + head * 64 + bj * 32 + n * 16 + fr] = (unsigned short)f2bf(v[bj][n] * ri * gn[bj][n]);
	v_fmamk_f32 v116, v116, 0x3c800000, v145
	v_mul_f32_e32 v120, 0x4b800000, v116
	v_cmp_gt_f32_e32 vcc, s52, v116
	s_nop 1
	v_cndmask_b32_e32 v116, v116, v120, vcc
	v_rsq_f32_e32 v116, v116
	v_mov_b32_e32 v120, v117
	v_mul_f32_e32 v115, 0x45800000, v116
	v_cndmask_b32_e32 v115, v116, v115, vcc
	v_mul_f32_e32 v116, v118, v115
	v_mul_f32_e32 v116, v151, v116
	v_cvt_pk_bf16_f32 v116, v116, v116
	global_store_short v[122:123], v116, off
	v_mul_f32_e32 v116, v119, v115
	v_mul_f32_e32 v116, v150, v116
	v_cvt_pk_bf16_f32 v116, v116, v116
	global_store_short v[122:123], v116, off offset:32
	v_mul_f32_e32 v116, v137, v115
	v_mul_f32_e32 v116, v143, v116
	v_cvt_pk_bf16_f32 v116, v116, v116
	global_store_short v[122:123], v116, off offset:64
	v_mov_b32_e32 v116, v133
	v_pk_mul_f32 v[118:119], v[120:121], v[116:117] op_sel_hi:[1,0]
	v_pk_mul_f32 v[116:117], v[124:125], v[116:117] op_sel_hi:[1,0]
	v_pk_mul_f32 v[120:121], v[118:119], v[118:119]
	v_pk_mul_f32 v[124:125], v[116:117], v[116:117]
	v_add_f32_e32 v120, v120, v121
	v_add_f32_e32 v120, v125, v120
	v_add_f32_e32 v120, v124, v120
	v_mul_f32_e32 v115, v136, v115
	v_mul_f32_e32 v115, v142, v115
	v_add_f32_dpp v120, v120, v120 quad_perm:[1,0,3,2] row_mask:0xf bank_mask:0xf bound_ctrl:1
	v_cvt_pk_bf16_f32 v115, v115, v115
	global_store_short v[122:123], v115, off offset:96
	v_mov_b32_e32 v122, v110
	v_add_f32_dpp v120, v120, v120 quad_perm:[2,3,0,1] row_mask:0xf bank_mask:0xf bound_ctrl:1
	v_mov_b32_e32 v123, v106
	v_pk_mul_f32 v[122:123], v[122:123], v[138:139] op_sel_hi:[1,0]
	v_add_f32_dpp v120, v120, v120 row_half_mirror row_mask:0xf bank_mask:0xf bound_ctrl:1
	v_pk_mul_f32 v[124:125], v[122:123], v[122:123]
	v_mov_b32_e32 v106, v111
	v_add_f32_dpp v120, v120, v120 row_mirror row_mask:0xf bank_mask:0xf bound_ctrl:1
	v_fmamk_f32 v120, v120, 0x3c800000, v145
	v_mul_f32_e32 v121, 0x4b800000, v120
	v_cmp_gt_f32_e32 vcc, s52, v120
	s_nop 1
	v_cndmask_b32_e32 v120, v120, v121, vcc
	v_rsq_f32_e32 v120, v120
	s_nop 0
	v_mul_f32_e32 v115, 0x45800000, v120
	v_cndmask_b32_e32 v115, v120, v115, vcc
	v_add_u32_e32 v120, 3, v114
	v_ashrrev_i32_e32 v121, 31, v120
	v_mul_f32_e32 v118, v118, v115
	v_lshlrev_b64 v[120:121], 10, v[120:121]
	v_mul_f32_e32 v118, v151, v118
	v_mul_f32_e32 v117, v117, v115
	v_lshl_add_u64 v[120:121], v[126:127], 0, v[120:121]
	v_cvt_pk_bf16_f32 v118, v118, v118
	v_mul_f32_e32 v117, v143, v117
	global_store_short v[120:121], v118, off
	v_mul_f32_e32 v118, v119, v115
	v_cvt_pk_bf16_f32 v117, v117, v117
	v_mul_f32_e32 v118, v150, v118
	global_store_short v[120:121], v117, off offset:64
	v_mul_f32_e32 v115, v116, v115
	v_mov_b32_e32 v116, v102
	v_mov_b32_e32 v117, v98
	v_cvt_pk_bf16_f32 v118, v118, v118
	v_pk_mul_f32 v[116:117], v[116:117], v[138:139] op_sel_hi:[1,0]
	global_store_short v[120:121], v118, off offset:32
	v_pk_mul_f32 v[118:119], v[116:117], v[116:117]
	s_nop 0
	v_add_f32_e32 v98, v118, v119
	v_add_f32_e32 v98, v125, v98
	v_add_f32_e32 v98, v124, v98
	v_add_u32_e32 v118, 16, v114
	v_ashrrev_i32_e32 v119, 31, v118
	v_add_f32_dpp v98, v98, v98 quad_perm:[1,0,3,2] row_mask:0xf bank_mask:0xf bound_ctrl:1
	v_lshlrev_b64 v[118:119], 10, v[118:119]
	v_lshl_add_u64 v[118:119], v[126:127], 0, v[118:119]
	v_add_f32_dpp v98, v98, v98 quad_perm:[2,3,0,1] row_mask:0xf bank_mask:0xf bound_ctrl:1
	s_nop 1
	v_add_f32_dpp v98, v98, v98 row_half_mirror row_mask:0xf bank_mask:0xf bound_ctrl:1
	s_nop 1
	v_add_f32_dpp v98, v98, v98 row_mirror row_mask:0xf bank_mask:0xf bound_ctrl:1
	v_fmamk_f32 v98, v98, 0x3c800000, v145
	v_mul_f32_e32 v102, 0x4b800000, v98
	v_cmp_gt_f32_e32 vcc, s52, v98
	s_nop 1
	v_cndmask_b32_e32 v98, v98, v102, vcc
	v_rsq_f32_e32 v98, v98
	v_mul_f32_e32 v102, v142, v115
	v_cvt_pk_bf16_f32 v102, v102, v102
	global_store_short v[120:121], v102, off offset:96
	v_mul_f32_e32 v102, 0x45800000, v98
	v_cndmask_b32_e32 v98, v98, v102, vcc
	v_mul_f32_e32 v102, v116, v98
	v_mul_f32_e32 v102, v151, v102
	v_cvt_pk_bf16_f32 v102, v102, v102
	global_store_short v[118:119], v102, off
	v_mul_f32_e32 v102, v117, v98
	v_mul_f32_e32 v102, v150, v102
	v_cvt_pk_bf16_f32 v102, v102, v102
	global_store_short v[118:119], v102, off offset:32
	v_mul_f32_e32 v102, v123, v98
	v_mul_f32_e32 v102, v143, v102
	v_cvt_pk_bf16_f32 v102, v102, v102
	global_store_short v[118:119], v102, off offset:64
	v_mul_f32_e32 v110, v122, v98
	v_mov_b32_e32 v98, v103
	v_mov_b32_e32 v102, v139
	v_pk_mul_f32 v[98:99], v[98:99], v[102:103] op_sel_hi:[1,0]
	v_pk_mul_f32 v[102:103], v[106:107], v[102:103] op_sel_hi:[1,0]
	v_pk_mul_f32 v[116:117], v[98:99], v[98:99]
	v_pk_mul_f32 v[106:107], v[102:103], v[102:103]
	v_add_f32_e32 v111, v116, v117
	v_add_f32_e32 v107, v107, v111
	v_add_f32_e32 v106, v106, v107
	v_mov_b32_e32 v111, v108
	v_mov_b32_e32 v108, v113
	v_add_f32_dpp v106, v106, v106 quad_perm:[1,0,3,2] row_mask:0xf bank_mask:0xf bound_ctrl:1
	v_mov_b32_e32 v113, v90
	v_mov_b32_e32 v90, v95
	v_add_f32_dpp v106, v106, v106 quad_perm:[2,3,0,1] row_mask:0xf bank_mask:0xf bound_ctrl:1
	s_nop 1
	v_add_f32_dpp v106, v106, v106 row_half_mirror row_mask:0xf bank_mask:0xf bound_ctrl:1
	s_nop 1
	v_add_f32_dpp v106, v106, v106 row_mirror row_mask:0xf bank_mask:0xf bound_ctrl:1
	v_fmamk_f32 v106, v106, 0x3c800000, v145
	v_mul_f32_e32 v107, 0x4b800000, v106
	v_cmp_gt_f32_e32 vcc, s52, v106
	s_nop 1
	v_cndmask_b32_e32 v106, v106, v107, vcc
	v_rsq_f32_e32 v106, v106
	v_mul_f32_e32 v107, v142, v110
	v_cvt_pk_bf16_f32 v107, v107, v107
	global_store_short v[118:119], v107, off offset:96
	v_mul_f32_e32 v107, 0x45800000, v106
	v_cndmask_b32_e32 v110, v106, v107, vcc
	v_add_u32_e32 v106, 17, v114
	v_ashrrev_i32_e32 v107, 31, v106
; __device__ __forceinline__ unsigned f2bf(float f) { return pk2(f, f) & 0xffffu; }
; __device__ __forceinline__ void phase_inproj() {
;     ...
;       for (int ai = 0; ai < 2; ++ai)
; #pragma unroll
;         for (int m = 0; m < 4; ++m)
; #pragma unroll
;           for (int j = 0; j < 4; ++j) {
;             const int rowl = ai * 128 + wr * 64 + m * 16 + fq * 4 + j;
;             const float r = rr[rowl];
;             float v[2][2]; float ss = 0.f;
; #pragma unroll
;             for (int bj = 0; bj < 2; ++bj)
; #pragma unroll
;               for (int n = 0; n < 2; ++n) { v[bj][n] = acc[ai][bj][m][n][j] * r; ss += v[bj][n] * v[bj][n]; }
;             ss = sum16(ss);
;             const float ri = rsqrtf(ss * (1.f / 64.f) + EPS);
; #pragma unroll
;             for (int bj = 0; bj < 2; ++bj)
; #pragma unroll
;               for (int n = 0; n < 2; ++n)
;                 dst[(size_t)(brow + rowl) * AW + head * 64 + bj * 32 + n * 16 + fr] = (unsigned short)f2bf(v[bj][n] * ri * gn[bj][n]);
	v_mul_f32_e32 v98, v98, v110
	v_lshlrev_b64 v[106:107], 10, v[106:107]
	v_mul_f32_e32 v98, v151, v98
	v_lshl_add_u64 v[106:107], v[126:127], 0, v[106:107]
	v_cvt_pk_bf16_f32 v98, v98, v98
	global_store_short v[106:107], v98, off
	v_mul_f32_e32 v98, v99, v110
	v_mul_f32_e32 v98, v150, v98
	v_cvt_pk_bf16_f32 v98, v98, v98
	global_store_short v[106:107], v98, off offset:32
	v_mul_f32_e32 v98, v103, v110
	v_mul_f32_e32 v98, v143, v98
	v_cvt_pk_bf16_f32 v98, v98, v98
	global_store_short v[106:107], v98, off offset:64
	v_mov_b32_e32 v98, v104
	v_mov_b32_e32 v99, v100
	v_mul_f32_e32 v115, v102, v110
	v_pk_mul_f32 v[98:99], v[98:99], v[140:141] op_sel_hi:[1,0]
	v_mov_b32_e32 v110, v112
	v_pk_mul_f32 v[102:103], v[98:99], v[98:99]
	v_pk_mul_f32 v[110:111], v[110:111], v[140:141] op_sel_hi:[1,0]
	v_add_f32_e32 v100, v102, v103
	v_pk_mul_f32 v[116:117], v[110:111], v[110:111]
	v_mov_b32_e32 v112, v94
	v_add_f32_e32 v100, v117, v100
	v_add_f32_e32 v100, v116, v100
	s_nop 1
	v_add_f32_dpp v100, v100, v100 quad_perm:[1,0,3,2] row_mask:0xf bank_mask:0xf bound_ctrl:1
	s_nop 1
	v_add_f32_dpp v100, v100, v100 quad_perm:[2,3,0,1] row_mask:0xf bank_mask:0xf bound_ctrl:1
	s_nop 1
	v_add_f32_dpp v100, v100, v100 row_half_mirror row_mask:0xf bank_mask:0xf bound_ctrl:1
	s_nop 1
	v_add_f32_dpp v100, v100, v100 row_mirror row_mask:0xf bank_mask:0xf bound_ctrl:1
	v_fmamk_f32 v100, v100, 0x3c800000, v145
	v_mul_f32_e32 v102, 0x4b800000, v100
	v_cmp_gt_f32_e32 vcc, s52, v100
	s_nop 1
	v_cndmask_b32_e32 v100, v100, v102, vcc
	v_rsq_f32_e32 v100, v100
	v_mul_f32_e32 v102, v142, v115
	v_cvt_pk_bf16_f32 v102, v102, v102
	global_store_short v[106:107], v102, off offset:96
	v_mul_f32_e32 v102, 0x45800000, v100
	v_cndmask_b32_e32 v100, v100, v102, vcc
	v_add_u32_e32 v102, 18, v114
	v_ashrrev_i32_e32 v103, 31, v102
	v_mul_f32_e32 v98, v98, v100
	v_lshlrev_b64 v[102:103], 10, v[102:103]
	v_mul_f32_e32 v98, v151, v98
	v_lshl_add_u64 v[102:103], v[126:127], 0, v[102:103]
	v_cvt_pk_bf16_f32 v98, v98, v98
	global_store_short v[102:103], v98, off
	v_mul_f32_e32 v98, v99, v100
	v_mul_f32_e32 v98, v150, v98
	v_cvt_pk_bf16_f32 v98, v98, v98
	global_store_short v[102:103], v98, off offset:32
	v_mul_f32_e32 v98, v111, v100
	v_mul_f32_e32 v98, v143, v98
	v_cvt_pk_bf16_f32 v98, v98, v98
	global_store_short v[102:103], v98, off offset:64
	v_mul_f32_e32 v110, v110, v100
	v_mov_b32_e32 v100, v105
	v_mov_b32_e32 v98, v141
	v_pk_mul_f32 v[100:101], v[100:101], v[98:99] op_sel_hi:[1,0]
	v_pk_mul_f32 v[106:107], v[108:109], v[98:99] op_sel_hi:[1,0]
	v_pk_mul_f32 v[104:105], v[100:101], v[100:101]
	v_pk_mul_f32 v[98:99], v[106:107], v[106:107]
	v_add_f32_e32 v104, v104, v105
	v_add_f32_e32 v99, v99, v104
	v_add_f32_e32 v98, v98, v99
	s_nop 1
	v_add_f32_dpp v98, v98, v98 quad_perm:[1,0,3,2] row_mask:0xf bank_mask:0xf bound_ctrl:1
	s_nop 1
	v_add_f32_dpp v98, v98, v98 quad_perm:[2,3,0,1] row_mask:0xf bank_mask:0xf bound_ctrl:1
	s_nop 1
	v_add_f32_dpp v98, v98, v98 row_half_mirror row_mask:0xf bank_mask:0xf bound_ctrl:1
	s_nop 1
	v_add_f32_dpp v98, v98, v98 row_mirror row_mask:0xf bank_mask:0xf bound_ctrl:1
	v_fmamk_f32 v98, v98, 0x3c800000, v145
	v_mul_f32_e32 v99, 0x4b800000, v98
	v_cmp_gt_f32_e32 vcc, s52, v98
	s_nop 1
	v_cndmask_b32_e32 v98, v98, v99, vcc
	v_rsq_f32_e32 v98, v98
	v_mul_f32_e32 v99, v142, v110
	v_cvt_pk_bf16_f32 v99, v99, v99
	global_store_short v[102:103], v99, off offset:96
	v_mul_f32_e32 v99, 0x45800000, v98
	v_cndmask_b32_e32 v102, v98, v99, vcc
	v_add_u32_e32 v98, 19, v114
	v_ashrrev_i32_e32 v99, 31, v98
	v_mul_f32_e32 v100, v100, v102
	v_lshlrev_b64 v[98:99], 10, v[98:99]
	v_mul_f32_e32 v100, v151, v100
	v_lshl_add_u64 v[98:99], v[126:127], 0, v[98:99]
	v_cvt_pk_bf16_f32 v100, v100, v100
	global_store_short v[98:99], v100, off
	v_mul_f32_e32 v100, v101, v102
	v_mul_f32_e32 v100, v150, v100
	v_cvt_pk_bf16_f32 v100, v100, v100
	global_store_short v[98:99], v100, off offset:32
	v_mul_f32_e32 v100, v107, v102
	v_mul_f32_e32 v100, v143, v100
	v_cvt_pk_bf16_f32 v100, v100, v100
	global_store_short v[98:99], v100, off offset:64
	ds_read2_b32 v[100:101], v148 offset0:32 offset1:33
	v_mul_f32_e32 v115, v106, v102
	v_mov_b32_e32 v106, v82
	v_mov_b32_e32 v107, v86
	ds_read2_b32 v[102:103], v148 offset0:34 offset1:35
	ds_read2_b32 v[104:105], v148 offset0:48 offset1:49
	ds_read2_b32 v[108:109], v148 offset0:50 offset1:51
	s_waitcnt lgkmcnt(3)
; __device__ __forceinline__ unsigned f2bf(float f) { return pk2(f, f) & 0xffffu; }
; __device__ __forceinline__ void phase_inproj() {
;     ...
;       for (int ai = 0; ai < 2; ++ai)
; #pragma unroll
;         for (int m = 0; m < 4; ++m)
; #pragma unroll
;           for (int j = 0; j < 4; ++j) {
;             const int rowl = ai * 128 + wr * 64 + m * 16 + fq * 4 + j;
;             const float r = rr[rowl];
;             float v[2][2]; float ss = 0.f;
; #pragma unroll
;             for (int bj = 0; bj < 2; ++bj)
; #pragma unroll
;               for (int n = 0; n < 2; ++n) { v[bj][n] = acc[ai][bj][m][n][j] * r; ss += v[bj][n] * v[bj][n]; }
;             ss = sum16(ss);
;             const float ri = rsqrtf(ss * (1.f / 64.f) + EPS);
; #pragma unroll
;             for (int bj = 0; bj < 2; ++bj)
; #pragma unroll
;               for (int n = 0; n < 2; ++n)
;                 dst[(size_t)(brow + rowl) * AW + head * 64 + bj * 32 + n * 16 + fr] = (unsigned short)f2bf(v[bj][n] * ri * gn[bj][n]);
	v_pk_mul_f32 v[106:107], v[106:107], v[100:101] op_sel_hi:[1,0]
	v_pk_mul_f32 v[112:113], v[112:113], v[100:101] op_sel_hi:[1,0]
	v_pk_mul_f32 v[110:111], v[106:107], v[106:107]
	v_pk_mul_f32 v[116:117], v[112:113], v[112:113]
	v_add_f32_e32 v82, v110, v111
	v_add_f32_e32 v82, v117, v82
	v_add_f32_e32 v82, v116, v82
	s_nop 1
	v_add_f32_dpp v82, v82, v82 quad_perm:[1,0,3,2] row_mask:0xf bank_mask:0xf bound_ctrl:1
	s_nop 1
	v_add_f32_dpp v82, v82, v82 quad_perm:[2,3,0,1] row_mask:0xf bank_mask:0xf bound_ctrl:1
	s_nop 1
	v_add_f32_dpp v82, v82, v82 row_half_mirror row_mask:0xf bank_mask:0xf bound_ctrl:1
	s_nop 1
	v_add_f32_dpp v82, v82, v82 row_mirror row_mask:0xf bank_mask:0xf bound_ctrl:1
	v_fmamk_f32 v82, v82, 0x3c800000, v145
	v_mul_f32_e32 v86, 0x4b800000, v82
	v_cmp_gt_f32_e32 vcc, s52, v82
	s_nop 1
	v_cndmask_b32_e32 v82, v82, v86, vcc
	v_rsq_f32_e32 v82, v82
	v_mul_f32_e32 v86, v142, v115
	v_cvt_pk_bf16_f32 v86, v86, v86
	global_store_short v[98:99], v86, off offset:96
	v_mul_f32_e32 v86, 0x45800000, v82
	v_cndmask_b32_e32 v82, v82, v86, vcc
	v_add_u32_e32 v98, 32, v114
	v_ashrrev_i32_e32 v99, 31, v98
	v_mul_f32_e32 v86, v106, v82
	v_lshlrev_b64 v[98:99], 10, v[98:99]
	v_mul_f32_e32 v86, v151, v86
	v_lshl_add_u64 v[98:99], v[126:127], 0, v[98:99]
	v_cvt_pk_bf16_f32 v86, v86, v86
	global_store_short v[98:99], v86, off
	v_mul_f32_e32 v86, v107, v82
	v_mul_f32_e32 v86, v150, v86
	v_cvt_pk_bf16_f32 v86, v86, v86
	global_store_short v[98:99], v86, off offset:32
	v_mul_f32_e32 v86, v113, v82
	v_mul_f32_e32 v86, v143, v86
	v_cvt_pk_bf16_f32 v86, v86, v86
	global_store_short v[98:99], v86, off offset:64
	v_mul_f32_e32 v94, v112, v82
	v_mov_b32_e32 v86, v83
	v_mov_b32_e32 v82, v101
	v_pk_mul_f32 v[86:87], v[86:87], v[82:83] op_sel_hi:[1,0]
	v_pk_mul_f32 v[82:83], v[90:91], v[82:83] op_sel_hi:[1,0]
	v_pk_mul_f32 v[100:101], v[86:87], v[86:87]
	v_pk_mul_f32 v[90:91], v[82:83], v[82:83]
	v_add_f32_e32 v95, v100, v101
	v_add_f32_e32 v91, v91, v95
	v_add_f32_e32 v90, v90, v91
	v_mov_b32_e32 v95, v92
	v_mov_b32_e32 v92, v97
	v_add_f32_dpp v90, v90, v90 quad_perm:[1,0,3,2] row_mask:0xf bank_mask:0xf bound_ctrl:1
	s_nop 1
	v_add_f32_dpp v90, v90, v90 quad_perm:[2,3,0,1] row_mask:0xf bank_mask:0xf bound_ctrl:1
	s_nop 1
	v_add_f32_dpp v90, v90, v90 row_half_mirror row_mask:0xf bank_mask:0xf bound_ctrl:1
	s_nop 1
	v_add_f32_dpp v90, v90, v90 row_mirror row_mask:0xf bank_mask:0xf bound_ctrl:1
	v_fmamk_f32 v90, v90, 0x3c800000, v145
	v_mul_f32_e32 v91, 0x4b800000, v90
	v_cmp_gt_f32_e32 vcc, s52, v90
	s_nop 1
	v_cndmask_b32_e32 v90, v90, v91, vcc
	v_rsq_f32_e32 v90, v90
	v_mul_f32_e32 v91, v142, v94
	v_cvt_pk_bf16_f32 v91, v91, v91
	global_store_short v[98:99], v91, off offset:96
	v_mul_f32_e32 v91, 0x45800000, v90
	v_cndmask_b32_e32 v94, v90, v91, vcc
	v_add_u32_e32 v90, 33, v114
	v_ashrrev_i32_e32 v91, 31, v90
	v_mul_f32_e32 v86, v86, v94
	v_lshlrev_b64 v[90:91], 10, v[90:91]
	v_mul_f32_e32 v86, v151, v86
	v_mul_f32_e32 v83, v83, v94
	v_lshl_add_u64 v[90:91], v[126:127], 0, v[90:91]
	v_cvt_pk_bf16_f32 v86, v86, v86
	v_mul_f32_e32 v83, v143, v83
	global_store_short v[90:91], v86, off
	v_mul_f32_e32 v86, v87, v94
	v_cvt_pk_bf16_f32 v83, v83, v83
	v_mul_f32_e32 v86, v150, v86
	global_store_short v[90:91], v83, off offset:64
	v_mul_f32_e32 v100, v82, v94
	v_mov_b32_e32 v82, v84
	v_mov_b32_e32 v83, v88
	v_cvt_pk_bf16_f32 v86, v86, v86
	s_waitcnt lgkmcnt(2)
	v_pk_mul_f32 v[82:83], v[82:83], v[102:103] op_sel_hi:[1,0]
	v_mov_b32_e32 v94, v96
	global_store_short v[90:91], v86, off offset:32
	v_pk_mul_f32 v[86:87], v[82:83], v[82:83]
	v_pk_mul_f32 v[94:95], v[94:95], v[102:103] op_sel_hi:[1,0]
	v_add_f32_e32 v84, v86, v87
	v_pk_mul_f32 v[98:99], v[94:95], v[94:95]
	v_mov_b32_e32 v88, v85
	v_add_f32_e32 v84, v99, v84
	v_add_f32_e32 v84, v98, v84
	s_nop 1
	v_add_f32_dpp v84, v84, v84 quad_perm:[1,0,3,2] row_mask:0xf bank_mask:0xf bound_ctrl:1
	s_nop 1
	v_add_f32_dpp v84, v84, v84 quad_perm:[2,3,0,1] row_mask:0xf bank_mask:0xf bound_ctrl:1
	s_nop 1
	v_add_f32_dpp v84, v84, v84 row_half_mirror row_mask:0xf bank_mask:0xf bound_ctrl:1
	s_nop 1
	v_add_f32_dpp v84, v84, v84 row_mirror row_mask:0xf bank_mask:0xf bound_ctrl:1
	v_fmamk_f32 v84, v84, 0x3c800000, v145
	v_mul_f32_e32 v86, 0x4b800000, v84
	v_cmp_gt_f32_e32 vcc, s52, v84
	s_nop 1
	v_cndmask_b32_e32 v84, v84, v86, vcc
	v_rsq_f32_e32 v84, v84
	v_mul_f32_e32 v86, v142, v100
	v_cvt_pk_bf16_f32 v86, v86, v86
	global_store_short v[90:91], v86, off offset:96
	v_mul_f32_e32 v86, 0x45800000, v84
	v_cndmask_b32_e32 v84, v84, v86, vcc
	v_add_u32_e32 v86, 34, v114
	v_ashrrev_i32_e32 v87, 31, v86
	v_mul_f32_e32 v82, v82, v84
	v_lshlrev_b64 v[86:87], 10, v[86:87]
	v_mul_f32_e32 v82, v151, v82
	v_lshl_add_u64 v[86:87], v[126:127], 0, v[86:87]
	v_cvt_pk_bf16_f32 v82, v82, v82
	global_store_short v[86:87], v82, off
	v_mul_f32_e32 v82, v83, v84
	v_mul_f32_e32 v82, v150, v82
	v_cvt_pk_bf16_f32 v82, v82, v82
	global_store_short v[86:87], v82, off offset:32
	v_mul_f32_e32 v82, v95, v84
	v_mul_f32_e32 v82, v143, v82
	v_cvt_pk_bf16_f32 v82, v82, v82
	global_store_short v[86:87], v82, off offset:64
	v_mov_b32_e32 v82, v103
	v_mul_f32_e32 v94, v94, v84
	v_pk_mul_f32 v[84:85], v[88:89], v[82:83] op_sel_hi:[1,0]
	v_pk_mul_f32 v[82:83], v[92:93], v[82:83] op_sel_hi:[1,0]
	v_pk_mul_f32 v[88:89], v[84:85], v[84:85]
	v_pk_mul_f32 v[90:91], v[82:83], v[82:83]
	v_add_f32_e32 v88, v88, v89
	v_add_f32_e32 v88, v91, v88
	v_add_f32_e32 v88, v90, v88
	s_nop 1
	v_add_f32_dpp v88, v88, v88 quad_perm:[1,0,3,2] row_mask:0xf bank_mask:0xf bound_ctrl:1
	s_nop 1
	v_add_f32_dpp v88, v88, v88 quad_perm:[2,3,0,1] row_mask:0xf bank_mask:0xf bound_ctrl:1
	s_nop 1
	v_add_f32_dpp v88, v88, v88 row_half_mirror row_mask:0xf bank_mask:0xf bound_ctrl:1
	s_nop 1
	v_add_f32_dpp v88, v88, v88 row_mirror row_mask:0xf bank_mask:0xf bound_ctrl:1
	v_fmamk_f32 v88, v88, 0x3c800000, v145
	v_mul_f32_e32 v89, 0x4b800000, v88
	v_cmp_gt_f32_e32 vcc, s52, v88
	s_nop 1
	v_cndmask_b32_e32 v88, v88, v89, vcc
	v_rsq_f32_e32 v88, v88
	v_mul_f32_e32 v89, v142, v94
	v_cvt_pk_bf16_f32 v89, v89, v89
	global_store_short v[86:87], v89, off offset:96
	v_mul_f32_e32 v86, 0x45800000, v88
	v_cndmask_b32_e32 v88, v88, v86, vcc
	v_add_u32_e32 v86, 35, v114
	v_ashrrev_i32_e32 v87, 31, v86
	v_mul_f32_e32 v84, v84, v88
	v_lshlrev_b64 v[86:87], 10, v[86:87]
	v_mul_f32_e32 v84, v151, v84
	v_mul_f32_e32 v83, v83, v88
	v_lshl_add_u64 v[86:87], v[126:127], 0, v[86:87]
	v_cvt_pk_bf16_f32 v84, v84, v84
	v_mul_f32_e32 v83, v143, v83
	global_store_short v[86:87], v84, off
	v_mul_f32_e32 v84, v85, v88
	v_cvt_pk_bf16_f32 v83, v83, v83
	v_mul_f32_e32 v84, v150, v84
	global_store_short v[86:87], v83, off offset:64
	v_mul_f32_e32 v92, v82, v88
	v_mov_b32_e32 v82, v70
	v_mov_b32_e32 v83, v66
	v_cvt_pk_bf16_f32 v84, v84, v84
	s_waitcnt lgkmcnt(1)
; __device__ __forceinline__ unsigned f2bf(float f) { return pk2(f, f) & 0xffffu; }
; __device__ __forceinline__ void phase_inproj() {
;     ...
;       for (int ai = 0; ai < 2; ++ai)
; #pragma unroll
;         for (int m = 0; m < 4; ++m)
; #pragma unroll
;           for (int j = 0; j < 4; ++j) {
;             const int rowl = ai * 128 + wr * 64 + m * 16 + fq * 4 + j;
;             const float r = rr[rowl];
;             float v[2][2]; float ss = 0.f;
; #pragma unroll
;             for (int bj = 0; bj < 2; ++bj)
; #pragma unroll
;               for (int n = 0; n < 2; ++n) { v[bj][n] = acc[ai][bj][m][n][j] * r; ss += v[bj][n] * v[bj][n]; }
;             ss = sum16(ss);
;             const float ri = rsqrtf(ss * (1.f / 64.f) + EPS);
; #pragma unroll
;             for (int bj = 0; bj < 2; ++bj)
; #pragma unroll
;               for (int n = 0; n < 2; ++n)
;                 dst[(size_t)(brow + rowl) * AW + head * 64 + bj * 32 + n * 16 + fr] = (unsigned short)f2bf(v[bj][n] * ri * gn[bj][n]);
	v_pk_mul_f32 v[82:83], v[82:83], v[104:105] op_sel_hi:[1,0]
	v_mov_b32_e32 v88, v78
	v_mov_b32_e32 v89, v74
	global_store_short v[86:87], v84, off offset:32
	v_pk_mul_f32 v[84:85], v[82:83], v[82:83]
	v_pk_mul_f32 v[88:89], v[88:89], v[104:105] op_sel_hi:[1,0]
	v_add_f32_e32 v66, v84, v85
	v_pk_mul_f32 v[90:91], v[88:89], v[88:89]
	v_add_u32_e32 v84, 48, v114
	v_add_f32_e32 v66, v91, v66
	v_add_f32_e32 v66, v90, v66
	v_ashrrev_i32_e32 v85, 31, v84
	v_lshlrev_b64 v[84:85], 10, v[84:85]
	v_add_f32_dpp v66, v66, v66 quad_perm:[1,0,3,2] row_mask:0xf bank_mask:0xf bound_ctrl:1
	v_lshl_add_u64 v[84:85], v[126:127], 0, v[84:85]
	v_mov_b32_e32 v74, v79
	v_add_f32_dpp v66, v66, v66 quad_perm:[2,3,0,1] row_mask:0xf bank_mask:0xf bound_ctrl:1
	s_nop 1
	v_add_f32_dpp v66, v66, v66 row_half_mirror row_mask:0xf bank_mask:0xf bound_ctrl:1
	s_nop 1
	v_add_f32_dpp v66, v66, v66 row_mirror row_mask:0xf bank_mask:0xf bound_ctrl:1
	v_fmamk_f32 v66, v66, 0x3c800000, v145
	v_mul_f32_e32 v70, 0x4b800000, v66
	v_cmp_gt_f32_e32 vcc, s52, v66
	s_nop 1
	v_cndmask_b32_e32 v66, v66, v70, vcc
	v_rsq_f32_e32 v66, v66
	v_mul_f32_e32 v70, v142, v92
	v_cvt_pk_bf16_f32 v70, v70, v70
	global_store_short v[86:87], v70, off offset:96
	v_mul_f32_e32 v70, 0x45800000, v66
	v_cndmask_b32_e32 v66, v66, v70, vcc
	v_mul_f32_e32 v70, v82, v66
	v_mul_f32_e32 v70, v151, v70
	v_cvt_pk_bf16_f32 v70, v70, v70
	global_store_short v[84:85], v70, off
	v_mul_f32_e32 v70, v83, v66
	v_mul_f32_e32 v70, v150, v70
	v_cvt_pk_bf16_f32 v70, v70, v70
	global_store_short v[84:85], v70, off offset:32
	v_mul_f32_e32 v70, v89, v66
	v_mul_f32_e32 v70, v143, v70
	v_cvt_pk_bf16_f32 v70, v70, v70
	global_store_short v[84:85], v70, off offset:64
	v_mul_f32_e32 v78, v88, v66
	v_mov_b32_e32 v66, v71
	v_mov_b32_e32 v70, v105
	v_pk_mul_f32 v[66:67], v[66:67], v[70:71] op_sel_hi:[1,0]
	v_pk_mul_f32 v[70:71], v[74:75], v[70:71] op_sel_hi:[1,0]
	v_pk_mul_f32 v[82:83], v[66:67], v[66:67]
	v_pk_mul_f32 v[74:75], v[70:71], v[70:71]
	v_add_f32_e32 v79, v82, v83
	v_add_f32_e32 v75, v75, v79
	v_add_f32_e32 v74, v74, v75
	v_mov_b32_e32 v79, v76
	v_mov_b32_e32 v76, v81
	v_add_f32_dpp v74, v74, v74 quad_perm:[1,0,3,2] row_mask:0xf bank_mask:0xf bound_ctrl:1
	v_mov_b32_e32 v81, v58
	v_mov_b32_e32 v58, v63
	v_add_f32_dpp v74, v74, v74 quad_perm:[2,3,0,1] row_mask:0xf bank_mask:0xf bound_ctrl:1
	s_nop 1
	v_add_f32_dpp v74, v74, v74 row_half_mirror row_mask:0xf bank_mask:0xf bound_ctrl:1
	s_nop 1
	v_add_f32_dpp v74, v74, v74 row_mirror row_mask:0xf bank_mask:0xf bound_ctrl:1
	v_fmamk_f32 v74, v74, 0x3c800000, v145
	v_mul_f32_e32 v75, 0x4b800000, v74
	v_cmp_gt_f32_e32 vcc, s52, v74
	s_nop 1
	v_cndmask_b32_e32 v74, v74, v75, vcc
	v_rsq_f32_e32 v74, v74
	v_mul_f32_e32 v75, v142, v78
	v_cvt_pk_bf16_f32 v75, v75, v75
	global_store_short v[84:85], v75, off offset:96
	v_mul_f32_e32 v75, 0x45800000, v74
	v_cndmask_b32_e32 v78, v74, v75, vcc
	v_add_u32_e32 v74, 49, v114
	v_ashrrev_i32_e32 v75, 31, v74
	v_mul_f32_e32 v66, v66, v78
	v_lshlrev_b64 v[74:75], 10, v[74:75]
	v_mul_f32_e32 v66, v151, v66
	v_lshl_add_u64 v[74:75], v[126:127], 0, v[74:75]
	v_cvt_pk_bf16_f32 v66, v66, v66
	global_store_short v[74:75], v66, off
	v_mul_f32_e32 v66, v67, v78
	v_mul_f32_e32 v66, v150, v66
	v_cvt_pk_bf16_f32 v66, v66, v66
	global_store_short v[74:75], v66, off offset:32
	v_mul_f32_e32 v66, v71, v78
	v_mul_f32_e32 v66, v143, v66
	v_cvt_pk_bf16_f32 v66, v66, v66
	global_store_short v[74:75], v66, off offset:64
	v_mov_b32_e32 v66, v72
	v_mov_b32_e32 v67, v68
	v_mul_f32_e32 v84, v70, v78
	s_waitcnt lgkmcnt(0)
	v_pk_mul_f32 v[66:67], v[66:67], v[108:109] op_sel_hi:[1,0]
	v_mov_b32_e32 v78, v80
	v_pk_mul_f32 v[70:71], v[66:67], v[66:67]
	v_pk_mul_f32 v[78:79], v[78:79], v[108:109] op_sel_hi:[1,0]
	v_add_f32_e32 v68, v70, v71
	v_pk_mul_f32 v[82:83], v[78:79], v[78:79]
	v_mov_b32_e32 v80, v62
	v_add_f32_e32 v68, v83, v68
	v_add_f32_e32 v68, v82, v68
	s_nop 1
	v_add_f32_dpp v68, v68, v68 quad_perm:[1,0,3,2] row_mask:0xf bank_mask:0xf bound_ctrl:1
	s_nop 1
	v_add_f32_dpp v68, v68, v68 quad_perm:[2,3,0,1] row_mask:0xf bank_mask:0xf bound_ctrl:1
	s_nop 1
	v_add_f32_dpp v68, v68, v68 row_half_mirror row_mask:0xf bank_mask:0xf bound_ctrl:1
	s_nop 1
	v_add_f32_dpp v68, v68, v68 row_mirror row_mask:0xf bank_mask:0xf bound_ctrl:1
	v_fmamk_f32 v68, v68, 0x3c800000, v145
	v_mul_f32_e32 v70, 0x4b800000, v68
	v_cmp_gt_f32_e32 vcc, s52, v68
	s_nop 1
	v_cndmask_b32_e32 v68, v68, v70, vcc
	v_rsq_f32_e32 v68, v68
	v_mul_f32_e32 v70, v142, v84
	v_cvt_pk_bf16_f32 v70, v70, v70
	global_store_short v[74:75], v70, off offset:96
	v_mul_f32_e32 v70, 0x45800000, v68
	v_cndmask_b32_e32 v68, v68, v70, vcc
	v_add_u32_e32 v70, 50, v114
	v_ashrrev_i32_e32 v71, 31, v70
	v_mul_f32_e32 v66, v66, v68
	v_lshlrev_b64 v[70:71], 10, v[70:71]
	v_mul_f32_e32 v66, v151, v66
	v_lshl_add_u64 v[70:71], v[126:127], 0, v[70:71]
	v_cvt_pk_bf16_f32 v66, v66, v66
	global_store_short v[70:71], v66, off
	v_mul_f32_e32 v66, v67, v68
	v_mul_f32_e32 v66, v150, v66
	v_cvt_pk_bf16_f32 v66, v66, v66
	global_store_short v[70:71], v66, off offset:32
	v_mul_f32_e32 v66, v79, v68
	v_mul_f32_e32 v66, v143, v66
	v_cvt_pk_bf16_f32 v66, v66, v66
	global_store_short v[70:71], v66, off offset:64
	v_mul_f32_e32 v78, v78, v68
	v_mov_b32_e32 v68, v73
	v_mov_b32_e32 v66, v109
	v_pk_mul_f32 v[68:69], v[68:69], v[66:67] op_sel_hi:[1,0]
	v_pk_mul_f32 v[74:75], v[76:77], v[66:67] op_sel_hi:[1,0]
	v_pk_mul_f32 v[72:73], v[68:69], v[68:69]
	v_pk_mul_f32 v[66:67], v[74:75], v[74:75]
	v_add_f32_e32 v72, v72, v73
	v_add_f32_e32 v67, v67, v72
	v_add_f32_e32 v66, v66, v67
	s_nop 1
	v_add_f32_dpp v66, v66, v66 quad_perm:[1,0,3,2] row_mask:0xf bank_mask:0xf bound_ctrl:1
; __device__ __forceinline__ unsigned f2bf(float f) { return pk2(f, f) & 0xffffu; }
; __device__ __forceinline__ void phase_inproj() {
;     ...
;       for (int ai = 0; ai < 2; ++ai)
; #pragma unroll
;         for (int m = 0; m < 4; ++m)
; #pragma unroll
;           for (int j = 0; j < 4; ++j) {
;             const int rowl = ai * 128 + wr * 64 + m * 16 + fq * 4 + j;
;             const float r = rr[rowl];
;             float v[2][2]; float ss = 0.f;
; #pragma unroll
;             for (int bj = 0; bj < 2; ++bj)
; #pragma unroll
;               for (int n = 0; n < 2; ++n) { v[bj][n] = acc[ai][bj][m][n][j] * r; ss += v[bj][n] * v[bj][n]; }
;             ss = sum16(ss);
;             const float ri = rsqrtf(ss * (1.f / 64.f) + EPS);
; #pragma unroll
;             for (int bj = 0; bj < 2; ++bj)
; #pragma unroll
;               for (int n = 0; n < 2; ++n)
;                 dst[(size_t)(brow + rowl) * AW + head * 64 + bj * 32 + n * 16 + fr] = (unsigned short)f2bf(v[bj][n] * ri * gn[bj][n]);
	s_nop 1
	v_add_f32_dpp v66, v66, v66 quad_perm:[2,3,0,1] row_mask:0xf bank_mask:0xf bound_ctrl:1
	s_nop 1
	v_add_f32_dpp v66, v66, v66 row_half_mirror row_mask:0xf bank_mask:0xf bound_ctrl:1
	s_nop 1
	v_add_f32_dpp v66, v66, v66 row_mirror row_mask:0xf bank_mask:0xf bound_ctrl:1
	v_fmamk_f32 v66, v66, 0x3c800000, v145
	v_mul_f32_e32 v67, 0x4b800000, v66
	v_cmp_gt_f32_e32 vcc, s52, v66
	s_nop 1
	v_cndmask_b32_e32 v66, v66, v67, vcc
	v_rsq_f32_e32 v66, v66
	v_mul_f32_e32 v67, v142, v78
	v_cvt_pk_bf16_f32 v67, v67, v67
	global_store_short v[70:71], v67, off offset:96
	v_mul_f32_e32 v67, 0x45800000, v66
	v_cndmask_b32_e32 v70, v66, v67, vcc
	v_add_u32_e32 v66, 51, v114
	v_ashrrev_i32_e32 v67, 31, v66
	v_mul_f32_e32 v68, v68, v70
	v_lshlrev_b64 v[66:67], 10, v[66:67]
	v_mul_f32_e32 v68, v151, v68
	v_lshl_add_u64 v[66:67], v[126:127], 0, v[66:67]
	v_cvt_pk_bf16_f32 v68, v68, v68
	global_store_short v[66:67], v68, off
	v_mul_f32_e32 v68, v69, v70
	v_mul_f32_e32 v68, v150, v68
	v_cvt_pk_bf16_f32 v68, v68, v68
	global_store_short v[66:67], v68, off offset:32
	v_mul_f32_e32 v68, v75, v70
	v_mul_f32_e32 v68, v143, v68
	v_cvt_pk_bf16_f32 v68, v68, v68
	global_store_short v[66:67], v68, off offset:64
	ds_read2_b32 v[68:69], v148 offset0:128 offset1:129
	v_mul_f32_e32 v84, v74, v70
	v_mov_b32_e32 v74, v50
	v_mov_b32_e32 v75, v54
	ds_read2_b32 v[70:71], v148 offset0:130 offset1:131
	ds_read2_b32 v[72:73], v148 offset0:144 offset1:145
	ds_read2_b32 v[76:77], v148 offset0:146 offset1:147
	s_waitcnt lgkmcnt(3)
	v_pk_mul_f32 v[74:75], v[74:75], v[68:69] op_sel_hi:[1,0]
	v_pk_mul_f32 v[80:81], v[80:81], v[68:69] op_sel_hi:[1,0]
	v_pk_mul_f32 v[78:79], v[74:75], v[74:75]
	v_pk_mul_f32 v[82:83], v[80:81], v[80:81]
	v_add_f32_e32 v50, v78, v79
	v_add_f32_e32 v50, v83, v50
	v_add_f32_e32 v50, v82, v50
	s_nop 1
	v_add_f32_dpp v50, v50, v50 quad_perm:[1,0,3,2] row_mask:0xf bank_mask:0xf bound_ctrl:1
	s_nop 1
	v_add_f32_dpp v50, v50, v50 quad_perm:[2,3,0,1] row_mask:0xf bank_mask:0xf bound_ctrl:1
	s_nop 1
	v_add_f32_dpp v50, v50, v50 row_half_mirror row_mask:0xf bank_mask:0xf bound_ctrl:1
	s_nop 1
	v_add_f32_dpp v50, v50, v50 row_mirror row_mask:0xf bank_mask:0xf bound_ctrl:1
	v_fmamk_f32 v50, v50, 0x3c800000, v145
	v_mul_f32_e32 v54, 0x4b800000, v50
	v_cmp_gt_f32_e32 vcc, s52, v50
	s_nop 1
	v_cndmask_b32_e32 v50, v50, v54, vcc
	v_rsq_f32_e32 v50, v50
	v_mul_f32_e32 v54, v142, v84
	v_cvt_pk_bf16_f32 v54, v54, v54
	global_store_short v[66:67], v54, off offset:96
	v_mul_f32_e32 v54, 0x45800000, v50
	v_cndmask_b32_e32 v50, v50, v54, vcc
	v_add_u32_e32 v66, 0x80, v114
	v_ashrrev_i32_e32 v67, 31, v66
	v_mul_f32_e32 v54, v74, v50
	v_lshlrev_b64 v[66:67], 10, v[66:67]
	v_mul_f32_e32 v54, v151, v54
	v_lshl_add_u64 v[66:67], v[126:127], 0, v[66:67]
	v_cvt_pk_bf16_f32 v54, v54, v54
	global_store_short v[66:67], v54, off
	v_mul_f32_e32 v54, v75, v50
	v_mul_f32_e32 v54, v150, v54
	v_cvt_pk_bf16_f32 v54, v54, v54
	global_store_short v[66:67], v54, off offset:32
	v_mul_f32_e32 v54, v81, v50
	v_mul_f32_e32 v54, v143, v54
	v_cvt_pk_bf16_f32 v54, v54, v54
	global_store_short v[66:67], v54, off offset:64
	v_mul_f32_e32 v62, v80, v50
	v_mov_b32_e32 v54, v51
	v_mov_b32_e32 v50, v69
	v_pk_mul_f32 v[54:55], v[54:55], v[50:51] op_sel_hi:[1,0]
	v_pk_mul_f32 v[50:51], v[58:59], v[50:51] op_sel_hi:[1,0]
	v_pk_mul_f32 v[68:69], v[54:55], v[54:55]
	v_pk_mul_f32 v[58:59], v[50:51], v[50:51]
	v_add_f32_e32 v63, v68, v69
	v_add_f32_e32 v59, v59, v63
	v_add_f32_e32 v58, v58, v59
	v_mov_b32_e32 v63, v60
	v_mov_b32_e32 v60, v65
	v_add_f32_dpp v58, v58, v58 quad_perm:[1,0,3,2] row_mask:0xf bank_mask:0xf bound_ctrl:1
	s_nop 1
	v_add_f32_dpp v58, v58, v58 quad_perm:[2,3,0,1] row_mask:0xf bank_mask:0xf bound_ctrl:1
	s_nop 1
	v_add_f32_dpp v58, v58, v58 row_half_mirror row_mask:0xf bank_mask:0xf bound_ctrl:1
	s_nop 1
	v_add_f32_dpp v58, v58, v58 row_mirror row_mask:0xf bank_mask:0xf bound_ctrl:1
	v_fmamk_f32 v58, v58, 0x3c800000, v145
	v_mul_f32_e32 v59, 0x4b800000, v58
	v_cmp_gt_f32_e32 vcc, s52, v58
	s_nop 1
	v_cndmask_b32_e32 v58, v58, v59, vcc
	v_rsq_f32_e32 v58, v58
	v_mul_f32_e32 v59, v142, v62
	v_cvt_pk_bf16_f32 v59, v59, v59
	global_store_short v[66:67], v59, off offset:96
	v_mul_f32_e32 v59, 0x45800000, v58
	v_cndmask_b32_e32 v62, v58, v59, vcc
	v_add_u32_e32 v58, 0x81, v114
	v_ashrrev_i32_e32 v59, 31, v58
	v_mul_f32_e32 v54, v54, v62
	v_lshlrev_b64 v[58:59], 10, v[58:59]
	v_mul_f32_e32 v54, v151, v54
	v_mul_f32_e32 v51, v51, v62
	v_lshl_add_u64 v[58:59], v[126:127], 0, v[58:59]
	v_cvt_pk_bf16_f32 v54, v54, v54
	v_mul_f32_e32 v51, v143, v51
	global_store_short v[58:59], v54, off
	v_mul_f32_e32 v54, v55, v62
	v_cvt_pk_bf16_f32 v51, v51, v51
	v_mul_f32_e32 v54, v150, v54
	global_store_short v[58:59], v51, off offset:64
	v_mul_f32_e32 v68, v50, v62
	v_mov_b32_e32 v50, v52
	v_mov_b32_e32 v51, v56
	v_cvt_pk_bf16_f32 v54, v54, v54
	s_waitcnt lgkmcnt(2)
; __device__ __forceinline__ unsigned f2bf(float f) { return pk2(f, f) & 0xffffu; }
; __device__ __forceinline__ void phase_inproj() {
;     ...
;       for (int ai = 0; ai < 2; ++ai)
; #pragma unroll
;         for (int m = 0; m < 4; ++m)
; #pragma unroll
;           for (int j = 0; j < 4; ++j) {
;             const int rowl = ai * 128 + wr * 64 + m * 16 + fq * 4 + j;
;             const float r = rr[rowl];
;             float v[2][2]; float ss = 0.f;
; #pragma unroll
;             for (int bj = 0; bj < 2; ++bj)
; #pragma unroll
;               for (int n = 0; n < 2; ++n) { v[bj][n] = acc[ai][bj][m][n][j] * r; ss += v[bj][n] * v[bj][n]; }
;             ss = sum16(ss);
;             const float ri = rsqrtf(ss * (1.f / 64.f) + EPS);
; #pragma unroll
;             for (int bj = 0; bj < 2; ++bj)
; #pragma unroll
;               for (int n = 0; n < 2; ++n)
;                 dst[(size_t)(brow + rowl) * AW + head * 64 + bj * 32 + n * 16 + fr] = (unsigned short)f2bf(v[bj][n] * ri * gn[bj][n]);
	v_pk_mul_f32 v[50:51], v[50:51], v[70:71] op_sel_hi:[1,0]
	v_mov_b32_e32 v62, v64
	global_store_short v[58:59], v54, off offset:32
	v_pk_mul_f32 v[54:55], v[50:51], v[50:51]
	v_pk_mul_f32 v[62:63], v[62:63], v[70:71] op_sel_hi:[1,0]
	v_add_f32_e32 v52, v54, v55
	v_pk_mul_f32 v[66:67], v[62:63], v[62:63]
	v_mov_b32_e32 v56, v53
	v_add_f32_e32 v52, v67, v52
	v_add_f32_e32 v52, v66, v52
	s_nop 1
	v_add_f32_dpp v52, v52, v52 quad_perm:[1,0,3,2] row_mask:0xf bank_mask:0xf bound_ctrl:1
	s_nop 1
	v_add_f32_dpp v52, v52, v52 quad_perm:[2,3,0,1] row_mask:0xf bank_mask:0xf bound_ctrl:1
	s_nop 1
	v_add_f32_dpp v52, v52, v52 row_half_mirror row_mask:0xf bank_mask:0xf bound_ctrl:1
	s_nop 1
	v_add_f32_dpp v52, v52, v52 row_mirror row_mask:0xf bank_mask:0xf bound_ctrl:1
	v_fmamk_f32 v52, v52, 0x3c800000, v145
	v_mul_f32_e32 v54, 0x4b800000, v52
	v_cmp_gt_f32_e32 vcc, s52, v52
	s_nop 1
	v_cndmask_b32_e32 v52, v52, v54, vcc
	v_rsq_f32_e32 v52, v52
	v_mul_f32_e32 v54, v142, v68
	v_cvt_pk_bf16_f32 v54, v54, v54
	global_store_short v[58:59], v54, off offset:96
	v_mul_f32_e32 v54, 0x45800000, v52
	v_cndmask_b32_e32 v52, v52, v54, vcc
	v_add_u32_e32 v54, 0x82, v114
	v_ashrrev_i32_e32 v55, 31, v54
	v_mul_f32_e32 v50, v50, v52
	v_lshlrev_b64 v[54:55], 10, v[54:55]
	v_mul_f32_e32 v50, v151, v50
	v_lshl_add_u64 v[54:55], v[126:127], 0, v[54:55]
	v_cvt_pk_bf16_f32 v50, v50, v50
	global_store_short v[54:55], v50, off
	v_mul_f32_e32 v50, v51, v52
	v_mul_f32_e32 v50, v150, v50
	v_cvt_pk_bf16_f32 v50, v50, v50
	global_store_short v[54:55], v50, off offset:32
	v_mul_f32_e32 v50, v63, v52
	v_mul_f32_e32 v50, v143, v50
	v_cvt_pk_bf16_f32 v50, v50, v50
	global_store_short v[54:55], v50, off offset:64
	v_mov_b32_e32 v50, v71
	v_mul_f32_e32 v62, v62, v52
	v_pk_mul_f32 v[52:53], v[56:57], v[50:51] op_sel_hi:[1,0]
	v_pk_mul_f32 v[50:51], v[60:61], v[50:51] op_sel_hi:[1,0]
	v_pk_mul_f32 v[56:57], v[52:53], v[52:53]
	v_pk_mul_f32 v[58:59], v[50:51], v[50:51]
	v_add_f32_e32 v56, v56, v57
	v_add_f32_e32 v56, v59, v56
	v_add_f32_e32 v56, v58, v56
	s_nop 1
	v_add_f32_dpp v56, v56, v56 quad_perm:[1,0,3,2] row_mask:0xf bank_mask:0xf bound_ctrl:1
	s_nop 1
	v_add_f32_dpp v56, v56, v56 quad_perm:[2,3,0,1] row_mask:0xf bank_mask:0xf bound_ctrl:1
	s_nop 1
	v_add_f32_dpp v56, v56, v56 row_half_mirror row_mask:0xf bank_mask:0xf bound_ctrl:1
	s_nop 1
	v_add_f32_dpp v56, v56, v56 row_mirror row_mask:0xf bank_mask:0xf bound_ctrl:1
	v_fmamk_f32 v56, v56, 0x3c800000, v145
	v_mul_f32_e32 v57, 0x4b800000, v56
	v_cmp_gt_f32_e32 vcc, s52, v56
	s_nop 1
	v_cndmask_b32_e32 v56, v56, v57, vcc
	v_rsq_f32_e32 v56, v56
	v_mul_f32_e32 v57, v142, v62
	v_cvt_pk_bf16_f32 v57, v57, v57
	global_store_short v[54:55], v57, off offset:96
	v_mul_f32_e32 v54, 0x45800000, v56
	v_cndmask_b32_e32 v56, v56, v54, vcc
	v_add_u32_e32 v54, 0x83, v114
	v_ashrrev_i32_e32 v55, 31, v54
	v_mul_f32_e32 v52, v52, v56
	v_lshlrev_b64 v[54:55], 10, v[54:55]
	v_mul_f32_e32 v52, v151, v52
	v_mul_f32_e32 v51, v51, v56
	v_lshl_add_u64 v[54:55], v[126:127], 0, v[54:55]
	v_cvt_pk_bf16_f32 v52, v52, v52
	v_mul_f32_e32 v51, v143, v51
	global_store_short v[54:55], v52, off
	v_mul_f32_e32 v52, v53, v56
	v_cvt_pk_bf16_f32 v51, v51, v51
	v_mul_f32_e32 v52, v150, v52
	global_store_short v[54:55], v51, off offset:64
	v_mul_f32_e32 v60, v50, v56
	v_mov_b32_e32 v50, v38
	v_mov_b32_e32 v51, v34
	v_cvt_pk_bf16_f32 v52, v52, v52
	s_waitcnt lgkmcnt(1)
	v_pk_mul_f32 v[50:51], v[50:51], v[72:73] op_sel_hi:[1,0]
	v_mov_b32_e32 v56, v46
	v_mov_b32_e32 v57, v42
	global_store_short v[54:55], v52, off offset:32
	v_pk_mul_f32 v[52:53], v[50:51], v[50:51]
	v_pk_mul_f32 v[56:57], v[56:57], v[72:73] op_sel_hi:[1,0]
	v_add_f32_e32 v34, v52, v53
	v_pk_mul_f32 v[58:59], v[56:57], v[56:57]
	v_add_u32_e32 v52, 0x90, v114
	v_add_f32_e32 v34, v59, v34
	v_add_f32_e32 v34, v58, v34
	v_ashrrev_i32_e32 v53, 31, v52
	v_lshlrev_b64 v[52:53], 10, v[52:53]
	v_add_f32_dpp v34, v34, v34 quad_perm:[1,0,3,2] row_mask:0xf bank_mask:0xf bound_ctrl:1
	v_lshl_add_u64 v[52:53], v[126:127], 0, v[52:53]
	v_mov_b32_e32 v42, v47
	v_add_f32_dpp v34, v34, v34 quad_perm:[2,3,0,1] row_mask:0xf bank_mask:0xf bound_ctrl:1
	s_nop 1
	v_add_f32_dpp v34, v34, v34 row_half_mirror row_mask:0xf bank_mask:0xf bound_ctrl:1
	s_nop 1
	v_add_f32_dpp v34, v34, v34 row_mirror row_mask:0xf bank_mask:0xf bound_ctrl:1
	v_fmamk_f32 v34, v34, 0x3c800000, v145
	v_mul_f32_e32 v38, 0x4b800000, v34
	v_cmp_gt_f32_e32 vcc, s52, v34
	s_nop 1
	v_cndmask_b32_e32 v34, v34, v38, vcc
	v_rsq_f32_e32 v34, v34
	v_mul_f32_e32 v38, v142, v60
	v_cvt_pk_bf16_f32 v38, v38, v38
	global_store_short v[54:55], v38, off offset:96
	v_mul_f32_e32 v38, 0x45800000, v34
	v_cndmask_b32_e32 v34, v34, v38, vcc
	v_mul_f32_e32 v38, v50, v34
	v_mul_f32_e32 v38, v151, v38
	v_cvt_pk_bf16_f32 v38, v38, v38
	global_store_short v[52:53], v38, off
	v_mul_f32_e32 v38, v51, v34
	v_mul_f32_e32 v38, v150, v38
	v_cvt_pk_bf16_f32 v38, v38, v38
	global_store_short v[52:53], v38, off offset:32
	v_mul_f32_e32 v38, v57, v34
	v_mul_f32_e32 v38, v143, v38
	v_cvt_pk_bf16_f32 v38, v38, v38
	global_store_short v[52:53], v38, off offset:64
	v_mul_f32_e32 v46, v56, v34
	v_mov_b32_e32 v34, v39
	v_mov_b32_e32 v38, v73
	v_pk_mul_f32 v[34:35], v[34:35], v[38:39] op_sel_hi:[1,0]
	v_pk_mul_f32 v[38:39], v[42:43], v[38:39] op_sel_hi:[1,0]
	v_pk_mul_f32 v[50:51], v[34:35], v[34:35]
	v_pk_mul_f32 v[42:43], v[38:39], v[38:39]
	v_add_f32_e32 v47, v50, v51
	v_add_f32_e32 v43, v43, v47
	v_add_f32_e32 v42, v42, v43
	v_mov_b32_e32 v47, v44
	v_mov_b32_e32 v44, v49
	v_add_f32_dpp v42, v42, v42 quad_perm:[1,0,3,2] row_mask:0xf bank_mask:0xf bound_ctrl:1
	v_mov_b32_e32 v49, v26
	v_mov_b32_e32 v26, v31
	v_add_f32_dpp v42, v42, v42 quad_perm:[2,3,0,1] row_mask:0xf bank_mask:0xf bound_ctrl:1
	s_nop 1
	v_add_f32_dpp v42, v42, v42 row_half_mirror row_mask:0xf bank_mask:0xf bound_ctrl:1
	s_nop 1
	v_add_f32_dpp v42, v42, v42 row_mirror row_mask:0xf bank_mask:0xf bound_ctrl:1
	v_fmamk_f32 v42, v42, 0x3c800000, v145
	v_mul_f32_e32 v43, 0x4b800000, v42
	v_cmp_gt_f32_e32 vcc, s52, v42
	s_nop 1
	v_cndmask_b32_e32 v42, v42, v43, vcc
	v_rsq_f32_e32 v42, v42
	v_mul_f32_e32 v43, v142, v46
	v_cvt_pk_bf16_f32 v43, v43, v43
	global_store_short v[52:53], v43, off offset:96
	v_mul_f32_e32 v43, 0x45800000, v42
	v_cndmask_b32_e32 v46, v42, v43, vcc
	v_add_u32_e32 v42, 0x91, v114
	v_ashrrev_i32_e32 v43, 31, v42
	v_mul_f32_e32 v34, v34, v46
	v_lshlrev_b64 v[42:43], 10, v[42:43]
	v_mul_f32_e32 v34, v151, v34
	v_lshl_add_u64 v[42:43], v[126:127], 0, v[42:43]
	v_cvt_pk_bf16_f32 v34, v34, v34
	global_store_short v[42:43], v34, off
	v_mul_f32_e32 v34, v35, v46
	v_mul_f32_e32 v34, v150, v34
	v_cvt_pk_bf16_f32 v34, v34, v34
	global_store_short v[42:43], v34, off offset:32
	v_mul_f32_e32 v34, v39, v46
	v_mul_f32_e32 v34, v143, v34
	v_cvt_pk_bf16_f32 v34, v34, v34
	global_store_short v[42:43], v34, off offset:64
	v_mov_b32_e32 v34, v40
	v_mov_b32_e32 v35, v36
	v_mul_f32_e32 v52, v38, v46
	s_waitcnt lgkmcnt(0)
; __device__ __forceinline__ unsigned f2bf(float f) { return pk2(f, f) & 0xffffu; }
; __device__ __forceinline__ void phase_inproj() {
;     ...
;       for (int ai = 0; ai < 2; ++ai)
; #pragma unroll
;         for (int m = 0; m < 4; ++m)
; #pragma unroll
;           for (int j = 0; j < 4; ++j) {
;             const int rowl = ai * 128 + wr * 64 + m * 16 + fq * 4 + j;
;             const float r = rr[rowl];
;             float v[2][2]; float ss = 0.f;
; #pragma unroll
;             for (int bj = 0; bj < 2; ++bj)
; #pragma unroll
;               for (int n = 0; n < 2; ++n) { v[bj][n] = acc[ai][bj][m][n][j] * r; ss += v[bj][n] * v[bj][n]; }
;             ss = sum16(ss);
;             const float ri = rsqrtf(ss * (1.f / 64.f) + EPS);
; #pragma unroll
;             for (int bj = 0; bj < 2; ++bj)
; #pragma unroll
;               for (int n = 0; n < 2; ++n)
;                 dst[(size_t)(brow + rowl) * AW + head * 64 + bj * 32 + n * 16 + fr] = (unsigned short)f2bf(v[bj][n] * ri * gn[bj][n]);
	v_pk_mul_f32 v[34:35], v[34:35], v[76:77] op_sel_hi:[1,0]
	v_mov_b32_e32 v46, v48
	v_pk_mul_f32 v[38:39], v[34:35], v[34:35]
	v_pk_mul_f32 v[46:47], v[46:47], v[76:77] op_sel_hi:[1,0]
	v_add_f32_e32 v36, v38, v39
	v_pk_mul_f32 v[50:51], v[46:47], v[46:47]
	v_mov_b32_e32 v48, v30
	v_add_f32_e32 v36, v51, v36
	v_add_f32_e32 v36, v50, v36
	s_nop 1
	v_add_f32_dpp v36, v36, v36 quad_perm:[1,0,3,2] row_mask:0xf bank_mask:0xf bound_ctrl:1
	s_nop 1
	v_add_f32_dpp v36, v36, v36 quad_perm:[2,3,0,1] row_mask:0xf bank_mask:0xf bound_ctrl:1
	s_nop 1
	v_add_f32_dpp v36, v36, v36 row_half_mirror row_mask:0xf bank_mask:0xf bound_ctrl:1
	s_nop 1
	v_add_f32_dpp v36, v36, v36 row_mirror row_mask:0xf bank_mask:0xf bound_ctrl:1
	v_fmamk_f32 v36, v36, 0x3c800000, v145
	v_mul_f32_e32 v38, 0x4b800000, v36
	v_cmp_gt_f32_e32 vcc, s52, v36
	s_nop 1
	v_cndmask_b32_e32 v36, v36, v38, vcc
	v_rsq_f32_e32 v36, v36
	v_mul_f32_e32 v38, v142, v52
	v_cvt_pk_bf16_f32 v38, v38, v38
	global_store_short v[42:43], v38, off offset:96
	v_mul_f32_e32 v38, 0x45800000, v36
	v_cndmask_b32_e32 v36, v36, v38, vcc
	v_add_u32_e32 v38, 0x92, v114
	v_ashrrev_i32_e32 v39, 31, v38
	v_mul_f32_e32 v34, v34, v36
	v_lshlrev_b64 v[38:39], 10, v[38:39]
	v_mul_f32_e32 v34, v151, v34
	v_lshl_add_u64 v[38:39], v[126:127], 0, v[38:39]
	v_cvt_pk_bf16_f32 v34, v34, v34
	global_store_short v[38:39], v34, off
	v_mul_f32_e32 v34, v35, v36
	v_mul_f32_e32 v34, v150, v34
	v_cvt_pk_bf16_f32 v34, v34, v34
	global_store_short v[38:39], v34, off offset:32
	v_mul_f32_e32 v34, v47, v36
	v_mul_f32_e32 v34, v143, v34
	v_cvt_pk_bf16_f32 v34, v34, v34
	global_store_short v[38:39], v34, off offset:64
	v_mul_f32_e32 v46, v46, v36
	v_mov_b32_e32 v36, v41
	v_mov_b32_e32 v34, v77
	v_pk_mul_f32 v[36:37], v[36:37], v[34:35] op_sel_hi:[1,0]
	v_pk_mul_f32 v[42:43], v[44:45], v[34:35] op_sel_hi:[1,0]
	v_pk_mul_f32 v[40:41], v[36:37], v[36:37]
	v_pk_mul_f32 v[34:35], v[42:43], v[42:43]
	v_add_f32_e32 v40, v40, v41
	v_add_f32_e32 v35, v35, v40
	v_add_f32_e32 v34, v34, v35
	s_nop 1
	v_add_f32_dpp v34, v34, v34 quad_perm:[1,0,3,2] row_mask:0xf bank_mask:0xf bound_ctrl:1
	s_nop 1
	v_add_f32_dpp v34, v34, v34 quad_perm:[2,3,0,1] row_mask:0xf bank_mask:0xf bound_ctrl:1
	s_nop 1
	v_add_f32_dpp v34, v34, v34 row_half_mirror row_mask:0xf bank_mask:0xf bound_ctrl:1
	s_nop 1
	v_add_f32_dpp v34, v34, v34 row_mirror row_mask:0xf bank_mask:0xf bound_ctrl:1
	v_fmamk_f32 v34, v34, 0x3c800000, v145
	v_mul_f32_e32 v35, 0x4b800000, v34
	v_cmp_gt_f32_e32 vcc, s52, v34
	s_nop 1
	v_cndmask_b32_e32 v34, v34, v35, vcc
	v_rsq_f32_e32 v34, v34
	v_mul_f32_e32 v35, v142, v46
	v_cvt_pk_bf16_f32 v35, v35, v35
	global_store_short v[38:39], v35, off offset:96
	v_mul_f32_e32 v35, 0x45800000, v34
	v_cndmask_b32_e32 v38, v34, v35, vcc
	v_add_u32_e32 v34, 0x93, v114
	v_ashrrev_i32_e32 v35, 31, v34
	v_mul_f32_e32 v36, v36, v38
	v_lshlrev_b64 v[34:35], 10, v[34:35]
	v_mul_f32_e32 v36, v151, v36
	v_lshl_add_u64 v[34:35], v[126:127], 0, v[34:35]
	v_cvt_pk_bf16_f32 v36, v36, v36
	global_store_short v[34:35], v36, off
	v_mul_f32_e32 v36, v37, v38
	v_mul_f32_e32 v36, v150, v36
	v_cvt_pk_bf16_f32 v36, v36, v36
	global_store_short v[34:35], v36, off offset:32
	v_mul_f32_e32 v36, v43, v38
	v_mul_f32_e32 v36, v143, v36
	v_cvt_pk_bf16_f32 v36, v36, v36
	global_store_short v[34:35], v36, off offset:64
	ds_read2_b32 v[36:37], v148 offset0:160 offset1:161
	v_mul_f32_e32 v52, v42, v38
	v_mov_b32_e32 v42, v18
	v_mov_b32_e32 v43, v22
	ds_read2_b32 v[38:39], v148 offset0:162 offset1:163
	ds_read2_b32 v[40:41], v148 offset0:176 offset1:177
	ds_read2_b32 v[44:45], v148 offset0:178 offset1:179
	s_waitcnt lgkmcnt(3)
	v_pk_mul_f32 v[42:43], v[42:43], v[36:37] op_sel_hi:[1,0]
	v_pk_mul_f32 v[48:49], v[48:49], v[36:37] op_sel_hi:[1,0]
	v_pk_mul_f32 v[46:47], v[42:43], v[42:43]
	v_pk_mul_f32 v[50:51], v[48:49], v[48:49]
	v_add_f32_e32 v18, v46, v47
	v_add_f32_e32 v18, v51, v18
	v_add_f32_e32 v18, v50, v18
	s_nop 1
	v_add_f32_dpp v18, v18, v18 quad_perm:[1,0,3,2] row_mask:0xf bank_mask:0xf bound_ctrl:1
	s_nop 1
	v_add_f32_dpp v18, v18, v18 quad_perm:[2,3,0,1] row_mask:0xf bank_mask:0xf bound_ctrl:1
	s_nop 1
	v_add_f32_dpp v18, v18, v18 row_half_mirror row_mask:0xf bank_mask:0xf bound_ctrl:1
	s_nop 1
	v_add_f32_dpp v18, v18, v18 row_mirror row_mask:0xf bank_mask:0xf bound_ctrl:1
	v_fmamk_f32 v18, v18, 0x3c800000, v145
	v_mul_f32_e32 v22, 0x4b800000, v18
	v_cmp_gt_f32_e32 vcc, s52, v18
	s_nop 1
	v_cndmask_b32_e32 v18, v18, v22, vcc
	v_rsq_f32_e32 v18, v18
	v_mul_f32_e32 v22, v142, v52
	v_cvt_pk_bf16_f32 v22, v22, v22
	global_store_short v[34:35], v22, off offset:96
	v_mul_f32_e32 v22, 0x45800000, v18
	v_cndmask_b32_e32 v18, v18, v22, vcc
	v_add_u32_e32 v34, 0xa0, v114
	v_ashrrev_i32_e32 v35, 31, v34
	v_mul_f32_e32 v22, v42, v18
	v_lshlrev_b64 v[34:35], 10, v[34:35]
	v_mul_f32_e32 v22, v151, v22
	v_lshl_add_u64 v[34:35], v[126:127], 0, v[34:35]
	v_cvt_pk_bf16_f32 v22, v22, v22
	global_store_short v[34:35], v22, off
	v_mul_f32_e32 v22, v43, v18
	v_mul_f32_e32 v22, v150, v22
	v_cvt_pk_bf16_f32 v22, v22, v22
	global_store_short v[34:35], v22, off offset:32
	v_mul_f32_e32 v22, v49, v18
	v_mul_f32_e32 v22, v143, v22
	v_cvt_pk_bf16_f32 v22, v22, v22
	global_store_short v[34:35], v22, off offset:64
	v_mul_f32_e32 v30, v48, v18
	v_mov_b32_e32 v22, v19
	v_mov_b32_e32 v18, v37
	v_pk_mul_f32 v[22:23], v[22:23], v[18:19] op_sel_hi:[1,0]
	v_pk_mul_f32 v[18:19], v[26:27], v[18:19] op_sel_hi:[1,0]
	v_pk_mul_f32 v[36:37], v[22:23], v[22:23]
	v_pk_mul_f32 v[26:27], v[18:19], v[18:19]
	v_add_f32_e32 v31, v36, v37
	v_add_f32_e32 v27, v27, v31
	v_add_f32_e32 v26, v26, v27
	v_mov_b32_e32 v31, v28
	v_mov_b32_e32 v28, v33
	v_add_f32_dpp v26, v26, v26 quad_perm:[1,0,3,2] row_mask:0xf bank_mask:0xf bound_ctrl:1
	s_nop 1
	v_add_f32_dpp v26, v26, v26 quad_perm:[2,3,0,1] row_mask:0xf bank_mask:0xf bound_ctrl:1
	s_nop 1
	v_add_f32_dpp v26, v26, v26 row_half_mirror row_mask:0xf bank_mask:0xf bound_ctrl:1
	s_nop 1
	v_add_f32_dpp v26, v26, v26 row_mirror row_mask:0xf bank_mask:0xf bound_ctrl:1
	v_fmamk_f32 v26, v26, 0x3c800000, v145
	v_mul_f32_e32 v27, 0x4b800000, v26
	v_cmp_gt_f32_e32 vcc, s52, v26
	s_nop 1
	v_cndmask_b32_e32 v26, v26, v27, vcc
	v_rsq_f32_e32 v26, v26
	v_mul_f32_e32 v27, v142, v30
	v_cvt_pk_bf16_f32 v27, v27, v27
	global_store_short v[34:35], v27, off offset:96
	v_mul_f32_e32 v27, 0x45800000, v26
	v_cndmask_b32_e32 v30, v26, v27, vcc
	v_add_u32_e32 v26, 0xa1, v114
	v_ashrrev_i32_e32 v27, 31, v26
	v_mul_f32_e32 v22, v22, v30
	v_lshlrev_b64 v[26:27], 10, v[26:27]
	v_mul_f32_e32 v22, v151, v22
	v_mul_f32_e32 v19, v19, v30
	v_lshl_add_u64 v[26:27], v[126:127], 0, v[26:27]
	v_cvt_pk_bf16_f32 v22, v22, v22
	v_mul_f32_e32 v19, v143, v19
	global_store_short v[26:27], v22, off
	v_mul_f32_e32 v22, v23, v30
	v_cvt_pk_bf16_f32 v19, v19, v19
	v_mul_f32_e32 v22, v150, v22
	global_store_short v[26:27], v19, off offset:64
	v_mul_f32_e32 v36, v18, v30
	v_mov_b32_e32 v18, v20
	v_mov_b32_e32 v19, v24
	v_cvt_pk_bf16_f32 v22, v22, v22
	s_waitcnt lgkmcnt(2)
; __device__ __forceinline__ unsigned f2bf(float f) { return pk2(f, f) & 0xffffu; }
; __device__ __forceinline__ void phase_inproj() {
;     ...
;       for (int ai = 0; ai < 2; ++ai)
; #pragma unroll
;         for (int m = 0; m < 4; ++m)
; #pragma unroll
;           for (int j = 0; j < 4; ++j) {
;             const int rowl = ai * 128 + wr * 64 + m * 16 + fq * 4 + j;
;             const float r = rr[rowl];
;             float v[2][2]; float ss = 0.f;
; #pragma unroll
;             for (int bj = 0; bj < 2; ++bj)
; #pragma unroll
;               for (int n = 0; n < 2; ++n) { v[bj][n] = acc[ai][bj][m][n][j] * r; ss += v[bj][n] * v[bj][n]; }
;             ss = sum16(ss);
;             const float ri = rsqrtf(ss * (1.f / 64.f) + EPS);
; #pragma unroll
;             for (int bj = 0; bj < 2; ++bj)
; #pragma unroll
;               for (int n = 0; n < 2; ++n)
;                 dst[(size_t)(brow + rowl) * AW + head * 64 + bj * 32 + n * 16 + fr] = (unsigned short)f2bf(v[bj][n] * ri * gn[bj][n]);
	v_pk_mul_f32 v[18:19], v[18:19], v[38:39] op_sel_hi:[1,0]
	v_mov_b32_e32 v30, v32
	global_store_short v[26:27], v22, off offset:32
	v_pk_mul_f32 v[22:23], v[18:19], v[18:19]
	v_pk_mul_f32 v[30:31], v[30:31], v[38:39] op_sel_hi:[1,0]
	v_add_f32_e32 v20, v22, v23
	v_pk_mul_f32 v[34:35], v[30:31], v[30:31]
	v_mov_b32_e32 v24, v21
	v_add_f32_e32 v20, v35, v20
	v_add_f32_e32 v20, v34, v20
	s_nop 1
	v_add_f32_dpp v20, v20, v20 quad_perm:[1,0,3,2] row_mask:0xf bank_mask:0xf bound_ctrl:1
	s_nop 1
	v_add_f32_dpp v20, v20, v20 quad_perm:[2,3,0,1] row_mask:0xf bank_mask:0xf bound_ctrl:1
	s_nop 1
	v_add_f32_dpp v20, v20, v20 row_half_mirror row_mask:0xf bank_mask:0xf bound_ctrl:1
	s_nop 1
	v_add_f32_dpp v20, v20, v20 row_mirror row_mask:0xf bank_mask:0xf bound_ctrl:1
	v_fmamk_f32 v20, v20, 0x3c800000, v145
	v_mul_f32_e32 v22, 0x4b800000, v20
	v_cmp_gt_f32_e32 vcc, s52, v20
	s_nop 1
	v_cndmask_b32_e32 v20, v20, v22, vcc
	v_rsq_f32_e32 v20, v20
	v_mul_f32_e32 v22, v142, v36
	v_cvt_pk_bf16_f32 v22, v22, v22
	global_store_short v[26:27], v22, off offset:96
	v_mul_f32_e32 v22, 0x45800000, v20
	v_cndmask_b32_e32 v20, v20, v22, vcc
	v_add_u32_e32 v22, 0xa2, v114
	v_ashrrev_i32_e32 v23, 31, v22
	v_mul_f32_e32 v18, v18, v20
	v_lshlrev_b64 v[22:23], 10, v[22:23]
	v_mul_f32_e32 v18, v151, v18
	v_lshl_add_u64 v[22:23], v[126:127], 0, v[22:23]
	v_cvt_pk_bf16_f32 v18, v18, v18
	global_store_short v[22:23], v18, off
	v_mul_f32_e32 v18, v19, v20
	v_mul_f32_e32 v18, v150, v18
	v_cvt_pk_bf16_f32 v18, v18, v18
	global_store_short v[22:23], v18, off offset:32
	v_mul_f32_e32 v18, v31, v20
	v_mul_f32_e32 v18, v143, v18
	v_cvt_pk_bf16_f32 v18, v18, v18
	global_store_short v[22:23], v18, off offset:64
	v_mov_b32_e32 v18, v39
	v_mul_f32_e32 v30, v30, v20
	v_pk_mul_f32 v[20:21], v[24:25], v[18:19] op_sel_hi:[1,0]
	v_pk_mul_f32 v[18:19], v[28:29], v[18:19] op_sel_hi:[1,0]
	v_pk_mul_f32 v[24:25], v[20:21], v[20:21]
	v_pk_mul_f32 v[26:27], v[18:19], v[18:19]
	v_add_f32_e32 v24, v24, v25
	v_add_f32_e32 v24, v27, v24
	v_add_f32_e32 v24, v26, v24
	s_nop 1
	v_add_f32_dpp v24, v24, v24 quad_perm:[1,0,3,2] row_mask:0xf bank_mask:0xf bound_ctrl:1
	s_nop 1
	v_add_f32_dpp v24, v24, v24 quad_perm:[2,3,0,1] row_mask:0xf bank_mask:0xf bound_ctrl:1
	s_nop 1
	v_add_f32_dpp v24, v24, v24 row_half_mirror row_mask:0xf bank_mask:0xf bound_ctrl:1
	s_nop 1
	v_add_f32_dpp v24, v24, v24 row_mirror row_mask:0xf bank_mask:0xf bound_ctrl:1
	v_fmamk_f32 v24, v24, 0x3c800000, v145
	v_mul_f32_e32 v25, 0x4b800000, v24
	v_cmp_gt_f32_e32 vcc, s52, v24
	s_nop 1
	v_cndmask_b32_e32 v24, v24, v25, vcc
	v_rsq_f32_e32 v24, v24
	v_mul_f32_e32 v25, v142, v30
	v_cvt_pk_bf16_f32 v25, v25, v25
	global_store_short v[22:23], v25, off offset:96
	v_mul_f32_e32 v22, 0x45800000, v24
	v_cndmask_b32_e32 v24, v24, v22, vcc
	v_add_u32_e32 v22, 0xa3, v114
	v_ashrrev_i32_e32 v23, 31, v22
	v_mul_f32_e32 v20, v20, v24
	v_lshlrev_b64 v[22:23], 10, v[22:23]
	v_mul_f32_e32 v20, v151, v20
	v_mul_f32_e32 v19, v19, v24
	v_lshl_add_u64 v[22:23], v[126:127], 0, v[22:23]
	v_cvt_pk_bf16_f32 v20, v20, v20
	v_mul_f32_e32 v19, v143, v19
	global_store_short v[22:23], v20, off
	v_mul_f32_e32 v20, v21, v24
	v_cvt_pk_bf16_f32 v19, v19, v19
	v_mul_f32_e32 v20, v150, v20
	global_store_short v[22:23], v19, off offset:64
	v_mul_f32_e32 v28, v18, v24
	v_mov_b32_e32 v18, v6
	v_mov_b32_e32 v19, v2
	v_cvt_pk_bf16_f32 v20, v20, v20
	s_waitcnt lgkmcnt(1)
; __device__ __forceinline__ unsigned f2bf(float f) { return pk2(f, f) & 0xffffu; }
; __device__ __forceinline__ void phase_inproj() {
;     ...
;       for (int ai = 0; ai < 2; ++ai)
; #pragma unroll
;         for (int m = 0; m < 4; ++m)
; #pragma unroll
;           for (int j = 0; j < 4; ++j) {
;             const int rowl = ai * 128 + wr * 64 + m * 16 + fq * 4 + j;
;             const float r = rr[rowl];
;             float v[2][2]; float ss = 0.f;
; #pragma unroll
;             for (int bj = 0; bj < 2; ++bj)
; #pragma unroll
;               for (int n = 0; n < 2; ++n) { v[bj][n] = acc[ai][bj][m][n][j] * r; ss += v[bj][n] * v[bj][n]; }
;             ss = sum16(ss);
;             const float ri = rsqrtf(ss * (1.f / 64.f) + EPS);
; #pragma unroll
;             for (int bj = 0; bj < 2; ++bj)
; #pragma unroll
;               for (int n = 0; n < 2; ++n)
;                 dst[(size_t)(brow + rowl) * AW + head * 64 + bj * 32 + n * 16 + fr] = (unsigned short)f2bf(v[bj][n] * ri * gn[bj][n]);
	v_pk_mul_f32 v[18:19], v[18:19], v[40:41] op_sel_hi:[1,0]
	v_mov_b32_e32 v24, v14
	v_mov_b32_e32 v25, v10
	global_store_short v[22:23], v20, off offset:32
	v_pk_mul_f32 v[20:21], v[18:19], v[18:19]
	v_pk_mul_f32 v[24:25], v[24:25], v[40:41] op_sel_hi:[1,0]
	v_add_f32_e32 v2, v20, v21
	v_pk_mul_f32 v[26:27], v[24:25], v[24:25]
	v_add_u32_e32 v20, 0xb0, v114
	v_add_f32_e32 v2, v27, v2
	v_add_f32_e32 v2, v26, v2
	v_ashrrev_i32_e32 v21, 31, v20
	v_lshlrev_b64 v[20:21], 10, v[20:21]
	v_add_f32_dpp v2, v2, v2 quad_perm:[1,0,3,2] row_mask:0xf bank_mask:0xf bound_ctrl:1
	v_lshl_add_u64 v[20:21], v[126:127], 0, v[20:21]
	v_mov_b32_e32 v10, v15
	v_add_f32_dpp v2, v2, v2 quad_perm:[2,3,0,1] row_mask:0xf bank_mask:0xf bound_ctrl:1
	s_nop 1
	v_add_f32_dpp v2, v2, v2 row_half_mirror row_mask:0xf bank_mask:0xf bound_ctrl:1
	s_nop 1
	v_add_f32_dpp v2, v2, v2 row_mirror row_mask:0xf bank_mask:0xf bound_ctrl:1
	v_fmamk_f32 v2, v2, 0x3c800000, v145
	v_mul_f32_e32 v6, 0x4b800000, v2
	v_cmp_gt_f32_e32 vcc, s52, v2
	s_nop 1
	v_cndmask_b32_e32 v2, v2, v6, vcc
	v_rsq_f32_e32 v2, v2
	v_mul_f32_e32 v6, v142, v28
	v_cvt_pk_bf16_f32 v6, v6, v6
	global_store_short v[22:23], v6, off offset:96
	v_mul_f32_e32 v6, 0x45800000, v2
	v_cndmask_b32_e32 v2, v2, v6, vcc
	v_mul_f32_e32 v6, v18, v2
	v_mul_f32_e32 v6, v151, v6
	v_cvt_pk_bf16_f32 v6, v6, v6
	global_store_short v[20:21], v6, off
	v_mul_f32_e32 v6, v19, v2
	v_mul_f32_e32 v6, v150, v6
	v_cvt_pk_bf16_f32 v6, v6, v6
	global_store_short v[20:21], v6, off offset:32
	v_mul_f32_e32 v6, v25, v2
	v_mul_f32_e32 v6, v143, v6
	v_cvt_pk_bf16_f32 v6, v6, v6
	global_store_short v[20:21], v6, off offset:64
	v_mul_f32_e32 v14, v24, v2
	v_mov_b32_e32 v2, v7
	v_mov_b32_e32 v6, v41
	v_pk_mul_f32 v[2:3], v[2:3], v[6:7] op_sel_hi:[1,0]
	v_pk_mul_f32 v[6:7], v[10:11], v[6:7] op_sel_hi:[1,0]
	v_pk_mul_f32 v[18:19], v[2:3], v[2:3]
	v_pk_mul_f32 v[10:11], v[6:7], v[6:7]
	v_add_f32_e32 v15, v18, v19
	v_add_f32_e32 v11, v11, v15
	v_add_f32_e32 v10, v10, v11
	v_mov_b32_e32 v15, v12
	v_mov_b32_e32 v12, v17
	v_add_f32_dpp v10, v10, v10 quad_perm:[1,0,3,2] row_mask:0xf bank_mask:0xf bound_ctrl:1
	s_nop 1
	v_add_f32_dpp v10, v10, v10 quad_perm:[2,3,0,1] row_mask:0xf bank_mask:0xf bound_ctrl:1
	s_nop 1
	v_add_f32_dpp v10, v10, v10 row_half_mirror row_mask:0xf bank_mask:0xf bound_ctrl:1
	s_nop 1
	v_add_f32_dpp v10, v10, v10 row_mirror row_mask:0xf bank_mask:0xf bound_ctrl:1
	v_fmamk_f32 v10, v10, 0x3c800000, v145
	v_mul_f32_e32 v11, 0x4b800000, v10
	v_cmp_gt_f32_e32 vcc, s52, v10
	s_nop 1
	v_cndmask_b32_e32 v10, v10, v11, vcc
	v_rsq_f32_e32 v10, v10
	v_mul_f32_e32 v11, v142, v14
	v_cvt_pk_bf16_f32 v11, v11, v11
	global_store_short v[20:21], v11, off offset:96
	v_mul_f32_e32 v11, 0x45800000, v10
	v_cndmask_b32_e32 v14, v10, v11, vcc
	v_add_u32_e32 v10, 0xb1, v114
	v_ashrrev_i32_e32 v11, 31, v10
	v_mul_f32_e32 v2, v2, v14
	v_lshlrev_b64 v[10:11], 10, v[10:11]
	v_mul_f32_e32 v2, v151, v2
	v_lshl_add_u64 v[10:11], v[126:127], 0, v[10:11]
	v_cvt_pk_bf16_f32 v2, v2, v2
	global_store_short v[10:11], v2, off
	v_mul_f32_e32 v2, v3, v14
	v_mul_f32_e32 v2, v150, v2
	v_cvt_pk_bf16_f32 v2, v2, v2
	global_store_short v[10:11], v2, off offset:32
	v_mul_f32_e32 v2, v7, v14
	v_mul_f32_e32 v2, v143, v2
	v_cvt_pk_bf16_f32 v2, v2, v2
	global_store_short v[10:11], v2, off offset:64
	v_mov_b32_e32 v2, v8
	v_mov_b32_e32 v3, v4
	v_mul_f32_e32 v20, v6, v14
	s_waitcnt lgkmcnt(0)
	v_pk_mul_f32 v[2:3], v[2:3], v[44:45] op_sel_hi:[1,0]
	v_mov_b32_e32 v14, v16
	v_pk_mul_f32 v[6:7], v[2:3], v[2:3]
	v_pk_mul_f32 v[14:15], v[14:15], v[44:45] op_sel_hi:[1,0]
	v_add_f32_e32 v4, v6, v7
	v_pk_mul_f32 v[18:19], v[14:15], v[14:15]
	s_nop 0
	v_add_f32_e32 v4, v19, v4
	v_add_f32_e32 v4, v18, v4
	s_nop 1
	v_add_f32_dpp v4, v4, v4 quad_perm:[1,0,3,2] row_mask:0xf bank_mask:0xf bound_ctrl:1
	s_nop 1
	v_add_f32_dpp v4, v4, v4 quad_perm:[2,3,0,1] row_mask:0xf bank_mask:0xf bound_ctrl:1
	s_nop 1
	v_add_f32_dpp v4, v4, v4 row_half_mirror row_mask:0xf bank_mask:0xf bound_ctrl:1
	s_nop 1
	v_add_f32_dpp v4, v4, v4 row_mirror row_mask:0xf bank_mask:0xf bound_ctrl:1
	v_fmamk_f32 v4, v4, 0x3c800000, v145
	v_mul_f32_e32 v6, 0x4b800000, v4
	v_cmp_gt_f32_e32 vcc, s52, v4
	s_nop 1
	v_cndmask_b32_e32 v4, v4, v6, vcc
	v_rsq_f32_e32 v4, v4
	v_mul_f32_e32 v6, v142, v20
	v_cvt_pk_bf16_f32 v6, v6, v6
	global_store_short v[10:11], v6, off offset:96
	v_mul_f32_e32 v6, 0x45800000, v4
	v_cndmask_b32_e32 v4, v4, v6, vcc
	v_add_u32_e32 v6, 0xb2, v114
	v_ashrrev_i32_e32 v7, 31, v6
	v_mul_f32_e32 v2, v2, v4
	v_lshlrev_b64 v[6:7], 10, v[6:7]
	v_mul_f32_e32 v2, v151, v2
	v_lshl_add_u64 v[6:7], v[126:127], 0, v[6:7]
	v_cvt_pk_bf16_f32 v2, v2, v2
	global_store_short v[6:7], v2, off
	v_mul_f32_e32 v2, v3, v4
	v_mul_f32_e32 v2, v150, v2
	v_cvt_pk_bf16_f32 v2, v2, v2
	global_store_short v[6:7], v2, off offset:32
	v_mul_f32_e32 v2, v15, v4
	v_mul_f32_e32 v2, v143, v2
	v_cvt_pk_bf16_f32 v2, v2, v2
	global_store_short v[6:7], v2, off offset:64
	v_mul_f32_e32 v14, v14, v4
	v_mov_b32_e32 v4, v9
	v_mov_b32_e32 v2, v45
	v_pk_mul_f32 v[4:5], v[4:5], v[2:3] op_sel_hi:[1,0]
	v_pk_mul_f32 v[2:3], v[12:13], v[2:3] op_sel_hi:[1,0]
	v_pk_mul_f32 v[8:9], v[4:5], v[4:5]
	v_pk_mul_f32 v[10:11], v[2:3], v[2:3]
	v_add_f32_e32 v8, v8, v9
	v_add_f32_e32 v8, v11, v8
	v_add_f32_e32 v8, v10, v8
	s_nop 1
	v_add_f32_dpp v8, v8, v8 quad_perm:[1,0,3,2] row_mask:0xf bank_mask:0xf bound_ctrl:1
	s_nop 1
	v_add_f32_dpp v8, v8, v8 quad_perm:[2,3,0,1] row_mask:0xf bank_mask:0xf bound_ctrl:1
	s_nop 1
	v_add_f32_dpp v8, v8, v8 row_half_mirror row_mask:0xf bank_mask:0xf bound_ctrl:1
	s_nop 1
	v_add_f32_dpp v8, v8, v8 row_mirror row_mask:0xf bank_mask:0xf bound_ctrl:1
	v_fmamk_f32 v8, v8, 0x3c800000, v145
	v_mul_f32_e32 v9, 0x4b800000, v8
	v_cmp_gt_f32_e32 vcc, s52, v8
	s_nop 1
	v_cndmask_b32_e32 v8, v8, v9, vcc
	v_rsq_f32_e32 v8, v8
	v_mul_f32_e32 v9, v142, v14
	v_cvt_pk_bf16_f32 v9, v9, v9
	global_store_short v[6:7], v9, off offset:96
	v_mul_f32_e32 v6, 0x45800000, v8
	v_cndmask_b32_e32 v8, v8, v6, vcc
	v_add_u32_e32 v6, 0xb3, v114
	v_ashrrev_i32_e32 v7, 31, v6
	v_mul_f32_e32 v4, v4, v8
	v_lshlrev_b64 v[6:7], 10, v[6:7]
	v_mul_f32_e32 v4, v151, v4
	v_lshl_add_u64 v[6:7], v[126:127], 0, v[6:7]
	v_cvt_pk_bf16_f32 v4, v4, v4
	global_store_short v[6:7], v4, off
	v_mul_f32_e32 v4, v5, v8
	v_mul_f32_e32 v3, v3, v8
	v_mul_f32_e32 v2, v2, v8
	v_mul_f32_e32 v4, v150, v4
	v_mul_f32_e32 v3, v143, v3
	v_mul_f32_e32 v2, v142, v2
	v_cvt_pk_bf16_f32 v4, v4, v4
	global_store_short v[6:7], v4, off offset:32
	v_cvt_pk_bf16_f32 v3, v3, v3
	global_store_short v[6:7], v3, off offset:64
	v_cvt_pk_bf16_f32 v2, v2, v2
	global_store_short v[6:7], v2, off offset:96
	s_branch .LBB0_342

; __device__ __forceinline__ void phase_branch() {
;     ...
;           unsigned short gv[4][2][2], tv[4][2][2];
; #pragma unroll
;           for (int j = 0; j < 4; ++j)
; #pragma unroll
;             for (int bj = 0; bj < 2; ++bj)
; #pragma unroll
;               for (int n = 0; n < 2; ++n) {
;                 const size_t idx = (size_t)(brow + ai * 128 + wr * 64 + m * 16 + fq * 4 + j) * DM + bcol + bj * 128 + wc * 32 + n * 16 + fr;
;                 gv[j][bj][n] = sg[idx]; tv[j][bj][n] = tmpb[idx];
;               }
.LBB0_705:
	v_mov_b32_e32 v130, v170
	v_mov_b32_e32 v135, s15
	v_and_b32_e32 v137, 15, v130
	v_ashrrev_i32_e32 v132, 2, v130
	v_lshrrev_b32_e32 v133, 2, v130
	v_lshrrev_b32_e32 v130, 1, v130
	v_and_b32_e32 v132, 0xffffffc0, v132
	v_and_b32_e32 v130, 0x60, v130
	v_add_u32_e32 v132, s16, v132
	v_or3_b32 v134, v130, v137, s14
	s_add_u32 s14, s35, s18
	v_and_or_b32 v136, v133, 12, v132
	s_addc_u32 s15, s36, s19
	v_lshlrev_b32_e32 v130, 1, v130
	v_lshl_add_u64 v[132:133], s[14:15], 0, v[130:131]
	v_lshlrev_b32_e32 v130, 1, v137
	v_ashrrev_i32_e32 v137, 31, v136
	v_lshlrev_b64 v[138:139], 10, v[136:137]
	v_lshl_add_u64 v[138:139], v[138:139], 0, v[134:135]
	v_lshlrev_b64 v[138:139], 1, v[138:139]
	v_lshl_add_u64 v[140:141], s[8:9], 0, v[138:139]
	v_lshl_add_u64 v[132:133], v[132:133], 0, v[130:131]
	v_lshl_add_u64 v[142:143], s[4:5], 0, v[138:139]
	global_load_ushort v130, v[140:141], off
	global_load_ushort v162, v[142:143], off
	v_or_b32_e32 v144, 32, v138
	v_mov_b32_e32 v145, v139
	v_lshl_add_u64 v[146:147], s[8:9], 0, v[144:145]
	v_lshl_add_u64 v[144:145], s[4:5], 0, v[144:145]
	v_or_b32_e32 v148, 0x100, v138
	v_mov_b32_e32 v149, v139
	v_or_b32_e32 v154, 1, v136
	global_load_ushort v163, v[146:147], off
	global_load_ushort v164, v[144:145], off
	v_lshl_add_u64 v[150:151], s[8:9], 0, v[148:149]
	v_ashrrev_i32_e32 v155, 31, v154
	v_lshl_add_u64 v[148:149], s[4:5], 0, v[148:149]
	v_or_b32_e32 v138, 0x120, v138
	v_lshlrev_b64 v[156:157], 10, v[154:155]
	global_load_ushort v165, v[150:151], off
	global_load_ushort v166, v[148:149], off
	v_lshl_add_u64 v[152:153], s[8:9], 0, v[138:139]
	v_lshl_add_u64 v[156:157], v[156:157], 0, v[134:135]
	v_lshl_add_u64 v[138:139], s[4:5], 0, v[138:139]
	v_lshlrev_b64 v[156:157], 1, v[156:157]
	global_load_ushort v167, v[152:153], off
	global_load_ushort v168, v[138:139], off
	v_lshl_add_u64 v[158:159], s[8:9], 0, v[156:157]
	v_lshl_add_u64 v[140:141], s[4:5], 0, v[156:157]
	v_or_b32_e32 v142, 32, v156
	v_mov_b32_e32 v143, v157
	global_load_ushort v169, v[158:159], off
	global_load_ushort v174, v[140:141], off
	v_lshl_add_u64 v[160:161], s[8:9], 0, v[142:143]
	v_lshl_add_u64 v[142:143], s[4:5], 0, v[142:143]
	v_or_b32_e32 v144, 0x100, v156
	v_mov_b32_e32 v145, v157
	v_or_b32_e32 v150, 2, v136
	global_load_ushort v160, v[160:161], off
	s_nop 0
	global_load_ushort v161, v[142:143], off
	v_lshl_add_u64 v[146:147], s[8:9], 0, v[144:145]
	v_ashrrev_i32_e32 v151, 31, v150
	v_lshl_add_u64 v[144:145], s[4:5], 0, v[144:145]
	v_or_b32_e32 v156, 0x120, v156
	v_lshlrev_b64 v[152:153], 10, v[150:151]
	global_load_ushort v175, v[146:147], off
	global_load_ushort v176, v[144:145], off
	v_lshl_add_u64 v[148:149], s[8:9], 0, v[156:157]
	v_lshl_add_u64 v[152:153], v[152:153], 0, v[134:135]
	v_lshl_add_u64 v[138:139], s[4:5], 0, v[156:157]
	v_lshlrev_b64 v[140:141], 1, v[152:153]
	global_load_ushort v177, v[148:149], off
	global_load_ushort v178, v[138:139], off
	v_lshl_add_u64 v[152:153], s[8:9], 0, v[140:141]
	v_lshl_add_u64 v[156:157], s[4:5], 0, v[140:141]
	v_or_b32_e32 v142, 32, v140
	v_mov_b32_e32 v143, v141
	global_load_ushort v179, v[152:153], off
	global_load_ushort v180, v[156:157], off
	v_lshl_add_u64 v[158:159], s[8:9], 0, v[142:143]
	v_lshl_add_u64 v[142:143], s[4:5], 0, v[142:143]
	v_or_b32_e32 v144, 0x100, v140
	v_mov_b32_e32 v145, v141
	v_or_b32_e32 v148, 3, v136
	global_load_ushort v158, v[158:159], off
	s_nop 0
	global_load_ushort v159, v[142:143], off
	v_lshl_add_u64 v[138:139], s[8:9], 0, v[144:145]
	v_ashrrev_i32_e32 v149, 31, v148
	v_lshl_add_u64 v[144:145], s[4:5], 0, v[144:145]
	v_or_b32_e32 v140, 0x120, v140
	v_lshlrev_b64 v[152:153], 10, v[148:149]
	global_load_ushort v181, v[138:139], off
	global_load_ushort v182, v[144:145], off
	v_lshl_add_u64 v[146:147], s[8:9], 0, v[140:141]
	v_lshl_add_u64 v[142:143], v[152:153], 0, v[134:135]
	v_lshl_add_u64 v[140:141], s[4:5], 0, v[140:141]
	v_lshlrev_b64 v[142:143], 1, v[142:143]
	global_load_ushort v183, v[146:147], off
	global_load_ushort v184, v[140:141], off
	v_lshl_add_u64 v[152:153], s[8:9], 0, v[142:143]
	v_lshl_add_u64 v[138:139], s[4:5], 0, v[142:143]
	v_or_b32_e32 v144, 32, v142
	v_mov_b32_e32 v145, v143
	global_load_ushort v152, v[152:153], off
	s_nop 0
	global_load_ushort v153, v[138:139], off
	v_lshl_add_u64 v[140:141], s[8:9], 0, v[144:145]
	v_lshl_add_u64 v[144:145], s[4:5], 0, v[144:145]
	v_or_b32_e32 v146, 0x100, v142
	v_mov_b32_e32 v147, v143
	global_load_ushort v185, v[140:141], off
	s_nop 0
	global_load_ushort v144, v[144:145], off
	v_lshl_add_u64 v[156:157], s[8:9], 0, v[146:147]
	v_or_b32_e32 v142, 0x120, v142
	v_lshl_add_u64 v[138:139], s[4:5], 0, v[146:147]
	v_lshl_add_u64 v[146:147], s[8:9], 0, v[142:143]
	v_lshl_add_u64 v[140:141], s[4:5], 0, v[142:143]
	v_lshlrev_b64 v[142:143], 11, v[136:137]
	global_load_ushort v137, v[156:157], off
	global_load_ushort v145, v[138:139], off
	s_waitcnt vmcnt(0)
; __device__ __forceinline__ unsigned f2bf(float f) { return pk2(f, f) & 0xffffu; }
; __device__ __forceinline__ void phase_branch() {
;     ...
;           unsigned short gv[4][2][2], tv[4][2][2];
; #pragma unroll
;           for (int j = 0; j < 4; ++j)
; #pragma unroll
;             for (int bj = 0; bj < 2; ++bj)
; #pragma unroll
;               for (int n = 0; n < 2; ++n) {
;                 const size_t idx = (size_t)(brow + ai * 128 + wr * 64 + m * 16 + fq * 4 + j) * DM + bcol + bj * 128 + wc * 32 + n * 16 + fr;
;                 gv[j][bj][n] = sg[idx]; tv[j][bj][n] = tmpb[idx];
;               }
; #pragma unroll
;           for (int j = 0; j < 4; ++j) {
;             const int row = brow + ai * 128 + wr * 64 + m * 16 + fq * 4 + j;
; #pragma unroll
;             for (int bj = 0; bj < 2; ++bj)
; #pragma unroll
;               for (int n = 0; n < 2; ++n) {
;                 const size_t idx = (size_t)row * DM + bcol + bj * 128 + wc * 32 + n * 16 + fr;
;                 merged[idx] = (unsigned short)f2bf(bf2f(gv[j][bj][n]) * acc[ai][bj][m][n][j] + bf2f(tv[j][bj][n]));
;               }
	v_lshlrev_b32_e32 v130, 16, v130
	v_lshlrev_b32_e32 v138, 16, v162
	v_fmac_f32_e32 v138, v118, v130
	global_load_ushort v118, v[146:147], off
	global_load_ushort v130, v[140:141], off
	v_lshl_add_u64 v[142:143], v[132:133], 0, v[142:143]
	v_cvt_pk_bf16_f32 v138, v138, v138
	global_store_short v[142:143], v138, off
	v_lshlrev_b32_e32 v138, 16, v163
	v_lshlrev_b32_e32 v139, 16, v164
	v_fmac_f32_e32 v139, v114, v138
	v_cvt_pk_bf16_f32 v114, v139, v139
	global_store_short v[142:143], v114, off offset:32
	v_lshlrev_b32_e32 v114, 16, v165
	v_lshlrev_b32_e32 v138, 16, v166
	v_fmac_f32_e32 v138, v126, v114
	v_cvt_pk_bf16_f32 v114, v138, v138
	global_store_short v[142:143], v114, off offset:256
	v_lshlrev_b32_e32 v114, 16, v167
	v_lshlrev_b32_e32 v126, 16, v168
	v_fmac_f32_e32 v126, v122, v114
	v_cvt_pk_bf16_f32 v114, v126, v126
	global_store_short v[142:143], v114, off offset:288
	v_lshlrev_b64 v[138:139], 11, v[154:155]
	v_lshlrev_b32_e32 v114, 16, v169
	v_lshlrev_b32_e32 v122, 16, v174
	v_lshl_add_u64 v[138:139], v[132:133], 0, v[138:139]
	v_fmac_f32_e32 v122, v119, v114
	v_cvt_pk_bf16_f32 v114, v122, v122
	global_store_short v[138:139], v114, off
	v_lshlrev_b32_e32 v114, 16, v160
	v_lshlrev_b32_e32 v119, 16, v161
	v_fmac_f32_e32 v119, v115, v114
	v_cvt_pk_bf16_f32 v114, v119, v119
	global_store_short v[138:139], v114, off offset:32
	v_lshlrev_b32_e32 v114, 16, v175
	v_lshlrev_b32_e32 v115, 16, v176
	v_fmac_f32_e32 v115, v127, v114
	v_cvt_pk_bf16_f32 v114, v115, v115
	global_store_short v[138:139], v114, off offset:256
	v_lshlrev_b32_e32 v114, 16, v177
	v_lshlrev_b32_e32 v115, 16, v178
	v_fmac_f32_e32 v115, v123, v114
	v_cvt_pk_bf16_f32 v114, v115, v115
	global_store_short v[138:139], v114, off offset:288
	v_lshlrev_b64 v[114:115], 11, v[150:151]
	v_lshlrev_b32_e32 v119, 16, v179
	v_lshlrev_b32_e32 v122, 16, v180
	v_lshl_add_u64 v[114:115], v[132:133], 0, v[114:115]
	v_fmac_f32_e32 v122, v120, v119
	v_cvt_pk_bf16_f32 v119, v122, v122
	global_store_short v[114:115], v119, off
	v_lshlrev_b32_e32 v119, 16, v158
	v_lshlrev_b32_e32 v120, 16, v159
	v_fmac_f32_e32 v120, v116, v119
	v_cvt_pk_bf16_f32 v116, v120, v120
	global_store_short v[114:115], v116, off offset:32
	v_lshlrev_b32_e32 v116, 16, v181
	v_lshlrev_b32_e32 v119, 16, v182
	v_fmac_f32_e32 v119, v128, v116
	v_cvt_pk_bf16_f32 v116, v119, v119
	global_store_short v[114:115], v116, off offset:256
	v_lshlrev_b32_e32 v116, 16, v183
	v_lshlrev_b32_e32 v119, 16, v184
	v_fmac_f32_e32 v119, v124, v116
	v_cvt_pk_bf16_f32 v116, v119, v119
	global_store_short v[114:115], v116, off offset:288
	v_lshlrev_b64 v[114:115], 11, v[148:149]
	v_lshlrev_b32_e32 v116, 16, v152
	v_lshlrev_b32_e32 v119, 16, v153
	v_lshl_add_u64 v[114:115], v[132:133], 0, v[114:115]
	v_fmac_f32_e32 v119, v121, v116
	v_cvt_pk_bf16_f32 v116, v119, v119
	global_store_short v[114:115], v116, off
	v_lshlrev_b32_e32 v116, 16, v185
	v_lshlrev_b32_e32 v119, 16, v144
	v_fmac_f32_e32 v119, v117, v116
	v_cvt_pk_bf16_f32 v116, v119, v119
	global_store_short v[114:115], v116, off offset:32
	v_lshlrev_b32_e32 v116, 16, v137
	v_lshlrev_b32_e32 v117, 16, v145
	v_fmac_f32_e32 v117, v129, v116
	v_cvt_pk_bf16_f32 v116, v117, v117
	global_store_short v[114:115], v116, off offset:256
	s_waitcnt vmcnt(0)
	v_lshlrev_b32_e32 v116, 16, v118
	v_lshlrev_b32_e32 v117, 16, v130
	v_fmac_f32_e32 v117, v125, v116
	v_cvt_pk_bf16_f32 v116, v117, v117
	global_store_short v[114:115], v116, off offset:288
	v_or_b32_e32 v114, 16, v136
	v_ashrrev_i32_e32 v115, 31, v114
	v_lshlrev_b64 v[116:117], 10, v[114:115]
	v_lshl_add_u64 v[116:117], v[116:117], 0, v[134:135]
	v_lshlrev_b64 v[116:117], 1, v[116:117]
	v_lshl_add_u64 v[118:119], s[8:9], 0, v[116:117]
	v_lshl_add_u64 v[120:121], s[4:5], 0, v[116:117]
	global_load_ushort v130, v[118:119], off
	global_load_ushort v137, v[120:121], off
	v_or_b32_e32 v122, 32, v116
	v_mov_b32_e32 v123, v117
	v_lshl_add_u64 v[124:125], s[8:9], 0, v[122:123]
	v_lshl_add_u64 v[122:123], s[4:5], 0, v[122:123]
	v_or_b32_e32 v126, 0x100, v116
	v_mov_b32_e32 v127, v117
	v_or_b32_e32 v140, 17, v136
	global_load_ushort v148, v[124:125], off
	global_load_ushort v149, v[122:123], off
	v_lshl_add_u64 v[128:129], s[8:9], 0, v[126:127]
	v_ashrrev_i32_e32 v141, 31, v140
	v_lshl_add_u64 v[126:127], s[4:5], 0, v[126:127]
	v_or_b32_e32 v116, 0x120, v116
	v_lshlrev_b64 v[142:143], 10, v[140:141]
	global_load_ushort v150, v[128:129], off
	global_load_ushort v151, v[126:127], off
	v_lshl_add_u64 v[138:139], s[8:9], 0, v[116:117]
	v_lshl_add_u64 v[142:143], v[142:143], 0, v[134:135]
	v_lshl_add_u64 v[116:117], s[4:5], 0, v[116:117]
	v_lshlrev_b64 v[142:143], 1, v[142:143]
	global_load_ushort v152, v[138:139], off
	global_load_ushort v153, v[116:117], off
	v_lshl_add_u64 v[144:145], s[8:9], 0, v[142:143]
	v_lshl_add_u64 v[118:119], s[4:5], 0, v[142:143]
	v_or_b32_e32 v120, 32, v142
	v_mov_b32_e32 v121, v143
	global_load_ushort v154, v[144:145], off
	global_load_ushort v155, v[118:119], off
	v_lshl_add_u64 v[146:147], s[8:9], 0, v[120:121]
	v_lshl_add_u64 v[120:121], s[4:5], 0, v[120:121]
	v_or_b32_e32 v122, 0x100, v142
	v_mov_b32_e32 v123, v143
	v_or_b32_e32 v128, 18, v136
	global_load_ushort v146, v[146:147], off
	s_nop 0
	global_load_ushort v147, v[120:121], off
	v_lshl_add_u64 v[124:125], s[8:9], 0, v[122:123]
	v_ashrrev_i32_e32 v129, 31, v128
	v_lshl_add_u64 v[122:123], s[4:5], 0, v[122:123]
	v_or_b32_e32 v142, 0x120, v142
	v_lshlrev_b64 v[138:139], 10, v[128:129]
	global_load_ushort v156, v[124:125], off
	global_load_ushort v157, v[122:123], off
	v_lshl_add_u64 v[126:127], s[8:9], 0, v[142:143]
	v_lshl_add_u64 v[138:139], v[138:139], 0, v[134:135]
; __device__ __forceinline__ unsigned f2bf(float f) { return pk2(f, f) & 0xffffu; }
; __device__ __forceinline__ void phase_branch() {
;     ...
;           unsigned short gv[4][2][2], tv[4][2][2];
; #pragma unroll
;           for (int j = 0; j < 4; ++j)
; #pragma unroll
;             for (int bj = 0; bj < 2; ++bj)
; #pragma unroll
;               for (int n = 0; n < 2; ++n) {
;                 const size_t idx = (size_t)(brow + ai * 128 + wr * 64 + m * 16 + fq * 4 + j) * DM + bcol + bj * 128 + wc * 32 + n * 16 + fr;
;                 gv[j][bj][n] = sg[idx]; tv[j][bj][n] = tmpb[idx];
;               }
; #pragma unroll
;           for (int j = 0; j < 4; ++j) {
;             const int row = brow + ai * 128 + wr * 64 + m * 16 + fq * 4 + j;
; #pragma unroll
;             for (int bj = 0; bj < 2; ++bj)
; #pragma unroll
;               for (int n = 0; n < 2; ++n) {
;                 const size_t idx = (size_t)row * DM + bcol + bj * 128 + wc * 32 + n * 16 + fr;
;                 merged[idx] = (unsigned short)f2bf(bf2f(gv[j][bj][n]) * acc[ai][bj][m][n][j] + bf2f(tv[j][bj][n]));
;               }
	v_lshl_add_u64 v[116:117], s[4:5], 0, v[142:143]
	v_lshlrev_b64 v[118:119], 1, v[138:139]
	global_load_ushort v158, v[126:127], off
	global_load_ushort v159, v[116:117], off
	v_lshl_add_u64 v[138:139], s[8:9], 0, v[118:119]
	v_lshl_add_u64 v[142:143], s[4:5], 0, v[118:119]
	v_or_b32_e32 v120, 32, v118
	v_mov_b32_e32 v121, v119
	global_load_ushort v160, v[138:139], off
	global_load_ushort v161, v[142:143], off
	v_lshl_add_u64 v[144:145], s[8:9], 0, v[120:121]
	v_lshl_add_u64 v[120:121], s[4:5], 0, v[120:121]
	v_or_b32_e32 v122, 0x100, v118
	v_mov_b32_e32 v123, v119
	v_or_b32_e32 v126, 19, v136
	global_load_ushort v144, v[144:145], off
	s_nop 0
	global_load_ushort v145, v[120:121], off
	v_lshl_add_u64 v[116:117], s[8:9], 0, v[122:123]
	v_ashrrev_i32_e32 v127, 31, v126
	v_lshl_add_u64 v[122:123], s[4:5], 0, v[122:123]
	v_or_b32_e32 v118, 0x120, v118
	v_lshlrev_b64 v[138:139], 10, v[126:127]
	global_load_ushort v162, v[116:117], off
	global_load_ushort v163, v[122:123], off
	v_lshl_add_u64 v[124:125], s[8:9], 0, v[118:119]
	v_lshl_add_u64 v[120:121], v[138:139], 0, v[134:135]
	v_lshl_add_u64 v[118:119], s[4:5], 0, v[118:119]
	v_lshlrev_b64 v[120:121], 1, v[120:121]
	global_load_ushort v164, v[124:125], off
	global_load_ushort v165, v[118:119], off
	v_lshl_add_u64 v[138:139], s[8:9], 0, v[120:121]
	v_lshl_add_u64 v[116:117], s[4:5], 0, v[120:121]
	v_or_b32_e32 v122, 32, v120
	v_mov_b32_e32 v123, v121
	global_load_ushort v138, v[138:139], off
	s_nop 0
	global_load_ushort v139, v[116:117], off
	v_lshl_add_u64 v[118:119], s[8:9], 0, v[122:123]
	v_lshl_add_u64 v[122:123], s[4:5], 0, v[122:123]
	v_or_b32_e32 v124, 0x100, v120
	v_mov_b32_e32 v125, v121
	global_load_ushort v166, v[118:119], off
	s_nop 0
	global_load_ushort v122, v[122:123], off
	v_lshl_add_u64 v[142:143], s[8:9], 0, v[124:125]
	v_lshl_add_u64 v[116:117], s[4:5], 0, v[124:125]
	v_or_b32_e32 v120, 0x120, v120
	v_lshl_add_u64 v[124:125], s[8:9], 0, v[120:121]
	v_lshl_add_u64 v[118:119], s[4:5], 0, v[120:121]
	global_load_ushort v120, v[142:143], off
	s_nop 0
	global_load_ushort v116, v[116:117], off
	s_waitcnt vmcnt(0)
	v_lshlrev_b32_e32 v117, 16, v130
	v_lshlrev_b32_e32 v121, 16, v137
	v_fmac_f32_e32 v121, v102, v117
	global_load_ushort v102, v[124:125], off
	global_load_ushort v117, v[118:119], off
	v_lshlrev_b64 v[114:115], 11, v[114:115]
	v_lshl_add_u64 v[114:115], v[132:133], 0, v[114:115]
	v_cvt_pk_bf16_f32 v118, v121, v121
	global_store_short v[114:115], v118, off
	v_lshlrev_b32_e32 v118, 16, v148
	v_lshlrev_b32_e32 v119, 16, v149
	v_fmac_f32_e32 v119, v98, v118
	v_cvt_pk_bf16_f32 v98, v119, v119
	global_store_short v[114:115], v98, off offset:32
	v_lshlrev_b32_e32 v98, 16, v150
	v_lshlrev_b32_e32 v118, 16, v151
	v_fmac_f32_e32 v118, v110, v98
	v_cvt_pk_bf16_f32 v98, v118, v118
	global_store_short v[114:115], v98, off offset:256
	v_lshlrev_b32_e32 v98, 16, v152
	v_lshlrev_b32_e32 v110, 16, v153
	v_fmac_f32_e32 v110, v106, v98
	v_cvt_pk_bf16_f32 v98, v110, v110
	global_store_short v[114:115], v98, off offset:288
	v_lshlrev_b64 v[114:115], 11, v[140:141]
	v_lshlrev_b32_e32 v98, 16, v154
	v_lshlrev_b32_e32 v106, 16, v155
	v_lshl_add_u64 v[114:115], v[132:133], 0, v[114:115]
	v_fmac_f32_e32 v106, v103, v98
	v_cvt_pk_bf16_f32 v98, v106, v106
	global_store_short v[114:115], v98, off
	v_lshlrev_b32_e32 v98, 16, v146
	v_lshlrev_b32_e32 v103, 16, v147
	v_fmac_f32_e32 v103, v99, v98
	v_cvt_pk_bf16_f32 v98, v103, v103
	global_store_short v[114:115], v98, off offset:32
	v_lshlrev_b32_e32 v98, 16, v156
	v_lshlrev_b32_e32 v99, 16, v157
	v_fmac_f32_e32 v99, v111, v98
	v_cvt_pk_bf16_f32 v98, v99, v99
	global_store_short v[114:115], v98, off offset:256
	v_lshlrev_b32_e32 v98, 16, v158
	v_lshlrev_b32_e32 v99, 16, v159
	v_fmac_f32_e32 v99, v107, v98
	v_cvt_pk_bf16_f32 v98, v99, v99
	global_store_short v[114:115], v98, off offset:288
	v_lshlrev_b64 v[98:99], 11, v[128:129]
	v_lshlrev_b32_e32 v103, 16, v160
	v_lshlrev_b32_e32 v106, 16, v161
	v_lshl_add_u64 v[98:99], v[132:133], 0, v[98:99]
	v_fmac_f32_e32 v106, v104, v103
	v_cvt_pk_bf16_f32 v103, v106, v106
	global_store_short v[98:99], v103, off
	v_lshlrev_b32_e32 v103, 16, v144
	v_lshlrev_b32_e32 v104, 16, v145
	v_fmac_f32_e32 v104, v100, v103
	v_cvt_pk_bf16_f32 v100, v104, v104
	global_store_short v[98:99], v100, off offset:32
	v_lshlrev_b32_e32 v100, 16, v162
	v_lshlrev_b32_e32 v103, 16, v163
	v_fmac_f32_e32 v103, v112, v100
	v_cvt_pk_bf16_f32 v100, v103, v103
	global_store_short v[98:99], v100, off offset:256
	v_lshlrev_b32_e32 v100, 16, v164
	v_lshlrev_b32_e32 v103, 16, v165
	v_fmac_f32_e32 v103, v108, v100
	v_cvt_pk_bf16_f32 v100, v103, v103
	global_store_short v[98:99], v100, off offset:288
	v_lshlrev_b64 v[98:99], 11, v[126:127]
	v_lshlrev_b32_e32 v100, 16, v138
	v_lshlrev_b32_e32 v103, 16, v139
	v_lshl_add_u64 v[98:99], v[132:133], 0, v[98:99]
	v_fmac_f32_e32 v103, v105, v100
	v_cvt_pk_bf16_f32 v100, v103, v103
	global_store_short v[98:99], v100, off
	v_lshlrev_b32_e32 v100, 16, v166
	v_lshlrev_b32_e32 v103, 16, v122
	v_fmac_f32_e32 v103, v101, v100
	v_cvt_pk_bf16_f32 v100, v103, v103
	global_store_short v[98:99], v100, off offset:32
	v_lshlrev_b32_e32 v100, 16, v120
	v_lshlrev_b32_e32 v101, 16, v116
	v_fmac_f32_e32 v101, v113, v100
	v_cvt_pk_bf16_f32 v100, v101, v101
	global_store_short v[98:99], v100, off offset:256
	s_waitcnt vmcnt(0)
; __device__ __forceinline__ unsigned f2bf(float f) { return pk2(f, f) & 0xffffu; }
; __device__ __forceinline__ void phase_branch() {
;     ...
;           unsigned short gv[4][2][2], tv[4][2][2];
; #pragma unroll
;           for (int j = 0; j < 4; ++j)
; #pragma unroll
;             for (int bj = 0; bj < 2; ++bj)
; #pragma unroll
;               for (int n = 0; n < 2; ++n) {
;                 const size_t idx = (size_t)(brow + ai * 128 + wr * 64 + m * 16 + fq * 4 + j) * DM + bcol + bj * 128 + wc * 32 + n * 16 + fr;
;                 gv[j][bj][n] = sg[idx]; tv[j][bj][n] = tmpb[idx];
;               }
; #pragma unroll
;           for (int j = 0; j < 4; ++j) {
;             const int row = brow + ai * 128 + wr * 64 + m * 16 + fq * 4 + j;
; #pragma unroll
;             for (int bj = 0; bj < 2; ++bj)
; #pragma unroll
;               for (int n = 0; n < 2; ++n) {
;                 const size_t idx = (size_t)row * DM + bcol + bj * 128 + wc * 32 + n * 16 + fr;
;                 merged[idx] = (unsigned short)f2bf(bf2f(gv[j][bj][n]) * acc[ai][bj][m][n][j] + bf2f(tv[j][bj][n]));
;               }
	v_lshlrev_b32_e32 v100, 16, v102
	v_lshlrev_b32_e32 v101, 16, v117
	v_fmac_f32_e32 v101, v109, v100
	v_cvt_pk_bf16_f32 v100, v101, v101
	global_store_short v[98:99], v100, off offset:288
	v_or_b32_e32 v98, 32, v136
	v_ashrrev_i32_e32 v99, 31, v98
	v_lshlrev_b64 v[100:101], 10, v[98:99]
	v_lshl_add_u64 v[100:101], v[100:101], 0, v[134:135]
	v_lshlrev_b64 v[100:101], 1, v[100:101]
	v_lshl_add_u64 v[102:103], s[8:9], 0, v[100:101]
	v_lshl_add_u64 v[104:105], s[4:5], 0, v[100:101]
	global_load_ushort v124, v[102:103], off
	global_load_ushort v125, v[104:105], off
	v_or_b32_e32 v106, 32, v100
	v_mov_b32_e32 v107, v101
	v_lshl_add_u64 v[108:109], s[8:9], 0, v[106:107]
	v_lshl_add_u64 v[106:107], s[4:5], 0, v[106:107]
	v_or_b32_e32 v110, 0x100, v100
	v_mov_b32_e32 v111, v101
	v_or_b32_e32 v116, 33, v136
	global_load_ushort v126, v[108:109], off
	global_load_ushort v127, v[106:107], off
	v_lshl_add_u64 v[112:113], s[8:9], 0, v[110:111]
	v_ashrrev_i32_e32 v117, 31, v116
	v_lshl_add_u64 v[110:111], s[4:5], 0, v[110:111]
	v_or_b32_e32 v100, 0x120, v100
	v_lshlrev_b64 v[118:119], 10, v[116:117]
	global_load_ushort v128, v[112:113], off
	global_load_ushort v129, v[110:111], off
	v_lshl_add_u64 v[114:115], s[8:9], 0, v[100:101]
	v_lshl_add_u64 v[118:119], v[118:119], 0, v[134:135]
	v_lshl_add_u64 v[100:101], s[4:5], 0, v[100:101]
	v_lshlrev_b64 v[118:119], 1, v[118:119]
	global_load_ushort v130, v[114:115], off
	global_load_ushort v137, v[100:101], off
	v_lshl_add_u64 v[120:121], s[8:9], 0, v[118:119]
	v_lshl_add_u64 v[102:103], s[4:5], 0, v[118:119]
	v_or_b32_e32 v104, 32, v118
	v_mov_b32_e32 v105, v119
	global_load_ushort v138, v[120:121], off
	global_load_ushort v139, v[102:103], off
	v_lshl_add_u64 v[122:123], s[8:9], 0, v[104:105]
	v_lshl_add_u64 v[104:105], s[4:5], 0, v[104:105]
	v_or_b32_e32 v106, 0x100, v118
	v_mov_b32_e32 v107, v119
	v_or_b32_e32 v112, 34, v136
	global_load_ushort v122, v[122:123], off
	s_nop 0
	global_load_ushort v123, v[104:105], off
	v_lshl_add_u64 v[108:109], s[8:9], 0, v[106:107]
	v_ashrrev_i32_e32 v113, 31, v112
	v_lshl_add_u64 v[106:107], s[4:5], 0, v[106:107]
	v_or_b32_e32 v118, 0x120, v118
	v_lshlrev_b64 v[114:115], 10, v[112:113]
	global_load_ushort v140, v[108:109], off
	global_load_ushort v141, v[106:107], off
	v_lshl_add_u64 v[110:111], s[8:9], 0, v[118:119]
	v_lshl_add_u64 v[114:115], v[114:115], 0, v[134:135]
	v_lshl_add_u64 v[100:101], s[4:5], 0, v[118:119]
	v_lshlrev_b64 v[102:103], 1, v[114:115]
	global_load_ushort v142, v[110:111], off
	global_load_ushort v143, v[100:101], off
	v_lshl_add_u64 v[114:115], s[8:9], 0, v[102:103]
	v_lshl_add_u64 v[118:119], s[4:5], 0, v[102:103]
	v_or_b32_e32 v104, 32, v102
	v_mov_b32_e32 v105, v103
	global_load_ushort v144, v[114:115], off
	global_load_ushort v145, v[118:119], off
	v_lshl_add_u64 v[120:121], s[8:9], 0, v[104:105]
	v_lshl_add_u64 v[104:105], s[4:5], 0, v[104:105]
	v_or_b32_e32 v106, 0x100, v102
	v_mov_b32_e32 v107, v103
	v_or_b32_e32 v110, 35, v136
	global_load_ushort v120, v[120:121], off
	s_nop 0
	global_load_ushort v121, v[104:105], off
	v_lshl_add_u64 v[100:101], s[8:9], 0, v[106:107]
	v_ashrrev_i32_e32 v111, 31, v110
	v_lshl_add_u64 v[106:107], s[4:5], 0, v[106:107]
	v_or_b32_e32 v102, 0x120, v102
	v_lshlrev_b64 v[114:115], 10, v[110:111]
	global_load_ushort v146, v[100:101], off
	global_load_ushort v147, v[106:107], off
	v_lshl_add_u64 v[108:109], s[8:9], 0, v[102:103]
	v_lshl_add_u64 v[104:105], v[114:115], 0, v[134:135]
	v_lshl_add_u64 v[102:103], s[4:5], 0, v[102:103]
	v_lshlrev_b64 v[104:105], 1, v[104:105]
	global_load_ushort v148, v[108:109], off
	global_load_ushort v149, v[102:103], off
	v_lshl_add_u64 v[114:115], s[8:9], 0, v[104:105]
	v_lshl_add_u64 v[100:101], s[4:5], 0, v[104:105]
	v_or_b32_e32 v106, 32, v104
	v_mov_b32_e32 v107, v105
	global_load_ushort v114, v[114:115], off
	s_nop 0
	global_load_ushort v115, v[100:101], off
	v_lshl_add_u64 v[102:103], s[8:9], 0, v[106:107]
	v_lshl_add_u64 v[106:107], s[4:5], 0, v[106:107]
	v_or_b32_e32 v108, 0x100, v104
	v_mov_b32_e32 v109, v105
	global_load_ushort v150, v[102:103], off
	s_nop 0
	global_load_ushort v106, v[106:107], off
	v_lshl_add_u64 v[118:119], s[8:9], 0, v[108:109]
	v_lshl_add_u64 v[100:101], s[4:5], 0, v[108:109]
	v_or_b32_e32 v104, 0x120, v104
	v_lshl_add_u64 v[108:109], s[8:9], 0, v[104:105]
	v_lshl_add_u64 v[102:103], s[4:5], 0, v[104:105]
	global_load_ushort v104, v[118:119], off
	s_nop 0
	global_load_ushort v100, v[100:101], off
	s_waitcnt vmcnt(0)
; __device__ __forceinline__ unsigned f2bf(float f) { return pk2(f, f) & 0xffffu; }
; __device__ __forceinline__ void phase_branch() {
;     ...
;           unsigned short gv[4][2][2], tv[4][2][2];
; #pragma unroll
;           for (int j = 0; j < 4; ++j)
; #pragma unroll
;             for (int bj = 0; bj < 2; ++bj)
; #pragma unroll
;               for (int n = 0; n < 2; ++n) {
;                 const size_t idx = (size_t)(brow + ai * 128 + wr * 64 + m * 16 + fq * 4 + j) * DM + bcol + bj * 128 + wc * 32 + n * 16 + fr;
;                 gv[j][bj][n] = sg[idx]; tv[j][bj][n] = tmpb[idx];
;               }
; #pragma unroll
;           for (int j = 0; j < 4; ++j) {
;             const int row = brow + ai * 128 + wr * 64 + m * 16 + fq * 4 + j;
; #pragma unroll
;             for (int bj = 0; bj < 2; ++bj)
; #pragma unroll
;               for (int n = 0; n < 2; ++n) {
;                 const size_t idx = (size_t)row * DM + bcol + bj * 128 + wc * 32 + n * 16 + fr;
;                 merged[idx] = (unsigned short)f2bf(bf2f(gv[j][bj][n]) * acc[ai][bj][m][n][j] + bf2f(tv[j][bj][n]));
;               }
	v_lshlrev_b32_e32 v101, 16, v124
	v_lshlrev_b32_e32 v105, 16, v125
	v_fmac_f32_e32 v105, v86, v101
	global_load_ushort v86, v[108:109], off
	global_load_ushort v101, v[102:103], off
	v_lshlrev_b64 v[98:99], 11, v[98:99]
	v_lshl_add_u64 v[98:99], v[132:133], 0, v[98:99]
	v_cvt_pk_bf16_f32 v102, v105, v105
	global_store_short v[98:99], v102, off
	v_lshlrev_b32_e32 v102, 16, v126
	v_lshlrev_b32_e32 v103, 16, v127
	v_fmac_f32_e32 v103, v82, v102
	v_cvt_pk_bf16_f32 v82, v103, v103
	global_store_short v[98:99], v82, off offset:32
	v_lshlrev_b32_e32 v82, 16, v128
	v_lshlrev_b32_e32 v102, 16, v129
	v_fmac_f32_e32 v102, v94, v82
	v_cvt_pk_bf16_f32 v82, v102, v102
	global_store_short v[98:99], v82, off offset:256
	v_lshlrev_b32_e32 v82, 16, v130
	v_lshlrev_b32_e32 v94, 16, v137
	v_fmac_f32_e32 v94, v90, v82
	v_cvt_pk_bf16_f32 v82, v94, v94
	global_store_short v[98:99], v82, off offset:288
	v_lshlrev_b64 v[98:99], 11, v[116:117]
	v_lshlrev_b32_e32 v82, 16, v138
	v_lshlrev_b32_e32 v90, 16, v139
	v_lshl_add_u64 v[98:99], v[132:133], 0, v[98:99]
	v_fmac_f32_e32 v90, v87, v82
	v_cvt_pk_bf16_f32 v82, v90, v90
	global_store_short v[98:99], v82, off
	v_lshlrev_b32_e32 v82, 16, v122
	v_lshlrev_b32_e32 v87, 16, v123
	v_fmac_f32_e32 v87, v83, v82
	v_cvt_pk_bf16_f32 v82, v87, v87
	global_store_short v[98:99], v82, off offset:32
	v_lshlrev_b32_e32 v82, 16, v140
	v_lshlrev_b32_e32 v83, 16, v141
	v_fmac_f32_e32 v83, v95, v82
	v_cvt_pk_bf16_f32 v82, v83, v83
	global_store_short v[98:99], v82, off offset:256
	v_lshlrev_b32_e32 v82, 16, v142
	v_lshlrev_b32_e32 v83, 16, v143
	v_fmac_f32_e32 v83, v91, v82
	v_cvt_pk_bf16_f32 v82, v83, v83
	global_store_short v[98:99], v82, off offset:288
	v_lshlrev_b64 v[82:83], 11, v[112:113]
	v_lshlrev_b32_e32 v87, 16, v144
	v_lshlrev_b32_e32 v90, 16, v145
	v_lshl_add_u64 v[82:83], v[132:133], 0, v[82:83]
	v_fmac_f32_e32 v90, v88, v87
	v_cvt_pk_bf16_f32 v87, v90, v90
	global_store_short v[82:83], v87, off
	v_lshlrev_b32_e32 v87, 16, v120
	v_lshlrev_b32_e32 v88, 16, v121
	v_fmac_f32_e32 v88, v84, v87
	v_cvt_pk_bf16_f32 v84, v88, v88
	global_store_short v[82:83], v84, off offset:32
	v_lshlrev_b32_e32 v84, 16, v146
	v_lshlrev_b32_e32 v87, 16, v147
	v_fmac_f32_e32 v87, v96, v84
	v_cvt_pk_bf16_f32 v84, v87, v87
	global_store_short v[82:83], v84, off offset:256
	v_lshlrev_b32_e32 v84, 16, v148
	v_lshlrev_b32_e32 v87, 16, v149
	v_fmac_f32_e32 v87, v92, v84
	v_cvt_pk_bf16_f32 v84, v87, v87
	global_store_short v[82:83], v84, off offset:288
	v_lshlrev_b64 v[82:83], 11, v[110:111]
	v_lshlrev_b32_e32 v84, 16, v114
	v_lshlrev_b32_e32 v87, 16, v115
	v_lshl_add_u64 v[82:83], v[132:133], 0, v[82:83]
	v_fmac_f32_e32 v87, v89, v84
	v_cvt_pk_bf16_f32 v84, v87, v87
	global_store_short v[82:83], v84, off
	v_lshlrev_b32_e32 v84, 16, v150
	v_lshlrev_b32_e32 v87, 16, v106
	v_fmac_f32_e32 v87, v85, v84
	v_cvt_pk_bf16_f32 v84, v87, v87
	global_store_short v[82:83], v84, off offset:32
	v_lshlrev_b32_e32 v84, 16, v104
	v_lshlrev_b32_e32 v85, 16, v100
	v_fmac_f32_e32 v85, v97, v84
	v_cvt_pk_bf16_f32 v84, v85, v85
	global_store_short v[82:83], v84, off offset:256
	s_waitcnt vmcnt(0)
	v_lshlrev_b32_e32 v84, 16, v86
	v_lshlrev_b32_e32 v85, 16, v101
	v_fmac_f32_e32 v85, v93, v84
	v_cvt_pk_bf16_f32 v84, v85, v85
	global_store_short v[82:83], v84, off offset:288
	v_or_b32_e32 v82, 48, v136
	v_ashrrev_i32_e32 v83, 31, v82
	v_lshlrev_b64 v[84:85], 10, v[82:83]
	v_lshl_add_u64 v[84:85], v[84:85], 0, v[134:135]
	v_lshlrev_b64 v[84:85], 1, v[84:85]
	v_lshl_add_u64 v[86:87], s[8:9], 0, v[84:85]
	v_lshl_add_u64 v[88:89], s[4:5], 0, v[84:85]
	global_load_ushort v108, v[86:87], off
	global_load_ushort v109, v[88:89], off
	v_or_b32_e32 v90, 32, v84
	v_mov_b32_e32 v91, v85
	v_lshl_add_u64 v[92:93], s[8:9], 0, v[90:91]
	v_lshl_add_u64 v[90:91], s[4:5], 0, v[90:91]
	v_or_b32_e32 v94, 0x100, v84
	v_mov_b32_e32 v95, v85
	v_or_b32_e32 v100, 49, v136
	global_load_ushort v110, v[92:93], off
	global_load_ushort v111, v[90:91], off
	v_lshl_add_u64 v[96:97], s[8:9], 0, v[94:95]
	v_ashrrev_i32_e32 v101, 31, v100
	v_lshl_add_u64 v[94:95], s[4:5], 0, v[94:95]
	v_or_b32_e32 v84, 0x120, v84
	v_lshlrev_b64 v[102:103], 10, v[100:101]
	global_load_ushort v112, v[96:97], off
	global_load_ushort v113, v[94:95], off
	v_lshl_add_u64 v[98:99], s[8:9], 0, v[84:85]
	v_lshl_add_u64 v[102:103], v[102:103], 0, v[134:135]
	v_lshl_add_u64 v[84:85], s[4:5], 0, v[84:85]
	v_lshlrev_b64 v[102:103], 1, v[102:103]
	global_load_ushort v114, v[98:99], off
	global_load_ushort v115, v[84:85], off
	v_lshl_add_u64 v[104:105], s[8:9], 0, v[102:103]
	v_lshl_add_u64 v[86:87], s[4:5], 0, v[102:103]
	v_or_b32_e32 v88, 32, v102
	v_mov_b32_e32 v89, v103
	global_load_ushort v116, v[104:105], off
	global_load_ushort v117, v[86:87], off
	v_lshl_add_u64 v[106:107], s[8:9], 0, v[88:89]
	v_lshl_add_u64 v[88:89], s[4:5], 0, v[88:89]
	v_or_b32_e32 v90, 0x100, v102
	v_mov_b32_e32 v91, v103
	v_or_b32_e32 v96, 50, v136
	global_load_ushort v118, v[106:107], off
	global_load_ushort v119, v[88:89], off
	v_lshl_add_u64 v[92:93], s[8:9], 0, v[90:91]
	v_ashrrev_i32_e32 v97, 31, v96
	v_lshl_add_u64 v[90:91], s[4:5], 0, v[90:91]
	v_or_b32_e32 v102, 0x120, v102
	v_lshlrev_b64 v[98:99], 10, v[96:97]
	global_load_ushort v106, v[92:93], off
	global_load_ushort v107, v[90:91], off
	v_lshl_add_u64 v[94:95], s[8:9], 0, v[102:103]
	v_lshl_add_u64 v[98:99], v[98:99], 0, v[134:135]
	v_lshl_add_u64 v[84:85], s[4:5], 0, v[102:103]
	v_lshlrev_b64 v[86:87], 1, v[98:99]
	global_load_ushort v120, v[94:95], off
	global_load_ushort v121, v[84:85], off
	v_lshl_add_u64 v[98:99], s[8:9], 0, v[86:87]
	v_lshl_add_u64 v[102:103], s[4:5], 0, v[86:87]
	v_or_b32_e32 v88, 32, v86
; __device__ __forceinline__ unsigned f2bf(float f) { return pk2(f, f) & 0xffffu; }
; __device__ __forceinline__ void phase_branch() {
;     ...
;           unsigned short gv[4][2][2], tv[4][2][2];
; #pragma unroll
;           for (int j = 0; j < 4; ++j)
; #pragma unroll
;             for (int bj = 0; bj < 2; ++bj)
; #pragma unroll
;               for (int n = 0; n < 2; ++n) {
;                 const size_t idx = (size_t)(brow + ai * 128 + wr * 64 + m * 16 + fq * 4 + j) * DM + bcol + bj * 128 + wc * 32 + n * 16 + fr;
;                 gv[j][bj][n] = sg[idx]; tv[j][bj][n] = tmpb[idx];
;               }
; #pragma unroll
;           for (int j = 0; j < 4; ++j) {
;             const int row = brow + ai * 128 + wr * 64 + m * 16 + fq * 4 + j;
; #pragma unroll
;             for (int bj = 0; bj < 2; ++bj)
; #pragma unroll
;               for (int n = 0; n < 2; ++n) {
;                 const size_t idx = (size_t)row * DM + bcol + bj * 128 + wc * 32 + n * 16 + fr;
;                 merged[idx] = (unsigned short)f2bf(bf2f(gv[j][bj][n]) * acc[ai][bj][m][n][j] + bf2f(tv[j][bj][n]));
;               }
	v_mov_b32_e32 v89, v87
	global_load_ushort v122, v[98:99], off
	global_load_ushort v123, v[102:103], off
	v_lshl_add_u64 v[104:105], s[8:9], 0, v[88:89]
	v_lshl_add_u64 v[88:89], s[4:5], 0, v[88:89]
	v_or_b32_e32 v90, 0x100, v86
	v_mov_b32_e32 v91, v87
	v_or_b32_e32 v94, 51, v136
	global_load_ushort v104, v[104:105], off
	s_nop 0
	global_load_ushort v105, v[88:89], off
	v_lshl_add_u64 v[84:85], s[8:9], 0, v[90:91]
	v_ashrrev_i32_e32 v95, 31, v94
	v_lshl_add_u64 v[90:91], s[4:5], 0, v[90:91]
	v_or_b32_e32 v86, 0x120, v86
	v_lshlrev_b64 v[98:99], 10, v[94:95]
	global_load_ushort v124, v[84:85], off
	global_load_ushort v125, v[90:91], off
	v_lshl_add_u64 v[92:93], s[8:9], 0, v[86:87]
	v_lshl_add_u64 v[88:89], v[98:99], 0, v[134:135]
	v_lshl_add_u64 v[86:87], s[4:5], 0, v[86:87]
	v_lshlrev_b64 v[88:89], 1, v[88:89]
	global_load_ushort v126, v[92:93], off
	global_load_ushort v127, v[86:87], off
	v_lshl_add_u64 v[98:99], s[8:9], 0, v[88:89]
	v_lshl_add_u64 v[84:85], s[4:5], 0, v[88:89]
	v_or_b32_e32 v90, 32, v88
	v_mov_b32_e32 v91, v89
	global_load_ushort v98, v[98:99], off
	s_nop 0
	global_load_ushort v99, v[84:85], off
	v_lshl_add_u64 v[86:87], s[8:9], 0, v[90:91]
	v_lshl_add_u64 v[90:91], s[4:5], 0, v[90:91]
	v_or_b32_e32 v92, 0x100, v88
	v_mov_b32_e32 v93, v89
	global_load_ushort v128, v[86:87], off
	s_nop 0
	global_load_ushort v90, v[90:91], off
	v_lshl_add_u64 v[102:103], s[8:9], 0, v[92:93]
	v_lshl_add_u64 v[84:85], s[4:5], 0, v[92:93]
	v_or_b32_e32 v88, 0x120, v88
	v_lshl_add_u64 v[92:93], s[8:9], 0, v[88:89]
	v_lshl_add_u64 v[86:87], s[4:5], 0, v[88:89]
	global_load_ushort v88, v[102:103], off
	s_nop 0
	global_load_ushort v84, v[84:85], off
	s_waitcnt vmcnt(0)
	v_lshlrev_b32_e32 v85, 16, v108
	v_lshlrev_b32_e32 v89, 16, v109
	v_fmac_f32_e32 v89, v70, v85
	global_load_ushort v70, v[92:93], off
	global_load_ushort v85, v[86:87], off
	v_lshlrev_b64 v[82:83], 11, v[82:83]
	v_lshl_add_u64 v[82:83], v[132:133], 0, v[82:83]
	v_cvt_pk_bf16_f32 v86, v89, v89
	global_store_short v[82:83], v86, off
	v_lshlrev_b32_e32 v86, 16, v110
	v_lshlrev_b32_e32 v87, 16, v111
	v_fmac_f32_e32 v87, v66, v86
	v_cvt_pk_bf16_f32 v66, v87, v87
	global_store_short v[82:83], v66, off offset:32
	v_lshlrev_b32_e32 v66, 16, v112
	v_lshlrev_b32_e32 v86, 16, v113
	v_fmac_f32_e32 v86, v78, v66
	v_cvt_pk_bf16_f32 v66, v86, v86
	global_store_short v[82:83], v66, off offset:256
	v_lshlrev_b32_e32 v66, 16, v114
	v_lshlrev_b32_e32 v78, 16, v115
	v_fmac_f32_e32 v78, v74, v66
	v_cvt_pk_bf16_f32 v66, v78, v78
	global_store_short v[82:83], v66, off offset:288
	v_lshlrev_b64 v[82:83], 11, v[100:101]
	v_lshlrev_b32_e32 v66, 16, v116
	v_lshlrev_b32_e32 v74, 16, v117
	v_lshl_add_u64 v[82:83], v[132:133], 0, v[82:83]
	v_fmac_f32_e32 v74, v71, v66
	v_cvt_pk_bf16_f32 v66, v74, v74
	global_store_short v[82:83], v66, off
	v_lshlrev_b32_e32 v66, 16, v118
	v_lshlrev_b32_e32 v71, 16, v119
	v_fmac_f32_e32 v71, v67, v66
	v_cvt_pk_bf16_f32 v66, v71, v71
	global_store_short v[82:83], v66, off offset:32
	v_lshlrev_b32_e32 v66, 16, v106
	v_lshlrev_b32_e32 v67, 16, v107
	v_fmac_f32_e32 v67, v79, v66
	v_cvt_pk_bf16_f32 v66, v67, v67
	global_store_short v[82:83], v66, off offset:256
	v_lshlrev_b32_e32 v66, 16, v120
	v_lshlrev_b32_e32 v67, 16, v121
	v_fmac_f32_e32 v67, v75, v66
	v_cvt_pk_bf16_f32 v66, v67, v67
	global_store_short v[82:83], v66, off offset:288
	v_lshlrev_b64 v[66:67], 11, v[96:97]
	v_lshlrev_b32_e32 v71, 16, v122
	v_lshlrev_b32_e32 v74, 16, v123
	v_lshl_add_u64 v[66:67], v[132:133], 0, v[66:67]
	v_fmac_f32_e32 v74, v72, v71
	v_cvt_pk_bf16_f32 v71, v74, v74
	global_store_short v[66:67], v71, off
	v_lshlrev_b32_e32 v71, 16, v104
	v_lshlrev_b32_e32 v72, 16, v105
	v_fmac_f32_e32 v72, v68, v71
	v_cvt_pk_bf16_f32 v68, v72, v72
	global_store_short v[66:67], v68, off offset:32
	v_lshlrev_b32_e32 v68, 16, v124
	v_lshlrev_b32_e32 v71, 16, v125
	v_fmac_f32_e32 v71, v80, v68
	v_cvt_pk_bf16_f32 v68, v71, v71
	global_store_short v[66:67], v68, off offset:256
	v_lshlrev_b32_e32 v68, 16, v126
	v_lshlrev_b32_e32 v71, 16, v127
	v_fmac_f32_e32 v71, v76, v68
	v_cvt_pk_bf16_f32 v68, v71, v71
	global_store_short v[66:67], v68, off offset:288
	v_lshlrev_b64 v[66:67], 11, v[94:95]
	v_lshlrev_b32_e32 v68, 16, v98
	v_lshlrev_b32_e32 v71, 16, v99
	v_lshl_add_u64 v[66:67], v[132:133], 0, v[66:67]
	v_fmac_f32_e32 v71, v73, v68
	v_cvt_pk_bf16_f32 v68, v71, v71
	global_store_short v[66:67], v68, off
	v_lshlrev_b32_e32 v68, 16, v128
	v_lshlrev_b32_e32 v71, 16, v90
	v_fmac_f32_e32 v71, v69, v68
	v_cvt_pk_bf16_f32 v68, v71, v71
	global_store_short v[66:67], v68, off offset:32
	v_lshlrev_b32_e32 v68, 16, v88
	v_lshlrev_b32_e32 v69, 16, v84
	v_fmac_f32_e32 v69, v81, v68
	v_cvt_pk_bf16_f32 v68, v69, v69
	global_store_short v[66:67], v68, off offset:256
	s_waitcnt vmcnt(0)
; __device__ __forceinline__ unsigned f2bf(float f) { return pk2(f, f) & 0xffffu; }
; __device__ __forceinline__ void phase_branch() {
;     ...
;           unsigned short gv[4][2][2], tv[4][2][2];
; #pragma unroll
;           for (int j = 0; j < 4; ++j)
; #pragma unroll
;             for (int bj = 0; bj < 2; ++bj)
; #pragma unroll
;               for (int n = 0; n < 2; ++n) {
;                 const size_t idx = (size_t)(brow + ai * 128 + wr * 64 + m * 16 + fq * 4 + j) * DM + bcol + bj * 128 + wc * 32 + n * 16 + fr;
;                 gv[j][bj][n] = sg[idx]; tv[j][bj][n] = tmpb[idx];
;               }
; #pragma unroll
;           for (int j = 0; j < 4; ++j) {
;             const int row = brow + ai * 128 + wr * 64 + m * 16 + fq * 4 + j;
; #pragma unroll
;             for (int bj = 0; bj < 2; ++bj)
; #pragma unroll
;               for (int n = 0; n < 2; ++n) {
;                 const size_t idx = (size_t)row * DM + bcol + bj * 128 + wc * 32 + n * 16 + fr;
;                 merged[idx] = (unsigned short)f2bf(bf2f(gv[j][bj][n]) * acc[ai][bj][m][n][j] + bf2f(tv[j][bj][n]));
;               }
	v_lshlrev_b32_e32 v68, 16, v70
	v_lshlrev_b32_e32 v69, 16, v85
	v_fmac_f32_e32 v69, v77, v68
	v_cvt_pk_bf16_f32 v68, v69, v69
	global_store_short v[66:67], v68, off offset:288
	v_add_u32_e32 v66, 0x80, v136
	v_ashrrev_i32_e32 v67, 31, v66
	v_lshlrev_b64 v[68:69], 10, v[66:67]
	v_lshl_add_u64 v[68:69], v[68:69], 0, v[134:135]
	v_lshlrev_b64 v[68:69], 1, v[68:69]
	v_lshl_add_u64 v[70:71], s[8:9], 0, v[68:69]
	v_lshl_add_u64 v[72:73], s[4:5], 0, v[68:69]
	global_load_ushort v92, v[70:71], off
	global_load_ushort v93, v[72:73], off
	v_or_b32_e32 v74, 32, v68
	v_mov_b32_e32 v75, v69
	v_lshl_add_u64 v[76:77], s[8:9], 0, v[74:75]
	v_lshl_add_u64 v[74:75], s[4:5], 0, v[74:75]
	v_or_b32_e32 v78, 0x100, v68
	v_mov_b32_e32 v79, v69
	v_add_u32_e32 v84, 0x81, v136
	global_load_ushort v94, v[76:77], off
	global_load_ushort v95, v[74:75], off
	v_lshl_add_u64 v[80:81], s[8:9], 0, v[78:79]
	v_ashrrev_i32_e32 v85, 31, v84
	v_lshl_add_u64 v[78:79], s[4:5], 0, v[78:79]
	v_or_b32_e32 v68, 0x120, v68
	v_lshlrev_b64 v[86:87], 10, v[84:85]
	global_load_ushort v96, v[80:81], off
	global_load_ushort v97, v[78:79], off
	v_lshl_add_u64 v[82:83], s[8:9], 0, v[68:69]
	v_lshl_add_u64 v[86:87], v[86:87], 0, v[134:135]
	v_lshl_add_u64 v[68:69], s[4:5], 0, v[68:69]
	v_lshlrev_b64 v[86:87], 1, v[86:87]
	global_load_ushort v98, v[82:83], off
	global_load_ushort v99, v[68:69], off
	v_lshl_add_u64 v[88:89], s[8:9], 0, v[86:87]
	v_lshl_add_u64 v[70:71], s[4:5], 0, v[86:87]
	v_or_b32_e32 v72, 32, v86
	v_mov_b32_e32 v73, v87
	global_load_ushort v100, v[88:89], off
	global_load_ushort v101, v[70:71], off
	v_lshl_add_u64 v[90:91], s[8:9], 0, v[72:73]
	v_lshl_add_u64 v[72:73], s[4:5], 0, v[72:73]
	v_or_b32_e32 v74, 0x100, v86
	v_mov_b32_e32 v75, v87
	v_add_u32_e32 v80, 0x82, v136
	global_load_ushort v102, v[90:91], off
	global_load_ushort v103, v[72:73], off
	v_lshl_add_u64 v[76:77], s[8:9], 0, v[74:75]
	v_ashrrev_i32_e32 v81, 31, v80
	v_lshl_add_u64 v[74:75], s[4:5], 0, v[74:75]
	v_or_b32_e32 v86, 0x120, v86
	v_lshlrev_b64 v[82:83], 10, v[80:81]
	global_load_ushort v90, v[76:77], off
	global_load_ushort v91, v[74:75], off
	v_lshl_add_u64 v[78:79], s[8:9], 0, v[86:87]
	v_lshl_add_u64 v[82:83], v[82:83], 0, v[134:135]
	v_lshl_add_u64 v[68:69], s[4:5], 0, v[86:87]
	v_lshlrev_b64 v[70:71], 1, v[82:83]
	global_load_ushort v104, v[78:79], off
	global_load_ushort v105, v[68:69], off
	v_lshl_add_u64 v[82:83], s[8:9], 0, v[70:71]
	v_lshl_add_u64 v[86:87], s[4:5], 0, v[70:71]
	v_or_b32_e32 v72, 32, v70
	v_mov_b32_e32 v73, v71
	global_load_ushort v106, v[82:83], off
	global_load_ushort v107, v[86:87], off
	v_lshl_add_u64 v[88:89], s[8:9], 0, v[72:73]
	v_lshl_add_u64 v[72:73], s[4:5], 0, v[72:73]
	v_or_b32_e32 v74, 0x100, v70
	v_mov_b32_e32 v75, v71
	v_add_u32_e32 v78, 0x83, v136
	global_load_ushort v108, v[88:89], off
	global_load_ushort v109, v[72:73], off
	v_lshl_add_u64 v[68:69], s[8:9], 0, v[74:75]
	v_ashrrev_i32_e32 v79, 31, v78
	v_lshl_add_u64 v[74:75], s[4:5], 0, v[74:75]
	v_or_b32_e32 v70, 0x120, v70
	v_lshlrev_b64 v[82:83], 10, v[78:79]
	global_load_ushort v88, v[68:69], off
	global_load_ushort v89, v[74:75], off
	v_lshl_add_u64 v[76:77], s[8:9], 0, v[70:71]
	v_lshl_add_u64 v[72:73], v[82:83], 0, v[134:135]
	v_lshl_add_u64 v[70:71], s[4:5], 0, v[70:71]
	v_lshlrev_b64 v[72:73], 1, v[72:73]
	global_load_ushort v110, v[76:77], off
	global_load_ushort v111, v[70:71], off
	v_lshl_add_u64 v[82:83], s[8:9], 0, v[72:73]
	v_lshl_add_u64 v[68:69], s[4:5], 0, v[72:73]
	v_or_b32_e32 v74, 32, v72
	v_mov_b32_e32 v75, v73
	global_load_ushort v112, v[82:83], off
	global_load_ushort v113, v[68:69], off
	v_lshl_add_u64 v[70:71], s[8:9], 0, v[74:75]
	v_lshl_add_u64 v[74:75], s[4:5], 0, v[74:75]
	v_or_b32_e32 v76, 0x100, v72
	v_mov_b32_e32 v77, v73
	global_load_ushort v82, v[70:71], off
	global_load_ushort v83, v[74:75], off
	v_lshl_add_u64 v[86:87], s[8:9], 0, v[76:77]
	v_or_b32_e32 v72, 0x120, v72
	v_lshl_add_u64 v[68:69], s[4:5], 0, v[76:77]
	v_lshl_add_u64 v[76:77], s[8:9], 0, v[72:73]
	v_lshl_add_u64 v[70:71], s[4:5], 0, v[72:73]
	global_load_ushort v72, v[86:87], off
	global_load_ushort v73, v[68:69], off
	s_waitcnt vmcnt(0)
	v_lshlrev_b32_e32 v68, 16, v92
	v_lshlrev_b32_e32 v69, 16, v93
	v_fmac_f32_e32 v69, v58, v68
	global_load_ushort v58, v[76:77], off
	global_load_ushort v68, v[70:71], off
	v_lshlrev_b64 v[66:67], 11, v[66:67]
	v_lshl_add_u64 v[66:67], v[132:133], 0, v[66:67]
	v_cvt_pk_bf16_f32 v69, v69, v69
	global_store_short v[66:67], v69, off
	v_lshlrev_b32_e32 v69, 16, v94
	v_lshlrev_b32_e32 v70, 16, v95
	v_fmac_f32_e32 v70, v50, v69
	v_cvt_pk_bf16_f32 v50, v70, v70
	global_store_short v[66:67], v50, off offset:32
	v_lshlrev_b32_e32 v50, 16, v96
	v_lshlrev_b32_e32 v69, 16, v97
	v_fmac_f32_e32 v69, v62, v50
	v_cvt_pk_bf16_f32 v50, v69, v69
	global_store_short v[66:67], v50, off offset:256
	v_lshlrev_b32_e32 v50, 16, v98
	v_lshlrev_b32_e32 v62, 16, v99
	v_fmac_f32_e32 v62, v54, v50
	v_cvt_pk_bf16_f32 v50, v62, v62
	global_store_short v[66:67], v50, off offset:288
	v_lshlrev_b64 v[66:67], 11, v[84:85]
	v_lshlrev_b32_e32 v50, 16, v100
	v_lshlrev_b32_e32 v54, 16, v101
	v_lshl_add_u64 v[66:67], v[132:133], 0, v[66:67]
	v_fmac_f32_e32 v54, v59, v50
	v_cvt_pk_bf16_f32 v50, v54, v54
	global_store_short v[66:67], v50, off
	v_lshlrev_b32_e32 v50, 16, v102
	v_lshlrev_b32_e32 v54, 16, v103
	v_fmac_f32_e32 v54, v51, v50
	v_cvt_pk_bf16_f32 v50, v54, v54
	global_store_short v[66:67], v50, off offset:32
	v_lshlrev_b32_e32 v50, 16, v90
	v_lshlrev_b32_e32 v51, 16, v91
	v_fmac_f32_e32 v51, v63, v50
	v_cvt_pk_bf16_f32 v50, v51, v51
	global_store_short v[66:67], v50, off offset:256
	v_lshlrev_b32_e32 v50, 16, v104
; __device__ __forceinline__ unsigned f2bf(float f) { return pk2(f, f) & 0xffffu; }
; __device__ __forceinline__ void phase_branch() {
;     ...
;           unsigned short gv[4][2][2], tv[4][2][2];
; #pragma unroll
;           for (int j = 0; j < 4; ++j)
; #pragma unroll
;             for (int bj = 0; bj < 2; ++bj)
; #pragma unroll
;               for (int n = 0; n < 2; ++n) {
;                 const size_t idx = (size_t)(brow + ai * 128 + wr * 64 + m * 16 + fq * 4 + j) * DM + bcol + bj * 128 + wc * 32 + n * 16 + fr;
;                 gv[j][bj][n] = sg[idx]; tv[j][bj][n] = tmpb[idx];
;               }
; #pragma unroll
;           for (int j = 0; j < 4; ++j) {
;             const int row = brow + ai * 128 + wr * 64 + m * 16 + fq * 4 + j;
; #pragma unroll
;             for (int bj = 0; bj < 2; ++bj)
; #pragma unroll
;               for (int n = 0; n < 2; ++n) {
;                 const size_t idx = (size_t)row * DM + bcol + bj * 128 + wc * 32 + n * 16 + fr;
;                 merged[idx] = (unsigned short)f2bf(bf2f(gv[j][bj][n]) * acc[ai][bj][m][n][j] + bf2f(tv[j][bj][n]));
;               }
	v_lshlrev_b32_e32 v51, 16, v105
	v_fmac_f32_e32 v51, v55, v50
	v_cvt_pk_bf16_f32 v50, v51, v51
	global_store_short v[66:67], v50, off offset:288
	v_lshlrev_b64 v[50:51], 11, v[80:81]
	v_lshlrev_b32_e32 v54, 16, v106
	v_lshlrev_b32_e32 v55, 16, v107
	v_lshl_add_u64 v[50:51], v[132:133], 0, v[50:51]
	v_fmac_f32_e32 v55, v60, v54
	v_cvt_pk_bf16_f32 v54, v55, v55
	global_store_short v[50:51], v54, off
	v_lshlrev_b32_e32 v54, 16, v108
	v_lshlrev_b32_e32 v55, 16, v109
	v_fmac_f32_e32 v55, v52, v54
	v_cvt_pk_bf16_f32 v52, v55, v55
	global_store_short v[50:51], v52, off offset:32
	v_lshlrev_b32_e32 v52, 16, v88
	v_lshlrev_b32_e32 v54, 16, v89
	v_fmac_f32_e32 v54, v64, v52
	v_cvt_pk_bf16_f32 v52, v54, v54
	global_store_short v[50:51], v52, off offset:256
	v_lshlrev_b32_e32 v52, 16, v110
	v_lshlrev_b32_e32 v54, 16, v111
	v_fmac_f32_e32 v54, v56, v52
	v_cvt_pk_bf16_f32 v52, v54, v54
	global_store_short v[50:51], v52, off offset:288
	v_lshlrev_b64 v[50:51], 11, v[78:79]
	v_lshlrev_b32_e32 v52, 16, v112
	v_lshlrev_b32_e32 v54, 16, v113
	v_lshl_add_u64 v[50:51], v[132:133], 0, v[50:51]
	v_fmac_f32_e32 v54, v61, v52
	v_cvt_pk_bf16_f32 v52, v54, v54
	global_store_short v[50:51], v52, off
	v_lshlrev_b32_e32 v52, 16, v82
	v_lshlrev_b32_e32 v54, 16, v83
	v_fmac_f32_e32 v54, v53, v52
	v_cvt_pk_bf16_f32 v52, v54, v54
	global_store_short v[50:51], v52, off offset:32
	v_lshlrev_b32_e32 v52, 16, v72
	v_lshlrev_b32_e32 v53, 16, v73
	v_fmac_f32_e32 v53, v65, v52
	v_cvt_pk_bf16_f32 v52, v53, v53
	global_store_short v[50:51], v52, off offset:256
	s_waitcnt vmcnt(0)
	v_lshlrev_b32_e32 v52, 16, v58
	v_lshlrev_b32_e32 v53, 16, v68
	v_fmac_f32_e32 v53, v57, v52
	v_cvt_pk_bf16_f32 v52, v53, v53
	global_store_short v[50:51], v52, off offset:288
	v_add_u32_e32 v50, 0x90, v136
	v_ashrrev_i32_e32 v51, 31, v50
	v_lshlrev_b64 v[52:53], 10, v[50:51]
	v_lshl_add_u64 v[52:53], v[52:53], 0, v[134:135]
	v_lshlrev_b64 v[52:53], 1, v[52:53]
	v_lshl_add_u64 v[54:55], s[8:9], 0, v[52:53]
	v_lshl_add_u64 v[56:57], s[4:5], 0, v[52:53]
	global_load_ushort v76, v[54:55], off
	global_load_ushort v77, v[56:57], off
	v_or_b32_e32 v58, 32, v52
	v_mov_b32_e32 v59, v53
	v_lshl_add_u64 v[60:61], s[8:9], 0, v[58:59]
	v_lshl_add_u64 v[58:59], s[4:5], 0, v[58:59]
	v_or_b32_e32 v62, 0x100, v52
	v_mov_b32_e32 v63, v53
	v_add_u32_e32 v68, 0x91, v136
	global_load_ushort v78, v[60:61], off
	global_load_ushort v79, v[58:59], off
	v_lshl_add_u64 v[64:65], s[8:9], 0, v[62:63]
	v_ashrrev_i32_e32 v69, 31, v68
	v_lshl_add_u64 v[62:63], s[4:5], 0, v[62:63]
	v_or_b32_e32 v52, 0x120, v52
	v_lshlrev_b64 v[70:71], 10, v[68:69]
	global_load_ushort v80, v[64:65], off
	global_load_ushort v81, v[62:63], off
	v_lshl_add_u64 v[66:67], s[8:9], 0, v[52:53]
	v_lshl_add_u64 v[70:71], v[70:71], 0, v[134:135]
	v_lshl_add_u64 v[52:53], s[4:5], 0, v[52:53]
	v_lshlrev_b64 v[70:71], 1, v[70:71]
	global_load_ushort v82, v[66:67], off
	global_load_ushort v83, v[52:53], off
	v_lshl_add_u64 v[72:73], s[8:9], 0, v[70:71]
	v_lshl_add_u64 v[54:55], s[4:5], 0, v[70:71]
	v_or_b32_e32 v56, 32, v70
	v_mov_b32_e32 v57, v71
	global_load_ushort v84, v[72:73], off
	global_load_ushort v85, v[54:55], off
	v_lshl_add_u64 v[74:75], s[8:9], 0, v[56:57]
	v_lshl_add_u64 v[56:57], s[4:5], 0, v[56:57]
	v_or_b32_e32 v58, 0x100, v70
	v_mov_b32_e32 v59, v71
	v_add_u32_e32 v64, 0x92, v136
	global_load_ushort v86, v[74:75], off
	global_load_ushort v87, v[56:57], off
	v_lshl_add_u64 v[60:61], s[8:9], 0, v[58:59]
	v_ashrrev_i32_e32 v65, 31, v64
	v_lshl_add_u64 v[58:59], s[4:5], 0, v[58:59]
	v_or_b32_e32 v70, 0x120, v70
	v_lshlrev_b64 v[66:67], 10, v[64:65]
	global_load_ushort v74, v[60:61], off
	global_load_ushort v75, v[58:59], off
	v_lshl_add_u64 v[62:63], s[8:9], 0, v[70:71]
	v_lshl_add_u64 v[66:67], v[66:67], 0, v[134:135]
	v_lshl_add_u64 v[52:53], s[4:5], 0, v[70:71]
	v_lshlrev_b64 v[54:55], 1, v[66:67]
	global_load_ushort v88, v[62:63], off
	global_load_ushort v89, v[52:53], off
	v_lshl_add_u64 v[66:67], s[8:9], 0, v[54:55]
	v_lshl_add_u64 v[70:71], s[4:5], 0, v[54:55]
	v_or_b32_e32 v56, 32, v54
	v_mov_b32_e32 v57, v55
	global_load_ushort v90, v[66:67], off
	global_load_ushort v91, v[70:71], off
	v_lshl_add_u64 v[72:73], s[8:9], 0, v[56:57]
	v_lshl_add_u64 v[56:57], s[4:5], 0, v[56:57]
	v_or_b32_e32 v58, 0x100, v54
	v_mov_b32_e32 v59, v55
	v_add_u32_e32 v62, 0x93, v136
	global_load_ushort v92, v[72:73], off
	global_load_ushort v93, v[56:57], off
	v_lshl_add_u64 v[52:53], s[8:9], 0, v[58:59]
	v_ashrrev_i32_e32 v63, 31, v62
	v_lshl_add_u64 v[58:59], s[4:5], 0, v[58:59]
	v_or_b32_e32 v54, 0x120, v54
	v_lshlrev_b64 v[66:67], 10, v[62:63]
	global_load_ushort v72, v[52:53], off
	global_load_ushort v73, v[58:59], off
	v_lshl_add_u64 v[60:61], s[8:9], 0, v[54:55]
	v_lshl_add_u64 v[56:57], v[66:67], 0, v[134:135]
	v_lshl_add_u64 v[54:55], s[4:5], 0, v[54:55]
	v_lshlrev_b64 v[56:57], 1, v[56:57]
	global_load_ushort v94, v[60:61], off
	global_load_ushort v95, v[54:55], off
	v_lshl_add_u64 v[66:67], s[8:9], 0, v[56:57]
	v_lshl_add_u64 v[52:53], s[4:5], 0, v[56:57]
	v_or_b32_e32 v58, 32, v56
	v_mov_b32_e32 v59, v57
	global_load_ushort v96, v[66:67], off
	global_load_ushort v97, v[52:53], off
	v_lshl_add_u64 v[54:55], s[8:9], 0, v[58:59]
	v_lshl_add_u64 v[58:59], s[4:5], 0, v[58:59]
	v_or_b32_e32 v60, 0x100, v56
	v_mov_b32_e32 v61, v57
	global_load_ushort v66, v[54:55], off
	global_load_ushort v67, v[58:59], off
	v_lshl_add_u64 v[70:71], s[8:9], 0, v[60:61]
	v_or_b32_e32 v56, 0x120, v56
	v_lshl_add_u64 v[52:53], s[4:5], 0, v[60:61]
	v_lshl_add_u64 v[60:61], s[8:9], 0, v[56:57]
	v_lshl_add_u64 v[54:55], s[4:5], 0, v[56:57]
	global_load_ushort v56, v[70:71], off
	global_load_ushort v57, v[52:53], off
	s_waitcnt vmcnt(0)
; __device__ __forceinline__ unsigned f2bf(float f) { return pk2(f, f) & 0xffffu; }
; __device__ __forceinline__ void phase_branch() {
;     ...
;           unsigned short gv[4][2][2], tv[4][2][2];
; #pragma unroll
;           for (int j = 0; j < 4; ++j)
; #pragma unroll
;             for (int bj = 0; bj < 2; ++bj)
; #pragma unroll
;               for (int n = 0; n < 2; ++n) {
;                 const size_t idx = (size_t)(brow + ai * 128 + wr * 64 + m * 16 + fq * 4 + j) * DM + bcol + bj * 128 + wc * 32 + n * 16 + fr;
;                 gv[j][bj][n] = sg[idx]; tv[j][bj][n] = tmpb[idx];
;               }
; #pragma unroll
;           for (int j = 0; j < 4; ++j) {
;             const int row = brow + ai * 128 + wr * 64 + m * 16 + fq * 4 + j;
; #pragma unroll
;             for (int bj = 0; bj < 2; ++bj)
; #pragma unroll
;               for (int n = 0; n < 2; ++n) {
;                 const size_t idx = (size_t)row * DM + bcol + bj * 128 + wc * 32 + n * 16 + fr;
;                 merged[idx] = (unsigned short)f2bf(bf2f(gv[j][bj][n]) * acc[ai][bj][m][n][j] + bf2f(tv[j][bj][n]));
;               }
	v_lshlrev_b32_e32 v52, 16, v76
	v_lshlrev_b32_e32 v53, 16, v77
	v_fmac_f32_e32 v53, v42, v52
	global_load_ushort v42, v[60:61], off
	global_load_ushort v52, v[54:55], off
	v_lshlrev_b64 v[50:51], 11, v[50:51]
	v_lshl_add_u64 v[50:51], v[132:133], 0, v[50:51]
	v_cvt_pk_bf16_f32 v53, v53, v53
	global_store_short v[50:51], v53, off
	v_lshlrev_b32_e32 v53, 16, v78
	v_lshlrev_b32_e32 v54, 16, v79
	v_fmac_f32_e32 v54, v34, v53
	v_cvt_pk_bf16_f32 v34, v54, v54
	global_store_short v[50:51], v34, off offset:32
	v_lshlrev_b32_e32 v34, 16, v80
	v_lshlrev_b32_e32 v53, 16, v81
	v_fmac_f32_e32 v53, v46, v34
	v_cvt_pk_bf16_f32 v34, v53, v53
	global_store_short v[50:51], v34, off offset:256
	v_lshlrev_b32_e32 v34, 16, v82
	v_lshlrev_b32_e32 v46, 16, v83
	v_fmac_f32_e32 v46, v38, v34
	v_cvt_pk_bf16_f32 v34, v46, v46
	global_store_short v[50:51], v34, off offset:288
	v_lshlrev_b64 v[50:51], 11, v[68:69]
	v_lshlrev_b32_e32 v34, 16, v84
	v_lshlrev_b32_e32 v38, 16, v85
	v_lshl_add_u64 v[50:51], v[132:133], 0, v[50:51]
	v_fmac_f32_e32 v38, v43, v34
	v_cvt_pk_bf16_f32 v34, v38, v38
	global_store_short v[50:51], v34, off
	v_lshlrev_b32_e32 v34, 16, v86
	v_lshlrev_b32_e32 v38, 16, v87
	v_fmac_f32_e32 v38, v35, v34
	v_cvt_pk_bf16_f32 v34, v38, v38
	global_store_short v[50:51], v34, off offset:32
	v_lshlrev_b32_e32 v34, 16, v74
	v_lshlrev_b32_e32 v35, 16, v75
	v_fmac_f32_e32 v35, v47, v34
	v_cvt_pk_bf16_f32 v34, v35, v35
	global_store_short v[50:51], v34, off offset:256
	v_lshlrev_b32_e32 v34, 16, v88
	v_lshlrev_b32_e32 v35, 16, v89
	v_fmac_f32_e32 v35, v39, v34
	v_cvt_pk_bf16_f32 v34, v35, v35
	global_store_short v[50:51], v34, off offset:288
	v_lshlrev_b64 v[34:35], 11, v[64:65]
	v_lshlrev_b32_e32 v38, 16, v90
	v_lshlrev_b32_e32 v39, 16, v91
	v_lshl_add_u64 v[34:35], v[132:133], 0, v[34:35]
	v_fmac_f32_e32 v39, v44, v38
	v_cvt_pk_bf16_f32 v38, v39, v39
	global_store_short v[34:35], v38, off
	v_lshlrev_b32_e32 v38, 16, v92
	v_lshlrev_b32_e32 v39, 16, v93
	v_fmac_f32_e32 v39, v36, v38
	v_cvt_pk_bf16_f32 v36, v39, v39
	global_store_short v[34:35], v36, off offset:32
	v_lshlrev_b32_e32 v36, 16, v72
	v_lshlrev_b32_e32 v38, 16, v73
	v_fmac_f32_e32 v38, v48, v36
	v_cvt_pk_bf16_f32 v36, v38, v38
	global_store_short v[34:35], v36, off offset:256
	v_lshlrev_b32_e32 v36, 16, v94
	v_lshlrev_b32_e32 v38, 16, v95
	v_fmac_f32_e32 v38, v40, v36
	v_cvt_pk_bf16_f32 v36, v38, v38
	global_store_short v[34:35], v36, off offset:288
	v_lshlrev_b64 v[34:35], 11, v[62:63]
	v_lshlrev_b32_e32 v36, 16, v96
	v_lshlrev_b32_e32 v38, 16, v97
	v_lshl_add_u64 v[34:35], v[132:133], 0, v[34:35]
	v_fmac_f32_e32 v38, v45, v36
	v_cvt_pk_bf16_f32 v36, v38, v38
	global_store_short v[34:35], v36, off
	v_lshlrev_b32_e32 v36, 16, v66
	v_lshlrev_b32_e32 v38, 16, v67
	v_fmac_f32_e32 v38, v37, v36
	v_cvt_pk_bf16_f32 v36, v38, v38
	global_store_short v[34:35], v36, off offset:32
	v_lshlrev_b32_e32 v36, 16, v56
	v_lshlrev_b32_e32 v37, 16, v57
	v_fmac_f32_e32 v37, v49, v36
	v_cvt_pk_bf16_f32 v36, v37, v37
	global_store_short v[34:35], v36, off offset:256
	s_waitcnt vmcnt(0)
	v_lshlrev_b32_e32 v36, 16, v42
	v_lshlrev_b32_e32 v37, 16, v52
	v_fmac_f32_e32 v37, v41, v36
	v_cvt_pk_bf16_f32 v36, v37, v37
	global_store_short v[34:35], v36, off offset:288
	v_add_u32_e32 v34, 0xa0, v136
	v_ashrrev_i32_e32 v35, 31, v34
	v_lshlrev_b64 v[36:37], 10, v[34:35]
	v_lshl_add_u64 v[36:37], v[36:37], 0, v[134:135]
	v_lshlrev_b64 v[36:37], 1, v[36:37]
	v_lshl_add_u64 v[38:39], s[8:9], 0, v[36:37]
	v_lshl_add_u64 v[40:41], s[4:5], 0, v[36:37]
	global_load_ushort v60, v[38:39], off
	global_load_ushort v61, v[40:41], off
	v_or_b32_e32 v42, 32, v36
	v_mov_b32_e32 v43, v37
	v_lshl_add_u64 v[44:45], s[8:9], 0, v[42:43]
	v_lshl_add_u64 v[42:43], s[4:5], 0, v[42:43]
	v_or_b32_e32 v46, 0x100, v36
	v_mov_b32_e32 v47, v37
	v_add_u32_e32 v52, 0xa1, v136
	global_load_ushort v62, v[44:45], off
	global_load_ushort v63, v[42:43], off
	v_lshl_add_u64 v[48:49], s[8:9], 0, v[46:47]
	v_ashrrev_i32_e32 v53, 31, v52
	v_lshl_add_u64 v[46:47], s[4:5], 0, v[46:47]
	v_or_b32_e32 v36, 0x120, v36
	v_lshlrev_b64 v[54:55], 10, v[52:53]
	global_load_ushort v64, v[48:49], off
	global_load_ushort v65, v[46:47], off
	v_lshl_add_u64 v[50:51], s[8:9], 0, v[36:37]
	v_lshl_add_u64 v[54:55], v[54:55], 0, v[134:135]
	v_lshl_add_u64 v[36:37], s[4:5], 0, v[36:37]
	v_lshlrev_b64 v[54:55], 1, v[54:55]
	global_load_ushort v66, v[50:51], off
	global_load_ushort v67, v[36:37], off
	v_lshl_add_u64 v[56:57], s[8:9], 0, v[54:55]
	v_lshl_add_u64 v[38:39], s[4:5], 0, v[54:55]
	v_or_b32_e32 v40, 32, v54
	v_mov_b32_e32 v41, v55
	global_load_ushort v68, v[56:57], off
	global_load_ushort v69, v[38:39], off
	v_lshl_add_u64 v[58:59], s[8:9], 0, v[40:41]
	v_lshl_add_u64 v[40:41], s[4:5], 0, v[40:41]
	v_or_b32_e32 v42, 0x100, v54
	v_mov_b32_e32 v43, v55
	v_add_u32_e32 v48, 0xa2, v136
	global_load_ushort v70, v[58:59], off
	global_load_ushort v71, v[40:41], off
	v_lshl_add_u64 v[44:45], s[8:9], 0, v[42:43]
	v_ashrrev_i32_e32 v49, 31, v48
	v_lshl_add_u64 v[42:43], s[4:5], 0, v[42:43]
	v_or_b32_e32 v54, 0x120, v54
	v_lshlrev_b64 v[50:51], 10, v[48:49]
	global_load_ushort v58, v[44:45], off
	global_load_ushort v59, v[42:43], off
	v_lshl_add_u64 v[46:47], s[8:9], 0, v[54:55]
	v_lshl_add_u64 v[50:51], v[50:51], 0, v[134:135]
	v_lshl_add_u64 v[36:37], s[4:5], 0, v[54:55]
	v_lshlrev_b64 v[38:39], 1, v[50:51]
	global_load_ushort v72, v[46:47], off
	global_load_ushort v73, v[36:37], off
	v_lshl_add_u64 v[50:51], s[8:9], 0, v[38:39]
	v_lshl_add_u64 v[54:55], s[4:5], 0, v[38:39]
	v_or_b32_e32 v40, 32, v38
	v_mov_b32_e32 v41, v39
	global_load_ushort v74, v[50:51], off
	global_load_ushort v75, v[54:55], off
; __device__ __forceinline__ unsigned f2bf(float f) { return pk2(f, f) & 0xffffu; }
; __device__ __forceinline__ void phase_branch() {
;     ...
;           unsigned short gv[4][2][2], tv[4][2][2];
; #pragma unroll
;           for (int j = 0; j < 4; ++j)
; #pragma unroll
;             for (int bj = 0; bj < 2; ++bj)
; #pragma unroll
;               for (int n = 0; n < 2; ++n) {
;                 const size_t idx = (size_t)(brow + ai * 128 + wr * 64 + m * 16 + fq * 4 + j) * DM + bcol + bj * 128 + wc * 32 + n * 16 + fr;
;                 gv[j][bj][n] = sg[idx]; tv[j][bj][n] = tmpb[idx];
;               }
; #pragma unroll
;           for (int j = 0; j < 4; ++j) {
;             const int row = brow + ai * 128 + wr * 64 + m * 16 + fq * 4 + j;
; #pragma unroll
;             for (int bj = 0; bj < 2; ++bj)
; #pragma unroll
;               for (int n = 0; n < 2; ++n) {
;                 const size_t idx = (size_t)row * DM + bcol + bj * 128 + wc * 32 + n * 16 + fr;
;                 merged[idx] = (unsigned short)f2bf(bf2f(gv[j][bj][n]) * acc[ai][bj][m][n][j] + bf2f(tv[j][bj][n]));
;               }
	v_lshl_add_u64 v[56:57], s[8:9], 0, v[40:41]
	v_lshl_add_u64 v[40:41], s[4:5], 0, v[40:41]
	v_or_b32_e32 v42, 0x100, v38
	v_mov_b32_e32 v43, v39
	v_add_u32_e32 v46, 0xa3, v136
	global_load_ushort v76, v[56:57], off
	global_load_ushort v77, v[40:41], off
	v_lshl_add_u64 v[36:37], s[8:9], 0, v[42:43]
	v_ashrrev_i32_e32 v47, 31, v46
	v_lshl_add_u64 v[42:43], s[4:5], 0, v[42:43]
	v_or_b32_e32 v38, 0x120, v38
	v_lshlrev_b64 v[50:51], 10, v[46:47]
	global_load_ushort v56, v[36:37], off
	global_load_ushort v57, v[42:43], off
	v_lshl_add_u64 v[44:45], s[8:9], 0, v[38:39]
	v_lshl_add_u64 v[40:41], v[50:51], 0, v[134:135]
	v_lshl_add_u64 v[38:39], s[4:5], 0, v[38:39]
	v_lshlrev_b64 v[40:41], 1, v[40:41]
	global_load_ushort v78, v[44:45], off
	global_load_ushort v79, v[38:39], off
	v_lshl_add_u64 v[50:51], s[8:9], 0, v[40:41]
	v_lshl_add_u64 v[36:37], s[4:5], 0, v[40:41]
	v_or_b32_e32 v42, 32, v40
	v_mov_b32_e32 v43, v41
	global_load_ushort v80, v[50:51], off
	global_load_ushort v81, v[36:37], off
	v_lshl_add_u64 v[38:39], s[8:9], 0, v[42:43]
	v_lshl_add_u64 v[42:43], s[4:5], 0, v[42:43]
	v_or_b32_e32 v44, 0x100, v40
	v_mov_b32_e32 v45, v41
	global_load_ushort v50, v[38:39], off
	global_load_ushort v51, v[42:43], off
	v_lshl_add_u64 v[54:55], s[8:9], 0, v[44:45]
	v_or_b32_e32 v40, 0x120, v40
	v_lshl_add_u64 v[36:37], s[4:5], 0, v[44:45]
	v_lshl_add_u64 v[44:45], s[8:9], 0, v[40:41]
	v_lshl_add_u64 v[38:39], s[4:5], 0, v[40:41]
	global_load_ushort v40, v[54:55], off
	global_load_ushort v41, v[36:37], off
	s_waitcnt vmcnt(0)
	v_lshlrev_b32_e32 v36, 16, v60
	v_lshlrev_b32_e32 v37, 16, v61
	v_fmac_f32_e32 v37, v26, v36
	global_load_ushort v26, v[44:45], off
	global_load_ushort v36, v[38:39], off
	v_lshlrev_b64 v[34:35], 11, v[34:35]
	v_lshl_add_u64 v[34:35], v[132:133], 0, v[34:35]
	v_cvt_pk_bf16_f32 v37, v37, v37
	global_store_short v[34:35], v37, off
	v_lshlrev_b32_e32 v37, 16, v62
	v_lshlrev_b32_e32 v38, 16, v63
	v_fmac_f32_e32 v38, v18, v37
	v_cvt_pk_bf16_f32 v18, v38, v38
	global_store_short v[34:35], v18, off offset:32
	v_lshlrev_b32_e32 v18, 16, v64
	v_lshlrev_b32_e32 v37, 16, v65
	v_fmac_f32_e32 v37, v30, v18
	v_cvt_pk_bf16_f32 v18, v37, v37
	global_store_short v[34:35], v18, off offset:256
	v_lshlrev_b32_e32 v18, 16, v66
	v_lshlrev_b32_e32 v30, 16, v67
	v_fmac_f32_e32 v30, v22, v18
	v_cvt_pk_bf16_f32 v18, v30, v30
	global_store_short v[34:35], v18, off offset:288
	v_lshlrev_b64 v[34:35], 11, v[52:53]
	v_lshlrev_b32_e32 v18, 16, v68
	v_lshlrev_b32_e32 v22, 16, v69
	v_lshl_add_u64 v[34:35], v[132:133], 0, v[34:35]
	v_fmac_f32_e32 v22, v27, v18
	v_cvt_pk_bf16_f32 v18, v22, v22
	global_store_short v[34:35], v18, off
	v_lshlrev_b32_e32 v18, 16, v70
	v_lshlrev_b32_e32 v22, 16, v71
	v_fmac_f32_e32 v22, v19, v18
	v_cvt_pk_bf16_f32 v18, v22, v22
	global_store_short v[34:35], v18, off offset:32
	v_lshlrev_b32_e32 v18, 16, v58
	v_lshlrev_b32_e32 v19, 16, v59
	v_fmac_f32_e32 v19, v31, v18
	v_cvt_pk_bf16_f32 v18, v19, v19
	global_store_short v[34:35], v18, off offset:256
	v_lshlrev_b32_e32 v18, 16, v72
	v_lshlrev_b32_e32 v19, 16, v73
	v_fmac_f32_e32 v19, v23, v18
	v_cvt_pk_bf16_f32 v18, v19, v19
	global_store_short v[34:35], v18, off offset:288
	v_lshlrev_b64 v[18:19], 11, v[48:49]
	v_lshlrev_b32_e32 v22, 16, v74
	v_lshlrev_b32_e32 v23, 16, v75
	v_lshl_add_u64 v[18:19], v[132:133], 0, v[18:19]
	v_fmac_f32_e32 v23, v28, v22
	v_cvt_pk_bf16_f32 v22, v23, v23
	global_store_short v[18:19], v22, off
	v_lshlrev_b32_e32 v22, 16, v76
	v_lshlrev_b32_e32 v23, 16, v77
	v_fmac_f32_e32 v23, v20, v22
	v_cvt_pk_bf16_f32 v20, v23, v23
	global_store_short v[18:19], v20, off offset:32
	v_lshlrev_b32_e32 v20, 16, v56
	v_lshlrev_b32_e32 v22, 16, v57
	v_fmac_f32_e32 v22, v32, v20
	v_cvt_pk_bf16_f32 v20, v22, v22
	global_store_short v[18:19], v20, off offset:256
	v_lshlrev_b32_e32 v20, 16, v78
	v_lshlrev_b32_e32 v22, 16, v79
	v_fmac_f32_e32 v22, v24, v20
	v_cvt_pk_bf16_f32 v20, v22, v22
	global_store_short v[18:19], v20, off offset:288
	v_lshlrev_b64 v[18:19], 11, v[46:47]
	v_lshlrev_b32_e32 v20, 16, v80
	v_lshlrev_b32_e32 v22, 16, v81
	v_lshl_add_u64 v[18:19], v[132:133], 0, v[18:19]
	v_fmac_f32_e32 v22, v29, v20
	v_cvt_pk_bf16_f32 v20, v22, v22
	global_store_short v[18:19], v20, off
	v_lshlrev_b32_e32 v20, 16, v50
	v_lshlrev_b32_e32 v22, 16, v51
	v_fmac_f32_e32 v22, v21, v20
	v_cvt_pk_bf16_f32 v20, v22, v22
	global_store_short v[18:19], v20, off offset:32
	v_lshlrev_b32_e32 v20, 16, v40
	v_lshlrev_b32_e32 v21, 16, v41
	v_fmac_f32_e32 v21, v33, v20
	v_cvt_pk_bf16_f32 v20, v21, v21
	global_store_short v[18:19], v20, off offset:256
	s_waitcnt vmcnt(0)
; __device__ __forceinline__ unsigned f2bf(float f) { return pk2(f, f) & 0xffffu; }
; __device__ __forceinline__ void phase_branch() {
;     ...
;           unsigned short gv[4][2][2], tv[4][2][2];
; #pragma unroll
;           for (int j = 0; j < 4; ++j)
; #pragma unroll
;             for (int bj = 0; bj < 2; ++bj)
; #pragma unroll
;               for (int n = 0; n < 2; ++n) {
;                 const size_t idx = (size_t)(brow + ai * 128 + wr * 64 + m * 16 + fq * 4 + j) * DM + bcol + bj * 128 + wc * 32 + n * 16 + fr;
;                 gv[j][bj][n] = sg[idx]; tv[j][bj][n] = tmpb[idx];
;               }
; #pragma unroll
;           for (int j = 0; j < 4; ++j) {
;             const int row = brow + ai * 128 + wr * 64 + m * 16 + fq * 4 + j;
; #pragma unroll
;             for (int bj = 0; bj < 2; ++bj)
; #pragma unroll
;               for (int n = 0; n < 2; ++n) {
;                 const size_t idx = (size_t)row * DM + bcol + bj * 128 + wc * 32 + n * 16 + fr;
;                 merged[idx] = (unsigned short)f2bf(bf2f(gv[j][bj][n]) * acc[ai][bj][m][n][j] + bf2f(tv[j][bj][n]));
;               }
	v_lshlrev_b32_e32 v20, 16, v26
	v_lshlrev_b32_e32 v21, 16, v36
	v_fmac_f32_e32 v21, v25, v20
	v_cvt_pk_bf16_f32 v20, v21, v21
	global_store_short v[18:19], v20, off offset:288
	v_add_u32_e32 v18, 0xb0, v136
	v_ashrrev_i32_e32 v19, 31, v18
	v_lshlrev_b64 v[20:21], 10, v[18:19]
	v_lshl_add_u64 v[20:21], v[20:21], 0, v[134:135]
	v_lshlrev_b64 v[20:21], 1, v[20:21]
	v_lshl_add_u64 v[22:23], s[8:9], 0, v[20:21]
	v_lshl_add_u64 v[24:25], s[4:5], 0, v[20:21]
	global_load_ushort v44, v[22:23], off
	global_load_ushort v45, v[24:25], off
	v_or_b32_e32 v26, 32, v20
	v_mov_b32_e32 v27, v21
	v_lshl_add_u64 v[28:29], s[8:9], 0, v[26:27]
	v_lshl_add_u64 v[26:27], s[4:5], 0, v[26:27]
	v_or_b32_e32 v30, 0x100, v20
	v_mov_b32_e32 v31, v21
	v_add_u32_e32 v36, 0xb1, v136
	global_load_ushort v46, v[28:29], off
	global_load_ushort v47, v[26:27], off
	v_lshl_add_u64 v[32:33], s[8:9], 0, v[30:31]
	v_ashrrev_i32_e32 v37, 31, v36
	v_lshl_add_u64 v[30:31], s[4:5], 0, v[30:31]
	v_or_b32_e32 v20, 0x120, v20
	v_lshlrev_b64 v[38:39], 10, v[36:37]
	global_load_ushort v48, v[32:33], off
	global_load_ushort v49, v[30:31], off
	v_lshl_add_u64 v[34:35], s[8:9], 0, v[20:21]
	v_lshl_add_u64 v[38:39], v[38:39], 0, v[134:135]
	v_lshl_add_u64 v[20:21], s[4:5], 0, v[20:21]
	v_lshlrev_b64 v[38:39], 1, v[38:39]
	global_load_ushort v50, v[34:35], off
	global_load_ushort v51, v[20:21], off
	v_lshl_add_u64 v[40:41], s[8:9], 0, v[38:39]
	v_lshl_add_u64 v[22:23], s[4:5], 0, v[38:39]
	v_or_b32_e32 v24, 32, v38
	v_mov_b32_e32 v25, v39
	global_load_ushort v52, v[40:41], off
	global_load_ushort v53, v[22:23], off
	v_lshl_add_u64 v[42:43], s[8:9], 0, v[24:25]
	v_lshl_add_u64 v[24:25], s[4:5], 0, v[24:25]
	v_or_b32_e32 v26, 0x100, v38
	v_mov_b32_e32 v27, v39
	v_add_u32_e32 v32, 0xb2, v136
	global_load_ushort v54, v[42:43], off
	global_load_ushort v55, v[24:25], off
	v_lshl_add_u64 v[28:29], s[8:9], 0, v[26:27]
	v_ashrrev_i32_e32 v33, 31, v32
	v_lshl_add_u64 v[26:27], s[4:5], 0, v[26:27]
	v_or_b32_e32 v38, 0x120, v38
	v_lshlrev_b64 v[34:35], 10, v[32:33]
	global_load_ushort v42, v[28:29], off
	global_load_ushort v43, v[26:27], off
	v_lshl_add_u64 v[30:31], s[8:9], 0, v[38:39]
	v_lshl_add_u64 v[34:35], v[34:35], 0, v[134:135]
	v_lshl_add_u64 v[20:21], s[4:5], 0, v[38:39]
	v_lshlrev_b64 v[22:23], 1, v[34:35]
	global_load_ushort v56, v[30:31], off
	global_load_ushort v57, v[20:21], off
	v_lshl_add_u64 v[34:35], s[8:9], 0, v[22:23]
	v_lshl_add_u64 v[38:39], s[4:5], 0, v[22:23]
	v_or_b32_e32 v24, 32, v22
	v_mov_b32_e32 v25, v23
	global_load_ushort v58, v[34:35], off
	global_load_ushort v59, v[38:39], off
	v_lshl_add_u64 v[40:41], s[8:9], 0, v[24:25]
	v_lshl_add_u64 v[24:25], s[4:5], 0, v[24:25]
	v_or_b32_e32 v26, 0x100, v22
	v_mov_b32_e32 v27, v23
	v_add_u32_e32 v30, 0xb3, v136
	global_load_ushort v60, v[40:41], off
	global_load_ushort v61, v[24:25], off
	v_lshl_add_u64 v[20:21], s[8:9], 0, v[26:27]
	v_ashrrev_i32_e32 v31, 31, v30
	v_lshl_add_u64 v[26:27], s[4:5], 0, v[26:27]
	v_or_b32_e32 v22, 0x120, v22
	v_lshlrev_b64 v[34:35], 10, v[30:31]
	global_load_ushort v40, v[20:21], off
	global_load_ushort v41, v[26:27], off
	v_lshl_add_u64 v[28:29], s[8:9], 0, v[22:23]
	v_lshl_add_u64 v[24:25], v[34:35], 0, v[134:135]
	v_lshl_add_u64 v[22:23], s[4:5], 0, v[22:23]
	v_lshlrev_b64 v[24:25], 1, v[24:25]
	global_load_ushort v62, v[28:29], off
	global_load_ushort v63, v[22:23], off
	v_lshl_add_u64 v[34:35], s[8:9], 0, v[24:25]
	v_lshl_add_u64 v[20:21], s[4:5], 0, v[24:25]
	v_or_b32_e32 v26, 32, v24
	v_mov_b32_e32 v27, v25
	global_load_ushort v64, v[34:35], off
	global_load_ushort v65, v[20:21], off
	v_lshl_add_u64 v[22:23], s[8:9], 0, v[26:27]
	v_lshl_add_u64 v[26:27], s[4:5], 0, v[26:27]
	v_or_b32_e32 v28, 0x100, v24
	v_mov_b32_e32 v29, v25
	global_load_ushort v34, v[22:23], off
	global_load_ushort v35, v[26:27], off
	v_lshl_add_u64 v[38:39], s[8:9], 0, v[28:29]
	v_or_b32_e32 v24, 0x120, v24
	v_lshl_add_u64 v[20:21], s[4:5], 0, v[28:29]
	v_lshl_add_u64 v[28:29], s[8:9], 0, v[24:25]
	v_lshl_add_u64 v[22:23], s[4:5], 0, v[24:25]
	global_load_ushort v24, v[38:39], off
	global_load_ushort v25, v[20:21], off
	s_waitcnt vmcnt(0)
; __device__ __forceinline__ unsigned f2bf(float f) { return pk2(f, f) & 0xffffu; }
; __device__ __forceinline__ void phase_branch() {
;     ...
;           unsigned short gv[4][2][2], tv[4][2][2];
; #pragma unroll
;           for (int j = 0; j < 4; ++j)
; #pragma unroll
;             for (int bj = 0; bj < 2; ++bj)
; #pragma unroll
;               for (int n = 0; n < 2; ++n) {
;                 const size_t idx = (size_t)(brow + ai * 128 + wr * 64 + m * 16 + fq * 4 + j) * DM + bcol + bj * 128 + wc * 32 + n * 16 + fr;
;                 gv[j][bj][n] = sg[idx]; tv[j][bj][n] = tmpb[idx];
;               }
; #pragma unroll
;           for (int j = 0; j < 4; ++j) {
;             const int row = brow + ai * 128 + wr * 64 + m * 16 + fq * 4 + j;
; #pragma unroll
;             for (int bj = 0; bj < 2; ++bj)
; #pragma unroll
;               for (int n = 0; n < 2; ++n) {
;                 const size_t idx = (size_t)row * DM + bcol + bj * 128 + wc * 32 + n * 16 + fr;
;                 merged[idx] = (unsigned short)f2bf(bf2f(gv[j][bj][n]) * acc[ai][bj][m][n][j] + bf2f(tv[j][bj][n]));
;               }
	v_lshlrev_b32_e32 v20, 16, v44
	v_lshlrev_b32_e32 v21, 16, v45
	v_fmac_f32_e32 v21, v10, v20
	global_load_ushort v10, v[28:29], off
	global_load_ushort v20, v[22:23], off
	v_lshlrev_b64 v[18:19], 11, v[18:19]
	v_lshl_add_u64 v[18:19], v[132:133], 0, v[18:19]
	v_cvt_pk_bf16_f32 v21, v21, v21
	global_store_short v[18:19], v21, off
	v_lshlrev_b32_e32 v21, 16, v46
	v_lshlrev_b32_e32 v22, 16, v47
	v_fmac_f32_e32 v22, v2, v21
	v_cvt_pk_bf16_f32 v2, v22, v22
	global_store_short v[18:19], v2, off offset:32
	v_lshlrev_b32_e32 v2, 16, v48
	v_lshlrev_b32_e32 v21, 16, v49
	v_fmac_f32_e32 v21, v14, v2
	v_cvt_pk_bf16_f32 v2, v21, v21
	global_store_short v[18:19], v2, off offset:256
	v_lshlrev_b32_e32 v2, 16, v50
	v_lshlrev_b32_e32 v14, 16, v51
	v_fmac_f32_e32 v14, v6, v2
	v_cvt_pk_bf16_f32 v2, v14, v14
	global_store_short v[18:19], v2, off offset:288
	v_lshlrev_b64 v[18:19], 11, v[36:37]
	v_lshlrev_b32_e32 v2, 16, v52
	v_lshlrev_b32_e32 v6, 16, v53
	v_lshl_add_u64 v[18:19], v[132:133], 0, v[18:19]
	v_fmac_f32_e32 v6, v11, v2
	v_cvt_pk_bf16_f32 v2, v6, v6
	global_store_short v[18:19], v2, off
	v_lshlrev_b32_e32 v2, 16, v54
	v_lshlrev_b32_e32 v6, 16, v55
	v_fmac_f32_e32 v6, v3, v2
	v_cvt_pk_bf16_f32 v2, v6, v6
	global_store_short v[18:19], v2, off offset:32
	v_lshlrev_b32_e32 v2, 16, v42
	v_lshlrev_b32_e32 v3, 16, v43
	v_fmac_f32_e32 v3, v15, v2
	v_cvt_pk_bf16_f32 v2, v3, v3
	global_store_short v[18:19], v2, off offset:256
	v_lshlrev_b32_e32 v2, 16, v56
	v_lshlrev_b32_e32 v3, 16, v57
	v_fmac_f32_e32 v3, v7, v2
	v_cvt_pk_bf16_f32 v2, v3, v3
	global_store_short v[18:19], v2, off offset:288
	v_lshlrev_b64 v[2:3], 11, v[32:33]
	v_lshlrev_b32_e32 v6, 16, v58
	v_lshlrev_b32_e32 v7, 16, v59
	v_lshl_add_u64 v[2:3], v[132:133], 0, v[2:3]
	v_fmac_f32_e32 v7, v12, v6
	v_cvt_pk_bf16_f32 v6, v7, v7
	global_store_short v[2:3], v6, off
	v_lshlrev_b32_e32 v6, 16, v60
	v_lshlrev_b32_e32 v7, 16, v61
	v_fmac_f32_e32 v7, v4, v6
	v_cvt_pk_bf16_f32 v4, v7, v7
	global_store_short v[2:3], v4, off offset:32
	v_lshlrev_b32_e32 v4, 16, v40
	v_lshlrev_b32_e32 v6, 16, v41
	v_fmac_f32_e32 v6, v16, v4
	v_cvt_pk_bf16_f32 v4, v6, v6
	global_store_short v[2:3], v4, off offset:256
	v_lshlrev_b32_e32 v4, 16, v62
	v_lshlrev_b32_e32 v6, 16, v63
	v_fmac_f32_e32 v6, v8, v4
	v_cvt_pk_bf16_f32 v4, v6, v6
	global_store_short v[2:3], v4, off offset:288
	v_lshlrev_b64 v[2:3], 11, v[30:31]
	v_lshlrev_b32_e32 v4, 16, v64
	v_lshlrev_b32_e32 v6, 16, v65
	v_lshl_add_u64 v[2:3], v[132:133], 0, v[2:3]
	v_fmac_f32_e32 v6, v13, v4
	v_cvt_pk_bf16_f32 v4, v6, v6
	global_store_short v[2:3], v4, off
	v_lshlrev_b32_e32 v4, 16, v34
	v_lshlrev_b32_e32 v6, 16, v35
	v_fmac_f32_e32 v6, v5, v4
	v_cvt_pk_bf16_f32 v4, v6, v6
	global_store_short v[2:3], v4, off offset:32
	v_lshlrev_b32_e32 v4, 16, v24
	v_lshlrev_b32_e32 v5, 16, v25
	v_fmac_f32_e32 v5, v17, v4
	v_cvt_pk_bf16_f32 v4, v5, v5
	global_store_short v[2:3], v4, off offset:256
	s_waitcnt vmcnt(0)
	v_lshlrev_b32_e32 v4, 16, v10
	v_lshlrev_b32_e32 v5, 16, v20
	s_andn2_b64 vcc, exec, s[20:21]
	v_fmac_f32_e32 v5, v9, v4
	v_cvt_pk_bf16_f32 v4, v5, v5
	global_store_short v[2:3], v4, off offset:288
	s_cbranch_vccz .LBB0_720

; #define GAS __attribute__((address_space(1)))
; __device__ __forceinline__ unsigned f2bf(float f) { return pk2(f, f) & 0xffffu; }
; #define STAGE(P, GP, ktrel) do { const GAS char* _g = (GP) + (ktrel) * (BK * 2); \
;     __builtin_amdgcn_global_load_lds((const GAS unsigned*)(_g + so0), (unsigned*)((char*)(P) + tid_ * 16), 16, 0, 0); \
;     __builtin_amdgcn_global_load_lds((const GAS unsigned*)(_g + so1), (unsigned*)((char*)(P) + tid_ * 16 + 8192), 16, 0, 0); } while (0)
; template <int K, int LD = K>
; __device__ __forceinline__ void gemm_prefetch(const GAS bf16* A, const GAS bf16* Bt, int brow, int bcol) {
;     ...
;   { int r_, c_; stage_rc(tid_ * 16, r_, c_); so0 = (unsigned)(r_ * LD + c_) * 2u; stage_rc(tid_ * 16 + 8192, r_, c_); so1 = (unsigned)(r_ * LD + c_) * 2u; }
;   const GAS char* pA0 = (const GAS char*)A + (long)brow * LD * 2; const GAS char* pA1 = pA0 + (long)HALF * LD * 2;
;   const GAS char* pB0 = (const GAS char*)Bt + (long)bcol * LD * 2; const GAS char* pB1 = pB0 + (long)HALF * LD * 2;
;   asm volatile("" : "+s"(pA0), "+s"(pA1), "+s"(pB0), "+s"(pB1));
;   STAGE(SB(0, 0), pB0, 0); STAGE(SA(0, 0), pA0, 0);
;   STAGE(SB(0, 1), pB1, 0); STAGE(SA(0, 1), pA1, 0);
;   STAGE(SB(1, 0), pB0, 1); STAGE(SA(1, 0), pA0, 1); STAGE(SB(1, 1), pB1, 1);
; __device__ __forceinline__ void phase_branch() {
;     ...
;       const GAS unsigned short* sg = (const GAS unsigned short*)(ws + OFF_SGF);
; #pragma unroll
;       for (int ai = 0; ai < 2; ++ai)
; #pragma unroll
;         for (int m = 0; m < 4; ++m) {
;           unsigned short gv[4][2][2];
; #pragma unroll
;           for (int j = 0; j < 4; ++j)
; #pragma unroll
;             for (int bj = 0; bj < 2; ++bj)
; #pragma unroll
;               for (int n = 0; n < 2; ++n)
;                 gv[j][bj][n] = sg[(size_t)(brow + ai * 128 + wr * 64 + m * 16 + fq * 4 + j) * DM + bcol + bj * 128 + wc * 32 + n * 16 + fr];
; #pragma unroll
;           for (int j = 0; j < 4; ++j) {
;             const int row = brow + ai * 128 + wr * 64 + m * 16 + fq * 4 + j;
; #pragma unroll
;             for (int bj = 0; bj < 2; ++bj)
; #pragma unroll
;               for (int n = 0; n < 2; ++n) {
;                 const size_t idx = (size_t)row * DM + bcol + bj * 128 + wc * 32 + n * 16 + fr;
;                 tmpb[idx] = (unsigned short)f2bf(bf2f(gv[j][bj][n]) * acc[ai][bj][m][n][j]);
.LBB0_712:
	s_or_b64 exec, exec, s[20:21]
	v_mov_b32_e32 v130, v170
	s_add_u32 s24, s39, s18
	v_ashrrev_i32_e32 v132, 31, v130
	v_lshrrev_b32_e32 v132, 26, v132
	v_lshlrev_b32_e32 v146, 4, v130
	v_add_u32_e32 v132, v130, v132
	v_bfe_i32 v130, v130, 27, 1
	v_lshrrev_b32_e32 v130, 22, v130
	v_add_u32_e32 v130, v146, v130
	v_and_b32_e32 v130, 0xfffffc00, v130
	v_sub_u32_e32 v130, v146, v130
	v_lshrrev_b32_e32 v133, 4, v130
	v_bitop3_b32 v133, v133, v130, 32 bitop3:0x6c
	v_ashrrev_i32_e32 v130, 31, v130
	v_lshrrev_b32_e32 v130, 26, v130
	v_add_u32_e32 v130, v133, v130
	v_ashrrev_i32_e32 v130, 6, v130
	v_ashrrev_i32_e32 v132, 6, v132
	v_mul_i32_i24_e32 v135, 64, v130
	v_lshlrev_b32_e32 v134, 3, v132
	v_lshlrev_b32_e32 v132, 5, v132
	v_sub_u32_e32 v133, v133, v135
	v_and_b32_e32 v134, 0x3ffff0, v134
	v_and_b32_e32 v132, 32, v132
	v_ashrrev_i16_sdwa v133, v1, sext(v133) dst_sel:DWORD dst_unused:UNUSED_PAD src0_sel:DWORD src1_sel:BYTE_0
	v_add_u32_sdwa v132, v132, sext(v133) dst_sel:DWORD dst_unused:UNUSED_PAD src0_sel:DWORD src1_sel:WORD_0
	v_add_lshl_u32 v130, v130, v134, 10
	v_lshl_add_u32 v130, v132, 1, v130
	v_add_u32_e32 v132, 0x2000, v146
	v_ashrrev_i32_e32 v133, 31, v132
	v_lshrrev_b32_e32 v133, 22, v133
	v_add_u32_e32 v133, v132, v133
	v_ashrrev_i32_e32 v133, 10, v133
	v_mul_i32_i24_e32 v134, 0x400, v133
	v_sub_u32_e32 v132, v132, v134
	v_lshrrev_b32_e32 v134, 4, v132
	v_bitop3_b32 v132, v134, v132, 32 bitop3:0x6c
	s_addc_u32 s25, s40, s19
	v_ashrrev_i32_e32 v135, 31, v132
	s_add_u32 s20, s24, 0x20000
	v_lshrrev_b32_e32 v135, 26, v135
	s_addc_u32 s21, s25, 0
	v_add_u32_e32 v135, v132, v135
	s_add_u32 s26, s41, s22
	v_lshrrev_b32_e32 v136, 6, v135
	v_and_b32_e32 v135, 0xc0, v135
	s_addc_u32 s27, s42, s23
	v_lshlrev_b32_e32 v134, 3, v133
	v_lshlrev_b32_e32 v133, 5, v133
	v_sub_u32_e32 v132, v132, v135
	s_add_u32 s22, s26, 0x20000
	v_add_u32_e32 v138, s47, v146
	v_and_b32_e32 v134, 0x3ffff0, v134
	v_and_b32_e32 v133, 32, v133
	v_ashrrev_i16_sdwa v132, v1, sext(v132) dst_sel:DWORD dst_unused:UNUSED_PAD src0_sel:DWORD src1_sel:BYTE_0
	s_addc_u32 s23, s27, 0
	v_readfirstlane_b32 s17, v138
	v_add_u32_e32 v138, 0x2000, v138
	v_add_u32_sdwa v132, v133, sext(v132) dst_sel:DWORD dst_unused:UNUSED_PAD src0_sel:DWORD src1_sel:WORD_0
	v_add_lshl_u32 v133, v136, v134, 10
	s_mov_b64 s[18:19], s[22:23]
	s_mov_b64 s[28:29], s[24:25]
	s_mov_b64 s[30:31], s[26:27]
	s_mov_b64 s[44:45], s[20:21]
	s_mov_b32 m0, s17
	v_readfirstlane_b32 s17, v138
	v_add_u32_e32 v147, 0x100, v146
	v_lshl_add_u32 v132, v132, 1, v133
	v_add_u32_e32 v142, 0x2000, v147
	global_load_lds_dwordx4 v130, s[30:31]
	s_mov_b32 m0, s17
	v_readfirstlane_b32 s17, v147
	v_mov_b32_e32 v133, v131
	global_load_lds_dwordx4 v132, s[30:31]
	s_mov_b32 m0, s17
	v_readfirstlane_b32 s17, v142
	v_add_u32_e32 v148, s48, v146
	v_lshl_add_u64 v[136:137], s[30:31], 0, v[132:133]
	global_load_lds_dwordx4 v130, s[28:29]
	v_lshl_add_u64 v[140:141], s[28:29], 0, v[132:133]
	s_mov_b32 m0, s17
	v_readfirstlane_b32 s17, v148
	v_lshl_add_u64 v[144:145], s[18:19], 0, v[132:133]
	v_add_u32_e32 v133, 0x2000, v148
	global_load_lds_dwordx4 v132, s[28:29]
	s_mov_b32 m0, s17
	v_readfirstlane_b32 s17, v133
	v_add_u32_e32 v133, 0x4000, v147
	global_load_lds_dwordx4 v130, s[18:19]
	s_mov_b32 m0, s17
	v_readfirstlane_b32 s17, v133
	global_load_lds_dwordx4 v132, s[18:19]
	s_mov_b32 m0, s17
	v_lshl_add_u64 v[134:135], s[30:31], 0, v[130:131]
	v_lshl_add_u64 v[138:139], s[28:29], 0, v[130:131]
	v_lshl_add_u64 v[142:143], s[18:19], 0, v[130:131]
	global_load_lds_dwordx4 v130, s[44:45]
	v_add_u32_e32 v130, 0x6000, v147
	s_lshl_b64 s[18:19], s[14:15], 1
	v_readfirstlane_b32 s17, v130
	v_add_u32_e32 v130, s49, v146
	s_mov_b32 m0, s17
	v_readfirstlane_b32 s17, v130
	v_add_u32_e32 v130, 0x2000, v130
	global_load_lds_dwordx4 v132, s[44:45]
	v_lshl_add_u64 v[132:133], v[134:135], 0, s[6:7]
	s_mov_b32 m0, s17
	v_readfirstlane_b32 s17, v130
	v_add_u32_e32 v130, 0x8000, v147
	global_load_lds_dwordx4 v[132:133], off
	v_lshl_add_u64 v[132:133], v[136:137], 0, s[6:7]
	s_mov_b32 m0, s17
	v_readfirstlane_b32 s17, v130
	v_add_u32_e32 v130, 0xa000, v147
	global_load_lds_dwordx4 v[132:133], off
	v_lshl_add_u64 v[132:133], v[138:139], 0, s[6:7]
	s_mov_b32 m0, s17
	v_readfirstlane_b32 s17, v130
	v_add_u32_e32 v130, s50, v146
	global_load_lds_dwordx4 v[132:133], off
	v_lshl_add_u64 v[132:133], v[140:141], 0, s[6:7]
	s_mov_b32 m0, s17
	v_readfirstlane_b32 s17, v130
	v_add_u32_e32 v130, 0x2000, v130
	global_load_lds_dwordx4 v[132:133], off
	v_lshl_add_u64 v[132:133], v[142:143], 0, s[6:7]
	s_mov_b32 m0, s17
	v_readfirstlane_b32 s17, v130
	global_load_lds_dwordx4 v[132:133], off
	v_lshl_add_u64 v[132:133], v[144:145], 0, s[6:7]
	s_mov_b32 m0, s17
	v_mov_b32_e32 v130, v170
	global_load_lds_dwordx4 v[132:133], off
	s_add_u32 s28, s52, s18
	v_ashrrev_i32_e32 v132, 2, v130
	v_and_b32_e32 v132, 0xffffffc0, v132
	v_add_u32_e32 v132, s16, v132
	v_lshrrev_b32_e32 v134, 2, v130
	v_and_b32_e32 v133, 15, v130
	v_and_or_b32 v132, v134, 12, v132
	s_addc_u32 s29, s53, s19
	v_and_b32_e32 v130, 0xc0, v130
	v_lshl_add_u64 v[134:135], s[28:29], 0, v[130:131]
	v_lshlrev_b32_e32 v138, 1, v133
	v_mov_b32_e32 v139, v131
	v_ashrrev_i32_e32 v133, 31, v132
	v_lshl_add_u64 v[136:137], v[134:135], 0, v[138:139]
	v_lshlrev_b64 v[140:141], 11, v[132:133]
	v_lshl_add_u64 v[134:135], v[136:137], 0, v[140:141]
	global_load_ushort v133, v[134:135], off
	global_load_ushort v150, v[134:135], off offset:32
	global_load_ushort v151, v[134:135], off offset:256
	global_load_ushort v152, v[134:135], off offset:288
	v_or_b32_e32 v134, 1, v132
	v_ashrrev_i32_e32 v135, 31, v134
	v_lshlrev_b64 v[142:143], 11, v[134:135]
	v_lshl_add_u64 v[134:135], v[136:137], 0, v[142:143]
	global_load_ushort v153, v[134:135], off
	global_load_ushort v154, v[134:135], off offset:32
	global_load_ushort v155, v[134:135], off offset:256
	global_load_ushort v156, v[134:135], off offset:288
	v_or_b32_e32 v134, 2, v132
	v_ashrrev_i32_e32 v135, 31, v134
	v_lshlrev_b64 v[144:145], 11, v[134:135]
	v_lshl_add_u64 v[134:135], v[136:137], 0, v[144:145]
	global_load_ushort v157, v[134:135], off
	global_load_ushort v158, v[134:135], off offset:32
	global_load_ushort v159, v[134:135], off offset:256
	global_load_ushort v160, v[134:135], off offset:288
	v_or_b32_e32 v134, 3, v132
	v_ashrrev_i32_e32 v135, 31, v134
	v_lshlrev_b64 v[146:147], 11, v[134:135]
	v_lshl_add_u64 v[148:149], v[136:137], 0, v[146:147]
	global_load_ushort v161, v[148:149], off
	s_add_u32 s28, s4, s18
	s_addc_u32 s29, s5, s19
	v_lshl_add_u64 v[134:135], s[28:29], 0, v[130:131]
	v_lshl_add_u64 v[134:135], v[134:135], 0, v[138:139]
	v_lshl_add_u64 v[138:139], v[134:135], 0, v[140:141]
	v_or_b32_e32 v140, 16, v132
	v_ashrrev_i32_e32 v141, 31, v140
	v_lshlrev_b64 v[140:141], 11, v[140:141]
	s_waitcnt vmcnt(0)
; #define GAS __attribute__((address_space(1)))
; __device__ __forceinline__ unsigned f2bf(float f) { return pk2(f, f) & 0xffffu; }
; __device__ __forceinline__ void phase_branch() {
;     ...
;       const GAS unsigned short* sg = (const GAS unsigned short*)(ws + OFF_SGF);
; #pragma unroll
;       for (int ai = 0; ai < 2; ++ai)
; #pragma unroll
;         for (int m = 0; m < 4; ++m) {
;           unsigned short gv[4][2][2];
; #pragma unroll
;           for (int j = 0; j < 4; ++j)
; #pragma unroll
;             for (int bj = 0; bj < 2; ++bj)
; #pragma unroll
;               for (int n = 0; n < 2; ++n)
;                 gv[j][bj][n] = sg[(size_t)(brow + ai * 128 + wr * 64 + m * 16 + fq * 4 + j) * DM + bcol + bj * 128 + wc * 32 + n * 16 + fr];
; #pragma unroll
;           for (int j = 0; j < 4; ++j) {
;             const int row = brow + ai * 128 + wr * 64 + m * 16 + fq * 4 + j;
; #pragma unroll
;             for (int bj = 0; bj < 2; ++bj)
; #pragma unroll
;               for (int n = 0; n < 2; ++n) {
;                 const size_t idx = (size_t)row * DM + bcol + bj * 128 + wc * 32 + n * 16 + fr;
;                 tmpb[idx] = (unsigned short)f2bf(bf2f(gv[j][bj][n]) * acc[ai][bj][m][n][j]);
	v_lshlrev_b32_e32 v130, 16, v133
	global_load_ushort v133, v[148:149], off offset:32
	v_mul_f32_e32 v118, v118, v130
	global_load_ushort v130, v[148:149], off offset:256
	global_load_ushort v162, v[148:149], off offset:288
	v_cvt_pk_bf16_f32 v118, v118, v118
	global_store_short v[138:139], v118, off
	v_lshlrev_b32_e32 v118, 16, v150
	v_mul_f32_e32 v114, v114, v118
	v_cvt_pk_bf16_f32 v114, v114, v114
	global_store_short v[138:139], v114, off offset:32
	v_lshlrev_b32_e32 v114, 16, v151
	v_mul_f32_e32 v114, v126, v114
	v_cvt_pk_bf16_f32 v114, v114, v114
	global_store_short v[138:139], v114, off offset:256
	v_lshlrev_b32_e32 v114, 16, v152
	v_mul_f32_e32 v114, v122, v114
	v_lshlrev_b32_e32 v122, 16, v156
	v_mul_f32_e32 v122, v123, v122
	v_lshlrev_b32_e32 v126, 16, v157
	v_cvt_pk_bf16_f32 v114, v114, v114
	global_store_short v[138:139], v114, off offset:288
	v_lshl_add_u64 v[138:139], v[134:135], 0, v[142:143]
	v_cvt_pk_bf16_f32 v122, v122, v122
	v_mul_f32_e32 v120, v120, v126
	v_lshl_add_u64 v[148:149], v[136:137], 0, v[140:141]
	global_store_short v[138:139], v122, off offset:288
	v_lshl_add_u64 v[122:123], v[134:135], 0, v[144:145]
	v_cvt_pk_bf16_f32 v120, v120, v120
	global_load_ushort v150, v[148:149], off
	global_load_ushort v142, v[148:149], off offset:32
	global_load_ushort v143, v[148:149], off offset:256
	v_lshlrev_b32_e32 v114, 16, v153
	global_store_short v[122:123], v120, off
	v_lshlrev_b32_e32 v120, 16, v158
	v_mul_f32_e32 v116, v116, v120
	v_cvt_pk_bf16_f32 v116, v116, v116
	v_mul_f32_e32 v114, v119, v114
	global_store_short v[122:123], v116, off offset:32
	v_lshlrev_b32_e32 v116, 16, v159
	v_cvt_pk_bf16_f32 v114, v114, v114
	v_mul_f32_e32 v116, v128, v116
	global_store_short v[138:139], v114, off
	v_lshlrev_b32_e32 v114, 16, v154
	v_cvt_pk_bf16_f32 v116, v116, v116
	v_mul_f32_e32 v114, v115, v114
	global_store_short v[122:123], v116, off offset:256
	v_lshlrev_b32_e32 v116, 16, v160
	v_cvt_pk_bf16_f32 v114, v114, v114
	v_mul_f32_e32 v116, v124, v116
	global_store_short v[138:139], v114, off offset:32
	v_lshlrev_b32_e32 v114, 16, v155
	v_cvt_pk_bf16_f32 v116, v116, v116
	v_mul_f32_e32 v114, v127, v114
	global_store_short v[122:123], v116, off offset:288
	v_lshlrev_b32_e32 v116, 16, v161
	v_cvt_pk_bf16_f32 v114, v114, v114
	v_mul_f32_e32 v116, v121, v116
	global_store_short v[138:139], v114, off offset:256
	v_or_b32_e32 v114, 17, v132
	v_lshl_add_u64 v[122:123], v[134:135], 0, v[146:147]
	v_cvt_pk_bf16_f32 v116, v116, v116
	global_load_ushort v148, v[148:149], off offset:288
	v_ashrrev_i32_e32 v115, 31, v114
	global_store_short v[122:123], v116, off
	v_lshlrev_b64 v[114:115], 11, v[114:115]
	v_lshl_add_u64 v[118:119], v[136:137], 0, v[114:115]
	global_load_ushort v149, v[118:119], off
	global_load_ushort v138, v[118:119], off offset:32
	global_load_ushort v139, v[118:119], off offset:256
	global_load_ushort v144, v[118:119], off offset:288
	v_lshl_add_u64 v[114:115], v[134:135], 0, v[114:115]
	s_waitcnt vmcnt(0)
	v_lshlrev_b32_e32 v116, 16, v133
	v_mul_f32_e32 v116, v117, v116
	v_cvt_pk_bf16_f32 v116, v116, v116
	global_store_short v[122:123], v116, off offset:32
	v_or_b32_e32 v116, 19, v132
	v_ashrrev_i32_e32 v117, 31, v116
	v_lshlrev_b64 v[116:117], 11, v[116:117]
	v_lshl_add_u64 v[120:121], v[136:137], 0, v[116:117]
	v_lshlrev_b32_e32 v124, 16, v130
	v_mul_f32_e32 v124, v129, v124
	global_load_ushort v129, v[120:121], off offset:32
	v_or_b32_e32 v118, 18, v132
	v_ashrrev_i32_e32 v119, 31, v118
	v_lshlrev_b64 v[118:119], 11, v[118:119]
	v_lshl_add_u64 v[126:127], v[136:137], 0, v[118:119]
	global_load_ushort v128, v[126:127], off
	global_load_ushort v145, v[126:127], off offset:32
	global_load_ushort v146, v[126:127], off offset:256
	v_cvt_pk_bf16_f32 v124, v124, v124
	global_load_ushort v126, v[126:127], off offset:288
	s_nop 0
	global_load_ushort v127, v[120:121], off
	s_nop 0
	global_store_short v[122:123], v124, off offset:256
	v_lshlrev_b32_e32 v124, 16, v162
	v_mul_f32_e32 v124, v125, v124
	v_cvt_pk_bf16_f32 v124, v124, v124
	global_store_short v[122:123], v124, off offset:288
	global_load_ushort v130, v[120:121], off offset:256
	global_load_ushort v133, v[120:121], off offset:288
	v_lshlrev_b32_e32 v124, 16, v150
	v_mul_f32_e32 v102, v102, v124
	v_lshl_add_u64 v[122:123], v[134:135], 0, v[140:141]
	v_cvt_pk_bf16_f32 v102, v102, v102
	global_store_short v[122:123], v102, off
	v_lshlrev_b32_e32 v102, 16, v142
	v_or_b32_e32 v120, 32, v132
	v_mul_f32_e32 v98, v98, v102
	v_ashrrev_i32_e32 v121, 31, v120
	v_cvt_pk_bf16_f32 v98, v98, v98
	v_lshlrev_b64 v[120:121], 11, v[120:121]
	global_store_short v[122:123], v98, off offset:32
	v_lshlrev_b32_e32 v98, 16, v143
	v_lshl_add_u64 v[124:125], v[136:137], 0, v[120:121]
	v_mul_f32_e32 v98, v110, v98
	global_load_ushort v110, v[124:125], off
	v_cvt_pk_bf16_f32 v98, v98, v98
	global_store_short v[122:123], v98, off offset:256
	v_lshlrev_b32_e32 v98, 16, v148
	v_mul_f32_e32 v98, v106, v98
	v_cvt_pk_bf16_f32 v98, v98, v98
	global_store_short v[122:123], v98, off offset:288
	global_load_ushort v122, v[124:125], off offset:32
	v_lshlrev_b32_e32 v98, 16, v149
	v_mul_f32_e32 v98, v103, v98
	v_cvt_pk_bf16_f32 v98, v98, v98
	global_store_short v[114:115], v98, off
	v_lshlrev_b32_e32 v98, 16, v138
	v_mul_f32_e32 v98, v99, v98
	v_cvt_pk_bf16_f32 v98, v98, v98
	global_store_short v[114:115], v98, off offset:32
	v_lshlrev_b32_e32 v98, 16, v139
	v_lshlrev_b32_e32 v106, 16, v144
	v_mul_f32_e32 v98, v111, v98
	v_mul_f32_e32 v106, v107, v106
	v_cvt_pk_bf16_f32 v98, v98, v98
	global_store_short v[114:115], v98, off offset:256
	v_cvt_pk_bf16_f32 v106, v106, v106
	global_store_short v[114:115], v106, off offset:288
	v_lshl_add_u64 v[106:107], v[134:135], 0, v[118:119]
	v_or_b32_e32 v98, 33, v132
	v_ashrrev_i32_e32 v99, 31, v98
	v_lshlrev_b64 v[98:99], 11, v[98:99]
	v_lshl_add_u64 v[102:103], v[136:137], 0, v[98:99]
	global_load_ushort v111, v[102:103], off
	global_load_ushort v114, v[102:103], off offset:32
	global_load_ushort v123, v[124:125], off offset:256
	v_lshl_add_u64 v[98:99], v[134:135], 0, v[98:99]
	s_waitcnt vmcnt(0)
; #define GAS __attribute__((address_space(1)))
; __device__ __forceinline__ unsigned f2bf(float f) { return pk2(f, f) & 0xffffu; }
; __device__ __forceinline__ void phase_branch() {
;     ...
;       const GAS unsigned short* sg = (const GAS unsigned short*)(ws + OFF_SGF);
; #pragma unroll
;       for (int ai = 0; ai < 2; ++ai)
; #pragma unroll
;         for (int m = 0; m < 4; ++m) {
;           unsigned short gv[4][2][2];
; #pragma unroll
;           for (int j = 0; j < 4; ++j)
; #pragma unroll
;             for (int bj = 0; bj < 2; ++bj)
; #pragma unroll
;               for (int n = 0; n < 2; ++n)
;                 gv[j][bj][n] = sg[(size_t)(brow + ai * 128 + wr * 64 + m * 16 + fq * 4 + j) * DM + bcol + bj * 128 + wc * 32 + n * 16 + fr];
; #pragma unroll
;           for (int j = 0; j < 4; ++j) {
;             const int row = brow + ai * 128 + wr * 64 + m * 16 + fq * 4 + j;
; #pragma unroll
;             for (int bj = 0; bj < 2; ++bj)
; #pragma unroll
;               for (int n = 0; n < 2; ++n) {
;                 const size_t idx = (size_t)row * DM + bcol + bj * 128 + wc * 32 + n * 16 + fr;
;                 tmpb[idx] = (unsigned short)f2bf(bf2f(gv[j][bj][n]) * acc[ai][bj][m][n][j]);
	v_lshlrev_b32_e32 v115, 16, v128
	v_mul_f32_e32 v104, v104, v115
	v_cvt_pk_bf16_f32 v104, v104, v104
	global_store_short v[106:107], v104, off
	v_lshlrev_b32_e32 v104, 16, v145
	v_mul_f32_e32 v100, v100, v104
	v_cvt_pk_bf16_f32 v100, v100, v100
	global_store_short v[106:107], v100, off offset:32
	v_lshlrev_b32_e32 v100, 16, v146
	v_mul_f32_e32 v100, v112, v100
	v_cvt_pk_bf16_f32 v100, v100, v100
	global_store_short v[106:107], v100, off offset:256
	v_lshlrev_b32_e32 v100, 16, v126
	v_mul_f32_e32 v100, v108, v100
	v_cvt_pk_bf16_f32 v100, v100, v100
	global_store_short v[106:107], v100, off offset:288
	v_lshlrev_b32_e32 v100, 16, v127
	v_or_b32_e32 v104, 34, v132
	v_mul_f32_e32 v100, v105, v100
	v_ashrrev_i32_e32 v105, 31, v104
	v_lshlrev_b64 v[104:105], 11, v[104:105]
	v_lshl_add_u64 v[106:107], v[136:137], 0, v[104:105]
	global_load_ushort v112, v[102:103], off offset:256
	global_load_ushort v115, v[102:103], off offset:288
	global_load_ushort v118, v[106:107], off offset:288
	v_lshl_add_u64 v[102:103], v[134:135], 0, v[116:117]
	v_cvt_pk_bf16_f32 v100, v100, v100
	global_store_short v[102:103], v100, off
	v_lshlrev_b32_e32 v100, 16, v129
	v_mul_f32_e32 v100, v101, v100
	v_cvt_pk_bf16_f32 v100, v100, v100
	global_store_short v[102:103], v100, off offset:32
	v_lshlrev_b32_e32 v100, 16, v130
	global_load_ushort v116, v[106:107], off
	global_load_ushort v117, v[106:107], off offset:32
	v_mul_f32_e32 v100, v113, v100
	global_load_ushort v113, v[106:107], off offset:256
	v_cvt_pk_bf16_f32 v100, v100, v100
	global_load_ushort v124, v[124:125], off offset:288
	v_lshlrev_b32_e32 v110, 16, v110
	global_store_short v[102:103], v100, off offset:256
	v_lshlrev_b32_e32 v100, 16, v133
	v_mul_f32_e32 v100, v109, v100
	v_cvt_pk_bf16_f32 v100, v100, v100
	global_store_short v[102:103], v100, off offset:288
	v_or_b32_e32 v100, 35, v132
	v_ashrrev_i32_e32 v101, 31, v100
	v_lshlrev_b64 v[100:101], 11, v[100:101]
	v_lshl_add_u64 v[102:103], v[136:137], 0, v[100:101]
	v_lshl_add_u64 v[108:109], v[134:135], 0, v[120:121]
	v_mul_f32_e32 v86, v86, v110
	global_load_ushort v110, v[102:103], off
	global_load_ushort v119, v[102:103], off offset:32
	global_load_ushort v120, v[102:103], off offset:256
	global_load_ushort v121, v[102:103], off offset:288
	v_cvt_pk_bf16_f32 v86, v86, v86
	global_store_short v[108:109], v86, off
	v_lshlrev_b32_e32 v86, 16, v122
	v_mul_f32_e32 v82, v82, v86
	v_cvt_pk_bf16_f32 v82, v82, v82
	global_store_short v[108:109], v82, off offset:32
	v_or_b32_e32 v102, 48, v132
	v_ashrrev_i32_e32 v103, 31, v102
	v_lshlrev_b64 v[102:103], 11, v[102:103]
	v_lshl_add_u64 v[106:107], v[136:137], 0, v[102:103]
	v_lshlrev_b32_e32 v82, 16, v123
	v_mul_f32_e32 v82, v94, v82
	v_cvt_pk_bf16_f32 v82, v82, v82
	global_store_short v[108:109], v82, off offset:256
	s_waitcnt vmcnt(0)
	v_lshlrev_b32_e32 v82, 16, v124
	v_mul_f32_e32 v82, v90, v82
	v_cvt_pk_bf16_f32 v82, v82, v82
	global_store_short v[108:109], v82, off offset:288
	global_load_ushort v108, v[106:107], off
	v_lshlrev_b32_e32 v82, 16, v111
	v_mul_f32_e32 v82, v87, v82
	global_load_ushort v109, v[106:107], off offset:32
	global_load_ushort v111, v[106:107], off offset:256
	v_cvt_pk_bf16_f32 v82, v82, v82
	global_store_short v[98:99], v82, off
	v_lshlrev_b32_e32 v82, 16, v114
	v_mul_f32_e32 v82, v83, v82
	v_cvt_pk_bf16_f32 v82, v82, v82
	global_store_short v[98:99], v82, off offset:32
	v_or_b32_e32 v82, 49, v132
	global_load_ushort v106, v[106:107], off offset:288
	v_ashrrev_i32_e32 v83, 31, v82
	v_lshlrev_b64 v[82:83], 11, v[82:83]
	v_lshl_add_u64 v[86:87], v[136:137], 0, v[82:83]
	global_load_ushort v107, v[86:87], off
	global_load_ushort v114, v[86:87], off offset:256
	v_lshlrev_b32_e32 v90, 16, v112
	v_mul_f32_e32 v90, v95, v90
	v_cvt_pk_bf16_f32 v90, v90, v90
	global_load_ushort v112, v[86:87], off offset:32
	v_lshl_add_u64 v[82:83], v[134:135], 0, v[82:83]
	global_store_short v[98:99], v90, off offset:256
	v_lshlrev_b32_e32 v90, 16, v115
	v_mul_f32_e32 v90, v91, v90
	v_cvt_pk_bf16_f32 v90, v90, v90
	global_store_short v[98:99], v90, off offset:288
	v_lshl_add_u64 v[90:91], v[134:135], 0, v[104:105]
	global_load_ushort v104, v[86:87], off offset:288
	v_or_b32_e32 v86, 50, v132
	v_ashrrev_i32_e32 v87, 31, v86
	v_lshlrev_b64 v[86:87], 11, v[86:87]
	v_lshl_add_u64 v[94:95], v[136:137], 0, v[86:87]
	global_load_ushort v105, v[94:95], off
	global_load_ushort v115, v[94:95], off offset:32
	v_lshlrev_b32_e32 v98, 16, v116
	v_mul_f32_e32 v88, v88, v98
	v_cvt_pk_bf16_f32 v88, v88, v88
	global_store_short v[90:91], v88, off
	v_lshlrev_b32_e32 v88, 16, v117
	v_mul_f32_e32 v84, v84, v88
	global_load_ushort v88, v[94:95], off offset:256
	v_cvt_pk_bf16_f32 v84, v84, v84
	global_store_short v[90:91], v84, off offset:32
	v_lshlrev_b32_e32 v84, 16, v113
	global_load_ushort v113, v[94:95], off offset:288
	v_or_b32_e32 v94, 51, v132
	v_ashrrev_i32_e32 v95, 31, v94
	v_lshlrev_b64 v[94:95], 11, v[94:95]
	v_lshl_add_u64 v[98:99], v[136:137], 0, v[94:95]
	global_load_ushort v116, v[98:99], off
	v_mul_f32_e32 v84, v96, v84
	v_cvt_pk_bf16_f32 v84, v84, v84
	global_store_short v[90:91], v84, off offset:256
	v_lshlrev_b32_e32 v84, 16, v118
	global_load_ushort v96, v[98:99], off offset:32
	v_mul_f32_e32 v84, v92, v84
	v_cvt_pk_bf16_f32 v84, v84, v84
	global_store_short v[90:91], v84, off offset:288
	v_lshlrev_b32_e32 v84, 16, v110
	v_mul_f32_e32 v84, v89, v84
	global_load_ushort v89, v[98:99], off offset:256
	global_load_ushort v92, v[98:99], off offset:288
	v_lshl_add_u64 v[90:91], v[134:135], 0, v[100:101]
	v_cvt_pk_bf16_f32 v84, v84, v84
	global_store_short v[90:91], v84, off
	v_lshlrev_b32_e32 v84, 16, v119
	v_mul_f32_e32 v84, v85, v84
	v_cvt_pk_bf16_f32 v84, v84, v84
	global_store_short v[90:91], v84, off offset:32
	v_lshlrev_b32_e32 v84, 16, v120
	v_mul_f32_e32 v84, v97, v84
	v_cvt_pk_bf16_f32 v84, v84, v84
	global_store_short v[90:91], v84, off offset:256
	v_lshlrev_b32_e32 v84, 16, v121
	v_mul_f32_e32 v84, v93, v84
	v_cvt_pk_bf16_f32 v84, v84, v84
	global_store_short v[90:91], v84, off offset:288
	v_lshl_add_u64 v[84:85], v[134:135], 0, v[102:103]
	s_waitcnt vmcnt(0)
; #define GAS __attribute__((address_space(1)))
; __device__ __forceinline__ unsigned f2bf(float f) { return pk2(f, f) & 0xffffu; }
; __device__ __forceinline__ void phase_branch() {
;     ...
;       const GAS unsigned short* sg = (const GAS unsigned short*)(ws + OFF_SGF);
; #pragma unroll
;       for (int ai = 0; ai < 2; ++ai)
; #pragma unroll
;         for (int m = 0; m < 4; ++m) {
;           unsigned short gv[4][2][2];
; #pragma unroll
;           for (int j = 0; j < 4; ++j)
; #pragma unroll
;             for (int bj = 0; bj < 2; ++bj)
; #pragma unroll
;               for (int n = 0; n < 2; ++n)
;                 gv[j][bj][n] = sg[(size_t)(brow + ai * 128 + wr * 64 + m * 16 + fq * 4 + j) * DM + bcol + bj * 128 + wc * 32 + n * 16 + fr];
; #pragma unroll
;           for (int j = 0; j < 4; ++j) {
;             const int row = brow + ai * 128 + wr * 64 + m * 16 + fq * 4 + j;
; #pragma unroll
;             for (int bj = 0; bj < 2; ++bj)
; #pragma unroll
;               for (int n = 0; n < 2; ++n) {
;                 const size_t idx = (size_t)row * DM + bcol + bj * 128 + wc * 32 + n * 16 + fr;
;                 tmpb[idx] = (unsigned short)f2bf(bf2f(gv[j][bj][n]) * acc[ai][bj][m][n][j]);
	v_lshlrev_b32_e32 v90, 16, v108
	v_mul_f32_e32 v78, v78, v90
	v_cvt_pk_bf16_f32 v78, v78, v78
	global_store_short v[84:85], v78, off
	v_lshlrev_b32_e32 v78, 16, v109
	v_mul_f32_e32 v74, v74, v78
	v_cvt_pk_bf16_f32 v74, v74, v74
	global_store_short v[84:85], v74, off offset:32
	v_lshlrev_b32_e32 v74, 16, v111
	v_mul_f32_e32 v70, v70, v74
	v_cvt_pk_bf16_f32 v70, v70, v70
	global_store_short v[84:85], v70, off offset:256
	v_lshlrev_b32_e32 v70, 16, v106
	v_mul_f32_e32 v66, v66, v70
	v_cvt_pk_bf16_f32 v66, v66, v66
	global_store_short v[84:85], v66, off offset:288
	v_lshlrev_b32_e32 v66, 16, v107
	v_mul_f32_e32 v66, v79, v66
	v_cvt_pk_bf16_f32 v66, v66, v66
	global_store_short v[82:83], v66, off
	v_lshlrev_b32_e32 v66, 16, v112
	v_mul_f32_e32 v66, v75, v66
	v_cvt_pk_bf16_f32 v66, v66, v66
	global_store_short v[82:83], v66, off offset:32
	v_lshlrev_b32_e32 v66, 16, v114
	v_mul_f32_e32 v66, v71, v66
	v_cvt_pk_bf16_f32 v66, v66, v66
	global_store_short v[82:83], v66, off offset:256
	v_lshlrev_b32_e32 v66, 16, v104
	v_mul_f32_e32 v66, v67, v66
	v_cvt_pk_bf16_f32 v66, v66, v66
	global_store_short v[82:83], v66, off offset:288
	v_lshl_add_u64 v[66:67], v[134:135], 0, v[86:87]
	v_lshlrev_b32_e32 v70, 16, v105
	v_mul_f32_e32 v70, v80, v70
	v_cvt_pk_bf16_f32 v70, v70, v70
	global_store_short v[66:67], v70, off
	v_lshlrev_b32_e32 v70, 16, v115
	v_mul_f32_e32 v70, v76, v70
	v_cvt_pk_bf16_f32 v70, v70, v70
	global_store_short v[66:67], v70, off offset:32
	v_lshlrev_b32_e32 v70, 16, v88
	v_mul_f32_e32 v70, v72, v70
	v_cvt_pk_bf16_f32 v70, v70, v70
	global_store_short v[66:67], v70, off offset:256
	v_lshlrev_b32_e32 v70, 16, v113
	v_mul_f32_e32 v68, v68, v70
	v_cvt_pk_bf16_f32 v68, v68, v68
	v_add_u32_e32 v70, 0x80, v132
	global_store_short v[66:67], v68, off offset:288
	v_lshlrev_b32_e32 v68, 16, v116
	v_ashrrev_i32_e32 v71, 31, v70
	v_lshl_add_u64 v[66:67], v[134:135], 0, v[94:95]
	v_mul_f32_e32 v68, v81, v68
	v_lshlrev_b64 v[70:71], 11, v[70:71]
	v_cvt_pk_bf16_f32 v68, v68, v68
	global_store_short v[66:67], v68, off
	v_lshl_add_u64 v[74:75], v[136:137], 0, v[70:71]
	v_lshlrev_b32_e32 v68, 16, v96
	global_load_ushort v76, v[74:75], off
	v_mul_f32_e32 v68, v77, v68
	v_cvt_pk_bf16_f32 v68, v68, v68
	global_store_short v[66:67], v68, off offset:32
	v_lshlrev_b32_e32 v68, 16, v89
	global_load_ushort v77, v[74:75], off offset:32
	v_mul_f32_e32 v68, v73, v68
	v_cvt_pk_bf16_f32 v68, v68, v68
	global_store_short v[66:67], v68, off offset:256
	v_lshlrev_b32_e32 v68, 16, v92
	global_load_ushort v78, v[74:75], off offset:256
	v_mul_f32_e32 v68, v69, v68
	v_cvt_pk_bf16_f32 v68, v68, v68
	global_store_short v[66:67], v68, off offset:288
	global_load_ushort v79, v[74:75], off offset:288
	v_add_u32_e32 v66, 0x81, v132
	v_ashrrev_i32_e32 v67, 31, v66
	v_lshlrev_b64 v[66:67], 11, v[66:67]
	v_lshl_add_u64 v[68:69], v[136:137], 0, v[66:67]
	global_load_ushort v80, v[68:69], off
	global_load_ushort v81, v[68:69], off offset:32
	global_load_ushort v82, v[68:69], off offset:256
	global_load_ushort v83, v[68:69], off offset:288
	v_add_u32_e32 v68, 0x82, v132
	v_ashrrev_i32_e32 v69, 31, v68
	v_lshlrev_b64 v[68:69], 11, v[68:69]
	v_lshl_add_u64 v[72:73], v[136:137], 0, v[68:69]
	global_load_ushort v84, v[72:73], off
	global_load_ushort v85, v[72:73], off offset:32
	global_load_ushort v86, v[72:73], off offset:256
	global_load_ushort v87, v[72:73], off offset:288
	v_add_u32_e32 v72, 0x83, v132
	v_ashrrev_i32_e32 v73, 31, v72
	v_lshlrev_b64 v[72:73], 11, v[72:73]
	v_lshl_add_u64 v[74:75], v[136:137], 0, v[72:73]
	global_load_ushort v88, v[74:75], off
	global_load_ushort v89, v[74:75], off offset:32
	global_load_ushort v90, v[74:75], off offset:256
	global_load_ushort v91, v[74:75], off offset:288
	v_lshl_add_u64 v[70:71], v[134:135], 0, v[70:71]
	v_lshl_add_u64 v[66:67], v[134:135], 0, v[66:67]
	s_waitcnt vmcnt(0)
	v_lshlrev_b32_e32 v74, 16, v76
	v_mul_f32_e32 v62, v62, v74
	v_cvt_pk_bf16_f32 v62, v62, v62
	global_store_short v[70:71], v62, off
	v_lshlrev_b32_e32 v62, 16, v77
	v_mul_f32_e32 v58, v58, v62
	v_cvt_pk_bf16_f32 v58, v58, v58
	global_store_short v[70:71], v58, off offset:32
	v_lshlrev_b32_e32 v58, 16, v78
	v_mul_f32_e32 v54, v54, v58
	v_cvt_pk_bf16_f32 v54, v54, v54
	global_store_short v[70:71], v54, off offset:256
	v_lshlrev_b32_e32 v54, 16, v79
	v_mul_f32_e32 v50, v50, v54
	v_cvt_pk_bf16_f32 v50, v50, v50
	global_store_short v[70:71], v50, off offset:288
	v_lshlrev_b32_e32 v50, 16, v80
	v_mul_f32_e32 v50, v63, v50
	v_cvt_pk_bf16_f32 v50, v50, v50
	global_store_short v[66:67], v50, off
	v_lshlrev_b32_e32 v50, 16, v81
	v_mul_f32_e32 v50, v59, v50
	v_cvt_pk_bf16_f32 v50, v50, v50
	global_store_short v[66:67], v50, off offset:32
	v_lshlrev_b32_e32 v50, 16, v82
	v_mul_f32_e32 v50, v55, v50
	v_cvt_pk_bf16_f32 v50, v50, v50
	global_store_short v[66:67], v50, off offset:256
	v_lshlrev_b32_e32 v50, 16, v83
	v_mul_f32_e32 v50, v51, v50
	v_lshlrev_b32_e32 v54, 16, v84
	v_cvt_pk_bf16_f32 v50, v50, v50
	v_mul_f32_e32 v54, v64, v54
	global_store_short v[66:67], v50, off offset:288
	v_lshl_add_u64 v[50:51], v[134:135], 0, v[68:69]
	v_cvt_pk_bf16_f32 v54, v54, v54
	global_store_short v[50:51], v54, off
	v_lshlrev_b32_e32 v54, 16, v85
	v_mul_f32_e32 v54, v60, v54
	v_cvt_pk_bf16_f32 v54, v54, v54
	global_store_short v[50:51], v54, off offset:32
	v_lshlrev_b32_e32 v54, 16, v86
	v_mul_f32_e32 v54, v56, v54
	v_cvt_pk_bf16_f32 v54, v54, v54
	global_store_short v[50:51], v54, off offset:256
	v_lshlrev_b32_e32 v54, 16, v87
	v_mul_f32_e32 v52, v52, v54
	v_cvt_pk_bf16_f32 v52, v52, v52
	v_add_u32_e32 v54, 0x90, v132
	global_store_short v[50:51], v52, off offset:288
	v_lshlrev_b32_e32 v52, 16, v88
; #define GAS __attribute__((address_space(1)))
; __device__ __forceinline__ unsigned f2bf(float f) { return pk2(f, f) & 0xffffu; }
; __device__ __forceinline__ void phase_branch() {
;     ...
;       const GAS unsigned short* sg = (const GAS unsigned short*)(ws + OFF_SGF);
; #pragma unroll
;       for (int ai = 0; ai < 2; ++ai)
; #pragma unroll
;         for (int m = 0; m < 4; ++m) {
;           unsigned short gv[4][2][2];
; #pragma unroll
;           for (int j = 0; j < 4; ++j)
; #pragma unroll
;             for (int bj = 0; bj < 2; ++bj)
; #pragma unroll
;               for (int n = 0; n < 2; ++n)
;                 gv[j][bj][n] = sg[(size_t)(brow + ai * 128 + wr * 64 + m * 16 + fq * 4 + j) * DM + bcol + bj * 128 + wc * 32 + n * 16 + fr];
; #pragma unroll
;           for (int j = 0; j < 4; ++j) {
;             const int row = brow + ai * 128 + wr * 64 + m * 16 + fq * 4 + j;
; #pragma unroll
;             for (int bj = 0; bj < 2; ++bj)
; #pragma unroll
;               for (int n = 0; n < 2; ++n) {
;                 const size_t idx = (size_t)row * DM + bcol + bj * 128 + wc * 32 + n * 16 + fr;
;                 tmpb[idx] = (unsigned short)f2bf(bf2f(gv[j][bj][n]) * acc[ai][bj][m][n][j]);
	v_ashrrev_i32_e32 v55, 31, v54
	v_lshl_add_u64 v[50:51], v[134:135], 0, v[72:73]
	v_mul_f32_e32 v52, v65, v52
	v_lshlrev_b64 v[54:55], 11, v[54:55]
	v_cvt_pk_bf16_f32 v52, v52, v52
	global_store_short v[50:51], v52, off
	v_lshl_add_u64 v[58:59], v[136:137], 0, v[54:55]
	v_lshlrev_b32_e32 v52, 16, v89
	global_load_ushort v60, v[58:59], off
	v_mul_f32_e32 v52, v61, v52
	v_cvt_pk_bf16_f32 v52, v52, v52
	global_store_short v[50:51], v52, off offset:32
	v_lshlrev_b32_e32 v52, 16, v90
	global_load_ushort v61, v[58:59], off offset:32
	v_mul_f32_e32 v52, v57, v52
	v_cvt_pk_bf16_f32 v52, v52, v52
	global_store_short v[50:51], v52, off offset:256
	v_lshlrev_b32_e32 v52, 16, v91
	global_load_ushort v62, v[58:59], off offset:256
	v_mul_f32_e32 v52, v53, v52
	v_cvt_pk_bf16_f32 v52, v52, v52
	global_store_short v[50:51], v52, off offset:288
	global_load_ushort v63, v[58:59], off offset:288
	v_add_u32_e32 v50, 0x91, v132
	v_ashrrev_i32_e32 v51, 31, v50
	v_lshlrev_b64 v[50:51], 11, v[50:51]
	v_lshl_add_u64 v[52:53], v[136:137], 0, v[50:51]
	global_load_ushort v64, v[52:53], off
	global_load_ushort v65, v[52:53], off offset:32
	global_load_ushort v66, v[52:53], off offset:256
	global_load_ushort v67, v[52:53], off offset:288
	v_add_u32_e32 v52, 0x92, v132
	v_ashrrev_i32_e32 v53, 31, v52
	v_lshlrev_b64 v[52:53], 11, v[52:53]
	v_lshl_add_u64 v[56:57], v[136:137], 0, v[52:53]
	global_load_ushort v68, v[56:57], off
	global_load_ushort v69, v[56:57], off offset:32
	global_load_ushort v70, v[56:57], off offset:256
	global_load_ushort v71, v[56:57], off offset:288
	v_add_u32_e32 v56, 0x93, v132
	v_ashrrev_i32_e32 v57, 31, v56
	v_lshlrev_b64 v[56:57], 11, v[56:57]
	v_lshl_add_u64 v[58:59], v[136:137], 0, v[56:57]
	global_load_ushort v72, v[58:59], off
	global_load_ushort v73, v[58:59], off offset:32
	global_load_ushort v74, v[58:59], off offset:256
	global_load_ushort v75, v[58:59], off offset:288
	v_lshl_add_u64 v[54:55], v[134:135], 0, v[54:55]
	v_lshl_add_u64 v[50:51], v[134:135], 0, v[50:51]
	s_waitcnt vmcnt(0)
	v_lshlrev_b32_e32 v58, 16, v60
	v_mul_f32_e32 v46, v46, v58
	v_cvt_pk_bf16_f32 v46, v46, v46
	global_store_short v[54:55], v46, off
	v_lshlrev_b32_e32 v46, 16, v61
	v_mul_f32_e32 v42, v42, v46
	v_cvt_pk_bf16_f32 v42, v42, v42
	global_store_short v[54:55], v42, off offset:32
	v_lshlrev_b32_e32 v42, 16, v62
	v_mul_f32_e32 v38, v38, v42
	v_cvt_pk_bf16_f32 v38, v38, v38
	global_store_short v[54:55], v38, off offset:256
	v_lshlrev_b32_e32 v38, 16, v63
	v_mul_f32_e32 v34, v34, v38
	v_cvt_pk_bf16_f32 v34, v34, v34
	global_store_short v[54:55], v34, off offset:288
	v_lshlrev_b32_e32 v34, 16, v64
	v_mul_f32_e32 v34, v47, v34
	v_cvt_pk_bf16_f32 v34, v34, v34
	global_store_short v[50:51], v34, off
	v_lshlrev_b32_e32 v34, 16, v65
	v_mul_f32_e32 v34, v43, v34
	v_cvt_pk_bf16_f32 v34, v34, v34
	global_store_short v[50:51], v34, off offset:32
	v_lshlrev_b32_e32 v34, 16, v66
	v_mul_f32_e32 v34, v39, v34
	v_cvt_pk_bf16_f32 v34, v34, v34
	global_store_short v[50:51], v34, off offset:256
	v_lshlrev_b32_e32 v34, 16, v67
	v_mul_f32_e32 v34, v35, v34
	v_lshlrev_b32_e32 v38, 16, v68
	v_cvt_pk_bf16_f32 v34, v34, v34
	v_mul_f32_e32 v38, v48, v38
	global_store_short v[50:51], v34, off offset:288
	v_lshl_add_u64 v[34:35], v[134:135], 0, v[52:53]
	v_cvt_pk_bf16_f32 v38, v38, v38
	global_store_short v[34:35], v38, off
	v_lshlrev_b32_e32 v38, 16, v69
	v_mul_f32_e32 v38, v44, v38
	v_cvt_pk_bf16_f32 v38, v38, v38
	global_store_short v[34:35], v38, off offset:32
	v_lshlrev_b32_e32 v38, 16, v70
	v_mul_f32_e32 v38, v40, v38
	v_cvt_pk_bf16_f32 v38, v38, v38
	global_store_short v[34:35], v38, off offset:256
	v_lshlrev_b32_e32 v38, 16, v71
	v_mul_f32_e32 v36, v36, v38
	v_cvt_pk_bf16_f32 v36, v36, v36
	v_add_u32_e32 v38, 0xa0, v132
	global_store_short v[34:35], v36, off offset:288
	v_lshlrev_b32_e32 v36, 16, v72
	v_ashrrev_i32_e32 v39, 31, v38
	v_lshl_add_u64 v[34:35], v[134:135], 0, v[56:57]
	v_mul_f32_e32 v36, v49, v36
	v_lshlrev_b64 v[38:39], 11, v[38:39]
	v_cvt_pk_bf16_f32 v36, v36, v36
	global_store_short v[34:35], v36, off
	v_lshl_add_u64 v[42:43], v[136:137], 0, v[38:39]
	v_lshlrev_b32_e32 v36, 16, v73
	global_load_ushort v44, v[42:43], off
	v_mul_f32_e32 v36, v45, v36
	v_cvt_pk_bf16_f32 v36, v36, v36
	global_store_short v[34:35], v36, off offset:32
	v_lshlrev_b32_e32 v36, 16, v74
	global_load_ushort v45, v[42:43], off offset:32
	v_mul_f32_e32 v36, v41, v36
	v_cvt_pk_bf16_f32 v36, v36, v36
	global_store_short v[34:35], v36, off offset:256
	v_lshlrev_b32_e32 v36, 16, v75
	global_load_ushort v46, v[42:43], off offset:256
	v_mul_f32_e32 v36, v37, v36
	v_cvt_pk_bf16_f32 v36, v36, v36
	global_store_short v[34:35], v36, off offset:288
	global_load_ushort v47, v[42:43], off offset:288
	v_add_u32_e32 v34, 0xa1, v132
	v_ashrrev_i32_e32 v35, 31, v34
	v_lshlrev_b64 v[34:35], 11, v[34:35]
	v_lshl_add_u64 v[36:37], v[136:137], 0, v[34:35]
	global_load_ushort v48, v[36:37], off
	global_load_ushort v49, v[36:37], off offset:32
	global_load_ushort v50, v[36:37], off offset:256
	global_load_ushort v51, v[36:37], off offset:288
	v_add_u32_e32 v36, 0xa2, v132
	v_ashrrev_i32_e32 v37, 31, v36
	v_lshlrev_b64 v[36:37], 11, v[36:37]
	v_lshl_add_u64 v[40:41], v[136:137], 0, v[36:37]
	global_load_ushort v52, v[40:41], off
	global_load_ushort v53, v[40:41], off offset:32
	global_load_ushort v54, v[40:41], off offset:256
	global_load_ushort v55, v[40:41], off offset:288
	v_add_u32_e32 v40, 0xa3, v132
	v_ashrrev_i32_e32 v41, 31, v40
	v_lshlrev_b64 v[40:41], 11, v[40:41]
	v_lshl_add_u64 v[42:43], v[136:137], 0, v[40:41]
	global_load_ushort v56, v[42:43], off
	global_load_ushort v57, v[42:43], off offset:32
	global_load_ushort v58, v[42:43], off offset:256
	global_load_ushort v59, v[42:43], off offset:288
	v_lshl_add_u64 v[38:39], v[134:135], 0, v[38:39]
	v_lshl_add_u64 v[34:35], v[134:135], 0, v[34:35]
	s_waitcnt vmcnt(0)
; #define GAS __attribute__((address_space(1)))
; __device__ __forceinline__ unsigned f2bf(float f) { return pk2(f, f) & 0xffffu; }
; #define BAR __builtin_amdgcn_s_barrier()
; template <int K, int LD = K>
; __device__ __forceinline__ void gemm_main(const GAS bf16* A, const GAS bf16* Bt, int brow, int bcol, f32x4 (&acc)[2][2][4][2]) {
;     ...
;   if (wr == 1) BAR;
; __device__ __forceinline__ void phase_branch() {
;     ...
;       const GAS unsigned short* sg = (const GAS unsigned short*)(ws + OFF_SGF);
; #pragma unroll
;       for (int ai = 0; ai < 2; ++ai)
; #pragma unroll
;         for (int m = 0; m < 4; ++m) {
;           unsigned short gv[4][2][2];
; #pragma unroll
;           for (int j = 0; j < 4; ++j)
; #pragma unroll
;             for (int bj = 0; bj < 2; ++bj)
; #pragma unroll
;               for (int n = 0; n < 2; ++n)
;                 gv[j][bj][n] = sg[(size_t)(brow + ai * 128 + wr * 64 + m * 16 + fq * 4 + j) * DM + bcol + bj * 128 + wc * 32 + n * 16 + fr];
; #pragma unroll
;           for (int j = 0; j < 4; ++j) {
;             const int row = brow + ai * 128 + wr * 64 + m * 16 + fq * 4 + j;
; #pragma unroll
;             for (int bj = 0; bj < 2; ++bj)
; #pragma unroll
;               for (int n = 0; n < 2; ++n) {
;                 const size_t idx = (size_t)row * DM + bcol + bj * 128 + wc * 32 + n * 16 + fr;
;                 tmpb[idx] = (unsigned short)f2bf(bf2f(gv[j][bj][n]) * acc[ai][bj][m][n][j]);
	v_lshlrev_b32_e32 v42, 16, v44
	v_mul_f32_e32 v30, v30, v42
	v_cvt_pk_bf16_f32 v30, v30, v30
	global_store_short v[38:39], v30, off
	v_lshlrev_b32_e32 v30, 16, v45
	v_mul_f32_e32 v26, v26, v30
	v_cvt_pk_bf16_f32 v26, v26, v26
	global_store_short v[38:39], v26, off offset:32
	v_lshlrev_b32_e32 v26, 16, v46
	v_mul_f32_e32 v22, v22, v26
	v_cvt_pk_bf16_f32 v22, v22, v22
	global_store_short v[38:39], v22, off offset:256
	v_lshlrev_b32_e32 v22, 16, v47
	v_mul_f32_e32 v18, v18, v22
	v_cvt_pk_bf16_f32 v18, v18, v18
	global_store_short v[38:39], v18, off offset:288
	v_lshlrev_b32_e32 v18, 16, v48
	v_mul_f32_e32 v18, v31, v18
	v_cvt_pk_bf16_f32 v18, v18, v18
	global_store_short v[34:35], v18, off
	v_lshlrev_b32_e32 v18, 16, v49
	v_mul_f32_e32 v18, v27, v18
	v_cvt_pk_bf16_f32 v18, v18, v18
	global_store_short v[34:35], v18, off offset:32
	v_lshlrev_b32_e32 v18, 16, v50
	v_mul_f32_e32 v18, v23, v18
	v_cvt_pk_bf16_f32 v18, v18, v18
	global_store_short v[34:35], v18, off offset:256
	v_lshlrev_b32_e32 v18, 16, v51
	v_mul_f32_e32 v18, v19, v18
	v_lshlrev_b32_e32 v22, 16, v52
	v_cvt_pk_bf16_f32 v18, v18, v18
	v_mul_f32_e32 v22, v32, v22
	global_store_short v[34:35], v18, off offset:288
	v_lshl_add_u64 v[18:19], v[134:135], 0, v[36:37]
	v_cvt_pk_bf16_f32 v22, v22, v22
	global_store_short v[18:19], v22, off
	v_lshlrev_b32_e32 v22, 16, v53
	v_mul_f32_e32 v22, v28, v22
	v_cvt_pk_bf16_f32 v22, v22, v22
	global_store_short v[18:19], v22, off offset:32
	v_lshlrev_b32_e32 v22, 16, v54
	v_mul_f32_e32 v22, v24, v22
	v_cvt_pk_bf16_f32 v22, v22, v22
	global_store_short v[18:19], v22, off offset:256
	v_lshlrev_b32_e32 v22, 16, v55
	v_mul_f32_e32 v20, v20, v22
	v_cvt_pk_bf16_f32 v20, v20, v20
	v_add_u32_e32 v22, 0xb0, v132
	global_store_short v[18:19], v20, off offset:288
	v_lshlrev_b32_e32 v20, 16, v56
	v_ashrrev_i32_e32 v23, 31, v22
	v_lshl_add_u64 v[18:19], v[134:135], 0, v[40:41]
	v_mul_f32_e32 v20, v33, v20
	v_lshlrev_b64 v[22:23], 11, v[22:23]
	v_cvt_pk_bf16_f32 v20, v20, v20
	global_store_short v[18:19], v20, off
	v_lshl_add_u64 v[26:27], v[136:137], 0, v[22:23]
	v_lshlrev_b32_e32 v20, 16, v57
	global_load_ushort v28, v[26:27], off
	v_mul_f32_e32 v20, v29, v20
	v_cvt_pk_bf16_f32 v20, v20, v20
	global_store_short v[18:19], v20, off offset:32
	v_lshlrev_b32_e32 v20, 16, v58
	global_load_ushort v29, v[26:27], off offset:32
	v_mul_f32_e32 v20, v25, v20
	v_cvt_pk_bf16_f32 v20, v20, v20
	global_store_short v[18:19], v20, off offset:256
	v_lshlrev_b32_e32 v20, 16, v59
	global_load_ushort v30, v[26:27], off offset:256
	v_mul_f32_e32 v20, v21, v20
	v_cvt_pk_bf16_f32 v20, v20, v20
	global_store_short v[18:19], v20, off offset:288
	global_load_ushort v31, v[26:27], off offset:288
	v_add_u32_e32 v18, 0xb1, v132
	v_ashrrev_i32_e32 v19, 31, v18
	v_lshlrev_b64 v[18:19], 11, v[18:19]
	v_lshl_add_u64 v[20:21], v[136:137], 0, v[18:19]
	global_load_ushort v32, v[20:21], off
	global_load_ushort v33, v[20:21], off offset:32
	global_load_ushort v34, v[20:21], off offset:256
	global_load_ushort v35, v[20:21], off offset:288
	v_add_u32_e32 v20, 0xb2, v132
	v_ashrrev_i32_e32 v21, 31, v20
	v_lshlrev_b64 v[20:21], 11, v[20:21]
	v_lshl_add_u64 v[24:25], v[136:137], 0, v[20:21]
	global_load_ushort v36, v[24:25], off
	global_load_ushort v37, v[24:25], off offset:32
	global_load_ushort v38, v[24:25], off offset:256
	global_load_ushort v39, v[24:25], off offset:288
	v_add_u32_e32 v24, 0xb3, v132
	v_ashrrev_i32_e32 v25, 31, v24
	v_lshlrev_b64 v[24:25], 11, v[24:25]
	v_lshl_add_u64 v[26:27], v[136:137], 0, v[24:25]
	global_load_ushort v40, v[26:27], off
	global_load_ushort v41, v[26:27], off offset:32
	global_load_ushort v42, v[26:27], off offset:256
	global_load_ushort v43, v[26:27], off offset:288
	v_lshl_add_u64 v[22:23], v[134:135], 0, v[22:23]
	v_lshl_add_u64 v[18:19], v[134:135], 0, v[18:19]
	s_waitcnt vmcnt(0)
	v_lshlrev_b32_e32 v26, 16, v28
	v_mul_f32_e32 v6, v6, v26
	v_cvt_pk_bf16_f32 v6, v6, v6
	global_store_short v[22:23], v6, off
	v_lshlrev_b32_e32 v6, 16, v29
	v_mul_f32_e32 v2, v2, v6
	v_cvt_pk_bf16_f32 v2, v2, v2
	global_store_short v[22:23], v2, off offset:32
	v_lshlrev_b32_e32 v2, 16, v30
	v_mul_f32_e32 v2, v14, v2
	v_cvt_pk_bf16_f32 v2, v2, v2
	global_store_short v[22:23], v2, off offset:256
	v_lshlrev_b32_e32 v2, 16, v31
	v_mul_f32_e32 v2, v10, v2
	v_cvt_pk_bf16_f32 v2, v2, v2
	global_store_short v[22:23], v2, off offset:288
	v_lshlrev_b32_e32 v2, 16, v32
	v_mul_f32_e32 v2, v7, v2
	v_cvt_pk_bf16_f32 v2, v2, v2
	global_store_short v[18:19], v2, off
	v_lshlrev_b32_e32 v2, 16, v33
	v_mul_f32_e32 v2, v3, v2
	v_cvt_pk_bf16_f32 v2, v2, v2
	global_store_short v[18:19], v2, off offset:32
	v_lshlrev_b32_e32 v2, 16, v34
	v_mul_f32_e32 v2, v15, v2
	v_cvt_pk_bf16_f32 v2, v2, v2
	global_store_short v[18:19], v2, off offset:256
	v_lshlrev_b32_e32 v2, 16, v35
	v_mul_f32_e32 v2, v11, v2
	v_lshlrev_b32_e32 v6, 16, v36
	v_cvt_pk_bf16_f32 v2, v2, v2
	v_mul_f32_e32 v6, v8, v6
	global_store_short v[18:19], v2, off offset:288
	v_lshl_add_u64 v[2:3], v[134:135], 0, v[20:21]
	v_cvt_pk_bf16_f32 v6, v6, v6
	global_store_short v[2:3], v6, off
	v_lshlrev_b32_e32 v6, 16, v37
	v_mul_f32_e32 v4, v4, v6
	v_cvt_pk_bf16_f32 v4, v4, v4
	global_store_short v[2:3], v4, off offset:32
	v_lshlrev_b32_e32 v4, 16, v38
	v_mul_f32_e32 v4, v16, v4
	v_cvt_pk_bf16_f32 v4, v4, v4
	global_store_short v[2:3], v4, off offset:256
	v_lshlrev_b32_e32 v4, 16, v39
	v_mul_f32_e32 v4, v12, v4
	v_cvt_pk_bf16_f32 v4, v4, v4
	global_store_short v[2:3], v4, off offset:288
	v_lshlrev_b32_e32 v4, 16, v40
	v_mul_f32_e32 v4, v9, v4
	v_lshl_add_u64 v[2:3], v[134:135], 0, v[24:25]
	v_cvt_pk_bf16_f32 v4, v4, v4
	global_store_short v[2:3], v4, off
	v_lshlrev_b32_e32 v4, 16, v41
	v_mul_f32_e32 v4, v5, v4
	v_cvt_pk_bf16_f32 v4, v4, v4
	global_store_short v[2:3], v4, off offset:32
	v_lshlrev_b32_e32 v4, 16, v42
	v_mul_f32_e32 v4, v17, v4
	v_cvt_pk_bf16_f32 v4, v4, v4
	global_store_short v[2:3], v4, off offset:256
	v_lshlrev_b32_e32 v4, 16, v43
	v_mul_f32_e32 v4, v13, v4
	v_mov_b32_e32 v134, v170
	v_cvt_pk_bf16_f32 v4, v4, v4
	global_store_short v[2:3], v4, off offset:288
	s_nop 0
	v_ashrrev_i32_e32 v2, 8, v134
	v_cmp_eq_u32_e32 vcc, 1, v2
	s_and_saveexec_b64 s[28:29], vcc
	s_cbranch_execz .LBB0_714
	s_barrier

; __device__ __forceinline__ unsigned f2bf(float f) { return pk2(f, f) & 0xffffu; }
; template <int K, int LD>
; __device__ __forceinline__ void phase_resid(int mode) {
;     ...
;       float xo[2][4][2][2];
; #pragma unroll
;       for (int m2 = 0; m2 < 2; ++m2)
; #pragma unroll
;         for (int j = 0; j < 4; ++j)
; #pragma unroll
;           for (int bj = 0; bj < 2; ++bj)
; #pragma unroll
;             for (int n = 0; n < 2; ++n) {
;               const size_t idx = (size_t)(brow + ai * 128 + wr * 64 + (mh * 2 + m2) * 16 + fq * 4 + j) * DM + bcol + bj * 128 + wc * 32 + n * 16 + fr;
;               xo[m2][j][bj][n] = (mode == 0) ? xin[idx] : bf2f(xg[idx]);
;             }
; #pragma unroll
;       for (int m2 = 0; m2 < 2; ++m2)
; #pragma unroll
;         for (int j = 0; j < 4; ++j) {
;           const int m = mh * 2 + m2; const int row = brow + ai * 128 + wr * 64 + m * 16 + fq * 4 + j;
;           float ss = 0.f;
; #pragma unroll
;           for (int bj = 0; bj < 2; ++bj)
; #pragma unroll
;             for (int n = 0; n < 2; ++n) {
;               const size_t idx = (size_t)row * DM + bcol + bj * 128 + wc * 32 + n * 16 + fr;
;               const float xn = xo[m2][j][bj][n] + scale * acc[ai][bj][m][n][j];
;               ss += xn * xn;
;               xg[idx] = (unsigned short)f2bf(xn);
;             }
;           ss = sum16(ss);
;           if (fr == 0) ssq[(size_t)row * 16 + pn0 * 4 + wc] = ss;
;         }
.LBB0_772:
	v_mov_b32_e32 v130, v170
	s_lshl_b64 s[12:13], s[12:13], 1
	v_ashrrev_i32_e32 v132, 2, v130
	v_and_b32_e32 v132, 0xffffffc0, v132
	v_bfe_u32 v200, v130, 6, 2
	v_and_b32_e32 v201, 15, v130
	v_lshrrev_b32_e32 v130, 2, v130
	v_add_u32_e32 v132, s14, v132
	s_add_u32 s12, s29, s12
	v_and_or_b32 v134, v130, 12, v132
	s_addc_u32 s13, s30, s13
	v_lshlrev_b32_e32 v130, 6, v200
	v_lshl_add_u64 v[132:133], s[12:13], 0, v[130:131]
	v_lshlrev_b32_e32 v130, 1, v201
	v_ashrrev_i32_e32 v135, 31, v134
	v_or_b32_e32 v162, 1, v134
	v_lshl_add_u64 v[136:137], v[132:133], 0, v[130:131]
	v_lshlrev_b64 v[132:133], 11, v[134:135]
	v_ashrrev_i32_e32 v163, 31, v162
	v_or_b32_e32 v158, 2, v134
	v_lshl_add_u64 v[198:199], v[136:137], 0, v[132:133]
	v_lshlrev_b64 v[132:133], 11, v[162:163]
	v_ashrrev_i32_e32 v159, 31, v158
	v_or_b32_e32 v154, 3, v134
	v_lshl_add_u64 v[164:165], v[136:137], 0, v[132:133]
	v_lshlrev_b64 v[132:133], 11, v[158:159]
	v_ashrrev_i32_e32 v155, 31, v154
	v_or_b32_e32 v150, 16, v134
	v_lshl_add_u64 v[160:161], v[136:137], 0, v[132:133]
	v_lshlrev_b64 v[132:133], 11, v[154:155]
	v_ashrrev_i32_e32 v151, 31, v150
	v_or_b32_e32 v146, 17, v134
	global_load_ushort v202, v[198:199], off
	global_load_ushort v203, v[198:199], off offset:32
	global_load_ushort v204, v[198:199], off offset:256
	global_load_ushort v205, v[198:199], off offset:288
	v_lshl_add_u64 v[156:157], v[136:137], 0, v[132:133]
	v_lshlrev_b64 v[132:133], 11, v[150:151]
	v_ashrrev_i32_e32 v147, 31, v146
	v_or_b32_e32 v142, 18, v134
	v_lshl_add_u64 v[152:153], v[136:137], 0, v[132:133]
	v_lshlrev_b64 v[132:133], 11, v[146:147]
	v_ashrrev_i32_e32 v143, 31, v142
	v_lshl_add_u64 v[148:149], v[136:137], 0, v[132:133]
	v_lshlrev_b64 v[132:133], 11, v[142:143]
	global_load_ushort v194, v[164:165], off
	global_load_ushort v195, v[164:165], off offset:32
	global_load_ushort v196, v[164:165], off offset:256
	global_load_ushort v197, v[164:165], off offset:288
	global_load_ushort v190, v[160:161], off
	global_load_ushort v191, v[160:161], off offset:32
	global_load_ushort v192, v[160:161], off offset:256
	global_load_ushort v193, v[160:161], off offset:288
	global_load_ushort v186, v[156:157], off
	global_load_ushort v187, v[156:157], off offset:32
	global_load_ushort v188, v[156:157], off offset:256
	global_load_ushort v189, v[156:157], off offset:288
	global_load_ushort v182, v[152:153], off
	global_load_ushort v183, v[152:153], off offset:32
	global_load_ushort v184, v[152:153], off offset:256
	global_load_ushort v185, v[152:153], off offset:288
	v_lshl_add_u64 v[144:145], v[136:137], 0, v[132:133]
	global_load_ushort v178, v[148:149], off
	global_load_ushort v179, v[148:149], off offset:32
	global_load_ushort v180, v[148:149], off offset:256
	global_load_ushort v181, v[148:149], off offset:288
	global_load_ushort v174, v[144:145], off
	global_load_ushort v175, v[144:145], off offset:32
	global_load_ushort v176, v[144:145], off offset:256
	global_load_ushort v177, v[144:145], off offset:288
	v_or_b32_e32 v138, 19, v134
	v_ashrrev_i32_e32 v139, 31, v138
	v_lshlrev_b64 v[132:133], 11, v[138:139]
	v_lshl_add_u64 v[140:141], v[136:137], 0, v[132:133]
	global_load_ushort v166, v[140:141], off
	global_load_ushort v167, v[140:141], off offset:32
	global_load_ushort v168, v[140:141], off offset:256
	global_load_ushort v169, v[140:141], off offset:288
	s_lshl_b32 s12, s40, 2
	s_ashr_i32 s13, s12, 31
	s_lshl_b64 s[12:13], s[12:13], 2
	s_add_u32 s12, s31, s12
	v_lshlrev_b32_e32 v130, 2, v200
	s_addc_u32 s13, s33, s13
	v_lshl_add_u64 v[132:133], s[12:13], 0, v[130:131]
	v_cmp_eq_u32_e32 vcc, 0, v201
	s_waitcnt vmcnt(0)
	v_lshlrev_b32_e32 v130, 16, v202
	v_lshlrev_b32_e32 v200, 16, v203
	v_add_f32_e32 v118, v118, v130
	v_cvt_pk_bf16_f32 v130, v118, v118
	v_add_f32_e32 v114, v114, v200
	v_lshlrev_b32_e32 v201, 16, v204
	global_store_short v[198:199], v130, off
	v_mul_f32_e32 v130, v114, v114
	v_cvt_pk_bf16_f32 v114, v114, v114
	v_fmac_f32_e32 v130, v118, v118
	global_store_short v[198:199], v114, off offset:32
	v_add_f32_e32 v114, v126, v201
	v_lshlrev_b32_e32 v202, 16, v205
	v_fmac_f32_e32 v130, v114, v114
	v_cvt_pk_bf16_f32 v114, v114, v114
	global_store_short v[198:199], v114, off offset:256
	v_add_f32_e32 v114, v122, v202
	v_fmac_f32_e32 v130, v114, v114
	v_cvt_pk_bf16_f32 v114, v114, v114
	global_store_short v[198:199], v114, off offset:288
	v_mov_b32_e32 v118, 0
	v_add_f32_dpp v114, v130, v130 quad_perm:[1,0,3,2] row_mask:0xf bank_mask:0xf bound_ctrl:1
	s_nop 1
	v_add_f32_dpp v114, v114, v114 quad_perm:[2,3,0,1] row_mask:0xf bank_mask:0xf bound_ctrl:1
	s_nop 1
	v_add_f32_dpp v114, v114, v114 row_half_mirror row_mask:0xf bank_mask:0xf bound_ctrl:1
	s_nop 1
	v_mov_b32_dpp v118, v114 row_mirror row_mask:0xf bank_mask:0xf
	s_and_saveexec_b64 s[12:13], vcc
	s_cbranch_execz .LBB0_774
	v_lshlrev_b64 v[198:199], 6, v[134:135]
	v_add_f32_e32 v114, v114, v118
	v_lshl_add_u64 v[198:199], v[132:133], 0, v[198:199]
	global_store_dword v[198:199], v114, off
; __device__ __forceinline__ unsigned f2bf(float f) { return pk2(f, f) & 0xffffu; }
; template <int K, int LD>
; __device__ __forceinline__ void phase_resid(int mode) {
;     ...
;       float xo[2][4][2][2];
; #pragma unroll
;       for (int m2 = 0; m2 < 2; ++m2)
; #pragma unroll
;         for (int j = 0; j < 4; ++j)
; #pragma unroll
;           for (int bj = 0; bj < 2; ++bj)
; #pragma unroll
;             for (int n = 0; n < 2; ++n) {
;               const size_t idx = (size_t)(brow + ai * 128 + wr * 64 + (mh * 2 + m2) * 16 + fq * 4 + j) * DM + bcol + bj * 128 + wc * 32 + n * 16 + fr;
;               xo[m2][j][bj][n] = (mode == 0) ? xin[idx] : bf2f(xg[idx]);
;             }
; #pragma unroll
;       for (int m2 = 0; m2 < 2; ++m2)
; #pragma unroll
;         for (int j = 0; j < 4; ++j) {
;           const int m = mh * 2 + m2; const int row = brow + ai * 128 + wr * 64 + m * 16 + fq * 4 + j;
;           float ss = 0.f;
; #pragma unroll
;           for (int bj = 0; bj < 2; ++bj)
; #pragma unroll
;             for (int n = 0; n < 2; ++n) {
;               const size_t idx = (size_t)row * DM + bcol + bj * 128 + wc * 32 + n * 16 + fr;
;               const float xn = xo[m2][j][bj][n] + scale * acc[ai][bj][m][n][j];
;               ss += xn * xn;
;               xg[idx] = (unsigned short)f2bf(xn);
;             }
;           ss = sum16(ss);
;           if (fr == 0) ssq[(size_t)row * 16 + pn0 * 4 + wc] = ss;
;         }
.LBB0_774:
	s_or_b64 exec, exec, s[12:13]
	v_lshlrev_b32_e32 v118, 16, v195
	v_lshlrev_b32_e32 v114, 16, v194
	v_add_f32_e32 v115, v115, v118
	v_add_f32_e32 v114, v119, v114
	v_mul_f32_e32 v118, v115, v115
	v_lshlrev_b32_e32 v122, 16, v196
	v_cvt_pk_bf16_f32 v119, v114, v114
	v_fmac_f32_e32 v118, v114, v114
	v_cvt_pk_bf16_f32 v114, v115, v115
	global_store_short v[164:165], v114, off offset:32
	v_add_f32_e32 v114, v127, v122
	v_lshlrev_b32_e32 v126, 16, v197
	v_fmac_f32_e32 v118, v114, v114
	v_cvt_pk_bf16_f32 v114, v114, v114
	global_store_short v[164:165], v114, off offset:256
	v_add_f32_e32 v114, v123, v126
	v_fmac_f32_e32 v118, v114, v114
	v_cvt_pk_bf16_f32 v114, v114, v114
	global_store_short v[164:165], v114, off offset:288
	v_mov_b32_e32 v115, 0
	v_add_f32_dpp v114, v118, v118 quad_perm:[1,0,3,2] row_mask:0xf bank_mask:0xf bound_ctrl:1
	global_store_short v[164:165], v119, off
	s_nop 0
	v_add_f32_dpp v114, v114, v114 quad_perm:[2,3,0,1] row_mask:0xf bank_mask:0xf bound_ctrl:1
	s_nop 1
	v_add_f32_dpp v114, v114, v114 row_half_mirror row_mask:0xf bank_mask:0xf bound_ctrl:1
	s_nop 1
	v_mov_b32_dpp v115, v114 row_mirror row_mask:0xf bank_mask:0xf
	s_and_saveexec_b64 s[12:13], vcc
	s_cbranch_execz .LBB0_776
	v_add_f32_e32 v118, v114, v115
	v_lshlrev_b64 v[114:115], 6, v[162:163]
	v_lshl_add_u64 v[114:115], v[132:133], 0, v[114:115]
	global_store_dword v[114:115], v118, off
.LBB0_776:
	s_or_b64 exec, exec, s[12:13]
	v_lshlrev_b32_e32 v115, 16, v191
	v_lshlrev_b32_e32 v114, 16, v190
	v_add_f32_e32 v115, v116, v115
	v_add_f32_e32 v114, v120, v114
	v_mul_f32_e32 v116, v115, v115
	v_lshlrev_b32_e32 v118, 16, v192
	v_cvt_pk_bf16_f32 v120, v114, v114
	v_fmac_f32_e32 v116, v114, v114
	v_cvt_pk_bf16_f32 v114, v115, v115
	global_store_short v[160:161], v114, off offset:32
	v_add_f32_e32 v114, v128, v118
	v_lshlrev_b32_e32 v119, 16, v193
	v_fmac_f32_e32 v116, v114, v114
	v_cvt_pk_bf16_f32 v114, v114, v114
	global_store_short v[160:161], v114, off offset:256
	v_add_f32_e32 v114, v124, v119
	v_fmac_f32_e32 v116, v114, v114
	v_cvt_pk_bf16_f32 v114, v114, v114
	global_store_short v[160:161], v114, off offset:288
	v_mov_b32_e32 v115, 0
	v_add_f32_dpp v114, v116, v116 quad_perm:[1,0,3,2] row_mask:0xf bank_mask:0xf bound_ctrl:1
	global_store_short v[160:161], v120, off
	s_nop 0
	v_add_f32_dpp v114, v114, v114 quad_perm:[2,3,0,1] row_mask:0xf bank_mask:0xf bound_ctrl:1
	s_nop 1
	v_add_f32_dpp v114, v114, v114 row_half_mirror row_mask:0xf bank_mask:0xf bound_ctrl:1
	s_nop 1
	v_mov_b32_dpp v115, v114 row_mirror row_mask:0xf bank_mask:0xf
	s_and_saveexec_b64 s[12:13], vcc
	s_cbranch_execz .LBB0_778
	v_add_f32_e32 v116, v114, v115
	v_lshlrev_b64 v[114:115], 6, v[158:159]
	v_lshl_add_u64 v[114:115], v[132:133], 0, v[114:115]
	global_store_dword v[114:115], v116, off
.LBB0_778:
	s_or_b64 exec, exec, s[12:13]
	v_lshlrev_b32_e32 v115, 16, v187
	v_lshlrev_b32_e32 v114, 16, v186
	v_add_f32_e32 v115, v117, v115
	v_add_f32_e32 v114, v121, v114
	v_mul_f32_e32 v117, v115, v115
	v_lshlrev_b32_e32 v116, 16, v188
	v_cvt_pk_bf16_f32 v119, v114, v114
	v_fmac_f32_e32 v117, v114, v114
	v_cvt_pk_bf16_f32 v114, v115, v115
	global_store_short v[156:157], v114, off offset:32
	v_add_f32_e32 v114, v129, v116
	v_lshlrev_b32_e32 v118, 16, v189
	v_fmac_f32_e32 v117, v114, v114
	v_cvt_pk_bf16_f32 v114, v114, v114
	global_store_short v[156:157], v114, off offset:256
	v_add_f32_e32 v114, v125, v118
	v_fmac_f32_e32 v117, v114, v114
	v_cvt_pk_bf16_f32 v114, v114, v114
	global_store_short v[156:157], v114, off offset:288
	v_mov_b32_e32 v115, 0
	v_add_f32_dpp v114, v117, v117 quad_perm:[1,0,3,2] row_mask:0xf bank_mask:0xf bound_ctrl:1
	global_store_short v[156:157], v119, off
	s_nop 0
	v_add_f32_dpp v114, v114, v114 quad_perm:[2,3,0,1] row_mask:0xf bank_mask:0xf bound_ctrl:1
	s_nop 1
	v_add_f32_dpp v114, v114, v114 row_half_mirror row_mask:0xf bank_mask:0xf bound_ctrl:1
	s_nop 1
	v_mov_b32_dpp v115, v114 row_mirror row_mask:0xf bank_mask:0xf
	s_and_saveexec_b64 s[12:13], vcc
	s_cbranch_execz .LBB0_780
	v_add_f32_e32 v116, v114, v115
	v_lshlrev_b64 v[114:115], 6, v[154:155]
	v_lshl_add_u64 v[114:115], v[132:133], 0, v[114:115]
	global_store_dword v[114:115], v116, off
.LBB0_780:
	s_or_b64 exec, exec, s[12:13]
	v_lshlrev_b32_e32 v114, 16, v182
	v_lshlrev_b32_e32 v115, 16, v183
	v_add_f32_e32 v102, v102, v114
	v_cvt_pk_bf16_f32 v114, v102, v102
	v_add_f32_e32 v98, v98, v115
	v_lshlrev_b32_e32 v116, 16, v184
	global_store_short v[152:153], v114, off
	v_mul_f32_e32 v114, v98, v98
	v_cvt_pk_bf16_f32 v98, v98, v98
	v_fmac_f32_e32 v114, v102, v102
	global_store_short v[152:153], v98, off offset:32
	v_add_f32_e32 v98, v110, v116
	v_lshlrev_b32_e32 v117, 16, v185
	v_fmac_f32_e32 v114, v98, v98
	v_cvt_pk_bf16_f32 v98, v98, v98
	global_store_short v[152:153], v98, off offset:256
	v_add_f32_e32 v98, v106, v117
	v_fmac_f32_e32 v114, v98, v98
	v_cvt_pk_bf16_f32 v98, v98, v98
	global_store_short v[152:153], v98, off offset:288
	v_mov_b32_e32 v102, 0
	v_add_f32_dpp v98, v114, v114 quad_perm:[1,0,3,2] row_mask:0xf bank_mask:0xf bound_ctrl:1
	s_nop 1
	v_add_f32_dpp v98, v98, v98 quad_perm:[2,3,0,1] row_mask:0xf bank_mask:0xf bound_ctrl:1
	s_nop 1
	v_add_f32_dpp v98, v98, v98 row_half_mirror row_mask:0xf bank_mask:0xf bound_ctrl:1
	s_nop 1
	v_mov_b32_dpp v102, v98 row_mirror row_mask:0xf bank_mask:0xf
	s_and_saveexec_b64 s[12:13], vcc
	s_cbranch_execz .LBB0_782
	v_lshlrev_b64 v[114:115], 6, v[150:151]
	v_add_f32_e32 v98, v98, v102
	v_lshl_add_u64 v[114:115], v[132:133], 0, v[114:115]
	global_store_dword v[114:115], v98, off
; __device__ __forceinline__ unsigned f2bf(float f) { return pk2(f, f) & 0xffffu; }
; template <int K, int LD>
; __device__ __forceinline__ void phase_resid(int mode) {
;     ...
; #pragma unroll
;       for (int m2 = 0; m2 < 2; ++m2)
; #pragma unroll
;         for (int j = 0; j < 4; ++j)
; #pragma unroll
;           for (int bj = 0; bj < 2; ++bj)
; #pragma unroll
;             for (int n = 0; n < 2; ++n) {
;               const size_t idx = (size_t)(brow + ai * 128 + wr * 64 + (mh * 2 + m2) * 16 + fq * 4 + j) * DM + bcol + bj * 128 + wc * 32 + n * 16 + fr;
;               xo[m2][j][bj][n] = (mode == 0) ? xin[idx] : bf2f(xg[idx]);
;             }
; #pragma unroll
;       for (int m2 = 0; m2 < 2; ++m2)
; #pragma unroll
;         for (int j = 0; j < 4; ++j) {
;           const int m = mh * 2 + m2; const int row = brow + ai * 128 + wr * 64 + m * 16 + fq * 4 + j;
;           float ss = 0.f;
; #pragma unroll
;           for (int bj = 0; bj < 2; ++bj)
; #pragma unroll
;             for (int n = 0; n < 2; ++n) {
;               const size_t idx = (size_t)row * DM + bcol + bj * 128 + wc * 32 + n * 16 + fr;
;               const float xn = xo[m2][j][bj][n] + scale * acc[ai][bj][m][n][j];
;               ss += xn * xn;
;               xg[idx] = (unsigned short)f2bf(xn);
;             }
;           ss = sum16(ss);
;           if (fr == 0) ssq[(size_t)row * 16 + pn0 * 4 + wc] = ss;
;         }
.LBB0_782:
	s_or_b64 exec, exec, s[12:13]
	v_lshlrev_b32_e32 v102, 16, v179
	v_lshlrev_b32_e32 v98, 16, v178
	v_add_f32_e32 v99, v99, v102
	v_add_f32_e32 v98, v103, v98
	v_mul_f32_e32 v102, v99, v99
	v_lshlrev_b32_e32 v106, 16, v180
	v_cvt_pk_bf16_f32 v103, v98, v98
	v_fmac_f32_e32 v102, v98, v98
	v_cvt_pk_bf16_f32 v98, v99, v99
	global_store_short v[148:149], v98, off offset:32
	v_add_f32_e32 v98, v111, v106
	v_lshlrev_b32_e32 v110, 16, v181
	v_fmac_f32_e32 v102, v98, v98
	v_cvt_pk_bf16_f32 v98, v98, v98
	global_store_short v[148:149], v98, off offset:256
	v_add_f32_e32 v98, v107, v110
	v_fmac_f32_e32 v102, v98, v98
	v_cvt_pk_bf16_f32 v98, v98, v98
	global_store_short v[148:149], v98, off offset:288
	v_mov_b32_e32 v99, 0
	v_add_f32_dpp v98, v102, v102 quad_perm:[1,0,3,2] row_mask:0xf bank_mask:0xf bound_ctrl:1
	global_store_short v[148:149], v103, off
	s_nop 0
	v_add_f32_dpp v98, v98, v98 quad_perm:[2,3,0,1] row_mask:0xf bank_mask:0xf bound_ctrl:1
	s_nop 1
	v_add_f32_dpp v98, v98, v98 row_half_mirror row_mask:0xf bank_mask:0xf bound_ctrl:1
	s_nop 1
	v_mov_b32_dpp v99, v98 row_mirror row_mask:0xf bank_mask:0xf
	s_and_saveexec_b64 s[12:13], vcc
	s_cbranch_execz .LBB0_784
	v_add_f32_e32 v102, v98, v99
	v_lshlrev_b64 v[98:99], 6, v[146:147]
	v_lshl_add_u64 v[98:99], v[132:133], 0, v[98:99]
	global_store_dword v[98:99], v102, off
.LBB0_784:
	s_or_b64 exec, exec, s[12:13]
	v_lshlrev_b32_e32 v99, 16, v175
	v_lshlrev_b32_e32 v98, 16, v174
	v_add_f32_e32 v99, v100, v99
	v_add_f32_e32 v98, v104, v98
	v_mul_f32_e32 v100, v99, v99
	v_lshlrev_b32_e32 v102, 16, v176
	v_cvt_pk_bf16_f32 v104, v98, v98
	v_fmac_f32_e32 v100, v98, v98
	v_cvt_pk_bf16_f32 v98, v99, v99
	global_store_short v[144:145], v98, off offset:32
	v_add_f32_e32 v98, v112, v102
	v_lshlrev_b32_e32 v103, 16, v177
	v_fmac_f32_e32 v100, v98, v98
	v_cvt_pk_bf16_f32 v98, v98, v98
	global_store_short v[144:145], v98, off offset:256
	v_add_f32_e32 v98, v108, v103
	v_fmac_f32_e32 v100, v98, v98
	v_cvt_pk_bf16_f32 v98, v98, v98
	global_store_short v[144:145], v98, off offset:288
	v_mov_b32_e32 v99, 0
	v_add_f32_dpp v98, v100, v100 quad_perm:[1,0,3,2] row_mask:0xf bank_mask:0xf bound_ctrl:1
	global_store_short v[144:145], v104, off
	s_nop 0
	v_add_f32_dpp v98, v98, v98 quad_perm:[2,3,0,1] row_mask:0xf bank_mask:0xf bound_ctrl:1
	s_nop 1
	v_add_f32_dpp v98, v98, v98 row_half_mirror row_mask:0xf bank_mask:0xf bound_ctrl:1
	s_nop 1
	v_mov_b32_dpp v99, v98 row_mirror row_mask:0xf bank_mask:0xf
	s_and_saveexec_b64 s[12:13], vcc
	s_cbranch_execz .LBB0_786
	v_add_f32_e32 v100, v98, v99
	v_lshlrev_b64 v[98:99], 6, v[142:143]
	v_lshl_add_u64 v[98:99], v[132:133], 0, v[98:99]
	global_store_dword v[98:99], v100, off
.LBB0_786:
	s_or_b64 exec, exec, s[12:13]
	v_lshlrev_b32_e32 v99, 16, v167
	v_lshlrev_b32_e32 v98, 16, v166
	v_add_f32_e32 v99, v101, v99
	v_add_f32_e32 v98, v105, v98
	v_mul_f32_e32 v101, v99, v99
	v_lshlrev_b32_e32 v100, 16, v168
	v_cvt_pk_bf16_f32 v103, v98, v98
	v_fmac_f32_e32 v101, v98, v98
	v_cvt_pk_bf16_f32 v98, v99, v99
	global_store_short v[140:141], v98, off offset:32
	v_add_f32_e32 v98, v113, v100
	v_lshlrev_b32_e32 v102, 16, v169
	v_fmac_f32_e32 v101, v98, v98
	v_cvt_pk_bf16_f32 v98, v98, v98
	global_store_short v[140:141], v98, off offset:256
	v_add_f32_e32 v98, v109, v102
	v_fmac_f32_e32 v101, v98, v98
	v_cvt_pk_bf16_f32 v98, v98, v98
	global_store_short v[140:141], v98, off offset:288
	v_mov_b32_e32 v99, 0
	v_add_f32_dpp v98, v101, v101 quad_perm:[1,0,3,2] row_mask:0xf bank_mask:0xf bound_ctrl:1
	global_store_short v[140:141], v103, off
	s_nop 0
	v_add_f32_dpp v98, v98, v98 quad_perm:[2,3,0,1] row_mask:0xf bank_mask:0xf bound_ctrl:1
	s_nop 1
	v_add_f32_dpp v98, v98, v98 row_half_mirror row_mask:0xf bank_mask:0xf bound_ctrl:1
	s_nop 1
	v_mov_b32_dpp v99, v98 row_mirror row_mask:0xf bank_mask:0xf
	s_and_saveexec_b64 s[12:13], vcc
	s_cbranch_execz .LBB0_788
	v_add_f32_e32 v100, v98, v99
	v_lshlrev_b64 v[98:99], 6, v[138:139]
	v_lshl_add_u64 v[98:99], v[132:133], 0, v[98:99]
	global_store_dword v[98:99], v100, off
.LBB0_788:
	s_or_b64 exec, exec, s[12:13]
	v_or_b32_e32 v126, 32, v134
	v_ashrrev_i32_e32 v127, 31, v126
	v_or_b32_e32 v122, 33, v134
	v_lshlrev_b64 v[98:99], 11, v[126:127]
	v_ashrrev_i32_e32 v123, 31, v122
	v_or_b32_e32 v118, 34, v134
	v_lshl_add_u64 v[162:163], v[136:137], 0, v[98:99]
	v_lshlrev_b64 v[98:99], 11, v[122:123]
	v_ashrrev_i32_e32 v119, 31, v118
	v_or_b32_e32 v114, 35, v134
	v_lshl_add_u64 v[124:125], v[136:137], 0, v[98:99]
	v_lshlrev_b64 v[98:99], 11, v[118:119]
	v_ashrrev_i32_e32 v115, 31, v114
	v_or_b32_e32 v110, 48, v134
	v_lshl_add_u64 v[120:121], v[136:137], 0, v[98:99]
	v_lshlrev_b64 v[98:99], 11, v[114:115]
	v_ashrrev_i32_e32 v111, 31, v110
	v_or_b32_e32 v106, 49, v134
	v_lshl_add_u64 v[116:117], v[136:137], 0, v[98:99]
	v_lshlrev_b64 v[98:99], 11, v[110:111]
	v_ashrrev_i32_e32 v107, 31, v106
	v_or_b32_e32 v102, 50, v134
	global_load_ushort v164, v[162:163], off
	global_load_ushort v165, v[162:163], off offset:32
	global_load_ushort v166, v[162:163], off offset:256
	global_load_ushort v167, v[162:163], off offset:288
	v_lshl_add_u64 v[112:113], v[136:137], 0, v[98:99]
	v_lshlrev_b64 v[98:99], 11, v[106:107]
	v_ashrrev_i32_e32 v103, 31, v102
	v_lshl_add_u64 v[108:109], v[136:137], 0, v[98:99]
	v_lshlrev_b64 v[98:99], 11, v[102:103]
	global_load_ushort v158, v[124:125], off
	global_load_ushort v159, v[124:125], off offset:32
	global_load_ushort v160, v[124:125], off offset:256
	global_load_ushort v161, v[124:125], off offset:288
	global_load_ushort v154, v[120:121], off
	global_load_ushort v155, v[120:121], off offset:32
	global_load_ushort v156, v[120:121], off offset:256
	global_load_ushort v157, v[120:121], off offset:288
	global_load_ushort v150, v[116:117], off
	global_load_ushort v151, v[116:117], off offset:32
	global_load_ushort v152, v[116:117], off offset:256
	global_load_ushort v153, v[116:117], off offset:288
	global_load_ushort v146, v[112:113], off
	global_load_ushort v147, v[112:113], off offset:32
	global_load_ushort v148, v[112:113], off offset:256
	global_load_ushort v149, v[112:113], off offset:288
	v_lshl_add_u64 v[104:105], v[136:137], 0, v[98:99]
	global_load_ushort v142, v[108:109], off
	global_load_ushort v143, v[108:109], off offset:32
	global_load_ushort v144, v[108:109], off offset:256
	global_load_ushort v145, v[108:109], off offset:288
	global_load_ushort v138, v[104:105], off
	global_load_ushort v139, v[104:105], off offset:32
	global_load_ushort v140, v[104:105], off offset:256
	global_load_ushort v141, v[104:105], off offset:288
	v_or_b32_e32 v98, 51, v134
	v_ashrrev_i32_e32 v99, 31, v98
	v_lshlrev_b64 v[100:101], 11, v[98:99]
	v_lshl_add_u64 v[100:101], v[136:137], 0, v[100:101]
	global_load_ushort v128, v[100:101], off
	global_load_ushort v129, v[100:101], off offset:32
	global_load_ushort v130, v[100:101], off offset:256
	global_load_ushort v135, v[100:101], off offset:288
	s_waitcnt vmcnt(0)
; __device__ __forceinline__ unsigned f2bf(float f) { return pk2(f, f) & 0xffffu; }
; template <int K, int LD>
; __device__ __forceinline__ void phase_resid(int mode) {
;     ...
;       for (int m2 = 0; m2 < 2; ++m2)
; #pragma unroll
;         for (int j = 0; j < 4; ++j) {
;           const int m = mh * 2 + m2; const int row = brow + ai * 128 + wr * 64 + m * 16 + fq * 4 + j;
;           float ss = 0.f;
; #pragma unroll
;           for (int bj = 0; bj < 2; ++bj)
; #pragma unroll
;             for (int n = 0; n < 2; ++n) {
;               const size_t idx = (size_t)row * DM + bcol + bj * 128 + wc * 32 + n * 16 + fr;
;               const float xn = xo[m2][j][bj][n] + scale * acc[ai][bj][m][n][j];
;               ss += xn * xn;
;               xg[idx] = (unsigned short)f2bf(xn);
;             }
;           ss = sum16(ss);
;           if (fr == 0) ssq[(size_t)row * 16 + pn0 * 4 + wc] = ss;
;         }
	v_lshlrev_b32_e32 v164, 16, v164
	v_lshlrev_b32_e32 v165, 16, v165
	v_add_f32_e32 v82, v82, v165
	v_lshlrev_b32_e32 v166, 16, v166
	v_add_f32_e32 v86, v86, v164
	v_mul_f32_e32 v165, v82, v82
	v_lshlrev_b32_e32 v167, 16, v167
	v_add_f32_e32 v94, v94, v166
	v_fmac_f32_e32 v165, v86, v86
	v_add_f32_e32 v90, v90, v167
	v_fmac_f32_e32 v165, v94, v94
	v_cvt_pk_bf16_f32 v82, v82, v82
	v_fmac_f32_e32 v165, v90, v90
	v_cvt_pk_bf16_f32 v164, v86, v86
	v_cvt_pk_bf16_f32 v166, v94, v94
	v_cvt_pk_bf16_f32 v167, v90, v90
	global_store_short v[162:163], v164, off
	global_store_short v[162:163], v82, off offset:32
	global_store_short v[162:163], v166, off offset:256
	global_store_short v[162:163], v167, off offset:288
	v_add_f32_dpp v82, v165, v165 quad_perm:[1,0,3,2] row_mask:0xf bank_mask:0xf bound_ctrl:1
	v_mov_b32_e32 v86, 0
	s_nop 0
	v_add_f32_dpp v82, v82, v82 quad_perm:[2,3,0,1] row_mask:0xf bank_mask:0xf bound_ctrl:1
	s_nop 1
	v_add_f32_dpp v82, v82, v82 row_half_mirror row_mask:0xf bank_mask:0xf bound_ctrl:1
	s_nop 1
	v_mov_b32_dpp v86, v82 row_mirror row_mask:0xf bank_mask:0xf
	s_and_saveexec_b64 s[12:13], vcc
	s_cbranch_execz .LBB0_790
	v_lshlrev_b64 v[126:127], 6, v[126:127]
	v_add_f32_e32 v82, v82, v86
	v_lshl_add_u64 v[126:127], v[132:133], 0, v[126:127]
	global_store_dword v[126:127], v82, off
.LBB0_790:
	s_or_b64 exec, exec, s[12:13]
	v_lshlrev_b32_e32 v86, 16, v159
	v_lshlrev_b32_e32 v82, 16, v158
	v_add_f32_e32 v83, v83, v86
	v_add_f32_e32 v82, v87, v82
	v_mul_f32_e32 v86, v83, v83
	v_lshlrev_b32_e32 v90, 16, v160
	v_cvt_pk_bf16_f32 v87, v82, v82
	v_fmac_f32_e32 v86, v82, v82
	v_cvt_pk_bf16_f32 v82, v83, v83
	global_store_short v[124:125], v82, off offset:32
	v_add_f32_e32 v82, v95, v90
	v_lshlrev_b32_e32 v94, 16, v161
	v_fmac_f32_e32 v86, v82, v82
	v_cvt_pk_bf16_f32 v82, v82, v82
	global_store_short v[124:125], v82, off offset:256
	v_add_f32_e32 v82, v91, v94
	v_fmac_f32_e32 v86, v82, v82
	v_cvt_pk_bf16_f32 v82, v82, v82
	global_store_short v[124:125], v82, off offset:288
	v_mov_b32_e32 v83, 0
	v_add_f32_dpp v82, v86, v86 quad_perm:[1,0,3,2] row_mask:0xf bank_mask:0xf bound_ctrl:1
	global_store_short v[124:125], v87, off
	s_nop 0
	v_add_f32_dpp v82, v82, v82 quad_perm:[2,3,0,1] row_mask:0xf bank_mask:0xf bound_ctrl:1
	s_nop 1
	v_add_f32_dpp v82, v82, v82 row_half_mirror row_mask:0xf bank_mask:0xf bound_ctrl:1
	s_nop 1
	v_mov_b32_dpp v83, v82 row_mirror row_mask:0xf bank_mask:0xf
	s_and_saveexec_b64 s[12:13], vcc
	s_cbranch_execz .LBB0_792
	v_add_f32_e32 v86, v82, v83
	v_lshlrev_b64 v[82:83], 6, v[122:123]
	v_lshl_add_u64 v[82:83], v[132:133], 0, v[82:83]
	global_store_dword v[82:83], v86, off
.LBB0_792:
	s_or_b64 exec, exec, s[12:13]
	v_lshlrev_b32_e32 v83, 16, v155
	v_lshlrev_b32_e32 v82, 16, v154
	v_add_f32_e32 v83, v84, v83
	v_add_f32_e32 v82, v88, v82
	v_mul_f32_e32 v84, v83, v83
	v_lshlrev_b32_e32 v86, 16, v156
	v_cvt_pk_bf16_f32 v88, v82, v82
	v_fmac_f32_e32 v84, v82, v82
	v_cvt_pk_bf16_f32 v82, v83, v83
	global_store_short v[120:121], v82, off offset:32
	v_add_f32_e32 v82, v96, v86
	v_lshlrev_b32_e32 v87, 16, v157
	v_fmac_f32_e32 v84, v82, v82
	v_cvt_pk_bf16_f32 v82, v82, v82
	global_store_short v[120:121], v82, off offset:256
	v_add_f32_e32 v82, v92, v87
	v_fmac_f32_e32 v84, v82, v82
	v_cvt_pk_bf16_f32 v82, v82, v82
	global_store_short v[120:121], v82, off offset:288
	v_mov_b32_e32 v83, 0
	v_add_f32_dpp v82, v84, v84 quad_perm:[1,0,3,2] row_mask:0xf bank_mask:0xf bound_ctrl:1
	global_store_short v[120:121], v88, off
	s_nop 0
	v_add_f32_dpp v82, v82, v82 quad_perm:[2,3,0,1] row_mask:0xf bank_mask:0xf bound_ctrl:1
	s_nop 1
	v_add_f32_dpp v82, v82, v82 row_half_mirror row_mask:0xf bank_mask:0xf bound_ctrl:1
	s_nop 1
	v_mov_b32_dpp v83, v82 row_mirror row_mask:0xf bank_mask:0xf
	s_and_saveexec_b64 s[12:13], vcc
	s_cbranch_execz .LBB0_794
	v_add_f32_e32 v84, v82, v83
	v_lshlrev_b64 v[82:83], 6, v[118:119]
	v_lshl_add_u64 v[82:83], v[132:133], 0, v[82:83]
	global_store_dword v[82:83], v84, off
.LBB0_794:
	s_or_b64 exec, exec, s[12:13]
	v_lshlrev_b32_e32 v83, 16, v151
	v_lshlrev_b32_e32 v82, 16, v150
	v_add_f32_e32 v83, v85, v83
	v_add_f32_e32 v82, v89, v82
	v_mul_f32_e32 v85, v83, v83
	v_lshlrev_b32_e32 v84, 16, v152
	v_cvt_pk_bf16_f32 v87, v82, v82
	v_fmac_f32_e32 v85, v82, v82
	v_cvt_pk_bf16_f32 v82, v83, v83
	global_store_short v[116:117], v82, off offset:32
	v_add_f32_e32 v82, v97, v84
	v_lshlrev_b32_e32 v86, 16, v153
	v_fmac_f32_e32 v85, v82, v82
	v_cvt_pk_bf16_f32 v82, v82, v82
	global_store_short v[116:117], v82, off offset:256
	v_add_f32_e32 v82, v93, v86
	v_fmac_f32_e32 v85, v82, v82
	v_cvt_pk_bf16_f32 v82, v82, v82
	global_store_short v[116:117], v82, off offset:288
	v_mov_b32_e32 v83, 0
	v_add_f32_dpp v82, v85, v85 quad_perm:[1,0,3,2] row_mask:0xf bank_mask:0xf bound_ctrl:1
	global_store_short v[116:117], v87, off
	s_nop 0
	v_add_f32_dpp v82, v82, v82 quad_perm:[2,3,0,1] row_mask:0xf bank_mask:0xf bound_ctrl:1
	s_nop 1
	v_add_f32_dpp v82, v82, v82 row_half_mirror row_mask:0xf bank_mask:0xf bound_ctrl:1
	s_nop 1
	v_mov_b32_dpp v83, v82 row_mirror row_mask:0xf bank_mask:0xf
	s_and_saveexec_b64 s[12:13], vcc
	s_cbranch_execz .LBB0_796
	v_add_f32_e32 v84, v82, v83
	v_lshlrev_b64 v[82:83], 6, v[114:115]
	v_lshl_add_u64 v[82:83], v[132:133], 0, v[82:83]
	global_store_dword v[82:83], v84, off
; __device__ __forceinline__ unsigned f2bf(float f) { return pk2(f, f) & 0xffffu; }
; template <int K, int LD>
; __device__ __forceinline__ void phase_resid(int mode) {
;     ...
;       for (int m2 = 0; m2 < 2; ++m2)
; #pragma unroll
;         for (int j = 0; j < 4; ++j) {
;           const int m = mh * 2 + m2; const int row = brow + ai * 128 + wr * 64 + m * 16 + fq * 4 + j;
;           float ss = 0.f;
; #pragma unroll
;           for (int bj = 0; bj < 2; ++bj)
; #pragma unroll
;             for (int n = 0; n < 2; ++n) {
;               const size_t idx = (size_t)row * DM + bcol + bj * 128 + wc * 32 + n * 16 + fr;
;               const float xn = xo[m2][j][bj][n] + scale * acc[ai][bj][m][n][j];
;               ss += xn * xn;
;               xg[idx] = (unsigned short)f2bf(xn);
;             }
;           ss = sum16(ss);
;           if (fr == 0) ssq[(size_t)row * 16 + pn0 * 4 + wc] = ss;
;         }
.LBB0_796:
	s_or_b64 exec, exec, s[12:13]
	v_lshlrev_b32_e32 v82, 16, v146
	v_lshlrev_b32_e32 v83, 16, v147
	v_add_f32_e32 v70, v70, v82
	v_cvt_pk_bf16_f32 v82, v70, v70
	v_add_f32_e32 v66, v66, v83
	v_lshlrev_b32_e32 v84, 16, v148
	global_store_short v[112:113], v82, off
	v_mul_f32_e32 v82, v66, v66
	v_cvt_pk_bf16_f32 v66, v66, v66
	v_fmac_f32_e32 v82, v70, v70
	global_store_short v[112:113], v66, off offset:32
	v_add_f32_e32 v66, v78, v84
	v_lshlrev_b32_e32 v85, 16, v149
	v_fmac_f32_e32 v82, v66, v66
	v_cvt_pk_bf16_f32 v66, v66, v66
	global_store_short v[112:113], v66, off offset:256
	v_add_f32_e32 v66, v74, v85
	v_fmac_f32_e32 v82, v66, v66
	v_cvt_pk_bf16_f32 v66, v66, v66
	global_store_short v[112:113], v66, off offset:288
	v_mov_b32_e32 v70, 0
	v_add_f32_dpp v66, v82, v82 quad_perm:[1,0,3,2] row_mask:0xf bank_mask:0xf bound_ctrl:1
	s_nop 1
	v_add_f32_dpp v66, v66, v66 quad_perm:[2,3,0,1] row_mask:0xf bank_mask:0xf bound_ctrl:1
	s_nop 1
	v_add_f32_dpp v66, v66, v66 row_half_mirror row_mask:0xf bank_mask:0xf bound_ctrl:1
	s_nop 1
	v_mov_b32_dpp v70, v66 row_mirror row_mask:0xf bank_mask:0xf
	s_and_saveexec_b64 s[12:13], vcc
	s_cbranch_execz .LBB0_798
	v_lshlrev_b64 v[82:83], 6, v[110:111]
	v_add_f32_e32 v66, v66, v70
	v_lshl_add_u64 v[82:83], v[132:133], 0, v[82:83]
	global_store_dword v[82:83], v66, off
.LBB0_798:
	s_or_b64 exec, exec, s[12:13]
	v_lshlrev_b32_e32 v70, 16, v143
	v_lshlrev_b32_e32 v66, 16, v142
	v_add_f32_e32 v67, v67, v70
	v_add_f32_e32 v66, v71, v66
	v_mul_f32_e32 v70, v67, v67
	v_lshlrev_b32_e32 v74, 16, v144
	v_cvt_pk_bf16_f32 v71, v66, v66
	v_fmac_f32_e32 v70, v66, v66
	v_cvt_pk_bf16_f32 v66, v67, v67
	global_store_short v[108:109], v66, off offset:32
	v_add_f32_e32 v66, v79, v74
	v_lshlrev_b32_e32 v78, 16, v145
	v_fmac_f32_e32 v70, v66, v66
	v_cvt_pk_bf16_f32 v66, v66, v66
	global_store_short v[108:109], v66, off offset:256
	v_add_f32_e32 v66, v75, v78
	v_fmac_f32_e32 v70, v66, v66
	v_cvt_pk_bf16_f32 v66, v66, v66
	global_store_short v[108:109], v66, off offset:288
	v_mov_b32_e32 v67, 0
	v_add_f32_dpp v66, v70, v70 quad_perm:[1,0,3,2] row_mask:0xf bank_mask:0xf bound_ctrl:1
	global_store_short v[108:109], v71, off
	s_nop 0
	v_add_f32_dpp v66, v66, v66 quad_perm:[2,3,0,1] row_mask:0xf bank_mask:0xf bound_ctrl:1
	s_nop 1
	v_add_f32_dpp v66, v66, v66 row_half_mirror row_mask:0xf bank_mask:0xf bound_ctrl:1
	s_nop 1
	v_mov_b32_dpp v67, v66 row_mirror row_mask:0xf bank_mask:0xf
	s_and_saveexec_b64 s[12:13], vcc
	s_cbranch_execz .LBB0_800
	v_add_f32_e32 v70, v66, v67
	v_lshlrev_b64 v[66:67], 6, v[106:107]
	v_lshl_add_u64 v[66:67], v[132:133], 0, v[66:67]
	global_store_dword v[66:67], v70, off
.LBB0_800:
	s_or_b64 exec, exec, s[12:13]
	v_lshlrev_b32_e32 v67, 16, v139
	v_lshlrev_b32_e32 v66, 16, v138
	v_add_f32_e32 v67, v68, v67
	v_add_f32_e32 v66, v72, v66
	v_mul_f32_e32 v68, v67, v67
	v_lshlrev_b32_e32 v70, 16, v140
	v_cvt_pk_bf16_f32 v72, v66, v66
	v_fmac_f32_e32 v68, v66, v66
	v_cvt_pk_bf16_f32 v66, v67, v67
	global_store_short v[104:105], v66, off offset:32
	v_add_f32_e32 v66, v80, v70
	v_lshlrev_b32_e32 v71, 16, v141
	v_fmac_f32_e32 v68, v66, v66
	v_cvt_pk_bf16_f32 v66, v66, v66
	global_store_short v[104:105], v66, off offset:256
	v_add_f32_e32 v66, v76, v71
	v_fmac_f32_e32 v68, v66, v66
	v_cvt_pk_bf16_f32 v66, v66, v66
	global_store_short v[104:105], v66, off offset:288
	v_mov_b32_e32 v67, 0
	v_add_f32_dpp v66, v68, v68 quad_perm:[1,0,3,2] row_mask:0xf bank_mask:0xf bound_ctrl:1
	global_store_short v[104:105], v72, off
	s_nop 0
	v_add_f32_dpp v66, v66, v66 quad_perm:[2,3,0,1] row_mask:0xf bank_mask:0xf bound_ctrl:1
	s_nop 1
	v_add_f32_dpp v66, v66, v66 row_half_mirror row_mask:0xf bank_mask:0xf bound_ctrl:1
	s_nop 1
	v_mov_b32_dpp v67, v66 row_mirror row_mask:0xf bank_mask:0xf
	s_and_saveexec_b64 s[12:13], vcc
	s_cbranch_execz .LBB0_802
	v_add_f32_e32 v68, v66, v67
	v_lshlrev_b64 v[66:67], 6, v[102:103]
	v_lshl_add_u64 v[66:67], v[132:133], 0, v[66:67]
	global_store_dword v[66:67], v68, off
.LBB0_802:
	s_or_b64 exec, exec, s[12:13]
	v_lshlrev_b32_e32 v67, 16, v129
	v_lshlrev_b32_e32 v66, 16, v128
	v_add_f32_e32 v67, v69, v67
	v_add_f32_e32 v66, v73, v66
	v_mul_f32_e32 v69, v67, v67
	v_lshlrev_b32_e32 v68, 16, v130
	v_cvt_pk_bf16_f32 v71, v66, v66
	v_fmac_f32_e32 v69, v66, v66
	v_cvt_pk_bf16_f32 v66, v67, v67
	global_store_short v[100:101], v66, off offset:32
	v_add_f32_e32 v66, v81, v68
	v_lshlrev_b32_e32 v70, 16, v135
	v_fmac_f32_e32 v69, v66, v66
	v_cvt_pk_bf16_f32 v66, v66, v66
	global_store_short v[100:101], v66, off offset:256
	v_add_f32_e32 v66, v77, v70
	v_fmac_f32_e32 v69, v66, v66
	v_cvt_pk_bf16_f32 v66, v66, v66
	global_store_short v[100:101], v66, off offset:288
	v_mov_b32_e32 v67, 0
	v_add_f32_dpp v66, v69, v69 quad_perm:[1,0,3,2] row_mask:0xf bank_mask:0xf bound_ctrl:1
	global_store_short v[100:101], v71, off
	s_nop 0
	v_add_f32_dpp v66, v66, v66 quad_perm:[2,3,0,1] row_mask:0xf bank_mask:0xf bound_ctrl:1
	s_nop 1
	v_add_f32_dpp v66, v66, v66 row_half_mirror row_mask:0xf bank_mask:0xf bound_ctrl:1
	s_nop 1
	v_mov_b32_dpp v67, v66 row_mirror row_mask:0xf bank_mask:0xf
	s_and_saveexec_b64 s[12:13], vcc
	s_cbranch_execz .LBB0_804
	v_add_f32_e32 v68, v66, v67
	v_lshlrev_b64 v[66:67], 6, v[98:99]
	v_lshl_add_u64 v[66:67], v[132:133], 0, v[66:67]
	global_store_dword v[66:67], v68, off
; __device__ __forceinline__ unsigned f2bf(float f) { return pk2(f, f) & 0xffffu; }
; template <int K, int LD>
; __device__ __forceinline__ void phase_resid(int mode) {
;     ...
; #pragma unroll
;       for (int m2 = 0; m2 < 2; ++m2)
; #pragma unroll
;         for (int j = 0; j < 4; ++j)
; #pragma unroll
;           for (int bj = 0; bj < 2; ++bj)
; #pragma unroll
;             for (int n = 0; n < 2; ++n) {
;               const size_t idx = (size_t)(brow + ai * 128 + wr * 64 + (mh * 2 + m2) * 16 + fq * 4 + j) * DM + bcol + bj * 128 + wc * 32 + n * 16 + fr;
;               xo[m2][j][bj][n] = (mode == 0) ? xin[idx] : bf2f(xg[idx]);
;             }
; #pragma unroll
;       for (int m2 = 0; m2 < 2; ++m2)
; #pragma unroll
;         for (int j = 0; j < 4; ++j) {
;           const int m = mh * 2 + m2; const int row = brow + ai * 128 + wr * 64 + m * 16 + fq * 4 + j;
;           float ss = 0.f;
; #pragma unroll
;           for (int bj = 0; bj < 2; ++bj)
; #pragma unroll
;             for (int n = 0; n < 2; ++n) {
;               const size_t idx = (size_t)row * DM + bcol + bj * 128 + wc * 32 + n * 16 + fr;
;               const float xn = xo[m2][j][bj][n] + scale * acc[ai][bj][m][n][j];
;               ss += xn * xn;
;               xg[idx] = (unsigned short)f2bf(xn);
;             }
;           ss = sum16(ss);
;           if (fr == 0) ssq[(size_t)row * 16 + pn0 * 4 + wc] = ss;
;         }
.LBB0_804:
	s_or_b64 exec, exec, s[12:13]
	v_add_u32_e32 v94, 0x80, v134
	v_ashrrev_i32_e32 v95, 31, v94
	v_add_u32_e32 v90, 0x81, v134
	v_lshlrev_b64 v[66:67], 11, v[94:95]
	v_ashrrev_i32_e32 v91, 31, v90
	v_add_u32_e32 v86, 0x82, v134
	v_lshl_add_u64 v[124:125], v[136:137], 0, v[66:67]
	v_lshlrev_b64 v[66:67], 11, v[90:91]
	v_ashrrev_i32_e32 v87, 31, v86
	v_add_u32_e32 v82, 0x83, v134
	v_lshl_add_u64 v[92:93], v[136:137], 0, v[66:67]
	v_lshlrev_b64 v[66:67], 11, v[86:87]
	v_ashrrev_i32_e32 v83, 31, v82
	v_add_u32_e32 v78, 0x90, v134
	v_lshl_add_u64 v[88:89], v[136:137], 0, v[66:67]
	v_lshlrev_b64 v[66:67], 11, v[82:83]
	v_ashrrev_i32_e32 v79, 31, v78
	v_add_u32_e32 v74, 0x91, v134
	v_lshl_add_u64 v[84:85], v[136:137], 0, v[66:67]
	v_lshlrev_b64 v[66:67], 11, v[78:79]
	v_ashrrev_i32_e32 v75, 31, v74
	v_add_u32_e32 v70, 0x92, v134
	global_load_ushort v126, v[124:125], off
	global_load_ushort v127, v[124:125], off offset:32
	global_load_ushort v128, v[124:125], off offset:256
	global_load_ushort v129, v[124:125], off offset:288
	v_lshl_add_u64 v[80:81], v[136:137], 0, v[66:67]
	v_lshlrev_b64 v[66:67], 11, v[74:75]
	v_ashrrev_i32_e32 v71, 31, v70
	v_lshl_add_u64 v[76:77], v[136:137], 0, v[66:67]
	v_lshlrev_b64 v[66:67], 11, v[70:71]
	global_load_ushort v120, v[92:93], off
	global_load_ushort v121, v[92:93], off offset:32
	global_load_ushort v122, v[92:93], off offset:256
	global_load_ushort v123, v[92:93], off offset:288
	global_load_ushort v116, v[88:89], off
	global_load_ushort v117, v[88:89], off offset:32
	global_load_ushort v118, v[88:89], off offset:256
	global_load_ushort v119, v[88:89], off offset:288
	global_load_ushort v112, v[84:85], off
	global_load_ushort v113, v[84:85], off offset:32
	global_load_ushort v114, v[84:85], off offset:256
	global_load_ushort v115, v[84:85], off offset:288
	global_load_ushort v108, v[80:81], off
	global_load_ushort v109, v[80:81], off offset:32
	global_load_ushort v110, v[80:81], off offset:256
	global_load_ushort v111, v[80:81], off offset:288
	v_lshl_add_u64 v[72:73], v[136:137], 0, v[66:67]
	global_load_ushort v104, v[76:77], off
	global_load_ushort v105, v[76:77], off offset:32
	global_load_ushort v106, v[76:77], off offset:256
	global_load_ushort v107, v[76:77], off offset:288
	global_load_ushort v100, v[72:73], off
	global_load_ushort v101, v[72:73], off offset:32
	global_load_ushort v102, v[72:73], off offset:256
	global_load_ushort v103, v[72:73], off offset:288
	v_add_u32_e32 v66, 0x93, v134
	v_ashrrev_i32_e32 v67, 31, v66
	v_lshlrev_b64 v[68:69], 11, v[66:67]
	v_lshl_add_u64 v[68:69], v[136:137], 0, v[68:69]
	global_load_ushort v96, v[68:69], off
	global_load_ushort v97, v[68:69], off offset:32
	global_load_ushort v98, v[68:69], off offset:256
	global_load_ushort v99, v[68:69], off offset:288
	s_waitcnt vmcnt(0)
	v_lshlrev_b32_e32 v126, 16, v126
	v_lshlrev_b32_e32 v127, 16, v127
	v_add_f32_e32 v50, v50, v127
	v_lshlrev_b32_e32 v128, 16, v128
	v_add_f32_e32 v54, v54, v126
	v_mul_f32_e32 v127, v50, v50
	v_lshlrev_b32_e32 v129, 16, v129
	v_add_f32_e32 v62, v62, v128
	v_fmac_f32_e32 v127, v54, v54
	v_add_f32_e32 v58, v58, v129
	v_fmac_f32_e32 v127, v62, v62
	v_cvt_pk_bf16_f32 v50, v50, v50
	v_fmac_f32_e32 v127, v58, v58
	v_cvt_pk_bf16_f32 v126, v54, v54
	v_cvt_pk_bf16_f32 v128, v62, v62
	v_cvt_pk_bf16_f32 v129, v58, v58
	global_store_short v[124:125], v126, off
	global_store_short v[124:125], v50, off offset:32
	global_store_short v[124:125], v128, off offset:256
	global_store_short v[124:125], v129, off offset:288
	v_add_f32_dpp v50, v127, v127 quad_perm:[1,0,3,2] row_mask:0xf bank_mask:0xf bound_ctrl:1
	v_mov_b32_e32 v54, 0
	s_nop 0
	v_add_f32_dpp v50, v50, v50 quad_perm:[2,3,0,1] row_mask:0xf bank_mask:0xf bound_ctrl:1
	s_nop 1
	v_add_f32_dpp v50, v50, v50 row_half_mirror row_mask:0xf bank_mask:0xf bound_ctrl:1
	s_nop 1
	v_mov_b32_dpp v54, v50 row_mirror row_mask:0xf bank_mask:0xf
	s_and_saveexec_b64 s[12:13], vcc
	s_cbranch_execz .LBB0_806
	v_lshlrev_b64 v[94:95], 6, v[94:95]
	v_add_f32_e32 v50, v50, v54
	v_lshl_add_u64 v[94:95], v[132:133], 0, v[94:95]
	global_store_dword v[94:95], v50, off
.LBB0_806:
	s_or_b64 exec, exec, s[12:13]
	v_lshlrev_b32_e32 v54, 16, v121
	v_lshlrev_b32_e32 v50, 16, v120
	v_add_f32_e32 v51, v51, v54
	v_add_f32_e32 v50, v55, v50
	v_mul_f32_e32 v54, v51, v51
	v_lshlrev_b32_e32 v58, 16, v122
	v_cvt_pk_bf16_f32 v55, v50, v50
	v_fmac_f32_e32 v54, v50, v50
	v_cvt_pk_bf16_f32 v50, v51, v51
	global_store_short v[92:93], v50, off offset:32
	v_add_f32_e32 v50, v63, v58
	v_lshlrev_b32_e32 v62, 16, v123
	v_fmac_f32_e32 v54, v50, v50
	v_cvt_pk_bf16_f32 v50, v50, v50
	global_store_short v[92:93], v50, off offset:256
	v_add_f32_e32 v50, v59, v62
	v_fmac_f32_e32 v54, v50, v50
	v_cvt_pk_bf16_f32 v50, v50, v50
	global_store_short v[92:93], v50, off offset:288
	v_mov_b32_e32 v51, 0
	v_add_f32_dpp v50, v54, v54 quad_perm:[1,0,3,2] row_mask:0xf bank_mask:0xf bound_ctrl:1
	global_store_short v[92:93], v55, off
	s_nop 0
	v_add_f32_dpp v50, v50, v50 quad_perm:[2,3,0,1] row_mask:0xf bank_mask:0xf bound_ctrl:1
	s_nop 1
	v_add_f32_dpp v50, v50, v50 row_half_mirror row_mask:0xf bank_mask:0xf bound_ctrl:1
	s_nop 1
	v_mov_b32_dpp v51, v50 row_mirror row_mask:0xf bank_mask:0xf
	s_and_saveexec_b64 s[12:13], vcc
	s_cbranch_execz .LBB0_808
	v_add_f32_e32 v54, v50, v51
	v_lshlrev_b64 v[50:51], 6, v[90:91]
	v_lshl_add_u64 v[50:51], v[132:133], 0, v[50:51]
	global_store_dword v[50:51], v54, off
; __device__ __forceinline__ unsigned f2bf(float f) { return pk2(f, f) & 0xffffu; }
; template <int K, int LD>
; __device__ __forceinline__ void phase_resid(int mode) {
;     ...
;       for (int m2 = 0; m2 < 2; ++m2)
; #pragma unroll
;         for (int j = 0; j < 4; ++j) {
;           const int m = mh * 2 + m2; const int row = brow + ai * 128 + wr * 64 + m * 16 + fq * 4 + j;
;           float ss = 0.f;
; #pragma unroll
;           for (int bj = 0; bj < 2; ++bj)
; #pragma unroll
;             for (int n = 0; n < 2; ++n) {
;               const size_t idx = (size_t)row * DM + bcol + bj * 128 + wc * 32 + n * 16 + fr;
;               const float xn = xo[m2][j][bj][n] + scale * acc[ai][bj][m][n][j];
;               ss += xn * xn;
;               xg[idx] = (unsigned short)f2bf(xn);
;             }
;           ss = sum16(ss);
;           if (fr == 0) ssq[(size_t)row * 16 + pn0 * 4 + wc] = ss;
;         }
.LBB0_808:
	s_or_b64 exec, exec, s[12:13]
	v_lshlrev_b32_e32 v51, 16, v117
	v_lshlrev_b32_e32 v50, 16, v116
	v_add_f32_e32 v51, v52, v51
	v_add_f32_e32 v50, v56, v50
	v_mul_f32_e32 v52, v51, v51
	v_lshlrev_b32_e32 v54, 16, v118
	v_cvt_pk_bf16_f32 v56, v50, v50
	v_fmac_f32_e32 v52, v50, v50
	v_cvt_pk_bf16_f32 v50, v51, v51
	global_store_short v[88:89], v50, off offset:32
	v_add_f32_e32 v50, v64, v54
	v_lshlrev_b32_e32 v55, 16, v119
	v_fmac_f32_e32 v52, v50, v50
	v_cvt_pk_bf16_f32 v50, v50, v50
	global_store_short v[88:89], v50, off offset:256
	v_add_f32_e32 v50, v60, v55
	v_fmac_f32_e32 v52, v50, v50
	v_cvt_pk_bf16_f32 v50, v50, v50
	global_store_short v[88:89], v50, off offset:288
	v_mov_b32_e32 v51, 0
	v_add_f32_dpp v50, v52, v52 quad_perm:[1,0,3,2] row_mask:0xf bank_mask:0xf bound_ctrl:1
	global_store_short v[88:89], v56, off
	s_nop 0
	v_add_f32_dpp v50, v50, v50 quad_perm:[2,3,0,1] row_mask:0xf bank_mask:0xf bound_ctrl:1
	s_nop 1
	v_add_f32_dpp v50, v50, v50 row_half_mirror row_mask:0xf bank_mask:0xf bound_ctrl:1
	s_nop 1
	v_mov_b32_dpp v51, v50 row_mirror row_mask:0xf bank_mask:0xf
	s_and_saveexec_b64 s[12:13], vcc
	s_cbranch_execz .LBB0_810
	v_add_f32_e32 v52, v50, v51
	v_lshlrev_b64 v[50:51], 6, v[86:87]
	v_lshl_add_u64 v[50:51], v[132:133], 0, v[50:51]
	global_store_dword v[50:51], v52, off
.LBB0_810:
	s_or_b64 exec, exec, s[12:13]
	v_lshlrev_b32_e32 v51, 16, v113
	v_lshlrev_b32_e32 v50, 16, v112
	v_add_f32_e32 v51, v53, v51
	v_add_f32_e32 v50, v57, v50
	v_mul_f32_e32 v53, v51, v51
	v_lshlrev_b32_e32 v52, 16, v114
	v_cvt_pk_bf16_f32 v55, v50, v50
	v_fmac_f32_e32 v53, v50, v50
	v_cvt_pk_bf16_f32 v50, v51, v51
	global_store_short v[84:85], v50, off offset:32
	v_add_f32_e32 v50, v65, v52
	v_lshlrev_b32_e32 v54, 16, v115
	v_fmac_f32_e32 v53, v50, v50
	v_cvt_pk_bf16_f32 v50, v50, v50
	global_store_short v[84:85], v50, off offset:256
	v_add_f32_e32 v50, v61, v54
	v_fmac_f32_e32 v53, v50, v50
	v_cvt_pk_bf16_f32 v50, v50, v50
	global_store_short v[84:85], v50, off offset:288
	v_mov_b32_e32 v51, 0
	v_add_f32_dpp v50, v53, v53 quad_perm:[1,0,3,2] row_mask:0xf bank_mask:0xf bound_ctrl:1
	global_store_short v[84:85], v55, off
	s_nop 0
	v_add_f32_dpp v50, v50, v50 quad_perm:[2,3,0,1] row_mask:0xf bank_mask:0xf bound_ctrl:1
	s_nop 1
	v_add_f32_dpp v50, v50, v50 row_half_mirror row_mask:0xf bank_mask:0xf bound_ctrl:1
	s_nop 1
	v_mov_b32_dpp v51, v50 row_mirror row_mask:0xf bank_mask:0xf
	s_and_saveexec_b64 s[12:13], vcc
	s_cbranch_execz .LBB0_812
	v_add_f32_e32 v52, v50, v51
	v_lshlrev_b64 v[50:51], 6, v[82:83]
	v_lshl_add_u64 v[50:51], v[132:133], 0, v[50:51]
	global_store_dword v[50:51], v52, off
.LBB0_812:
	s_or_b64 exec, exec, s[12:13]
	v_lshlrev_b32_e32 v50, 16, v108
	v_lshlrev_b32_e32 v51, 16, v109
	v_add_f32_e32 v38, v38, v50
	v_cvt_pk_bf16_f32 v50, v38, v38
	v_add_f32_e32 v34, v34, v51
	v_lshlrev_b32_e32 v52, 16, v110
	global_store_short v[80:81], v50, off
	v_mul_f32_e32 v50, v34, v34
	v_cvt_pk_bf16_f32 v34, v34, v34
	v_fmac_f32_e32 v50, v38, v38
	global_store_short v[80:81], v34, off offset:32
	v_add_f32_e32 v34, v46, v52
	v_lshlrev_b32_e32 v53, 16, v111
	v_fmac_f32_e32 v50, v34, v34
	v_cvt_pk_bf16_f32 v34, v34, v34
	global_store_short v[80:81], v34, off offset:256
	v_add_f32_e32 v34, v42, v53
	v_fmac_f32_e32 v50, v34, v34
	v_cvt_pk_bf16_f32 v34, v34, v34
	global_store_short v[80:81], v34, off offset:288
	v_mov_b32_e32 v38, 0
	v_add_f32_dpp v34, v50, v50 quad_perm:[1,0,3,2] row_mask:0xf bank_mask:0xf bound_ctrl:1
	s_nop 1
	v_add_f32_dpp v34, v34, v34 quad_perm:[2,3,0,1] row_mask:0xf bank_mask:0xf bound_ctrl:1
	s_nop 1
	v_add_f32_dpp v34, v34, v34 row_half_mirror row_mask:0xf bank_mask:0xf bound_ctrl:1
	s_nop 1
	v_mov_b32_dpp v38, v34 row_mirror row_mask:0xf bank_mask:0xf
	s_and_saveexec_b64 s[12:13], vcc
	s_cbranch_execz .LBB0_814
	v_lshlrev_b64 v[50:51], 6, v[78:79]
	v_add_f32_e32 v34, v34, v38
	v_lshl_add_u64 v[50:51], v[132:133], 0, v[50:51]
	global_store_dword v[50:51], v34, off
.LBB0_814:
	s_or_b64 exec, exec, s[12:13]
	v_lshlrev_b32_e32 v38, 16, v105
	v_lshlrev_b32_e32 v34, 16, v104
	v_add_f32_e32 v35, v35, v38
	v_add_f32_e32 v34, v39, v34
	v_mul_f32_e32 v38, v35, v35
	v_lshlrev_b32_e32 v42, 16, v106
	v_cvt_pk_bf16_f32 v39, v34, v34
	v_fmac_f32_e32 v38, v34, v34
	v_cvt_pk_bf16_f32 v34, v35, v35
	global_store_short v[76:77], v34, off offset:32
	v_add_f32_e32 v34, v47, v42
	v_lshlrev_b32_e32 v46, 16, v107
	v_fmac_f32_e32 v38, v34, v34
	v_cvt_pk_bf16_f32 v34, v34, v34
	global_store_short v[76:77], v34, off offset:256
	v_add_f32_e32 v34, v43, v46
	v_fmac_f32_e32 v38, v34, v34
	v_cvt_pk_bf16_f32 v34, v34, v34
	global_store_short v[76:77], v34, off offset:288
	v_mov_b32_e32 v35, 0
	v_add_f32_dpp v34, v38, v38 quad_perm:[1,0,3,2] row_mask:0xf bank_mask:0xf bound_ctrl:1
	global_store_short v[76:77], v39, off
	s_nop 0
	v_add_f32_dpp v34, v34, v34 quad_perm:[2,3,0,1] row_mask:0xf bank_mask:0xf bound_ctrl:1
	s_nop 1
	v_add_f32_dpp v34, v34, v34 row_half_mirror row_mask:0xf bank_mask:0xf bound_ctrl:1
	s_nop 1
	v_mov_b32_dpp v35, v34 row_mirror row_mask:0xf bank_mask:0xf
	s_and_saveexec_b64 s[12:13], vcc
	s_cbranch_execz .LBB0_816
	v_add_f32_e32 v38, v34, v35
	v_lshlrev_b64 v[34:35], 6, v[74:75]
	v_lshl_add_u64 v[34:35], v[132:133], 0, v[34:35]
	global_store_dword v[34:35], v38, off
; __device__ __forceinline__ unsigned f2bf(float f) { return pk2(f, f) & 0xffffu; }
; template <int K, int LD>
; __device__ __forceinline__ void phase_resid(int mode) {
;     ...
; #pragma unroll
;       for (int m2 = 0; m2 < 2; ++m2)
; #pragma unroll
;         for (int j = 0; j < 4; ++j)
; #pragma unroll
;           for (int bj = 0; bj < 2; ++bj)
; #pragma unroll
;             for (int n = 0; n < 2; ++n) {
;               const size_t idx = (size_t)(brow + ai * 128 + wr * 64 + (mh * 2 + m2) * 16 + fq * 4 + j) * DM + bcol + bj * 128 + wc * 32 + n * 16 + fr;
;               xo[m2][j][bj][n] = (mode == 0) ? xin[idx] : bf2f(xg[idx]);
;             }
; #pragma unroll
;       for (int m2 = 0; m2 < 2; ++m2)
; #pragma unroll
;         for (int j = 0; j < 4; ++j) {
;           const int m = mh * 2 + m2; const int row = brow + ai * 128 + wr * 64 + m * 16 + fq * 4 + j;
;           float ss = 0.f;
; #pragma unroll
;           for (int bj = 0; bj < 2; ++bj)
; #pragma unroll
;             for (int n = 0; n < 2; ++n) {
;               const size_t idx = (size_t)row * DM + bcol + bj * 128 + wc * 32 + n * 16 + fr;
;               const float xn = xo[m2][j][bj][n] + scale * acc[ai][bj][m][n][j];
;               ss += xn * xn;
;               xg[idx] = (unsigned short)f2bf(xn);
;             }
;           ss = sum16(ss);
;           if (fr == 0) ssq[(size_t)row * 16 + pn0 * 4 + wc] = ss;
;         }
.LBB0_816:
	s_or_b64 exec, exec, s[12:13]
	v_lshlrev_b32_e32 v35, 16, v101
	v_lshlrev_b32_e32 v34, 16, v100
	v_add_f32_e32 v35, v36, v35
	v_add_f32_e32 v34, v40, v34
	v_mul_f32_e32 v36, v35, v35
	v_lshlrev_b32_e32 v38, 16, v102
	v_cvt_pk_bf16_f32 v40, v34, v34
	v_fmac_f32_e32 v36, v34, v34
	v_cvt_pk_bf16_f32 v34, v35, v35
	global_store_short v[72:73], v34, off offset:32
	v_add_f32_e32 v34, v48, v38
	v_lshlrev_b32_e32 v39, 16, v103
	v_fmac_f32_e32 v36, v34, v34
	v_cvt_pk_bf16_f32 v34, v34, v34
	global_store_short v[72:73], v34, off offset:256
	v_add_f32_e32 v34, v44, v39
	v_fmac_f32_e32 v36, v34, v34
	v_cvt_pk_bf16_f32 v34, v34, v34
	global_store_short v[72:73], v34, off offset:288
	v_mov_b32_e32 v35, 0
	v_add_f32_dpp v34, v36, v36 quad_perm:[1,0,3,2] row_mask:0xf bank_mask:0xf bound_ctrl:1
	global_store_short v[72:73], v40, off
	s_nop 0
	v_add_f32_dpp v34, v34, v34 quad_perm:[2,3,0,1] row_mask:0xf bank_mask:0xf bound_ctrl:1
	s_nop 1
	v_add_f32_dpp v34, v34, v34 row_half_mirror row_mask:0xf bank_mask:0xf bound_ctrl:1
	s_nop 1
	v_mov_b32_dpp v35, v34 row_mirror row_mask:0xf bank_mask:0xf
	s_and_saveexec_b64 s[12:13], vcc
	s_cbranch_execz .LBB0_818
	v_add_f32_e32 v36, v34, v35
	v_lshlrev_b64 v[34:35], 6, v[70:71]
	v_lshl_add_u64 v[34:35], v[132:133], 0, v[34:35]
	global_store_dword v[34:35], v36, off
.LBB0_818:
	s_or_b64 exec, exec, s[12:13]
	v_lshlrev_b32_e32 v35, 16, v97
	v_lshlrev_b32_e32 v34, 16, v96
	v_add_f32_e32 v35, v37, v35
	v_add_f32_e32 v34, v41, v34
	v_mul_f32_e32 v37, v35, v35
	v_lshlrev_b32_e32 v36, 16, v98
	v_cvt_pk_bf16_f32 v39, v34, v34
	v_fmac_f32_e32 v37, v34, v34
	v_cvt_pk_bf16_f32 v34, v35, v35
	global_store_short v[68:69], v34, off offset:32
	v_add_f32_e32 v34, v49, v36
	v_lshlrev_b32_e32 v38, 16, v99
	v_fmac_f32_e32 v37, v34, v34
	v_cvt_pk_bf16_f32 v34, v34, v34
	global_store_short v[68:69], v34, off offset:256
	v_add_f32_e32 v34, v45, v38
	v_fmac_f32_e32 v37, v34, v34
	v_cvt_pk_bf16_f32 v34, v34, v34
	global_store_short v[68:69], v34, off offset:288
	v_mov_b32_e32 v35, 0
	v_add_f32_dpp v34, v37, v37 quad_perm:[1,0,3,2] row_mask:0xf bank_mask:0xf bound_ctrl:1
	global_store_short v[68:69], v39, off
	s_nop 0
	v_add_f32_dpp v34, v34, v34 quad_perm:[2,3,0,1] row_mask:0xf bank_mask:0xf bound_ctrl:1
	s_nop 1
	v_add_f32_dpp v34, v34, v34 row_half_mirror row_mask:0xf bank_mask:0xf bound_ctrl:1
	s_nop 1
	v_mov_b32_dpp v35, v34 row_mirror row_mask:0xf bank_mask:0xf
	s_and_saveexec_b64 s[12:13], vcc
	s_cbranch_execz .LBB0_820
	v_add_f32_e32 v36, v34, v35
	v_lshlrev_b64 v[34:35], 6, v[66:67]
	v_lshl_add_u64 v[34:35], v[132:133], 0, v[34:35]
	global_store_dword v[34:35], v36, off
.LBB0_820:
	s_or_b64 exec, exec, s[12:13]
	v_add_u32_e32 v62, 0xa0, v134
	v_ashrrev_i32_e32 v63, 31, v62
	v_add_u32_e32 v58, 0xa1, v134
	v_lshlrev_b64 v[34:35], 11, v[62:63]
	v_ashrrev_i32_e32 v59, 31, v58
	v_add_u32_e32 v54, 0xa2, v134
	v_lshl_add_u64 v[92:93], v[136:137], 0, v[34:35]
	v_lshlrev_b64 v[34:35], 11, v[58:59]
	v_ashrrev_i32_e32 v55, 31, v54
	v_add_u32_e32 v50, 0xa3, v134
	v_lshl_add_u64 v[60:61], v[136:137], 0, v[34:35]
	v_lshlrev_b64 v[34:35], 11, v[54:55]
	v_ashrrev_i32_e32 v51, 31, v50
	v_add_u32_e32 v46, 0xb0, v134
	v_lshl_add_u64 v[56:57], v[136:137], 0, v[34:35]
	v_lshlrev_b64 v[34:35], 11, v[50:51]
	v_ashrrev_i32_e32 v47, 31, v46
	v_add_u32_e32 v42, 0xb1, v134
	v_lshl_add_u64 v[52:53], v[136:137], 0, v[34:35]
	v_lshlrev_b64 v[34:35], 11, v[46:47]
	v_ashrrev_i32_e32 v43, 31, v42
	v_add_u32_e32 v38, 0xb2, v134
	global_load_ushort v94, v[92:93], off
	global_load_ushort v95, v[92:93], off offset:32
	global_load_ushort v96, v[92:93], off offset:256
	global_load_ushort v97, v[92:93], off offset:288
	v_lshl_add_u64 v[48:49], v[136:137], 0, v[34:35]
	v_lshlrev_b64 v[34:35], 11, v[42:43]
	v_ashrrev_i32_e32 v39, 31, v38
	v_lshl_add_u64 v[44:45], v[136:137], 0, v[34:35]
	v_lshlrev_b64 v[34:35], 11, v[38:39]
	global_load_ushort v88, v[60:61], off
	global_load_ushort v89, v[60:61], off offset:32
	global_load_ushort v90, v[60:61], off offset:256
	global_load_ushort v91, v[60:61], off offset:288
	global_load_ushort v84, v[56:57], off
	global_load_ushort v85, v[56:57], off offset:32
	global_load_ushort v86, v[56:57], off offset:256
	global_load_ushort v87, v[56:57], off offset:288
	global_load_ushort v80, v[52:53], off
	global_load_ushort v81, v[52:53], off offset:32
	global_load_ushort v82, v[52:53], off offset:256
	global_load_ushort v83, v[52:53], off offset:288
	global_load_ushort v76, v[48:49], off
	global_load_ushort v77, v[48:49], off offset:32
	global_load_ushort v78, v[48:49], off offset:256
	global_load_ushort v79, v[48:49], off offset:288
	v_lshl_add_u64 v[40:41], v[136:137], 0, v[34:35]
	global_load_ushort v72, v[44:45], off
	global_load_ushort v73, v[44:45], off offset:32
	global_load_ushort v74, v[44:45], off offset:256
	global_load_ushort v75, v[44:45], off offset:288
	global_load_ushort v68, v[40:41], off
	global_load_ushort v69, v[40:41], off offset:32
	global_load_ushort v70, v[40:41], off offset:256
	global_load_ushort v71, v[40:41], off offset:288
	v_add_u32_e32 v34, 0xb3, v134
	v_ashrrev_i32_e32 v35, 31, v34
	v_lshlrev_b64 v[36:37], 11, v[34:35]
	v_lshl_add_u64 v[36:37], v[136:137], 0, v[36:37]
	global_load_ushort v64, v[36:37], off
	global_load_ushort v65, v[36:37], off offset:32
	global_load_ushort v66, v[36:37], off offset:256
	global_load_ushort v67, v[36:37], off offset:288
	s_waitcnt vmcnt(0)
	v_lshlrev_b32_e32 v94, 16, v94
	v_lshlrev_b32_e32 v95, 16, v95
	v_add_f32_e32 v18, v18, v95
	v_lshlrev_b32_e32 v96, 16, v96
	v_add_f32_e32 v22, v22, v94
	v_mul_f32_e32 v95, v18, v18
	v_lshlrev_b32_e32 v97, 16, v97
	v_add_f32_e32 v30, v30, v96
	v_fmac_f32_e32 v95, v22, v22
	v_add_f32_e32 v26, v26, v97
	v_fmac_f32_e32 v95, v30, v30
	v_cvt_pk_bf16_f32 v18, v18, v18
	v_fmac_f32_e32 v95, v26, v26
	v_cvt_pk_bf16_f32 v94, v22, v22
	v_cvt_pk_bf16_f32 v96, v30, v30
	v_cvt_pk_bf16_f32 v97, v26, v26
	global_store_short v[92:93], v94, off
	global_store_short v[92:93], v18, off offset:32
	global_store_short v[92:93], v96, off offset:256
	global_store_short v[92:93], v97, off offset:288
	v_add_f32_dpp v18, v95, v95 quad_perm:[1,0,3,2] row_mask:0xf bank_mask:0xf bound_ctrl:1
	v_mov_b32_e32 v22, 0
	s_nop 0
	v_add_f32_dpp v18, v18, v18 quad_perm:[2,3,0,1] row_mask:0xf bank_mask:0xf bound_ctrl:1
	s_nop 1
	v_add_f32_dpp v18, v18, v18 row_half_mirror row_mask:0xf bank_mask:0xf bound_ctrl:1
	s_nop 1
	v_mov_b32_dpp v22, v18 row_mirror row_mask:0xf bank_mask:0xf
	s_and_saveexec_b64 s[12:13], vcc
	s_cbranch_execz .LBB0_822
	v_lshlrev_b64 v[62:63], 6, v[62:63]
	v_add_f32_e32 v18, v18, v22
	v_lshl_add_u64 v[62:63], v[132:133], 0, v[62:63]
	global_store_dword v[62:63], v18, off
; __device__ __forceinline__ unsigned f2bf(float f) { return pk2(f, f) & 0xffffu; }
; template <int K, int LD>
; __device__ __forceinline__ void phase_resid(int mode) {
;     ...
;       for (int m2 = 0; m2 < 2; ++m2)
; #pragma unroll
;         for (int j = 0; j < 4; ++j) {
;           const int m = mh * 2 + m2; const int row = brow + ai * 128 + wr * 64 + m * 16 + fq * 4 + j;
;           float ss = 0.f;
; #pragma unroll
;           for (int bj = 0; bj < 2; ++bj)
; #pragma unroll
;             for (int n = 0; n < 2; ++n) {
;               const size_t idx = (size_t)row * DM + bcol + bj * 128 + wc * 32 + n * 16 + fr;
;               const float xn = xo[m2][j][bj][n] + scale * acc[ai][bj][m][n][j];
;               ss += xn * xn;
;               xg[idx] = (unsigned short)f2bf(xn);
;             }
;           ss = sum16(ss);
;           if (fr == 0) ssq[(size_t)row * 16 + pn0 * 4 + wc] = ss;
;         }
.LBB0_822:
	s_or_b64 exec, exec, s[12:13]
	v_lshlrev_b32_e32 v22, 16, v89
	v_lshlrev_b32_e32 v18, 16, v88
	v_add_f32_e32 v19, v19, v22
	v_add_f32_e32 v18, v23, v18
	v_mul_f32_e32 v22, v19, v19
	v_lshlrev_b32_e32 v26, 16, v90
	v_cvt_pk_bf16_f32 v23, v18, v18
	v_fmac_f32_e32 v22, v18, v18
	v_cvt_pk_bf16_f32 v18, v19, v19
	global_store_short v[60:61], v18, off offset:32
	v_add_f32_e32 v18, v31, v26
	v_lshlrev_b32_e32 v30, 16, v91
	v_fmac_f32_e32 v22, v18, v18
	v_cvt_pk_bf16_f32 v18, v18, v18
	global_store_short v[60:61], v18, off offset:256
	v_add_f32_e32 v18, v27, v30
	v_fmac_f32_e32 v22, v18, v18
	v_cvt_pk_bf16_f32 v18, v18, v18
	global_store_short v[60:61], v18, off offset:288
	v_mov_b32_e32 v19, 0
	v_add_f32_dpp v18, v22, v22 quad_perm:[1,0,3,2] row_mask:0xf bank_mask:0xf bound_ctrl:1
	global_store_short v[60:61], v23, off
	s_nop 0
	v_add_f32_dpp v18, v18, v18 quad_perm:[2,3,0,1] row_mask:0xf bank_mask:0xf bound_ctrl:1
	s_nop 1
	v_add_f32_dpp v18, v18, v18 row_half_mirror row_mask:0xf bank_mask:0xf bound_ctrl:1
	s_nop 1
	v_mov_b32_dpp v19, v18 row_mirror row_mask:0xf bank_mask:0xf
	s_and_saveexec_b64 s[12:13], vcc
	s_cbranch_execz .LBB0_824
	v_add_f32_e32 v22, v18, v19
	v_lshlrev_b64 v[18:19], 6, v[58:59]
	v_lshl_add_u64 v[18:19], v[132:133], 0, v[18:19]
	global_store_dword v[18:19], v22, off
.LBB0_824:
	s_or_b64 exec, exec, s[12:13]
	v_lshlrev_b32_e32 v19, 16, v85
	v_lshlrev_b32_e32 v18, 16, v84
	v_add_f32_e32 v19, v20, v19
	v_add_f32_e32 v18, v24, v18
	v_mul_f32_e32 v20, v19, v19
	v_lshlrev_b32_e32 v22, 16, v86
	v_cvt_pk_bf16_f32 v24, v18, v18
	v_fmac_f32_e32 v20, v18, v18
	v_cvt_pk_bf16_f32 v18, v19, v19
	global_store_short v[56:57], v18, off offset:32
	v_add_f32_e32 v18, v32, v22
	v_lshlrev_b32_e32 v23, 16, v87
	v_fmac_f32_e32 v20, v18, v18
	v_cvt_pk_bf16_f32 v18, v18, v18
	global_store_short v[56:57], v18, off offset:256
	v_add_f32_e32 v18, v28, v23
	v_fmac_f32_e32 v20, v18, v18
	v_cvt_pk_bf16_f32 v18, v18, v18
	global_store_short v[56:57], v18, off offset:288
	v_mov_b32_e32 v19, 0
	v_add_f32_dpp v18, v20, v20 quad_perm:[1,0,3,2] row_mask:0xf bank_mask:0xf bound_ctrl:1
	global_store_short v[56:57], v24, off
	s_nop 0
	v_add_f32_dpp v18, v18, v18 quad_perm:[2,3,0,1] row_mask:0xf bank_mask:0xf bound_ctrl:1
	s_nop 1
	v_add_f32_dpp v18, v18, v18 row_half_mirror row_mask:0xf bank_mask:0xf bound_ctrl:1
	s_nop 1
	v_mov_b32_dpp v19, v18 row_mirror row_mask:0xf bank_mask:0xf
	s_and_saveexec_b64 s[12:13], vcc
	s_cbranch_execz .LBB0_826
	v_add_f32_e32 v20, v18, v19
	v_lshlrev_b64 v[18:19], 6, v[54:55]
	v_lshl_add_u64 v[18:19], v[132:133], 0, v[18:19]
	global_store_dword v[18:19], v20, off
.LBB0_826:
	s_or_b64 exec, exec, s[12:13]
	v_lshlrev_b32_e32 v19, 16, v81
	v_lshlrev_b32_e32 v18, 16, v80
	v_add_f32_e32 v19, v21, v19
	v_add_f32_e32 v18, v25, v18
	v_mul_f32_e32 v21, v19, v19
	v_lshlrev_b32_e32 v20, 16, v82
	v_cvt_pk_bf16_f32 v23, v18, v18
	v_fmac_f32_e32 v21, v18, v18
	v_cvt_pk_bf16_f32 v18, v19, v19
	global_store_short v[52:53], v18, off offset:32
	v_add_f32_e32 v18, v33, v20
	v_lshlrev_b32_e32 v22, 16, v83
	v_fmac_f32_e32 v21, v18, v18
	v_cvt_pk_bf16_f32 v18, v18, v18
	global_store_short v[52:53], v18, off offset:256
	v_add_f32_e32 v18, v29, v22
	v_fmac_f32_e32 v21, v18, v18
	v_cvt_pk_bf16_f32 v18, v18, v18
	global_store_short v[52:53], v18, off offset:288
	v_mov_b32_e32 v19, 0
	v_add_f32_dpp v18, v21, v21 quad_perm:[1,0,3,2] row_mask:0xf bank_mask:0xf bound_ctrl:1
	global_store_short v[52:53], v23, off
	s_nop 0
	v_add_f32_dpp v18, v18, v18 quad_perm:[2,3,0,1] row_mask:0xf bank_mask:0xf bound_ctrl:1
	s_nop 1
	v_add_f32_dpp v18, v18, v18 row_half_mirror row_mask:0xf bank_mask:0xf bound_ctrl:1
	s_nop 1
	v_mov_b32_dpp v19, v18 row_mirror row_mask:0xf bank_mask:0xf
	s_and_saveexec_b64 s[12:13], vcc
	s_cbranch_execz .LBB0_828
	v_add_f32_e32 v20, v18, v19
	v_lshlrev_b64 v[18:19], 6, v[50:51]
	v_lshl_add_u64 v[18:19], v[132:133], 0, v[18:19]
	global_store_dword v[18:19], v20, off
; __device__ __forceinline__ unsigned f2bf(float f) { return pk2(f, f) & 0xffffu; }
; template <int K, int LD>
; __device__ __forceinline__ void phase_resid(int mode) {
;     ...
;       for (int m2 = 0; m2 < 2; ++m2)
; #pragma unroll
;         for (int j = 0; j < 4; ++j) {
;           const int m = mh * 2 + m2; const int row = brow + ai * 128 + wr * 64 + m * 16 + fq * 4 + j;
;           float ss = 0.f;
; #pragma unroll
;           for (int bj = 0; bj < 2; ++bj)
; #pragma unroll
;             for (int n = 0; n < 2; ++n) {
;               const size_t idx = (size_t)row * DM + bcol + bj * 128 + wc * 32 + n * 16 + fr;
;               const float xn = xo[m2][j][bj][n] + scale * acc[ai][bj][m][n][j];
;               ss += xn * xn;
;               xg[idx] = (unsigned short)f2bf(xn);
;             }
;           ss = sum16(ss);
;           if (fr == 0) ssq[(size_t)row * 16 + pn0 * 4 + wc] = ss;
;         }
;     }
;   }
.LBB0_828:
	s_or_b64 exec, exec, s[12:13]
	v_lshlrev_b32_e32 v18, 16, v76
	v_lshlrev_b32_e32 v19, 16, v77
	v_add_f32_e32 v6, v6, v18
	v_cvt_pk_bf16_f32 v18, v6, v6
	v_add_f32_e32 v2, v2, v19
	v_lshlrev_b32_e32 v20, 16, v78
	global_store_short v[48:49], v18, off
	v_mul_f32_e32 v18, v2, v2
	v_cvt_pk_bf16_f32 v2, v2, v2
	v_fmac_f32_e32 v18, v6, v6
	global_store_short v[48:49], v2, off offset:32
	v_add_f32_e32 v2, v14, v20
	v_lshlrev_b32_e32 v21, 16, v79
	v_fmac_f32_e32 v18, v2, v2
	v_cvt_pk_bf16_f32 v2, v2, v2
	global_store_short v[48:49], v2, off offset:256
	v_add_f32_e32 v2, v10, v21
	v_fmac_f32_e32 v18, v2, v2
	v_cvt_pk_bf16_f32 v2, v2, v2
	global_store_short v[48:49], v2, off offset:288
	v_mov_b32_e32 v6, 0
	v_add_f32_dpp v2, v18, v18 quad_perm:[1,0,3,2] row_mask:0xf bank_mask:0xf bound_ctrl:1
	s_nop 1
	v_add_f32_dpp v2, v2, v2 quad_perm:[2,3,0,1] row_mask:0xf bank_mask:0xf bound_ctrl:1
	s_nop 1
	v_add_f32_dpp v2, v2, v2 row_half_mirror row_mask:0xf bank_mask:0xf bound_ctrl:1
	s_nop 1
	v_mov_b32_dpp v6, v2 row_mirror row_mask:0xf bank_mask:0xf
	s_and_saveexec_b64 s[12:13], vcc
	s_cbranch_execz .LBB0_830
	v_lshlrev_b64 v[18:19], 6, v[46:47]
	v_add_f32_e32 v2, v2, v6
	v_lshl_add_u64 v[18:19], v[132:133], 0, v[18:19]
	global_store_dword v[18:19], v2, off
.LBB0_830:
	s_or_b64 exec, exec, s[12:13]
	v_lshlrev_b32_e32 v6, 16, v73
	v_lshlrev_b32_e32 v2, 16, v72
	v_add_f32_e32 v3, v3, v6
	v_add_f32_e32 v2, v7, v2
	v_mul_f32_e32 v6, v3, v3
	v_lshlrev_b32_e32 v10, 16, v74
	v_cvt_pk_bf16_f32 v7, v2, v2
	v_fmac_f32_e32 v6, v2, v2
	v_cvt_pk_bf16_f32 v2, v3, v3
	global_store_short v[44:45], v2, off offset:32
	v_add_f32_e32 v2, v15, v10
	v_lshlrev_b32_e32 v14, 16, v75
	v_fmac_f32_e32 v6, v2, v2
	v_cvt_pk_bf16_f32 v2, v2, v2
	global_store_short v[44:45], v2, off offset:256
	v_add_f32_e32 v2, v11, v14
	v_fmac_f32_e32 v6, v2, v2
	v_cvt_pk_bf16_f32 v2, v2, v2
	global_store_short v[44:45], v2, off offset:288
	v_mov_b32_e32 v3, 0
	v_add_f32_dpp v2, v6, v6 quad_perm:[1,0,3,2] row_mask:0xf bank_mask:0xf bound_ctrl:1
	global_store_short v[44:45], v7, off
	s_nop 0
	v_add_f32_dpp v2, v2, v2 quad_perm:[2,3,0,1] row_mask:0xf bank_mask:0xf bound_ctrl:1
	s_nop 1
	v_add_f32_dpp v2, v2, v2 row_half_mirror row_mask:0xf bank_mask:0xf bound_ctrl:1
	s_nop 1
	v_mov_b32_dpp v3, v2 row_mirror row_mask:0xf bank_mask:0xf
	s_and_saveexec_b64 s[12:13], vcc
	s_cbranch_execz .LBB0_832
	v_add_f32_e32 v6, v2, v3
	v_lshlrev_b64 v[2:3], 6, v[42:43]
	v_lshl_add_u64 v[2:3], v[132:133], 0, v[2:3]
	global_store_dword v[2:3], v6, off
.LBB0_832:
	s_or_b64 exec, exec, s[12:13]
	v_lshlrev_b32_e32 v3, 16, v69
	v_lshlrev_b32_e32 v2, 16, v68
	v_add_f32_e32 v3, v4, v3
	v_add_f32_e32 v2, v8, v2
	v_mul_f32_e32 v4, v3, v3
	v_lshlrev_b32_e32 v6, 16, v70
	v_cvt_pk_bf16_f32 v8, v2, v2
	v_fmac_f32_e32 v4, v2, v2
	v_cvt_pk_bf16_f32 v2, v3, v3
	global_store_short v[40:41], v2, off offset:32
	v_add_f32_e32 v2, v16, v6
	v_lshlrev_b32_e32 v7, 16, v71
	v_fmac_f32_e32 v4, v2, v2
	v_cvt_pk_bf16_f32 v2, v2, v2
	global_store_short v[40:41], v2, off offset:256
	v_add_f32_e32 v2, v12, v7
	v_fmac_f32_e32 v4, v2, v2
	v_cvt_pk_bf16_f32 v2, v2, v2
	global_store_short v[40:41], v2, off offset:288
	v_mov_b32_e32 v3, 0
	v_add_f32_dpp v2, v4, v4 quad_perm:[1,0,3,2] row_mask:0xf bank_mask:0xf bound_ctrl:1
	global_store_short v[40:41], v8, off
	s_nop 0
	v_add_f32_dpp v2, v2, v2 quad_perm:[2,3,0,1] row_mask:0xf bank_mask:0xf bound_ctrl:1
	s_nop 1
	v_add_f32_dpp v2, v2, v2 row_half_mirror row_mask:0xf bank_mask:0xf bound_ctrl:1
	s_nop 1
	v_mov_b32_dpp v3, v2 row_mirror row_mask:0xf bank_mask:0xf
	s_and_saveexec_b64 s[12:13], vcc
	s_cbranch_execz .LBB0_834
	v_add_f32_e32 v4, v2, v3
	v_lshlrev_b64 v[2:3], 6, v[38:39]
	v_lshl_add_u64 v[2:3], v[132:133], 0, v[2:3]
	global_store_dword v[2:3], v4, off
.LBB0_834:
	s_or_b64 exec, exec, s[12:13]
	v_lshlrev_b32_e32 v3, 16, v65
	v_lshlrev_b32_e32 v2, 16, v64
	v_add_f32_e32 v3, v5, v3
	v_add_f32_e32 v2, v9, v2
	v_mul_f32_e32 v5, v3, v3
	v_lshlrev_b32_e32 v4, 16, v66
	v_cvt_pk_bf16_f32 v7, v2, v2
	v_fmac_f32_e32 v5, v2, v2
	v_cvt_pk_bf16_f32 v2, v3, v3
	global_store_short v[36:37], v2, off offset:32
	v_add_f32_e32 v2, v17, v4
	v_lshlrev_b32_e32 v6, 16, v67
	v_fmac_f32_e32 v5, v2, v2
	v_cvt_pk_bf16_f32 v2, v2, v2
	global_store_short v[36:37], v2, off offset:256
	v_add_f32_e32 v2, v13, v6
	v_fmac_f32_e32 v5, v2, v2
	v_cvt_pk_bf16_f32 v2, v2, v2
	global_store_short v[36:37], v2, off offset:288
	v_mov_b32_e32 v3, 0
	v_add_f32_dpp v2, v5, v5 quad_perm:[1,0,3,2] row_mask:0xf bank_mask:0xf bound_ctrl:1
	global_store_short v[36:37], v7, off
	s_nop 0
	v_add_f32_dpp v2, v2, v2 quad_perm:[2,3,0,1] row_mask:0xf bank_mask:0xf bound_ctrl:1
	s_nop 1
	v_add_f32_dpp v2, v2, v2 row_half_mirror row_mask:0xf bank_mask:0xf bound_ctrl:1
	s_nop 1
	v_mov_b32_dpp v3, v2 row_mirror row_mask:0xf bank_mask:0xf
	s_and_saveexec_b64 s[12:13], vcc
	s_cbranch_execz .LBB0_763
	v_add_f32_e32 v4, v2, v3
	v_lshlrev_b64 v[2:3], 6, v[34:35]
	v_lshl_add_u64 v[2:3], v[132:133], 0, v[2:3]
	global_store_dword v[2:3], v4, off
	s_branch .LBB0_763

; #define GAS __attribute__((address_space(1)))
; __device__ __forceinline__ unsigned f2bf(float f) { return pk2(f, f) & 0xffffu; }
; __device__ __forceinline__ float sigmoidf_(float v) { return __builtin_amdgcn_rcpf(1.f + __builtin_amdgcn_exp2f(-LOG2E * v)); }
; __device__ __forceinline__ void phase_up(int pass) {
;     ...
;     EPI_IDS
;     const float* rr = (const float*)(smem_raw + LDS_RR) + par * 256;
;     GAS char* tb = (GAS char*)act + ((size_t)brow * FFP + (bcol >> 1)) * 2;
;     const unsigned off0 = (unsigned)((wr * 64 + fq * 4) * FFP + wc * 16 + fr) * 2u;
; #pragma unroll
;     for (int ai = 0; ai < 2; ++ai)
; #pragma unroll
;       for (int m = 0; m < 4; ++m)
; #pragma unroll
;         for (int j = 0; j < 4; ++j) {
;           const int rowl = ai * 128 + wr * 64 + m * 16 + fq * 4 + j;
;           const float r = rr[rowl];
; #pragma unroll
;           for (int bj = 0; bj < 2; ++bj) {
;             const float g = acc[ai][bj][m][0][j] * r, u = acc[ai][bj][m][1][j] * r;
;             const float v = g * sigmoidf_(g) * u;
;             *(GAS unsigned short*)(tb + (off0 + (unsigned)(((ai * 128 + m * 16 + j) * FFP + bj * 64) * 2))) = (unsigned short)f2bf(v);
;           }
;         }
.LBB0_880:
	v_mov_b32_e32 v130, v170
	s_lshl_b32 s15, s37, 10
	v_ashrrev_i32_e32 v132, 2, v130
	v_lshrrev_b32_e32 v142, 2, v130
	v_and_b32_e32 v135, 15, v130
	s_addk_i32 s15, 0x100
	v_and_b32_e32 v132, 0xffffffc0, v132
	v_and_b32_e32 v130, 12, v142
	s_add_i32 s16, s15, 0x20000
	v_or_b32_e32 v136, v132, v130
	v_lshlrev_b32_e32 v132, 2, v132
	v_lshlrev_b32_e32 v130, 2, v130
	v_add3_u32 v130, s16, v132, v130
	ds_read2_b32 v[132:133], v130 offset1:1
	v_mul_lo_u32 v143, v136, s40
	s_lshl_b32 s17, s41, 7
	s_mul_hi_i32 s15, s14, 0xb40
	s_mulk_i32 s14, 0xb40
	s_waitcnt lgkmcnt(0)
	v_mul_f32_e32 v144, v118, v132
	v_mul_f32_e32 v118, 0xbfb8aa3b, v144
	v_exp_f32_e32 v145, v118
	v_and_b32_e32 v118, 48, v142
	v_or3_b32 v118, v143, v118, v135
	v_mul_f32_e32 v126, v126, v132
	v_add_f32_e32 v135, 1.0, v145
	v_rcp_f32_e32 v135, v135
	v_mul_f32_e32 v142, 0xbfb8aa3b, v126
	v_exp_f32_e32 v142, v142
	s_ashr_i32 s18, s17, 31
	v_mul_f32_e32 v114, v114, v132
	v_mul_f32_e32 v135, v144, v135
	s_add_u32 s14, s14, s17
	v_mul_f32_e32 v114, v114, v135
	v_add_f32_e32 v135, 1.0, v142
	s_addc_u32 s15, s15, s18
	v_rcp_f32_e32 v135, v135
	s_lshl_b64 s[14:15], s[14:15], 1
	s_add_u32 s14, s35, s14
	s_addc_u32 s15, s36, s15
	v_lshlrev_b32_e32 v118, 1, v118
	v_cvt_pk_bf16_f32 v114, v114, v114
	ds_read2_b32 v[136:137], v130 offset0:2 offset1:3
	ds_read2_b32 v[138:139], v130 offset0:16 offset1:17
	ds_read2_b32 v[140:141], v130 offset0:18 offset1:19
	global_store_short v118, v114, s[14:15]
	v_mul_f32_e32 v114, v122, v132
	v_mul_f32_e32 v122, v126, v135
	v_mul_f32_e32 v119, v119, v133
	v_mul_f32_e32 v114, v114, v122
	v_mul_f32_e32 v122, 0xbfb8aa3b, v119
	v_exp_f32_e32 v122, v122
	v_mul_f32_e32 v126, v127, v133
	v_mul_f32_e32 v127, 0xbfb8aa3b, v126
	v_exp_f32_e32 v127, v127
	v_add_f32_e32 v122, 1.0, v122
	v_rcp_f32_e32 v122, v122
	v_mul_f32_e32 v115, v115, v133
	v_cvt_pk_bf16_f32 v114, v114, v114
	global_store_short v118, v114, s[14:15] offset:128
	v_mul_f32_e32 v119, v119, v122
	v_mul_f32_e32 v115, v115, v119
	v_add_f32_e32 v119, 1.0, v127
	v_rcp_f32_e32 v119, v119
	v_add_u32_e32 v114, 0x1680, v118
	v_cvt_pk_bf16_f32 v115, v115, v115
	global_store_short v114, v115, s[14:15]
	v_mul_f32_e32 v114, v123, v133
	v_mul_f32_e32 v115, v126, v119
	v_mul_f32_e32 v114, v114, v115
	s_waitcnt lgkmcnt(0)
	v_mul_f32_e32 v115, v120, v136
	v_mul_f32_e32 v119, 0xbfb8aa3b, v115
	v_exp_f32_e32 v119, v119
	v_add_u32_e32 v120, 0x1700, v118
	v_cvt_pk_bf16_f32 v114, v114, v114
	global_store_short v120, v114, s[14:15]
	v_add_f32_e32 v119, 1.0, v119
	v_mul_f32_e32 v120, v128, v136
	v_rcp_f32_e32 v119, v119
	v_mul_f32_e32 v122, 0xbfb8aa3b, v120
	v_exp_f32_e32 v122, v122
	v_mul_f32_e32 v116, v116, v136
	v_mul_f32_e32 v115, v115, v119
	v_mul_f32_e32 v115, v116, v115
	v_add_f32_e32 v116, 1.0, v122
	v_rcp_f32_e32 v116, v116
	v_add_u32_e32 v114, 0x2d00, v118
	v_cvt_pk_bf16_f32 v115, v115, v115
	global_store_short v114, v115, s[14:15]
	v_mul_f32_e32 v114, v124, v136
	v_mul_f32_e32 v115, v120, v116
	v_mul_f32_e32 v114, v114, v115
	v_mul_f32_e32 v115, v121, v137
	v_mul_f32_e32 v116, 0xbfb8aa3b, v115
	v_exp_f32_e32 v116, v116
	v_add_u32_e32 v119, 0x2d80, v118
	v_cvt_pk_bf16_f32 v114, v114, v114
	global_store_short v119, v114, s[14:15]
	v_mul_f32_e32 v119, v129, v137
	v_add_f32_e32 v116, 1.0, v116
	v_mul_f32_e32 v120, 0xbfb8aa3b, v119
	v_rcp_f32_e32 v116, v116
	v_exp_f32_e32 v120, v120
	v_mul_f32_e32 v117, v117, v137
	v_add_u32_e32 v114, 0x4380, v118
	v_mul_f32_e32 v115, v115, v116
	v_add_f32_e32 v116, 1.0, v120
	v_rcp_f32_e32 v116, v116
	v_mul_f32_e32 v115, v117, v115
	v_cvt_pk_bf16_f32 v115, v115, v115
	global_store_short v114, v115, s[14:15]
	v_mul_f32_e32 v114, v125, v137
	v_mul_f32_e32 v115, v119, v116
	v_mul_f32_e32 v102, v102, v138
	v_mul_f32_e32 v114, v114, v115
	v_mul_f32_e32 v115, 0xbfb8aa3b, v102
	v_exp_f32_e32 v115, v115
	v_add_u32_e32 v116, 0x4400, v118
	v_mul_f32_e32 v110, v110, v138
	v_cvt_pk_bf16_f32 v114, v114, v114
	v_add_f32_e32 v115, 1.0, v115
	global_store_short v116, v114, s[14:15]
	v_rcp_f32_e32 v115, v115
	v_mul_f32_e32 v116, 0xbfb8aa3b, v110
	v_exp_f32_e32 v116, v116
	v_mul_f32_e32 v98, v98, v138
	v_mul_f32_e32 v102, v102, v115
	v_mul_f32_e32 v98, v98, v102
	v_add_f32_e32 v102, 1.0, v116
	v_rcp_f32_e32 v102, v102
	v_add_u32_e32 v114, 0x16800, v118
	v_cvt_pk_bf16_f32 v98, v98, v98
	global_store_short v114, v98, s[14:15]
	v_mul_f32_e32 v98, v106, v138
	v_mul_f32_e32 v102, v110, v102
	v_mul_f32_e32 v98, v98, v102
	v_mul_f32_e32 v102, v103, v139
	v_mul_f32_e32 v103, 0xbfb8aa3b, v102
	v_exp_f32_e32 v103, v103
	v_add_u32_e32 v106, 0x16880, v118
	v_cvt_pk_bf16_f32 v98, v98, v98
	global_store_short v106, v98, s[14:15]
	v_add_f32_e32 v103, 1.0, v103
	v_mul_f32_e32 v106, v111, v139
	v_rcp_f32_e32 v103, v103
	v_mul_f32_e32 v110, 0xbfb8aa3b, v106
	v_exp_f32_e32 v110, v110
	v_mul_f32_e32 v99, v99, v139
	v_mul_f32_e32 v102, v102, v103
	v_mul_f32_e32 v99, v99, v102
	v_add_f32_e32 v102, 1.0, v110
	v_rcp_f32_e32 v102, v102
	v_add_u32_e32 v98, 0x17e80, v118
	v_cvt_pk_bf16_f32 v99, v99, v99
	global_store_short v98, v99, s[14:15]
	v_mul_f32_e32 v98, v107, v139
	v_mul_f32_e32 v99, v106, v102
	v_mul_f32_e32 v98, v98, v99
	v_mul_f32_e32 v99, v104, v140
	v_mul_f32_e32 v102, 0xbfb8aa3b, v99
	v_exp_f32_e32 v102, v102
	v_add_u32_e32 v103, 0x17f00, v118
	v_cvt_pk_bf16_f32 v98, v98, v98
	global_store_short v103, v98, s[14:15]
	v_add_f32_e32 v102, 1.0, v102
	v_mul_f32_e32 v103, v112, v140
	v_rcp_f32_e32 v102, v102
	v_mul_f32_e32 v104, 0xbfb8aa3b, v103
	v_exp_f32_e32 v104, v104
	v_mul_f32_e32 v100, v100, v140
	v_mul_f32_e32 v99, v99, v102
	v_mul_f32_e32 v99, v100, v99
	v_add_f32_e32 v100, 1.0, v104
	v_rcp_f32_e32 v100, v100
	v_add_u32_e32 v98, 0x19500, v118
	v_cvt_pk_bf16_f32 v99, v99, v99
	global_store_short v98, v99, s[14:15]
	v_mul_f32_e32 v98, v108, v140
	v_mul_f32_e32 v99, v103, v100
	v_mul_f32_e32 v98, v98, v99
	v_mul_f32_e32 v99, v105, v141
	v_mul_f32_e32 v100, 0xbfb8aa3b, v99
	v_exp_f32_e32 v100, v100
	v_add_u32_e32 v102, 0x19580, v118
	v_cvt_pk_bf16_f32 v98, v98, v98
	global_store_short v102, v98, s[14:15]
	v_mul_f32_e32 v102, v113, v141
	v_add_f32_e32 v100, 1.0, v100
	v_mul_f32_e32 v103, 0xbfb8aa3b, v102
	v_rcp_f32_e32 v100, v100
	v_exp_f32_e32 v103, v103
	v_mul_f32_e32 v101, v101, v141
	v_add_u32_e32 v98, 0x1ab80, v118
	v_mul_f32_e32 v99, v99, v100
	v_add_f32_e32 v100, 1.0, v103
	v_rcp_f32_e32 v100, v100
	v_mul_f32_e32 v99, v101, v99
	v_cvt_pk_bf16_f32 v99, v99, v99
	global_store_short v98, v99, s[14:15]
	v_mul_f32_e32 v98, v109, v141
	v_mul_f32_e32 v99, v102, v100
	v_mul_f32_e32 v100, v98, v99
	ds_read2_b32 v[98:99], v130 offset0:32 offset1:33
	v_add_u32_e32 v108, 0x1ac00, v118
	v_cvt_pk_bf16_f32 v106, v100, v100
	ds_read2_b32 v[100:101], v130 offset0:34 offset1:35
	ds_read2_b32 v[102:103], v130 offset0:48 offset1:49
	ds_read2_b32 v[104:105], v130 offset0:50 offset1:51
	global_store_short v108, v106, s[14:15]
	s_waitcnt lgkmcnt(0)
; #define GAS __attribute__((address_space(1)))
; __device__ __forceinline__ unsigned f2bf(float f) { return pk2(f, f) & 0xffffu; }
; __device__ __forceinline__ float sigmoidf_(float v) { return __builtin_amdgcn_rcpf(1.f + __builtin_amdgcn_exp2f(-LOG2E * v)); }
; __device__ __forceinline__ void phase_up(int pass) {
;     ...
; #pragma unroll
;     for (int ai = 0; ai < 2; ++ai)
; #pragma unroll
;       for (int m = 0; m < 4; ++m)
; #pragma unroll
;         for (int j = 0; j < 4; ++j) {
;           const int rowl = ai * 128 + wr * 64 + m * 16 + fq * 4 + j;
;           const float r = rr[rowl];
; #pragma unroll
;           for (int bj = 0; bj < 2; ++bj) {
;             const float g = acc[ai][bj][m][0][j] * r, u = acc[ai][bj][m][1][j] * r;
;             const float v = g * sigmoidf_(g) * u;
;             *(GAS unsigned short*)(tb + (off0 + (unsigned)(((ai * 128 + m * 16 + j) * FFP + bj * 64) * 2))) = (unsigned short)f2bf(v);
;           }
;         }
	v_mul_f32_e32 v86, v86, v98
	v_mul_f32_e32 v107, 0xbfb8aa3b, v86
	v_exp_f32_e32 v107, v107
	v_mul_f32_e32 v94, v94, v98
	v_mul_f32_e32 v108, 0xbfb8aa3b, v94
	v_exp_f32_e32 v108, v108
	v_add_f32_e32 v107, 1.0, v107
	v_rcp_f32_e32 v107, v107
	v_mul_f32_e32 v82, v82, v98
	v_add_u32_e32 v106, 0x2d000, v118
	v_mul_f32_e32 v83, v83, v99
	v_mul_f32_e32 v86, v86, v107
	v_mul_f32_e32 v82, v82, v86
	v_add_f32_e32 v86, 1.0, v108
	v_rcp_f32_e32 v86, v86
	v_cvt_pk_bf16_f32 v82, v82, v82
	global_store_short v106, v82, s[14:15]
	v_mul_f32_e32 v82, v90, v98
	v_mul_f32_e32 v86, v94, v86
	v_mul_f32_e32 v82, v82, v86
	v_mul_f32_e32 v86, v87, v99
	v_mul_f32_e32 v87, 0xbfb8aa3b, v86
	v_exp_f32_e32 v87, v87
	v_add_u32_e32 v90, 0x2d080, v118
	v_cvt_pk_bf16_f32 v82, v82, v82
	global_store_short v90, v82, s[14:15]
	v_add_f32_e32 v87, 1.0, v87
	v_mul_f32_e32 v90, v95, v99
	v_rcp_f32_e32 v87, v87
	v_mul_f32_e32 v94, 0xbfb8aa3b, v90
	v_exp_f32_e32 v94, v94
	v_add_u32_e32 v82, 0x2e680, v118
	v_mul_f32_e32 v86, v86, v87
	v_mul_f32_e32 v83, v83, v86
	v_add_f32_e32 v86, 1.0, v94
	v_rcp_f32_e32 v86, v86
	v_cvt_pk_bf16_f32 v83, v83, v83
	global_store_short v82, v83, s[14:15]
	v_mul_f32_e32 v82, v91, v99
	v_mul_f32_e32 v83, v90, v86
	v_mul_f32_e32 v82, v82, v83
	v_mul_f32_e32 v83, v88, v100
	v_mul_f32_e32 v86, 0xbfb8aa3b, v83
	v_exp_f32_e32 v86, v86
	v_add_u32_e32 v87, 0x2e700, v118
	v_cvt_pk_bf16_f32 v82, v82, v82
	global_store_short v87, v82, s[14:15]
	v_add_f32_e32 v86, 1.0, v86
	v_mul_f32_e32 v87, v96, v100
	v_rcp_f32_e32 v86, v86
	v_mul_f32_e32 v88, 0xbfb8aa3b, v87
	v_exp_f32_e32 v88, v88
	v_mul_f32_e32 v84, v84, v100
	v_mul_f32_e32 v83, v83, v86
	v_mul_f32_e32 v83, v84, v83
	v_add_f32_e32 v84, 1.0, v88
	v_rcp_f32_e32 v84, v84
	v_add_u32_e32 v82, 0x2fd00, v118
	v_cvt_pk_bf16_f32 v83, v83, v83
	global_store_short v82, v83, s[14:15]
	v_mul_f32_e32 v82, v92, v100
	v_mul_f32_e32 v83, v87, v84
	v_mul_f32_e32 v82, v82, v83
	v_mul_f32_e32 v83, v89, v101
	v_mul_f32_e32 v84, 0xbfb8aa3b, v83
	v_exp_f32_e32 v84, v84
	v_add_u32_e32 v86, 0x2fd80, v118
	v_cvt_pk_bf16_f32 v82, v82, v82
	global_store_short v86, v82, s[14:15]
	v_mul_f32_e32 v86, v97, v101
	v_add_f32_e32 v84, 1.0, v84
	v_mul_f32_e32 v87, 0xbfb8aa3b, v86
	v_rcp_f32_e32 v84, v84
	v_exp_f32_e32 v87, v87
	v_mul_f32_e32 v85, v85, v101
	v_add_u32_e32 v82, 0x31380, v118
	v_mul_f32_e32 v83, v83, v84
	v_add_f32_e32 v84, 1.0, v87
	v_rcp_f32_e32 v84, v84
	v_mul_f32_e32 v83, v85, v83
	v_cvt_pk_bf16_f32 v83, v83, v83
	global_store_short v82, v83, s[14:15]
	v_mul_f32_e32 v82, v93, v101
	v_mul_f32_e32 v83, v86, v84
	v_mul_f32_e32 v70, v70, v102
	v_mul_f32_e32 v82, v82, v83
	v_mul_f32_e32 v83, 0xbfb8aa3b, v70
	v_exp_f32_e32 v83, v83
	v_add_u32_e32 v84, 0x31400, v118
	v_mul_f32_e32 v78, v78, v102
	v_cvt_pk_bf16_f32 v82, v82, v82
	v_add_f32_e32 v83, 1.0, v83
	global_store_short v84, v82, s[14:15]
	v_rcp_f32_e32 v83, v83
	v_mul_f32_e32 v84, 0xbfb8aa3b, v78
	v_exp_f32_e32 v84, v84
	v_mul_f32_e32 v66, v66, v102
	v_mul_f32_e32 v70, v70, v83
	v_mul_f32_e32 v66, v66, v70
	v_add_f32_e32 v70, 1.0, v84
	v_rcp_f32_e32 v70, v70
	v_add_u32_e32 v82, 0x43800, v118
	v_cvt_pk_bf16_f32 v66, v66, v66
	global_store_short v82, v66, s[14:15]
	v_mul_f32_e32 v66, v74, v102
	v_mul_f32_e32 v70, v78, v70
	v_mul_f32_e32 v66, v66, v70
	v_mul_f32_e32 v70, v71, v103
	v_mul_f32_e32 v71, 0xbfb8aa3b, v70
	v_exp_f32_e32 v71, v71
	v_add_u32_e32 v74, 0x43880, v118
	v_cvt_pk_bf16_f32 v66, v66, v66
	global_store_short v74, v66, s[14:15]
	v_add_f32_e32 v71, 1.0, v71
	v_mul_f32_e32 v74, v79, v103
	v_rcp_f32_e32 v71, v71
	v_mul_f32_e32 v78, 0xbfb8aa3b, v74
	v_exp_f32_e32 v78, v78
	v_mul_f32_e32 v67, v67, v103
	v_mul_f32_e32 v70, v70, v71
	v_mul_f32_e32 v67, v67, v70
	v_add_f32_e32 v70, 1.0, v78
	v_rcp_f32_e32 v70, v70
	v_add_u32_e32 v66, 0x44e80, v118
	v_cvt_pk_bf16_f32 v67, v67, v67
	global_store_short v66, v67, s[14:15]
	v_mul_f32_e32 v66, v75, v103
	v_mul_f32_e32 v67, v74, v70
	v_mul_f32_e32 v66, v66, v67
	v_mul_f32_e32 v67, v72, v104
	v_mul_f32_e32 v70, 0xbfb8aa3b, v67
	v_exp_f32_e32 v70, v70
	v_add_u32_e32 v71, 0x44f00, v118
	v_cvt_pk_bf16_f32 v66, v66, v66
	global_store_short v71, v66, s[14:15]
	v_add_f32_e32 v70, 1.0, v70
	v_mul_f32_e32 v71, v80, v104
	v_rcp_f32_e32 v70, v70
	v_mul_f32_e32 v72, 0xbfb8aa3b, v71
	v_exp_f32_e32 v72, v72
	v_mul_f32_e32 v68, v68, v104
	v_mul_f32_e32 v67, v67, v70
	v_mul_f32_e32 v67, v68, v67
	v_add_f32_e32 v68, 1.0, v72
	v_rcp_f32_e32 v68, v68
	v_add_u32_e32 v66, 0x46500, v118
	v_cvt_pk_bf16_f32 v67, v67, v67
	global_store_short v66, v67, s[14:15]
	v_mul_f32_e32 v66, v76, v104
	v_mul_f32_e32 v67, v71, v68
	v_mul_f32_e32 v66, v66, v67
	v_mul_f32_e32 v67, v73, v105
	v_mul_f32_e32 v68, 0xbfb8aa3b, v67
	v_exp_f32_e32 v68, v68
	v_add_u32_e32 v70, 0x46580, v118
	v_cvt_pk_bf16_f32 v66, v66, v66
	global_store_short v70, v66, s[14:15]
	v_mul_f32_e32 v70, v81, v105
	v_add_f32_e32 v68, 1.0, v68
	v_mul_f32_e32 v71, 0xbfb8aa3b, v70
	v_rcp_f32_e32 v68, v68
	v_exp_f32_e32 v71, v71
	v_mul_f32_e32 v69, v69, v105
	v_add_u32_e32 v66, 0x47b80, v118
	v_mul_f32_e32 v67, v67, v68
	v_add_f32_e32 v68, 1.0, v71
	v_rcp_f32_e32 v68, v68
	v_mul_f32_e32 v67, v69, v67
	v_cvt_pk_bf16_f32 v67, v67, v67
	global_store_short v66, v67, s[14:15]
	v_mul_f32_e32 v66, v77, v105
	v_mul_f32_e32 v67, v70, v68
	v_mul_f32_e32 v68, v66, v67
	ds_read2_b32 v[66:67], v130 offset0:128 offset1:129
	v_add_u32_e32 v76, 0x47c00, v118
	v_cvt_pk_bf16_f32 v74, v68, v68
	ds_read2_b32 v[68:69], v130 offset0:130 offset1:131
	ds_read2_b32 v[70:71], v130 offset0:144 offset1:145
	ds_read2_b32 v[72:73], v130 offset0:146 offset1:147
	global_store_short v76, v74, s[14:15]
	s_waitcnt lgkmcnt(0)
; #define GAS __attribute__((address_space(1)))
; __device__ __forceinline__ unsigned f2bf(float f) { return pk2(f, f) & 0xffffu; }
; __device__ __forceinline__ float sigmoidf_(float v) { return __builtin_amdgcn_rcpf(1.f + __builtin_amdgcn_exp2f(-LOG2E * v)); }
; __device__ __forceinline__ void phase_up(int pass) {
;     ...
; #pragma unroll
;     for (int ai = 0; ai < 2; ++ai)
; #pragma unroll
;       for (int m = 0; m < 4; ++m)
; #pragma unroll
;         for (int j = 0; j < 4; ++j) {
;           const int rowl = ai * 128 + wr * 64 + m * 16 + fq * 4 + j;
;           const float r = rr[rowl];
; #pragma unroll
;           for (int bj = 0; bj < 2; ++bj) {
;             const float g = acc[ai][bj][m][0][j] * r, u = acc[ai][bj][m][1][j] * r;
;             const float v = g * sigmoidf_(g) * u;
;             *(GAS unsigned short*)(tb + (off0 + (unsigned)(((ai * 128 + m * 16 + j) * FFP + bj * 64) * 2))) = (unsigned short)f2bf(v);
;           }
;         }
	v_mul_f32_e32 v54, v54, v66
	v_mul_f32_e32 v75, 0xbfb8aa3b, v54
	v_exp_f32_e32 v75, v75
	v_mul_f32_e32 v62, v62, v66
	v_mul_f32_e32 v76, 0xbfb8aa3b, v62
	v_exp_f32_e32 v76, v76
	v_add_f32_e32 v75, 1.0, v75
	v_rcp_f32_e32 v75, v75
	v_mul_f32_e32 v50, v50, v66
	v_add_u32_e32 v74, 0xb4000, v118
	v_mul_f32_e32 v51, v51, v67
	v_mul_f32_e32 v54, v54, v75
	v_mul_f32_e32 v50, v50, v54
	v_add_f32_e32 v54, 1.0, v76
	v_rcp_f32_e32 v54, v54
	v_cvt_pk_bf16_f32 v50, v50, v50
	global_store_short v74, v50, s[14:15]
	v_mul_f32_e32 v50, v58, v66
	v_mul_f32_e32 v54, v62, v54
	v_mul_f32_e32 v50, v50, v54
	v_mul_f32_e32 v54, v55, v67
	v_mul_f32_e32 v55, 0xbfb8aa3b, v54
	v_exp_f32_e32 v55, v55
	v_add_u32_e32 v58, 0xb4080, v118
	v_cvt_pk_bf16_f32 v50, v50, v50
	global_store_short v58, v50, s[14:15]
	v_add_f32_e32 v55, 1.0, v55
	v_mul_f32_e32 v58, v63, v67
	v_rcp_f32_e32 v55, v55
	v_mul_f32_e32 v62, 0xbfb8aa3b, v58
	v_exp_f32_e32 v62, v62
	v_add_u32_e32 v50, 0xb5680, v118
	v_mul_f32_e32 v54, v54, v55
	v_mul_f32_e32 v51, v51, v54
	v_add_f32_e32 v54, 1.0, v62
	v_rcp_f32_e32 v54, v54
	v_cvt_pk_bf16_f32 v51, v51, v51
	global_store_short v50, v51, s[14:15]
	v_mul_f32_e32 v50, v59, v67
	v_mul_f32_e32 v51, v58, v54
	v_mul_f32_e32 v50, v50, v51
	v_mul_f32_e32 v51, v56, v68
	v_mul_f32_e32 v54, 0xbfb8aa3b, v51
	v_exp_f32_e32 v54, v54
	v_add_u32_e32 v55, 0xb5700, v118
	v_cvt_pk_bf16_f32 v50, v50, v50
	global_store_short v55, v50, s[14:15]
	v_add_f32_e32 v54, 1.0, v54
	v_mul_f32_e32 v55, v64, v68
	v_rcp_f32_e32 v54, v54
	v_mul_f32_e32 v56, 0xbfb8aa3b, v55
	v_exp_f32_e32 v56, v56
	v_mul_f32_e32 v52, v52, v68
	v_mul_f32_e32 v51, v51, v54
	v_mul_f32_e32 v51, v52, v51
	v_add_f32_e32 v52, 1.0, v56
	v_rcp_f32_e32 v52, v52
	v_add_u32_e32 v50, 0xb6d00, v118
	v_cvt_pk_bf16_f32 v51, v51, v51
	global_store_short v50, v51, s[14:15]
	v_mul_f32_e32 v50, v60, v68
	v_mul_f32_e32 v51, v55, v52
	v_mul_f32_e32 v50, v50, v51
	v_mul_f32_e32 v51, v57, v69
	v_mul_f32_e32 v52, 0xbfb8aa3b, v51
	v_exp_f32_e32 v52, v52
	v_add_u32_e32 v54, 0xb6d80, v118
	v_cvt_pk_bf16_f32 v50, v50, v50
	global_store_short v54, v50, s[14:15]
	v_mul_f32_e32 v54, v65, v69
	v_add_f32_e32 v52, 1.0, v52
	v_mul_f32_e32 v55, 0xbfb8aa3b, v54
	v_rcp_f32_e32 v52, v52
	v_exp_f32_e32 v55, v55
	v_mul_f32_e32 v53, v53, v69
	v_add_u32_e32 v50, 0xb8380, v118
	v_mul_f32_e32 v51, v51, v52
	v_add_f32_e32 v52, 1.0, v55
	v_rcp_f32_e32 v52, v52
	v_mul_f32_e32 v51, v53, v51
	v_cvt_pk_bf16_f32 v51, v51, v51
	global_store_short v50, v51, s[14:15]
	v_mul_f32_e32 v50, v61, v69
	v_mul_f32_e32 v51, v54, v52
	v_mul_f32_e32 v42, v42, v70
	v_mul_f32_e32 v50, v50, v51
	v_mul_f32_e32 v51, 0xbfb8aa3b, v42
	v_exp_f32_e32 v51, v51
	v_add_u32_e32 v52, 0xb8400, v118
	v_mul_f32_e32 v46, v46, v70
	v_cvt_pk_bf16_f32 v50, v50, v50
	v_add_f32_e32 v51, 1.0, v51
	global_store_short v52, v50, s[14:15]
	v_rcp_f32_e32 v51, v51
	v_mul_f32_e32 v52, 0xbfb8aa3b, v46
	v_exp_f32_e32 v52, v52
	v_mul_f32_e32 v34, v34, v70
	v_mul_f32_e32 v42, v42, v51
	v_mul_f32_e32 v34, v34, v42
	v_add_f32_e32 v42, 1.0, v52
	v_rcp_f32_e32 v42, v42
	v_add_u32_e32 v50, 0xca800, v118
	v_cvt_pk_bf16_f32 v34, v34, v34
	global_store_short v50, v34, s[14:15]
	v_mul_f32_e32 v34, v38, v70
	v_mul_f32_e32 v38, v46, v42
	v_mul_f32_e32 v34, v34, v38
	v_mul_f32_e32 v38, v43, v71
	v_mul_f32_e32 v42, 0xbfb8aa3b, v38
	v_exp_f32_e32 v42, v42
	v_add_u32_e32 v43, 0xca880, v118
	v_cvt_pk_bf16_f32 v34, v34, v34
	global_store_short v43, v34, s[14:15]
	v_add_f32_e32 v42, 1.0, v42
	v_mul_f32_e32 v43, v47, v71
	v_rcp_f32_e32 v42, v42
	v_mul_f32_e32 v46, 0xbfb8aa3b, v43
	v_exp_f32_e32 v46, v46
	v_mul_f32_e32 v35, v35, v71
	v_mul_f32_e32 v38, v38, v42
	v_mul_f32_e32 v35, v35, v38
	v_add_f32_e32 v38, 1.0, v46
	v_rcp_f32_e32 v38, v38
	v_add_u32_e32 v34, 0xcbe80, v118
	v_cvt_pk_bf16_f32 v35, v35, v35
	global_store_short v34, v35, s[14:15]
	v_mul_f32_e32 v34, v39, v71
	v_mul_f32_e32 v35, v43, v38
	v_mul_f32_e32 v34, v34, v35
	v_mul_f32_e32 v35, v44, v72
	v_mul_f32_e32 v38, 0xbfb8aa3b, v35
	v_exp_f32_e32 v38, v38
	v_add_u32_e32 v39, 0xcbf00, v118
	v_cvt_pk_bf16_f32 v34, v34, v34
	global_store_short v39, v34, s[14:15]
	v_add_f32_e32 v38, 1.0, v38
	v_mul_f32_e32 v39, v48, v72
	v_rcp_f32_e32 v38, v38
	v_mul_f32_e32 v42, 0xbfb8aa3b, v39
	v_exp_f32_e32 v42, v42
	v_mul_f32_e32 v36, v36, v72
	v_mul_f32_e32 v35, v35, v38
	v_mul_f32_e32 v35, v36, v35
	v_add_f32_e32 v36, 1.0, v42
	v_rcp_f32_e32 v36, v36
	v_add_u32_e32 v34, 0xcd500, v118
	v_cvt_pk_bf16_f32 v35, v35, v35
	global_store_short v34, v35, s[14:15]
	v_mul_f32_e32 v34, v40, v72
	v_mul_f32_e32 v35, v39, v36
	v_mul_f32_e32 v34, v34, v35
	v_mul_f32_e32 v35, v45, v73
	v_mul_f32_e32 v36, 0xbfb8aa3b, v35
	v_exp_f32_e32 v36, v36
	v_add_u32_e32 v38, 0xcd580, v118
	v_cvt_pk_bf16_f32 v34, v34, v34
	global_store_short v38, v34, s[14:15]
	v_mul_f32_e32 v38, v49, v73
	v_add_f32_e32 v36, 1.0, v36
	v_mul_f32_e32 v39, 0xbfb8aa3b, v38
	v_rcp_f32_e32 v36, v36
	v_exp_f32_e32 v39, v39
	v_mul_f32_e32 v37, v37, v73
	v_add_u32_e32 v34, 0xceb80, v118
	v_mul_f32_e32 v35, v35, v36
	v_add_f32_e32 v36, 1.0, v39
	v_rcp_f32_e32 v36, v36
	v_mul_f32_e32 v35, v37, v35
	v_cvt_pk_bf16_f32 v35, v35, v35
	global_store_short v34, v35, s[14:15]
	v_mul_f32_e32 v34, v41, v73
	v_mul_f32_e32 v35, v38, v36
	v_mul_f32_e32 v36, v34, v35
	ds_read2_b32 v[34:35], v130 offset0:160 offset1:161
	v_add_u32_e32 v44, 0xcec00, v118
	v_cvt_pk_bf16_f32 v42, v36, v36
	ds_read2_b32 v[36:37], v130 offset0:162 offset1:163
	ds_read2_b32 v[38:39], v130 offset0:176 offset1:177
	ds_read2_b32 v[40:41], v130 offset0:178 offset1:179
	global_store_short v44, v42, s[14:15]
	s_waitcnt lgkmcnt(0)
; #define GAS __attribute__((address_space(1)))
; __device__ __forceinline__ unsigned f2bf(float f) { return pk2(f, f) & 0xffffu; }
; __device__ __forceinline__ float sigmoidf_(float v) { return __builtin_amdgcn_rcpf(1.f + __builtin_amdgcn_exp2f(-LOG2E * v)); }
; __device__ __forceinline__ void phase_up(int pass) {
;     ...
; #pragma unroll
;     for (int ai = 0; ai < 2; ++ai)
; #pragma unroll
;       for (int m = 0; m < 4; ++m)
; #pragma unroll
;         for (int j = 0; j < 4; ++j) {
;           const int rowl = ai * 128 + wr * 64 + m * 16 + fq * 4 + j;
;           const float r = rr[rowl];
; #pragma unroll
;           for (int bj = 0; bj < 2; ++bj) {
;             const float g = acc[ai][bj][m][0][j] * r, u = acc[ai][bj][m][1][j] * r;
;             const float v = g * sigmoidf_(g) * u;
;             *(GAS unsigned short*)(tb + (off0 + (unsigned)(((ai * 128 + m * 16 + j) * FFP + bj * 64) * 2))) = (unsigned short)f2bf(v);
;           }
;         }
;     par ^= 1;
	v_mul_f32_e32 v22, v22, v34
	v_mul_f32_e32 v43, 0xbfb8aa3b, v22
	v_exp_f32_e32 v43, v43
	v_mul_f32_e32 v30, v30, v34
	v_mul_f32_e32 v44, 0xbfb8aa3b, v30
	v_exp_f32_e32 v44, v44
	v_add_f32_e32 v43, 1.0, v43
	v_rcp_f32_e32 v43, v43
	v_mul_f32_e32 v18, v18, v34
	v_add_u32_e32 v42, 0xe1000, v118
	v_mul_f32_e32 v19, v19, v35
	v_mul_f32_e32 v22, v22, v43
	v_mul_f32_e32 v18, v18, v22
	v_add_f32_e32 v22, 1.0, v44
	v_rcp_f32_e32 v22, v22
	v_cvt_pk_bf16_f32 v18, v18, v18
	global_store_short v42, v18, s[14:15]
	v_mul_f32_e32 v18, v26, v34
	v_mul_f32_e32 v22, v30, v22
	v_mul_f32_e32 v18, v18, v22
	v_mul_f32_e32 v22, v23, v35
	v_mul_f32_e32 v23, 0xbfb8aa3b, v22
	v_exp_f32_e32 v23, v23
	v_add_u32_e32 v26, 0xe1080, v118
	v_cvt_pk_bf16_f32 v18, v18, v18
	global_store_short v26, v18, s[14:15]
	v_add_f32_e32 v23, 1.0, v23
	v_mul_f32_e32 v26, v31, v35
	v_rcp_f32_e32 v23, v23
	v_mul_f32_e32 v30, 0xbfb8aa3b, v26
	v_exp_f32_e32 v30, v30
	v_add_u32_e32 v18, 0xe2680, v118
	v_mul_f32_e32 v22, v22, v23
	v_mul_f32_e32 v19, v19, v22
	v_add_f32_e32 v22, 1.0, v30
	v_rcp_f32_e32 v22, v22
	v_cvt_pk_bf16_f32 v19, v19, v19
	global_store_short v18, v19, s[14:15]
	v_mul_f32_e32 v18, v27, v35
	v_mul_f32_e32 v19, v26, v22
	v_mul_f32_e32 v18, v18, v19
	v_mul_f32_e32 v19, v24, v36
	v_mul_f32_e32 v22, 0xbfb8aa3b, v19
	v_exp_f32_e32 v22, v22
	v_add_u32_e32 v23, 0xe2700, v118
	v_cvt_pk_bf16_f32 v18, v18, v18
	global_store_short v23, v18, s[14:15]
	v_add_f32_e32 v22, 1.0, v22
	v_mul_f32_e32 v23, v32, v36
	v_rcp_f32_e32 v22, v22
	v_mul_f32_e32 v24, 0xbfb8aa3b, v23
	v_exp_f32_e32 v24, v24
	v_mul_f32_e32 v20, v20, v36
	v_mul_f32_e32 v19, v19, v22
	v_mul_f32_e32 v19, v20, v19
	v_add_f32_e32 v20, 1.0, v24
	v_rcp_f32_e32 v20, v20
	v_add_u32_e32 v18, 0xe3d00, v118
	v_cvt_pk_bf16_f32 v19, v19, v19
	global_store_short v18, v19, s[14:15]
	v_mul_f32_e32 v18, v28, v36
	v_mul_f32_e32 v19, v23, v20
	v_mul_f32_e32 v18, v18, v19
	v_mul_f32_e32 v19, v25, v37
	v_mul_f32_e32 v20, 0xbfb8aa3b, v19
	v_exp_f32_e32 v20, v20
	v_add_u32_e32 v22, 0xe3d80, v118
	v_cvt_pk_bf16_f32 v18, v18, v18
	global_store_short v22, v18, s[14:15]
	v_mul_f32_e32 v22, v33, v37
	v_add_f32_e32 v20, 1.0, v20
	v_mul_f32_e32 v23, 0xbfb8aa3b, v22
	v_rcp_f32_e32 v20, v20
	v_exp_f32_e32 v23, v23
	v_mul_f32_e32 v21, v21, v37
	v_add_u32_e32 v18, 0xe5380, v118
	v_mul_f32_e32 v19, v19, v20
	v_add_f32_e32 v20, 1.0, v23
	v_rcp_f32_e32 v20, v20
	v_mul_f32_e32 v19, v21, v19
	v_cvt_pk_bf16_f32 v19, v19, v19
	global_store_short v18, v19, s[14:15]
	v_mul_f32_e32 v18, v29, v37
	v_mul_f32_e32 v19, v22, v20
	v_mul_f32_e32 v10, v10, v38
	v_mul_f32_e32 v18, v18, v19
	v_mul_f32_e32 v19, 0xbfb8aa3b, v10
	v_exp_f32_e32 v19, v19
	v_add_u32_e32 v20, 0xe5400, v118
	v_mul_f32_e32 v14, v14, v38
	v_cvt_pk_bf16_f32 v18, v18, v18
	v_add_f32_e32 v19, 1.0, v19
	global_store_short v20, v18, s[14:15]
	v_rcp_f32_e32 v19, v19
	v_mul_f32_e32 v20, 0xbfb8aa3b, v14
	v_exp_f32_e32 v20, v20
	v_mul_f32_e32 v2, v2, v38
	v_mul_f32_e32 v10, v10, v19
	v_mul_f32_e32 v2, v2, v10
	v_add_f32_e32 v10, 1.0, v20
	v_rcp_f32_e32 v10, v10
	v_add_u32_e32 v18, 0xf7800, v118
	v_cvt_pk_bf16_f32 v2, v2, v2
	global_store_short v18, v2, s[14:15]
	v_mul_f32_e32 v2, v6, v38
	v_mul_f32_e32 v6, v14, v10
	v_mul_f32_e32 v2, v2, v6
	v_mul_f32_e32 v6, v11, v39
	v_mul_f32_e32 v10, 0xbfb8aa3b, v6
	v_exp_f32_e32 v10, v10
	v_add_u32_e32 v11, 0xf7880, v118
	v_cvt_pk_bf16_f32 v2, v2, v2
	global_store_short v11, v2, s[14:15]
	v_add_f32_e32 v10, 1.0, v10
	v_mul_f32_e32 v11, v15, v39
	v_rcp_f32_e32 v10, v10
	v_mul_f32_e32 v14, 0xbfb8aa3b, v11
	v_exp_f32_e32 v14, v14
	v_mul_f32_e32 v3, v3, v39
	v_mul_f32_e32 v6, v6, v10
	v_mul_f32_e32 v3, v3, v6
	v_add_f32_e32 v6, 1.0, v14
	v_rcp_f32_e32 v6, v6
	v_add_u32_e32 v2, 0xf8e80, v118
	v_cvt_pk_bf16_f32 v3, v3, v3
	global_store_short v2, v3, s[14:15]
	v_mul_f32_e32 v2, v7, v39
	v_mul_f32_e32 v3, v11, v6
	v_mul_f32_e32 v2, v2, v3
	v_mul_f32_e32 v3, v12, v40
	v_mul_f32_e32 v6, 0xbfb8aa3b, v3
	v_exp_f32_e32 v6, v6
	v_add_u32_e32 v7, 0xf8f00, v118
	v_cvt_pk_bf16_f32 v2, v2, v2
	global_store_short v7, v2, s[14:15]
	v_add_f32_e32 v6, 1.0, v6
	v_mul_f32_e32 v7, v16, v40
	v_rcp_f32_e32 v6, v6
	v_mul_f32_e32 v10, 0xbfb8aa3b, v7
	v_exp_f32_e32 v10, v10
	v_mul_f32_e32 v4, v4, v40
	v_mul_f32_e32 v3, v3, v6
	v_mul_f32_e32 v3, v4, v3
	v_add_f32_e32 v4, 1.0, v10
	v_rcp_f32_e32 v4, v4
	v_add_u32_e32 v2, 0xfa500, v118
	v_cvt_pk_bf16_f32 v3, v3, v3
	global_store_short v2, v3, s[14:15]
	v_mul_f32_e32 v2, v8, v40
	v_mul_f32_e32 v3, v7, v4
	v_mul_f32_e32 v2, v2, v3
	v_mul_f32_e32 v3, v13, v41
	v_mul_f32_e32 v4, 0xbfb8aa3b, v3
	v_exp_f32_e32 v4, v4
	v_add_u32_e32 v6, 0xfa580, v118
	v_cvt_pk_bf16_f32 v2, v2, v2
	global_store_short v6, v2, s[14:15]
	v_mul_f32_e32 v6, v17, v41
	v_add_f32_e32 v4, 1.0, v4
	v_mul_f32_e32 v7, 0xbfb8aa3b, v6
	v_rcp_f32_e32 v4, v4
	v_exp_f32_e32 v7, v7
	v_mul_f32_e32 v5, v5, v41
	v_add_u32_e32 v2, 0xfbb80, v118
	v_mul_f32_e32 v3, v3, v4
	v_add_f32_e32 v4, 1.0, v7
	v_rcp_f32_e32 v4, v4
	v_mul_f32_e32 v3, v5, v3
	v_cvt_pk_bf16_f32 v3, v3, v3
	global_store_short v2, v3, s[14:15]
	v_mul_f32_e32 v2, v9, v41
	v_mul_f32_e32 v3, v6, v4
	v_mul_f32_e32 v2, v2, v3
	v_add_u32_e32 v3, 0xfbc00, v118
	s_xor_b32 s37, s37, 1
	s_andn2_b64 vcc, exec, s[12:13]
	s_mov_b32 s41, s20
	v_cvt_pk_bf16_f32 v2, v2, v2
	global_store_short v3, v2, s[14:15]
	s_cbranch_vccz .LBB0_890

; #define LAS __attribute__((address_space(3)))
; #define GAS __attribute__((address_space(1)))
; __device__ __forceinline__ unsigned pk2(float lo, float hi) { unsigned r; asm("s_nop 1\n\tv_cvt_pk_bf16_f32 %0, %1, %2" : "=v"(r) : "v"(lo), "v"(hi)); return r; }
; __device__ __forceinline__ void tr_wave_job(const GAS float* src0, const GAS float* src1, int ld, int mode, GAS bf16* dst, int K, int ldd, int n0, int k0, int lane, int wid, const GAS float* gk) {
;     ...
; #pragma unroll
;   for (int q = 0; q < 8; ++q) {
;     u32x4 o = {pk2(v[8 * q + 0], v[8 * q + 1]), pk2(v[8 * q + 2], v[8 * q + 3]), pk2(v[8 * q + 4], v[8 * q + 5]), pk2(v[8 * q + 6], v[8 * q + 7])};
;     *(LAS u32x4*)(scr + (lane * 8 + (q ^ (lane & 7))) * 16) = o;
;   }
;   asm volatile("s_waitcnt lgkmcnt(0)" ::: "memory");
;   const int rq = lane & 7;
; #pragma unroll
;   for (int i = 0; i < 8; ++i) {
;     const int r = i * 8 + (lane >> 3);
;     const u32x4 o = *(const LAS u32x4*)(scr + (r * 8 + (rq ^ (r & 7))) * 16);
;     *(GAS u32x4*)(dst + (size_t)(n0 + r) * ldd + k0 + rq * 8) = o;
;   }
;   asm volatile("s_waitcnt lgkmcnt(0)" ::: "memory");
.LBB0_896:
	s_or_b64 exec, exec, s[60:61]
	s_waitcnt vmcnt(62)
	v_cvt_pk_bf16_f32 v14, v14, v15
	s_waitcnt vmcnt(60)
	v_cvt_pk_bf16_f32 v15, v16, v17
	s_waitcnt vmcnt(58)
	v_cvt_pk_bf16_f32 v16, v18, v19
	s_waitcnt vmcnt(56)
	v_cvt_pk_bf16_f32 v17, v20, v21
	v_add_u32_e32 v2, v81, v82
	ds_write_b128 v2, v[14:17]
	s_waitcnt vmcnt(54)
	v_cvt_pk_bf16_f32 v14, v22, v23
	s_waitcnt vmcnt(52)
	v_cvt_pk_bf16_f32 v15, v24, v25
	s_waitcnt vmcnt(50)
	v_cvt_pk_bf16_f32 v16, v26, v27
	s_waitcnt vmcnt(48)
	v_cvt_pk_bf16_f32 v17, v28, v29
	ds_write_b128 v92, v[14:17]
	s_waitcnt vmcnt(46)
	v_cvt_pk_bf16_f32 v14, v30, v31
	s_waitcnt vmcnt(44)
	v_cvt_pk_bf16_f32 v15, v32, v33
	s_waitcnt vmcnt(42)
	v_cvt_pk_bf16_f32 v16, v34, v35
	s_waitcnt vmcnt(40)
	v_cvt_pk_bf16_f32 v17, v36, v37
	ds_write_b128 v93, v[14:17]
	s_waitcnt vmcnt(38)
	v_cvt_pk_bf16_f32 v14, v38, v39
	s_waitcnt vmcnt(36)
	v_cvt_pk_bf16_f32 v15, v40, v41
	s_waitcnt vmcnt(34)
	v_cvt_pk_bf16_f32 v16, v42, v43
	s_waitcnt vmcnt(32)
	v_cvt_pk_bf16_f32 v17, v44, v45
	ds_write_b128 v94, v[14:17]
	s_waitcnt vmcnt(30)
	v_cvt_pk_bf16_f32 v14, v46, v47
	s_waitcnt vmcnt(28)
	v_cvt_pk_bf16_f32 v15, v48, v49
	s_waitcnt vmcnt(26)
	v_cvt_pk_bf16_f32 v16, v50, v51
	s_waitcnt vmcnt(24)
	v_cvt_pk_bf16_f32 v17, v52, v53
	ds_write_b128 v95, v[14:17]
	s_waitcnt vmcnt(22)
	v_cvt_pk_bf16_f32 v14, v54, v55
	s_waitcnt vmcnt(20)
	v_cvt_pk_bf16_f32 v15, v56, v57
	s_waitcnt vmcnt(18)
	v_cvt_pk_bf16_f32 v16, v58, v59
	s_waitcnt vmcnt(16)
	v_cvt_pk_bf16_f32 v17, v60, v61
	ds_write_b128 v96, v[14:17]
	s_waitcnt vmcnt(14)
	v_cvt_pk_bf16_f32 v14, v62, v63
	s_waitcnt vmcnt(12)
	v_cvt_pk_bf16_f32 v15, v64, v65
	s_waitcnt vmcnt(10)
	v_cvt_pk_bf16_f32 v16, v66, v67
	s_waitcnt vmcnt(8)
	v_cvt_pk_bf16_f32 v17, v68, v69
	ds_write_b128 v97, v[14:17]
	s_waitcnt vmcnt(6)
	v_cvt_pk_bf16_f32 v14, v70, v71
	s_waitcnt vmcnt(4)
	v_cvt_pk_bf16_f32 v15, v72, v73
	s_waitcnt vmcnt(2)
	v_cvt_pk_bf16_f32 v16, v74, v75
	s_waitcnt vmcnt(0)
	v_cvt_pk_bf16_f32 v17, v76, v77
	ds_write_b128 v98, v[14:17]
	s_waitcnt lgkmcnt(0)
	v_lshl_add_u64 v[8:9], v[12:13], 1, v[8:9]
	v_mov_b32_e32 v5, v3
	v_lshl_add_u64 v[16:17], v[8:9], 0, v[4:5]
	ds_read_b128 v[8:11], v99
	v_or_b32_e32 v2, v107, v83
	v_ashrrev_i32_e32 v5, 31, v107
	v_mul_lo_u32 v14, v7, v2
	v_mul_lo_u32 v5, v6, v5
	v_mad_u64_u32 v[12:13], s[4:5], v6, v2, 0
	v_add3_u32 v13, v13, v5, v14
	v_lshl_add_u64 v[18:19], v[12:13], 1, v[16:17]
	ds_read_b128 v[12:15], v100
	v_or_b32_e32 v2, v107, v84
	s_waitcnt lgkmcnt(1)
	global_store_dwordx4 v[18:19], v[8:11], off
	v_add_u32_e32 v91, s80, v91
	v_add_u32_e32 v79, s80, v79
	v_mul_lo_u32 v10, v7, v2
	v_mad_u64_u32 v[8:9], s[4:5], v6, v2, 0
	v_add3_u32 v9, v9, v5, v10
	v_lshl_add_u64 v[8:9], v[8:9], 1, v[16:17]
	s_waitcnt lgkmcnt(0)
	global_store_dwordx4 v[8:9], v[12:15], off
	ds_read_b128 v[8:11], v101
	v_or_b32_e32 v2, v107, v85
	v_mul_lo_u32 v14, v7, v2
	v_mad_u64_u32 v[12:13], s[4:5], v6, v2, 0
	v_add3_u32 v13, v13, v5, v14
	v_lshl_add_u64 v[18:19], v[12:13], 1, v[16:17]
	ds_read_b128 v[12:15], v102
	v_or_b32_e32 v2, v107, v86
	s_waitcnt lgkmcnt(1)
	global_store_dwordx4 v[18:19], v[8:11], off
	s_nop 1
	v_mul_lo_u32 v10, v7, v2
	v_mad_u64_u32 v[8:9], s[4:5], v6, v2, 0
	v_add3_u32 v9, v9, v5, v10
	v_lshl_add_u64 v[8:9], v[8:9], 1, v[16:17]
	s_waitcnt lgkmcnt(0)
	global_store_dwordx4 v[8:9], v[12:15], off
	ds_read_b128 v[8:11], v103
	v_or_b32_e32 v2, v107, v87
	v_mul_lo_u32 v14, v7, v2
	v_mad_u64_u32 v[12:13], s[4:5], v6, v2, 0
	v_add3_u32 v13, v13, v5, v14
	v_lshl_add_u64 v[18:19], v[12:13], 1, v[16:17]
	ds_read_b128 v[12:15], v104
	v_or_b32_e32 v2, v107, v88
	s_waitcnt lgkmcnt(1)
	global_store_dwordx4 v[18:19], v[8:11], off
	s_nop 1
	v_mul_lo_u32 v10, v7, v2
	v_mad_u64_u32 v[8:9], s[4:5], v6, v2, 0
	v_add3_u32 v9, v9, v5, v10
	v_lshl_add_u64 v[8:9], v[8:9], 1, v[16:17]
	s_waitcnt lgkmcnt(0)
	global_store_dwordx4 v[8:9], v[12:15], off
	ds_read_b128 v[8:11], v105
	v_or_b32_e32 v2, v107, v89
	v_mul_lo_u32 v14, v7, v2
	v_mad_u64_u32 v[12:13], s[4:5], v6, v2, 0
	v_add3_u32 v13, v13, v5, v14
	v_lshl_add_u64 v[18:19], v[12:13], 1, v[16:17]
	ds_read_b128 v[12:15], v106
	v_or_b32_e32 v2, v107, v90
	s_waitcnt lgkmcnt(1)
	global_store_dwordx4 v[18:19], v[8:11], off
	s_nop 1
	v_mul_lo_u32 v8, v7, v2
	v_mad_u64_u32 v[6:7], s[4:5], v6, v2, 0
	v_add3_u32 v7, v7, v5, v8
	v_lshl_add_u64 v[6:7], v[6:7], 1, v[16:17]
	s_waitcnt lgkmcnt(0)
	global_store_dwordx4 v[6:7], v[12:15], off
	s_waitcnt lgkmcnt(0)
	v_add_u32_e32 v2, 0x1880, v91
	v_cmp_lt_i32_e64 s[4:5], s92, v2
	s_or_b64 s[58:59], s[4:5], s[58:59]
	s_andn2_b64 exec, exec, s[58:59]
	s_cbranch_execz .LBB0_943

; #define GAS __attribute__((address_space(1)))
; __device__ __forceinline__ unsigned pk2(float lo, float hi) { unsigned r; asm("s_nop 1\n\tv_cvt_pk_bf16_f32 %0, %1, %2" : "=v"(r) : "v"(lo), "v"(hi)); return r; }
; __device__ __forceinline__ void convert_late(int part, int brank, int nblocks) {
;     ...
; #pragma unroll
;       for (int u = 0; u < 8; ++u) { const int i = i0 + u * gn; if (i < T * PLE / 4) { u32x2 o = {pk2(v[u].x, v[u].y), pk2(v[u].z, v[u].w)}; ((GAS u32x2*)(ws + OFF_PB))[i] = o; } }
.LBB0_960:
	s_or_b64 exec, exec, s[26:27]
	s_waitcnt vmcnt(0)
	v_cvt_pk_bf16_f32 v56, v14, v15
	v_lshl_add_u64 v[14:15], v[34:35], 3, s[20:21]
	v_cvt_pk_bf16_f32 v57, v16, v17
	global_store_dwordx2 v[14:15], v[56:57], off
	s_and_saveexec_b64 s[26:27], vcc
	s_cbranch_execnz .LBB0_967
	s_or_b64 exec, exec, s[26:27]
	s_and_saveexec_b64 s[26:27], s[4:5]
	s_cbranch_execnz .LBB0_968

; #define GAS __attribute__((address_space(1)))
; __device__ __forceinline__ unsigned pk2(float lo, float hi) { unsigned r; asm("s_nop 1\n\tv_cvt_pk_bf16_f32 %0, %1, %2" : "=v"(r) : "v"(lo), "v"(hi)); return r; }
; __device__ __forceinline__ void convert_late(int part, int brank, int nblocks) {
;     ...
;       for (int u = 0; u < 8; ++u) { const int i = i0 + u * gn; v[u] = (i < T * PLE / 4) ? ((const GAS f32x4*)P.p)[i] : f32x4{0.f, 0.f, 0.f, 0.f}; }
; #pragma unroll
;       for (int u = 0; u < 8; ++u) { const int i = i0 + u * gn; if (i < T * PLE / 4) { u32x2 o = {pk2(v[u].x, v[u].y), pk2(v[u].z, v[u].w)}; ((GAS u32x2*)(ws + OFF_PB))[i] = o; } }
.LBB0_967:
	v_cvt_pk_bf16_f32 v6, v6, v7
	v_cvt_pk_bf16_f32 v7, v8, v9
	v_lshl_add_u64 v[8:9], s[18:19], 3, v[14:15]
	global_store_dwordx2 v[8:9], v[6:7], off
	s_or_b64 exec, exec, s[26:27]
	s_and_saveexec_b64 s[26:27], s[4:5]
	s_cbranch_execz .LBB0_962
.LBB0_968:
	v_cvt_pk_bf16_f32 v2, v2, v3
	v_cvt_pk_bf16_f32 v3, v4, v5
	v_lshl_add_u64 v[4:5], v[36:37], 3, s[20:21]
	global_store_dwordx2 v[4:5], v[2:3], off
	s_or_b64 exec, exec, s[26:27]
	s_and_saveexec_b64 s[4:5], s[6:7]
	s_cbranch_execz .LBB0_963
.LBB0_969:
	v_lshl_add_u64 v[4:5], v[38:39], 3, s[20:21]
	v_cvt_pk_bf16_f32 v2, v18, v19
	v_cvt_pk_bf16_f32 v3, v20, v21
	global_store_dwordx2 v[4:5], v[2:3], off
	s_or_b64 exec, exec, s[4:5]
	s_and_saveexec_b64 s[4:5], s[8:9]
	s_cbranch_execz .LBB0_964
.LBB0_970:
	v_lshl_add_u64 v[4:5], v[40:41], 3, s[20:21]
	v_cvt_pk_bf16_f32 v2, v10, v11
	v_cvt_pk_bf16_f32 v3, v12, v13
	global_store_dwordx2 v[4:5], v[2:3], off
	s_or_b64 exec, exec, s[4:5]
	s_and_saveexec_b64 s[4:5], s[10:11]
	s_cbranch_execz .LBB0_965
.LBB0_971:
	v_lshl_add_u64 v[4:5], v[42:43], 3, s[20:21]
	v_cvt_pk_bf16_f32 v2, v26, v27
	v_cvt_pk_bf16_f32 v3, v28, v29
	global_store_dwordx2 v[4:5], v[2:3], off
	s_or_b64 exec, exec, s[4:5]
	s_and_saveexec_b64 s[4:5], s[12:13]
	s_cbranch_execz .LBB0_966
.LBB0_972:
	v_lshl_add_u64 v[4:5], v[44:45], 3, s[20:21]
	v_cvt_pk_bf16_f32 v2, v22, v23
	v_cvt_pk_bf16_f32 v3, v24, v25
	global_store_dwordx2 v[4:5], v[2:3], off
	s_or_b64 exec, exec, s[4:5]
	s_and_saveexec_b64 s[4:5], s[14:15]
	s_cbranch_execz .LBB0_945
.LBB0_973:
	v_lshl_add_u64 v[4:5], v[46:47], 3, s[20:21]
	v_cvt_pk_bf16_f32 v2, v30, v31
	v_cvt_pk_bf16_f32 v3, v32, v33
	global_store_dwordx2 v[4:5], v[2:3], off
	s_branch .LBB0_945

; #define LAS __attribute__((address_space(3)))
; #define GAS __attribute__((address_space(1)))
; __device__ __forceinline__ unsigned pk2(float lo, float hi) { unsigned r; asm("s_nop 1\n\tv_cvt_pk_bf16_f32 %0, %1, %2" : "=v"(r) : "v"(lo), "v"(hi)); return r; }
; __device__ __forceinline__ void tr_wave_job(const GAS float* src0, const GAS float* src1, int ld, int mode, GAS bf16* dst, int K, int ldd, int n0, int k0, int lane, int wid, const GAS float* gk) {
;     ...
; #pragma unroll
;   for (int q = 0; q < 8; ++q) {
;     u32x4 o = {pk2(v[8 * q + 0], v[8 * q + 1]), pk2(v[8 * q + 2], v[8 * q + 3]), pk2(v[8 * q + 4], v[8 * q + 5]), pk2(v[8 * q + 6], v[8 * q + 7])};
;     *(LAS u32x4*)(scr + (lane * 8 + (q ^ (lane & 7))) * 16) = o;
;   }
;   asm volatile("s_waitcnt lgkmcnt(0)" ::: "memory");
;   const int rq = lane & 7;
; #pragma unroll
;   for (int i = 0; i < 8; ++i) {
;     const int r = i * 8 + (lane >> 3);
;     const u32x4 o = *(const LAS u32x4*)(scr + (r * 8 + (rq ^ (r & 7))) * 16);
;     *(GAS u32x4*)(dst + (size_t)(n0 + r) * ldd + k0 + rq * 8) = o;
;   }
;   asm volatile("s_waitcnt lgkmcnt(0)" ::: "memory");
.LBB0_979:
	s_or_b64 exec, exec, s[60:61]
	s_waitcnt vmcnt(62)
	v_cvt_pk_bf16_f32 v14, v14, v15
	s_waitcnt vmcnt(60)
	v_cvt_pk_bf16_f32 v15, v16, v17
	s_waitcnt vmcnt(58)
	v_cvt_pk_bf16_f32 v16, v18, v19
	s_waitcnt vmcnt(56)
	v_cvt_pk_bf16_f32 v17, v20, v21
	v_add_u32_e32 v2, v81, v82
	ds_write_b128 v2, v[14:17]
	s_waitcnt vmcnt(54)
	v_cvt_pk_bf16_f32 v14, v22, v23
	s_waitcnt vmcnt(52)
	v_cvt_pk_bf16_f32 v15, v24, v25
	s_waitcnt vmcnt(50)
	v_cvt_pk_bf16_f32 v16, v26, v27
	s_waitcnt vmcnt(48)
	v_cvt_pk_bf16_f32 v17, v28, v29
	ds_write_b128 v92, v[14:17]
	s_waitcnt vmcnt(46)
	v_cvt_pk_bf16_f32 v14, v30, v31
	s_waitcnt vmcnt(44)
	v_cvt_pk_bf16_f32 v15, v32, v33
	s_waitcnt vmcnt(42)
	v_cvt_pk_bf16_f32 v16, v34, v35
	s_waitcnt vmcnt(40)
	v_cvt_pk_bf16_f32 v17, v36, v37
	ds_write_b128 v93, v[14:17]
	s_waitcnt vmcnt(38)
	v_cvt_pk_bf16_f32 v14, v38, v39
	s_waitcnt vmcnt(36)
	v_cvt_pk_bf16_f32 v15, v40, v41
	s_waitcnt vmcnt(34)
	v_cvt_pk_bf16_f32 v16, v42, v43
	s_waitcnt vmcnt(32)
	v_cvt_pk_bf16_f32 v17, v44, v45
	ds_write_b128 v94, v[14:17]
	s_waitcnt vmcnt(30)
	v_cvt_pk_bf16_f32 v14, v46, v47
	s_waitcnt vmcnt(28)
	v_cvt_pk_bf16_f32 v15, v48, v49
	s_waitcnt vmcnt(26)
	v_cvt_pk_bf16_f32 v16, v50, v51
	s_waitcnt vmcnt(24)
	v_cvt_pk_bf16_f32 v17, v52, v53
	ds_write_b128 v95, v[14:17]
	s_waitcnt vmcnt(22)
	v_cvt_pk_bf16_f32 v14, v54, v55
	s_waitcnt vmcnt(20)
	v_cvt_pk_bf16_f32 v15, v56, v57
	s_waitcnt vmcnt(18)
	v_cvt_pk_bf16_f32 v16, v58, v59
	s_waitcnt vmcnt(16)
	v_cvt_pk_bf16_f32 v17, v60, v61
	ds_write_b128 v96, v[14:17]
	s_waitcnt vmcnt(14)
	v_cvt_pk_bf16_f32 v14, v62, v63
	s_waitcnt vmcnt(12)
	v_cvt_pk_bf16_f32 v15, v64, v65
	s_waitcnt vmcnt(10)
	v_cvt_pk_bf16_f32 v16, v66, v67
	s_waitcnt vmcnt(8)
	v_cvt_pk_bf16_f32 v17, v68, v69
	ds_write_b128 v97, v[14:17]
	s_waitcnt vmcnt(6)
	v_cvt_pk_bf16_f32 v14, v70, v71
	s_waitcnt vmcnt(4)
	v_cvt_pk_bf16_f32 v15, v72, v73
	s_waitcnt vmcnt(2)
	v_cvt_pk_bf16_f32 v16, v74, v75
	s_waitcnt vmcnt(0)
	v_cvt_pk_bf16_f32 v17, v76, v77
	ds_write_b128 v98, v[14:17]
	s_waitcnt lgkmcnt(0)
	v_lshl_add_u64 v[8:9], v[12:13], 1, v[8:9]
	v_mov_b32_e32 v5, v3
	v_lshl_add_u64 v[16:17], v[8:9], 0, v[4:5]
	ds_read_b128 v[8:11], v99
	v_or_b32_e32 v2, v107, v83
	v_ashrrev_i32_e32 v5, 31, v107
	v_mul_lo_u32 v14, v7, v2
	v_mul_lo_u32 v5, v6, v5
	v_mad_u64_u32 v[12:13], s[4:5], v6, v2, 0
	v_add3_u32 v13, v13, v5, v14
	v_lshl_add_u64 v[18:19], v[12:13], 1, v[16:17]
	ds_read_b128 v[12:15], v100
	v_or_b32_e32 v2, v107, v84
	s_waitcnt lgkmcnt(1)
	global_store_dwordx4 v[18:19], v[8:11], off
	v_add_u32_e32 v91, s44, v91
	v_add_u32_e32 v79, s44, v79
	v_mul_lo_u32 v10, v7, v2
	v_mad_u64_u32 v[8:9], s[4:5], v6, v2, 0
	v_add3_u32 v9, v9, v5, v10
	v_lshl_add_u64 v[8:9], v[8:9], 1, v[16:17]
	s_waitcnt lgkmcnt(0)
	global_store_dwordx4 v[8:9], v[12:15], off
	ds_read_b128 v[8:11], v101
	v_or_b32_e32 v2, v107, v85
	v_mul_lo_u32 v14, v7, v2
	v_mad_u64_u32 v[12:13], s[4:5], v6, v2, 0
	v_add3_u32 v13, v13, v5, v14
	v_lshl_add_u64 v[18:19], v[12:13], 1, v[16:17]
	ds_read_b128 v[12:15], v102
	v_or_b32_e32 v2, v107, v86
	s_waitcnt lgkmcnt(1)
	global_store_dwordx4 v[18:19], v[8:11], off
	s_nop 1
	v_mul_lo_u32 v10, v7, v2
	v_mad_u64_u32 v[8:9], s[4:5], v6, v2, 0
	v_add3_u32 v9, v9, v5, v10
	v_lshl_add_u64 v[8:9], v[8:9], 1, v[16:17]
	s_waitcnt lgkmcnt(0)
	global_store_dwordx4 v[8:9], v[12:15], off
	ds_read_b128 v[8:11], v103
	v_or_b32_e32 v2, v107, v87
	v_mul_lo_u32 v14, v7, v2
	v_mad_u64_u32 v[12:13], s[4:5], v6, v2, 0
	v_add3_u32 v13, v13, v5, v14
	v_lshl_add_u64 v[18:19], v[12:13], 1, v[16:17]
	ds_read_b128 v[12:15], v104
	v_or_b32_e32 v2, v107, v88
	s_waitcnt lgkmcnt(1)
	global_store_dwordx4 v[18:19], v[8:11], off
	s_nop 1
	v_mul_lo_u32 v10, v7, v2
	v_mad_u64_u32 v[8:9], s[4:5], v6, v2, 0
	v_add3_u32 v9, v9, v5, v10
	v_lshl_add_u64 v[8:9], v[8:9], 1, v[16:17]
	s_waitcnt lgkmcnt(0)
	global_store_dwordx4 v[8:9], v[12:15], off
	ds_read_b128 v[8:11], v105
	v_or_b32_e32 v2, v107, v89
	v_mul_lo_u32 v14, v7, v2
	v_mad_u64_u32 v[12:13], s[4:5], v6, v2, 0
	v_add3_u32 v13, v13, v5, v14
	v_lshl_add_u64 v[18:19], v[12:13], 1, v[16:17]
	ds_read_b128 v[12:15], v106
	v_or_b32_e32 v2, v107, v90
	s_waitcnt lgkmcnt(1)
	global_store_dwordx4 v[18:19], v[8:11], off
	s_nop 1
	v_mul_lo_u32 v8, v7, v2
	v_mad_u64_u32 v[6:7], s[4:5], v6, v2, 0
	v_add3_u32 v7, v7, v5, v8
	v_lshl_add_u64 v[6:7], v[6:7], 1, v[16:17]
	s_waitcnt lgkmcnt(0)
	global_store_dwordx4 v[6:7], v[12:15], off
	s_waitcnt lgkmcnt(0)
	v_add_u32_e32 v2, 0x1880, v91
	v_cmp_lt_i32_e64 s[4:5], s88, v2
	s_or_b64 s[58:59], s[4:5], s[58:59]
	s_andn2_b64 exec, exec, s[58:59]
	s_cbranch_execz .LBB0_1026

; #define GAS __attribute__((address_space(1)))
; __device__ __forceinline__ unsigned pk2(float lo, float hi) { unsigned r; asm("s_nop 1\n\tv_cvt_pk_bf16_f32 %0, %1, %2" : "=v"(r) : "v"(lo), "v"(hi)); return r; }
; __device__ __forceinline__ void convert_late(int part, int brank, int nblocks) {
;     ...
; #pragma unroll
;       for (int u = 0; u < 8; ++u) { const int i = i0 + u * gn; if (i < T * PLE / 4) { u32x2 o = {pk2(v[u].x, v[u].y), pk2(v[u].z, v[u].w)}; ((GAS u32x2*)(ws + OFF_PB))[i] = o; } }
.LBB0_1043:
	s_or_b64 exec, exec, s[26:27]
	s_waitcnt vmcnt(0)
	v_cvt_pk_bf16_f32 v48, v14, v15
	v_lshl_add_u64 v[14:15], v[34:35], 3, s[20:21]
	v_cvt_pk_bf16_f32 v49, v16, v17
	global_store_dwordx2 v[14:15], v[48:49], off
	s_and_saveexec_b64 s[26:27], vcc
	s_cbranch_execnz .LBB0_1050
	s_or_b64 exec, exec, s[26:27]
	s_and_saveexec_b64 s[26:27], s[4:5]
	s_cbranch_execnz .LBB0_1051

; __device__ __forceinline__ unsigned f2bf(float f) { return pk2(f, f) & 0xffffu; }
; template <int K, int LD>
; __device__ __forceinline__ void phase_resid(int mode) {
;     ...
; #pragma unroll
;       for (int m2 = 0; m2 < 2; ++m2)
; #pragma unroll
;         for (int j = 0; j < 4; ++j)
; #pragma unroll
;           for (int bj = 0; bj < 2; ++bj)
; #pragma unroll
;             for (int n = 0; n < 2; ++n) {
;               const size_t idx = (size_t)(brow + ai * 128 + wr * 64 + (mh * 2 + m2) * 16 + fq * 4 + j) * DM + bcol + bj * 128 + wc * 32 + n * 16 + fr;
;               xo[m2][j][bj][n] = (mode == 0) ? xin[idx] : bf2f(xg[idx]);
;             }
; #pragma unroll
;       for (int m2 = 0; m2 < 2; ++m2)
; #pragma unroll
;         for (int j = 0; j < 4; ++j) {
;           const int m = mh * 2 + m2; const int row = brow + ai * 128 + wr * 64 + m * 16 + fq * 4 + j;
;           float ss = 0.f;
; #pragma unroll
;           for (int bj = 0; bj < 2; ++bj)
; #pragma unroll
;             for (int n = 0; n < 2; ++n) {
;               const size_t idx = (size_t)row * DM + bcol + bj * 128 + wc * 32 + n * 16 + fr;
;               const float xn = xo[m2][j][bj][n] + scale * acc[ai][bj][m][n][j];
;               ss += xn * xn;
;               xg[idx] = (unsigned short)f2bf(xn);
;             }
;           ss = sum16(ss);
;           if (fr == 0) ssq[(size_t)row * 16 + pn0 * 4 + wc] = ss;
;         }
.LBB0_1110:
	v_mov_b32_e32 v130, v170
	v_mov_b32_e32 v133, s15
	v_ashrrev_i32_e32 v132, 2, v130
	v_and_b32_e32 v132, 0xffffffc0, v132
	v_bfe_u32 v202, v130, 6, 2
	v_and_b32_e32 v203, 15, v130
	v_lshrrev_b32_e32 v130, 2, v130
	v_add_u32_e32 v132, s40, v132
	v_and_or_b32 v136, v130, 12, v132
	v_lshlrev_b32_e32 v130, 5, v202
	v_ashrrev_i32_e32 v137, 31, v136
	v_or_b32_e32 v162, 1, v136
	v_or3_b32 v132, v130, v203, s14
	v_lshlrev_b64 v[200:201], 11, v[136:137]
	v_ashrrev_i32_e32 v163, 31, v162
	v_or_b32_e32 v158, 2, v136
	v_lshl_add_u64 v[134:135], s[4:5], 0, v[200:201]
	v_lshlrev_b64 v[138:139], 1, v[132:133]
	v_lshlrev_b64 v[166:167], 11, v[162:163]
	v_ashrrev_i32_e32 v159, 31, v158
	v_or_b32_e32 v154, 3, v136
	v_lshl_add_u64 v[132:133], v[134:135], 0, v[138:139]
	v_lshl_add_u64 v[134:135], s[4:5], 0, v[166:167]
	v_lshlrev_b64 v[164:165], 11, v[158:159]
	v_ashrrev_i32_e32 v155, 31, v154
	v_or_b32_e32 v150, 16, v136
	v_lshl_add_u64 v[134:135], v[134:135], 0, v[138:139]
	global_load_ushort v204, v[132:133], off
	global_load_ushort v205, v[132:133], off offset:32
	global_load_ushort v206, v[132:133], off offset:256
	global_load_ushort v207, v[132:133], off offset:288
	global_load_ushort v196, v[134:135], off
	global_load_ushort v197, v[134:135], off offset:32
	global_load_ushort v198, v[134:135], off offset:256
	global_load_ushort v199, v[134:135], off offset:288
	v_lshl_add_u64 v[132:133], s[4:5], 0, v[164:165]
	v_lshlrev_b64 v[160:161], 11, v[154:155]
	v_ashrrev_i32_e32 v151, 31, v150
	v_or_b32_e32 v146, 17, v136
	v_lshl_add_u64 v[132:133], v[132:133], 0, v[138:139]
	v_lshl_add_u64 v[134:135], s[4:5], 0, v[160:161]
	v_lshlrev_b64 v[156:157], 11, v[150:151]
	v_ashrrev_i32_e32 v147, 31, v146
	v_or_b32_e32 v142, 18, v136
	v_lshl_add_u64 v[134:135], v[134:135], 0, v[138:139]
	global_load_ushort v192, v[132:133], off
	global_load_ushort v193, v[132:133], off offset:32
	global_load_ushort v194, v[132:133], off offset:256
	global_load_ushort v195, v[132:133], off offset:288
	global_load_ushort v188, v[134:135], off
	global_load_ushort v189, v[134:135], off offset:32
	global_load_ushort v190, v[134:135], off offset:256
	global_load_ushort v191, v[134:135], off offset:288
	v_lshl_add_u64 v[132:133], s[4:5], 0, v[156:157]
	v_lshlrev_b64 v[152:153], 11, v[146:147]
	v_ashrrev_i32_e32 v143, 31, v142
	v_or_b32_e32 v140, 19, v136
	v_lshl_add_u64 v[132:133], v[132:133], 0, v[138:139]
	v_lshl_add_u64 v[134:135], s[4:5], 0, v[152:153]
	v_lshlrev_b64 v[148:149], 11, v[142:143]
	v_ashrrev_i32_e32 v141, 31, v140
	v_lshl_add_u64 v[134:135], v[134:135], 0, v[138:139]
	global_load_ushort v184, v[132:133], off
	global_load_ushort v185, v[132:133], off offset:32
	global_load_ushort v186, v[132:133], off offset:256
	global_load_ushort v187, v[132:133], off offset:288
	global_load_ushort v180, v[134:135], off
	global_load_ushort v181, v[134:135], off offset:32
	global_load_ushort v182, v[134:135], off offset:256
	global_load_ushort v183, v[134:135], off offset:288
	v_lshl_add_u64 v[132:133], s[4:5], 0, v[148:149]
	v_lshlrev_b64 v[144:145], 11, v[140:141]
	v_lshl_add_u64 v[132:133], v[132:133], 0, v[138:139]
	v_lshl_add_u64 v[134:135], s[4:5], 0, v[144:145]
	v_lshl_add_u64 v[134:135], v[134:135], 0, v[138:139]
	global_load_ushort v176, v[132:133], off
	global_load_ushort v177, v[132:133], off offset:32
	global_load_ushort v178, v[132:133], off offset:256
	global_load_ushort v179, v[132:133], off offset:288
	global_load_ushort v168, v[134:135], off
	global_load_ushort v169, v[134:135], off offset:32
	global_load_ushort v174, v[134:135], off offset:256
	global_load_ushort v175, v[134:135], off offset:288
	s_lshl_b64 s[14:15], s[14:15], 1
	s_add_u32 s14, s4, s14
	s_addc_u32 s15, s5, s15
	v_lshlrev_b32_e32 v130, 6, v202
	v_lshl_add_u64 v[132:133], s[14:15], 0, v[130:131]
	s_lshl_b32 s14, s39, 2
	s_ashr_i32 s15, s14, 31
	s_lshl_b64 s[14:15], s[14:15], 2
	v_lshlrev_b32_e32 v130, 1, v203
	s_add_u32 s14, s29, s14
	v_lshl_add_u64 v[134:135], v[132:133], 0, v[130:131]
	s_addc_u32 s15, s30, s15
	v_lshlrev_b32_e32 v130, 2, v202
	v_lshl_add_u64 v[132:133], s[14:15], 0, v[130:131]
	v_cmp_eq_u32_e32 vcc, 0, v203
	v_lshl_add_u64 v[200:201], v[134:135], 0, v[200:201]
	s_waitcnt vmcnt(0)
	v_lshlrev_b32_e32 v130, 16, v204
	v_lshlrev_b32_e32 v202, 16, v205
	v_fmac_f32_e32 v202, 0.5, v114
	v_lshlrev_b32_e32 v203, 16, v206
	v_fmac_f32_e32 v130, 0.5, v118
	v_mul_f32_e32 v114, v202, v202
	v_lshlrev_b32_e32 v204, 16, v207
	v_fmac_f32_e32 v114, v130, v130
	v_fmac_f32_e32 v203, 0.5, v126
	v_cvt_pk_bf16_f32 v118, v130, v130
	v_fmac_f32_e32 v114, v203, v203
	v_fmac_f32_e32 v204, 0.5, v122
	global_store_short v[200:201], v118, off
	v_cvt_pk_bf16_f32 v118, v202, v202
	v_fmac_f32_e32 v114, v204, v204
	global_store_short v[200:201], v118, off offset:32
	v_cvt_pk_bf16_f32 v118, v203, v203
	global_store_short v[200:201], v118, off offset:256
	v_add_f32_dpp v114, v114, v114 quad_perm:[1,0,3,2] row_mask:0xf bank_mask:0xf bound_ctrl:1
	v_cvt_pk_bf16_f32 v118, v204, v204
	global_store_short v[200:201], v118, off offset:288
	v_mov_b32_e32 v118, 0
	v_add_f32_dpp v114, v114, v114 quad_perm:[2,3,0,1] row_mask:0xf bank_mask:0xf bound_ctrl:1
	s_nop 1
	v_add_f32_dpp v114, v114, v114 row_half_mirror row_mask:0xf bank_mask:0xf bound_ctrl:1
	s_nop 1
	v_mov_b32_dpp v118, v114 row_mirror row_mask:0xf bank_mask:0xf
	s_and_saveexec_b64 s[14:15], vcc
	s_cbranch_execz .LBB0_1112
	v_lshlrev_b64 v[200:201], 6, v[136:137]
	v_add_f32_e32 v114, v114, v118
	v_lshl_add_u64 v[200:201], v[132:133], 0, v[200:201]
	global_store_dword v[200:201], v114, off
; __device__ __forceinline__ unsigned f2bf(float f) { return pk2(f, f) & 0xffffu; }
; template <int K, int LD>
; __device__ __forceinline__ void phase_resid(int mode) {
;     ...
;       for (int m2 = 0; m2 < 2; ++m2)
; #pragma unroll
;         for (int j = 0; j < 4; ++j) {
;           const int m = mh * 2 + m2; const int row = brow + ai * 128 + wr * 64 + m * 16 + fq * 4 + j;
;           float ss = 0.f;
; #pragma unroll
;           for (int bj = 0; bj < 2; ++bj)
; #pragma unroll
;             for (int n = 0; n < 2; ++n) {
;               const size_t idx = (size_t)row * DM + bcol + bj * 128 + wc * 32 + n * 16 + fr;
;               const float xn = xo[m2][j][bj][n] + scale * acc[ai][bj][m][n][j];
;               ss += xn * xn;
;               xg[idx] = (unsigned short)f2bf(xn);
;             }
;           ss = sum16(ss);
;           if (fr == 0) ssq[(size_t)row * 16 + pn0 * 4 + wc] = ss;
;         }
.LBB0_1112:
	s_or_b64 exec, exec, s[14:15]
	v_lshlrev_b32_e32 v118, 16, v197
	v_lshlrev_b32_e32 v114, 16, v196
	v_fmac_f32_e32 v118, 0.5, v115
	v_lshlrev_b32_e32 v122, 16, v198
	v_fmac_f32_e32 v114, 0.5, v119
	v_mul_f32_e32 v115, v118, v118
	v_lshlrev_b32_e32 v126, 16, v199
	v_lshl_add_u64 v[166:167], v[134:135], 0, v[166:167]
	v_cvt_pk_bf16_f32 v119, v114, v114
	v_fmac_f32_e32 v115, v114, v114
	v_cvt_pk_bf16_f32 v114, v118, v118
	v_fmac_f32_e32 v122, 0.5, v127
	global_store_short v[166:167], v114, off offset:32
	v_fmac_f32_e32 v115, v122, v122
	v_cvt_pk_bf16_f32 v114, v122, v122
	v_fmac_f32_e32 v126, 0.5, v123
	global_store_short v[166:167], v114, off offset:256
	v_fmac_f32_e32 v115, v126, v126
	v_cvt_pk_bf16_f32 v114, v126, v126
	global_store_short v[166:167], v114, off offset:288
	global_store_short v[166:167], v119, off
	v_add_f32_dpp v114, v115, v115 quad_perm:[1,0,3,2] row_mask:0xf bank_mask:0xf bound_ctrl:1
	v_mov_b32_e32 v115, 0
	s_nop 0
	v_add_f32_dpp v114, v114, v114 quad_perm:[2,3,0,1] row_mask:0xf bank_mask:0xf bound_ctrl:1
	s_nop 1
	v_add_f32_dpp v114, v114, v114 row_half_mirror row_mask:0xf bank_mask:0xf bound_ctrl:1
	s_nop 1
	v_mov_b32_dpp v115, v114 row_mirror row_mask:0xf bank_mask:0xf
	s_and_saveexec_b64 s[14:15], vcc
	s_cbranch_execz .LBB0_1114
	v_add_f32_e32 v118, v114, v115
	v_lshlrev_b64 v[114:115], 6, v[162:163]
	v_lshl_add_u64 v[114:115], v[132:133], 0, v[114:115]
	global_store_dword v[114:115], v118, off
.LBB0_1114:
	s_or_b64 exec, exec, s[14:15]
	v_lshlrev_b32_e32 v119, 16, v193
	v_lshlrev_b32_e32 v118, 16, v192
	v_fmac_f32_e32 v119, 0.5, v116
	v_lshlrev_b32_e32 v122, 16, v194
	v_fmac_f32_e32 v118, 0.5, v120
	v_mul_f32_e32 v116, v119, v119
	v_lshlrev_b32_e32 v123, 16, v195
	v_fmac_f32_e32 v116, v118, v118
	v_fmac_f32_e32 v122, 0.5, v128
	v_lshl_add_u64 v[114:115], v[134:135], 0, v[164:165]
	v_cvt_pk_bf16_f32 v120, v118, v118
	v_cvt_pk_bf16_f32 v118, v119, v119
	v_fmac_f32_e32 v116, v122, v122
	v_fmac_f32_e32 v123, 0.5, v124
	global_store_short v[114:115], v118, off offset:32
	v_cvt_pk_bf16_f32 v118, v122, v122
	v_fmac_f32_e32 v116, v123, v123
	global_store_short v[114:115], v120, off
	global_store_short v[114:115], v118, off offset:256
	v_cvt_pk_bf16_f32 v118, v123, v123
	global_store_short v[114:115], v118, off offset:288
	v_add_f32_dpp v114, v116, v116 quad_perm:[1,0,3,2] row_mask:0xf bank_mask:0xf bound_ctrl:1
	v_mov_b32_e32 v115, 0
	s_nop 0
	v_add_f32_dpp v114, v114, v114 quad_perm:[2,3,0,1] row_mask:0xf bank_mask:0xf bound_ctrl:1
	s_nop 1
	v_add_f32_dpp v114, v114, v114 row_half_mirror row_mask:0xf bank_mask:0xf bound_ctrl:1
	s_nop 1
	v_mov_b32_dpp v115, v114 row_mirror row_mask:0xf bank_mask:0xf
	s_and_saveexec_b64 s[14:15], vcc
	s_cbranch_execz .LBB0_1116
	v_add_f32_e32 v116, v114, v115
	v_lshlrev_b64 v[114:115], 6, v[158:159]
	v_lshl_add_u64 v[114:115], v[132:133], 0, v[114:115]
	global_store_dword v[114:115], v116, off
.LBB0_1116:
	s_or_b64 exec, exec, s[14:15]
	v_lshlrev_b32_e32 v118, 16, v189
	v_lshlrev_b32_e32 v116, 16, v188
	v_fmac_f32_e32 v118, 0.5, v117
	v_lshlrev_b32_e32 v119, 16, v190
	v_fmac_f32_e32 v116, 0.5, v121
	v_mul_f32_e32 v117, v118, v118
	v_lshlrev_b32_e32 v120, 16, v191
	v_fmac_f32_e32 v117, v116, v116
	v_fmac_f32_e32 v119, 0.5, v129
	v_lshl_add_u64 v[114:115], v[134:135], 0, v[160:161]
	v_cvt_pk_bf16_f32 v121, v116, v116
	v_cvt_pk_bf16_f32 v116, v118, v118
	v_fmac_f32_e32 v117, v119, v119
	v_fmac_f32_e32 v120, 0.5, v125
	global_store_short v[114:115], v116, off offset:32
	v_cvt_pk_bf16_f32 v116, v119, v119
	v_fmac_f32_e32 v117, v120, v120
	global_store_short v[114:115], v121, off
	global_store_short v[114:115], v116, off offset:256
	v_cvt_pk_bf16_f32 v116, v120, v120
	global_store_short v[114:115], v116, off offset:288
	v_add_f32_dpp v114, v117, v117 quad_perm:[1,0,3,2] row_mask:0xf bank_mask:0xf bound_ctrl:1
	v_mov_b32_e32 v115, 0
	s_nop 0
	v_add_f32_dpp v114, v114, v114 quad_perm:[2,3,0,1] row_mask:0xf bank_mask:0xf bound_ctrl:1
	s_nop 1
	v_add_f32_dpp v114, v114, v114 row_half_mirror row_mask:0xf bank_mask:0xf bound_ctrl:1
	s_nop 1
	v_mov_b32_dpp v115, v114 row_mirror row_mask:0xf bank_mask:0xf
	s_and_saveexec_b64 s[14:15], vcc
	s_cbranch_execz .LBB0_1118
	v_add_f32_e32 v116, v114, v115
	v_lshlrev_b64 v[114:115], 6, v[154:155]
	v_lshl_add_u64 v[114:115], v[132:133], 0, v[114:115]
	global_store_dword v[114:115], v116, off
.LBB0_1118:
	s_or_b64 exec, exec, s[14:15]
	v_lshlrev_b32_e32 v117, 16, v185
	v_lshlrev_b32_e32 v116, 16, v184
	v_fmac_f32_e32 v117, 0.5, v98
	v_lshlrev_b32_e32 v118, 16, v186
	v_fmac_f32_e32 v116, 0.5, v102
	v_mul_f32_e32 v98, v117, v117
	v_lshlrev_b32_e32 v119, 16, v187
	v_fmac_f32_e32 v98, v116, v116
	v_fmac_f32_e32 v118, 0.5, v110
	v_lshl_add_u64 v[114:115], v[134:135], 0, v[156:157]
	v_cvt_pk_bf16_f32 v102, v116, v116
	v_fmac_f32_e32 v98, v118, v118
	v_fmac_f32_e32 v119, 0.5, v106
	global_store_short v[114:115], v102, off
	v_cvt_pk_bf16_f32 v102, v117, v117
	v_fmac_f32_e32 v98, v119, v119
	global_store_short v[114:115], v102, off offset:32
	v_cvt_pk_bf16_f32 v102, v118, v118
	global_store_short v[114:115], v102, off offset:256
	v_add_f32_dpp v98, v98, v98 quad_perm:[1,0,3,2] row_mask:0xf bank_mask:0xf bound_ctrl:1
	v_cvt_pk_bf16_f32 v102, v119, v119
	global_store_short v[114:115], v102, off offset:288
	v_mov_b32_e32 v102, 0
	v_add_f32_dpp v98, v98, v98 quad_perm:[2,3,0,1] row_mask:0xf bank_mask:0xf bound_ctrl:1
	s_nop 1
	v_add_f32_dpp v98, v98, v98 row_half_mirror row_mask:0xf bank_mask:0xf bound_ctrl:1
	s_nop 1
	v_mov_b32_dpp v102, v98 row_mirror row_mask:0xf bank_mask:0xf
	s_and_saveexec_b64 s[14:15], vcc
	s_cbranch_execz .LBB0_1120
	v_lshlrev_b64 v[114:115], 6, v[150:151]
	v_add_f32_e32 v98, v98, v102
	v_lshl_add_u64 v[114:115], v[132:133], 0, v[114:115]
	global_store_dword v[114:115], v98, off
; __device__ __forceinline__ unsigned f2bf(float f) { return pk2(f, f) & 0xffffu; }
; template <int K, int LD>
; __device__ __forceinline__ void phase_resid(int mode) {
;     ...
;       for (int m2 = 0; m2 < 2; ++m2)
; #pragma unroll
;         for (int j = 0; j < 4; ++j) {
;           const int m = mh * 2 + m2; const int row = brow + ai * 128 + wr * 64 + m * 16 + fq * 4 + j;
;           float ss = 0.f;
; #pragma unroll
;           for (int bj = 0; bj < 2; ++bj)
; #pragma unroll
;             for (int n = 0; n < 2; ++n) {
;               const size_t idx = (size_t)row * DM + bcol + bj * 128 + wc * 32 + n * 16 + fr;
;               const float xn = xo[m2][j][bj][n] + scale * acc[ai][bj][m][n][j];
;               ss += xn * xn;
;               xg[idx] = (unsigned short)f2bf(xn);
;             }
;           ss = sum16(ss);
;           if (fr == 0) ssq[(size_t)row * 16 + pn0 * 4 + wc] = ss;
;         }
.LBB0_1120:
	s_or_b64 exec, exec, s[14:15]
	v_lshlrev_b32_e32 v102, 16, v181
	v_lshlrev_b32_e32 v98, 16, v180
	v_fmac_f32_e32 v102, 0.5, v99
	v_lshlrev_b32_e32 v106, 16, v182
	v_fmac_f32_e32 v98, 0.5, v103
	v_mul_f32_e32 v99, v102, v102
	v_lshlrev_b32_e32 v110, 16, v183
	v_lshl_add_u64 v[114:115], v[134:135], 0, v[152:153]
	v_cvt_pk_bf16_f32 v103, v98, v98
	v_fmac_f32_e32 v99, v98, v98
	v_cvt_pk_bf16_f32 v98, v102, v102
	v_fmac_f32_e32 v106, 0.5, v111
	global_store_short v[114:115], v98, off offset:32
	v_fmac_f32_e32 v99, v106, v106
	v_cvt_pk_bf16_f32 v98, v106, v106
	v_fmac_f32_e32 v110, 0.5, v107
	global_store_short v[114:115], v98, off offset:256
	v_fmac_f32_e32 v99, v110, v110
	v_cvt_pk_bf16_f32 v98, v110, v110
	global_store_short v[114:115], v98, off offset:288
	global_store_short v[114:115], v103, off
	v_add_f32_dpp v98, v99, v99 quad_perm:[1,0,3,2] row_mask:0xf bank_mask:0xf bound_ctrl:1
	v_mov_b32_e32 v99, 0
	s_nop 0
	v_add_f32_dpp v98, v98, v98 quad_perm:[2,3,0,1] row_mask:0xf bank_mask:0xf bound_ctrl:1
	s_nop 1
	v_add_f32_dpp v98, v98, v98 row_half_mirror row_mask:0xf bank_mask:0xf bound_ctrl:1
	s_nop 1
	v_mov_b32_dpp v99, v98 row_mirror row_mask:0xf bank_mask:0xf
	s_and_saveexec_b64 s[14:15], vcc
	s_cbranch_execz .LBB0_1122
	v_add_f32_e32 v102, v98, v99
	v_lshlrev_b64 v[98:99], 6, v[146:147]
	v_lshl_add_u64 v[98:99], v[132:133], 0, v[98:99]
	global_store_dword v[98:99], v102, off
.LBB0_1122:
	s_or_b64 exec, exec, s[14:15]
	v_lshlrev_b32_e32 v103, 16, v177
	v_lshlrev_b32_e32 v102, 16, v176
	v_fmac_f32_e32 v103, 0.5, v100
	v_lshlrev_b32_e32 v106, 16, v178
	v_fmac_f32_e32 v102, 0.5, v104
	v_mul_f32_e32 v100, v103, v103
	v_lshlrev_b32_e32 v107, 16, v179
	v_fmac_f32_e32 v100, v102, v102
	v_fmac_f32_e32 v106, 0.5, v112
	v_lshl_add_u64 v[98:99], v[134:135], 0, v[148:149]
	v_cvt_pk_bf16_f32 v104, v102, v102
	v_cvt_pk_bf16_f32 v102, v103, v103
	v_fmac_f32_e32 v100, v106, v106
	v_fmac_f32_e32 v107, 0.5, v108
	global_store_short v[98:99], v102, off offset:32
	v_cvt_pk_bf16_f32 v102, v106, v106
	v_fmac_f32_e32 v100, v107, v107
	global_store_short v[98:99], v104, off
	global_store_short v[98:99], v102, off offset:256
	v_cvt_pk_bf16_f32 v102, v107, v107
	global_store_short v[98:99], v102, off offset:288
	v_add_f32_dpp v98, v100, v100 quad_perm:[1,0,3,2] row_mask:0xf bank_mask:0xf bound_ctrl:1
	v_mov_b32_e32 v99, 0
	s_nop 0
	v_add_f32_dpp v98, v98, v98 quad_perm:[2,3,0,1] row_mask:0xf bank_mask:0xf bound_ctrl:1
	s_nop 1
	v_add_f32_dpp v98, v98, v98 row_half_mirror row_mask:0xf bank_mask:0xf bound_ctrl:1
	s_nop 1
	v_mov_b32_dpp v99, v98 row_mirror row_mask:0xf bank_mask:0xf
	s_and_saveexec_b64 s[14:15], vcc
	s_cbranch_execz .LBB0_1124
	v_add_f32_e32 v100, v98, v99
	v_lshlrev_b64 v[98:99], 6, v[142:143]
	v_lshl_add_u64 v[98:99], v[132:133], 0, v[98:99]
	global_store_dword v[98:99], v100, off
.LBB0_1124:
	s_or_b64 exec, exec, s[14:15]
	v_lshlrev_b32_e32 v102, 16, v169
	v_lshlrev_b32_e32 v100, 16, v168
	v_fmac_f32_e32 v102, 0.5, v101
	v_lshlrev_b32_e32 v103, 16, v174
	v_fmac_f32_e32 v100, 0.5, v105
	v_mul_f32_e32 v101, v102, v102
	v_lshlrev_b32_e32 v104, 16, v175
	v_fmac_f32_e32 v101, v100, v100
	v_fmac_f32_e32 v103, 0.5, v113
	v_lshl_add_u64 v[98:99], v[134:135], 0, v[144:145]
	v_cvt_pk_bf16_f32 v105, v100, v100
	v_cvt_pk_bf16_f32 v100, v102, v102
	v_fmac_f32_e32 v101, v103, v103
	v_fmac_f32_e32 v104, 0.5, v109
	global_store_short v[98:99], v100, off offset:32
	v_cvt_pk_bf16_f32 v100, v103, v103
	v_fmac_f32_e32 v101, v104, v104
	global_store_short v[98:99], v105, off
	global_store_short v[98:99], v100, off offset:256
	v_cvt_pk_bf16_f32 v100, v104, v104
	global_store_short v[98:99], v100, off offset:288
	v_add_f32_dpp v98, v101, v101 quad_perm:[1,0,3,2] row_mask:0xf bank_mask:0xf bound_ctrl:1
	v_mov_b32_e32 v99, 0
	s_nop 0
	v_add_f32_dpp v98, v98, v98 quad_perm:[2,3,0,1] row_mask:0xf bank_mask:0xf bound_ctrl:1
	s_nop 1
	v_add_f32_dpp v98, v98, v98 row_half_mirror row_mask:0xf bank_mask:0xf bound_ctrl:1
	s_nop 1
	v_mov_b32_dpp v99, v98 row_mirror row_mask:0xf bank_mask:0xf
	s_and_saveexec_b64 s[14:15], vcc
	s_cbranch_execz .LBB0_1126
	v_add_f32_e32 v100, v98, v99
	v_lshlrev_b64 v[98:99], 6, v[140:141]
	v_lshl_add_u64 v[98:99], v[132:133], 0, v[98:99]
	global_store_dword v[98:99], v100, off
; __device__ __forceinline__ unsigned f2bf(float f) { return pk2(f, f) & 0xffffu; }
; template <int K, int LD>
; __device__ __forceinline__ void phase_resid(int mode) {
;     ...
; #pragma unroll
;       for (int m2 = 0; m2 < 2; ++m2)
; #pragma unroll
;         for (int j = 0; j < 4; ++j)
; #pragma unroll
;           for (int bj = 0; bj < 2; ++bj)
; #pragma unroll
;             for (int n = 0; n < 2; ++n) {
;               const size_t idx = (size_t)(brow + ai * 128 + wr * 64 + (mh * 2 + m2) * 16 + fq * 4 + j) * DM + bcol + bj * 128 + wc * 32 + n * 16 + fr;
;               xo[m2][j][bj][n] = (mode == 0) ? xin[idx] : bf2f(xg[idx]);
;             }
; #pragma unroll
;       for (int m2 = 0; m2 < 2; ++m2)
; #pragma unroll
;         for (int j = 0; j < 4; ++j) {
;           const int m = mh * 2 + m2; const int row = brow + ai * 128 + wr * 64 + m * 16 + fq * 4 + j;
;           float ss = 0.f;
; #pragma unroll
;           for (int bj = 0; bj < 2; ++bj)
; #pragma unroll
;             for (int n = 0; n < 2; ++n) {
;               const size_t idx = (size_t)row * DM + bcol + bj * 128 + wc * 32 + n * 16 + fr;
;               const float xn = xo[m2][j][bj][n] + scale * acc[ai][bj][m][n][j];
;               ss += xn * xn;
;               xg[idx] = (unsigned short)f2bf(xn);
;             }
;           ss = sum16(ss);
;           if (fr == 0) ssq[(size_t)row * 16 + pn0 * 4 + wc] = ss;
;         }
.LBB0_1126:
	s_or_b64 exec, exec, s[14:15]
	v_or_b32_e32 v124, 32, v136
	v_or_b32_e32 v120, 33, v136
	v_ashrrev_i32_e32 v125, 31, v124
	v_ashrrev_i32_e32 v121, 31, v120
	v_lshlrev_b64 v[164:165], 11, v[124:125]
	v_lshlrev_b64 v[126:127], 11, v[120:121]
	v_or_b32_e32 v116, 34, v136
	v_or_b32_e32 v112, 35, v136
	v_lshl_add_u64 v[98:99], s[4:5], 0, v[164:165]
	v_lshl_add_u64 v[100:101], s[4:5], 0, v[126:127]
	v_ashrrev_i32_e32 v117, 31, v116
	v_ashrrev_i32_e32 v113, 31, v112
	v_lshl_add_u64 v[98:99], v[98:99], 0, v[138:139]
	v_lshl_add_u64 v[100:101], v[100:101], 0, v[138:139]
	v_lshlrev_b64 v[122:123], 11, v[116:117]
	v_lshlrev_b64 v[118:119], 11, v[112:113]
	v_or_b32_e32 v108, 48, v136
	v_or_b32_e32 v104, 49, v136
	global_load_ushort v168, v[98:99], off
	global_load_ushort v169, v[98:99], off offset:32
	global_load_ushort v174, v[98:99], off offset:256
	global_load_ushort v175, v[98:99], off offset:288
	global_load_ushort v160, v[100:101], off
	global_load_ushort v161, v[100:101], off offset:32
	global_load_ushort v162, v[100:101], off offset:256
	global_load_ushort v163, v[100:101], off offset:288
	v_lshl_add_u64 v[98:99], s[4:5], 0, v[122:123]
	v_lshl_add_u64 v[100:101], s[4:5], 0, v[118:119]
	v_ashrrev_i32_e32 v109, 31, v108
	v_ashrrev_i32_e32 v105, 31, v104
	v_lshl_add_u64 v[98:99], v[98:99], 0, v[138:139]
	v_lshl_add_u64 v[100:101], v[100:101], 0, v[138:139]
	v_lshlrev_b64 v[114:115], 11, v[108:109]
	v_lshlrev_b64 v[110:111], 11, v[104:105]
	global_load_ushort v156, v[98:99], off
	global_load_ushort v157, v[98:99], off offset:32
	global_load_ushort v158, v[98:99], off offset:256
	global_load_ushort v159, v[98:99], off offset:288
	global_load_ushort v152, v[100:101], off
	global_load_ushort v153, v[100:101], off offset:32
	global_load_ushort v154, v[100:101], off offset:256
	global_load_ushort v155, v[100:101], off offset:288
	v_lshl_add_u64 v[98:99], s[4:5], 0, v[114:115]
	v_lshl_add_u64 v[100:101], s[4:5], 0, v[110:111]
	v_lshl_add_u64 v[98:99], v[98:99], 0, v[138:139]
	v_lshl_add_u64 v[100:101], v[100:101], 0, v[138:139]
	global_load_ushort v148, v[98:99], off
	global_load_ushort v149, v[98:99], off offset:32
	global_load_ushort v150, v[98:99], off offset:256
	global_load_ushort v151, v[98:99], off offset:288
	global_load_ushort v144, v[100:101], off
	global_load_ushort v145, v[100:101], off offset:32
	global_load_ushort v146, v[100:101], off offset:256
	global_load_ushort v147, v[100:101], off offset:288
	v_or_b32_e32 v100, 50, v136
	v_ashrrev_i32_e32 v101, 31, v100
	v_lshlrev_b64 v[106:107], 11, v[100:101]
	v_lshl_add_u64 v[98:99], s[4:5], 0, v[106:107]
	v_lshl_add_u64 v[128:129], v[98:99], 0, v[138:139]
	v_or_b32_e32 v98, 51, v136
	v_ashrrev_i32_e32 v99, 31, v98
	v_lshlrev_b64 v[102:103], 11, v[98:99]
	v_lshl_add_u64 v[140:141], s[4:5], 0, v[102:103]
	v_lshl_add_u64 v[166:167], v[140:141], 0, v[138:139]
	global_load_ushort v140, v[128:129], off
	global_load_ushort v141, v[128:129], off offset:32
	global_load_ushort v142, v[128:129], off offset:256
	global_load_ushort v143, v[128:129], off offset:288
	s_nop 0
	global_load_ushort v128, v[166:167], off
	global_load_ushort v129, v[166:167], off offset:32
	global_load_ushort v130, v[166:167], off offset:256
	global_load_ushort v137, v[166:167], off offset:288
	v_lshl_add_u64 v[164:165], v[134:135], 0, v[164:165]
	s_waitcnt vmcnt(0)
	v_lshlrev_b32_e32 v166, 16, v168
	v_lshlrev_b32_e32 v167, 16, v169
	v_fmac_f32_e32 v167, 0.5, v82
	v_lshlrev_b32_e32 v168, 16, v174
	v_fmac_f32_e32 v166, 0.5, v86
	v_mul_f32_e32 v86, v167, v167
	v_lshlrev_b32_e32 v169, 16, v175
	v_fmac_f32_e32 v168, 0.5, v94
	v_fmac_f32_e32 v86, v166, v166
	v_fmac_f32_e32 v169, 0.5, v90
	v_cvt_pk_bf16_f32 v82, v166, v166
	v_fmac_f32_e32 v86, v168, v168
	v_cvt_pk_bf16_f32 v90, v167, v167
	global_store_short v[164:165], v82, off
	v_fmac_f32_e32 v86, v169, v169
	v_cvt_pk_bf16_f32 v82, v169, v169
	v_cvt_pk_bf16_f32 v94, v168, v168
	global_store_short v[164:165], v90, off offset:32
	global_store_short v[164:165], v94, off offset:256
	global_store_short v[164:165], v82, off offset:288
	v_add_f32_dpp v82, v86, v86 quad_perm:[1,0,3,2] row_mask:0xf bank_mask:0xf bound_ctrl:1
	v_mov_b32_e32 v86, 0
	s_nop 0
	v_add_f32_dpp v82, v82, v82 quad_perm:[2,3,0,1] row_mask:0xf bank_mask:0xf bound_ctrl:1
	s_nop 1
	v_add_f32_dpp v82, v82, v82 row_half_mirror row_mask:0xf bank_mask:0xf bound_ctrl:1
	s_nop 1
	v_mov_b32_dpp v86, v82 row_mirror row_mask:0xf bank_mask:0xf
	s_and_saveexec_b64 s[14:15], vcc
	s_cbranch_execz .LBB0_1128
	v_lshlrev_b64 v[124:125], 6, v[124:125]
	v_add_f32_e32 v82, v82, v86
	v_lshl_add_u64 v[124:125], v[132:133], 0, v[124:125]
	global_store_dword v[124:125], v82, off
.LBB0_1128:
	s_or_b64 exec, exec, s[14:15]
	v_lshlrev_b32_e32 v86, 16, v161
	v_lshlrev_b32_e32 v82, 16, v160
	v_fmac_f32_e32 v86, 0.5, v83
	v_lshlrev_b32_e32 v90, 16, v162
	v_fmac_f32_e32 v82, 0.5, v87
	v_mul_f32_e32 v83, v86, v86
	v_lshlrev_b32_e32 v94, 16, v163
	v_lshl_add_u64 v[124:125], v[134:135], 0, v[126:127]
	v_cvt_pk_bf16_f32 v87, v82, v82
	v_fmac_f32_e32 v83, v82, v82
	v_cvt_pk_bf16_f32 v82, v86, v86
	v_fmac_f32_e32 v90, 0.5, v95
	global_store_short v[124:125], v82, off offset:32
	v_fmac_f32_e32 v83, v90, v90
	v_cvt_pk_bf16_f32 v82, v90, v90
	v_fmac_f32_e32 v94, 0.5, v91
	global_store_short v[124:125], v82, off offset:256
	v_fmac_f32_e32 v83, v94, v94
	v_cvt_pk_bf16_f32 v82, v94, v94
	global_store_short v[124:125], v82, off offset:288
	global_store_short v[124:125], v87, off
	v_add_f32_dpp v82, v83, v83 quad_perm:[1,0,3,2] row_mask:0xf bank_mask:0xf bound_ctrl:1
	v_mov_b32_e32 v83, 0
	s_nop 0
	v_add_f32_dpp v82, v82, v82 quad_perm:[2,3,0,1] row_mask:0xf bank_mask:0xf bound_ctrl:1
	s_nop 1
	v_add_f32_dpp v82, v82, v82 row_half_mirror row_mask:0xf bank_mask:0xf bound_ctrl:1
	s_nop 1
	v_mov_b32_dpp v83, v82 row_mirror row_mask:0xf bank_mask:0xf
	s_and_saveexec_b64 s[14:15], vcc
	s_cbranch_execz .LBB0_1130
	v_add_f32_e32 v86, v82, v83
	v_lshlrev_b64 v[82:83], 6, v[120:121]
	v_lshl_add_u64 v[82:83], v[132:133], 0, v[82:83]
	global_store_dword v[82:83], v86, off
; __device__ __forceinline__ unsigned f2bf(float f) { return pk2(f, f) & 0xffffu; }
; template <int K, int LD>
; __device__ __forceinline__ void phase_resid(int mode) {
;     ...
;       for (int m2 = 0; m2 < 2; ++m2)
; #pragma unroll
;         for (int j = 0; j < 4; ++j) {
;           const int m = mh * 2 + m2; const int row = brow + ai * 128 + wr * 64 + m * 16 + fq * 4 + j;
;           float ss = 0.f;
; #pragma unroll
;           for (int bj = 0; bj < 2; ++bj)
; #pragma unroll
;             for (int n = 0; n < 2; ++n) {
;               const size_t idx = (size_t)row * DM + bcol + bj * 128 + wc * 32 + n * 16 + fr;
;               const float xn = xo[m2][j][bj][n] + scale * acc[ai][bj][m][n][j];
;               ss += xn * xn;
;               xg[idx] = (unsigned short)f2bf(xn);
;             }
;           ss = sum16(ss);
;           if (fr == 0) ssq[(size_t)row * 16 + pn0 * 4 + wc] = ss;
;         }
.LBB0_1130:
	s_or_b64 exec, exec, s[14:15]
	v_lshlrev_b32_e32 v87, 16, v157
	v_lshlrev_b32_e32 v86, 16, v156
	v_fmac_f32_e32 v87, 0.5, v84
	v_lshlrev_b32_e32 v90, 16, v158
	v_fmac_f32_e32 v86, 0.5, v88
	v_mul_f32_e32 v84, v87, v87
	v_lshlrev_b32_e32 v91, 16, v159
	v_fmac_f32_e32 v84, v86, v86
	v_fmac_f32_e32 v90, 0.5, v96
	v_lshl_add_u64 v[82:83], v[134:135], 0, v[122:123]
	v_cvt_pk_bf16_f32 v88, v86, v86
	v_cvt_pk_bf16_f32 v86, v87, v87
	v_fmac_f32_e32 v84, v90, v90
	v_fmac_f32_e32 v91, 0.5, v92
	global_store_short v[82:83], v86, off offset:32
	v_cvt_pk_bf16_f32 v86, v90, v90
	v_fmac_f32_e32 v84, v91, v91
	global_store_short v[82:83], v88, off
	global_store_short v[82:83], v86, off offset:256
	v_cvt_pk_bf16_f32 v86, v91, v91
	global_store_short v[82:83], v86, off offset:288
	v_add_f32_dpp v82, v84, v84 quad_perm:[1,0,3,2] row_mask:0xf bank_mask:0xf bound_ctrl:1
	v_mov_b32_e32 v83, 0
	s_nop 0
	v_add_f32_dpp v82, v82, v82 quad_perm:[2,3,0,1] row_mask:0xf bank_mask:0xf bound_ctrl:1
	s_nop 1
	v_add_f32_dpp v82, v82, v82 row_half_mirror row_mask:0xf bank_mask:0xf bound_ctrl:1
	s_nop 1
	v_mov_b32_dpp v83, v82 row_mirror row_mask:0xf bank_mask:0xf
	s_and_saveexec_b64 s[14:15], vcc
	s_cbranch_execz .LBB0_1132
	v_add_f32_e32 v84, v82, v83
	v_lshlrev_b64 v[82:83], 6, v[116:117]
	v_lshl_add_u64 v[82:83], v[132:133], 0, v[82:83]
	global_store_dword v[82:83], v84, off
.LBB0_1132:
	s_or_b64 exec, exec, s[14:15]
	v_lshlrev_b32_e32 v86, 16, v153
	v_lshlrev_b32_e32 v84, 16, v152
	v_fmac_f32_e32 v86, 0.5, v85
	v_lshlrev_b32_e32 v87, 16, v154
	v_fmac_f32_e32 v84, 0.5, v89
	v_mul_f32_e32 v85, v86, v86
	v_lshlrev_b32_e32 v88, 16, v155
	v_fmac_f32_e32 v85, v84, v84
	v_fmac_f32_e32 v87, 0.5, v97
	v_lshl_add_u64 v[82:83], v[134:135], 0, v[118:119]
	v_cvt_pk_bf16_f32 v89, v84, v84
	v_cvt_pk_bf16_f32 v84, v86, v86
	v_fmac_f32_e32 v85, v87, v87
	v_fmac_f32_e32 v88, 0.5, v93
	global_store_short v[82:83], v84, off offset:32
	v_cvt_pk_bf16_f32 v84, v87, v87
	v_fmac_f32_e32 v85, v88, v88
	global_store_short v[82:83], v89, off
	global_store_short v[82:83], v84, off offset:256
	v_cvt_pk_bf16_f32 v84, v88, v88
	global_store_short v[82:83], v84, off offset:288
	v_add_f32_dpp v82, v85, v85 quad_perm:[1,0,3,2] row_mask:0xf bank_mask:0xf bound_ctrl:1
	v_mov_b32_e32 v83, 0
	s_nop 0
	v_add_f32_dpp v82, v82, v82 quad_perm:[2,3,0,1] row_mask:0xf bank_mask:0xf bound_ctrl:1
	s_nop 1
	v_add_f32_dpp v82, v82, v82 row_half_mirror row_mask:0xf bank_mask:0xf bound_ctrl:1
	s_nop 1
	v_mov_b32_dpp v83, v82 row_mirror row_mask:0xf bank_mask:0xf
	s_and_saveexec_b64 s[14:15], vcc
	s_cbranch_execz .LBB0_1134
	v_add_f32_e32 v84, v82, v83
	v_lshlrev_b64 v[82:83], 6, v[112:113]
	v_lshl_add_u64 v[82:83], v[132:133], 0, v[82:83]
	global_store_dword v[82:83], v84, off
.LBB0_1134:
	s_or_b64 exec, exec, s[14:15]
	v_lshlrev_b32_e32 v85, 16, v149
	v_lshlrev_b32_e32 v84, 16, v148
	v_fmac_f32_e32 v85, 0.5, v66
	v_lshlrev_b32_e32 v86, 16, v150
	v_fmac_f32_e32 v84, 0.5, v70
	v_mul_f32_e32 v66, v85, v85
	v_lshlrev_b32_e32 v87, 16, v151
	v_fmac_f32_e32 v66, v84, v84
	v_fmac_f32_e32 v86, 0.5, v78
	v_lshl_add_u64 v[82:83], v[134:135], 0, v[114:115]
	v_cvt_pk_bf16_f32 v70, v84, v84
	v_fmac_f32_e32 v66, v86, v86
	v_fmac_f32_e32 v87, 0.5, v74
	global_store_short v[82:83], v70, off
	v_cvt_pk_bf16_f32 v70, v85, v85
	v_fmac_f32_e32 v66, v87, v87
	global_store_short v[82:83], v70, off offset:32
	v_cvt_pk_bf16_f32 v70, v86, v86
	global_store_short v[82:83], v70, off offset:256
	v_add_f32_dpp v66, v66, v66 quad_perm:[1,0,3,2] row_mask:0xf bank_mask:0xf bound_ctrl:1
	v_cvt_pk_bf16_f32 v70, v87, v87
	global_store_short v[82:83], v70, off offset:288
	v_mov_b32_e32 v70, 0
	v_add_f32_dpp v66, v66, v66 quad_perm:[2,3,0,1] row_mask:0xf bank_mask:0xf bound_ctrl:1
	s_nop 1
	v_add_f32_dpp v66, v66, v66 row_half_mirror row_mask:0xf bank_mask:0xf bound_ctrl:1
	s_nop 1
	v_mov_b32_dpp v70, v66 row_mirror row_mask:0xf bank_mask:0xf
	s_and_saveexec_b64 s[14:15], vcc
	s_cbranch_execz .LBB0_1136
	v_lshlrev_b64 v[82:83], 6, v[108:109]
	v_add_f32_e32 v66, v66, v70
	v_lshl_add_u64 v[82:83], v[132:133], 0, v[82:83]
	global_store_dword v[82:83], v66, off
.LBB0_1136:
	s_or_b64 exec, exec, s[14:15]
	v_lshlrev_b32_e32 v70, 16, v145
	v_lshlrev_b32_e32 v66, 16, v144
	v_fmac_f32_e32 v70, 0.5, v67
	v_lshlrev_b32_e32 v74, 16, v146
	v_fmac_f32_e32 v66, 0.5, v71
	v_mul_f32_e32 v67, v70, v70
	v_lshlrev_b32_e32 v78, 16, v147
	v_lshl_add_u64 v[82:83], v[134:135], 0, v[110:111]
	v_cvt_pk_bf16_f32 v71, v66, v66
	v_fmac_f32_e32 v67, v66, v66
	v_cvt_pk_bf16_f32 v66, v70, v70
	v_fmac_f32_e32 v74, 0.5, v79
	global_store_short v[82:83], v66, off offset:32
	v_fmac_f32_e32 v67, v74, v74
	v_cvt_pk_bf16_f32 v66, v74, v74
	v_fmac_f32_e32 v78, 0.5, v75
	global_store_short v[82:83], v66, off offset:256
	v_fmac_f32_e32 v67, v78, v78
	v_cvt_pk_bf16_f32 v66, v78, v78
	global_store_short v[82:83], v66, off offset:288
	global_store_short v[82:83], v71, off
	v_add_f32_dpp v66, v67, v67 quad_perm:[1,0,3,2] row_mask:0xf bank_mask:0xf bound_ctrl:1
	v_mov_b32_e32 v67, 0
	s_nop 0
	v_add_f32_dpp v66, v66, v66 quad_perm:[2,3,0,1] row_mask:0xf bank_mask:0xf bound_ctrl:1
	s_nop 1
	v_add_f32_dpp v66, v66, v66 row_half_mirror row_mask:0xf bank_mask:0xf bound_ctrl:1
	s_nop 1
	v_mov_b32_dpp v67, v66 row_mirror row_mask:0xf bank_mask:0xf
	s_and_saveexec_b64 s[14:15], vcc
	s_cbranch_execz .LBB0_1138
	v_add_f32_e32 v70, v66, v67
	v_lshlrev_b64 v[66:67], 6, v[104:105]
	v_lshl_add_u64 v[66:67], v[132:133], 0, v[66:67]
	global_store_dword v[66:67], v70, off
; __device__ __forceinline__ unsigned f2bf(float f) { return pk2(f, f) & 0xffffu; }
; template <int K, int LD>
; __device__ __forceinline__ void phase_resid(int mode) {
;     ...
; #pragma unroll
;     for (int ai = 0; ai < 2; ++ai)
; #pragma unroll
;     for (int mh = 0; mh < 2; ++mh) {
;       float xo[2][4][2][2];
; #pragma unroll
;       for (int m2 = 0; m2 < 2; ++m2)
; #pragma unroll
;         for (int j = 0; j < 4; ++j)
; #pragma unroll
;           for (int bj = 0; bj < 2; ++bj)
; #pragma unroll
;             for (int n = 0; n < 2; ++n) {
;               const size_t idx = (size_t)(brow + ai * 128 + wr * 64 + (mh * 2 + m2) * 16 + fq * 4 + j) * DM + bcol + bj * 128 + wc * 32 + n * 16 + fr;
;               xo[m2][j][bj][n] = (mode == 0) ? xin[idx] : bf2f(xg[idx]);
;             }
; #pragma unroll
;       for (int m2 = 0; m2 < 2; ++m2)
; #pragma unroll
;         for (int j = 0; j < 4; ++j) {
;           const int m = mh * 2 + m2; const int row = brow + ai * 128 + wr * 64 + m * 16 + fq * 4 + j;
;           float ss = 0.f;
; #pragma unroll
;           for (int bj = 0; bj < 2; ++bj)
; #pragma unroll
;             for (int n = 0; n < 2; ++n) {
;               const size_t idx = (size_t)row * DM + bcol + bj * 128 + wc * 32 + n * 16 + fr;
;               const float xn = xo[m2][j][bj][n] + scale * acc[ai][bj][m][n][j];
;               ss += xn * xn;
;               xg[idx] = (unsigned short)f2bf(xn);
;             }
;           ss = sum16(ss);
;           if (fr == 0) ssq[(size_t)row * 16 + pn0 * 4 + wc] = ss;
;         }
;     }
.LBB0_1138:
	s_or_b64 exec, exec, s[14:15]
	v_lshlrev_b32_e32 v71, 16, v141
	v_lshlrev_b32_e32 v70, 16, v140
	v_fmac_f32_e32 v71, 0.5, v68
	v_lshlrev_b32_e32 v74, 16, v142
	v_fmac_f32_e32 v70, 0.5, v72
	v_mul_f32_e32 v68, v71, v71
	v_lshlrev_b32_e32 v75, 16, v143
	v_fmac_f32_e32 v68, v70, v70
	v_fmac_f32_e32 v74, 0.5, v80
	v_lshl_add_u64 v[66:67], v[134:135], 0, v[106:107]
	v_cvt_pk_bf16_f32 v72, v70, v70
	v_cvt_pk_bf16_f32 v70, v71, v71
	v_fmac_f32_e32 v68, v74, v74
	v_fmac_f32_e32 v75, 0.5, v76
	global_store_short v[66:67], v70, off offset:32
	v_cvt_pk_bf16_f32 v70, v74, v74
	v_fmac_f32_e32 v68, v75, v75
	global_store_short v[66:67], v72, off
	global_store_short v[66:67], v70, off offset:256
	v_cvt_pk_bf16_f32 v70, v75, v75
	global_store_short v[66:67], v70, off offset:288
	v_add_f32_dpp v66, v68, v68 quad_perm:[1,0,3,2] row_mask:0xf bank_mask:0xf bound_ctrl:1
	v_mov_b32_e32 v67, 0
	s_nop 0
	v_add_f32_dpp v66, v66, v66 quad_perm:[2,3,0,1] row_mask:0xf bank_mask:0xf bound_ctrl:1
	s_nop 1
	v_add_f32_dpp v66, v66, v66 row_half_mirror row_mask:0xf bank_mask:0xf bound_ctrl:1
	s_nop 1
	v_mov_b32_dpp v67, v66 row_mirror row_mask:0xf bank_mask:0xf
	s_and_saveexec_b64 s[14:15], vcc
	s_cbranch_execz .LBB0_1140
	v_add_f32_e32 v68, v66, v67
	v_lshlrev_b64 v[66:67], 6, v[100:101]
	v_lshl_add_u64 v[66:67], v[132:133], 0, v[66:67]
	global_store_dword v[66:67], v68, off
.LBB0_1140:
	s_or_b64 exec, exec, s[14:15]
	v_lshlrev_b32_e32 v70, 16, v129
	v_lshlrev_b32_e32 v68, 16, v128
	v_fmac_f32_e32 v70, 0.5, v69
	v_lshlrev_b32_e32 v71, 16, v130
	v_fmac_f32_e32 v68, 0.5, v73
	v_mul_f32_e32 v69, v70, v70
	v_lshlrev_b32_e32 v72, 16, v137
	v_fmac_f32_e32 v69, v68, v68
	v_fmac_f32_e32 v71, 0.5, v81
	v_lshl_add_u64 v[66:67], v[134:135], 0, v[102:103]
	v_cvt_pk_bf16_f32 v73, v68, v68
	v_cvt_pk_bf16_f32 v68, v70, v70
	v_fmac_f32_e32 v69, v71, v71
	v_fmac_f32_e32 v72, 0.5, v77
	global_store_short v[66:67], v68, off offset:32
	v_cvt_pk_bf16_f32 v68, v71, v71
	v_fmac_f32_e32 v69, v72, v72
	global_store_short v[66:67], v73, off
	global_store_short v[66:67], v68, off offset:256
	v_cvt_pk_bf16_f32 v68, v72, v72
	global_store_short v[66:67], v68, off offset:288
	v_add_f32_dpp v66, v69, v69 quad_perm:[1,0,3,2] row_mask:0xf bank_mask:0xf bound_ctrl:1
	v_mov_b32_e32 v67, 0
	s_nop 0
	v_add_f32_dpp v66, v66, v66 quad_perm:[2,3,0,1] row_mask:0xf bank_mask:0xf bound_ctrl:1
	s_nop 1
	v_add_f32_dpp v66, v66, v66 row_half_mirror row_mask:0xf bank_mask:0xf bound_ctrl:1
	s_nop 1
	v_mov_b32_dpp v67, v66 row_mirror row_mask:0xf bank_mask:0xf
	s_and_saveexec_b64 s[14:15], vcc
	s_cbranch_execz .LBB0_1142
	v_add_f32_e32 v68, v66, v67
	v_lshlrev_b64 v[66:67], 6, v[98:99]
	v_lshl_add_u64 v[66:67], v[132:133], 0, v[66:67]
	global_store_dword v[66:67], v68, off
.LBB0_1142:
	s_or_b64 exec, exec, s[14:15]
	v_add_u32_e32 v92, 0x80, v136
	v_add_u32_e32 v88, 0x81, v136
	v_ashrrev_i32_e32 v93, 31, v92
	v_ashrrev_i32_e32 v89, 31, v88
	v_lshlrev_b64 v[124:125], 11, v[92:93]
	v_lshlrev_b64 v[94:95], 11, v[88:89]
	v_add_u32_e32 v84, 0x82, v136
	v_add_u32_e32 v80, 0x83, v136
	v_lshl_add_u64 v[66:67], s[4:5], 0, v[124:125]
	v_lshl_add_u64 v[68:69], s[4:5], 0, v[94:95]
	v_ashrrev_i32_e32 v85, 31, v84
	v_ashrrev_i32_e32 v81, 31, v80
	v_lshl_add_u64 v[66:67], v[66:67], 0, v[138:139]
	v_lshl_add_u64 v[68:69], v[68:69], 0, v[138:139]
	v_lshlrev_b64 v[90:91], 11, v[84:85]
	v_lshlrev_b64 v[86:87], 11, v[80:81]
	v_add_u32_e32 v76, 0x90, v136
	v_add_u32_e32 v72, 0x91, v136
	global_load_ushort v128, v[66:67], off
	global_load_ushort v129, v[66:67], off offset:32
	global_load_ushort v130, v[66:67], off offset:256
	global_load_ushort v137, v[66:67], off offset:288
	global_load_ushort v120, v[68:69], off
	global_load_ushort v121, v[68:69], off offset:32
	global_load_ushort v122, v[68:69], off offset:256
	global_load_ushort v123, v[68:69], off offset:288
	v_lshl_add_u64 v[66:67], s[4:5], 0, v[90:91]
	v_lshl_add_u64 v[68:69], s[4:5], 0, v[86:87]
	v_ashrrev_i32_e32 v77, 31, v76
	v_ashrrev_i32_e32 v73, 31, v72
	v_lshl_add_u64 v[66:67], v[66:67], 0, v[138:139]
	v_lshl_add_u64 v[68:69], v[68:69], 0, v[138:139]
	v_lshlrev_b64 v[82:83], 11, v[76:77]
	v_lshlrev_b64 v[78:79], 11, v[72:73]
	global_load_ushort v116, v[66:67], off
	global_load_ushort v117, v[66:67], off offset:32
	global_load_ushort v118, v[66:67], off offset:256
	global_load_ushort v119, v[66:67], off offset:288
	global_load_ushort v112, v[68:69], off
	global_load_ushort v113, v[68:69], off offset:32
	global_load_ushort v114, v[68:69], off offset:256
	global_load_ushort v115, v[68:69], off offset:288
	v_lshl_add_u64 v[66:67], s[4:5], 0, v[82:83]
	v_lshl_add_u64 v[68:69], s[4:5], 0, v[78:79]
	v_lshl_add_u64 v[66:67], v[66:67], 0, v[138:139]
	v_lshl_add_u64 v[68:69], v[68:69], 0, v[138:139]
	global_load_ushort v108, v[66:67], off
	global_load_ushort v109, v[66:67], off offset:32
	global_load_ushort v110, v[66:67], off offset:256
	global_load_ushort v111, v[66:67], off offset:288
	global_load_ushort v104, v[68:69], off
	global_load_ushort v105, v[68:69], off offset:32
	global_load_ushort v106, v[68:69], off offset:256
	global_load_ushort v107, v[68:69], off offset:288
	v_add_u32_e32 v68, 0x92, v136
	v_ashrrev_i32_e32 v69, 31, v68
	v_lshlrev_b64 v[74:75], 11, v[68:69]
	v_lshl_add_u64 v[66:67], s[4:5], 0, v[74:75]
	v_lshl_add_u64 v[96:97], v[66:67], 0, v[138:139]
	v_add_u32_e32 v66, 0x93, v136
	v_ashrrev_i32_e32 v67, 31, v66
	v_lshlrev_b64 v[70:71], 11, v[66:67]
	v_lshl_add_u64 v[98:99], s[4:5], 0, v[70:71]
	v_lshl_add_u64 v[126:127], v[98:99], 0, v[138:139]
	global_load_ushort v100, v[96:97], off
	global_load_ushort v101, v[96:97], off offset:32
	global_load_ushort v102, v[96:97], off offset:256
	global_load_ushort v103, v[96:97], off offset:288
	s_nop 0
	global_load_ushort v96, v[126:127], off
	global_load_ushort v97, v[126:127], off offset:32
	global_load_ushort v98, v[126:127], off offset:256
	global_load_ushort v99, v[126:127], off offset:288
	v_lshl_add_u64 v[124:125], v[134:135], 0, v[124:125]
	s_waitcnt vmcnt(0)
; __device__ __forceinline__ unsigned f2bf(float f) { return pk2(f, f) & 0xffffu; }
; template <int K, int LD>
; __device__ __forceinline__ void phase_resid(int mode) {
;     ...
; #pragma unroll
;       for (int m2 = 0; m2 < 2; ++m2)
; #pragma unroll
;         for (int j = 0; j < 4; ++j) {
;           const int m = mh * 2 + m2; const int row = brow + ai * 128 + wr * 64 + m * 16 + fq * 4 + j;
;           float ss = 0.f;
; #pragma unroll
;           for (int bj = 0; bj < 2; ++bj)
; #pragma unroll
;             for (int n = 0; n < 2; ++n) {
;               const size_t idx = (size_t)row * DM + bcol + bj * 128 + wc * 32 + n * 16 + fr;
;               const float xn = xo[m2][j][bj][n] + scale * acc[ai][bj][m][n][j];
;               ss += xn * xn;
;               xg[idx] = (unsigned short)f2bf(xn);
;             }
;           ss = sum16(ss);
;           if (fr == 0) ssq[(size_t)row * 16 + pn0 * 4 + wc] = ss;
;         }
;     }
	v_lshlrev_b32_e32 v126, 16, v128
	v_lshlrev_b32_e32 v127, 16, v129
	v_fmac_f32_e32 v127, 0.5, v50
	v_lshlrev_b32_e32 v128, 16, v130
	v_fmac_f32_e32 v126, 0.5, v54
	v_mul_f32_e32 v54, v127, v127
	v_lshlrev_b32_e32 v129, 16, v137
	v_fmac_f32_e32 v128, 0.5, v62
	v_fmac_f32_e32 v54, v126, v126
	v_fmac_f32_e32 v129, 0.5, v58
	v_cvt_pk_bf16_f32 v50, v126, v126
	v_fmac_f32_e32 v54, v128, v128
	v_cvt_pk_bf16_f32 v58, v127, v127
	global_store_short v[124:125], v50, off
	v_fmac_f32_e32 v54, v129, v129
	v_cvt_pk_bf16_f32 v50, v129, v129
	v_cvt_pk_bf16_f32 v62, v128, v128
	global_store_short v[124:125], v58, off offset:32
	global_store_short v[124:125], v62, off offset:256
	global_store_short v[124:125], v50, off offset:288
	v_add_f32_dpp v50, v54, v54 quad_perm:[1,0,3,2] row_mask:0xf bank_mask:0xf bound_ctrl:1
	v_mov_b32_e32 v54, 0
	s_nop 0
	v_add_f32_dpp v50, v50, v50 quad_perm:[2,3,0,1] row_mask:0xf bank_mask:0xf bound_ctrl:1
	s_nop 1
	v_add_f32_dpp v50, v50, v50 row_half_mirror row_mask:0xf bank_mask:0xf bound_ctrl:1
	s_nop 1
	v_mov_b32_dpp v54, v50 row_mirror row_mask:0xf bank_mask:0xf
	s_and_saveexec_b64 s[14:15], vcc
	s_cbranch_execz .LBB0_1144
	v_lshlrev_b64 v[92:93], 6, v[92:93]
	v_add_f32_e32 v50, v50, v54
	v_lshl_add_u64 v[92:93], v[132:133], 0, v[92:93]
	global_store_dword v[92:93], v50, off
.LBB0_1144:
	s_or_b64 exec, exec, s[14:15]
	v_lshlrev_b32_e32 v54, 16, v121
	v_lshlrev_b32_e32 v50, 16, v120
	v_fmac_f32_e32 v54, 0.5, v51
	v_lshlrev_b32_e32 v58, 16, v122
	v_fmac_f32_e32 v50, 0.5, v55
	v_mul_f32_e32 v51, v54, v54
	v_lshlrev_b32_e32 v62, 16, v123
	v_lshl_add_u64 v[92:93], v[134:135], 0, v[94:95]
	v_cvt_pk_bf16_f32 v55, v50, v50
	v_fmac_f32_e32 v51, v50, v50
	v_cvt_pk_bf16_f32 v50, v54, v54
	v_fmac_f32_e32 v58, 0.5, v63
	global_store_short v[92:93], v50, off offset:32
	v_fmac_f32_e32 v51, v58, v58
	v_cvt_pk_bf16_f32 v50, v58, v58
	v_fmac_f32_e32 v62, 0.5, v59
	global_store_short v[92:93], v50, off offset:256
	v_fmac_f32_e32 v51, v62, v62
	v_cvt_pk_bf16_f32 v50, v62, v62
	global_store_short v[92:93], v50, off offset:288
	global_store_short v[92:93], v55, off
	v_add_f32_dpp v50, v51, v51 quad_perm:[1,0,3,2] row_mask:0xf bank_mask:0xf bound_ctrl:1
	v_mov_b32_e32 v51, 0
	s_nop 0
	v_add_f32_dpp v50, v50, v50 quad_perm:[2,3,0,1] row_mask:0xf bank_mask:0xf bound_ctrl:1
	s_nop 1
	v_add_f32_dpp v50, v50, v50 row_half_mirror row_mask:0xf bank_mask:0xf bound_ctrl:1
	s_nop 1
	v_mov_b32_dpp v51, v50 row_mirror row_mask:0xf bank_mask:0xf
	s_and_saveexec_b64 s[14:15], vcc
	s_cbranch_execz .LBB0_1146
	v_add_f32_e32 v54, v50, v51
	v_lshlrev_b64 v[50:51], 6, v[88:89]
	v_lshl_add_u64 v[50:51], v[132:133], 0, v[50:51]
	global_store_dword v[50:51], v54, off
.LBB0_1146:
	s_or_b64 exec, exec, s[14:15]
	v_lshlrev_b32_e32 v55, 16, v117
	v_lshlrev_b32_e32 v54, 16, v116
	v_fmac_f32_e32 v55, 0.5, v52
	v_lshlrev_b32_e32 v58, 16, v118
	v_fmac_f32_e32 v54, 0.5, v56
	v_mul_f32_e32 v52, v55, v55
	v_lshlrev_b32_e32 v59, 16, v119
	v_fmac_f32_e32 v52, v54, v54
	v_fmac_f32_e32 v58, 0.5, v64
	v_lshl_add_u64 v[50:51], v[134:135], 0, v[90:91]
	v_cvt_pk_bf16_f32 v56, v54, v54
	v_cvt_pk_bf16_f32 v54, v55, v55
	v_fmac_f32_e32 v52, v58, v58
	v_fmac_f32_e32 v59, 0.5, v60
	global_store_short v[50:51], v54, off offset:32
	v_cvt_pk_bf16_f32 v54, v58, v58
	v_fmac_f32_e32 v52, v59, v59
	global_store_short v[50:51], v56, off
	global_store_short v[50:51], v54, off offset:256
	v_cvt_pk_bf16_f32 v54, v59, v59
	global_store_short v[50:51], v54, off offset:288
	v_add_f32_dpp v50, v52, v52 quad_perm:[1,0,3,2] row_mask:0xf bank_mask:0xf bound_ctrl:1
	v_mov_b32_e32 v51, 0
	s_nop 0
	v_add_f32_dpp v50, v50, v50 quad_perm:[2,3,0,1] row_mask:0xf bank_mask:0xf bound_ctrl:1
	s_nop 1
	v_add_f32_dpp v50, v50, v50 row_half_mirror row_mask:0xf bank_mask:0xf bound_ctrl:1
	s_nop 1
	v_mov_b32_dpp v51, v50 row_mirror row_mask:0xf bank_mask:0xf
	s_and_saveexec_b64 s[14:15], vcc
	s_cbranch_execz .LBB0_1148
	v_add_f32_e32 v52, v50, v51
	v_lshlrev_b64 v[50:51], 6, v[84:85]
	v_lshl_add_u64 v[50:51], v[132:133], 0, v[50:51]
	global_store_dword v[50:51], v52, off
.LBB0_1148:
	s_or_b64 exec, exec, s[14:15]
	v_lshlrev_b32_e32 v54, 16, v113
	v_lshlrev_b32_e32 v52, 16, v112
	v_fmac_f32_e32 v54, 0.5, v53
	v_lshlrev_b32_e32 v55, 16, v114
	v_fmac_f32_e32 v52, 0.5, v57
	v_mul_f32_e32 v53, v54, v54
	v_lshlrev_b32_e32 v56, 16, v115
	v_fmac_f32_e32 v53, v52, v52
	v_fmac_f32_e32 v55, 0.5, v65
	v_lshl_add_u64 v[50:51], v[134:135], 0, v[86:87]
	v_cvt_pk_bf16_f32 v57, v52, v52
	v_cvt_pk_bf16_f32 v52, v54, v54
	v_fmac_f32_e32 v53, v55, v55
	v_fmac_f32_e32 v56, 0.5, v61
	global_store_short v[50:51], v52, off offset:32
	v_cvt_pk_bf16_f32 v52, v55, v55
	v_fmac_f32_e32 v53, v56, v56
	global_store_short v[50:51], v57, off
	global_store_short v[50:51], v52, off offset:256
	v_cvt_pk_bf16_f32 v52, v56, v56
	global_store_short v[50:51], v52, off offset:288
	v_add_f32_dpp v50, v53, v53 quad_perm:[1,0,3,2] row_mask:0xf bank_mask:0xf bound_ctrl:1
	v_mov_b32_e32 v51, 0
	s_nop 0
	v_add_f32_dpp v50, v50, v50 quad_perm:[2,3,0,1] row_mask:0xf bank_mask:0xf bound_ctrl:1
	s_nop 1
	v_add_f32_dpp v50, v50, v50 row_half_mirror row_mask:0xf bank_mask:0xf bound_ctrl:1
	s_nop 1
	v_mov_b32_dpp v51, v50 row_mirror row_mask:0xf bank_mask:0xf
	s_and_saveexec_b64 s[14:15], vcc
	s_cbranch_execz .LBB0_1150
	v_add_f32_e32 v52, v50, v51
	v_lshlrev_b64 v[50:51], 6, v[80:81]
	v_lshl_add_u64 v[50:51], v[132:133], 0, v[50:51]
	global_store_dword v[50:51], v52, off
; __device__ __forceinline__ unsigned f2bf(float f) { return pk2(f, f) & 0xffffu; }
; template <int K, int LD>
; __device__ __forceinline__ void phase_resid(int mode) {
;     ...
; #pragma unroll
;       for (int m2 = 0; m2 < 2; ++m2)
; #pragma unroll
;         for (int j = 0; j < 4; ++j) {
;           const int m = mh * 2 + m2; const int row = brow + ai * 128 + wr * 64 + m * 16 + fq * 4 + j;
;           float ss = 0.f;
; #pragma unroll
;           for (int bj = 0; bj < 2; ++bj)
; #pragma unroll
;             for (int n = 0; n < 2; ++n) {
;               const size_t idx = (size_t)row * DM + bcol + bj * 128 + wc * 32 + n * 16 + fr;
;               const float xn = xo[m2][j][bj][n] + scale * acc[ai][bj][m][n][j];
;               ss += xn * xn;
;               xg[idx] = (unsigned short)f2bf(xn);
;             }
;           ss = sum16(ss);
;           if (fr == 0) ssq[(size_t)row * 16 + pn0 * 4 + wc] = ss;
;         }
;     }
.LBB0_1150:
	s_or_b64 exec, exec, s[14:15]
	v_lshlrev_b32_e32 v53, 16, v109
	v_lshlrev_b32_e32 v52, 16, v108
	v_fmac_f32_e32 v53, 0.5, v34
	v_lshlrev_b32_e32 v54, 16, v110
	v_fmac_f32_e32 v52, 0.5, v38
	v_mul_f32_e32 v34, v53, v53
	v_lshlrev_b32_e32 v55, 16, v111
	v_fmac_f32_e32 v34, v52, v52
	v_fmac_f32_e32 v54, 0.5, v46
	v_lshl_add_u64 v[50:51], v[134:135], 0, v[82:83]
	v_cvt_pk_bf16_f32 v38, v52, v52
	v_fmac_f32_e32 v34, v54, v54
	v_fmac_f32_e32 v55, 0.5, v42
	global_store_short v[50:51], v38, off
	v_cvt_pk_bf16_f32 v38, v53, v53
	v_fmac_f32_e32 v34, v55, v55
	global_store_short v[50:51], v38, off offset:32
	v_cvt_pk_bf16_f32 v38, v54, v54
	global_store_short v[50:51], v38, off offset:256
	v_add_f32_dpp v34, v34, v34 quad_perm:[1,0,3,2] row_mask:0xf bank_mask:0xf bound_ctrl:1
	v_cvt_pk_bf16_f32 v38, v55, v55
	global_store_short v[50:51], v38, off offset:288
	v_mov_b32_e32 v38, 0
	v_add_f32_dpp v34, v34, v34 quad_perm:[2,3,0,1] row_mask:0xf bank_mask:0xf bound_ctrl:1
	s_nop 1
	v_add_f32_dpp v34, v34, v34 row_half_mirror row_mask:0xf bank_mask:0xf bound_ctrl:1
	s_nop 1
	v_mov_b32_dpp v38, v34 row_mirror row_mask:0xf bank_mask:0xf
	s_and_saveexec_b64 s[14:15], vcc
	s_cbranch_execz .LBB0_1152
	v_lshlrev_b64 v[50:51], 6, v[76:77]
	v_add_f32_e32 v34, v34, v38
	v_lshl_add_u64 v[50:51], v[132:133], 0, v[50:51]
	global_store_dword v[50:51], v34, off
.LBB0_1152:
	s_or_b64 exec, exec, s[14:15]
	v_lshlrev_b32_e32 v38, 16, v105
	v_lshlrev_b32_e32 v34, 16, v104
	v_fmac_f32_e32 v38, 0.5, v35
	v_lshlrev_b32_e32 v42, 16, v106
	v_fmac_f32_e32 v34, 0.5, v39
	v_mul_f32_e32 v35, v38, v38
	v_lshlrev_b32_e32 v46, 16, v107
	v_lshl_add_u64 v[50:51], v[134:135], 0, v[78:79]
	v_cvt_pk_bf16_f32 v39, v34, v34
	v_fmac_f32_e32 v35, v34, v34
	v_cvt_pk_bf16_f32 v34, v38, v38
	v_fmac_f32_e32 v42, 0.5, v47
	global_store_short v[50:51], v34, off offset:32
	v_fmac_f32_e32 v35, v42, v42
	v_cvt_pk_bf16_f32 v34, v42, v42
	v_fmac_f32_e32 v46, 0.5, v43
	global_store_short v[50:51], v34, off offset:256
	v_fmac_f32_e32 v35, v46, v46
	v_cvt_pk_bf16_f32 v34, v46, v46
	global_store_short v[50:51], v34, off offset:288
	global_store_short v[50:51], v39, off
	v_add_f32_dpp v34, v35, v35 quad_perm:[1,0,3,2] row_mask:0xf bank_mask:0xf bound_ctrl:1
	v_mov_b32_e32 v35, 0
	s_nop 0
	v_add_f32_dpp v34, v34, v34 quad_perm:[2,3,0,1] row_mask:0xf bank_mask:0xf bound_ctrl:1
	s_nop 1
	v_add_f32_dpp v34, v34, v34 row_half_mirror row_mask:0xf bank_mask:0xf bound_ctrl:1
	s_nop 1
	v_mov_b32_dpp v35, v34 row_mirror row_mask:0xf bank_mask:0xf
	s_and_saveexec_b64 s[14:15], vcc
	s_cbranch_execz .LBB0_1154
	v_add_f32_e32 v38, v34, v35
	v_lshlrev_b64 v[34:35], 6, v[72:73]
	v_lshl_add_u64 v[34:35], v[132:133], 0, v[34:35]
	global_store_dword v[34:35], v38, off
.LBB0_1154:
	s_or_b64 exec, exec, s[14:15]
	v_lshlrev_b32_e32 v39, 16, v101
	v_lshlrev_b32_e32 v38, 16, v100
	v_fmac_f32_e32 v39, 0.5, v36
	v_lshlrev_b32_e32 v42, 16, v102
	v_fmac_f32_e32 v38, 0.5, v40
	v_mul_f32_e32 v36, v39, v39
	v_lshlrev_b32_e32 v43, 16, v103
	v_fmac_f32_e32 v36, v38, v38
	v_fmac_f32_e32 v42, 0.5, v48
	v_lshl_add_u64 v[34:35], v[134:135], 0, v[74:75]
	v_cvt_pk_bf16_f32 v40, v38, v38
	v_cvt_pk_bf16_f32 v38, v39, v39
	v_fmac_f32_e32 v36, v42, v42
	v_fmac_f32_e32 v43, 0.5, v44
	global_store_short v[34:35], v38, off offset:32
	v_cvt_pk_bf16_f32 v38, v42, v42
	v_fmac_f32_e32 v36, v43, v43
	global_store_short v[34:35], v40, off
	global_store_short v[34:35], v38, off offset:256
	v_cvt_pk_bf16_f32 v38, v43, v43
	global_store_short v[34:35], v38, off offset:288
	v_add_f32_dpp v34, v36, v36 quad_perm:[1,0,3,2] row_mask:0xf bank_mask:0xf bound_ctrl:1
	v_mov_b32_e32 v35, 0
	s_nop 0
	v_add_f32_dpp v34, v34, v34 quad_perm:[2,3,0,1] row_mask:0xf bank_mask:0xf bound_ctrl:1
	s_nop 1
	v_add_f32_dpp v34, v34, v34 row_half_mirror row_mask:0xf bank_mask:0xf bound_ctrl:1
	s_nop 1
	v_mov_b32_dpp v35, v34 row_mirror row_mask:0xf bank_mask:0xf
	s_and_saveexec_b64 s[14:15], vcc
	s_cbranch_execz .LBB0_1156
	v_add_f32_e32 v36, v34, v35
	v_lshlrev_b64 v[34:35], 6, v[68:69]
	v_lshl_add_u64 v[34:35], v[132:133], 0, v[34:35]
	global_store_dword v[34:35], v36, off
.LBB0_1156:
	s_or_b64 exec, exec, s[14:15]
	v_lshlrev_b32_e32 v38, 16, v97
	v_lshlrev_b32_e32 v36, 16, v96
	v_fmac_f32_e32 v38, 0.5, v37
	v_lshlrev_b32_e32 v39, 16, v98
	v_fmac_f32_e32 v36, 0.5, v41
	v_mul_f32_e32 v37, v38, v38
	v_lshlrev_b32_e32 v40, 16, v99
	v_fmac_f32_e32 v37, v36, v36
	v_fmac_f32_e32 v39, 0.5, v49
	v_lshl_add_u64 v[34:35], v[134:135], 0, v[70:71]
	v_cvt_pk_bf16_f32 v41, v36, v36
	v_cvt_pk_bf16_f32 v36, v38, v38
	v_fmac_f32_e32 v37, v39, v39
	v_fmac_f32_e32 v40, 0.5, v45
	global_store_short v[34:35], v36, off offset:32
	v_cvt_pk_bf16_f32 v36, v39, v39
	v_fmac_f32_e32 v37, v40, v40
	global_store_short v[34:35], v41, off
	global_store_short v[34:35], v36, off offset:256
	v_cvt_pk_bf16_f32 v36, v40, v40
	global_store_short v[34:35], v36, off offset:288
	v_add_f32_dpp v34, v37, v37 quad_perm:[1,0,3,2] row_mask:0xf bank_mask:0xf bound_ctrl:1
	v_mov_b32_e32 v35, 0
	s_nop 0
	v_add_f32_dpp v34, v34, v34 quad_perm:[2,3,0,1] row_mask:0xf bank_mask:0xf bound_ctrl:1
	s_nop 1
	v_add_f32_dpp v34, v34, v34 row_half_mirror row_mask:0xf bank_mask:0xf bound_ctrl:1
	s_nop 1
	v_mov_b32_dpp v35, v34 row_mirror row_mask:0xf bank_mask:0xf
	s_and_saveexec_b64 s[14:15], vcc
	s_cbranch_execz .LBB0_1158
	v_add_f32_e32 v36, v34, v35
	v_lshlrev_b64 v[34:35], 6, v[66:67]
	v_lshl_add_u64 v[34:35], v[132:133], 0, v[34:35]
	global_store_dword v[34:35], v36, off
; __device__ __forceinline__ unsigned f2bf(float f) { return pk2(f, f) & 0xffffu; }
; template <int K, int LD>
; __device__ __forceinline__ void phase_resid(int mode) {
;     ...
;       float xo[2][4][2][2];
; #pragma unroll
;       for (int m2 = 0; m2 < 2; ++m2)
; #pragma unroll
;         for (int j = 0; j < 4; ++j)
; #pragma unroll
;           for (int bj = 0; bj < 2; ++bj)
; #pragma unroll
;             for (int n = 0; n < 2; ++n) {
;               const size_t idx = (size_t)(brow + ai * 128 + wr * 64 + (mh * 2 + m2) * 16 + fq * 4 + j) * DM + bcol + bj * 128 + wc * 32 + n * 16 + fr;
;               xo[m2][j][bj][n] = (mode == 0) ? xin[idx] : bf2f(xg[idx]);
;             }
; #pragma unroll
;       for (int m2 = 0; m2 < 2; ++m2)
; #pragma unroll
;         for (int j = 0; j < 4; ++j) {
;           const int m = mh * 2 + m2; const int row = brow + ai * 128 + wr * 64 + m * 16 + fq * 4 + j;
;           float ss = 0.f;
; #pragma unroll
;           for (int bj = 0; bj < 2; ++bj)
; #pragma unroll
;             for (int n = 0; n < 2; ++n) {
;               const size_t idx = (size_t)row * DM + bcol + bj * 128 + wc * 32 + n * 16 + fr;
;               const float xn = xo[m2][j][bj][n] + scale * acc[ai][bj][m][n][j];
;               ss += xn * xn;
;               xg[idx] = (unsigned short)f2bf(xn);
;             }
;           ss = sum16(ss);
;           if (fr == 0) ssq[(size_t)row * 16 + pn0 * 4 + wc] = ss;
;         }
;     }
.LBB0_1158:
	s_or_b64 exec, exec, s[14:15]
	v_add_u32_e32 v60, 0xa0, v136
	v_add_u32_e32 v56, 0xa1, v136
	v_ashrrev_i32_e32 v61, 31, v60
	v_ashrrev_i32_e32 v57, 31, v56
	v_lshlrev_b64 v[92:93], 11, v[60:61]
	v_lshlrev_b64 v[62:63], 11, v[56:57]
	v_add_u32_e32 v52, 0xa2, v136
	v_add_u32_e32 v48, 0xa3, v136
	v_lshl_add_u64 v[34:35], s[4:5], 0, v[92:93]
	v_lshl_add_u64 v[36:37], s[4:5], 0, v[62:63]
	v_ashrrev_i32_e32 v53, 31, v52
	v_ashrrev_i32_e32 v49, 31, v48
	v_lshl_add_u64 v[34:35], v[34:35], 0, v[138:139]
	v_lshl_add_u64 v[36:37], v[36:37], 0, v[138:139]
	v_lshlrev_b64 v[58:59], 11, v[52:53]
	v_lshlrev_b64 v[54:55], 11, v[48:49]
	v_add_u32_e32 v44, 0xb0, v136
	v_add_u32_e32 v40, 0xb1, v136
	global_load_ushort v98, v[34:35], off
	global_load_ushort v99, v[34:35], off offset:32
	global_load_ushort v100, v[34:35], off offset:256
	global_load_ushort v101, v[34:35], off offset:288
	global_load_ushort v88, v[36:37], off
	global_load_ushort v89, v[36:37], off offset:32
	global_load_ushort v90, v[36:37], off offset:256
	global_load_ushort v91, v[36:37], off offset:288
	v_lshl_add_u64 v[34:35], s[4:5], 0, v[58:59]
	v_lshl_add_u64 v[36:37], s[4:5], 0, v[54:55]
	v_ashrrev_i32_e32 v45, 31, v44
	v_ashrrev_i32_e32 v41, 31, v40
	v_lshl_add_u64 v[34:35], v[34:35], 0, v[138:139]
	v_lshl_add_u64 v[36:37], v[36:37], 0, v[138:139]
	v_lshlrev_b64 v[50:51], 11, v[44:45]
	v_lshlrev_b64 v[46:47], 11, v[40:41]
	global_load_ushort v84, v[34:35], off
	global_load_ushort v85, v[34:35], off offset:32
	global_load_ushort v86, v[34:35], off offset:256
	global_load_ushort v87, v[34:35], off offset:288
	global_load_ushort v80, v[36:37], off
	global_load_ushort v81, v[36:37], off offset:32
	global_load_ushort v82, v[36:37], off offset:256
	global_load_ushort v83, v[36:37], off offset:288
	v_lshl_add_u64 v[34:35], s[4:5], 0, v[50:51]
	v_lshl_add_u64 v[36:37], s[4:5], 0, v[46:47]
	v_lshl_add_u64 v[34:35], v[34:35], 0, v[138:139]
	v_lshl_add_u64 v[36:37], v[36:37], 0, v[138:139]
	global_load_ushort v76, v[34:35], off
	global_load_ushort v77, v[34:35], off offset:32
	global_load_ushort v78, v[34:35], off offset:256
	global_load_ushort v79, v[34:35], off offset:288
	global_load_ushort v72, v[36:37], off
	global_load_ushort v73, v[36:37], off offset:32
	global_load_ushort v74, v[36:37], off offset:256
	global_load_ushort v75, v[36:37], off offset:288
	v_add_u32_e32 v36, 0xb2, v136
	v_ashrrev_i32_e32 v37, 31, v36
	v_lshlrev_b64 v[42:43], 11, v[36:37]
	v_lshl_add_u64 v[34:35], s[4:5], 0, v[42:43]
	v_lshl_add_u64 v[94:95], v[34:35], 0, v[138:139]
	v_add_u32_e32 v34, 0xb3, v136
	v_ashrrev_i32_e32 v35, 31, v34
	v_lshlrev_b64 v[38:39], 11, v[34:35]
	v_lshl_add_u64 v[64:65], s[4:5], 0, v[38:39]
	v_lshl_add_u64 v[96:97], v[64:65], 0, v[138:139]
	global_load_ushort v68, v[94:95], off
	global_load_ushort v69, v[94:95], off offset:32
	global_load_ushort v70, v[94:95], off offset:256
	global_load_ushort v71, v[94:95], off offset:288
	global_load_ushort v64, v[96:97], off
	global_load_ushort v65, v[96:97], off offset:32
	global_load_ushort v66, v[96:97], off offset:256
	global_load_ushort v67, v[96:97], off offset:288
	v_lshl_add_u64 v[92:93], v[134:135], 0, v[92:93]
	s_waitcnt vmcnt(0)
	v_lshlrev_b32_e32 v94, 16, v98
	v_lshlrev_b32_e32 v95, 16, v99
	v_fmac_f32_e32 v95, 0.5, v18
	v_lshlrev_b32_e32 v96, 16, v100
	v_fmac_f32_e32 v94, 0.5, v22
	v_mul_f32_e32 v22, v95, v95
	v_lshlrev_b32_e32 v97, 16, v101
	v_fmac_f32_e32 v96, 0.5, v30
	v_fmac_f32_e32 v22, v94, v94
	v_fmac_f32_e32 v97, 0.5, v26
	v_cvt_pk_bf16_f32 v18, v94, v94
	v_fmac_f32_e32 v22, v96, v96
	v_cvt_pk_bf16_f32 v26, v95, v95
	global_store_short v[92:93], v18, off
	v_fmac_f32_e32 v22, v97, v97
	v_cvt_pk_bf16_f32 v18, v97, v97
	v_cvt_pk_bf16_f32 v30, v96, v96
	global_store_short v[92:93], v26, off offset:32
	global_store_short v[92:93], v30, off offset:256
	global_store_short v[92:93], v18, off offset:288
	v_add_f32_dpp v18, v22, v22 quad_perm:[1,0,3,2] row_mask:0xf bank_mask:0xf bound_ctrl:1
	v_mov_b32_e32 v22, 0
	s_nop 0
	v_add_f32_dpp v18, v18, v18 quad_perm:[2,3,0,1] row_mask:0xf bank_mask:0xf bound_ctrl:1
	s_nop 1
	v_add_f32_dpp v18, v18, v18 row_half_mirror row_mask:0xf bank_mask:0xf bound_ctrl:1
	s_nop 1
	v_mov_b32_dpp v22, v18 row_mirror row_mask:0xf bank_mask:0xf
	s_and_saveexec_b64 s[14:15], vcc
	s_cbranch_execz .LBB0_1160
	v_lshlrev_b64 v[60:61], 6, v[60:61]
	v_add_f32_e32 v18, v18, v22
	v_lshl_add_u64 v[60:61], v[132:133], 0, v[60:61]
	global_store_dword v[60:61], v18, off
.LBB0_1160:
	s_or_b64 exec, exec, s[14:15]
	v_lshlrev_b32_e32 v22, 16, v89
	v_lshlrev_b32_e32 v18, 16, v88
	v_fmac_f32_e32 v22, 0.5, v19
	v_lshlrev_b32_e32 v26, 16, v90
	v_fmac_f32_e32 v18, 0.5, v23
	v_mul_f32_e32 v19, v22, v22
	v_lshlrev_b32_e32 v30, 16, v91
	v_lshl_add_u64 v[60:61], v[134:135], 0, v[62:63]
	v_cvt_pk_bf16_f32 v23, v18, v18
	v_fmac_f32_e32 v19, v18, v18
	v_cvt_pk_bf16_f32 v18, v22, v22
	v_fmac_f32_e32 v26, 0.5, v31
	global_store_short v[60:61], v18, off offset:32
	v_fmac_f32_e32 v19, v26, v26
	v_cvt_pk_bf16_f32 v18, v26, v26
	v_fmac_f32_e32 v30, 0.5, v27
	global_store_short v[60:61], v18, off offset:256
	v_fmac_f32_e32 v19, v30, v30
	v_cvt_pk_bf16_f32 v18, v30, v30
	global_store_short v[60:61], v18, off offset:288
	global_store_short v[60:61], v23, off
	v_add_f32_dpp v18, v19, v19 quad_perm:[1,0,3,2] row_mask:0xf bank_mask:0xf bound_ctrl:1
	v_mov_b32_e32 v19, 0
	s_nop 0
	v_add_f32_dpp v18, v18, v18 quad_perm:[2,3,0,1] row_mask:0xf bank_mask:0xf bound_ctrl:1
	s_nop 1
	v_add_f32_dpp v18, v18, v18 row_half_mirror row_mask:0xf bank_mask:0xf bound_ctrl:1
	s_nop 1
	v_mov_b32_dpp v19, v18 row_mirror row_mask:0xf bank_mask:0xf
	s_and_saveexec_b64 s[14:15], vcc
	s_cbranch_execz .LBB0_1162
	v_add_f32_e32 v22, v18, v19
	v_lshlrev_b64 v[18:19], 6, v[56:57]
	v_lshl_add_u64 v[18:19], v[132:133], 0, v[18:19]
	global_store_dword v[18:19], v22, off
; __device__ __forceinline__ unsigned f2bf(float f) { return pk2(f, f) & 0xffffu; }
; template <int K, int LD>
; __device__ __forceinline__ void phase_resid(int mode) {
;     ...
; #pragma unroll
;       for (int m2 = 0; m2 < 2; ++m2)
; #pragma unroll
;         for (int j = 0; j < 4; ++j) {
;           const int m = mh * 2 + m2; const int row = brow + ai * 128 + wr * 64 + m * 16 + fq * 4 + j;
;           float ss = 0.f;
; #pragma unroll
;           for (int bj = 0; bj < 2; ++bj)
; #pragma unroll
;             for (int n = 0; n < 2; ++n) {
;               const size_t idx = (size_t)row * DM + bcol + bj * 128 + wc * 32 + n * 16 + fr;
;               const float xn = xo[m2][j][bj][n] + scale * acc[ai][bj][m][n][j];
;               ss += xn * xn;
;               xg[idx] = (unsigned short)f2bf(xn);
;             }
;           ss = sum16(ss);
;           if (fr == 0) ssq[(size_t)row * 16 + pn0 * 4 + wc] = ss;
;         }
;     }
.LBB0_1162:
	s_or_b64 exec, exec, s[14:15]
	v_lshlrev_b32_e32 v23, 16, v85
	v_lshlrev_b32_e32 v22, 16, v84
	v_fmac_f32_e32 v23, 0.5, v20
	v_lshlrev_b32_e32 v26, 16, v86
	v_fmac_f32_e32 v22, 0.5, v24
	v_mul_f32_e32 v20, v23, v23
	v_lshlrev_b32_e32 v27, 16, v87
	v_fmac_f32_e32 v20, v22, v22
	v_fmac_f32_e32 v26, 0.5, v32
	v_lshl_add_u64 v[18:19], v[134:135], 0, v[58:59]
	v_cvt_pk_bf16_f32 v24, v22, v22
	v_cvt_pk_bf16_f32 v22, v23, v23
	v_fmac_f32_e32 v20, v26, v26
	v_fmac_f32_e32 v27, 0.5, v28
	global_store_short v[18:19], v22, off offset:32
	v_cvt_pk_bf16_f32 v22, v26, v26
	v_fmac_f32_e32 v20, v27, v27
	global_store_short v[18:19], v24, off
	global_store_short v[18:19], v22, off offset:256
	v_cvt_pk_bf16_f32 v22, v27, v27
	global_store_short v[18:19], v22, off offset:288
	v_add_f32_dpp v18, v20, v20 quad_perm:[1,0,3,2] row_mask:0xf bank_mask:0xf bound_ctrl:1
	v_mov_b32_e32 v19, 0
	s_nop 0
	v_add_f32_dpp v18, v18, v18 quad_perm:[2,3,0,1] row_mask:0xf bank_mask:0xf bound_ctrl:1
	s_nop 1
	v_add_f32_dpp v18, v18, v18 row_half_mirror row_mask:0xf bank_mask:0xf bound_ctrl:1
	s_nop 1
	v_mov_b32_dpp v19, v18 row_mirror row_mask:0xf bank_mask:0xf
	s_and_saveexec_b64 s[14:15], vcc
	s_cbranch_execz .LBB0_1164
	v_add_f32_e32 v20, v18, v19
	v_lshlrev_b64 v[18:19], 6, v[52:53]
	v_lshl_add_u64 v[18:19], v[132:133], 0, v[18:19]
	global_store_dword v[18:19], v20, off
.LBB0_1164:
	s_or_b64 exec, exec, s[14:15]
	v_lshlrev_b32_e32 v22, 16, v81
	v_lshlrev_b32_e32 v20, 16, v80
	v_fmac_f32_e32 v22, 0.5, v21
	v_lshlrev_b32_e32 v23, 16, v82
	v_fmac_f32_e32 v20, 0.5, v25
	v_mul_f32_e32 v21, v22, v22
	v_lshlrev_b32_e32 v24, 16, v83
	v_fmac_f32_e32 v21, v20, v20
	v_fmac_f32_e32 v23, 0.5, v33
	v_lshl_add_u64 v[18:19], v[134:135], 0, v[54:55]
	v_cvt_pk_bf16_f32 v25, v20, v20
	v_cvt_pk_bf16_f32 v20, v22, v22
	v_fmac_f32_e32 v21, v23, v23
	v_fmac_f32_e32 v24, 0.5, v29
	global_store_short v[18:19], v20, off offset:32
	v_cvt_pk_bf16_f32 v20, v23, v23
	v_fmac_f32_e32 v21, v24, v24
	global_store_short v[18:19], v25, off
	global_store_short v[18:19], v20, off offset:256
	v_cvt_pk_bf16_f32 v20, v24, v24
	global_store_short v[18:19], v20, off offset:288
	v_add_f32_dpp v18, v21, v21 quad_perm:[1,0,3,2] row_mask:0xf bank_mask:0xf bound_ctrl:1
	v_mov_b32_e32 v19, 0
	s_nop 0
	v_add_f32_dpp v18, v18, v18 quad_perm:[2,3,0,1] row_mask:0xf bank_mask:0xf bound_ctrl:1
	s_nop 1
	v_add_f32_dpp v18, v18, v18 row_half_mirror row_mask:0xf bank_mask:0xf bound_ctrl:1
	s_nop 1
	v_mov_b32_dpp v19, v18 row_mirror row_mask:0xf bank_mask:0xf
	s_and_saveexec_b64 s[14:15], vcc
	s_cbranch_execz .LBB0_1166
	v_add_f32_e32 v20, v18, v19
	v_lshlrev_b64 v[18:19], 6, v[48:49]
	v_lshl_add_u64 v[18:19], v[132:133], 0, v[18:19]
	global_store_dword v[18:19], v20, off
.LBB0_1166:
	s_or_b64 exec, exec, s[14:15]
	v_lshlrev_b32_e32 v21, 16, v77
	v_lshlrev_b32_e32 v20, 16, v76
	v_fmac_f32_e32 v21, 0.5, v2
	v_lshlrev_b32_e32 v22, 16, v78
	v_fmac_f32_e32 v20, 0.5, v6
	v_mul_f32_e32 v2, v21, v21
	v_lshlrev_b32_e32 v23, 16, v79
	v_fmac_f32_e32 v2, v20, v20
	v_fmac_f32_e32 v22, 0.5, v14
	v_lshl_add_u64 v[18:19], v[134:135], 0, v[50:51]
	v_cvt_pk_bf16_f32 v6, v20, v20
	v_fmac_f32_e32 v2, v22, v22
	v_fmac_f32_e32 v23, 0.5, v10
	global_store_short v[18:19], v6, off
	v_cvt_pk_bf16_f32 v6, v21, v21
	v_fmac_f32_e32 v2, v23, v23
	global_store_short v[18:19], v6, off offset:32
	v_cvt_pk_bf16_f32 v6, v22, v22
	global_store_short v[18:19], v6, off offset:256
	v_add_f32_dpp v2, v2, v2 quad_perm:[1,0,3,2] row_mask:0xf bank_mask:0xf bound_ctrl:1
	v_cvt_pk_bf16_f32 v6, v23, v23
	global_store_short v[18:19], v6, off offset:288
	v_mov_b32_e32 v6, 0
	v_add_f32_dpp v2, v2, v2 quad_perm:[2,3,0,1] row_mask:0xf bank_mask:0xf bound_ctrl:1
	s_nop 1
	v_add_f32_dpp v2, v2, v2 row_half_mirror row_mask:0xf bank_mask:0xf bound_ctrl:1
	s_nop 1
	v_mov_b32_dpp v6, v2 row_mirror row_mask:0xf bank_mask:0xf
	s_and_saveexec_b64 s[14:15], vcc
	s_cbranch_execz .LBB0_1168
	v_lshlrev_b64 v[18:19], 6, v[44:45]
	v_add_f32_e32 v2, v2, v6
	v_lshl_add_u64 v[18:19], v[132:133], 0, v[18:19]
	global_store_dword v[18:19], v2, off
; __device__ __forceinline__ unsigned f2bf(float f) { return pk2(f, f) & 0xffffu; }
; template <int K, int LD>
; __device__ __forceinline__ void phase_resid(int mode) {
;     ...
; #pragma unroll
;       for (int m2 = 0; m2 < 2; ++m2)
; #pragma unroll
;         for (int j = 0; j < 4; ++j) {
;           const int m = mh * 2 + m2; const int row = brow + ai * 128 + wr * 64 + m * 16 + fq * 4 + j;
;           float ss = 0.f;
; #pragma unroll
;           for (int bj = 0; bj < 2; ++bj)
; #pragma unroll
;             for (int n = 0; n < 2; ++n) {
;               const size_t idx = (size_t)row * DM + bcol + bj * 128 + wc * 32 + n * 16 + fr;
;               const float xn = xo[m2][j][bj][n] + scale * acc[ai][bj][m][n][j];
;               ss += xn * xn;
;               xg[idx] = (unsigned short)f2bf(xn);
;             }
;           ss = sum16(ss);
;           if (fr == 0) ssq[(size_t)row * 16 + pn0 * 4 + wc] = ss;
;         }
;     }
.LBB0_1168:
	s_or_b64 exec, exec, s[14:15]
	v_lshlrev_b32_e32 v6, 16, v73
	v_lshlrev_b32_e32 v2, 16, v72
	v_fmac_f32_e32 v6, 0.5, v3
	v_lshlrev_b32_e32 v10, 16, v74
	v_fmac_f32_e32 v2, 0.5, v7
	v_mul_f32_e32 v3, v6, v6
	v_lshlrev_b32_e32 v14, 16, v75
	v_lshl_add_u64 v[18:19], v[134:135], 0, v[46:47]
	v_cvt_pk_bf16_f32 v7, v2, v2
	v_fmac_f32_e32 v3, v2, v2
	v_cvt_pk_bf16_f32 v2, v6, v6
	v_fmac_f32_e32 v10, 0.5, v15
	global_store_short v[18:19], v2, off offset:32
	v_fmac_f32_e32 v3, v10, v10
	v_cvt_pk_bf16_f32 v2, v10, v10
	v_fmac_f32_e32 v14, 0.5, v11
	global_store_short v[18:19], v2, off offset:256
	v_fmac_f32_e32 v3, v14, v14
	v_cvt_pk_bf16_f32 v2, v14, v14
	global_store_short v[18:19], v2, off offset:288
	global_store_short v[18:19], v7, off
	v_add_f32_dpp v2, v3, v3 quad_perm:[1,0,3,2] row_mask:0xf bank_mask:0xf bound_ctrl:1
	v_mov_b32_e32 v3, 0
	s_nop 0
	v_add_f32_dpp v2, v2, v2 quad_perm:[2,3,0,1] row_mask:0xf bank_mask:0xf bound_ctrl:1
	s_nop 1
	v_add_f32_dpp v2, v2, v2 row_half_mirror row_mask:0xf bank_mask:0xf bound_ctrl:1
	s_nop 1
	v_mov_b32_dpp v3, v2 row_mirror row_mask:0xf bank_mask:0xf
	s_and_saveexec_b64 s[14:15], vcc
	s_cbranch_execz .LBB0_1170
	v_add_f32_e32 v6, v2, v3
	v_lshlrev_b64 v[2:3], 6, v[40:41]
	v_lshl_add_u64 v[2:3], v[132:133], 0, v[2:3]
	global_store_dword v[2:3], v6, off
.LBB0_1170:
	s_or_b64 exec, exec, s[14:15]
	v_lshlrev_b32_e32 v7, 16, v69
	v_lshlrev_b32_e32 v6, 16, v68
	v_fmac_f32_e32 v7, 0.5, v4
	v_lshlrev_b32_e32 v10, 16, v70
	v_fmac_f32_e32 v6, 0.5, v8
	v_mul_f32_e32 v4, v7, v7
	v_lshlrev_b32_e32 v11, 16, v71
	v_fmac_f32_e32 v4, v6, v6
	v_fmac_f32_e32 v10, 0.5, v16
	v_lshl_add_u64 v[2:3], v[134:135], 0, v[42:43]
	v_cvt_pk_bf16_f32 v8, v6, v6
	v_cvt_pk_bf16_f32 v6, v7, v7
	v_fmac_f32_e32 v4, v10, v10
	v_fmac_f32_e32 v11, 0.5, v12
	global_store_short v[2:3], v6, off offset:32
	v_cvt_pk_bf16_f32 v6, v10, v10
	v_fmac_f32_e32 v4, v11, v11
	global_store_short v[2:3], v8, off
	global_store_short v[2:3], v6, off offset:256
	v_cvt_pk_bf16_f32 v6, v11, v11
	global_store_short v[2:3], v6, off offset:288
	v_add_f32_dpp v2, v4, v4 quad_perm:[1,0,3,2] row_mask:0xf bank_mask:0xf bound_ctrl:1
	v_mov_b32_e32 v3, 0
	s_nop 0
	v_add_f32_dpp v2, v2, v2 quad_perm:[2,3,0,1] row_mask:0xf bank_mask:0xf bound_ctrl:1
	s_nop 1
	v_add_f32_dpp v2, v2, v2 row_half_mirror row_mask:0xf bank_mask:0xf bound_ctrl:1
	s_nop 1
	v_mov_b32_dpp v3, v2 row_mirror row_mask:0xf bank_mask:0xf
	s_and_saveexec_b64 s[14:15], vcc
	s_cbranch_execz .LBB0_1172
	v_add_f32_e32 v4, v2, v3
	v_lshlrev_b64 v[2:3], 6, v[36:37]
	v_lshl_add_u64 v[2:3], v[132:133], 0, v[2:3]
	global_store_dword v[2:3], v4, off
.LBB0_1172:
	s_or_b64 exec, exec, s[14:15]
	v_lshlrev_b32_e32 v6, 16, v65
	v_lshlrev_b32_e32 v4, 16, v64
	v_fmac_f32_e32 v6, 0.5, v5
	v_lshlrev_b32_e32 v7, 16, v66
	v_fmac_f32_e32 v4, 0.5, v9
	v_mul_f32_e32 v5, v6, v6
	v_lshlrev_b32_e32 v8, 16, v67
	v_fmac_f32_e32 v5, v4, v4
	v_fmac_f32_e32 v7, 0.5, v17
	v_lshl_add_u64 v[2:3], v[134:135], 0, v[38:39]
	v_cvt_pk_bf16_f32 v9, v4, v4
	v_cvt_pk_bf16_f32 v4, v6, v6
	v_fmac_f32_e32 v5, v7, v7
	v_fmac_f32_e32 v8, 0.5, v13
	global_store_short v[2:3], v4, off offset:32
	v_cvt_pk_bf16_f32 v4, v7, v7
	v_fmac_f32_e32 v5, v8, v8
	global_store_short v[2:3], v9, off
	global_store_short v[2:3], v4, off offset:256
	v_cvt_pk_bf16_f32 v4, v8, v8
	global_store_short v[2:3], v4, off offset:288
	v_add_f32_dpp v2, v5, v5 quad_perm:[1,0,3,2] row_mask:0xf bank_mask:0xf bound_ctrl:1
	v_mov_b32_e32 v3, 0
	s_nop 0
	v_add_f32_dpp v2, v2, v2 quad_perm:[2,3,0,1] row_mask:0xf bank_mask:0xf bound_ctrl:1
	s_nop 1
	v_add_f32_dpp v2, v2, v2 row_half_mirror row_mask:0xf bank_mask:0xf bound_ctrl:1
	s_nop 1
	v_mov_b32_dpp v3, v2 row_mirror row_mask:0xf bank_mask:0xf
	s_and_saveexec_b64 s[14:15], vcc
	s_cbranch_execz .LBB0_1101
	v_add_f32_e32 v4, v2, v3
	v_lshlrev_b64 v[2:3], 6, v[34:35]
	v_lshl_add_u64 v[2:3], v[132:133], 0, v[2:3]
	global_store_dword v[2:3], v4, off
	s_branch .LBB0_1101

; #define GAS __attribute__((address_space(1)))
; __device__ __forceinline__ int otid() { int t = threadIdx.x; asm volatile("" : "+v"(t)); return t; }
; __device__ __forceinline__ unsigned f2bf(float f) { return pk2(f, f) & 0xffffu; }
; #define STAGE(P, GP, ktrel) do { const GAS char* _g = (GP) + (ktrel) * (BK * 2); \
;     __builtin_amdgcn_global_load_lds((const GAS unsigned*)(_g + so0), (unsigned*)((char*)(P) + tid_ * 16), 16, 0, 0); \
;     __builtin_amdgcn_global_load_lds((const GAS unsigned*)(_g + so1), (unsigned*)((char*)(P) + tid_ * 16 + 8192), 16, 0, 0); } while (0)
; template <int K, int LD = K>
; __device__ __forceinline__ void gemm_prefetch(const GAS bf16* A, const GAS bf16* Bt, int brow, int bcol) {
;   bf16* shm = (bf16*)smem_raw;
;   const int tid_ = otid();
;   unsigned so0, so1;
;   { int r_, c_; stage_rc(tid_ * 16, r_, c_); so0 = (unsigned)(r_ * LD + c_) * 2u; stage_rc(tid_ * 16 + 8192, r_, c_); so1 = (unsigned)(r_ * LD + c_) * 2u; }
;   const GAS char* pA0 = (const GAS char*)A + (long)brow * LD * 2; const GAS char* pA1 = pA0 + (long)HALF * LD * 2;
;   const GAS char* pB0 = (const GAS char*)Bt + (long)bcol * LD * 2; const GAS char* pB1 = pB0 + (long)HALF * LD * 2;
;   asm volatile("" : "+s"(pA0), "+s"(pA1), "+s"(pB0), "+s"(pB1));
;   STAGE(SB(0, 0), pB0, 0); STAGE(SA(0, 0), pA0, 0);
;   STAGE(SB(0, 1), pB1, 0); STAGE(SA(0, 1), pA1, 0);
;   STAGE(SB(1, 0), pB0, 1); STAGE(SA(1, 0), pA0, 1); STAGE(SB(1, 1), pB1, 1);
; }
; __device__ __forceinline__ void phase_ple() {
;     ...
;       gemm_prefetch<DM>(A2, W2, brow, bcol);
;       EPI_IDS
; #pragma unroll
;       for (int ai = 0; ai < 2; ++ai)
; #pragma unroll
;         for (int m = 0; m < 4; ++m)
; #pragma unroll
;           for (int j = 0; j < 4; ++j) {
;             const int row = brow + ai * 128 + wr * 64 + m * 16 + fq * 4 + j;
; #pragma unroll
;             for (int bj = 0; bj < 2; ++bj)
; #pragma unroll
;               for (int n = 0; n < 2; ++n) tmp[(size_t)row * DM + bcol + bj * 128 + wc * 32 + n * 16 + fr] = (unsigned short)f2bf(acc[ai][bj][m][n][j]);
;           }
.LBB0_1223:
	s_or_b64 exec, exec, s[18:19]
	v_mov_b32_e32 v130, v170
	s_lshl_b64 s[18:19], s[20:21], 11
	v_ashrrev_i32_e32 v131, 31, v130
	v_lshrrev_b32_e32 v131, 26, v131
	v_lshlrev_b32_e32 v146, 4, v130
	v_add_u32_e32 v131, v130, v131
	v_bfe_i32 v130, v130, 27, 1
	v_lshrrev_b32_e32 v130, 22, v130
	v_add_u32_e32 v130, v146, v130
	v_and_b32_e32 v130, 0xfffffc00, v130
	v_sub_u32_e32 v130, v146, v130
	v_lshrrev_b32_e32 v132, 4, v130
	v_bitop3_b32 v132, v132, v130, 32 bitop3:0x6c
	v_ashrrev_i32_e32 v130, 31, v130
	v_lshrrev_b32_e32 v130, 26, v130
	v_add_u32_e32 v130, v132, v130
	v_ashrrev_i32_e32 v130, 6, v130
	v_ashrrev_i32_e32 v131, 6, v131
	v_mul_i32_i24_e32 v134, 64, v130
	v_lshlrev_b32_e32 v133, 3, v131
	v_lshlrev_b32_e32 v131, 5, v131
	v_sub_u32_e32 v132, v132, v134
	v_and_b32_e32 v133, 0x1ffff0, v133
	v_and_b32_e32 v131, 32, v131
	v_ashrrev_i16_sdwa v132, v1, sext(v132) dst_sel:DWORD dst_unused:UNUSED_PAD src0_sel:DWORD src1_sel:BYTE_0
	v_add_u32_sdwa v131, v131, sext(v132) dst_sel:DWORD dst_unused:UNUSED_PAD src0_sel:DWORD src1_sel:WORD_0
	v_add_lshl_u32 v130, v130, v133, 11
	v_lshl_add_u32 v138, v131, 1, v130
	v_add_u32_e32 v130, 0x2000, v146
	v_ashrrev_i32_e32 v131, 31, v130
	v_lshrrev_b32_e32 v131, 22, v131
	v_add_u32_e32 v131, v130, v131
	v_ashrrev_i32_e32 v131, 10, v131
	v_mul_i32_i24_e32 v132, 0x400, v131
	v_sub_u32_e32 v130, v130, v132
	v_lshrrev_b32_e32 v132, 4, v130
	s_add_u32 s26, s12, s18
	v_bitop3_b32 v130, v132, v130, 32 bitop3:0x6c
	s_addc_u32 s27, s13, s19
	v_ashrrev_i32_e32 v133, 31, v130
	s_add_u32 s18, s26, 0x40000
	v_lshrrev_b32_e32 v133, 26, v133
	s_addc_u32 s19, s27, 0
	s_lshl_b64 s[24:25], s[22:23], 11
	v_add_u32_e32 v133, v130, v133
	s_add_u32 s28, s43, s24
	v_lshrrev_b32_e32 v134, 6, v133
	v_and_b32_e32 v133, 0xc0, v133
	s_addc_u32 s29, s44, s25
	v_lshlrev_b32_e32 v132, 3, v131
	v_lshlrev_b32_e32 v131, 5, v131
	v_sub_u32_e32 v130, v130, v133
	s_add_u32 s24, s28, 0x40000
	v_add_u32_e32 v136, s38, v146
	v_and_b32_e32 v132, 0x1ffff0, v132
	v_and_b32_e32 v131, 32, v131
	v_ashrrev_i16_sdwa v130, v1, sext(v130) dst_sel:DWORD dst_unused:UNUSED_PAD src0_sel:DWORD src1_sel:BYTE_0
	s_addc_u32 s25, s29, 0
	v_readfirstlane_b32 s21, v136
	v_add_u32_e32 v136, 0x2000, v136
	v_add_u32_sdwa v130, v131, sext(v130) dst_sel:DWORD dst_unused:UNUSED_PAD src0_sel:DWORD src1_sel:WORD_0
	v_add_lshl_u32 v131, v134, v132, 11
	s_mov_b64 s[30:31], s[18:19]
	s_mov_b64 s[48:49], s[24:25]
	s_mov_b64 s[50:51], s[26:27]
	s_mov_b64 s[52:53], s[28:29]
	s_mov_b32 m0, s21
	v_readfirstlane_b32 s21, v136
	v_add_u32_e32 v147, 0x100, v146
	v_lshl_add_u32 v130, v130, 1, v131
	v_add_u32_e32 v142, 0x2000, v147
	global_load_lds_dwordx4 v138, s[52:53]
	s_mov_b32 m0, s21
	v_readfirstlane_b32 s21, v147
	v_mov_b32_e32 v131, v139
	global_load_lds_dwordx4 v130, s[52:53]
	s_mov_b32 m0, s21
	v_readfirstlane_b32 s21, v142
	v_add_u32_e32 v148, s39, v146
	v_lshl_add_u64 v[134:135], s[52:53], 0, v[130:131]
	global_load_lds_dwordx4 v138, s[50:51]
	v_lshl_add_u64 v[140:141], s[50:51], 0, v[130:131]
	s_mov_b32 m0, s21
	v_readfirstlane_b32 s21, v148
	v_lshl_add_u64 v[144:145], s[48:49], 0, v[130:131]
	v_add_u32_e32 v131, 0x2000, v148
	global_load_lds_dwordx4 v130, s[50:51]
	s_mov_b32 m0, s21
	v_readfirstlane_b32 s21, v131
	v_add_u32_e32 v131, 0x4000, v147
	global_load_lds_dwordx4 v138, s[48:49]
	s_mov_b32 m0, s21
	v_readfirstlane_b32 s21, v131
	v_add_u32_e32 v131, 0x6000, v147
	global_load_lds_dwordx4 v130, s[48:49]
	s_mov_b32 m0, s21
	v_readfirstlane_b32 s21, v131
	v_lshl_add_u64 v[132:133], s[52:53], 0, v[138:139]
	global_load_lds_dwordx4 v138, s[30:31]
	s_mov_b32 m0, s21
	v_lshl_add_u64 v[136:137], s[50:51], 0, v[138:139]
	global_load_lds_dwordx4 v130, s[30:31]
	v_lshl_add_u64 v[130:131], v[132:133], 0, s[8:9]
	v_add_u32_e32 v132, s40, v146
	v_lshl_add_u64 v[142:143], s[48:49], 0, v[138:139]
	v_readfirstlane_b32 s21, v132
	v_add_u32_e32 v132, 0x2000, v132
	s_mov_b32 m0, s21
	v_readfirstlane_b32 s21, v132
	v_add_u32_e32 v132, 0x8000, v147
	global_load_lds_dwordx4 v[130:131], off
	v_lshl_add_u64 v[130:131], v[134:135], 0, s[8:9]
	s_mov_b32 m0, s21
	v_readfirstlane_b32 s21, v132
	v_add_u32_e32 v132, 0xa000, v147
	global_load_lds_dwordx4 v[130:131], off
	v_lshl_add_u64 v[130:131], v[136:137], 0, s[8:9]
	s_mov_b32 m0, s21
	v_readfirstlane_b32 s21, v132
	v_add_u32_e32 v132, s41, v146
	global_load_lds_dwordx4 v[130:131], off
	v_lshl_add_u64 v[130:131], v[140:141], 0, s[8:9]
	s_mov_b32 m0, s21
	v_readfirstlane_b32 s21, v132
	v_add_u32_e32 v132, 0x2000, v132
	global_load_lds_dwordx4 v[130:131], off
	v_lshl_add_u64 v[130:131], v[142:143], 0, s[8:9]
	s_mov_b32 m0, s21
	v_readfirstlane_b32 s21, v132
	global_load_lds_dwordx4 v[130:131], off
	v_lshl_add_u64 v[130:131], v[144:145], 0, s[8:9]
	s_mov_b32 m0, s21
	s_lshl_b64 s[30:31], s[22:23], 1
	global_load_lds_dwordx4 v[130:131], off
	v_mov_b32_e32 v131, v170
	s_add_u32 s30, s10, s30
	v_ashrrev_i32_e32 v130, 2, v131
	v_and_b32_e32 v130, 0xffffffc0, v130
	v_add_u32_e32 v130, s20, v130
	v_lshrrev_b32_e32 v132, 2, v131
	v_and_b32_e32 v134, 15, v131
	v_and_or_b32 v130, v132, 12, v130
	s_addc_u32 s31, s11, s31
	v_and_b32_e32 v138, 0xc0, v131
	v_lshl_add_u64 v[132:133], s[30:31], 0, v[138:139]
	v_lshlrev_b32_e32 v138, 1, v134
	v_ashrrev_i32_e32 v131, 31, v130
	v_lshl_add_u64 v[132:133], v[132:133], 0, v[138:139]
	v_lshlrev_b64 v[134:135], 11, v[130:131]
	v_lshl_add_u64 v[134:135], v[132:133], 0, v[134:135]
	v_cvt_pk_bf16_f32 v114, v114, v114
	global_store_short v[134:135], v114, off offset:32
	v_cvt_pk_bf16_f32 v114, v126, v126
	v_cvt_pk_bf16_f32 v118, v118, v118
	global_store_short v[134:135], v118, off
	global_store_short v[134:135], v114, off offset:256
; __device__ __forceinline__ unsigned f2bf(float f) { return pk2(f, f) & 0xffffu; }
; __device__ __forceinline__ void phase_ple() {
;     ...
; #pragma unroll
;       for (int ai = 0; ai < 2; ++ai)
; #pragma unroll
;         for (int m = 0; m < 4; ++m)
; #pragma unroll
;           for (int j = 0; j < 4; ++j) {
;             const int row = brow + ai * 128 + wr * 64 + m * 16 + fq * 4 + j;
; #pragma unroll
;             for (int bj = 0; bj < 2; ++bj)
; #pragma unroll
;               for (int n = 0; n < 2; ++n) tmp[(size_t)row * DM + bcol + bj * 128 + wc * 32 + n * 16 + fr] = (unsigned short)f2bf(acc[ai][bj][m][n][j]);
;           }
	v_cvt_pk_bf16_f32 v114, v122, v122
	global_store_short v[134:135], v114, off offset:288
	v_or_b32_e32 v134, 1, v130
	v_ashrrev_i32_e32 v135, 31, v134
	v_lshlrev_b64 v[134:135], 11, v[134:135]
	v_lshl_add_u64 v[134:135], v[132:133], 0, v[134:135]
	v_cvt_pk_bf16_f32 v114, v119, v119
	global_store_short v[134:135], v114, off
	v_cvt_pk_bf16_f32 v114, v115, v115
	global_store_short v[134:135], v114, off offset:32
	v_cvt_pk_bf16_f32 v114, v127, v127
	global_store_short v[134:135], v114, off offset:256
	v_cvt_pk_bf16_f32 v114, v123, v123
	global_store_short v[134:135], v114, off offset:288
	v_or_b32_e32 v114, 2, v130
	v_ashrrev_i32_e32 v115, 31, v114
	v_lshlrev_b64 v[114:115], 11, v[114:115]
	v_lshl_add_u64 v[114:115], v[132:133], 0, v[114:115]
	v_cvt_pk_bf16_f32 v116, v116, v116
	global_store_short v[114:115], v116, off offset:32
	v_cvt_pk_bf16_f32 v116, v128, v128
	v_cvt_pk_bf16_f32 v118, v120, v120
	global_store_short v[114:115], v118, off
	global_store_short v[114:115], v116, off offset:256
	v_cvt_pk_bf16_f32 v116, v124, v124
	global_store_short v[114:115], v116, off offset:288
	v_or_b32_e32 v114, 3, v130
	v_ashrrev_i32_e32 v115, 31, v114
	v_lshlrev_b64 v[114:115], 11, v[114:115]
	v_lshl_add_u64 v[114:115], v[132:133], 0, v[114:115]
	v_cvt_pk_bf16_f32 v116, v121, v121
	global_store_short v[114:115], v116, off
	v_cvt_pk_bf16_f32 v116, v117, v117
	global_store_short v[114:115], v116, off offset:32
	v_cvt_pk_bf16_f32 v116, v129, v129
	global_store_short v[114:115], v116, off offset:256
	v_cvt_pk_bf16_f32 v116, v125, v125
	global_store_short v[114:115], v116, off offset:288
	v_or_b32_e32 v114, 16, v130
	v_ashrrev_i32_e32 v115, 31, v114
	v_lshlrev_b64 v[114:115], 11, v[114:115]
	v_lshl_add_u64 v[114:115], v[132:133], 0, v[114:115]
	v_cvt_pk_bf16_f32 v98, v98, v98
	global_store_short v[114:115], v98, off offset:32
	v_cvt_pk_bf16_f32 v98, v110, v110
	v_cvt_pk_bf16_f32 v102, v102, v102
	global_store_short v[114:115], v102, off
	global_store_short v[114:115], v98, off offset:256
	v_cvt_pk_bf16_f32 v98, v106, v106
	global_store_short v[114:115], v98, off offset:288
	v_or_b32_e32 v114, 17, v130
	v_ashrrev_i32_e32 v115, 31, v114
	v_lshlrev_b64 v[114:115], 11, v[114:115]
	v_lshl_add_u64 v[114:115], v[132:133], 0, v[114:115]
	v_cvt_pk_bf16_f32 v98, v103, v103
	global_store_short v[114:115], v98, off
	v_cvt_pk_bf16_f32 v98, v99, v99
	global_store_short v[114:115], v98, off offset:32
	v_cvt_pk_bf16_f32 v98, v111, v111
	global_store_short v[114:115], v98, off offset:256
	v_cvt_pk_bf16_f32 v98, v107, v107
	global_store_short v[114:115], v98, off offset:288
	v_or_b32_e32 v98, 18, v130
	v_ashrrev_i32_e32 v99, 31, v98
	v_lshlrev_b64 v[98:99], 11, v[98:99]
	v_lshl_add_u64 v[98:99], v[132:133], 0, v[98:99]
	v_cvt_pk_bf16_f32 v100, v100, v100
	global_store_short v[98:99], v100, off offset:32
	v_cvt_pk_bf16_f32 v100, v112, v112
	v_cvt_pk_bf16_f32 v102, v104, v104
	global_store_short v[98:99], v102, off
	global_store_short v[98:99], v100, off offset:256
	v_cvt_pk_bf16_f32 v100, v108, v108
	global_store_short v[98:99], v100, off offset:288
	v_or_b32_e32 v98, 19, v130
	v_ashrrev_i32_e32 v99, 31, v98
	v_lshlrev_b64 v[98:99], 11, v[98:99]
	v_lshl_add_u64 v[98:99], v[132:133], 0, v[98:99]
	v_cvt_pk_bf16_f32 v100, v105, v105
	global_store_short v[98:99], v100, off
	v_cvt_pk_bf16_f32 v100, v101, v101
	global_store_short v[98:99], v100, off offset:32
	v_cvt_pk_bf16_f32 v100, v113, v113
	global_store_short v[98:99], v100, off offset:256
	v_cvt_pk_bf16_f32 v100, v109, v109
	global_store_short v[98:99], v100, off offset:288
	v_or_b32_e32 v98, 32, v130
	v_ashrrev_i32_e32 v99, 31, v98
	v_lshlrev_b64 v[98:99], 11, v[98:99]
	v_lshl_add_u64 v[98:99], v[132:133], 0, v[98:99]
	v_cvt_pk_bf16_f32 v82, v82, v82
	global_store_short v[98:99], v82, off offset:32
	v_cvt_pk_bf16_f32 v82, v94, v94
	v_cvt_pk_bf16_f32 v86, v86, v86
	global_store_short v[98:99], v86, off
	global_store_short v[98:99], v82, off offset:256
	v_cvt_pk_bf16_f32 v82, v90, v90
	global_store_short v[98:99], v82, off offset:288
	v_or_b32_e32 v98, 33, v130
	v_ashrrev_i32_e32 v99, 31, v98
	v_lshlrev_b64 v[98:99], 11, v[98:99]
	v_lshl_add_u64 v[98:99], v[132:133], 0, v[98:99]
	v_cvt_pk_bf16_f32 v82, v87, v87
	global_store_short v[98:99], v82, off
	v_cvt_pk_bf16_f32 v82, v83, v83
	global_store_short v[98:99], v82, off offset:32
	v_cvt_pk_bf16_f32 v82, v95, v95
	global_store_short v[98:99], v82, off offset:256
	v_cvt_pk_bf16_f32 v82, v91, v91
	global_store_short v[98:99], v82, off offset:288
	v_or_b32_e32 v82, 34, v130
	v_ashrrev_i32_e32 v83, 31, v82
	v_lshlrev_b64 v[82:83], 11, v[82:83]
	v_lshl_add_u64 v[82:83], v[132:133], 0, v[82:83]
	v_cvt_pk_bf16_f32 v84, v84, v84
	global_store_short v[82:83], v84, off offset:32
	v_cvt_pk_bf16_f32 v84, v96, v96
	v_cvt_pk_bf16_f32 v86, v88, v88
	global_store_short v[82:83], v86, off
	global_store_short v[82:83], v84, off offset:256
	v_cvt_pk_bf16_f32 v84, v92, v92
	global_store_short v[82:83], v84, off offset:288
	v_or_b32_e32 v82, 35, v130
	v_ashrrev_i32_e32 v83, 31, v82
	v_lshlrev_b64 v[82:83], 11, v[82:83]
	v_lshl_add_u64 v[82:83], v[132:133], 0, v[82:83]
	v_cvt_pk_bf16_f32 v84, v89, v89
	global_store_short v[82:83], v84, off
	v_cvt_pk_bf16_f32 v84, v85, v85
	global_store_short v[82:83], v84, off offset:32
	v_cvt_pk_bf16_f32 v84, v97, v97
	global_store_short v[82:83], v84, off offset:256
	v_cvt_pk_bf16_f32 v84, v93, v93
	global_store_short v[82:83], v84, off offset:288
	v_or_b32_e32 v82, 48, v130
	v_ashrrev_i32_e32 v83, 31, v82
	v_lshlrev_b64 v[82:83], 11, v[82:83]
	v_lshl_add_u64 v[82:83], v[132:133], 0, v[82:83]
	v_cvt_pk_bf16_f32 v66, v66, v66
	global_store_short v[82:83], v66, off offset:32
; __device__ __forceinline__ unsigned f2bf(float f) { return pk2(f, f) & 0xffffu; }
; __device__ __forceinline__ void phase_ple() {
;     ...
; #pragma unroll
;       for (int ai = 0; ai < 2; ++ai)
; #pragma unroll
;         for (int m = 0; m < 4; ++m)
; #pragma unroll
;           for (int j = 0; j < 4; ++j) {
;             const int row = brow + ai * 128 + wr * 64 + m * 16 + fq * 4 + j;
; #pragma unroll
;             for (int bj = 0; bj < 2; ++bj)
; #pragma unroll
;               for (int n = 0; n < 2; ++n) tmp[(size_t)row * DM + bcol + bj * 128 + wc * 32 + n * 16 + fr] = (unsigned short)f2bf(acc[ai][bj][m][n][j]);
;           }
	v_cvt_pk_bf16_f32 v66, v78, v78
	v_cvt_pk_bf16_f32 v70, v70, v70
	global_store_short v[82:83], v70, off
	global_store_short v[82:83], v66, off offset:256
	v_cvt_pk_bf16_f32 v66, v74, v74
	global_store_short v[82:83], v66, off offset:288
	v_or_b32_e32 v82, 49, v130
	v_ashrrev_i32_e32 v83, 31, v82
	v_lshlrev_b64 v[82:83], 11, v[82:83]
	v_lshl_add_u64 v[82:83], v[132:133], 0, v[82:83]
	v_cvt_pk_bf16_f32 v66, v71, v71
	global_store_short v[82:83], v66, off
	v_cvt_pk_bf16_f32 v66, v67, v67
	global_store_short v[82:83], v66, off offset:32
	v_cvt_pk_bf16_f32 v66, v79, v79
	global_store_short v[82:83], v66, off offset:256
	v_cvt_pk_bf16_f32 v66, v75, v75
	global_store_short v[82:83], v66, off offset:288
	v_or_b32_e32 v66, 50, v130
	v_ashrrev_i32_e32 v67, 31, v66
	v_lshlrev_b64 v[66:67], 11, v[66:67]
	v_lshl_add_u64 v[66:67], v[132:133], 0, v[66:67]
	v_cvt_pk_bf16_f32 v68, v68, v68
	global_store_short v[66:67], v68, off offset:32
	v_cvt_pk_bf16_f32 v68, v80, v80
	v_cvt_pk_bf16_f32 v70, v72, v72
	global_store_short v[66:67], v70, off
	global_store_short v[66:67], v68, off offset:256
	v_cvt_pk_bf16_f32 v68, v76, v76
	global_store_short v[66:67], v68, off offset:288
	v_or_b32_e32 v66, 51, v130
	v_ashrrev_i32_e32 v67, 31, v66
	v_lshlrev_b64 v[66:67], 11, v[66:67]
	v_lshl_add_u64 v[66:67], v[132:133], 0, v[66:67]
	v_cvt_pk_bf16_f32 v68, v73, v73
	global_store_short v[66:67], v68, off
	v_cvt_pk_bf16_f32 v68, v69, v69
	global_store_short v[66:67], v68, off offset:32
	v_cvt_pk_bf16_f32 v68, v81, v81
	global_store_short v[66:67], v68, off offset:256
	v_cvt_pk_bf16_f32 v68, v77, v77
	global_store_short v[66:67], v68, off offset:288
	v_add_u32_e32 v66, 0x80, v130
	v_ashrrev_i32_e32 v67, 31, v66
	v_lshlrev_b64 v[66:67], 11, v[66:67]
	v_lshl_add_u64 v[66:67], v[132:133], 0, v[66:67]
	v_cvt_pk_bf16_f32 v50, v50, v50
	global_store_short v[66:67], v50, off offset:32
	v_cvt_pk_bf16_f32 v50, v62, v62
	v_cvt_pk_bf16_f32 v54, v54, v54
	global_store_short v[66:67], v54, off
	global_store_short v[66:67], v50, off offset:256
	v_cvt_pk_bf16_f32 v50, v58, v58
	global_store_short v[66:67], v50, off offset:288
	v_add_u32_e32 v66, 0x81, v130
	v_ashrrev_i32_e32 v67, 31, v66
	v_lshlrev_b64 v[66:67], 11, v[66:67]
	v_lshl_add_u64 v[66:67], v[132:133], 0, v[66:67]
	v_cvt_pk_bf16_f32 v50, v55, v55
	global_store_short v[66:67], v50, off
	v_cvt_pk_bf16_f32 v50, v51, v51
	global_store_short v[66:67], v50, off offset:32
	v_cvt_pk_bf16_f32 v50, v63, v63
	global_store_short v[66:67], v50, off offset:256
	v_cvt_pk_bf16_f32 v50, v59, v59
	global_store_short v[66:67], v50, off offset:288
	v_add_u32_e32 v50, 0x82, v130
	v_ashrrev_i32_e32 v51, 31, v50
	v_lshlrev_b64 v[50:51], 11, v[50:51]
	v_lshl_add_u64 v[50:51], v[132:133], 0, v[50:51]
	v_cvt_pk_bf16_f32 v52, v52, v52
	global_store_short v[50:51], v52, off offset:32
	v_cvt_pk_bf16_f32 v52, v64, v64
	v_cvt_pk_bf16_f32 v54, v56, v56
	global_store_short v[50:51], v54, off
	global_store_short v[50:51], v52, off offset:256
	v_cvt_pk_bf16_f32 v52, v60, v60
	global_store_short v[50:51], v52, off offset:288
	v_add_u32_e32 v50, 0x83, v130
	v_ashrrev_i32_e32 v51, 31, v50
	v_lshlrev_b64 v[50:51], 11, v[50:51]
	v_lshl_add_u64 v[50:51], v[132:133], 0, v[50:51]
	v_cvt_pk_bf16_f32 v52, v57, v57
	global_store_short v[50:51], v52, off
	v_cvt_pk_bf16_f32 v52, v53, v53
	global_store_short v[50:51], v52, off offset:32
	v_cvt_pk_bf16_f32 v52, v65, v65
	global_store_short v[50:51], v52, off offset:256
	v_cvt_pk_bf16_f32 v52, v61, v61
	global_store_short v[50:51], v52, off offset:288
	v_add_u32_e32 v50, 0x90, v130
	v_ashrrev_i32_e32 v51, 31, v50
	v_lshlrev_b64 v[50:51], 11, v[50:51]
	v_lshl_add_u64 v[50:51], v[132:133], 0, v[50:51]
	v_cvt_pk_bf16_f32 v34, v34, v34
	global_store_short v[50:51], v34, off offset:32
	v_cvt_pk_bf16_f32 v34, v46, v46
	v_cvt_pk_bf16_f32 v38, v38, v38
	global_store_short v[50:51], v38, off
	global_store_short v[50:51], v34, off offset:256
	v_cvt_pk_bf16_f32 v34, v42, v42
	global_store_short v[50:51], v34, off offset:288
	v_add_u32_e32 v50, 0x91, v130
	v_ashrrev_i32_e32 v51, 31, v50
	v_lshlrev_b64 v[50:51], 11, v[50:51]
	v_lshl_add_u64 v[50:51], v[132:133], 0, v[50:51]
	v_cvt_pk_bf16_f32 v34, v39, v39
	global_store_short v[50:51], v34, off
	v_cvt_pk_bf16_f32 v34, v35, v35
	global_store_short v[50:51], v34, off offset:32
	v_cvt_pk_bf16_f32 v34, v47, v47
	global_store_short v[50:51], v34, off offset:256
	v_cvt_pk_bf16_f32 v34, v43, v43
	global_store_short v[50:51], v34, off offset:288
	v_add_u32_e32 v34, 0x92, v130
	v_ashrrev_i32_e32 v35, 31, v34
	v_lshlrev_b64 v[34:35], 11, v[34:35]
	v_lshl_add_u64 v[34:35], v[132:133], 0, v[34:35]
; __device__ __forceinline__ unsigned f2bf(float f) { return pk2(f, f) & 0xffffu; }
; #define BAR __builtin_amdgcn_s_barrier()
; template <int K, int LD = K>
; __device__ __forceinline__ void gemm_main(const GAS bf16* A, const GAS bf16* Bt, int brow, int bcol, f32x4 (&acc)[2][2][4][2]) {
;     ...
;   if (wr == 1) BAR;
; __device__ __forceinline__ void phase_ple() {
;     ...
; #pragma unroll
;       for (int ai = 0; ai < 2; ++ai)
; #pragma unroll
;         for (int m = 0; m < 4; ++m)
; #pragma unroll
;           for (int j = 0; j < 4; ++j) {
;             const int row = brow + ai * 128 + wr * 64 + m * 16 + fq * 4 + j;
; #pragma unroll
;             for (int bj = 0; bj < 2; ++bj)
; #pragma unroll
;               for (int n = 0; n < 2; ++n) tmp[(size_t)row * DM + bcol + bj * 128 + wc * 32 + n * 16 + fr] = (unsigned short)f2bf(acc[ai][bj][m][n][j]);
;           }
	v_cvt_pk_bf16_f32 v36, v36, v36
	global_store_short v[34:35], v36, off offset:32
	v_cvt_pk_bf16_f32 v36, v48, v48
	v_cvt_pk_bf16_f32 v38, v40, v40
	global_store_short v[34:35], v38, off
	global_store_short v[34:35], v36, off offset:256
	v_cvt_pk_bf16_f32 v36, v44, v44
	global_store_short v[34:35], v36, off offset:288
	v_add_u32_e32 v34, 0x93, v130
	v_ashrrev_i32_e32 v35, 31, v34
	v_lshlrev_b64 v[34:35], 11, v[34:35]
	v_lshl_add_u64 v[34:35], v[132:133], 0, v[34:35]
	v_cvt_pk_bf16_f32 v36, v41, v41
	global_store_short v[34:35], v36, off
	v_cvt_pk_bf16_f32 v36, v37, v37
	global_store_short v[34:35], v36, off offset:32
	v_cvt_pk_bf16_f32 v36, v49, v49
	global_store_short v[34:35], v36, off offset:256
	v_cvt_pk_bf16_f32 v36, v45, v45
	global_store_short v[34:35], v36, off offset:288
	v_add_u32_e32 v34, 0xa0, v130
	v_ashrrev_i32_e32 v35, 31, v34
	v_lshlrev_b64 v[34:35], 11, v[34:35]
	v_lshl_add_u64 v[34:35], v[132:133], 0, v[34:35]
	v_cvt_pk_bf16_f32 v18, v18, v18
	global_store_short v[34:35], v18, off offset:32
	v_cvt_pk_bf16_f32 v18, v30, v30
	v_cvt_pk_bf16_f32 v22, v22, v22
	global_store_short v[34:35], v22, off
	global_store_short v[34:35], v18, off offset:256
	v_cvt_pk_bf16_f32 v18, v26, v26
	global_store_short v[34:35], v18, off offset:288
	v_add_u32_e32 v34, 0xa1, v130
	v_ashrrev_i32_e32 v35, 31, v34
	v_lshlrev_b64 v[34:35], 11, v[34:35]
	v_lshl_add_u64 v[34:35], v[132:133], 0, v[34:35]
	v_cvt_pk_bf16_f32 v18, v23, v23
	global_store_short v[34:35], v18, off
	v_cvt_pk_bf16_f32 v18, v19, v19
	global_store_short v[34:35], v18, off offset:32
	v_cvt_pk_bf16_f32 v18, v31, v31
	global_store_short v[34:35], v18, off offset:256
	v_cvt_pk_bf16_f32 v18, v27, v27
	global_store_short v[34:35], v18, off offset:288
	v_add_u32_e32 v18, 0xa2, v130
	v_ashrrev_i32_e32 v19, 31, v18
	v_lshlrev_b64 v[18:19], 11, v[18:19]
	v_lshl_add_u64 v[18:19], v[132:133], 0, v[18:19]
	v_cvt_pk_bf16_f32 v20, v20, v20
	global_store_short v[18:19], v20, off offset:32
	v_cvt_pk_bf16_f32 v20, v32, v32
	v_cvt_pk_bf16_f32 v22, v24, v24
	global_store_short v[18:19], v22, off
	global_store_short v[18:19], v20, off offset:256
	v_cvt_pk_bf16_f32 v20, v28, v28
	global_store_short v[18:19], v20, off offset:288
	v_add_u32_e32 v18, 0xa3, v130
	v_ashrrev_i32_e32 v19, 31, v18
	v_lshlrev_b64 v[18:19], 11, v[18:19]
	v_lshl_add_u64 v[18:19], v[132:133], 0, v[18:19]
	v_cvt_pk_bf16_f32 v20, v25, v25
	global_store_short v[18:19], v20, off
	v_cvt_pk_bf16_f32 v20, v21, v21
	global_store_short v[18:19], v20, off offset:32
	v_cvt_pk_bf16_f32 v20, v33, v33
	global_store_short v[18:19], v20, off offset:256
	v_cvt_pk_bf16_f32 v20, v29, v29
	global_store_short v[18:19], v20, off offset:288
	v_add_u32_e32 v18, 0xb0, v130
	v_ashrrev_i32_e32 v19, 31, v18
	v_lshlrev_b64 v[18:19], 11, v[18:19]
	v_lshl_add_u64 v[18:19], v[132:133], 0, v[18:19]
	v_cvt_pk_bf16_f32 v2, v2, v2
	global_store_short v[18:19], v2, off offset:32
	v_cvt_pk_bf16_f32 v2, v14, v14
	v_cvt_pk_bf16_f32 v6, v6, v6
	global_store_short v[18:19], v6, off
	global_store_short v[18:19], v2, off offset:256
	v_cvt_pk_bf16_f32 v2, v10, v10
	global_store_short v[18:19], v2, off offset:288
	v_add_u32_e32 v18, 0xb1, v130
	v_ashrrev_i32_e32 v19, 31, v18
	v_lshlrev_b64 v[18:19], 11, v[18:19]
	v_lshl_add_u64 v[18:19], v[132:133], 0, v[18:19]
	v_cvt_pk_bf16_f32 v2, v7, v7
	global_store_short v[18:19], v2, off
	v_cvt_pk_bf16_f32 v2, v3, v3
	global_store_short v[18:19], v2, off offset:32
	v_cvt_pk_bf16_f32 v2, v15, v15
	global_store_short v[18:19], v2, off offset:256
	v_cvt_pk_bf16_f32 v2, v11, v11
	global_store_short v[18:19], v2, off offset:288
	v_add_u32_e32 v2, 0xb2, v130
	v_ashrrev_i32_e32 v3, 31, v2
	v_lshlrev_b64 v[2:3], 11, v[2:3]
	v_lshl_add_u64 v[2:3], v[132:133], 0, v[2:3]
	v_cvt_pk_bf16_f32 v4, v4, v4
	global_store_short v[2:3], v4, off offset:32
	v_cvt_pk_bf16_f32 v4, v16, v16
	v_cvt_pk_bf16_f32 v6, v8, v8
	global_store_short v[2:3], v6, off
	global_store_short v[2:3], v4, off offset:256
	v_cvt_pk_bf16_f32 v4, v12, v12
	global_store_short v[2:3], v4, off offset:288
	v_add_u32_e32 v2, 0xb3, v130
	v_ashrrev_i32_e32 v3, 31, v2
	v_lshlrev_b64 v[2:3], 11, v[2:3]
	v_lshl_add_u64 v[2:3], v[132:133], 0, v[2:3]
	v_cvt_pk_bf16_f32 v4, v9, v9
	global_store_short v[2:3], v4, off
	v_cvt_pk_bf16_f32 v4, v5, v5
	global_store_short v[2:3], v4, off offset:32
	v_cvt_pk_bf16_f32 v4, v17, v17
	v_mov_b32_e32 v132, v170
	global_store_short v[2:3], v4, off offset:256
	v_cvt_pk_bf16_f32 v4, v13, v13
	global_store_short v[2:3], v4, off offset:288
	s_nop 0
	v_ashrrev_i32_e32 v2, 8, v132
	v_cmp_eq_u32_e32 vcc, 1, v2
	s_and_saveexec_b64 s[30:31], vcc
	s_cbranch_execz .LBB0_1225
	s_barrier
